# lagging half's extra barrier moved from the tile latch to the end of the tile header (first tile included); prologue stagger barrier and closing wr0 barrier dropped
# speedup vs baseline: 1.0108x; 1.0011x over previous
; __device__ __forceinline__ int otid() { int t = (int)threadIdx.x; asm volatile("" : "+v"(t)); return t; }
; __device__ __forceinline__ int obid() { int t = (int)blockIdx.x; asm volatile("" : "+s"(t)); return t; }
; #define PG8_WAIT_V(n) asm volatile("s_waitcnt vmcnt(" #n ")" ::: "memory")
; #define PG8_BAR __builtin_amdgcn_s_barrier()
; template <class Epi, class AMap>
; __device__ __forceinline__ void gemm_phase(LAS unsigned char* lds, const AMap am, const int lda, const h16* Bt, const int ldb, const int M, const int N, const int K, const Epi& E) {
;     const int tid = otid(), wid = __builtin_amdgcn_readfirstlane(tid >> 6), lane = tid & 63, wr = wid >> 2, wc = wid & 3, fr = lane & 15, fq = lane >> 4;
;     const int nt = K / BK;
;     Order S; S.init(M, N, (int)gridDim.x, obid());
;     unsigned voffA[2], voffB[2];
; #pragma unroll
;     for (int i = 0; i < 2; ++i) { int R, C; stage_rc(tid * 16 + i * 8192, R, C); const int Rb = Epi::PERM ? ((R & ~31) + perm32(R & 31)) : R;
;         voffA[i] = (unsigned)(R * lda + C) * 2u; voffB[i] = (unsigned)(Rb * ldb + C) * 2u; }
;     const size_t kstep = (size_t)(BK * 2);
;     const size_t hstepA = (size_t)HALF * lda * 2, hstepB = (size_t)HALF * ldb * 2;
;     const size_t tstepA = 2 * hstepA, tstepB = 2 * hstepB;
;     const unsigned ldsw = (unsigned)wid * 1024u;
;     const int aoff = lds_byte(wr * 64 + fr, fq * 8), boff = lds_byte(wc * 32 + fr, fq * 8);
;     ...
;     Unit cur, nxt; int ui = 0;
;     if (!S.next(0, cur)) return;
;     f32x4 acc[2][2][4][2];
; #pragma unroll
;     for (int a = 0; a < 2; ++a)
; #pragma unroll
;         for (int b = 0; b < 2; ++b)
; #pragma unroll
;             for (int m = 0; m < 4; ++m)
; #pragma unroll
;                 for (int n = 0; n < 2; ++n) acc[a][b][m][n] = (f32x4){0.f, 0.f, 0.f, 0.f};
;     h16x8 At[4][2], B0[2][2], B1[2][2];
;     const char* cA = am(cur.pn) + (size_t)cur.pm * tstepA; const char* cB = (const char*)Bt + (size_t)cur.pn * tstepB;
;     PG8_STAGE(PG8_SB(0, 0), cB, voffB); PG8_STAGE(PG8_SA(0, 0), cA, voffA); PG8_STAGE(PG8_SB(0, 1), cB + hstepB, voffB); PG8_STAGE(PG8_SA(0, 1), cA + hstepA, voffA);
;     if (wr == 1) PG8_BAR;
;     PG8_WAIT_V(4); PG8_BAR;
;     PG8_STAGE(PG8_SB(1, 0), cB + kstep, voffB); PG8_STAGE(PG8_SA(1, 0), cA + kstep, voffA); PG8_STAGE(PG8_SB(1, 1), cB + hstepB + kstep, voffB);
;     PG8_WAIT_V(6); PG8_BAR;
.LBB0_47:
	v_ashrrev_i32_e32 v0, 31, v10
	v_lshrrev_b32_e32 v0, 26, v0
	v_add_u32_e32 v0, v10, v0
	s_waitcnt vmcnt(0)
	v_ashrrev_i32_e32 v2, 6, v0
	v_bfe_i32 v0, v10, 27, 1
	v_lshlrev_b32_e32 v6, 4, v10
	v_lshrrev_b32_e32 v0, 22, v0
	v_add_u32_e32 v0, v6, v0
	v_and_b32_e32 v0, 0xfffffc00, v0
	v_sub_u32_e32 v0, v6, v0
	v_lshrrev_b32_e32 v3, 4, v0
	v_bitop3_b32 v5, v3, v0, 32 bitop3:0x6c
	v_ashrrev_i32_e32 v0, 31, v0
	v_lshrrev_b32_e32 v0, 26, v0
	v_add_u32_e32 v0, v5, v0
	v_lshlrev_b32_e32 v3, 3, v2
	v_ashrrev_i32_e32 v4, 6, v0
	v_and_b32_e32 v3, -16, v3
	v_mul_i32_i24_e32 v7, 64, v4
	v_add_u32_e32 v0, v4, v3
	v_sub_u32_e32 v5, v5, v7
	v_mov_b32_e32 v13, 1
	v_lshlrev_b32_e32 v3, 5, v2
	v_ashrrev_i16_sdwa v5, v13, sext(v5) dst_sel:DWORD dst_unused:UNUSED_PAD src0_sel:DWORD src1_sel:BYTE_0
	v_lshlrev_b32_e32 v8, 1, v0
	v_lshrrev_b32_e32 v9, 2, v0
	v_and_b32_e32 v11, 3, v4
	s_mov_b32 s1, 0x1ffffe0
	v_and_b32_e32 v3, 32, v3
	v_bfe_i32 v5, v5, 0, 16
	v_and_b32_e32 v8, 24, v8
	v_and_b32_e32 v9, 4, v9
	v_and_or_b32 v11, v0, s1, v11
	s_movk_i32 s3, 0x1580
	v_add_u32_e32 v7, v3, v5
	v_or3_b32 v8, v11, v9, v8
	v_mul_lo_u32 v0, v0, s3
	v_add_lshl_u32 v130, v7, v0, 1
	v_mul_lo_u32 v0, v8, s3
	v_add_lshl_u32 v0, v0, v7, 1
	v_add_u32_e32 v7, 0x2000, v6
	v_ashrrev_i32_e32 v6, 31, v7
	v_lshrrev_b32_e32 v6, 22, v6
	v_add_u32_e32 v6, v7, v6
	v_ashrrev_i32_e32 v6, 10, v6
	v_mul_i32_i24_e32 v8, 0x400, v6
	v_sub_u32_e32 v7, v7, v8
	v_lshrrev_b32_e32 v8, 4, v7
	v_bitop3_b32 v9, v8, v7, 32 bitop3:0x6c
	v_ashrrev_i32_e32 v8, 31, v9
	v_lshrrev_b32_e32 v8, 26, v8
	v_lshlrev_b32_e32 v7, 3, v6
	v_add_u32_e32 v11, v9, v8
	v_and_b32_e32 v7, -16, v7
	v_ashrrev_i32_e32 v8, 6, v11
	s_ashr_i32 s0, s46, 6
	v_add_u32_e32 v12, v8, v7
	v_and_b32_e32 v15, 3, v8
	v_and_or_b32 v15, v12, s1, v15
	s_ashr_i32 s1, s46, 8
	s_lshl_b32 s48, s0, 10
	s_add_u32 s49, s4, 0x5300000
	s_addc_u32 s62, s5, 0
	s_add_i32 s20, s20, s21
	s_ashr_i32 s21, s20, 31
	s_lshr_b32 s21, s21, 27
	s_add_i32 s21, s20, s21
	s_ashr_i32 s22, s21, 5
	s_and_b32 s21, s21, 0xffe0
	s_sub_i32 s21, s20, s21
	s_bfe_i32 s20, s21, 0x80000
	s_bfe_u32 s20, s20, 0x2000d
	s_add_i32 s23, s21, s20
	s_bfe_i32 s20, s23, 0x80000
	s_and_b32 s23, s23, 0xfc
	s_sext_i32_i16 s20, s20
	s_sub_i32 s21, s21, s23
	v_and_b32_e32 v11, 0xc0, v11
	s_lshl_b32 s22, s22, 2
	s_sext_i32_i8 s21, s21
	s_ashr_i32 s23, s20, 2
	v_sub_u32_e32 v9, v9, v11
	s_add_i32 s35, s22, s21
	s_mul_hi_i32 s27, s23, 0x2b0000
	s_mul_i32 s23, s23, 0x2b0000
	v_lshlrev_b32_e32 v7, 5, v6
	v_ashrrev_i16_sdwa v9, v13, sext(v9) dst_sel:DWORD dst_unused:UNUSED_PAD src0_sel:DWORD src1_sel:BYTE_0
	v_lshlrev_b32_e32 v13, 1, v12
	v_lshrrev_b32_e32 v14, 2, v12
	s_add_u32 s26, s49, s23
	v_and_b32_e32 v7, 32, v7
	v_bfe_i32 v9, v9, 0, 16
	v_and_b32_e32 v13, 24, v13
	v_and_b32_e32 v14, 4, v14
	s_addc_u32 s27, s62, s27
	s_add_i32 s63, s48, 0
	v_add_u32_e32 v11, v7, v9
	v_or3_b32 v13, v15, v14, v13
	v_mul_lo_u32 v12, v12, s3
	s_add_i32 m0, s63, 0x10000
	v_add_lshl_u32 v132, v11, v12, 1
	v_mul_lo_u32 v12, v13, s3
	s_mul_i32 s22, s35, 0x2b0000
	global_load_lds_dwordx4 v0, s[26:27]
	s_add_i32 m0, s63, 0x12000
	v_add_lshl_u32 v134, v12, v11, 1
	s_mul_hi_i32 s21, s35, 0x2b0000
	s_add_u32 s22, s10, s22
	global_load_lds_dwordx4 v134, s[26:27]
	s_addc_u32 s23, s11, s21
	s_mov_b32 m0, s63
	s_add_i32 s64, s63, 0x2000
	global_load_lds_dwordx4 v130, s[22:23]
	s_mov_b32 m0, s64
	s_add_u32 s38, s26, 0x158000
	global_load_lds_dwordx4 v132, s[22:23]
	s_addc_u32 s39, s27, 0
	s_add_i32 m0, s63, 0x14000
	s_mov_b64 s[40:41], s[6:7]
	global_load_lds_dwordx4 v0, s[38:39]
	s_add_i32 m0, s63, 0x16000
	s_nop 0
	global_load_lds_dwordx4 v134, s[38:39]
	s_add_u32 s38, s22, 0x158000
	s_addc_u32 s39, s23, 0
	s_add_i32 s65, s63, 0x4000
	s_mov_b32 m0, s65
	s_add_i32 s68, s63, 0x6000
	global_load_lds_dwordx4 v130, s[38:39]
	s_mov_b32 m0, s68
	s_cmp_lg_u32 s1, 1
	global_load_lds_dwordx4 v132, s[38:39]
	s_cbranch_scc1 .LBB0_49
.LBB0_49:
	v_lshrrev_b32_e32 v20, 1, v10
	s_lshr_b32 s20, s20, 2
	v_and_b32_e32 v20, 24, v20
	s_lshl_b32 s0, s0, 5
	s_sext_i32_i8 s50, s20
	v_and_b32_e32 v11, 15, v10
	v_lshlrev_b32_e32 v21, 1, v20
	v_lshlrev_b32_e32 v10, 2, v10
	s_and_b32 s20, s0, 0x60
	v_lshl_add_u64 v[12:13], s[26:27], 0, v[0:1]
	v_mov_b32_e32 v135, v1
	v_lshl_or_b32 v146, s1, 6, v11
	v_lshl_or_b32 v11, v11, 6, v21
	s_lshl_b32 s1, s1, 13
	v_and_b32_e32 v10, 32, v10
	s_lshl_b32 s0, s20, 7
	v_lshl_add_u64 v[14:15], s[26:27], 0, v[134:135]
	v_mov_b32_e32 v131, v1
	v_bitop3_b32 v21, v11, s1, v10 bitop3:0xde
	v_bitop3_b32 v147, v11, s0, v10 bitop3:0xde
	s_add_i32 m0, s63, 0x18000
	v_lshl_add_u64 v[10:11], v[12:13], 0, s[92:93]
	v_lshl_add_u64 v[16:17], s[22:23], 0, v[130:131]
	v_mov_b32_e32 v133, v1
	s_waitcnt vmcnt(0)
	s_barrier
	global_load_lds_dwordx4 v[10:11], off
	v_lshl_add_u64 v[10:11], v[14:15], 0, s[92:93]
	s_add_i32 m0, s63, 0x1a000
	s_add_i32 s69, s63, 0x8000
	s_add_i32 s70, s63, 0xa000
	v_lshl_add_u64 v[18:19], s[22:23], 0, v[132:133]
	global_load_lds_dwordx4 v[10:11], off
	v_lshl_add_u64 v[10:11], v[16:17], 0, s[92:93]
	s_mov_b32 m0, s69
	s_add_u32 s0, s26, 0x158080
	global_load_lds_dwordx4 v[10:11], off
	v_lshl_add_u64 v[10:11], v[18:19], 0, s[92:93]
	s_mov_b32 m0, s70
	s_addc_u32 s1, s27, 0
	global_load_lds_dwordx4 v[10:11], off
	s_add_i32 m0, s63, 0x1c000
	v_lshl_add_u64 v[10:11], s[0:1], 0, v[0:1]
	global_load_lds_dwordx4 v[10:11], off
	v_lshl_add_u64 v[10:11], s[0:1], 0, v[134:135]
	s_add_i32 m0, s63, 0x1e000
	s_mov_b32 s4, 0x15800
	global_load_lds_dwordx4 v[10:11], off
	v_lshrrev_b32_e32 v10, 1, v2
	v_mul_lo_u32 v2, v4, s3
	v_mad_u64_u32 v[10:11], s[0:1], v10, s4, v[2:3]
	v_or_b32_e32 v2, v10, v3
	v_add_lshl_u32 v2, v2, v5, 1
	v_mov_b32_e32 v3, v1
	s_mov_b64 s[6:7], 0x158080
	v_lshl_add_u64 v[136:137], v[2:3], 0, s[6:7]
	v_lshrrev_b32_e32 v3, 1, v6
	v_mul_lo_u32 v2, v8, s3
	v_mad_u64_u32 v[2:3], s[0:1], v3, s4, v[2:3]
	s_waitcnt vmcnt(6)
	v_or_b32_e32 v2, v2, v7
	v_add_lshl_u32 v2, v2, v9, 1
	v_mov_b32_e32 v3, v1
	v_or_b32_e32 v148, s20, v20
	v_lshl_add_u64 v[138:139], v[2:3], 0, s[6:7]
	s_mov_b32 s71, 0
	v_add_u32_e32 v149, 0, v21
	s_mov_b64 s[6:7], s[40:41]
	s_barrier

; #define PG8_STAGE(bufoff, gbase, voff) do { _Pragma("unroll") for (int _i = 0; _i < 2; ++_i) \
;         __builtin_amdgcn_global_load_lds((const unsigned*)((const char*)(gbase) + (voff)[_i]), (LAS unsigned*)(lds + (bufoff) + ldsw + _i * 8192), 16, 0, 0); } while (0)
; #define PG8_LDA(dst, b, h) do { _Pragma("unroll") for (int m = 0; m < 4; ++m) _Pragma("unroll") for (int k = 0; k < 2; ++k) dst[m][k] = *(const LAS h16x8*)(lds + PG8_SA(b, h) + aoff + m * 2048 + k * 1024); } while (0)
; #define PG8_LDB(dst, b, h) do { _Pragma("unroll") for (int n = 0; n < 2; ++n) _Pragma("unroll") for (int k = 0; k < 2; ++k) dst[n][k] = *(const LAS h16x8*)(lds + PG8_SB(b, h) + boff + n * 2048 + k * 1024); } while (0)
; #define PG8_WAIT_V(n) asm volatile("s_waitcnt vmcnt(" #n ")" ::: "memory")
; #define PG8_WAIT_L(n) asm volatile("s_waitcnt lgkmcnt(" #n ")" ::: "memory")
; #define PG8_BAR __builtin_amdgcn_s_barrier()
; #define PG8_SCHED __builtin_amdgcn_sched_barrier(0)
; template <class Epi, class AMap>
; __device__ __forceinline__ void gemm_phase(LAS unsigned char* lds, const AMap am, const int lda, const h16* Bt, const int ldb, const int M, const int N, const int K, const Epi& E) {
;     ...
;         const bool has_next = S.next(ui + 1, nxt);
;         const char* nA = has_next ? am(nxt.pn) + (size_t)nxt.pm * tstepA : cA; const char* nB = has_next ? (const char*)Bt + (size_t)nxt.pn * tstepB : cB;
; #pragma unroll 1
;         for (int t = 0; t < nt; t += 2) {
;             const bool last = (t == nt - 2);
;             const char* a1 = cA + (size_t)(t + 1) * kstep;
;             const char* a2 = last ? nA : cA + (size_t)(t + 2) * kstep; const char* b2 = last ? nB : cB + (size_t)(t + 2) * kstep;
;             const char* a3 = a2 + kstep; const char* b3 = b2 + kstep;
;             PG8_LDB(B0, 0, 0); PG8_SCHED; PG8_LDA(At, 0, 0); PG8_STAGE(PG8_SA(1, 1), a1 + hstepA, voffA);
;             PG8_WAIT_L(8); PG8_BAR; PG8_WAIT_L(0); PG8_MMA(0, 0, At, B0); PG8_BAR; PG8_SCHED;
;             PG8_LDB(B1, 0, 1); PG8_STAGE(PG8_SB(0, 0), b2, voffB);
;             PG8_BAR; PG8_WAIT_L(0); PG8_MMA(0, 1, At, B1); PG8_BAR;
;             PG8_LDA(At, 0, 1); PG8_STAGE(PG8_SA(0, 0), a2, voffA);
;             PG8_BAR; PG8_WAIT_L(0); PG8_MMA(1, 0, At, B0); PG8_BAR; PG8_SCHED;
;             PG8_STAGE(PG8_SB(0, 1), b2 + hstepB, voffB);
;             PG8_WAIT_V(6); PG8_BAR; PG8_MMA(1, 1, At, B1); PG8_BAR;
.LBB0_60:
	s_add_u32 s20, s26, 0x100
	s_addc_u32 s21, s27, 0
	s_mov_b32 s29, -2
	s_cmpk_lt_u32 s46, 0x100
	s_cbranch_scc1 .Lgy0
	s_barrier
.Lgy0:
.Lg4p_61:
	s_add_u32 s26, s22, 0x100
	s_addc_u32 s27, s23, 0
	s_add_i32 s51, 0, 0x10000
	v_add_u32_e32 v144, s51, v147
	ds_read_b128 v[140:143], v144
	ds_read_b128 v[150:153], v144 offset:1024
	ds_read_b128 v[154:157], v144 offset:2048
	ds_read_b128 v[158:161], v144 offset:3072
	s_cmpk_eq_i32 s29, 0x52
	s_cselect_b32 s45, s1, s27
	s_cselect_b32 s44, s0, s26
	s_cselect_b32 s43, s41, s21
	s_cselect_b32 s42, s40, s20
	v_lshl_add_u64 v[144:145], s[22:23], 0, v[136:137]
	s_add_i32 m0, s63, 0xc000
	ds_read_b128 v[162:165], v149
	ds_read_b128 v[166:169], v149 offset:1024
	ds_read_b128 v[170:173], v149 offset:2048
	ds_read_b128 v[174:177], v149 offset:3072
	ds_read_b128 v[178:181], v149 offset:4096
	ds_read_b128 v[182:185], v149 offset:5120
	ds_read_b128 v[186:189], v149 offset:6144
	ds_read_b128 v[190:193], v149 offset:7168
	global_load_lds_dwordx4 v[144:145], off
	v_lshl_add_u64 v[144:145], s[22:23], 0, v[138:139]
	s_add_i32 m0, s63, 0xe000
	s_nop 0
	global_load_lds_dwordx4 v[144:145], off
	s_waitcnt lgkmcnt(11)
	s_add_i32 s60, 0, 0x14000
	v_add_u32_e32 v144, s60, v147
	s_add_i32 s22, s51, s48
	ds_read_b128 v[194:197], v144
	ds_read_b128 v[198:201], v144 offset:1024
	ds_read_b128 v[202:205], v144 offset:2048
	ds_read_b128 v[220:223], v144 offset:3072
	s_waitcnt vmcnt(8) lgkmcnt(0)
	s_barrier
	v_mfma_f32_16x16x32_f16 v[126:129], v[140:143], v[162:165], 0
	v_mfma_f32_16x16x32_f16 v[122:125], v[154:157], v[162:165], 0
	v_mfma_f32_16x16x32_f16 v[110:113], v[140:143], v[170:173], 0
	v_mfma_f32_16x16x32_f16 v[106:109], v[154:157], v[170:173], 0
	v_mfma_f32_16x16x32_f16 v[94:97], v[140:143], v[178:181], 0
	v_mfma_f32_16x16x32_f16 v[90:93], v[154:157], v[178:181], 0
	v_mfma_f32_16x16x32_f16 v[78:81], v[140:143], v[186:189], 0
	v_mfma_f32_16x16x32_f16 v[74:77], v[154:157], v[186:189], 0
	v_mfma_f32_16x16x32_f16 v[126:129], v[150:153], v[166:169], v[126:129]
	v_mfma_f32_16x16x32_f16 v[122:125], v[158:161], v[166:169], v[122:125]
	v_mfma_f32_16x16x32_f16 v[110:113], v[150:153], v[174:177], v[110:113]
	v_mfma_f32_16x16x32_f16 v[106:109], v[158:161], v[174:177], v[106:109]
	v_mfma_f32_16x16x32_f16 v[94:97], v[150:153], v[182:185], v[94:97]
	v_mfma_f32_16x16x32_f16 v[90:93], v[158:161], v[182:185], v[90:93]
	v_mfma_f32_16x16x32_f16 v[78:81], v[150:153], v[190:193], v[78:81]
	v_mfma_f32_16x16x32_f16 v[74:77], v[158:161], v[190:193], v[74:77]
	v_mfma_f32_16x16x32_f16 v[118:121], v[194:197], v[162:165], 0
	v_mfma_f32_16x16x32_f16 v[114:117], v[202:205], v[162:165], 0
	v_mfma_f32_16x16x32_f16 v[102:105], v[194:197], v[170:173], 0
	v_mfma_f32_16x16x32_f16 v[98:101], v[202:205], v[170:173], 0
	v_mfma_f32_16x16x32_f16 v[86:89], v[194:197], v[178:181], 0
	v_mfma_f32_16x16x32_f16 v[82:85], v[202:205], v[178:181], 0
	v_mfma_f32_16x16x32_f16 v[70:73], v[194:197], v[186:189], 0
	v_mfma_f32_16x16x32_f16 v[66:69], v[202:205], v[186:189], 0
	v_mfma_f32_16x16x32_f16 v[118:121], v[198:201], v[166:169], v[118:121]
	v_mfma_f32_16x16x32_f16 v[114:117], v[220:223], v[166:169], v[114:117]
	v_mfma_f32_16x16x32_f16 v[102:105], v[198:201], v[174:177], v[102:105]
	v_mfma_f32_16x16x32_f16 v[98:101], v[220:223], v[174:177], v[98:101]
	v_mfma_f32_16x16x32_f16 v[86:89], v[198:201], v[182:185], v[86:89]
	v_mfma_f32_16x16x32_f16 v[82:85], v[220:223], v[182:185], v[82:85]
	v_mfma_f32_16x16x32_f16 v[70:73], v[198:201], v[190:193], v[70:73]
	v_mfma_f32_16x16x32_f16 v[66:69], v[220:223], v[190:193], v[66:69]
	s_barrier
	v_lshl_add_u64 v[144:145], s[42:43], 0, v[0:1]
	s_mov_b32 m0, s22
	v_lshl_add_u64 v[206:207], s[42:43], 0, v[134:135]
	global_load_lds_dwordx4 v[144:145], off
	s_add_i32 m0, s22, 0x2000
	s_nop 0
	global_load_lds_dwordx4 v[206:207], off
	s_mov_b32 m0, s63
	v_lshl_add_u64 v[212:213], s[44:45], 0, v[130:131]
	ds_read_b128 v[162:165], v149 offset:16384
	ds_read_b128 v[166:169], v149 offset:17408
	ds_read_b128 v[170:173], v149 offset:18432
	ds_read_b128 v[174:177], v149 offset:19456
	ds_read_b128 v[178:181], v149 offset:20480
	ds_read_b128 v[182:185], v149 offset:21504
	ds_read_b128 v[186:189], v149 offset:22528
	ds_read_b128 v[190:193], v149 offset:23552
	global_load_lds_dwordx4 v[212:213], off
	v_lshl_add_u64 v[214:215], s[44:45], 0, v[132:133]
	s_mov_b32 m0, s64
	s_nop 0
	global_load_lds_dwordx4 v[214:215], off
	s_add_u32 s22, s42, 0x158000
	s_addc_u32 s23, s43, 0
	s_add_i32 s51, s60, s48
	v_lshl_add_u64 v[232:233], s[22:23], 0, v[0:1]
	s_mov_b32 m0, s51
	s_nop 0
	global_load_lds_dwordx4 v[232:233], off
	v_lshl_add_u64 v[232:233], s[22:23], 0, v[134:135]
	s_add_i32 m0, s51, 0x2000
	s_nop 0
	global_load_lds_dwordx4 v[232:233], off
	s_waitcnt vmcnt(8) lgkmcnt(0)
	s_barrier
; #define PG8_STAGE(bufoff, gbase, voff) do { _Pragma("unroll") for (int _i = 0; _i < 2; ++_i) \
;         __builtin_amdgcn_global_load_lds((const unsigned*)((const char*)(gbase) + (voff)[_i]), (LAS unsigned*)(lds + (bufoff) + ldsw + _i * 8192), 16, 0, 0); } while (0)
; #define PG8_LDA(dst, b, h) do { _Pragma("unroll") for (int m = 0; m < 4; ++m) _Pragma("unroll") for (int k = 0; k < 2; ++k) dst[m][k] = *(const LAS h16x8*)(lds + PG8_SA(b, h) + aoff + m * 2048 + k * 1024); } while (0)
; #define PG8_LDB(dst, b, h) do { _Pragma("unroll") for (int n = 0; n < 2; ++n) _Pragma("unroll") for (int k = 0; k < 2; ++k) dst[n][k] = *(const LAS h16x8*)(lds + PG8_SB(b, h) + boff + n * 2048 + k * 1024); } while (0)
; #define PG8_MMA(ai, bj, At, Bt_) do { __builtin_amdgcn_s_setprio(1); _Pragma("unroll") for (int m = 0; m < 4; ++m) _Pragma("unroll") for (int n = 0; n < 2; ++n) _Pragma("unroll") for (int k = 0; k < 2; ++k) \
;         acc[ai][bj][m][n] = __builtin_amdgcn_mfma_f32_16x16x32_f16(Bt_[n][k], At[m][k], acc[ai][bj][m][n], 0, 0, 0); __builtin_amdgcn_s_setprio(0); } while (0)
; #define PG8_WAIT_V(n) asm volatile("s_waitcnt vmcnt(" #n ")" ::: "memory")
; #define PG8_WAIT_L(n) asm volatile("s_waitcnt lgkmcnt(" #n ")" ::: "memory")
; #define PG8_BAR __builtin_amdgcn_s_barrier()
; #define PG8_SCHED __builtin_amdgcn_sched_barrier(0)
; template <class Epi, class AMap>
; __device__ __forceinline__ void gemm_phase(LAS unsigned char* lds, const AMap am, const int lda, const h16* Bt, const int ldb, const int M, const int N, const int K, const Epi& E) {
;     ...
;             PG8_BAR; PG8_WAIT_L(0); PG8_MMA(1, 0, At, B0); PG8_BAR; PG8_SCHED;
;             PG8_STAGE(PG8_SB(0, 1), b2 + hstepB, voffB);
;             PG8_WAIT_V(6); PG8_BAR; PG8_MMA(1, 1, At, B1); PG8_BAR;
;             PG8_LDB(B0, 1, 0); PG8_SCHED; PG8_LDA(At, 1, 0); PG8_STAGE(PG8_SA(0, 1), a2 + hstepA, voffA);
;             PG8_WAIT_L(8); PG8_BAR; PG8_WAIT_L(0); PG8_MMA(0, 0, At, B0); PG8_BAR; PG8_SCHED;
;             PG8_LDB(B1, 1, 1); PG8_STAGE(PG8_SB(1, 0), b3, voffB);
;             PG8_BAR; PG8_WAIT_L(0); PG8_MMA(0, 1, At, B1); PG8_BAR;
;             PG8_LDA(At, 1, 1); PG8_STAGE(PG8_SA(1, 0), a3, voffA);
;             PG8_BAR; PG8_WAIT_L(0); PG8_MMA(1, 0, At, B0); PG8_BAR; PG8_SCHED;
	v_mfma_f32_16x16x32_f16 v[62:65], v[140:143], v[162:165], 0
	v_mfma_f32_16x16x32_f16 v[58:61], v[154:157], v[162:165], 0
	v_mfma_f32_16x16x32_f16 v[46:49], v[140:143], v[170:173], 0
	v_mfma_f32_16x16x32_f16 v[42:45], v[154:157], v[170:173], 0
	v_mfma_f32_16x16x32_f16 v[30:33], v[140:143], v[178:181], 0
	v_mfma_f32_16x16x32_f16 v[26:29], v[154:157], v[178:181], 0
	v_mfma_f32_16x16x32_f16 v[14:17], v[140:143], v[186:189], 0
	v_mfma_f32_16x16x32_f16 v[10:13], v[154:157], v[186:189], 0
	v_mfma_f32_16x16x32_f16 v[62:65], v[150:153], v[166:169], v[62:65]
	v_mfma_f32_16x16x32_f16 v[58:61], v[158:161], v[166:169], v[58:61]
	v_mfma_f32_16x16x32_f16 v[46:49], v[150:153], v[174:177], v[46:49]
	v_mfma_f32_16x16x32_f16 v[42:45], v[158:161], v[174:177], v[42:45]
	v_mfma_f32_16x16x32_f16 v[30:33], v[150:153], v[182:185], v[30:33]
	v_mfma_f32_16x16x32_f16 v[26:29], v[158:161], v[182:185], v[26:29]
	v_mfma_f32_16x16x32_f16 v[14:17], v[150:153], v[190:193], v[14:17]
	v_mfma_f32_16x16x32_f16 v[10:13], v[158:161], v[190:193], v[10:13]
	v_mfma_f32_16x16x32_f16 v[54:57], v[194:197], v[162:165], 0
	v_mfma_f32_16x16x32_f16 v[50:53], v[202:205], v[162:165], 0
	v_mfma_f32_16x16x32_f16 v[38:41], v[194:197], v[170:173], 0
	v_mfma_f32_16x16x32_f16 v[34:37], v[202:205], v[170:173], 0
	v_mfma_f32_16x16x32_f16 v[22:25], v[194:197], v[178:181], 0
	v_mfma_f32_16x16x32_f16 v[18:21], v[202:205], v[178:181], 0
	v_mfma_f32_16x16x32_f16 v[6:9], v[194:197], v[186:189], 0
	v_mfma_f32_16x16x32_f16 v[2:5], v[202:205], v[186:189], 0
	v_mfma_f32_16x16x32_f16 v[54:57], v[198:201], v[166:169], v[54:57]
	v_mfma_f32_16x16x32_f16 v[50:53], v[220:223], v[166:169], v[50:53]
	v_mfma_f32_16x16x32_f16 v[38:41], v[198:201], v[174:177], v[38:41]
	v_mfma_f32_16x16x32_f16 v[34:37], v[220:223], v[174:177], v[34:37]
	v_mfma_f32_16x16x32_f16 v[22:25], v[198:201], v[182:185], v[22:25]
	v_mfma_f32_16x16x32_f16 v[18:21], v[220:223], v[182:185], v[18:21]
	v_mfma_f32_16x16x32_f16 v[6:9], v[198:201], v[190:193], v[6:9]
	v_mfma_f32_16x16x32_f16 v[2:5], v[220:223], v[190:193], v[2:5]
	s_barrier
	s_add_i32 s51, 0, 0x18000
	v_add_u32_e32 v234, s51, v147
	ds_read_b128 v[140:143], v234
	ds_read_b128 v[150:153], v234 offset:1024
	ds_read_b128 v[154:157], v234 offset:2048
	ds_read_b128 v[158:161], v234 offset:3072
	s_add_u32 s22, s44, 0x158000
	s_addc_u32 s23, s45, 0
	s_mov_b32 m0, s65
	v_lshl_add_u64 v[232:233], s[22:23], 0, v[130:131]
	ds_read_b128 v[162:165], v149 offset:32768
	ds_read_b128 v[166:169], v149 offset:33792
	ds_read_b128 v[170:173], v149 offset:34816
	ds_read_b128 v[174:177], v149 offset:35840
	ds_read_b128 v[178:181], v149 offset:36864
	ds_read_b128 v[182:185], v149 offset:37888
	ds_read_b128 v[186:189], v149 offset:38912
	ds_read_b128 v[190:193], v149 offset:39936
	global_load_lds_dwordx4 v[232:233], off
	v_lshl_add_u64 v[232:233], s[22:23], 0, v[132:133]
	s_mov_b32 m0, s68
	s_nop 0
	global_load_lds_dwordx4 v[232:233], off
	s_waitcnt lgkmcnt(11)
	s_add_i32 s44, 0, 0x1c000
	s_add_i32 s22, s51, s48
	v_add_u32_e32 v216, s44, v147
	v_lshl_add_u64 v[144:145], v[144:145], 0, s[92:93]
	s_mov_b32 m0, s22
	ds_read_b128 v[194:197], v216
	ds_read_b128 v[198:201], v216 offset:1024
	ds_read_b128 v[202:205], v216 offset:2048
	ds_read_b128 v[220:223], v216 offset:3072
	s_waitcnt vmcnt(8) lgkmcnt(0)
	s_barrier
	v_mfma_f32_16x16x32_f16 v[126:129], v[140:143], v[162:165], v[126:129]
	v_mfma_f32_16x16x32_f16 v[122:125], v[154:157], v[162:165], v[122:125]
	v_mfma_f32_16x16x32_f16 v[110:113], v[140:143], v[170:173], v[110:113]
	v_mfma_f32_16x16x32_f16 v[106:109], v[154:157], v[170:173], v[106:109]
	v_mfma_f32_16x16x32_f16 v[94:97], v[140:143], v[178:181], v[94:97]
	v_mfma_f32_16x16x32_f16 v[90:93], v[154:157], v[178:181], v[90:93]
	v_mfma_f32_16x16x32_f16 v[78:81], v[140:143], v[186:189], v[78:81]
	v_mfma_f32_16x16x32_f16 v[74:77], v[154:157], v[186:189], v[74:77]
	v_mfma_f32_16x16x32_f16 v[126:129], v[150:153], v[166:169], v[126:129]
	v_mfma_f32_16x16x32_f16 v[122:125], v[158:161], v[166:169], v[122:125]
	v_mfma_f32_16x16x32_f16 v[110:113], v[150:153], v[174:177], v[110:113]
	v_mfma_f32_16x16x32_f16 v[106:109], v[158:161], v[174:177], v[106:109]
	v_mfma_f32_16x16x32_f16 v[94:97], v[150:153], v[182:185], v[94:97]
	v_mfma_f32_16x16x32_f16 v[90:93], v[158:161], v[182:185], v[90:93]
	v_mfma_f32_16x16x32_f16 v[78:81], v[150:153], v[190:193], v[78:81]
	v_mfma_f32_16x16x32_f16 v[74:77], v[158:161], v[190:193], v[74:77]
	v_mfma_f32_16x16x32_f16 v[118:121], v[194:197], v[162:165], v[118:121]
	v_mfma_f32_16x16x32_f16 v[114:117], v[202:205], v[162:165], v[114:117]
	v_mfma_f32_16x16x32_f16 v[102:105], v[194:197], v[170:173], v[102:105]
	v_mfma_f32_16x16x32_f16 v[98:101], v[202:205], v[170:173], v[98:101]
	v_mfma_f32_16x16x32_f16 v[86:89], v[194:197], v[178:181], v[86:89]
	v_mfma_f32_16x16x32_f16 v[82:85], v[202:205], v[178:181], v[82:85]
	v_mfma_f32_16x16x32_f16 v[70:73], v[194:197], v[186:189], v[70:73]
	v_mfma_f32_16x16x32_f16 v[66:69], v[202:205], v[186:189], v[66:69]
	v_mfma_f32_16x16x32_f16 v[118:121], v[198:201], v[166:169], v[118:121]
	v_mfma_f32_16x16x32_f16 v[114:117], v[220:223], v[166:169], v[114:117]
	v_mfma_f32_16x16x32_f16 v[102:105], v[198:201], v[174:177], v[102:105]
	v_mfma_f32_16x16x32_f16 v[98:101], v[220:223], v[174:177], v[98:101]
	v_mfma_f32_16x16x32_f16 v[86:89], v[198:201], v[182:185], v[86:89]
	v_mfma_f32_16x16x32_f16 v[82:85], v[220:223], v[182:185], v[82:85]
	v_mfma_f32_16x16x32_f16 v[70:73], v[198:201], v[190:193], v[70:73]
	v_mfma_f32_16x16x32_f16 v[66:69], v[220:223], v[190:193], v[66:69]
	s_barrier
; #define PG8_STAGE(bufoff, gbase, voff) do { _Pragma("unroll") for (int _i = 0; _i < 2; ++_i) \
;         __builtin_amdgcn_global_load_lds((const unsigned*)((const char*)(gbase) + (voff)[_i]), (LAS unsigned*)(lds + (bufoff) + ldsw + _i * 8192), 16, 0, 0); } while (0)
; #define PG8_LDA(dst, b, h) do { _Pragma("unroll") for (int m = 0; m < 4; ++m) _Pragma("unroll") for (int k = 0; k < 2; ++k) dst[m][k] = *(const LAS h16x8*)(lds + PG8_SA(b, h) + aoff + m * 2048 + k * 1024); } while (0)
; #define PG8_MMA(ai, bj, At, Bt_) do { __builtin_amdgcn_s_setprio(1); _Pragma("unroll") for (int m = 0; m < 4; ++m) _Pragma("unroll") for (int n = 0; n < 2; ++n) _Pragma("unroll") for (int k = 0; k < 2; ++k) \
;         acc[ai][bj][m][n] = __builtin_amdgcn_mfma_f32_16x16x32_f16(Bt_[n][k], At[m][k], acc[ai][bj][m][n], 0, 0, 0); __builtin_amdgcn_s_setprio(0); } while (0)
; #define PG8_WAIT_V(n) asm volatile("s_waitcnt vmcnt(" #n ")" ::: "memory")
; #define PG8_WAIT_L(n) asm volatile("s_waitcnt lgkmcnt(" #n ")" ::: "memory")
; #define PG8_BAR __builtin_amdgcn_s_barrier()
; #define PG8_SCHED __builtin_amdgcn_sched_barrier(0)
; template <class Epi, class AMap>
; __device__ __forceinline__ void gemm_phase(LAS unsigned char* lds, const AMap am, const int lda, const h16* Bt, const int ldb, const int M, const int N, const int K, const Epi& E) {
;     ...
;             PG8_LDA(At, 1, 1); PG8_STAGE(PG8_SA(1, 0), a3, voffA);
;             PG8_BAR; PG8_WAIT_L(0); PG8_MMA(1, 0, At, B0); PG8_BAR; PG8_SCHED;
;             PG8_STAGE(PG8_SB(1, 1), b3 + hstepB, voffB);
;             PG8_WAIT_V(6); PG8_BAR; PG8_MMA(1, 1, At, B1); PG8_BAR;
;         }
	global_load_lds_dwordx4 v[144:145], off
	v_lshl_add_u64 v[144:145], v[206:207], 0, s[92:93]
	s_add_i32 m0, s22, 0x2000
	s_nop 0
	global_load_lds_dwordx4 v[144:145], off
	s_mov_b32 m0, s69
	v_lshl_add_u64 v[144:145], v[212:213], 0, s[92:93]
	ds_read_b128 v[162:165], v149 offset:49152
	ds_read_b128 v[166:169], v149 offset:50176
	ds_read_b128 v[170:173], v149 offset:51200
	ds_read_b128 v[174:177], v149 offset:52224
	ds_read_b128 v[178:181], v149 offset:53248
	ds_read_b128 v[182:185], v149 offset:54272
	ds_read_b128 v[186:189], v149 offset:55296
	ds_read_b128 v[190:193], v149 offset:56320
	global_load_lds_dwordx4 v[144:145], off
	v_lshl_add_u64 v[144:145], v[214:215], 0, s[92:93]
	s_mov_b32 m0, s70
	s_nop 0
	global_load_lds_dwordx4 v[144:145], off
	s_add_u32 s22, s42, 0x158080
	s_addc_u32 s23, s43, 0
	s_add_i32 s42, s44, s48
	v_lshl_add_u64 v[232:233], s[22:23], 0, v[0:1]
	s_mov_b32 m0, s42
	s_nop 0
	global_load_lds_dwordx4 v[232:233], off
	v_lshl_add_u64 v[232:233], s[22:23], 0, v[134:135]
	s_add_i32 m0, s42, 0x2000
	s_nop 0
	global_load_lds_dwordx4 v[232:233], off
	s_add_i32 s29, s29, 2
	s_add_u32 s20, s20, 0x100
	s_addc_u32 s21, s21, 0
	s_cmpk_gt_u32 s29, 0x53
	s_mov_b64 s[22:23], s[26:27]
	s_waitcnt vmcnt(8) lgkmcnt(0)
	s_barrier
	v_mfma_f32_16x16x32_f16 v[62:65], v[140:143], v[162:165], v[62:65]
	v_mfma_f32_16x16x32_f16 v[58:61], v[154:157], v[162:165], v[58:61]
	v_mfma_f32_16x16x32_f16 v[46:49], v[140:143], v[170:173], v[46:49]
	v_mfma_f32_16x16x32_f16 v[42:45], v[154:157], v[170:173], v[42:45]
	v_mfma_f32_16x16x32_f16 v[30:33], v[140:143], v[178:181], v[30:33]
	v_mfma_f32_16x16x32_f16 v[26:29], v[154:157], v[178:181], v[26:29]
	v_mfma_f32_16x16x32_f16 v[14:17], v[140:143], v[186:189], v[14:17]
	v_mfma_f32_16x16x32_f16 v[10:13], v[154:157], v[186:189], v[10:13]
	v_mfma_f32_16x16x32_f16 v[62:65], v[150:153], v[166:169], v[62:65]
	v_mfma_f32_16x16x32_f16 v[58:61], v[158:161], v[166:169], v[58:61]
	v_mfma_f32_16x16x32_f16 v[46:49], v[150:153], v[174:177], v[46:49]
	v_mfma_f32_16x16x32_f16 v[42:45], v[158:161], v[174:177], v[42:45]
	v_mfma_f32_16x16x32_f16 v[30:33], v[150:153], v[182:185], v[30:33]
	v_mfma_f32_16x16x32_f16 v[26:29], v[158:161], v[182:185], v[26:29]
	v_mfma_f32_16x16x32_f16 v[14:17], v[150:153], v[190:193], v[14:17]
	v_mfma_f32_16x16x32_f16 v[10:13], v[158:161], v[190:193], v[10:13]
	v_mfma_f32_16x16x32_f16 v[54:57], v[194:197], v[162:165], v[54:57]
	v_mfma_f32_16x16x32_f16 v[50:53], v[202:205], v[162:165], v[50:53]
	v_mfma_f32_16x16x32_f16 v[38:41], v[194:197], v[170:173], v[38:41]
	v_mfma_f32_16x16x32_f16 v[34:37], v[202:205], v[170:173], v[34:37]
	v_mfma_f32_16x16x32_f16 v[22:25], v[194:197], v[178:181], v[22:25]
	v_mfma_f32_16x16x32_f16 v[18:21], v[202:205], v[178:181], v[18:21]
	v_mfma_f32_16x16x32_f16 v[6:9], v[194:197], v[186:189], v[6:9]
	v_mfma_f32_16x16x32_f16 v[2:5], v[202:205], v[186:189], v[2:5]
	v_mfma_f32_16x16x32_f16 v[54:57], v[198:201], v[166:169], v[54:57]
	v_mfma_f32_16x16x32_f16 v[50:53], v[220:223], v[166:169], v[50:53]
	v_mfma_f32_16x16x32_f16 v[38:41], v[198:201], v[174:177], v[38:41]
	v_mfma_f32_16x16x32_f16 v[34:37], v[220:223], v[174:177], v[34:37]
	v_mfma_f32_16x16x32_f16 v[22:25], v[198:201], v[182:185], v[22:25]
	v_mfma_f32_16x16x32_f16 v[18:21], v[220:223], v[182:185], v[18:21]
	v_mfma_f32_16x16x32_f16 v[6:9], v[198:201], v[190:193], v[6:9]
	v_mfma_f32_16x16x32_f16 v[2:5], v[220:223], v[190:193], v[2:5]
	s_barrier
	s_cbranch_scc1 .Lg4x_61

;     __device__ __forceinline__ void operator()(const f32x4 (&acc)[2][2][4][2], const Unit& u, int wr, int wc, int fr, int fq) const {
;         EPI_ROWS_PERM
; #pragma unroll
;         for (int ai = 0; ai < 2; ++ai)
; #pragma unroll
;             for (int m = 0; m < 4; ++m) { const size_t off = (size_t)(row0 + ai * 128 + m * 16) * DM + colt;
; #pragma unroll
;                 for (int bj = 0; bj < 2; ++bj) {
;                     const h16x8 x = *(const h16x8*)(X + off + bj * 128);
;                     f32x4 o0, o1;
; #pragma unroll
;                     for (int e = 0; e < 4; ++e) { o0[e] = (float)x[e] * ALPHA + acc[ai][bj][m][0][e]; o1[e] = (float)x[4 + e] * ALPHA + acc[ai][bj][m][1][e]; }
;                     *(u32x4*)(PRE + off + bj * 128) = pack8(o0, o1); } }
.Lgx0:
	s_waitcnt vmcnt(15)
	v_mov_b64_e32 v[150:151], v[158:159]
	v_mov_b64_e32 v[152:153], v[160:161]
	v_cvt_f32_f16_e32 v156, v150
	v_cvt_f32_f16_sdwa v157, v150 dst_sel:DWORD dst_unused:UNUSED_PAD src0_sel:WORD_1
	v_cvt_f32_f16_e32 v150, v151
	v_cvt_f32_f16_sdwa v151, v151 dst_sel:DWORD dst_unused:UNUSED_PAD src0_sel:WORD_1
	v_pk_fma_f32 v[126:127], v[156:157], s[34:35], v[126:127] op_sel_hi:[1,0,1]
	s_nop 0
	v_cvt_pk_f16_f32 v126, v126, v127
	v_pk_fma_f32 v[128:129], v[150:151], s[34:35], v[128:129] op_sel_hi:[1,0,1]
	v_lshl_add_u64 v[150:151], s[8:9], 0, v[140:141]
	v_cvt_pk_f16_f32 v127, v128, v129
	v_cvt_f32_f16_e32 v128, v152
	v_cvt_f32_f16_sdwa v129, v152 dst_sel:DWORD dst_unused:UNUSED_PAD src0_sel:WORD_1
	v_pk_fma_f32 v[122:123], v[128:129], s[34:35], v[122:123] op_sel_hi:[1,0,1]
	s_nop 0
	v_cvt_pk_f16_f32 v128, v122, v123
	v_cvt_f32_f16_e32 v122, v153
	v_cvt_f32_f16_sdwa v123, v153 dst_sel:DWORD dst_unused:UNUSED_PAD src0_sel:WORD_1
	v_pk_fma_f32 v[122:123], v[122:123], s[34:35], v[124:125] op_sel_hi:[1,0,1]
	s_nop 0
	v_cvt_pk_f16_f32 v129, v122, v123
	s_nop 0
	global_store_dwordx4 v[150:151], v[126:129], off
	s_waitcnt vmcnt(15)
	v_mov_b64_e32 v[122:123], v[162:163]
	v_mov_b64_e32 v[124:125], v[164:165]
	s_nop 0
	v_cvt_f32_f16_e32 v126, v122
	v_cvt_f32_f16_sdwa v127, v122 dst_sel:DWORD dst_unused:UNUSED_PAD src0_sel:WORD_1
	v_cvt_f32_f16_e32 v122, v123
	v_cvt_f32_f16_sdwa v123, v123 dst_sel:DWORD dst_unused:UNUSED_PAD src0_sel:WORD_1
	v_pk_fma_f32 v[118:119], v[126:127], s[34:35], v[118:119] op_sel_hi:[1,0,1]
	s_nop 0
	v_cvt_pk_f16_f32 v118, v118, v119
	v_pk_fma_f32 v[120:121], v[122:123], s[34:35], v[120:121] op_sel_hi:[1,0,1]
	s_nop 0
	v_cvt_pk_f16_f32 v119, v120, v121
	v_cvt_f32_f16_e32 v120, v124
	v_cvt_f32_f16_sdwa v121, v124 dst_sel:DWORD dst_unused:UNUSED_PAD src0_sel:WORD_1
	v_pk_fma_f32 v[114:115], v[120:121], s[34:35], v[114:115] op_sel_hi:[1,0,1]
	s_nop 0
	v_cvt_pk_f16_f32 v120, v114, v115
	v_cvt_f32_f16_e32 v114, v125
	v_cvt_f32_f16_sdwa v115, v125 dst_sel:DWORD dst_unused:UNUSED_PAD src0_sel:WORD_1
	v_pk_fma_f32 v[114:115], v[114:115], s[34:35], v[116:117] op_sel_hi:[1,0,1]
	s_nop 0
	v_cvt_pk_f16_f32 v121, v114, v115
	v_or_b32_e32 v114, 16, v144
	v_ashrrev_i32_e32 v115, 31, v114
	v_lshlrev_b64 v[114:115], 11, v[114:115]
	v_lshl_add_u64 v[114:115], v[114:115], 0, v[142:143]
	global_store_dwordx4 v[150:151], v[118:121], off offset:256
	s_nop 1
	v_lshlrev_b64 v[118:119], 1, v[114:115]
	v_lshl_add_u64 v[120:121], s[94:95], 0, v[118:119]
	s_waitcnt vmcnt(15)
	v_mov_b64_e32 v[114:115], v[166:167]
	v_mov_b64_e32 v[116:117], v[168:169]
	v_cvt_f32_f16_e32 v122, v114
	v_cvt_f32_f16_sdwa v123, v114 dst_sel:DWORD dst_unused:UNUSED_PAD src0_sel:WORD_1
	v_cvt_f32_f16_e32 v114, v115
	v_cvt_f32_f16_sdwa v115, v115 dst_sel:DWORD dst_unused:UNUSED_PAD src0_sel:WORD_1
	v_pk_fma_f32 v[110:111], v[122:123], s[34:35], v[110:111] op_sel_hi:[1,0,1]
	s_nop 0
	v_cvt_pk_f16_f32 v110, v110, v111
	v_pk_fma_f32 v[112:113], v[114:115], s[34:35], v[112:113] op_sel_hi:[1,0,1]
	v_lshl_add_u64 v[114:115], s[8:9], 0, v[118:119]
	v_cvt_pk_f16_f32 v111, v112, v113
	v_cvt_f32_f16_e32 v112, v116
	v_cvt_f32_f16_sdwa v113, v116 dst_sel:DWORD dst_unused:UNUSED_PAD src0_sel:WORD_1
	v_pk_fma_f32 v[106:107], v[112:113], s[34:35], v[106:107] op_sel_hi:[1,0,1]
	s_nop 0
	v_cvt_pk_f16_f32 v112, v106, v107
	v_cvt_f32_f16_e32 v106, v117
	v_cvt_f32_f16_sdwa v107, v117 dst_sel:DWORD dst_unused:UNUSED_PAD src0_sel:WORD_1
	v_pk_fma_f32 v[106:107], v[106:107], s[34:35], v[108:109] op_sel_hi:[1,0,1]
	s_nop 0
	v_cvt_pk_f16_f32 v113, v106, v107
	s_nop 0
	global_store_dwordx4 v[114:115], v[110:113], off
	s_waitcnt vmcnt(15)
	v_mov_b64_e32 v[106:107], v[170:171]
	v_mov_b64_e32 v[108:109], v[172:173]
	s_nop 0
	v_cvt_f32_f16_e32 v110, v106
	v_cvt_f32_f16_sdwa v111, v106 dst_sel:DWORD dst_unused:UNUSED_PAD src0_sel:WORD_1
	v_cvt_f32_f16_e32 v106, v107
	v_cvt_f32_f16_sdwa v107, v107 dst_sel:DWORD dst_unused:UNUSED_PAD src0_sel:WORD_1
	v_pk_fma_f32 v[102:103], v[110:111], s[34:35], v[102:103] op_sel_hi:[1,0,1]
	s_nop 0
	v_cvt_pk_f16_f32 v102, v102, v103
	v_pk_fma_f32 v[104:105], v[106:107], s[34:35], v[104:105] op_sel_hi:[1,0,1]
	s_nop 0
	v_cvt_pk_f16_f32 v103, v104, v105
	v_cvt_f32_f16_e32 v104, v108
	v_cvt_f32_f16_sdwa v105, v108 dst_sel:DWORD dst_unused:UNUSED_PAD src0_sel:WORD_1
	v_pk_fma_f32 v[98:99], v[104:105], s[34:35], v[98:99] op_sel_hi:[1,0,1]
	s_nop 0
	v_cvt_pk_f16_f32 v104, v98, v99
	v_cvt_f32_f16_e32 v98, v109
	v_cvt_f32_f16_sdwa v99, v109 dst_sel:DWORD dst_unused:UNUSED_PAD src0_sel:WORD_1
	v_pk_fma_f32 v[98:99], v[98:99], s[34:35], v[100:101] op_sel_hi:[1,0,1]
	s_nop 0
	v_cvt_pk_f16_f32 v105, v98, v99
	v_or_b32_e32 v98, 32, v144
	v_ashrrev_i32_e32 v99, 31, v98
	v_lshlrev_b64 v[98:99], 11, v[98:99]
	v_lshl_add_u64 v[98:99], v[98:99], 0, v[142:143]
	global_store_dwordx4 v[114:115], v[102:105], off offset:256
	s_nop 1
	v_lshlrev_b64 v[102:103], 1, v[98:99]
	v_lshl_add_u64 v[104:105], s[94:95], 0, v[102:103]
	s_waitcnt vmcnt(15)
	v_mov_b64_e32 v[98:99], v[174:175]
	v_mov_b64_e32 v[100:101], v[176:177]
	v_cvt_f32_f16_e32 v106, v98
	v_cvt_f32_f16_sdwa v107, v98 dst_sel:DWORD dst_unused:UNUSED_PAD src0_sel:WORD_1
	v_cvt_f32_f16_e32 v98, v99
	v_cvt_f32_f16_sdwa v99, v99 dst_sel:DWORD dst_unused:UNUSED_PAD src0_sel:WORD_1
	v_pk_fma_f32 v[94:95], v[106:107], s[34:35], v[94:95] op_sel_hi:[1,0,1]
	s_nop 0
	v_cvt_pk_f16_f32 v94, v94, v95
	v_pk_fma_f32 v[96:97], v[98:99], s[34:35], v[96:97] op_sel_hi:[1,0,1]
	v_lshl_add_u64 v[98:99], s[8:9], 0, v[102:103]
	v_cvt_pk_f16_f32 v95, v96, v97
	v_cvt_f32_f16_e32 v96, v100
	v_cvt_f32_f16_sdwa v97, v100 dst_sel:DWORD dst_unused:UNUSED_PAD src0_sel:WORD_1
	v_pk_fma_f32 v[90:91], v[96:97], s[34:35], v[90:91] op_sel_hi:[1,0,1]
	s_nop 0
	v_cvt_pk_f16_f32 v96, v90, v91
	v_cvt_f32_f16_e32 v90, v101
	v_cvt_f32_f16_sdwa v91, v101 dst_sel:DWORD dst_unused:UNUSED_PAD src0_sel:WORD_1
	v_pk_fma_f32 v[90:91], v[90:91], s[34:35], v[92:93] op_sel_hi:[1,0,1]
	s_nop 0
	v_cvt_pk_f16_f32 v97, v90, v91
	s_nop 0
	global_store_dwordx4 v[98:99], v[94:97], off
	s_waitcnt vmcnt(15)
;     __device__ __forceinline__ void operator()(const f32x4 (&acc)[2][2][4][2], const Unit& u, int wr, int wc, int fr, int fq) const {
;     ...
;             for (int m = 0; m < 4; ++m) { const size_t off = (size_t)(row0 + ai * 128 + m * 16) * DM + colt;
; #pragma unroll
;                 for (int bj = 0; bj < 2; ++bj) {
;                     const h16x8 x = *(const h16x8*)(X + off + bj * 128);
;                     f32x4 o0, o1;
; #pragma unroll
;                     for (int e = 0; e < 4; ++e) { o0[e] = (float)x[e] * ALPHA + acc[ai][bj][m][0][e]; o1[e] = (float)x[4 + e] * ALPHA + acc[ai][bj][m][1][e]; }
;                     *(u32x4*)(PRE + off + bj * 128) = pack8(o0, o1); } }
	v_mov_b64_e32 v[90:91], v[178:179]
	v_mov_b64_e32 v[92:93], v[180:181]
	s_nop 0
	v_cvt_f32_f16_e32 v94, v90
	v_cvt_f32_f16_sdwa v95, v90 dst_sel:DWORD dst_unused:UNUSED_PAD src0_sel:WORD_1
	v_cvt_f32_f16_e32 v90, v91
	v_cvt_f32_f16_sdwa v91, v91 dst_sel:DWORD dst_unused:UNUSED_PAD src0_sel:WORD_1
	v_pk_fma_f32 v[86:87], v[94:95], s[34:35], v[86:87] op_sel_hi:[1,0,1]
	s_nop 0
	v_cvt_pk_f16_f32 v86, v86, v87
	v_pk_fma_f32 v[88:89], v[90:91], s[34:35], v[88:89] op_sel_hi:[1,0,1]
	s_nop 0
	v_cvt_pk_f16_f32 v87, v88, v89
	v_cvt_f32_f16_e32 v88, v92
	v_cvt_f32_f16_sdwa v89, v92 dst_sel:DWORD dst_unused:UNUSED_PAD src0_sel:WORD_1
	v_pk_fma_f32 v[82:83], v[88:89], s[34:35], v[82:83] op_sel_hi:[1,0,1]
	s_nop 0
	v_cvt_pk_f16_f32 v88, v82, v83
	v_cvt_f32_f16_e32 v82, v93
	v_cvt_f32_f16_sdwa v83, v93 dst_sel:DWORD dst_unused:UNUSED_PAD src0_sel:WORD_1
	v_pk_fma_f32 v[82:83], v[82:83], s[34:35], v[84:85] op_sel_hi:[1,0,1]
	s_nop 0
	v_cvt_pk_f16_f32 v89, v82, v83
	v_or_b32_e32 v82, 48, v144
	v_ashrrev_i32_e32 v83, 31, v82
	v_lshlrev_b64 v[82:83], 11, v[82:83]
	v_lshl_add_u64 v[82:83], v[82:83], 0, v[142:143]
	global_store_dwordx4 v[98:99], v[86:89], off offset:256
	s_nop 1
	v_lshlrev_b64 v[86:87], 1, v[82:83]
	v_lshl_add_u64 v[88:89], s[94:95], 0, v[86:87]
	s_waitcnt vmcnt(15)
	v_mov_b64_e32 v[82:83], v[182:183]
	v_mov_b64_e32 v[84:85], v[184:185]
	v_cvt_f32_f16_e32 v90, v82
	v_cvt_f32_f16_sdwa v91, v82 dst_sel:DWORD dst_unused:UNUSED_PAD src0_sel:WORD_1
	v_cvt_f32_f16_e32 v82, v83
	v_cvt_f32_f16_sdwa v83, v83 dst_sel:DWORD dst_unused:UNUSED_PAD src0_sel:WORD_1
	v_pk_fma_f32 v[78:79], v[90:91], s[34:35], v[78:79] op_sel_hi:[1,0,1]
	s_nop 0
	v_cvt_pk_f16_f32 v78, v78, v79
	v_pk_fma_f32 v[80:81], v[82:83], s[34:35], v[80:81] op_sel_hi:[1,0,1]
	v_lshl_add_u64 v[82:83], s[8:9], 0, v[86:87]
	v_cvt_pk_f16_f32 v79, v80, v81
	v_cvt_f32_f16_e32 v80, v84
	v_cvt_f32_f16_sdwa v81, v84 dst_sel:DWORD dst_unused:UNUSED_PAD src0_sel:WORD_1
	v_pk_fma_f32 v[74:75], v[80:81], s[34:35], v[74:75] op_sel_hi:[1,0,1]
	s_nop 0
	v_cvt_pk_f16_f32 v80, v74, v75
	v_cvt_f32_f16_e32 v74, v85
	v_cvt_f32_f16_sdwa v75, v85 dst_sel:DWORD dst_unused:UNUSED_PAD src0_sel:WORD_1
	v_pk_fma_f32 v[74:75], v[74:75], s[34:35], v[76:77] op_sel_hi:[1,0,1]
	s_nop 0
	v_cvt_pk_f16_f32 v81, v74, v75
	s_nop 0
	global_store_dwordx4 v[82:83], v[78:81], off
	s_waitcnt vmcnt(15)
	v_mov_b64_e32 v[74:75], v[186:187]
	v_mov_b64_e32 v[76:77], v[188:189]
	s_nop 0
	v_cvt_f32_f16_e32 v78, v74
	v_cvt_f32_f16_sdwa v79, v74 dst_sel:DWORD dst_unused:UNUSED_PAD src0_sel:WORD_1
	v_cvt_f32_f16_e32 v74, v75
	v_cvt_f32_f16_sdwa v75, v75 dst_sel:DWORD dst_unused:UNUSED_PAD src0_sel:WORD_1
	v_pk_fma_f32 v[70:71], v[78:79], s[34:35], v[70:71] op_sel_hi:[1,0,1]
	s_nop 0
	v_cvt_pk_f16_f32 v70, v70, v71
	v_pk_fma_f32 v[72:73], v[74:75], s[34:35], v[72:73] op_sel_hi:[1,0,1]
	s_nop 0
	v_cvt_pk_f16_f32 v71, v72, v73
	v_cvt_f32_f16_e32 v72, v76
	v_cvt_f32_f16_sdwa v73, v76 dst_sel:DWORD dst_unused:UNUSED_PAD src0_sel:WORD_1
	v_pk_fma_f32 v[66:67], v[72:73], s[34:35], v[66:67] op_sel_hi:[1,0,1]
	s_nop 0
	v_cvt_pk_f16_f32 v72, v66, v67
	v_cvt_f32_f16_e32 v66, v77
	v_cvt_f32_f16_sdwa v67, v77 dst_sel:DWORD dst_unused:UNUSED_PAD src0_sel:WORD_1
	v_pk_fma_f32 v[66:67], v[66:67], s[34:35], v[68:69] op_sel_hi:[1,0,1]
	s_nop 0
	v_cvt_pk_f16_f32 v73, v66, v67
	global_store_dwordx4 v[82:83], v[70:73], off offset:256
	s_nop 1
	v_lshl_add_u64 v[70:71], v[140:141], 0, s[16:17]
	v_lshl_add_u64 v[72:73], s[94:95], 0, v[70:71]
	s_waitcnt vmcnt(15)
	v_mov_b64_e32 v[66:67], v[190:191]
	v_mov_b64_e32 v[68:69], v[192:193]
	v_cvt_f32_f16_e32 v74, v66
	v_cvt_f32_f16_sdwa v75, v66 dst_sel:DWORD dst_unused:UNUSED_PAD src0_sel:WORD_1
	v_cvt_f32_f16_e32 v66, v67
	v_cvt_f32_f16_sdwa v67, v67 dst_sel:DWORD dst_unused:UNUSED_PAD src0_sel:WORD_1
	v_pk_fma_f32 v[62:63], v[74:75], s[34:35], v[62:63] op_sel_hi:[1,0,1]
	s_nop 0
	v_cvt_pk_f16_f32 v62, v62, v63
	v_pk_fma_f32 v[64:65], v[66:67], s[34:35], v[64:65] op_sel_hi:[1,0,1]
	v_lshl_add_u64 v[66:67], s[8:9], 0, v[70:71]
	v_cvt_pk_f16_f32 v63, v64, v65
	v_cvt_f32_f16_e32 v64, v68
	v_cvt_f32_f16_sdwa v65, v68 dst_sel:DWORD dst_unused:UNUSED_PAD src0_sel:WORD_1
	v_pk_fma_f32 v[58:59], v[64:65], s[34:35], v[58:59] op_sel_hi:[1,0,1]
	s_nop 0
	v_cvt_pk_f16_f32 v64, v58, v59
	v_cvt_f32_f16_e32 v58, v69
	v_cvt_f32_f16_sdwa v59, v69 dst_sel:DWORD dst_unused:UNUSED_PAD src0_sel:WORD_1
	v_pk_fma_f32 v[58:59], v[58:59], s[34:35], v[60:61] op_sel_hi:[1,0,1]
	s_nop 0
	v_cvt_pk_f16_f32 v65, v58, v59
	s_nop 0
	global_store_dwordx4 v[66:67], v[62:65], off
	s_waitcnt vmcnt(15)
	v_mov_b64_e32 v[58:59], v[194:195]
	v_mov_b64_e32 v[60:61], v[196:197]
	s_nop 0
	v_cvt_f32_f16_e32 v62, v58
	v_cvt_f32_f16_sdwa v63, v58 dst_sel:DWORD dst_unused:UNUSED_PAD src0_sel:WORD_1
	v_cvt_f32_f16_e32 v58, v59
	v_cvt_f32_f16_sdwa v59, v59 dst_sel:DWORD dst_unused:UNUSED_PAD src0_sel:WORD_1
	v_pk_fma_f32 v[54:55], v[62:63], s[34:35], v[54:55] op_sel_hi:[1,0,1]
	s_nop 0
	v_cvt_pk_f16_f32 v54, v54, v55
	v_pk_fma_f32 v[56:57], v[58:59], s[34:35], v[56:57] op_sel_hi:[1,0,1]
	s_nop 0
	v_cvt_pk_f16_f32 v55, v56, v57
	v_cvt_f32_f16_e32 v56, v60
	v_cvt_f32_f16_sdwa v57, v60 dst_sel:DWORD dst_unused:UNUSED_PAD src0_sel:WORD_1
	v_pk_fma_f32 v[50:51], v[56:57], s[34:35], v[50:51] op_sel_hi:[1,0,1]
	s_nop 0
	v_cvt_pk_f16_f32 v56, v50, v51
	v_cvt_f32_f16_e32 v50, v61
	v_cvt_f32_f16_sdwa v51, v61 dst_sel:DWORD dst_unused:UNUSED_PAD src0_sel:WORD_1
	v_pk_fma_f32 v[50:51], v[50:51], s[34:35], v[52:53] op_sel_hi:[1,0,1]
	s_nop 0
	v_cvt_pk_f16_f32 v57, v50, v51
	global_store_dwordx4 v[66:67], v[54:57], off offset:256
	s_nop 1
	v_lshl_add_u64 v[54:55], v[140:141], 0, s[18:19]
	v_lshl_add_u64 v[56:57], s[94:95], 0, v[54:55]
	s_waitcnt vmcnt(15)
; #define PG8_WAIT_V(n) asm volatile("s_waitcnt vmcnt(" #n ")" ::: "memory")
; #define PG8_BAR __builtin_amdgcn_s_barrier()
; template <class Epi, class AMap>
; __device__ __forceinline__ void gemm_phase(LAS unsigned char* lds, const AMap am, const int lda, const h16* Bt, const int ldb, const int M, const int N, const int K, const Epi& E) {
;     ...
;         if (!has_next) break;
; #pragma unroll
;         for (int a = 0; a < 2; ++a)
; #pragma unroll
;             for (int b = 0; b < 2; ++b)
; #pragma unroll
;                 for (int m = 0; m < 4; ++m)
; #pragma unroll
;                     for (int n = 0; n < 2; ++n) acc[a][b][m][n] = (f32x4){0.f, 0.f, 0.f, 0.f};
;         cur = nxt; cA = nA; cB = nB; ++ui;
;     }
;     PG8_WAIT_V(0);
;     if (wr == 0) PG8_BAR;
;     PG8_BAR;
;     __device__ __forceinline__ void operator()(const f32x4 (&acc)[2][2][4][2], const Unit& u, int wr, int wc, int fr, int fq) const {
;     ...
;             for (int m = 0; m < 4; ++m) { const size_t off = (size_t)(row0 + ai * 128 + m * 16) * DM + colt;
; #pragma unroll
;                 for (int bj = 0; bj < 2; ++bj) {
;                     const h16x8 x = *(const h16x8*)(X + off + bj * 128);
;                     f32x4 o0, o1;
; #pragma unroll
;                     for (int e = 0; e < 4; ++e) { o0[e] = (float)x[e] * ALPHA + acc[ai][bj][m][0][e]; o1[e] = (float)x[4 + e] * ALPHA + acc[ai][bj][m][1][e]; }
;                     *(u32x4*)(PRE + off + bj * 128) = pack8(o0, o1); } }
	v_mov_b64_e32 v[50:51], v[198:199]
	v_mov_b64_e32 v[52:53], v[200:201]
	v_cvt_f32_f16_e32 v58, v50
	v_cvt_f32_f16_sdwa v59, v50 dst_sel:DWORD dst_unused:UNUSED_PAD src0_sel:WORD_1
	v_cvt_f32_f16_e32 v50, v51
	v_cvt_f32_f16_sdwa v51, v51 dst_sel:DWORD dst_unused:UNUSED_PAD src0_sel:WORD_1
	v_pk_fma_f32 v[46:47], v[58:59], s[34:35], v[46:47] op_sel_hi:[1,0,1]
	s_nop 0
	v_cvt_pk_f16_f32 v46, v46, v47
	v_pk_fma_f32 v[48:49], v[50:51], s[34:35], v[48:49] op_sel_hi:[1,0,1]
	v_lshl_add_u64 v[50:51], s[8:9], 0, v[54:55]
	v_cvt_pk_f16_f32 v47, v48, v49
	v_cvt_f32_f16_e32 v48, v52
	v_cvt_f32_f16_sdwa v49, v52 dst_sel:DWORD dst_unused:UNUSED_PAD src0_sel:WORD_1
	v_pk_fma_f32 v[42:43], v[48:49], s[34:35], v[42:43] op_sel_hi:[1,0,1]
	s_nop 0
	v_cvt_pk_f16_f32 v48, v42, v43
	v_cvt_f32_f16_e32 v42, v53
	v_cvt_f32_f16_sdwa v43, v53 dst_sel:DWORD dst_unused:UNUSED_PAD src0_sel:WORD_1
	v_pk_fma_f32 v[42:43], v[42:43], s[34:35], v[44:45] op_sel_hi:[1,0,1]
	s_nop 0
	v_cvt_pk_f16_f32 v49, v42, v43
	s_nop 0
	global_store_dwordx4 v[50:51], v[46:49], off
	s_waitcnt vmcnt(15)
	v_mov_b64_e32 v[42:43], v[202:203]
	v_mov_b64_e32 v[44:45], v[204:205]
	s_nop 0
	v_cvt_f32_f16_e32 v46, v42
	v_cvt_f32_f16_sdwa v47, v42 dst_sel:DWORD dst_unused:UNUSED_PAD src0_sel:WORD_1
	v_cvt_f32_f16_e32 v42, v43
	v_cvt_f32_f16_sdwa v43, v43 dst_sel:DWORD dst_unused:UNUSED_PAD src0_sel:WORD_1
	v_pk_fma_f32 v[38:39], v[46:47], s[34:35], v[38:39] op_sel_hi:[1,0,1]
	s_nop 0
	v_cvt_pk_f16_f32 v38, v38, v39
	v_pk_fma_f32 v[40:41], v[42:43], s[34:35], v[40:41] op_sel_hi:[1,0,1]
	s_nop 0
	v_cvt_pk_f16_f32 v39, v40, v41
	v_cvt_f32_f16_e32 v40, v44
	v_cvt_f32_f16_sdwa v41, v44 dst_sel:DWORD dst_unused:UNUSED_PAD src0_sel:WORD_1
	v_pk_fma_f32 v[34:35], v[40:41], s[34:35], v[34:35] op_sel_hi:[1,0,1]
	s_nop 0
	v_cvt_pk_f16_f32 v40, v34, v35
	v_cvt_f32_f16_e32 v34, v45
	v_cvt_f32_f16_sdwa v35, v45 dst_sel:DWORD dst_unused:UNUSED_PAD src0_sel:WORD_1
	v_pk_fma_f32 v[34:35], v[34:35], s[34:35], v[36:37] op_sel_hi:[1,0,1]
	s_nop 0
	v_cvt_pk_f16_f32 v41, v34, v35
	global_store_dwordx4 v[50:51], v[38:41], off offset:256
	s_nop 1
	v_lshl_add_u64 v[38:39], v[140:141], 0, s[14:15]
	v_lshl_add_u64 v[40:41], s[94:95], 0, v[38:39]
	s_waitcnt vmcnt(15)
	v_mov_b64_e32 v[34:35], v[212:213]
	v_mov_b64_e32 v[36:37], v[214:215]
	v_cvt_f32_f16_e32 v42, v34
	v_cvt_f32_f16_sdwa v43, v34 dst_sel:DWORD dst_unused:UNUSED_PAD src0_sel:WORD_1
	v_cvt_f32_f16_e32 v34, v35
	v_cvt_f32_f16_sdwa v35, v35 dst_sel:DWORD dst_unused:UNUSED_PAD src0_sel:WORD_1
	v_pk_fma_f32 v[30:31], v[42:43], s[34:35], v[30:31] op_sel_hi:[1,0,1]
	s_nop 0
	v_cvt_pk_f16_f32 v30, v30, v31
	v_pk_fma_f32 v[32:33], v[34:35], s[34:35], v[32:33] op_sel_hi:[1,0,1]
	v_lshl_add_u64 v[34:35], s[8:9], 0, v[38:39]
	v_cvt_pk_f16_f32 v31, v32, v33
	v_cvt_f32_f16_e32 v32, v36
	v_cvt_f32_f16_sdwa v33, v36 dst_sel:DWORD dst_unused:UNUSED_PAD src0_sel:WORD_1
	v_pk_fma_f32 v[26:27], v[32:33], s[34:35], v[26:27] op_sel_hi:[1,0,1]
	s_nop 0
	v_cvt_pk_f16_f32 v32, v26, v27
	v_cvt_f32_f16_e32 v26, v37
	v_cvt_f32_f16_sdwa v27, v37 dst_sel:DWORD dst_unused:UNUSED_PAD src0_sel:WORD_1
	v_pk_fma_f32 v[26:27], v[26:27], s[34:35], v[28:29] op_sel_hi:[1,0,1]
	s_nop 0
	v_cvt_pk_f16_f32 v33, v26, v27
	s_nop 0
	global_store_dwordx4 v[34:35], v[30:33], off
	s_waitcnt vmcnt(15)
	v_mov_b64_e32 v[26:27], v[220:221]
	v_mov_b64_e32 v[28:29], v[222:223]
	s_nop 0
	v_cvt_f32_f16_e32 v30, v26
	v_cvt_f32_f16_sdwa v31, v26 dst_sel:DWORD dst_unused:UNUSED_PAD src0_sel:WORD_1
	v_cvt_f32_f16_e32 v26, v27
	v_cvt_f32_f16_sdwa v27, v27 dst_sel:DWORD dst_unused:UNUSED_PAD src0_sel:WORD_1
	v_pk_fma_f32 v[22:23], v[30:31], s[34:35], v[22:23] op_sel_hi:[1,0,1]
	s_nop 0
	v_cvt_pk_f16_f32 v22, v22, v23
	v_pk_fma_f32 v[24:25], v[26:27], s[34:35], v[24:25] op_sel_hi:[1,0,1]
	s_nop 0
	v_cvt_pk_f16_f32 v23, v24, v25
	v_cvt_f32_f16_e32 v24, v28
	v_cvt_f32_f16_sdwa v25, v28 dst_sel:DWORD dst_unused:UNUSED_PAD src0_sel:WORD_1
	v_pk_fma_f32 v[18:19], v[24:25], s[34:35], v[18:19] op_sel_hi:[1,0,1]
	s_nop 0
	v_cvt_pk_f16_f32 v24, v18, v19
	v_cvt_f32_f16_e32 v18, v29
	v_cvt_f32_f16_sdwa v19, v29 dst_sel:DWORD dst_unused:UNUSED_PAD src0_sel:WORD_1
	v_pk_fma_f32 v[18:19], v[18:19], s[34:35], v[20:21] op_sel_hi:[1,0,1]
	s_nop 0
	v_cvt_pk_f16_f32 v25, v18, v19
	global_store_dwordx4 v[34:35], v[22:25], off offset:256
	s_nop 1
	v_lshl_add_u64 v[22:23], v[140:141], 0, s[4:5]
	v_lshl_add_u64 v[24:25], s[94:95], 0, v[22:23]
	s_waitcnt vmcnt(15)
	v_mov_b64_e32 v[18:19], v[224:225]
	v_mov_b64_e32 v[20:21], v[226:227]
	v_cvt_f32_f16_e32 v26, v18
	v_cvt_f32_f16_sdwa v27, v18 dst_sel:DWORD dst_unused:UNUSED_PAD src0_sel:WORD_1
	v_cvt_f32_f16_e32 v18, v19
	v_cvt_f32_f16_sdwa v19, v19 dst_sel:DWORD dst_unused:UNUSED_PAD src0_sel:WORD_1
	v_pk_fma_f32 v[14:15], v[26:27], s[34:35], v[14:15] op_sel_hi:[1,0,1]
	s_nop 0
	v_cvt_pk_f16_f32 v14, v14, v15
	v_pk_fma_f32 v[16:17], v[18:19], s[34:35], v[16:17] op_sel_hi:[1,0,1]
	v_lshl_add_u64 v[18:19], s[8:9], 0, v[22:23]
	v_cvt_pk_f16_f32 v15, v16, v17
	v_cvt_f32_f16_e32 v16, v20
	v_cvt_f32_f16_sdwa v17, v20 dst_sel:DWORD dst_unused:UNUSED_PAD src0_sel:WORD_1
	v_pk_fma_f32 v[10:11], v[16:17], s[34:35], v[10:11] op_sel_hi:[1,0,1]
	s_nop 0
	v_cvt_pk_f16_f32 v16, v10, v11
	v_cvt_f32_f16_e32 v10, v21
	v_cvt_f32_f16_sdwa v11, v21 dst_sel:DWORD dst_unused:UNUSED_PAD src0_sel:WORD_1
	v_pk_fma_f32 v[10:11], v[10:11], s[34:35], v[12:13] op_sel_hi:[1,0,1]
	s_nop 0
	v_cvt_pk_f16_f32 v17, v10, v11
	s_nop 0
	global_store_dwordx4 v[18:19], v[14:17], off
	s_waitcnt vmcnt(15)
	v_mov_b64_e32 v[10:11], v[228:229]
	v_mov_b64_e32 v[12:13], v[230:231]
	s_nop 0
	v_cvt_f32_f16_e32 v14, v10
	v_cvt_f32_f16_sdwa v15, v10 dst_sel:DWORD dst_unused:UNUSED_PAD src0_sel:WORD_1
	v_cvt_f32_f16_e32 v10, v11
	v_cvt_f32_f16_sdwa v11, v11 dst_sel:DWORD dst_unused:UNUSED_PAD src0_sel:WORD_1
	v_pk_fma_f32 v[6:7], v[14:15], s[34:35], v[6:7] op_sel_hi:[1,0,1]
	s_nop 0
	v_cvt_pk_f16_f32 v6, v6, v7
	v_pk_fma_f32 v[8:9], v[10:11], s[34:35], v[8:9] op_sel_hi:[1,0,1]
	s_nop 0
	v_cvt_pk_f16_f32 v7, v8, v9
	v_cvt_f32_f16_e32 v8, v12
	v_cvt_f32_f16_sdwa v9, v12 dst_sel:DWORD dst_unused:UNUSED_PAD src0_sel:WORD_1
	v_pk_fma_f32 v[2:3], v[8:9], s[34:35], v[2:3] op_sel_hi:[1,0,1]
	s_nop 0
	v_cvt_pk_f16_f32 v8, v2, v3
	v_cvt_f32_f16_e32 v2, v13
	v_cvt_f32_f16_sdwa v3, v13 dst_sel:DWORD dst_unused:UNUSED_PAD src0_sel:WORD_1
	v_pk_fma_f32 v[2:3], v[2:3], s[34:35], v[4:5] op_sel_hi:[1,0,1]
	s_nop 0
	v_cvt_pk_f16_f32 v9, v2, v3
	s_mov_b32 s35, s73
	global_store_dwordx4 v[18:19], v[6:9], off offset:256
	s_cbranch_vccz .LBB0_50
	s_waitcnt vmcnt(0)
	s_cmpk_gt_u32 s46, 0xff
	s_cbranch_scc1 .LBB0_65

; __device__ __forceinline__ int otid() { int t = (int)threadIdx.x; asm volatile("" : "+v"(t)); return t; }
; __device__ __forceinline__ int obid() { int t = (int)blockIdx.x; asm volatile("" : "+s"(t)); return t; }
; #define PG8_WAIT_V(n) asm volatile("s_waitcnt vmcnt(" #n ")" ::: "memory")
; #define PG8_BAR __builtin_amdgcn_s_barrier()
; template <class Epi, class AMap>
; __device__ __forceinline__ void gemm_phase(LAS unsigned char* lds, const AMap am, const int lda, const h16* Bt, const int ldb, const int M, const int N, const int K, const Epi& E) {
;     const int tid = otid(), wid = __builtin_amdgcn_readfirstlane(tid >> 6), lane = tid & 63, wr = wid >> 2, wc = wid & 3, fr = lane & 15, fq = lane >> 4;
;     const int nt = K / BK;
;     Order S; S.init(M, N, (int)gridDim.x, obid());
;     unsigned voffA[2], voffB[2];
; #pragma unroll
;     for (int i = 0; i < 2; ++i) { int R, C; stage_rc(tid * 16 + i * 8192, R, C); const int Rb = Epi::PERM ? ((R & ~31) + perm32(R & 31)) : R;
;         voffA[i] = (unsigned)(R * lda + C) * 2u; voffB[i] = (unsigned)(Rb * ldb + C) * 2u; }
;     const size_t kstep = (size_t)(BK * 2);
;     const size_t hstepA = (size_t)HALF * lda * 2, hstepB = (size_t)HALF * ldb * 2;
;     const size_t tstepA = 2 * hstepA, tstepB = 2 * hstepB;
;     const unsigned ldsw = (unsigned)wid * 1024u;
;     const int aoff = lds_byte(wr * 64 + fr, fq * 8), boff = lds_byte(wc * 32 + fr, fq * 8);
;     ...
;     Unit cur, nxt; int ui = 0;
;     if (!S.next(0, cur)) return;
;     f32x4 acc[2][2][4][2];
; #pragma unroll
;     for (int a = 0; a < 2; ++a)
; #pragma unroll
;         for (int b = 0; b < 2; ++b)
; #pragma unroll
;             for (int m = 0; m < 4; ++m)
; #pragma unroll
;                 for (int n = 0; n < 2; ++n) acc[a][b][m][n] = (f32x4){0.f, 0.f, 0.f, 0.f};
;     h16x8 At[4][2], B0[2][2], B1[2][2];
;     const char* cA = am(cur.pn) + (size_t)cur.pm * tstepA; const char* cB = (const char*)Bt + (size_t)cur.pn * tstepB;
;     PG8_STAGE(PG8_SB(0, 0), cB, voffB); PG8_STAGE(PG8_SA(0, 0), cA, voffA); PG8_STAGE(PG8_SB(0, 1), cB + hstepB, voffB); PG8_STAGE(PG8_SA(0, 1), cA + hstepA, voffA);
;     if (wr == 1) PG8_BAR;
;     PG8_WAIT_V(4); PG8_BAR;
;     PG8_STAGE(PG8_SB(1, 0), cB + kstep, voffB); PG8_STAGE(PG8_SA(1, 0), cA + kstep, voffA); PG8_STAGE(PG8_SB(1, 1), cB + hstepB + kstep, voffB);
;     PG8_WAIT_V(6); PG8_BAR;
.LBB0_83:
	s_andn2_b64 vcc, exec, s[0:1]
	s_cbranch_vccnz .LBB0_108
	v_mov_b32_e32 v10, v240
	s_mov_b32 s62, s29
	s_cmpk_gt_i32 s62, 0xabf
	v_readfirstlane_b32 s10, v10
	s_cbranch_scc1 .LBB0_108
	v_lshlrev_b32_e32 v0, 4, v10
	s_waitcnt vmcnt(0)
	v_add_u32_e32 v2, 0x2000, v0
	v_ashrrev_i32_e32 v3, 31, v2
	v_lshrrev_b32_e32 v3, 22, v3
	v_add_u32_e32 v3, v2, v3
	v_ashrrev_i32_e32 v11, 10, v3
	v_mul_i32_i24_e32 v3, 0x400, v11
	v_sub_u32_e32 v2, v2, v3
	v_lshrrev_b32_e32 v3, 4, v2
	v_bitop3_b32 v2, v3, v2, 32 bitop3:0x6c
	v_ashrrev_i32_e32 v3, 31, v2
	v_lshrrev_b32_e32 v3, 26, v3
	v_add_u32_e32 v3, v2, v3
	v_lshlrev_b32_e32 v4, 3, v11
	v_ashrrev_i32_e32 v12, 6, v3
	v_and_b32_e32 v4, -16, v4
	v_add_u32_e32 v4, v12, v4
	v_and_b32_e32 v5, 3, v12
	s_mov_b32 s5, 0xfffe0
	v_lshrrev_b32_e32 v6, 2, v4
	v_lshlrev_b32_e32 v7, 1, v4
	v_and_or_b32 v5, v4, s5, v5
	v_and_b32_e32 v6, 4, v6
	v_and_b32_e32 v7, 24, v7
	v_and_b32_e32 v3, 0xc0, v3
	v_or3_b32 v5, v5, v6, v7
	v_sub_u32_e32 v2, v2, v3
	v_mov_b32_e32 v7, 1
	v_lshlrev_b32_e32 v6, 5, v11
	v_ashrrev_i16_sdwa v2, v7, sext(v2) dst_sel:DWORD dst_unused:UNUSED_PAD src0_sel:DWORD src1_sel:BYTE_0
	v_and_b32_e32 v6, 32, v6
	v_bfe_i32 v13, v2, 0, 16
	v_add_lshl_u32 v2, v6, v13, 1
	v_lshl_add_u32 v162, v5, 12, v2
	v_lshl_add_u32 v164, v4, 12, v2
	v_bfe_i32 v2, v10, 27, 1
	v_lshrrev_b32_e32 v2, 22, v2
	v_add_u32_e32 v2, v0, v2
	v_and_b32_e32 v2, 0xfffffc00, v2
	v_sub_u32_e32 v0, v0, v2
	v_lshrrev_b32_e32 v2, 4, v0
	v_bitop3_b32 v2, v2, v0, 32 bitop3:0x6c
	v_ashrrev_i32_e32 v0, 31, v0
	v_lshrrev_b32_e32 v0, 26, v0
	v_readlane_b32 s0, v251, 6
	v_add_u32_e32 v0, v2, v0
	s_ashr_i32 s0, s10, 6
	v_ashrrev_i32_e32 v14, 6, v0
	v_ashrrev_i32_e32 v0, 31, v10
	s_ashr_i32 s1, s10, 8
	s_lshl_b32 s64, s0, 10
	s_ashr_i32 s11, s62, 31
	v_readlane_b32 s3, v255, 10
	v_lshrrev_b32_e32 v0, 26, v0
	s_add_u32 s63, s3, 0x2800000
	v_readlane_b32 s3, v255, 11
	v_add_u32_e32 v0, v10, v0
	s_addc_u32 s80, s3, 0
	v_ashrrev_i32_e32 v15, 6, v0
	s_lshr_b32 s20, s11, 29
	v_lshlrev_b32_e32 v0, 3, v15
	s_add_i32 s20, s62, s20
	v_and_b32_e32 v0, -16, v0
	s_ashr_i32 s21, s20, 3
	s_and_b32 s20, s20, -8
	v_add_u32_e32 v3, v14, v0
	v_and_b32_e32 v0, 3, v14
	s_sub_i32 s20, s62, s20
	v_and_or_b32 v0, v3, s5, v0
	s_cmp_lt_i32 s20, 0
	s_movk_i32 s5, 0x159
	s_cselect_b32 s22, s5, 0x158
	s_mul_i32 s20, s22, s20
	s_add_i32 s20, s20, s21
	s_mul_hi_i32 s21, s20, 0x2fa0be83
	s_lshr_b32 s22, s21, 31
	s_ashr_i32 s21, s21, 5
	s_add_i32 s21, s21, s22
	s_lshl_b32 s22, s21, 2
	s_mulk_i32 s21, 0xac
	s_sub_i32 s20, s20, s21
	s_bfe_u32 s21, s20, 0x2001d
	s_add_i32 s21, s20, s21
	s_sext_i32_i16 s23, s21
	s_and_b32 s21, s21, 0xfffc
	v_lshrrev_b32_e32 v4, 2, v3
	v_lshlrev_b32_e32 v5, 1, v3
	s_sub_i32 s20, s20, s21
	v_and_b32_e32 v4, 4, v4
	v_and_b32_e32 v5, 24, v5
	s_sext_i32_i16 s20, s20
	v_or3_b32 v0, v0, v4, v5
	v_mul_i32_i24_e32 v5, 64, v14
	s_lshr_b32 s24, s23, 2
	s_add_i32 s22, s22, s20
	v_sub_u32_e32 v2, v2, v5
	s_ashr_i32 s23, s22, 31
	s_bfe_i64 s[26:27], s[24:25], 0x100000
	v_lshlrev_b32_e32 v4, 5, v15
	v_ashrrev_i16_sdwa v2, v7, sext(v2) dst_sel:DWORD dst_unused:UNUSED_PAD src0_sel:DWORD src1_sel:BYTE_0
	s_lshl_b64 s[20:21], s[22:23], 20
	s_lshl_b64 s[26:27], s[26:27], 20
	v_and_b32_e32 v4, 32, v4
	v_bfe_i32 v16, v2, 0, 16
	s_add_u32 s48, s63, s26
	v_add_lshl_u32 v2, v4, v16, 1
	s_addc_u32 s49, s80, s27
	s_add_i32 s81, s64, 0
	v_lshl_add_u32 v0, v0, 12, v2
	s_add_i32 m0, s81, 0x10000
	v_lshl_add_u32 v166, v3, 12, v2
	global_load_lds_dwordx4 v0, s[48:49]
	s_add_i32 m0, s81, 0x12000
	s_add_u32 s26, s94, s20
	global_load_lds_dwordx4 v162, s[48:49]
	s_addc_u32 s27, s95, s21
	s_mov_b32 m0, s81
	s_add_i32 s82, s81, 0x2000
	global_load_lds_dwordx4 v166, s[26:27]
	s_mov_b32 m0, s82
	s_add_u32 s20, s48, 0x80000
	global_load_lds_dwordx4 v164, s[26:27]
	s_addc_u32 s21, s49, 0
	s_add_i32 m0, s81, 0x14000
	v_mov_b32_e32 v163, v1
	global_load_lds_dwordx4 v0, s[20:21]
	s_add_i32 m0, s81, 0x16000
	v_mov_b32_e32 v167, v1
	global_load_lds_dwordx4 v162, s[20:21]
	s_add_u32 s20, s26, 0x80000
	s_addc_u32 s21, s27, 0
	s_add_i32 s83, s81, 0x4000
	s_mov_b32 m0, s83
	s_add_i32 s50, s81, 0x6000
	global_load_lds_dwordx4 v166, s[20:21]
	s_mov_b32 m0, s50
	v_mov_b32_e32 v165, v1
	global_load_lds_dwordx4 v164, s[20:21]
	s_mov_b32 s4, s89
	v_lshl_add_u64 v[8:9], s[48:49], 0, v[0:1]
	v_lshl_add_u64 v[6:7], s[48:49], 0, v[162:163]
	v_lshl_add_u64 v[4:5], s[26:27], 0, v[166:167]
	s_cmp_lg_u32 s1, 1
	v_lshl_add_u64 v[2:3], s[26:27], 0, v[164:165]
	s_cbranch_scc1 .LBB0_87
.LBB0_87:
	s_lshl_b32 s0, s0, 5
	s_and_b32 s0, s0, 0x60
	s_lshl_b32 s51, s1, 6
	s_lshl_b32 s1, s1, 13
	s_lshl_b32 s29, s0, 7
	s_add_u32 s8, s74, 0x5600
	s_addc_u32 s9, s75, 0
	s_add_u32 s70, s74, 0xac00
	s_addc_u32 s71, s75, 0
	s_add_i32 m0, s81, 0x18000
	v_lshl_add_u64 v[8:9], v[8:9], 0, s[92:93]
	s_waitcnt vmcnt(0)
	s_barrier
	global_load_lds_dwordx4 v[8:9], off
	v_lshl_add_u64 v[6:7], v[6:7], 0, s[92:93]
	s_add_i32 m0, s81, 0x1a000
	s_add_i32 s89, s81, 0x8000
	s_add_i32 s35, s81, 0xa000
	global_load_lds_dwordx4 v[6:7], off
	v_lshl_add_u64 v[4:5], v[4:5], 0, s[92:93]
	s_mov_b32 m0, s89
	s_add_u32 s20, s48, 0x80080
	global_load_lds_dwordx4 v[4:5], off
	v_lshl_add_u64 v[2:3], v[2:3], 0, s[92:93]
	s_mov_b32 m0, s35
	s_addc_u32 s21, s49, 0
	global_load_lds_dwordx4 v[2:3], off
	s_add_i32 m0, s81, 0x1c000
	v_lshl_add_u64 v[2:3], s[20:21], 0, v[0:1]
	global_load_lds_dwordx4 v[2:3], off
	v_lshl_add_u64 v[2:3], s[20:21], 0, v[162:163]
	s_add_i32 m0, s81, 0x1e000
	v_and_b32_e32 v168, 15, v10
	global_load_lds_dwordx4 v[2:3], off
	v_lshrrev_b32_e32 v2, 1, v10
	v_and_b32_e32 v2, 24, v2
	v_lshlrev_b32_e32 v3, 1, v2
	v_lshlrev_b32_e32 v4, 2, v10
	v_or_b32_e32 v194, s0, v2
	v_lshlrev_b32_e32 v2, 15, v15
	v_lshl_or_b32 v3, v168, 6, v3
	v_and_b32_e32 v4, 32, v4
	v_and_b32_e32 v2, 0xffff0000, v2
	v_bitop3_b32 v5, v3, s1, v4 bitop3:0xde
	v_bitop3_b32 v169, v3, s29, v4 bitop3:0xde
	v_lshl_add_u32 v2, v14, 12, v2
	v_and_b32_e32 v3, 1, v15
	v_lshl_or_b32 v2, v3, 6, v2
	v_lshl_add_u32 v172, v16, 1, v2
	v_lshlrev_b32_e32 v2, 15, v11
	v_and_b32_e32 v2, 0xffff0000, v2
	s_waitcnt vmcnt(6)
	v_lshl_add_u32 v2, v12, 12, v2
	v_and_b32_e32 v3, 1, v11
	v_lshl_or_b32 v2, v3, 6, v2
	s_sext_i32_i16 s23, s24
	s_mov_b32 s24, 0
	v_cmp_eq_u32_e64 s[38:39], 0, v168
	v_cmp_lt_u32_e64 s[40:41], 1, v168
	v_cmp_gt_u32_e64 s[42:43], 2, v168
	v_cmp_lt_u32_e64 s[44:45], 13, v168
	v_add_u32_e32 v170, -14, v168
	v_mov_b32_e32 v171, v1
	v_mov_b32_e32 v173, v1
	v_lshl_add_u32 v174, v13, 1, v2
	v_mov_b32_e32 v175, v1
	v_add_u32_e32 v195, 0, v5
	s_barrier
	s_branch .LBB0_89

; #define PG8_STAGE(bufoff, gbase, voff) do { _Pragma("unroll") for (int _i = 0; _i < 2; ++_i) \
;         __builtin_amdgcn_global_load_lds((const unsigned*)((const char*)(gbase) + (voff)[_i]), (LAS unsigned*)(lds + (bufoff) + ldsw + _i * 8192), 16, 0, 0); } while (0)
; #define PG8_LDA(dst, b, h) do { _Pragma("unroll") for (int m = 0; m < 4; ++m) _Pragma("unroll") for (int k = 0; k < 2; ++k) dst[m][k] = *(const LAS h16x8*)(lds + PG8_SA(b, h) + aoff + m * 2048 + k * 1024); } while (0)
; #define PG8_LDB(dst, b, h) do { _Pragma("unroll") for (int n = 0; n < 2; ++n) _Pragma("unroll") for (int k = 0; k < 2; ++k) dst[n][k] = *(const LAS h16x8*)(lds + PG8_SB(b, h) + boff + n * 2048 + k * 1024); } while (0)
; #define PG8_WAIT_V(n) asm volatile("s_waitcnt vmcnt(" #n ")" ::: "memory")
; #define PG8_WAIT_L(n) asm volatile("s_waitcnt lgkmcnt(" #n ")" ::: "memory")
; #define PG8_BAR __builtin_amdgcn_s_barrier()
; #define PG8_SCHED __builtin_amdgcn_sched_barrier(0)
; template <class Epi, class AMap>
; __device__ __forceinline__ void gemm_phase(LAS unsigned char* lds, const AMap am, const int lda, const h16* Bt, const int ldb, const int M, const int N, const int K, const Epi& E) {
;     ...
;         const bool has_next = S.next(ui + 1, nxt);
;         const char* nA = has_next ? am(nxt.pn) + (size_t)nxt.pm * tstepA : cA; const char* nB = has_next ? (const char*)Bt + (size_t)nxt.pn * tstepB : cB;
; #pragma unroll 1
;         for (int t = 0; t < nt; t += 2) {
;             const bool last = (t == nt - 2);
;             const char* a1 = cA + (size_t)(t + 1) * kstep;
;             const char* a2 = last ? nA : cA + (size_t)(t + 2) * kstep; const char* b2 = last ? nB : cB + (size_t)(t + 2) * kstep;
;             const char* a3 = a2 + kstep; const char* b3 = b2 + kstep;
;             PG8_LDB(B0, 0, 0); PG8_SCHED; PG8_LDA(At, 0, 0); PG8_STAGE(PG8_SA(1, 1), a1 + hstepA, voffA);
;             PG8_WAIT_L(8); PG8_BAR; PG8_WAIT_L(0); PG8_MMA(0, 0, At, B0); PG8_BAR; PG8_SCHED;
;             PG8_LDB(B1, 0, 1); PG8_STAGE(PG8_SB(0, 0), b2, voffB);
;             PG8_BAR; PG8_WAIT_L(0); PG8_MMA(0, 1, At, B1); PG8_BAR;
;             PG8_LDA(At, 0, 1); PG8_STAGE(PG8_SA(0, 0), a2, voffA);
;             PG8_BAR; PG8_WAIT_L(0); PG8_MMA(1, 0, At, B0); PG8_BAR; PG8_SCHED;
;             PG8_STAGE(PG8_SB(0, 1), b2 + hstepB, voffB);
;             PG8_WAIT_V(6); PG8_BAR; PG8_MMA(1, 1, At, B1); PG8_BAR;
.LBB0_91:
	s_ashr_i32 s69, s68, 31
	s_lshl_b64 s[20:21], s[68:69], 20
	v_mov_b64_e32 v[2:3], 0xac0
	s_add_u32 s96, s94, s20
	v_cmp_lt_i64_e32 vcc, s[76:77], v[2:3]
	s_addc_u32 s97, s95, s21
	s_and_b64 s[20:21], vcc, exec
	s_cselect_b32 s69, s97, s27
	s_cselect_b32 s29, s96, s26
	s_ashr_i32 s73, s72, 31
	s_lshl_b64 s[20:21], s[72:73], 20
	s_add_u32 s76, s63, s20
	s_addc_u32 s77, s80, s21
	s_and_b64 s[20:21], vcc, exec
	s_cselect_b32 s73, s77, s49
	s_cselect_b32 s20, s76, s48
	s_add_u32 vcc_lo, s26, 0x80080
	s_addc_u32 vcc_hi, s27, 0
	s_add_u32 s21, s48, 0x100
	s_addc_u32 s66, s49, 0
	s_mov_b32 s60, -2
	s_cmpk_lt_u32 s10, 0x100
	s_cbranch_scc1 .Lgy1
	s_barrier
.Lgy1:
.Lg4p_92:
	s_add_u32 s0, vcc_lo, 0xfff80080
	s_addc_u32 s1, vcc_hi, -1
	s_add_i32 s67, 0, 0x10000
	v_add_u32_e32 v226, s67, v169
	ds_read_b128 v[66:69], v226
	ds_read_b128 v[70:73], v226 offset:1024
	ds_read_b128 v[74:77], v226 offset:2048
	ds_read_b128 v[78:81], v226 offset:3072
	s_cmp_eq_u32 s60, 28
	s_cselect_b32 s27, s69, s1
	s_cselect_b32 s26, s29, s0
	s_cselect_b32 s49, s73, s66
	s_cselect_b32 s48, s20, s21
	v_lshl_add_u64 v[192:193], vcc, 0, v[172:173]
	s_add_i32 m0, s81, 0xc000
	ds_read_b128 v[90:93], v195
	ds_read_b128 v[94:97], v195 offset:1024
	ds_read_b128 v[98:101], v195 offset:2048
	ds_read_b128 v[102:105], v195 offset:3072
	ds_read_b128 v[176:179], v195 offset:4096
	ds_read_b128 v[180:183], v195 offset:5120
	ds_read_b128 v[184:187], v195 offset:6144
	ds_read_b128 v[188:191], v195 offset:7168
	global_load_lds_dwordx4 v[192:193], off
	v_lshl_add_u64 v[192:193], vcc, 0, v[174:175]
	s_add_i32 m0, s81, 0xe000
	s_nop 0
	global_load_lds_dwordx4 v[192:193], off
	s_waitcnt lgkmcnt(11)
	s_add_i32 s65, 0, 0x14000
	v_add_u32_e32 v192, s65, v169
	s_add_i32 s0, s67, s64
	ds_read_b128 v[196:199], v192
	ds_read_b128 v[200:203], v192 offset:1024
	ds_read_b128 v[204:207], v192 offset:2048
	ds_read_b128 v[220:223], v192 offset:3072
	s_waitcnt vmcnt(8) lgkmcnt(0)
	s_barrier
	v_mfma_f32_16x16x32_f16 v[158:161], v[66:69], v[90:93], 0
	v_mfma_f32_16x16x32_f16 v[154:157], v[74:77], v[90:93], 0
	v_mfma_f32_16x16x32_f16 v[142:145], v[66:69], v[98:101], 0
	v_mfma_f32_16x16x32_f16 v[134:137], v[74:77], v[98:101], 0
	v_mfma_f32_16x16x32_f16 v[126:129], v[66:69], v[176:179], 0
	v_mfma_f32_16x16x32_f16 v[118:121], v[74:77], v[176:179], 0
	v_mfma_f32_16x16x32_f16 v[110:113], v[66:69], v[184:187], 0
	v_mfma_f32_16x16x32_f16 v[106:109], v[74:77], v[184:187], 0
	v_mfma_f32_16x16x32_f16 v[158:161], v[70:73], v[94:97], v[158:161]
	v_mfma_f32_16x16x32_f16 v[154:157], v[78:81], v[94:97], v[154:157]
	v_mfma_f32_16x16x32_f16 v[142:145], v[70:73], v[102:105], v[142:145]
	v_mfma_f32_16x16x32_f16 v[134:137], v[78:81], v[102:105], v[134:137]
	v_mfma_f32_16x16x32_f16 v[126:129], v[70:73], v[180:183], v[126:129]
	v_mfma_f32_16x16x32_f16 v[118:121], v[78:81], v[180:183], v[118:121]
	v_mfma_f32_16x16x32_f16 v[110:113], v[70:73], v[188:191], v[110:113]
	v_mfma_f32_16x16x32_f16 v[106:109], v[78:81], v[188:191], v[106:109]
	v_mfma_f32_16x16x32_f16 v[150:153], v[196:199], v[90:93], 0
	v_mfma_f32_16x16x32_f16 v[146:149], v[204:207], v[90:93], 0
	v_mfma_f32_16x16x32_f16 v[150:153], v[200:203], v[94:97], v[150:153]
	v_mfma_f32_16x16x32_f16 v[146:149], v[220:223], v[94:97], v[146:149]
	v_mfma_f32_16x16x32_f16 v[138:141], v[196:199], v[98:101], 0
	v_mfma_f32_16x16x32_f16 v[130:133], v[204:207], v[98:101], 0
	v_mfma_f32_16x16x32_f16 v[114:117], v[204:207], v[176:179], 0
	v_mfma_f32_16x16x32_f16 v[86:89], v[196:199], v[184:187], 0
	v_mfma_f32_16x16x32_f16 v[82:85], v[204:207], v[184:187], 0
	v_mfma_f32_16x16x32_f16 v[138:141], v[200:203], v[102:105], v[138:141]
	v_mfma_f32_16x16x32_f16 v[130:133], v[220:223], v[102:105], v[130:133]
	v_mfma_f32_16x16x32_f16 v[122:125], v[196:199], v[176:179], 0
	v_mfma_f32_16x16x32_f16 v[114:117], v[220:223], v[180:183], v[114:117]
	v_mfma_f32_16x16x32_f16 v[86:89], v[200:203], v[188:191], v[86:89]
	v_mfma_f32_16x16x32_f16 v[82:85], v[220:223], v[188:191], v[82:85]
	v_mfma_f32_16x16x32_f16 v[122:125], v[200:203], v[180:183], v[122:125]
	s_barrier
	v_lshl_add_u64 v[192:193], s[48:49], 0, v[0:1]
	s_mov_b32 m0, s0
	v_lshl_add_u64 v[212:213], s[48:49], 0, v[162:163]
	global_load_lds_dwordx4 v[192:193], off
	s_add_i32 m0, s0, 0x2000
	s_nop 0
	global_load_lds_dwordx4 v[212:213], off
	s_mov_b32 m0, s81
	v_lshl_add_u64 v[214:215], s[26:27], 0, v[166:167]
	ds_read_b128 v[90:93], v195 offset:16384
	ds_read_b128 v[94:97], v195 offset:17408
	ds_read_b128 v[98:101], v195 offset:18432
	ds_read_b128 v[102:105], v195 offset:19456
	ds_read_b128 v[176:179], v195 offset:20480
	ds_read_b128 v[180:183], v195 offset:21504
	ds_read_b128 v[184:187], v195 offset:22528
	ds_read_b128 v[188:191], v195 offset:23552
	global_load_lds_dwordx4 v[214:215], off
	v_lshl_add_u64 v[216:217], s[26:27], 0, v[164:165]
	s_mov_b32 m0, s82
	s_nop 0
	global_load_lds_dwordx4 v[216:217], off
	s_add_u32 s0, s48, 0x80000
	s_addc_u32 s1, s49, 0
	s_add_i32 s65, s65, s64
	v_lshl_add_u64 v[224:225], s[0:1], 0, v[0:1]
	s_mov_b32 m0, s65
	s_nop 0
	global_load_lds_dwordx4 v[224:225], off
	v_lshl_add_u64 v[224:225], s[0:1], 0, v[162:163]
	s_add_i32 m0, s65, 0x2000
	s_nop 0
	global_load_lds_dwordx4 v[224:225], off
	s_waitcnt vmcnt(8) lgkmcnt(0)
	s_barrier
; #define PG8_STAGE(bufoff, gbase, voff) do { _Pragma("unroll") for (int _i = 0; _i < 2; ++_i) \
;         __builtin_amdgcn_global_load_lds((const unsigned*)((const char*)(gbase) + (voff)[_i]), (LAS unsigned*)(lds + (bufoff) + ldsw + _i * 8192), 16, 0, 0); } while (0)
; #define PG8_LDA(dst, b, h) do { _Pragma("unroll") for (int m = 0; m < 4; ++m) _Pragma("unroll") for (int k = 0; k < 2; ++k) dst[m][k] = *(const LAS h16x8*)(lds + PG8_SA(b, h) + aoff + m * 2048 + k * 1024); } while (0)
; #define PG8_LDB(dst, b, h) do { _Pragma("unroll") for (int n = 0; n < 2; ++n) _Pragma("unroll") for (int k = 0; k < 2; ++k) dst[n][k] = *(const LAS h16x8*)(lds + PG8_SB(b, h) + boff + n * 2048 + k * 1024); } while (0)
; #define PG8_MMA(ai, bj, At, Bt_) do { __builtin_amdgcn_s_setprio(1); _Pragma("unroll") for (int m = 0; m < 4; ++m) _Pragma("unroll") for (int n = 0; n < 2; ++n) _Pragma("unroll") for (int k = 0; k < 2; ++k) \
;         acc[ai][bj][m][n] = __builtin_amdgcn_mfma_f32_16x16x32_f16(Bt_[n][k], At[m][k], acc[ai][bj][m][n], 0, 0, 0); __builtin_amdgcn_s_setprio(0); } while (0)
; #define PG8_WAIT_V(n) asm volatile("s_waitcnt vmcnt(" #n ")" ::: "memory")
; #define PG8_WAIT_L(n) asm volatile("s_waitcnt lgkmcnt(" #n ")" ::: "memory")
; #define PG8_BAR __builtin_amdgcn_s_barrier()
; #define PG8_SCHED __builtin_amdgcn_sched_barrier(0)
; template <class Epi, class AMap>
; __device__ __forceinline__ void gemm_phase(LAS unsigned char* lds, const AMap am, const int lda, const h16* Bt, const int ldb, const int M, const int N, const int K, const Epi& E) {
;     ...
;             PG8_WAIT_V(6); PG8_BAR; PG8_MMA(1, 1, At, B1); PG8_BAR;
;             PG8_LDB(B0, 1, 0); PG8_SCHED; PG8_LDA(At, 1, 0); PG8_STAGE(PG8_SA(0, 1), a2 + hstepA, voffA);
;             PG8_WAIT_L(8); PG8_BAR; PG8_WAIT_L(0); PG8_MMA(0, 0, At, B0); PG8_BAR; PG8_SCHED;
;             PG8_LDB(B1, 1, 1); PG8_STAGE(PG8_SB(1, 0), b3, voffB);
;             PG8_BAR; PG8_WAIT_L(0); PG8_MMA(0, 1, At, B1); PG8_BAR;
;             PG8_LDA(At, 1, 1); PG8_STAGE(PG8_SA(1, 0), a3, voffA);
;             PG8_BAR; PG8_WAIT_L(0); PG8_MMA(1, 0, At, B0); PG8_BAR; PG8_SCHED;
	v_mfma_f32_16x16x32_f16 v[62:65], v[66:69], v[90:93], 0
	v_mfma_f32_16x16x32_f16 v[58:61], v[74:77], v[90:93], 0
	v_mfma_f32_16x16x32_f16 v[46:49], v[66:69], v[98:101], 0
	v_mfma_f32_16x16x32_f16 v[38:41], v[74:77], v[98:101], 0
	v_mfma_f32_16x16x32_f16 v[30:33], v[66:69], v[176:179], 0
	v_mfma_f32_16x16x32_f16 v[22:25], v[74:77], v[176:179], 0
	v_mfma_f32_16x16x32_f16 v[14:17], v[66:69], v[184:187], 0
	v_mfma_f32_16x16x32_f16 v[10:13], v[74:77], v[184:187], 0
	v_mfma_f32_16x16x32_f16 v[62:65], v[70:73], v[94:97], v[62:65]
	v_mfma_f32_16x16x32_f16 v[58:61], v[78:81], v[94:97], v[58:61]
	v_mfma_f32_16x16x32_f16 v[46:49], v[70:73], v[102:105], v[46:49]
	v_mfma_f32_16x16x32_f16 v[38:41], v[78:81], v[102:105], v[38:41]
	v_mfma_f32_16x16x32_f16 v[30:33], v[70:73], v[180:183], v[30:33]
	v_mfma_f32_16x16x32_f16 v[22:25], v[78:81], v[180:183], v[22:25]
	v_mfma_f32_16x16x32_f16 v[14:17], v[70:73], v[188:191], v[14:17]
	v_mfma_f32_16x16x32_f16 v[10:13], v[78:81], v[188:191], v[10:13]
	v_mfma_f32_16x16x32_f16 v[54:57], v[196:199], v[90:93], 0
	v_mfma_f32_16x16x32_f16 v[50:53], v[204:207], v[90:93], 0
	v_mfma_f32_16x16x32_f16 v[42:45], v[196:199], v[98:101], 0
	v_mfma_f32_16x16x32_f16 v[34:37], v[204:207], v[98:101], 0
	v_mfma_f32_16x16x32_f16 v[26:29], v[196:199], v[176:179], 0
	v_mfma_f32_16x16x32_f16 v[18:21], v[204:207], v[176:179], 0
	v_mfma_f32_16x16x32_f16 v[6:9], v[196:199], v[184:187], 0
	v_mfma_f32_16x16x32_f16 v[2:5], v[204:207], v[184:187], 0
	v_mfma_f32_16x16x32_f16 v[54:57], v[200:203], v[94:97], v[54:57]
	v_mfma_f32_16x16x32_f16 v[50:53], v[220:223], v[94:97], v[50:53]
	v_mfma_f32_16x16x32_f16 v[42:45], v[200:203], v[102:105], v[42:45]
	v_mfma_f32_16x16x32_f16 v[34:37], v[220:223], v[102:105], v[34:37]
	v_mfma_f32_16x16x32_f16 v[26:29], v[200:203], v[180:183], v[26:29]
	v_mfma_f32_16x16x32_f16 v[18:21], v[220:223], v[180:183], v[18:21]
	v_mfma_f32_16x16x32_f16 v[6:9], v[200:203], v[188:191], v[6:9]
	v_mfma_f32_16x16x32_f16 v[2:5], v[220:223], v[188:191], v[2:5]
	s_barrier
	s_add_i32 s65, 0, 0x18000
	v_add_u32_e32 v226, s65, v169
	ds_read_b128 v[66:69], v226
	ds_read_b128 v[70:73], v226 offset:1024
	ds_read_b128 v[74:77], v226 offset:2048
	ds_read_b128 v[78:81], v226 offset:3072
	s_add_u32 s0, s26, 0x80000
	s_addc_u32 s1, s27, 0
	s_mov_b32 m0, s83
	v_lshl_add_u64 v[224:225], s[0:1], 0, v[166:167]
	ds_read_b128 v[90:93], v195 offset:32768
	ds_read_b128 v[94:97], v195 offset:33792
	ds_read_b128 v[98:101], v195 offset:34816
	ds_read_b128 v[102:105], v195 offset:35840
	ds_read_b128 v[176:179], v195 offset:36864
	ds_read_b128 v[180:183], v195 offset:37888
	ds_read_b128 v[184:187], v195 offset:38912
	ds_read_b128 v[188:191], v195 offset:39936
	global_load_lds_dwordx4 v[224:225], off
	v_lshl_add_u64 v[224:225], s[0:1], 0, v[164:165]
	s_mov_b32 m0, s50
	s_nop 0
	global_load_lds_dwordx4 v[224:225], off
	s_waitcnt lgkmcnt(11)
	s_add_i32 s26, 0, 0x1c000
	v_add_u32_e32 v226, s26, v169
	s_add_i32 s0, s65, s64
	ds_read_b128 v[196:199], v226
	ds_read_b128 v[200:203], v226 offset:1024
	ds_read_b128 v[204:207], v226 offset:2048
	ds_read_b128 v[220:223], v226 offset:3072
	s_waitcnt vmcnt(8) lgkmcnt(0)
	s_barrier
	v_mfma_f32_16x16x32_f16 v[158:161], v[66:69], v[90:93], v[158:161]
	v_mfma_f32_16x16x32_f16 v[158:161], v[70:73], v[94:97], v[158:161]
	v_mfma_f32_16x16x32_f16 v[154:157], v[74:77], v[90:93], v[154:157]
	v_mfma_f32_16x16x32_f16 v[154:157], v[78:81], v[94:97], v[154:157]
	v_mfma_f32_16x16x32_f16 v[142:145], v[66:69], v[98:101], v[142:145]
	v_mfma_f32_16x16x32_f16 v[134:137], v[74:77], v[98:101], v[134:137]
	v_mfma_f32_16x16x32_f16 v[126:129], v[66:69], v[176:179], v[126:129]
	v_mfma_f32_16x16x32_f16 v[118:121], v[74:77], v[176:179], v[118:121]
	v_mfma_f32_16x16x32_f16 v[110:113], v[66:69], v[184:187], v[110:113]
	v_mfma_f32_16x16x32_f16 v[106:109], v[74:77], v[184:187], v[106:109]
	v_mfma_f32_16x16x32_f16 v[142:145], v[70:73], v[102:105], v[142:145]
	v_mfma_f32_16x16x32_f16 v[134:137], v[78:81], v[102:105], v[134:137]
	v_mfma_f32_16x16x32_f16 v[126:129], v[70:73], v[180:183], v[126:129]
	v_mfma_f32_16x16x32_f16 v[118:121], v[78:81], v[180:183], v[118:121]
	v_mfma_f32_16x16x32_f16 v[110:113], v[70:73], v[188:191], v[110:113]
	v_mfma_f32_16x16x32_f16 v[106:109], v[78:81], v[188:191], v[106:109]
	v_mfma_f32_16x16x32_f16 v[146:149], v[204:207], v[90:93], v[146:149]
	v_mfma_f32_16x16x32_f16 v[150:153], v[196:199], v[90:93], v[150:153]
	v_mfma_f32_16x16x32_f16 v[146:149], v[220:223], v[94:97], v[146:149]
	v_mfma_f32_16x16x32_f16 v[138:141], v[196:199], v[98:101], v[138:141]
	v_mfma_f32_16x16x32_f16 v[150:153], v[200:203], v[94:97], v[150:153]
	v_mfma_f32_16x16x32_f16 v[138:141], v[200:203], v[102:105], v[138:141]
	v_mfma_f32_16x16x32_f16 v[130:133], v[204:207], v[98:101], v[130:133]
	v_mfma_f32_16x16x32_f16 v[130:133], v[220:223], v[102:105], v[130:133]
	v_mfma_f32_16x16x32_f16 v[122:125], v[196:199], v[176:179], v[122:125]
	v_mfma_f32_16x16x32_f16 v[122:125], v[200:203], v[180:183], v[122:125]
	v_mfma_f32_16x16x32_f16 v[114:117], v[204:207], v[176:179], v[114:117]
	v_mfma_f32_16x16x32_f16 v[86:89], v[196:199], v[184:187], v[86:89]
	v_mfma_f32_16x16x32_f16 v[82:85], v[204:207], v[184:187], v[82:85]
	v_mfma_f32_16x16x32_f16 v[114:117], v[220:223], v[180:183], v[114:117]
	v_mfma_f32_16x16x32_f16 v[86:89], v[200:203], v[188:191], v[86:89]
	v_mfma_f32_16x16x32_f16 v[82:85], v[220:223], v[188:191], v[82:85]
	s_barrier
; #define PG8_STAGE(bufoff, gbase, voff) do { _Pragma("unroll") for (int _i = 0; _i < 2; ++_i) \
;         __builtin_amdgcn_global_load_lds((const unsigned*)((const char*)(gbase) + (voff)[_i]), (LAS unsigned*)(lds + (bufoff) + ldsw + _i * 8192), 16, 0, 0); } while (0)
; #define PG8_MMA(ai, bj, At, Bt_) do { __builtin_amdgcn_s_setprio(1); _Pragma("unroll") for (int m = 0; m < 4; ++m) _Pragma("unroll") for (int n = 0; n < 2; ++n) _Pragma("unroll") for (int k = 0; k < 2; ++k) \
;         acc[ai][bj][m][n] = __builtin_amdgcn_mfma_f32_16x16x32_f16(Bt_[n][k], At[m][k], acc[ai][bj][m][n], 0, 0, 0); __builtin_amdgcn_s_setprio(0); } while (0)
; #define PG8_WAIT_V(n) asm volatile("s_waitcnt vmcnt(" #n ")" ::: "memory")
; #define PG8_WAIT_L(n) asm volatile("s_waitcnt lgkmcnt(" #n ")" ::: "memory")
; #define PG8_BAR __builtin_amdgcn_s_barrier()
; #define PG8_SCHED __builtin_amdgcn_sched_barrier(0)
; template <class Epi, class AMap>
; __device__ __forceinline__ void gemm_phase(LAS unsigned char* lds, const AMap am, const int lda, const h16* Bt, const int ldb, const int M, const int N, const int K, const Epi& E) {
;     ...
;             PG8_BAR; PG8_WAIT_L(0); PG8_MMA(1, 0, At, B0); PG8_BAR; PG8_SCHED;
;             PG8_STAGE(PG8_SB(1, 1), b3 + hstepB, voffB);
;             PG8_WAIT_V(6); PG8_BAR; PG8_MMA(1, 1, At, B1); PG8_BAR;
;         }
	v_lshl_add_u64 v[224:225], v[192:193], 0, s[92:93]
	s_mov_b32 m0, s0
	s_nop 0
	global_load_lds_dwordx4 v[224:225], off
	v_lshl_add_u64 v[224:225], v[212:213], 0, s[92:93]
	s_add_i32 m0, s0, 0x2000
	s_nop 0
	global_load_lds_dwordx4 v[224:225], off
	s_mov_b32 m0, s89
	v_lshl_add_u64 v[192:193], v[214:215], 0, s[92:93]
	ds_read_b128 v[90:93], v195 offset:49152
	ds_read_b128 v[94:97], v195 offset:50176
	ds_read_b128 v[98:101], v195 offset:51200
	ds_read_b128 v[102:105], v195 offset:52224
	ds_read_b128 v[176:179], v195 offset:53248
	ds_read_b128 v[180:183], v195 offset:54272
	ds_read_b128 v[184:187], v195 offset:55296
	ds_read_b128 v[188:191], v195 offset:56320
	global_load_lds_dwordx4 v[192:193], off
	v_lshl_add_u64 v[192:193], v[216:217], 0, s[92:93]
	s_mov_b32 m0, s35
	s_nop 0
	global_load_lds_dwordx4 v[192:193], off
	s_add_u32 s0, s48, 0x80080
	s_addc_u32 s1, s49, 0
	s_add_i32 s26, s26, s64
	v_lshl_add_u64 v[224:225], s[0:1], 0, v[0:1]
	s_mov_b32 m0, s26
	s_nop 0
	global_load_lds_dwordx4 v[224:225], off
	v_lshl_add_u64 v[224:225], s[0:1], 0, v[162:163]
	s_add_i32 m0, s26, 0x2000
	s_nop 0
	global_load_lds_dwordx4 v[224:225], off
	s_add_i32 s60, s60, 2
	s_add_u32 vcc_lo, vcc_lo, 0x100
	s_addc_u32 vcc_hi, vcc_hi, 0
	s_add_u32 s21, s21, 0x100
	s_addc_u32 s66, s66, 0
	s_cmp_gt_u32 s60, 29
	s_waitcnt vmcnt(8) lgkmcnt(0)
	s_barrier
	v_mfma_f32_16x16x32_f16 v[62:65], v[66:69], v[90:93], v[62:65]
	v_mfma_f32_16x16x32_f16 v[58:61], v[74:77], v[90:93], v[58:61]
	v_mfma_f32_16x16x32_f16 v[46:49], v[66:69], v[98:101], v[46:49]
	v_mfma_f32_16x16x32_f16 v[38:41], v[74:77], v[98:101], v[38:41]
	v_mfma_f32_16x16x32_f16 v[30:33], v[66:69], v[176:179], v[30:33]
	v_mfma_f32_16x16x32_f16 v[22:25], v[74:77], v[176:179], v[22:25]
	v_mfma_f32_16x16x32_f16 v[14:17], v[66:69], v[184:187], v[14:17]
	v_mfma_f32_16x16x32_f16 v[10:13], v[74:77], v[184:187], v[10:13]
	v_mfma_f32_16x16x32_f16 v[62:65], v[70:73], v[94:97], v[62:65]
	v_mfma_f32_16x16x32_f16 v[58:61], v[78:81], v[94:97], v[58:61]
	v_mfma_f32_16x16x32_f16 v[46:49], v[70:73], v[102:105], v[46:49]
	v_mfma_f32_16x16x32_f16 v[38:41], v[78:81], v[102:105], v[38:41]
	v_mfma_f32_16x16x32_f16 v[30:33], v[70:73], v[180:183], v[30:33]
	v_mfma_f32_16x16x32_f16 v[22:25], v[78:81], v[180:183], v[22:25]
	v_mfma_f32_16x16x32_f16 v[14:17], v[70:73], v[188:191], v[14:17]
	v_mfma_f32_16x16x32_f16 v[10:13], v[78:81], v[188:191], v[10:13]
	v_mfma_f32_16x16x32_f16 v[54:57], v[196:199], v[90:93], v[54:57]
	v_mfma_f32_16x16x32_f16 v[50:53], v[204:207], v[90:93], v[50:53]
	v_mfma_f32_16x16x32_f16 v[42:45], v[196:199], v[98:101], v[42:45]
	v_mfma_f32_16x16x32_f16 v[34:37], v[204:207], v[98:101], v[34:37]
	v_mfma_f32_16x16x32_f16 v[26:29], v[196:199], v[176:179], v[26:29]
	v_mfma_f32_16x16x32_f16 v[18:21], v[204:207], v[176:179], v[18:21]
	v_mfma_f32_16x16x32_f16 v[6:9], v[196:199], v[184:187], v[6:9]
	v_mfma_f32_16x16x32_f16 v[2:5], v[204:207], v[184:187], v[2:5]
	v_mfma_f32_16x16x32_f16 v[54:57], v[200:203], v[94:97], v[54:57]
	v_mfma_f32_16x16x32_f16 v[50:53], v[220:223], v[94:97], v[50:53]
	v_mfma_f32_16x16x32_f16 v[42:45], v[200:203], v[102:105], v[42:45]
	v_mfma_f32_16x16x32_f16 v[34:37], v[220:223], v[102:105], v[34:37]
	v_mfma_f32_16x16x32_f16 v[26:29], v[200:203], v[180:183], v[26:29]
	v_mfma_f32_16x16x32_f16 v[18:21], v[220:223], v[180:183], v[18:21]
	v_mfma_f32_16x16x32_f16 v[6:9], v[200:203], v[188:191], v[6:9]
	v_mfma_f32_16x16x32_f16 v[2:5], v[220:223], v[188:191], v[2:5]
	s_barrier
	s_cbranch_scc1 .Lg4x_92

; #define PG8_WAIT_V(n) asm volatile("s_waitcnt vmcnt(" #n ")" ::: "memory")
; #define PG8_BAR __builtin_amdgcn_s_barrier()
; template <class Epi, class AMap>
; __device__ __forceinline__ void gemm_phase(LAS unsigned char* lds, const AMap am, const int lda, const h16* Bt, const int ldb, const int M, const int N, const int K, const Epi& E) {
;     ...
;     PG8_WAIT_V(0);
;     if (wr == 0) PG8_BAR;
;     PG8_BAR;
.LBB0_105:
	s_waitcnt vmcnt(0)
	s_cmpk_gt_u32 s10, 0xff
	v_readlane_b32 s29, v254, 37
	s_mov_b32 s89, s4
	s_cbranch_scc1 .LBB0_107
.LBB0_107:
	s_barrier

; __device__ __forceinline__ int otid() { int t = (int)threadIdx.x; asm volatile("" : "+v"(t)); return t; }
; __device__ __forceinline__ int obid() { int t = (int)blockIdx.x; asm volatile("" : "+s"(t)); return t; }
; #define PG8_WAIT_V(n) asm volatile("s_waitcnt vmcnt(" #n ")" ::: "memory")
; #define PG8_BAR __builtin_amdgcn_s_barrier()
; template <class Epi, class AMap>
; __device__ __forceinline__ void gemm_phase(LAS unsigned char* lds, const AMap am, const int lda, const h16* Bt, const int ldb, const int M, const int N, const int K, const Epi& E) {
;     const int tid = otid(), wid = __builtin_amdgcn_readfirstlane(tid >> 6), lane = tid & 63, wr = wid >> 2, wc = wid & 3, fr = lane & 15, fq = lane >> 4;
;     const int nt = K / BK;
;     Order S; S.init(M, N, (int)gridDim.x, obid());
;     unsigned voffA[2], voffB[2];
; #pragma unroll
;     for (int i = 0; i < 2; ++i) { int R, C; stage_rc(tid * 16 + i * 8192, R, C); const int Rb = Epi::PERM ? ((R & ~31) + perm32(R & 31)) : R;
;         voffA[i] = (unsigned)(R * lda + C) * 2u; voffB[i] = (unsigned)(Rb * ldb + C) * 2u; }
;     const size_t kstep = (size_t)(BK * 2);
;     const size_t hstepA = (size_t)HALF * lda * 2, hstepB = (size_t)HALF * ldb * 2;
;     const size_t tstepA = 2 * hstepA, tstepB = 2 * hstepB;
;     const unsigned ldsw = (unsigned)wid * 1024u;
;     const int aoff = lds_byte(wr * 64 + fr, fq * 8), boff = lds_byte(wc * 32 + fr, fq * 8);
;     ...
;     Unit cur, nxt; int ui = 0;
;     if (!S.next(0, cur)) return;
;     f32x4 acc[2][2][4][2];
; #pragma unroll
;     for (int a = 0; a < 2; ++a)
; #pragma unroll
;         for (int b = 0; b < 2; ++b)
; #pragma unroll
;             for (int m = 0; m < 4; ++m)
; #pragma unroll
;                 for (int n = 0; n < 2; ++n) acc[a][b][m][n] = (f32x4){0.f, 0.f, 0.f, 0.f};
;     h16x8 At[4][2], B0[2][2], B1[2][2];
;     const char* cA = am(cur.pn) + (size_t)cur.pm * tstepA; const char* cB = (const char*)Bt + (size_t)cur.pn * tstepB;
;     PG8_STAGE(PG8_SB(0, 0), cB, voffB); PG8_STAGE(PG8_SA(0, 0), cA, voffA); PG8_STAGE(PG8_SB(0, 1), cB + hstepB, voffB); PG8_STAGE(PG8_SA(0, 1), cA + hstepA, voffA);
;     if (wr == 1) PG8_BAR;
;     PG8_WAIT_V(4); PG8_BAR;
;     PG8_STAGE(PG8_SB(1, 0), cB + kstep, voffB); PG8_STAGE(PG8_SA(1, 0), cA + kstep, voffA); PG8_STAGE(PG8_SB(1, 1), cB + hstepB + kstep, voffB);
;     PG8_WAIT_V(6); PG8_BAR;
.LBB0_137:
	v_ashrrev_i32_e32 v0, 31, v8
	v_lshrrev_b32_e32 v0, 26, v0
	v_add_u32_e32 v0, v8, v0
	v_ashrrev_i32_e32 v2, 6, v0
	v_bfe_i32 v0, v8, 27, 1
	v_lshlrev_b32_e32 v5, 4, v8
	v_lshrrev_b32_e32 v0, 22, v0
	v_add_u32_e32 v0, v5, v0
	v_and_b32_e32 v0, 0xfffffc00, v0
	v_sub_u32_e32 v0, v5, v0
	v_lshrrev_b32_e32 v3, 4, v0
	v_bitop3_b32 v4, v3, v0, 32 bitop3:0x6c
	v_ashrrev_i32_e32 v0, 31, v0
	v_lshrrev_b32_e32 v0, 26, v0
	v_lshlrev_b32_e32 v3, 3, v2
	v_add_u32_e32 v0, v4, v0
	v_and_b32_e32 v6, -16, v3
	v_ashrrev_i32_e32 v3, 6, v0
	v_mul_i32_i24_e32 v7, 64, v3
	v_add_u32_e32 v0, v3, v6
	v_sub_u32_e32 v4, v4, v7
	v_mov_b32_e32 v12, 1
	v_lshlrev_b32_e32 v6, 5, v2
	v_ashrrev_i16_sdwa v4, v12, sext(v4) dst_sel:DWORD dst_unused:UNUSED_PAD src0_sel:DWORD src1_sel:BYTE_0
	v_lshlrev_b32_e32 v7, 1, v0
	v_lshrrev_b32_e32 v9, 2, v0
	v_and_b32_e32 v10, 3, v3
	s_mov_b32 s2, 0xfffe0
	v_and_b32_e32 v6, 32, v6
	v_bfe_i32 v4, v4, 0, 16
	v_and_b32_e32 v7, 24, v7
	v_and_b32_e32 v9, 4, v9
	v_and_or_b32 v10, v0, s2, v10
	v_or3_b32 v7, v10, v9, v7
	v_add_lshl_u32 v6, v6, v4, 1
	v_lshl_add_u32 v130, v0, 12, v6
	v_lshl_add_u32 v0, v7, 12, v6
	v_add_u32_e32 v6, 0x2000, v5
	v_ashrrev_i32_e32 v5, 31, v6
	v_lshrrev_b32_e32 v5, 22, v5
	v_add_u32_e32 v5, v6, v5
	v_ashrrev_i32_e32 v5, 10, v5
	v_mul_i32_i24_e32 v7, 0x400, v5
	v_sub_u32_e32 v6, v6, v7
	v_lshrrev_b32_e32 v7, 4, v6
	v_bitop3_b32 v7, v7, v6, 32 bitop3:0x6c
	v_lshlrev_b32_e32 v6, 3, v5
	v_and_b32_e32 v9, -16, v6
	v_ashrrev_i32_e32 v6, 31, v7
	s_ashr_i32 s1, s62, 6
	v_lshrrev_b32_e32 v6, 26, v6
	v_add_u32_e32 v10, v7, v6
	s_ashr_i32 s20, s62, 8
	s_lshl_b32 s64, s1, 10
	v_ashrrev_i32_e32 v6, 6, v10
	s_add_u32 s65, s3, 0x2000000
	v_add_u32_e32 v9, v6, v9
	v_and_b32_e32 v13, 3, v6
	s_addc_u32 s68, s6, 0
	v_readlane_b32 s6, v254, 56
	v_and_or_b32 v13, v9, s2, v13
	s_and_b64 s[22:23], s[78:79], exec
	v_readlane_b32 s2, v251, 12
	v_readlane_b32 s7, v254, 57
	s_cselect_b32 s69, s2, s7
	v_readlane_b32 s2, v251, 11
	s_cselect_b32 s70, s2, s6
	s_add_i32 s0, s21, s0
	s_ashr_i32 s21, s0, 31
	s_lshr_b32 s21, s21, 27
	s_add_i32 s21, s0, s21
	s_ashr_i32 s22, s21, 5
	s_and_b32 s21, s21, 0xffe0
	s_sub_i32 s21, s0, s21
	s_bfe_i32 s0, s21, 0x80000
	s_bfe_u32 s0, s0, 0x2000d
	s_add_i32 s23, s21, s0
	s_bfe_i32 s0, s23, 0x80000
	s_and_b32 s23, s23, 0xfc
	s_sub_i32 s21, s21, s23
	s_lshl_b32 s22, s22, 2
	s_sext_i32_i16 s0, s0
	s_sext_i32_i8 s21, s21
	s_lshr_b32 s0, s0, 2
	s_add_i32 s22, s22, s21
	s_ashr_i32 s23, s22, 31
	s_bfe_i64 s[38:39], s[0:1], 0x100000
	v_and_b32_e32 v10, 0xc0, v10
	s_lshl_b64 s[26:27], s[22:23], 20
	s_lshl_b64 s[38:39], s[38:39], 20
	v_sub_u32_e32 v7, v7, v10
	s_add_u32 s46, s65, s38
	v_lshlrev_b32_e32 v11, 5, v5
	v_ashrrev_i16_sdwa v7, v12, sext(v7) dst_sel:DWORD dst_unused:UNUSED_PAD src0_sel:DWORD src1_sel:BYTE_0
	v_lshlrev_b32_e32 v10, 1, v9
	v_lshrrev_b32_e32 v12, 2, v9
	s_addc_u32 s47, s68, s39
	s_add_i32 s23, s64, 0
	v_and_b32_e32 v11, 32, v11
	v_bfe_i32 v7, v7, 0, 16
	v_and_b32_e32 v10, 24, v10
	v_and_b32_e32 v12, 4, v12
	s_add_i32 m0, s23, 0x10000
	v_or3_b32 v10, v13, v12, v10
	v_add_lshl_u32 v11, v11, v7, 1
	global_load_lds_dwordx4 v0, s[46:47]
	s_add_i32 m0, s23, 0x12000
	v_lshl_add_u32 v134, v10, 12, v11
	s_add_u32 s26, s70, s26
	global_load_lds_dwordx4 v134, s[46:47]
	s_addc_u32 s27, s69, s27
	s_mov_b32 m0, s23
	s_add_i32 s71, s23, 0x2000
	v_lshl_add_u32 v132, v9, 12, v11
	global_load_lds_dwordx4 v130, s[26:27]
	s_mov_b32 m0, s71
	s_add_u32 s38, s46, 0x80000
	global_load_lds_dwordx4 v132, s[26:27]
	s_addc_u32 s39, s47, 0
	s_add_i32 m0, s23, 0x14000
	s_nop 0
	global_load_lds_dwordx4 v0, s[38:39]
	s_add_i32 m0, s23, 0x16000
	s_nop 0
	global_load_lds_dwordx4 v134, s[38:39]
	s_add_u32 s38, s26, 0x80000
	s_addc_u32 s39, s27, 0
	s_add_i32 s72, s23, 0x4000
	s_mov_b32 m0, s72
	s_add_i32 s73, s23, 0x6000
	global_load_lds_dwordx4 v130, s[38:39]
	s_mov_b32 m0, s73
	s_cmp_lg_u32 s20, 1
	global_load_lds_dwordx4 v132, s[38:39]
	s_cbranch_scc1 .LBB0_139
.LBB0_139:
	v_lshrrev_b32_e32 v18, 1, v8
	v_and_b32_e32 v18, 24, v18
	v_and_b32_e32 v9, 15, v8
	v_lshlrev_b32_e32 v19, 1, v18
	v_lshlrev_b32_e32 v8, 2, v8
	s_sext_i32_i8 s35, s0
	v_lshl_or_b32 v146, s20, 6, v9
	v_lshl_or_b32 v9, v9, 6, v19
	s_lshl_b32 s0, s20, 13
	v_and_b32_e32 v8, 32, v8
	v_bitop3_b32 v19, v9, s0, v8 bitop3:0xde
	s_lshl_b32 s0, s1, 5
	s_and_b32 s20, s0, 0x60
	v_lshl_add_u64 v[10:11], s[46:47], 0, v[0:1]
	v_mov_b32_e32 v135, v1
	s_lshl_b32 s0, s20, 7
	v_lshl_add_u64 v[12:13], s[46:47], 0, v[134:135]
	v_mov_b32_e32 v131, v1
	v_bitop3_b32 v147, v9, s0, v8 bitop3:0xde
	s_add_i32 m0, s23, 0x18000
	v_lshl_add_u64 v[8:9], v[10:11], 0, s[92:93]
	v_lshl_add_u64 v[14:15], s[26:27], 0, v[130:131]
	v_mov_b32_e32 v133, v1
	s_waitcnt vmcnt(0)
	s_barrier
	global_load_lds_dwordx4 v[8:9], off
	v_lshl_add_u64 v[8:9], v[12:13], 0, s[92:93]
	s_add_i32 m0, s23, 0x1a000
	s_add_i32 s74, s23, 0x8000
	s_add_i32 s75, s23, 0xa000
	v_lshl_add_u64 v[16:17], s[26:27], 0, v[132:133]
	global_load_lds_dwordx4 v[8:9], off
	v_lshl_add_u64 v[8:9], v[14:15], 0, s[92:93]
	s_mov_b32 m0, s74
	s_add_u32 s0, s46, 0x80080
	global_load_lds_dwordx4 v[8:9], off
	v_lshl_add_u64 v[8:9], v[16:17], 0, s[92:93]
	s_mov_b32 m0, s75
	s_addc_u32 s1, s47, 0
	global_load_lds_dwordx4 v[8:9], off
	s_add_i32 m0, s23, 0x1c000
	v_lshl_add_u64 v[8:9], s[0:1], 0, v[0:1]
	global_load_lds_dwordx4 v[8:9], off
	v_lshl_add_u64 v[8:9], s[0:1], 0, v[134:135]
	s_add_i32 m0, s23, 0x1e000
	v_or_b32_e32 v148, s20, v18
	global_load_lds_dwordx4 v[8:9], off
	v_lshlrev_b32_e32 v8, 15, v2
	v_and_b32_e32 v8, 0xffff0000, v8
	v_lshl_add_u32 v3, v3, 12, v8
	v_and_b32_e32 v2, 1, v2
	v_lshl_or_b32 v2, v2, 6, v3
	v_lshl_add_u32 v136, v4, 1, v2
	v_lshlrev_b32_e32 v2, 15, v5
	v_and_b32_e32 v2, 0xffff0000, v2
	s_waitcnt vmcnt(6)
	v_lshl_add_u32 v2, v6, 12, v2
	v_and_b32_e32 v3, 1, v5
	v_lshl_or_b32 v2, v3, 6, v2
	v_mov_b32_e32 v137, v1
	v_lshl_add_u32 v138, v7, 1, v2
	v_mov_b32_e32 v139, v1
	s_mov_b32 s76, 0
	v_add_u32_e32 v149, 0, v19
	s_barrier

; #define PG8_STAGE(bufoff, gbase, voff) do { _Pragma("unroll") for (int _i = 0; _i < 2; ++_i) \
;         __builtin_amdgcn_global_load_lds((const unsigned*)((const char*)(gbase) + (voff)[_i]), (LAS unsigned*)(lds + (bufoff) + ldsw + _i * 8192), 16, 0, 0); } while (0)
; #define PG8_LDA(dst, b, h) do { _Pragma("unroll") for (int m = 0; m < 4; ++m) _Pragma("unroll") for (int k = 0; k < 2; ++k) dst[m][k] = *(const LAS h16x8*)(lds + PG8_SA(b, h) + aoff + m * 2048 + k * 1024); } while (0)
; #define PG8_LDB(dst, b, h) do { _Pragma("unroll") for (int n = 0; n < 2; ++n) _Pragma("unroll") for (int k = 0; k < 2; ++k) dst[n][k] = *(const LAS h16x8*)(lds + PG8_SB(b, h) + boff + n * 2048 + k * 1024); } while (0)
; #define PG8_WAIT_V(n) asm volatile("s_waitcnt vmcnt(" #n ")" ::: "memory")
; #define PG8_WAIT_L(n) asm volatile("s_waitcnt lgkmcnt(" #n ")" ::: "memory")
; #define PG8_BAR __builtin_amdgcn_s_barrier()
; #define PG8_SCHED __builtin_amdgcn_sched_barrier(0)
; template <class Epi, class AMap>
; __device__ __forceinline__ void gemm_phase(LAS unsigned char* lds, const AMap am, const int lda, const h16* Bt, const int ldb, const int M, const int N, const int K, const Epi& E) {
;     ...
;         const bool has_next = S.next(ui + 1, nxt);
;         const char* nA = has_next ? am(nxt.pn) + (size_t)nxt.pm * tstepA : cA; const char* nB = has_next ? (const char*)Bt + (size_t)nxt.pn * tstepB : cB;
; #pragma unroll 1
;         for (int t = 0; t < nt; t += 2) {
;             const bool last = (t == nt - 2);
;             const char* a1 = cA + (size_t)(t + 1) * kstep;
;             const char* a2 = last ? nA : cA + (size_t)(t + 2) * kstep; const char* b2 = last ? nB : cB + (size_t)(t + 2) * kstep;
;             const char* a3 = a2 + kstep; const char* b3 = b2 + kstep;
;             PG8_LDB(B0, 0, 0); PG8_SCHED; PG8_LDA(At, 0, 0); PG8_STAGE(PG8_SA(1, 1), a1 + hstepA, voffA);
;             PG8_WAIT_L(8); PG8_BAR; PG8_WAIT_L(0); PG8_MMA(0, 0, At, B0); PG8_BAR; PG8_SCHED;
;             PG8_LDB(B1, 0, 1); PG8_STAGE(PG8_SB(0, 0), b2, voffB);
;             PG8_BAR; PG8_WAIT_L(0); PG8_MMA(0, 1, At, B1); PG8_BAR;
;             PG8_LDA(At, 0, 1); PG8_STAGE(PG8_SA(0, 0), a2, voffA);
;             PG8_BAR; PG8_WAIT_L(0); PG8_MMA(1, 0, At, B0); PG8_BAR; PG8_SCHED;
;             PG8_STAGE(PG8_SB(0, 1), b2 + hstepB, voffB);
;             PG8_WAIT_V(6); PG8_BAR; PG8_MMA(1, 1, At, B1); PG8_BAR;
.LBB0_146:
	s_ashr_i32 s41, s40, 31
	s_lshl_b64 s[20:21], s[40:41], 20
	v_cmp_lt_i64_e32 vcc, s[42:43], v[208:209]
	s_add_u32 s42, s70, s20
	s_addc_u32 s43, s69, s21
	s_and_b64 s[20:21], vcc, exec
	s_cselect_b32 s41, s43, s27
	s_cselect_b32 s29, s42, s26
	s_ashr_i32 s1, s0, 31
	s_lshl_b64 s[20:21], s[0:1], 20
	s_add_u32 s44, s65, s20
	s_addc_u32 s45, s68, s21
	s_and_b64 s[20:21], vcc, exec
	s_cselect_b32 s1, s45, s47
	s_cselect_b32 s20, s44, s46
	s_add_u32 s26, s26, 0x80080
	s_addc_u32 s27, s27, 0
	s_add_u32 s21, s46, 0x100
	s_addc_u32 s50, s47, 0
	s_mov_b32 s51, -2
	s_cmpk_lt_u32 s62, 0x100
	s_cbranch_scc1 .Lgy2
	s_barrier
.Lgy2:
.Lg4p_147:
	s_add_u32 s46, s26, 0xfff80080
	s_addc_u32 s47, s27, -1
	s_add_i32 s60, 0, 0x10000
	v_add_u32_e32 v144, s60, v147
	ds_read_b128 v[140:143], v144
	ds_read_b128 v[150:153], v144 offset:1024
	ds_read_b128 v[154:157], v144 offset:2048
	ds_read_b128 v[158:161], v144 offset:3072
	s_cmp_eq_u32 s51, 28
	s_cselect_b32 s49, s41, s47
	s_cselect_b32 s48, s29, s46
	s_cselect_b32 s47, s1, s50
	s_cselect_b32 s46, s20, s21
	v_lshl_add_u64 v[144:145], s[26:27], 0, v[136:137]
	s_add_i32 m0, s23, 0xc000
	ds_read_b128 v[162:165], v149
	ds_read_b128 v[166:169], v149 offset:1024
	ds_read_b128 v[170:173], v149 offset:2048
	ds_read_b128 v[174:177], v149 offset:3072
	ds_read_b128 v[178:181], v149 offset:4096
	ds_read_b128 v[182:185], v149 offset:5120
	ds_read_b128 v[186:189], v149 offset:6144
	ds_read_b128 v[190:193], v149 offset:7168
	global_load_lds_dwordx4 v[144:145], off
	v_lshl_add_u64 v[144:145], s[26:27], 0, v[138:139]
	s_add_i32 m0, s23, 0xe000
	s_nop 0
	global_load_lds_dwordx4 v[144:145], off
	s_waitcnt lgkmcnt(11)
	s_add_i32 s66, 0, 0x14000
	v_add_u32_e32 v144, s66, v147
	s_add_i32 s60, s60, s64
	ds_read_b128 v[194:197], v144
	ds_read_b128 v[198:201], v144 offset:1024
	ds_read_b128 v[202:205], v144 offset:2048
	ds_read_b128 v[220:223], v144 offset:3072
	s_waitcnt vmcnt(8) lgkmcnt(0)
	s_barrier
	v_mfma_f32_16x16x32_f16 v[126:129], v[140:143], v[162:165], 0
	v_mfma_f32_16x16x32_f16 v[122:125], v[154:157], v[162:165], 0
	v_mfma_f32_16x16x32_f16 v[110:113], v[140:143], v[170:173], 0
	v_mfma_f32_16x16x32_f16 v[106:109], v[154:157], v[170:173], 0
	v_mfma_f32_16x16x32_f16 v[94:97], v[140:143], v[178:181], 0
	v_mfma_f32_16x16x32_f16 v[90:93], v[154:157], v[178:181], 0
	v_mfma_f32_16x16x32_f16 v[78:81], v[140:143], v[186:189], 0
	v_mfma_f32_16x16x32_f16 v[74:77], v[154:157], v[186:189], 0
	v_mfma_f32_16x16x32_f16 v[126:129], v[150:153], v[166:169], v[126:129]
	v_mfma_f32_16x16x32_f16 v[122:125], v[158:161], v[166:169], v[122:125]
	v_mfma_f32_16x16x32_f16 v[110:113], v[150:153], v[174:177], v[110:113]
	v_mfma_f32_16x16x32_f16 v[106:109], v[158:161], v[174:177], v[106:109]
	v_mfma_f32_16x16x32_f16 v[94:97], v[150:153], v[182:185], v[94:97]
	v_mfma_f32_16x16x32_f16 v[90:93], v[158:161], v[182:185], v[90:93]
	v_mfma_f32_16x16x32_f16 v[78:81], v[150:153], v[190:193], v[78:81]
	v_mfma_f32_16x16x32_f16 v[74:77], v[158:161], v[190:193], v[74:77]
	v_mfma_f32_16x16x32_f16 v[118:121], v[194:197], v[162:165], 0
	v_mfma_f32_16x16x32_f16 v[114:117], v[202:205], v[162:165], 0
	v_mfma_f32_16x16x32_f16 v[102:105], v[194:197], v[170:173], 0
	v_mfma_f32_16x16x32_f16 v[98:101], v[202:205], v[170:173], 0
	v_mfma_f32_16x16x32_f16 v[86:89], v[194:197], v[178:181], 0
	v_mfma_f32_16x16x32_f16 v[82:85], v[202:205], v[178:181], 0
	v_mfma_f32_16x16x32_f16 v[70:73], v[194:197], v[186:189], 0
	v_mfma_f32_16x16x32_f16 v[66:69], v[202:205], v[186:189], 0
	v_mfma_f32_16x16x32_f16 v[118:121], v[198:201], v[166:169], v[118:121]
	v_mfma_f32_16x16x32_f16 v[114:117], v[220:223], v[166:169], v[114:117]
	v_mfma_f32_16x16x32_f16 v[102:105], v[198:201], v[174:177], v[102:105]
	v_mfma_f32_16x16x32_f16 v[98:101], v[220:223], v[174:177], v[98:101]
	v_mfma_f32_16x16x32_f16 v[86:89], v[198:201], v[182:185], v[86:89]
	v_mfma_f32_16x16x32_f16 v[82:85], v[220:223], v[182:185], v[82:85]
	v_mfma_f32_16x16x32_f16 v[70:73], v[198:201], v[190:193], v[70:73]
	v_mfma_f32_16x16x32_f16 v[66:69], v[220:223], v[190:193], v[66:69]
	s_barrier
	v_lshl_add_u64 v[144:145], s[46:47], 0, v[0:1]
	s_mov_b32 m0, s60
	v_lshl_add_u64 v[206:207], s[46:47], 0, v[134:135]
	global_load_lds_dwordx4 v[144:145], off
	s_add_i32 m0, s60, 0x2000
	s_nop 0
	global_load_lds_dwordx4 v[206:207], off
	s_mov_b32 m0, s23
	v_lshl_add_u64 v[212:213], s[48:49], 0, v[130:131]
	ds_read_b128 v[162:165], v149 offset:16384
	ds_read_b128 v[166:169], v149 offset:17408
	ds_read_b128 v[170:173], v149 offset:18432
	ds_read_b128 v[174:177], v149 offset:19456
	ds_read_b128 v[178:181], v149 offset:20480
	ds_read_b128 v[182:185], v149 offset:21504
	ds_read_b128 v[186:189], v149 offset:22528
	ds_read_b128 v[190:193], v149 offset:23552
	global_load_lds_dwordx4 v[212:213], off
	v_lshl_add_u64 v[214:215], s[48:49], 0, v[132:133]
	s_mov_b32 m0, s71
	s_nop 0
	global_load_lds_dwordx4 v[214:215], off
	s_add_u32 s78, s46, 0x80000
	s_addc_u32 s79, s47, 0
	s_add_i32 s60, s66, s64
	v_lshl_add_u64 v[232:233], s[78:79], 0, v[0:1]
	s_mov_b32 m0, s60
	s_nop 0
	global_load_lds_dwordx4 v[232:233], off
	v_lshl_add_u64 v[232:233], s[78:79], 0, v[134:135]
	s_add_i32 m0, s60, 0x2000
	s_nop 0
	global_load_lds_dwordx4 v[232:233], off
	s_waitcnt vmcnt(8) lgkmcnt(0)
	s_barrier
; #define PG8_STAGE(bufoff, gbase, voff) do { _Pragma("unroll") for (int _i = 0; _i < 2; ++_i) \
;         __builtin_amdgcn_global_load_lds((const unsigned*)((const char*)(gbase) + (voff)[_i]), (LAS unsigned*)(lds + (bufoff) + ldsw + _i * 8192), 16, 0, 0); } while (0)
; #define PG8_LDA(dst, b, h) do { _Pragma("unroll") for (int m = 0; m < 4; ++m) _Pragma("unroll") for (int k = 0; k < 2; ++k) dst[m][k] = *(const LAS h16x8*)(lds + PG8_SA(b, h) + aoff + m * 2048 + k * 1024); } while (0)
; #define PG8_LDB(dst, b, h) do { _Pragma("unroll") for (int n = 0; n < 2; ++n) _Pragma("unroll") for (int k = 0; k < 2; ++k) dst[n][k] = *(const LAS h16x8*)(lds + PG8_SB(b, h) + boff + n * 2048 + k * 1024); } while (0)
; #define PG8_MMA(ai, bj, At, Bt_) do { __builtin_amdgcn_s_setprio(1); _Pragma("unroll") for (int m = 0; m < 4; ++m) _Pragma("unroll") for (int n = 0; n < 2; ++n) _Pragma("unroll") for (int k = 0; k < 2; ++k) \
;         acc[ai][bj][m][n] = __builtin_amdgcn_mfma_f32_16x16x32_f16(Bt_[n][k], At[m][k], acc[ai][bj][m][n], 0, 0, 0); __builtin_amdgcn_s_setprio(0); } while (0)
; #define PG8_WAIT_V(n) asm volatile("s_waitcnt vmcnt(" #n ")" ::: "memory")
; #define PG8_WAIT_L(n) asm volatile("s_waitcnt lgkmcnt(" #n ")" ::: "memory")
; #define PG8_BAR __builtin_amdgcn_s_barrier()
; #define PG8_SCHED __builtin_amdgcn_sched_barrier(0)
; template <class Epi, class AMap>
; __device__ __forceinline__ void gemm_phase(LAS unsigned char* lds, const AMap am, const int lda, const h16* Bt, const int ldb, const int M, const int N, const int K, const Epi& E) {
;     ...
;             PG8_WAIT_V(6); PG8_BAR; PG8_MMA(1, 1, At, B1); PG8_BAR;
;             PG8_LDB(B0, 1, 0); PG8_SCHED; PG8_LDA(At, 1, 0); PG8_STAGE(PG8_SA(0, 1), a2 + hstepA, voffA);
;             PG8_WAIT_L(8); PG8_BAR; PG8_WAIT_L(0); PG8_MMA(0, 0, At, B0); PG8_BAR; PG8_SCHED;
;             PG8_LDB(B1, 1, 1); PG8_STAGE(PG8_SB(1, 0), b3, voffB);
;             PG8_BAR; PG8_WAIT_L(0); PG8_MMA(0, 1, At, B1); PG8_BAR;
;             PG8_LDA(At, 1, 1); PG8_STAGE(PG8_SA(1, 0), a3, voffA);
;             PG8_BAR; PG8_WAIT_L(0); PG8_MMA(1, 0, At, B0); PG8_BAR; PG8_SCHED;
	v_mfma_f32_16x16x32_f16 v[62:65], v[140:143], v[162:165], 0
	v_mfma_f32_16x16x32_f16 v[58:61], v[154:157], v[162:165], 0
	v_mfma_f32_16x16x32_f16 v[46:49], v[140:143], v[170:173], 0
	v_mfma_f32_16x16x32_f16 v[42:45], v[154:157], v[170:173], 0
	v_mfma_f32_16x16x32_f16 v[30:33], v[140:143], v[178:181], 0
	v_mfma_f32_16x16x32_f16 v[26:29], v[154:157], v[178:181], 0
	v_mfma_f32_16x16x32_f16 v[14:17], v[140:143], v[186:189], 0
	v_mfma_f32_16x16x32_f16 v[10:13], v[154:157], v[186:189], 0
	v_mfma_f32_16x16x32_f16 v[62:65], v[150:153], v[166:169], v[62:65]
	v_mfma_f32_16x16x32_f16 v[58:61], v[158:161], v[166:169], v[58:61]
	v_mfma_f32_16x16x32_f16 v[46:49], v[150:153], v[174:177], v[46:49]
	v_mfma_f32_16x16x32_f16 v[42:45], v[158:161], v[174:177], v[42:45]
	v_mfma_f32_16x16x32_f16 v[30:33], v[150:153], v[182:185], v[30:33]
	v_mfma_f32_16x16x32_f16 v[26:29], v[158:161], v[182:185], v[26:29]
	v_mfma_f32_16x16x32_f16 v[14:17], v[150:153], v[190:193], v[14:17]
	v_mfma_f32_16x16x32_f16 v[10:13], v[158:161], v[190:193], v[10:13]
	v_mfma_f32_16x16x32_f16 v[54:57], v[194:197], v[162:165], 0
	v_mfma_f32_16x16x32_f16 v[50:53], v[202:205], v[162:165], 0
	v_mfma_f32_16x16x32_f16 v[38:41], v[194:197], v[170:173], 0
	v_mfma_f32_16x16x32_f16 v[34:37], v[202:205], v[170:173], 0
	v_mfma_f32_16x16x32_f16 v[22:25], v[194:197], v[178:181], 0
	v_mfma_f32_16x16x32_f16 v[18:21], v[202:205], v[178:181], 0
	v_mfma_f32_16x16x32_f16 v[6:9], v[194:197], v[186:189], 0
	v_mfma_f32_16x16x32_f16 v[2:5], v[202:205], v[186:189], 0
	v_mfma_f32_16x16x32_f16 v[54:57], v[198:201], v[166:169], v[54:57]
	v_mfma_f32_16x16x32_f16 v[50:53], v[220:223], v[166:169], v[50:53]
	v_mfma_f32_16x16x32_f16 v[38:41], v[198:201], v[174:177], v[38:41]
	v_mfma_f32_16x16x32_f16 v[34:37], v[220:223], v[174:177], v[34:37]
	v_mfma_f32_16x16x32_f16 v[22:25], v[198:201], v[182:185], v[22:25]
	v_mfma_f32_16x16x32_f16 v[18:21], v[220:223], v[182:185], v[18:21]
	v_mfma_f32_16x16x32_f16 v[6:9], v[198:201], v[190:193], v[6:9]
	v_mfma_f32_16x16x32_f16 v[2:5], v[220:223], v[190:193], v[2:5]
	s_barrier
	s_add_i32 s60, 0, 0x18000
	v_add_u32_e32 v234, s60, v147
	ds_read_b128 v[140:143], v234
	ds_read_b128 v[150:153], v234 offset:1024
	ds_read_b128 v[154:157], v234 offset:2048
	ds_read_b128 v[158:161], v234 offset:3072
	s_add_u32 s48, s48, 0x80000
	s_addc_u32 s49, s49, 0
	s_mov_b32 m0, s72
	v_lshl_add_u64 v[232:233], s[48:49], 0, v[130:131]
	ds_read_b128 v[162:165], v149 offset:32768
	ds_read_b128 v[166:169], v149 offset:33792
	ds_read_b128 v[170:173], v149 offset:34816
	ds_read_b128 v[174:177], v149 offset:35840
	ds_read_b128 v[178:181], v149 offset:36864
	ds_read_b128 v[182:185], v149 offset:37888
	ds_read_b128 v[186:189], v149 offset:38912
	ds_read_b128 v[190:193], v149 offset:39936
	global_load_lds_dwordx4 v[232:233], off
	v_lshl_add_u64 v[232:233], s[48:49], 0, v[132:133]
	s_mov_b32 m0, s73
	s_nop 0
	global_load_lds_dwordx4 v[232:233], off
	s_waitcnt lgkmcnt(11)
	s_add_i32 s48, 0, 0x1c000
	s_add_i32 s49, s60, s64
	v_add_u32_e32 v216, s48, v147
	v_lshl_add_u64 v[144:145], v[144:145], 0, s[92:93]
	s_mov_b32 m0, s49
	ds_read_b128 v[194:197], v216
	ds_read_b128 v[198:201], v216 offset:1024
	ds_read_b128 v[202:205], v216 offset:2048
	ds_read_b128 v[220:223], v216 offset:3072
	s_waitcnt vmcnt(8) lgkmcnt(0)
	s_barrier
	v_mfma_f32_16x16x32_f16 v[126:129], v[140:143], v[162:165], v[126:129]
	v_mfma_f32_16x16x32_f16 v[122:125], v[154:157], v[162:165], v[122:125]
	v_mfma_f32_16x16x32_f16 v[110:113], v[140:143], v[170:173], v[110:113]
	v_mfma_f32_16x16x32_f16 v[106:109], v[154:157], v[170:173], v[106:109]
	v_mfma_f32_16x16x32_f16 v[94:97], v[140:143], v[178:181], v[94:97]
	v_mfma_f32_16x16x32_f16 v[90:93], v[154:157], v[178:181], v[90:93]
	v_mfma_f32_16x16x32_f16 v[78:81], v[140:143], v[186:189], v[78:81]
	v_mfma_f32_16x16x32_f16 v[74:77], v[154:157], v[186:189], v[74:77]
	v_mfma_f32_16x16x32_f16 v[126:129], v[150:153], v[166:169], v[126:129]
	v_mfma_f32_16x16x32_f16 v[122:125], v[158:161], v[166:169], v[122:125]
	v_mfma_f32_16x16x32_f16 v[110:113], v[150:153], v[174:177], v[110:113]
	v_mfma_f32_16x16x32_f16 v[106:109], v[158:161], v[174:177], v[106:109]
	v_mfma_f32_16x16x32_f16 v[94:97], v[150:153], v[182:185], v[94:97]
	v_mfma_f32_16x16x32_f16 v[90:93], v[158:161], v[182:185], v[90:93]
	v_mfma_f32_16x16x32_f16 v[78:81], v[150:153], v[190:193], v[78:81]
	v_mfma_f32_16x16x32_f16 v[74:77], v[158:161], v[190:193], v[74:77]
	v_mfma_f32_16x16x32_f16 v[118:121], v[194:197], v[162:165], v[118:121]
	v_mfma_f32_16x16x32_f16 v[114:117], v[202:205], v[162:165], v[114:117]
	v_mfma_f32_16x16x32_f16 v[102:105], v[194:197], v[170:173], v[102:105]
	v_mfma_f32_16x16x32_f16 v[98:101], v[202:205], v[170:173], v[98:101]
	v_mfma_f32_16x16x32_f16 v[86:89], v[194:197], v[178:181], v[86:89]
	v_mfma_f32_16x16x32_f16 v[82:85], v[202:205], v[178:181], v[82:85]
	v_mfma_f32_16x16x32_f16 v[70:73], v[194:197], v[186:189], v[70:73]
	v_mfma_f32_16x16x32_f16 v[66:69], v[202:205], v[186:189], v[66:69]
	v_mfma_f32_16x16x32_f16 v[118:121], v[198:201], v[166:169], v[118:121]
	v_mfma_f32_16x16x32_f16 v[114:117], v[220:223], v[166:169], v[114:117]
	v_mfma_f32_16x16x32_f16 v[102:105], v[198:201], v[174:177], v[102:105]
	v_mfma_f32_16x16x32_f16 v[98:101], v[220:223], v[174:177], v[98:101]
	v_mfma_f32_16x16x32_f16 v[86:89], v[198:201], v[182:185], v[86:89]
	v_mfma_f32_16x16x32_f16 v[82:85], v[220:223], v[182:185], v[82:85]
	v_mfma_f32_16x16x32_f16 v[70:73], v[198:201], v[190:193], v[70:73]
	v_mfma_f32_16x16x32_f16 v[66:69], v[220:223], v[190:193], v[66:69]
	s_barrier
; #define PG8_STAGE(bufoff, gbase, voff) do { _Pragma("unroll") for (int _i = 0; _i < 2; ++_i) \
;         __builtin_amdgcn_global_load_lds((const unsigned*)((const char*)(gbase) + (voff)[_i]), (LAS unsigned*)(lds + (bufoff) + ldsw + _i * 8192), 16, 0, 0); } while (0)
; #define PG8_MMA(ai, bj, At, Bt_) do { __builtin_amdgcn_s_setprio(1); _Pragma("unroll") for (int m = 0; m < 4; ++m) _Pragma("unroll") for (int n = 0; n < 2; ++n) _Pragma("unroll") for (int k = 0; k < 2; ++k) \
;         acc[ai][bj][m][n] = __builtin_amdgcn_mfma_f32_16x16x32_f16(Bt_[n][k], At[m][k], acc[ai][bj][m][n], 0, 0, 0); __builtin_amdgcn_s_setprio(0); } while (0)
; #define PG8_WAIT_V(n) asm volatile("s_waitcnt vmcnt(" #n ")" ::: "memory")
; #define PG8_WAIT_L(n) asm volatile("s_waitcnt lgkmcnt(" #n ")" ::: "memory")
; #define PG8_BAR __builtin_amdgcn_s_barrier()
; #define PG8_SCHED __builtin_amdgcn_sched_barrier(0)
; template <class Epi, class AMap>
; __device__ __forceinline__ void gemm_phase(LAS unsigned char* lds, const AMap am, const int lda, const h16* Bt, const int ldb, const int M, const int N, const int K, const Epi& E) {
;     ...
;             PG8_BAR; PG8_WAIT_L(0); PG8_MMA(1, 0, At, B0); PG8_BAR; PG8_SCHED;
;             PG8_STAGE(PG8_SB(1, 1), b3 + hstepB, voffB);
;             PG8_WAIT_V(6); PG8_BAR; PG8_MMA(1, 1, At, B1); PG8_BAR;
;         }
	global_load_lds_dwordx4 v[144:145], off
	v_lshl_add_u64 v[144:145], v[206:207], 0, s[92:93]
	s_add_i32 m0, s49, 0x2000
	s_nop 0
	global_load_lds_dwordx4 v[144:145], off
	s_mov_b32 m0, s74
	v_lshl_add_u64 v[144:145], v[212:213], 0, s[92:93]
	ds_read_b128 v[162:165], v149 offset:49152
	ds_read_b128 v[166:169], v149 offset:50176
	ds_read_b128 v[170:173], v149 offset:51200
	ds_read_b128 v[174:177], v149 offset:52224
	ds_read_b128 v[178:181], v149 offset:53248
	ds_read_b128 v[182:185], v149 offset:54272
	ds_read_b128 v[186:189], v149 offset:55296
	ds_read_b128 v[190:193], v149 offset:56320
	global_load_lds_dwordx4 v[144:145], off
	v_lshl_add_u64 v[144:145], v[214:215], 0, s[92:93]
	s_mov_b32 m0, s75
	s_nop 0
	global_load_lds_dwordx4 v[144:145], off
	s_add_u32 s46, s46, 0x80080
	s_addc_u32 s47, s47, 0
	s_add_i32 s48, s48, s64
	v_lshl_add_u64 v[232:233], s[46:47], 0, v[0:1]
	s_mov_b32 m0, s48
	s_nop 0
	global_load_lds_dwordx4 v[232:233], off
	v_lshl_add_u64 v[232:233], s[46:47], 0, v[134:135]
	s_add_i32 m0, s48, 0x2000
	s_nop 0
	global_load_lds_dwordx4 v[232:233], off
	s_add_i32 s51, s51, 2
	s_add_u32 s26, s26, 0x100
	s_addc_u32 s27, s27, 0
	s_add_u32 s21, s21, 0x100
	s_addc_u32 s50, s50, 0
	s_cmp_gt_u32 s51, 29
	s_waitcnt vmcnt(8) lgkmcnt(0)
	s_barrier
	v_mfma_f32_16x16x32_f16 v[62:65], v[140:143], v[162:165], v[62:65]
	v_mfma_f32_16x16x32_f16 v[58:61], v[154:157], v[162:165], v[58:61]
	v_mfma_f32_16x16x32_f16 v[46:49], v[140:143], v[170:173], v[46:49]
	v_mfma_f32_16x16x32_f16 v[42:45], v[154:157], v[170:173], v[42:45]
	v_mfma_f32_16x16x32_f16 v[30:33], v[140:143], v[178:181], v[30:33]
	v_mfma_f32_16x16x32_f16 v[26:29], v[154:157], v[178:181], v[26:29]
	v_mfma_f32_16x16x32_f16 v[14:17], v[140:143], v[186:189], v[14:17]
	v_mfma_f32_16x16x32_f16 v[10:13], v[154:157], v[186:189], v[10:13]
	v_mfma_f32_16x16x32_f16 v[62:65], v[150:153], v[166:169], v[62:65]
	v_mfma_f32_16x16x32_f16 v[58:61], v[158:161], v[166:169], v[58:61]
	v_mfma_f32_16x16x32_f16 v[46:49], v[150:153], v[174:177], v[46:49]
	v_mfma_f32_16x16x32_f16 v[42:45], v[158:161], v[174:177], v[42:45]
	v_mfma_f32_16x16x32_f16 v[30:33], v[150:153], v[182:185], v[30:33]
	v_mfma_f32_16x16x32_f16 v[26:29], v[158:161], v[182:185], v[26:29]
	v_mfma_f32_16x16x32_f16 v[14:17], v[150:153], v[190:193], v[14:17]
	v_mfma_f32_16x16x32_f16 v[10:13], v[158:161], v[190:193], v[10:13]
	v_mfma_f32_16x16x32_f16 v[54:57], v[194:197], v[162:165], v[54:57]
	v_mfma_f32_16x16x32_f16 v[50:53], v[202:205], v[162:165], v[50:53]
	v_mfma_f32_16x16x32_f16 v[38:41], v[194:197], v[170:173], v[38:41]
	v_mfma_f32_16x16x32_f16 v[34:37], v[202:205], v[170:173], v[34:37]
	v_mfma_f32_16x16x32_f16 v[22:25], v[194:197], v[178:181], v[22:25]
	v_mfma_f32_16x16x32_f16 v[18:21], v[202:205], v[178:181], v[18:21]
	v_mfma_f32_16x16x32_f16 v[6:9], v[194:197], v[186:189], v[6:9]
	v_mfma_f32_16x16x32_f16 v[2:5], v[202:205], v[186:189], v[2:5]
	v_mfma_f32_16x16x32_f16 v[54:57], v[198:201], v[166:169], v[54:57]
	v_mfma_f32_16x16x32_f16 v[50:53], v[220:223], v[166:169], v[50:53]
	v_mfma_f32_16x16x32_f16 v[38:41], v[198:201], v[174:177], v[38:41]
	v_mfma_f32_16x16x32_f16 v[34:37], v[220:223], v[174:177], v[34:37]
	v_mfma_f32_16x16x32_f16 v[22:25], v[198:201], v[182:185], v[22:25]
	v_mfma_f32_16x16x32_f16 v[18:21], v[220:223], v[182:185], v[18:21]
	v_mfma_f32_16x16x32_f16 v[6:9], v[198:201], v[190:193], v[6:9]
	v_mfma_f32_16x16x32_f16 v[2:5], v[220:223], v[190:193], v[2:5]
	s_barrier
	s_cbranch_scc1 .Lg4x_147

;     __device__ __forceinline__ void operator()(const f32x4 (&acc)[2][2][4][2], const Unit& u, int wr, int wc, int fr, int fq) const {
;         EPI_ROWS_PERM
; #pragma unroll
;         for (int ai = 0; ai < 2; ++ai)
; #pragma unroll
;             for (int m = 0; m < 4; ++m) { const size_t off = (size_t)(row0 + ai * 128 + m * 16) * DM + colt;
; #pragma unroll
;                 for (int bj = 0; bj < 2; ++bj) {
;                     const h16x8 x = *(const h16x8*)(X + off + bj * 128);
;                     f32x4 o0, o1;
; #pragma unroll
;                     for (int e = 0; e < 4; ++e) { o0[e] = (float)x[e] * ALPHA + acc[ai][bj][m][0][e]; o1[e] = (float)x[4 + e] * ALPHA + acc[ai][bj][m][1][e]; }
;                     *(u32x4*)(PRE + off + bj * 128) = pack8(o0, o1); } }
;     }
.Lgx2:
	s_waitcnt vmcnt(15)
	v_mov_b64_e32 v[150:151], v[158:159]
	v_mov_b64_e32 v[152:153], v[160:161]
	v_cvt_f32_f16_e32 v156, v150
	v_cvt_f32_f16_sdwa v157, v150 dst_sel:DWORD dst_unused:UNUSED_PAD src0_sel:WORD_1
	v_cvt_f32_f16_e32 v150, v151
	v_cvt_f32_f16_sdwa v151, v151 dst_sel:DWORD dst_unused:UNUSED_PAD src0_sel:WORD_1
	v_pk_fma_f32 v[126:127], v[156:157], s[34:35], v[126:127] op_sel_hi:[1,0,1]
	s_nop 0
	v_cvt_pk_f16_f32 v126, v126, v127
	v_pk_fma_f32 v[128:129], v[150:151], s[34:35], v[128:129] op_sel_hi:[1,0,1]
	v_lshl_add_u64 v[150:151], s[4:5], 0, v[140:141]
	v_cvt_pk_f16_f32 v127, v128, v129
	v_cvt_f32_f16_e32 v128, v152
	v_cvt_f32_f16_sdwa v129, v152 dst_sel:DWORD dst_unused:UNUSED_PAD src0_sel:WORD_1
	v_pk_fma_f32 v[122:123], v[128:129], s[34:35], v[122:123] op_sel_hi:[1,0,1]
	s_nop 0
	v_cvt_pk_f16_f32 v128, v122, v123
	v_cvt_f32_f16_e32 v122, v153
	v_cvt_f32_f16_sdwa v123, v153 dst_sel:DWORD dst_unused:UNUSED_PAD src0_sel:WORD_1
	v_pk_fma_f32 v[122:123], v[122:123], s[34:35], v[124:125] op_sel_hi:[1,0,1]
	s_nop 0
	v_cvt_pk_f16_f32 v129, v122, v123
	s_nop 0
	global_store_dwordx4 v[150:151], v[126:129], off
	s_waitcnt vmcnt(15)
	v_mov_b64_e32 v[122:123], v[162:163]
	v_mov_b64_e32 v[124:125], v[164:165]
	s_nop 0
	v_cvt_f32_f16_e32 v126, v122
	v_cvt_f32_f16_sdwa v127, v122 dst_sel:DWORD dst_unused:UNUSED_PAD src0_sel:WORD_1
	v_cvt_f32_f16_e32 v122, v123
	v_cvt_f32_f16_sdwa v123, v123 dst_sel:DWORD dst_unused:UNUSED_PAD src0_sel:WORD_1
	v_pk_fma_f32 v[118:119], v[126:127], s[34:35], v[118:119] op_sel_hi:[1,0,1]
	s_nop 0
	v_cvt_pk_f16_f32 v118, v118, v119
	v_pk_fma_f32 v[120:121], v[122:123], s[34:35], v[120:121] op_sel_hi:[1,0,1]
	s_nop 0
	v_cvt_pk_f16_f32 v119, v120, v121
	v_cvt_f32_f16_e32 v120, v124
	v_cvt_f32_f16_sdwa v121, v124 dst_sel:DWORD dst_unused:UNUSED_PAD src0_sel:WORD_1
	v_pk_fma_f32 v[114:115], v[120:121], s[34:35], v[114:115] op_sel_hi:[1,0,1]
	s_nop 0
	v_cvt_pk_f16_f32 v120, v114, v115
	v_cvt_f32_f16_e32 v114, v125
	v_cvt_f32_f16_sdwa v115, v125 dst_sel:DWORD dst_unused:UNUSED_PAD src0_sel:WORD_1
	v_pk_fma_f32 v[114:115], v[114:115], s[34:35], v[116:117] op_sel_hi:[1,0,1]
	s_nop 0
	v_cvt_pk_f16_f32 v121, v114, v115
	v_or_b32_e32 v114, 16, v144
	v_ashrrev_i32_e32 v115, 31, v114
	v_lshlrev_b64 v[114:115], 11, v[114:115]
	v_lshl_add_u64 v[114:115], v[114:115], 0, v[142:143]
	global_store_dwordx4 v[150:151], v[118:121], off offset:256
	s_nop 1
	v_lshlrev_b64 v[118:119], 1, v[114:115]
	v_lshl_add_u64 v[120:121], s[94:95], 0, v[118:119]
	s_waitcnt vmcnt(15)
	v_mov_b64_e32 v[114:115], v[166:167]
	v_mov_b64_e32 v[116:117], v[168:169]
	v_cvt_f32_f16_e32 v122, v114
	v_cvt_f32_f16_sdwa v123, v114 dst_sel:DWORD dst_unused:UNUSED_PAD src0_sel:WORD_1
	v_cvt_f32_f16_e32 v114, v115
	v_cvt_f32_f16_sdwa v115, v115 dst_sel:DWORD dst_unused:UNUSED_PAD src0_sel:WORD_1
	v_pk_fma_f32 v[110:111], v[122:123], s[34:35], v[110:111] op_sel_hi:[1,0,1]
	s_nop 0
	v_cvt_pk_f16_f32 v110, v110, v111
	v_pk_fma_f32 v[112:113], v[114:115], s[34:35], v[112:113] op_sel_hi:[1,0,1]
	v_lshl_add_u64 v[114:115], s[4:5], 0, v[118:119]
	v_cvt_pk_f16_f32 v111, v112, v113
	v_cvt_f32_f16_e32 v112, v116
	v_cvt_f32_f16_sdwa v113, v116 dst_sel:DWORD dst_unused:UNUSED_PAD src0_sel:WORD_1
	v_pk_fma_f32 v[106:107], v[112:113], s[34:35], v[106:107] op_sel_hi:[1,0,1]
	s_nop 0
	v_cvt_pk_f16_f32 v112, v106, v107
	v_cvt_f32_f16_e32 v106, v117
	v_cvt_f32_f16_sdwa v107, v117 dst_sel:DWORD dst_unused:UNUSED_PAD src0_sel:WORD_1
	v_pk_fma_f32 v[106:107], v[106:107], s[34:35], v[108:109] op_sel_hi:[1,0,1]
	s_nop 0
	v_cvt_pk_f16_f32 v113, v106, v107
	s_nop 0
	global_store_dwordx4 v[114:115], v[110:113], off
	s_waitcnt vmcnt(15)
	v_mov_b64_e32 v[106:107], v[170:171]
	v_mov_b64_e32 v[108:109], v[172:173]
	s_nop 0
	v_cvt_f32_f16_e32 v110, v106
	v_cvt_f32_f16_sdwa v111, v106 dst_sel:DWORD dst_unused:UNUSED_PAD src0_sel:WORD_1
	v_cvt_f32_f16_e32 v106, v107
	v_cvt_f32_f16_sdwa v107, v107 dst_sel:DWORD dst_unused:UNUSED_PAD src0_sel:WORD_1
	v_pk_fma_f32 v[102:103], v[110:111], s[34:35], v[102:103] op_sel_hi:[1,0,1]
	s_nop 0
	v_cvt_pk_f16_f32 v102, v102, v103
	v_pk_fma_f32 v[104:105], v[106:107], s[34:35], v[104:105] op_sel_hi:[1,0,1]
	s_nop 0
	v_cvt_pk_f16_f32 v103, v104, v105
	v_cvt_f32_f16_e32 v104, v108
	v_cvt_f32_f16_sdwa v105, v108 dst_sel:DWORD dst_unused:UNUSED_PAD src0_sel:WORD_1
	v_pk_fma_f32 v[98:99], v[104:105], s[34:35], v[98:99] op_sel_hi:[1,0,1]
	s_nop 0
	v_cvt_pk_f16_f32 v104, v98, v99
	v_cvt_f32_f16_e32 v98, v109
	v_cvt_f32_f16_sdwa v99, v109 dst_sel:DWORD dst_unused:UNUSED_PAD src0_sel:WORD_1
	v_pk_fma_f32 v[98:99], v[98:99], s[34:35], v[100:101] op_sel_hi:[1,0,1]
	s_nop 0
	v_cvt_pk_f16_f32 v105, v98, v99
	v_or_b32_e32 v98, 32, v144
	v_ashrrev_i32_e32 v99, 31, v98
	v_lshlrev_b64 v[98:99], 11, v[98:99]
	v_lshl_add_u64 v[98:99], v[98:99], 0, v[142:143]
	global_store_dwordx4 v[114:115], v[102:105], off offset:256
	s_nop 1
	v_lshlrev_b64 v[102:103], 1, v[98:99]
	v_lshl_add_u64 v[104:105], s[94:95], 0, v[102:103]
	s_waitcnt vmcnt(15)
	v_mov_b64_e32 v[98:99], v[174:175]
	v_mov_b64_e32 v[100:101], v[176:177]
	v_cvt_f32_f16_e32 v106, v98
	v_cvt_f32_f16_sdwa v107, v98 dst_sel:DWORD dst_unused:UNUSED_PAD src0_sel:WORD_1
	v_cvt_f32_f16_e32 v98, v99
	v_cvt_f32_f16_sdwa v99, v99 dst_sel:DWORD dst_unused:UNUSED_PAD src0_sel:WORD_1
	v_pk_fma_f32 v[94:95], v[106:107], s[34:35], v[94:95] op_sel_hi:[1,0,1]
	s_nop 0
	v_cvt_pk_f16_f32 v94, v94, v95
	v_pk_fma_f32 v[96:97], v[98:99], s[34:35], v[96:97] op_sel_hi:[1,0,1]
	v_lshl_add_u64 v[98:99], s[4:5], 0, v[102:103]
	v_cvt_pk_f16_f32 v95, v96, v97
	v_cvt_f32_f16_e32 v96, v100
	v_cvt_f32_f16_sdwa v97, v100 dst_sel:DWORD dst_unused:UNUSED_PAD src0_sel:WORD_1
	v_pk_fma_f32 v[90:91], v[96:97], s[34:35], v[90:91] op_sel_hi:[1,0,1]
	s_nop 0
	v_cvt_pk_f16_f32 v96, v90, v91
	v_cvt_f32_f16_e32 v90, v101
	v_cvt_f32_f16_sdwa v91, v101 dst_sel:DWORD dst_unused:UNUSED_PAD src0_sel:WORD_1
	v_pk_fma_f32 v[90:91], v[90:91], s[34:35], v[92:93] op_sel_hi:[1,0,1]
	s_nop 0
	v_cvt_pk_f16_f32 v97, v90, v91
	s_nop 0
	global_store_dwordx4 v[98:99], v[94:97], off
	s_waitcnt vmcnt(15)
;     __device__ __forceinline__ void operator()(const f32x4 (&acc)[2][2][4][2], const Unit& u, int wr, int wc, int fr, int fq) const {
;         EPI_ROWS_PERM
; #pragma unroll
;         for (int ai = 0; ai < 2; ++ai)
; #pragma unroll
;             for (int m = 0; m < 4; ++m) { const size_t off = (size_t)(row0 + ai * 128 + m * 16) * DM + colt;
; #pragma unroll
;                 for (int bj = 0; bj < 2; ++bj) {
;                     const h16x8 x = *(const h16x8*)(X + off + bj * 128);
;                     f32x4 o0, o1;
; #pragma unroll
;                     for (int e = 0; e < 4; ++e) { o0[e] = (float)x[e] * ALPHA + acc[ai][bj][m][0][e]; o1[e] = (float)x[4 + e] * ALPHA + acc[ai][bj][m][1][e]; }
;                     *(u32x4*)(PRE + off + bj * 128) = pack8(o0, o1); } }
;     }
	v_mov_b64_e32 v[90:91], v[178:179]
	v_mov_b64_e32 v[92:93], v[180:181]
	s_nop 0
	v_cvt_f32_f16_e32 v94, v90
	v_cvt_f32_f16_sdwa v95, v90 dst_sel:DWORD dst_unused:UNUSED_PAD src0_sel:WORD_1
	v_cvt_f32_f16_e32 v90, v91
	v_cvt_f32_f16_sdwa v91, v91 dst_sel:DWORD dst_unused:UNUSED_PAD src0_sel:WORD_1
	v_pk_fma_f32 v[86:87], v[94:95], s[34:35], v[86:87] op_sel_hi:[1,0,1]
	s_nop 0
	v_cvt_pk_f16_f32 v86, v86, v87
	v_pk_fma_f32 v[88:89], v[90:91], s[34:35], v[88:89] op_sel_hi:[1,0,1]
	s_nop 0
	v_cvt_pk_f16_f32 v87, v88, v89
	v_cvt_f32_f16_e32 v88, v92
	v_cvt_f32_f16_sdwa v89, v92 dst_sel:DWORD dst_unused:UNUSED_PAD src0_sel:WORD_1
	v_pk_fma_f32 v[82:83], v[88:89], s[34:35], v[82:83] op_sel_hi:[1,0,1]
	s_nop 0
	v_cvt_pk_f16_f32 v88, v82, v83
	v_cvt_f32_f16_e32 v82, v93
	v_cvt_f32_f16_sdwa v83, v93 dst_sel:DWORD dst_unused:UNUSED_PAD src0_sel:WORD_1
	v_pk_fma_f32 v[82:83], v[82:83], s[34:35], v[84:85] op_sel_hi:[1,0,1]
	s_nop 0
	v_cvt_pk_f16_f32 v89, v82, v83
	v_or_b32_e32 v82, 48, v144
	v_ashrrev_i32_e32 v83, 31, v82
	v_lshlrev_b64 v[82:83], 11, v[82:83]
	v_lshl_add_u64 v[82:83], v[82:83], 0, v[142:143]
	global_store_dwordx4 v[98:99], v[86:89], off offset:256
	s_nop 1
	v_lshlrev_b64 v[86:87], 1, v[82:83]
	v_lshl_add_u64 v[88:89], s[94:95], 0, v[86:87]
	s_waitcnt vmcnt(15)
	v_mov_b64_e32 v[82:83], v[182:183]
	v_mov_b64_e32 v[84:85], v[184:185]
	v_cvt_f32_f16_e32 v90, v82
	v_cvt_f32_f16_sdwa v91, v82 dst_sel:DWORD dst_unused:UNUSED_PAD src0_sel:WORD_1
	v_cvt_f32_f16_e32 v82, v83
	v_cvt_f32_f16_sdwa v83, v83 dst_sel:DWORD dst_unused:UNUSED_PAD src0_sel:WORD_1
	v_pk_fma_f32 v[78:79], v[90:91], s[34:35], v[78:79] op_sel_hi:[1,0,1]
	s_nop 0
	v_cvt_pk_f16_f32 v78, v78, v79
	v_pk_fma_f32 v[80:81], v[82:83], s[34:35], v[80:81] op_sel_hi:[1,0,1]
	v_lshl_add_u64 v[82:83], s[4:5], 0, v[86:87]
	v_cvt_pk_f16_f32 v79, v80, v81
	v_cvt_f32_f16_e32 v80, v84
	v_cvt_f32_f16_sdwa v81, v84 dst_sel:DWORD dst_unused:UNUSED_PAD src0_sel:WORD_1
	v_pk_fma_f32 v[74:75], v[80:81], s[34:35], v[74:75] op_sel_hi:[1,0,1]
	s_nop 0
	v_cvt_pk_f16_f32 v80, v74, v75
	v_cvt_f32_f16_e32 v74, v85
	v_cvt_f32_f16_sdwa v75, v85 dst_sel:DWORD dst_unused:UNUSED_PAD src0_sel:WORD_1
	v_pk_fma_f32 v[74:75], v[74:75], s[34:35], v[76:77] op_sel_hi:[1,0,1]
	s_nop 0
	v_cvt_pk_f16_f32 v81, v74, v75
	s_nop 0
	global_store_dwordx4 v[82:83], v[78:81], off
	s_waitcnt vmcnt(15)
	v_mov_b64_e32 v[74:75], v[186:187]
	v_mov_b64_e32 v[76:77], v[188:189]
	s_nop 0
	v_cvt_f32_f16_e32 v78, v74
	v_cvt_f32_f16_sdwa v79, v74 dst_sel:DWORD dst_unused:UNUSED_PAD src0_sel:WORD_1
	v_cvt_f32_f16_e32 v74, v75
	v_cvt_f32_f16_sdwa v75, v75 dst_sel:DWORD dst_unused:UNUSED_PAD src0_sel:WORD_1
	v_pk_fma_f32 v[70:71], v[78:79], s[34:35], v[70:71] op_sel_hi:[1,0,1]
	s_nop 0
	v_cvt_pk_f16_f32 v70, v70, v71
	v_pk_fma_f32 v[72:73], v[74:75], s[34:35], v[72:73] op_sel_hi:[1,0,1]
	s_nop 0
	v_cvt_pk_f16_f32 v71, v72, v73
	v_cvt_f32_f16_e32 v72, v76
	v_cvt_f32_f16_sdwa v73, v76 dst_sel:DWORD dst_unused:UNUSED_PAD src0_sel:WORD_1
	v_pk_fma_f32 v[66:67], v[72:73], s[34:35], v[66:67] op_sel_hi:[1,0,1]
	s_nop 0
	v_cvt_pk_f16_f32 v72, v66, v67
	v_cvt_f32_f16_e32 v66, v77
	v_cvt_f32_f16_sdwa v67, v77 dst_sel:DWORD dst_unused:UNUSED_PAD src0_sel:WORD_1
	v_pk_fma_f32 v[66:67], v[66:67], s[34:35], v[68:69] op_sel_hi:[1,0,1]
	s_nop 0
	v_cvt_pk_f16_f32 v73, v66, v67
	global_store_dwordx4 v[82:83], v[70:73], off offset:256
	s_nop 1
	v_lshl_add_u64 v[70:71], v[140:141], 0, s[16:17]
	v_lshl_add_u64 v[72:73], s[94:95], 0, v[70:71]
	s_waitcnt vmcnt(15)
	v_mov_b64_e32 v[66:67], v[190:191]
	v_mov_b64_e32 v[68:69], v[192:193]
	v_cvt_f32_f16_e32 v74, v66
	v_cvt_f32_f16_sdwa v75, v66 dst_sel:DWORD dst_unused:UNUSED_PAD src0_sel:WORD_1
	v_cvt_f32_f16_e32 v66, v67
	v_cvt_f32_f16_sdwa v67, v67 dst_sel:DWORD dst_unused:UNUSED_PAD src0_sel:WORD_1
	v_pk_fma_f32 v[62:63], v[74:75], s[34:35], v[62:63] op_sel_hi:[1,0,1]
	s_nop 0
	v_cvt_pk_f16_f32 v62, v62, v63
	v_pk_fma_f32 v[64:65], v[66:67], s[34:35], v[64:65] op_sel_hi:[1,0,1]
	v_lshl_add_u64 v[66:67], s[4:5], 0, v[70:71]
	v_cvt_pk_f16_f32 v63, v64, v65
	v_cvt_f32_f16_e32 v64, v68
	v_cvt_f32_f16_sdwa v65, v68 dst_sel:DWORD dst_unused:UNUSED_PAD src0_sel:WORD_1
	v_pk_fma_f32 v[58:59], v[64:65], s[34:35], v[58:59] op_sel_hi:[1,0,1]
	s_nop 0
	v_cvt_pk_f16_f32 v64, v58, v59
	v_cvt_f32_f16_e32 v58, v69
	v_cvt_f32_f16_sdwa v59, v69 dst_sel:DWORD dst_unused:UNUSED_PAD src0_sel:WORD_1
	v_pk_fma_f32 v[58:59], v[58:59], s[34:35], v[60:61] op_sel_hi:[1,0,1]
	s_nop 0
	v_cvt_pk_f16_f32 v65, v58, v59
	s_nop 0
	global_store_dwordx4 v[66:67], v[62:65], off
	s_waitcnt vmcnt(15)
	v_mov_b64_e32 v[58:59], v[194:195]
	v_mov_b64_e32 v[60:61], v[196:197]
	s_nop 0
	v_cvt_f32_f16_e32 v62, v58
	v_cvt_f32_f16_sdwa v63, v58 dst_sel:DWORD dst_unused:UNUSED_PAD src0_sel:WORD_1
	v_cvt_f32_f16_e32 v58, v59
	v_cvt_f32_f16_sdwa v59, v59 dst_sel:DWORD dst_unused:UNUSED_PAD src0_sel:WORD_1
	v_pk_fma_f32 v[54:55], v[62:63], s[34:35], v[54:55] op_sel_hi:[1,0,1]
	s_nop 0
	v_cvt_pk_f16_f32 v54, v54, v55
	v_pk_fma_f32 v[56:57], v[58:59], s[34:35], v[56:57] op_sel_hi:[1,0,1]
	s_nop 0
	v_cvt_pk_f16_f32 v55, v56, v57
	v_cvt_f32_f16_e32 v56, v60
	v_cvt_f32_f16_sdwa v57, v60 dst_sel:DWORD dst_unused:UNUSED_PAD src0_sel:WORD_1
	v_pk_fma_f32 v[50:51], v[56:57], s[34:35], v[50:51] op_sel_hi:[1,0,1]
	s_nop 0
	v_cvt_pk_f16_f32 v56, v50, v51
	v_cvt_f32_f16_e32 v50, v61
	v_cvt_f32_f16_sdwa v51, v61 dst_sel:DWORD dst_unused:UNUSED_PAD src0_sel:WORD_1
	v_pk_fma_f32 v[50:51], v[50:51], s[34:35], v[52:53] op_sel_hi:[1,0,1]
	s_nop 0
	v_cvt_pk_f16_f32 v57, v50, v51
	global_store_dwordx4 v[66:67], v[54:57], off offset:256
	s_nop 1
	v_lshl_add_u64 v[54:55], v[140:141], 0, s[18:19]
	v_lshl_add_u64 v[56:57], s[94:95], 0, v[54:55]
	s_waitcnt vmcnt(15)
; #define PG8_WAIT_V(n) asm volatile("s_waitcnt vmcnt(" #n ")" ::: "memory")
; #define PG8_BAR __builtin_amdgcn_s_barrier()
; template <class Epi, class AMap>
; __device__ __forceinline__ void gemm_phase(LAS unsigned char* lds, const AMap am, const int lda, const h16* Bt, const int ldb, const int M, const int N, const int K, const Epi& E) {
;     ...
;         if (!has_next) break;
; #pragma unroll
;         for (int a = 0; a < 2; ++a)
; #pragma unroll
;             for (int b = 0; b < 2; ++b)
; #pragma unroll
;                 for (int m = 0; m < 4; ++m)
; #pragma unroll
;                     for (int n = 0; n < 2; ++n) acc[a][b][m][n] = (f32x4){0.f, 0.f, 0.f, 0.f};
;         cur = nxt; cA = nA; cB = nB; ++ui;
;     }
;     PG8_WAIT_V(0);
;     if (wr == 0) PG8_BAR;
;     PG8_BAR;
;     __device__ __forceinline__ void operator()(const f32x4 (&acc)[2][2][4][2], const Unit& u, int wr, int wc, int fr, int fq) const {
;     ...
;             for (int m = 0; m < 4; ++m) { const size_t off = (size_t)(row0 + ai * 128 + m * 16) * DM + colt;
; #pragma unroll
;                 for (int bj = 0; bj < 2; ++bj) {
;                     const h16x8 x = *(const h16x8*)(X + off + bj * 128);
;                     f32x4 o0, o1;
; #pragma unroll
;                     for (int e = 0; e < 4; ++e) { o0[e] = (float)x[e] * ALPHA + acc[ai][bj][m][0][e]; o1[e] = (float)x[4 + e] * ALPHA + acc[ai][bj][m][1][e]; }
;                     *(u32x4*)(PRE + off + bj * 128) = pack8(o0, o1); } }
	v_mov_b64_e32 v[50:51], v[198:199]
	v_mov_b64_e32 v[52:53], v[200:201]
	v_cvt_f32_f16_e32 v58, v50
	v_cvt_f32_f16_sdwa v59, v50 dst_sel:DWORD dst_unused:UNUSED_PAD src0_sel:WORD_1
	v_cvt_f32_f16_e32 v50, v51
	v_cvt_f32_f16_sdwa v51, v51 dst_sel:DWORD dst_unused:UNUSED_PAD src0_sel:WORD_1
	v_pk_fma_f32 v[46:47], v[58:59], s[34:35], v[46:47] op_sel_hi:[1,0,1]
	s_nop 0
	v_cvt_pk_f16_f32 v46, v46, v47
	v_pk_fma_f32 v[48:49], v[50:51], s[34:35], v[48:49] op_sel_hi:[1,0,1]
	v_lshl_add_u64 v[50:51], s[4:5], 0, v[54:55]
	v_cvt_pk_f16_f32 v47, v48, v49
	v_cvt_f32_f16_e32 v48, v52
	v_cvt_f32_f16_sdwa v49, v52 dst_sel:DWORD dst_unused:UNUSED_PAD src0_sel:WORD_1
	v_pk_fma_f32 v[42:43], v[48:49], s[34:35], v[42:43] op_sel_hi:[1,0,1]
	s_nop 0
	v_cvt_pk_f16_f32 v48, v42, v43
	v_cvt_f32_f16_e32 v42, v53
	v_cvt_f32_f16_sdwa v43, v53 dst_sel:DWORD dst_unused:UNUSED_PAD src0_sel:WORD_1
	v_pk_fma_f32 v[42:43], v[42:43], s[34:35], v[44:45] op_sel_hi:[1,0,1]
	s_nop 0
	v_cvt_pk_f16_f32 v49, v42, v43
	s_nop 0
	global_store_dwordx4 v[50:51], v[46:49], off
	s_waitcnt vmcnt(15)
	v_mov_b64_e32 v[42:43], v[202:203]
	v_mov_b64_e32 v[44:45], v[204:205]
	s_nop 0
	v_cvt_f32_f16_e32 v46, v42
	v_cvt_f32_f16_sdwa v47, v42 dst_sel:DWORD dst_unused:UNUSED_PAD src0_sel:WORD_1
	v_cvt_f32_f16_e32 v42, v43
	v_cvt_f32_f16_sdwa v43, v43 dst_sel:DWORD dst_unused:UNUSED_PAD src0_sel:WORD_1
	v_pk_fma_f32 v[38:39], v[46:47], s[34:35], v[38:39] op_sel_hi:[1,0,1]
	s_nop 0
	v_cvt_pk_f16_f32 v38, v38, v39
	v_pk_fma_f32 v[40:41], v[42:43], s[34:35], v[40:41] op_sel_hi:[1,0,1]
	s_nop 0
	v_cvt_pk_f16_f32 v39, v40, v41
	v_cvt_f32_f16_e32 v40, v44
	v_cvt_f32_f16_sdwa v41, v44 dst_sel:DWORD dst_unused:UNUSED_PAD src0_sel:WORD_1
	v_pk_fma_f32 v[34:35], v[40:41], s[34:35], v[34:35] op_sel_hi:[1,0,1]
	s_nop 0
	v_cvt_pk_f16_f32 v40, v34, v35
	v_cvt_f32_f16_e32 v34, v45
	v_cvt_f32_f16_sdwa v35, v45 dst_sel:DWORD dst_unused:UNUSED_PAD src0_sel:WORD_1
	v_pk_fma_f32 v[34:35], v[34:35], s[34:35], v[36:37] op_sel_hi:[1,0,1]
	s_nop 0
	v_cvt_pk_f16_f32 v41, v34, v35
	global_store_dwordx4 v[50:51], v[38:41], off offset:256
	s_nop 1
	v_lshl_add_u64 v[38:39], v[140:141], 0, s[8:9]
	v_lshl_add_u64 v[40:41], s[94:95], 0, v[38:39]
	s_waitcnt vmcnt(15)
	v_mov_b64_e32 v[34:35], v[212:213]
	v_mov_b64_e32 v[36:37], v[214:215]
	v_cvt_f32_f16_e32 v42, v34
	v_cvt_f32_f16_sdwa v43, v34 dst_sel:DWORD dst_unused:UNUSED_PAD src0_sel:WORD_1
	v_cvt_f32_f16_e32 v34, v35
	v_cvt_f32_f16_sdwa v35, v35 dst_sel:DWORD dst_unused:UNUSED_PAD src0_sel:WORD_1
	v_pk_fma_f32 v[30:31], v[42:43], s[34:35], v[30:31] op_sel_hi:[1,0,1]
	s_nop 0
	v_cvt_pk_f16_f32 v30, v30, v31
	v_pk_fma_f32 v[32:33], v[34:35], s[34:35], v[32:33] op_sel_hi:[1,0,1]
	v_lshl_add_u64 v[34:35], s[4:5], 0, v[38:39]
	v_cvt_pk_f16_f32 v31, v32, v33
	v_cvt_f32_f16_e32 v32, v36
	v_cvt_f32_f16_sdwa v33, v36 dst_sel:DWORD dst_unused:UNUSED_PAD src0_sel:WORD_1
	v_pk_fma_f32 v[26:27], v[32:33], s[34:35], v[26:27] op_sel_hi:[1,0,1]
	s_nop 0
	v_cvt_pk_f16_f32 v32, v26, v27
	v_cvt_f32_f16_e32 v26, v37
	v_cvt_f32_f16_sdwa v27, v37 dst_sel:DWORD dst_unused:UNUSED_PAD src0_sel:WORD_1
	v_pk_fma_f32 v[26:27], v[26:27], s[34:35], v[28:29] op_sel_hi:[1,0,1]
	s_nop 0
	v_cvt_pk_f16_f32 v33, v26, v27
	s_nop 0
	global_store_dwordx4 v[34:35], v[30:33], off
	s_waitcnt vmcnt(15)
	v_mov_b64_e32 v[26:27], v[220:221]
	v_mov_b64_e32 v[28:29], v[222:223]
	s_nop 0
	v_cvt_f32_f16_e32 v30, v26
	v_cvt_f32_f16_sdwa v31, v26 dst_sel:DWORD dst_unused:UNUSED_PAD src0_sel:WORD_1
	v_cvt_f32_f16_e32 v26, v27
	v_cvt_f32_f16_sdwa v27, v27 dst_sel:DWORD dst_unused:UNUSED_PAD src0_sel:WORD_1
	v_pk_fma_f32 v[22:23], v[30:31], s[34:35], v[22:23] op_sel_hi:[1,0,1]
	s_nop 0
	v_cvt_pk_f16_f32 v22, v22, v23
	v_pk_fma_f32 v[24:25], v[26:27], s[34:35], v[24:25] op_sel_hi:[1,0,1]
	s_nop 0
	v_cvt_pk_f16_f32 v23, v24, v25
	v_cvt_f32_f16_e32 v24, v28
	v_cvt_f32_f16_sdwa v25, v28 dst_sel:DWORD dst_unused:UNUSED_PAD src0_sel:WORD_1
	v_pk_fma_f32 v[18:19], v[24:25], s[34:35], v[18:19] op_sel_hi:[1,0,1]
	s_nop 0
	v_cvt_pk_f16_f32 v24, v18, v19
	v_cvt_f32_f16_e32 v18, v29
	v_cvt_f32_f16_sdwa v19, v29 dst_sel:DWORD dst_unused:UNUSED_PAD src0_sel:WORD_1
	v_pk_fma_f32 v[18:19], v[18:19], s[34:35], v[20:21] op_sel_hi:[1,0,1]
	s_nop 0
	v_cvt_pk_f16_f32 v25, v18, v19
	global_store_dwordx4 v[34:35], v[22:25], off offset:256
	s_nop 1
	v_lshl_add_u64 v[22:23], v[140:141], 0, s[2:3]
	v_lshl_add_u64 v[24:25], s[94:95], 0, v[22:23]
	s_waitcnt vmcnt(15)
	v_mov_b64_e32 v[18:19], v[224:225]
	v_mov_b64_e32 v[20:21], v[226:227]
	v_cvt_f32_f16_e32 v26, v18
	v_cvt_f32_f16_sdwa v27, v18 dst_sel:DWORD dst_unused:UNUSED_PAD src0_sel:WORD_1
	v_cvt_f32_f16_e32 v18, v19
	v_cvt_f32_f16_sdwa v19, v19 dst_sel:DWORD dst_unused:UNUSED_PAD src0_sel:WORD_1
	v_pk_fma_f32 v[14:15], v[26:27], s[34:35], v[14:15] op_sel_hi:[1,0,1]
	s_nop 0
	v_cvt_pk_f16_f32 v14, v14, v15
	v_pk_fma_f32 v[16:17], v[18:19], s[34:35], v[16:17] op_sel_hi:[1,0,1]
	v_lshl_add_u64 v[18:19], s[4:5], 0, v[22:23]
	v_cvt_pk_f16_f32 v15, v16, v17
	v_cvt_f32_f16_e32 v16, v20
	v_cvt_f32_f16_sdwa v17, v20 dst_sel:DWORD dst_unused:UNUSED_PAD src0_sel:WORD_1
	v_pk_fma_f32 v[10:11], v[16:17], s[34:35], v[10:11] op_sel_hi:[1,0,1]
	s_nop 0
	v_cvt_pk_f16_f32 v16, v10, v11
	v_cvt_f32_f16_e32 v10, v21
	v_cvt_f32_f16_sdwa v11, v21 dst_sel:DWORD dst_unused:UNUSED_PAD src0_sel:WORD_1
	v_pk_fma_f32 v[10:11], v[10:11], s[34:35], v[12:13] op_sel_hi:[1,0,1]
	s_nop 0
	v_cvt_pk_f16_f32 v17, v10, v11
	s_nop 0
	global_store_dwordx4 v[18:19], v[14:17], off
	s_waitcnt vmcnt(15)
	v_mov_b64_e32 v[10:11], v[228:229]
	v_mov_b64_e32 v[12:13], v[230:231]
	s_nop 0
	v_cvt_f32_f16_e32 v14, v10
	v_cvt_f32_f16_sdwa v15, v10 dst_sel:DWORD dst_unused:UNUSED_PAD src0_sel:WORD_1
	v_cvt_f32_f16_e32 v10, v11
	v_cvt_f32_f16_sdwa v11, v11 dst_sel:DWORD dst_unused:UNUSED_PAD src0_sel:WORD_1
	v_pk_fma_f32 v[6:7], v[14:15], s[34:35], v[6:7] op_sel_hi:[1,0,1]
	s_nop 0
	v_cvt_pk_f16_f32 v6, v6, v7
	v_pk_fma_f32 v[8:9], v[10:11], s[34:35], v[8:9] op_sel_hi:[1,0,1]
	s_nop 0
	v_cvt_pk_f16_f32 v7, v8, v9
	v_cvt_f32_f16_e32 v8, v12
	v_cvt_f32_f16_sdwa v9, v12 dst_sel:DWORD dst_unused:UNUSED_PAD src0_sel:WORD_1
	v_pk_fma_f32 v[2:3], v[8:9], s[34:35], v[2:3] op_sel_hi:[1,0,1]
	s_nop 0
	v_cvt_pk_f16_f32 v8, v2, v3
	v_cvt_f32_f16_e32 v2, v13
	v_cvt_f32_f16_sdwa v3, v13 dst_sel:DWORD dst_unused:UNUSED_PAD src0_sel:WORD_1
	v_pk_fma_f32 v[2:3], v[2:3], s[34:35], v[4:5] op_sel_hi:[1,0,1]
	s_nop 0
	v_cvt_pk_f16_f32 v9, v2, v3
	s_mov_b32 s35, s0
	global_store_dwordx4 v[18:19], v[6:9], off offset:256
	s_cbranch_vccz .LBB0_140
	s_waitcnt vmcnt(0)
	s_cmpk_gt_u32 s62, 0xff
	s_cbranch_scc1 .LBB0_151

; __device__ __forceinline__ int otid() { int t = (int)threadIdx.x; asm volatile("" : "+v"(t)); return t; }
; __device__ __forceinline__ int obid() { int t = (int)blockIdx.x; asm volatile("" : "+s"(t)); return t; }
; #define PG8_WAIT_V(n) asm volatile("s_waitcnt vmcnt(" #n ")" ::: "memory")
; #define PG8_BAR __builtin_amdgcn_s_barrier()
; template <class Epi, class AMap>
; __device__ __forceinline__ void gemm_phase(LAS unsigned char* lds, const AMap am, const int lda, const h16* Bt, const int ldb, const int M, const int N, const int K, const Epi& E) {
;     const int tid = otid(), wid = __builtin_amdgcn_readfirstlane(tid >> 6), lane = tid & 63, wr = wid >> 2, wc = wid & 3, fr = lane & 15, fq = lane >> 4;
;     const int nt = K / BK;
;     Order S; S.init(M, N, (int)gridDim.x, obid());
;     unsigned voffA[2], voffB[2];
; #pragma unroll
;     for (int i = 0; i < 2; ++i) { int R, C; stage_rc(tid * 16 + i * 8192, R, C); const int Rb = Epi::PERM ? ((R & ~31) + perm32(R & 31)) : R;
;         voffA[i] = (unsigned)(R * lda + C) * 2u; voffB[i] = (unsigned)(Rb * ldb + C) * 2u; }
;     const size_t kstep = (size_t)(BK * 2);
;     const size_t hstepA = (size_t)HALF * lda * 2, hstepB = (size_t)HALF * ldb * 2;
;     const size_t tstepA = 2 * hstepA, tstepB = 2 * hstepB;
;     const unsigned ldsw = (unsigned)wid * 1024u;
;     const int aoff = lds_byte(wr * 64 + fr, fq * 8), boff = lds_byte(wc * 32 + fr, fq * 8);
;     ...
;     Unit cur, nxt; int ui = 0;
;     if (!S.next(0, cur)) return;
;     f32x4 acc[2][2][4][2];
; #pragma unroll
;     for (int a = 0; a < 2; ++a)
; #pragma unroll
;         for (int b = 0; b < 2; ++b)
; #pragma unroll
;             for (int m = 0; m < 4; ++m)
; #pragma unroll
;                 for (int n = 0; n < 2; ++n) acc[a][b][m][n] = (f32x4){0.f, 0.f, 0.f, 0.f};
;     h16x8 At[4][2], B0[2][2], B1[2][2];
;     const char* cA = am(cur.pn) + (size_t)cur.pm * tstepA; const char* cB = (const char*)Bt + (size_t)cur.pn * tstepB;
;     PG8_STAGE(PG8_SB(0, 0), cB, voffB); PG8_STAGE(PG8_SA(0, 0), cA, voffA); PG8_STAGE(PG8_SB(0, 1), cB + hstepB, voffB); PG8_STAGE(PG8_SA(0, 1), cA + hstepA, voffA);
;     if (wr == 1) PG8_BAR;
;     PG8_WAIT_V(4); PG8_BAR;
;     PG8_STAGE(PG8_SB(1, 0), cB + kstep, voffB); PG8_STAGE(PG8_SA(1, 0), cA + kstep, voffA); PG8_STAGE(PG8_SB(1, 1), cB + hstepB + kstep, voffB);
;     PG8_WAIT_V(6); PG8_BAR;
.LBB0_260:
	s_andn2_b64 vcc, exec, s[0:1]
	s_cbranch_vccnz .LBB0_400
	s_waitcnt vmcnt(0)
	v_ashrrev_i32_e32 v3, 31, v0
	v_lshrrev_b32_e32 v3, 26, v3
	v_add_u32_e32 v3, v0, v3
	v_ashrrev_i32_e32 v10, 6, v3
	v_bfe_i32 v3, v0, 27, 1
	v_lshlrev_b32_e32 v2, 4, v0
	v_lshrrev_b32_e32 v3, 22, v3
	v_add_u32_e32 v3, v2, v3
	v_and_b32_e32 v3, 0xfffffc00, v3
	v_sub_u32_e32 v3, v2, v3
	v_lshrrev_b32_e32 v4, 4, v3
	v_bitop3_b32 v4, v4, v3, 32 bitop3:0x6c
	v_ashrrev_i32_e32 v3, 31, v3
	v_lshrrev_b32_e32 v3, 26, v3
	v_add_u32_e32 v3, v4, v3
	v_ashrrev_i32_e32 v11, 6, v3
	v_lshlrev_b32_e32 v5, 3, v10
	v_mul_i32_i24_e32 v6, 64, v11
	v_and_b32_e32 v5, -16, v5
	v_sub_u32_e32 v4, v4, v6
	v_mov_b32_e32 v8, 1
	v_add_u32_e32 v3, v11, v5
	v_lshlrev_b32_e32 v5, 5, v10
	v_ashrrev_i16_sdwa v4, v8, sext(v4) dst_sel:DWORD dst_unused:UNUSED_PAD src0_sel:DWORD src1_sel:BYTE_0
	v_and_b32_e32 v5, 32, v5
	v_bfe_i32 v12, v4, 0, 16
	v_and_b32_e32 v7, 3, v11
	s_mov_b32 s1, 0xfffe0
	v_add_lshl_u32 v5, v5, v12, 1
	v_add_u32_e32 v2, 0x2000, v2
	v_lshlrev_b32_e32 v4, 1, v3
	v_lshrrev_b32_e32 v6, 2, v3
	v_and_or_b32 v7, v3, s1, v7
	v_lshl_add_u32 v130, v3, 12, v5
	v_ashrrev_i32_e32 v3, 31, v2
	v_lshrrev_b32_e32 v3, 22, v3
	v_add_u32_e32 v3, v2, v3
	v_ashrrev_i32_e32 v13, 10, v3
	v_mul_i32_i24_e32 v3, 0x400, v13
	v_sub_u32_e32 v2, v2, v3
	v_and_b32_e32 v4, 24, v4
	v_and_b32_e32 v6, 4, v6
	v_lshrrev_b32_e32 v3, 4, v2
	v_or3_b32 v4, v7, v6, v4
	v_bitop3_b32 v2, v3, v2, 32 bitop3:0x6c
	v_lshl_add_u32 v132, v4, 12, v5
	v_ashrrev_i32_e32 v4, 31, v2
	v_lshrrev_b32_e32 v4, 26, v4
	v_lshlrev_b32_e32 v3, 3, v13
	v_add_u32_e32 v4, v2, v4
	v_and_b32_e32 v3, -16, v3
	v_ashrrev_i32_e32 v14, 6, v4
	v_add_u32_e32 v3, v14, v3
	v_and_b32_e32 v6, 3, v14
	v_and_b32_e32 v4, 0xc0, v4
	v_and_or_b32 v6, v3, s1, v6
	s_ashr_i32 s1, s64, 6
	s_ashr_i32 s27, s26, 31
	s_ashr_i32 s23, s22, 31
	s_ashr_i32 s0, s64, 8
	v_sub_u32_e32 v2, v2, v4
	s_lshl_b32 s65, s1, 10
	s_lshl_b64 s[20:21], s[26:27], 20
	s_lshl_b64 s[38:39], s[22:23], 20
	v_readlane_b32 s9, v255, 10
	v_ashrrev_i16_sdwa v2, v8, sext(v2) dst_sel:DWORD dst_unused:UNUSED_PAD src0_sel:DWORD src1_sel:BYTE_0
	s_add_u32 s42, s9, s38
	v_readlane_b32 s11, v255, 11
	v_lshlrev_b32_e32 v5, 5, v13
	v_bfe_i32 v15, v2, 0, 16
	v_lshlrev_b32_e32 v2, 1, v3
	v_lshrrev_b32_e32 v4, 2, v3
	s_addc_u32 s43, s11, s39
	s_add_i32 s72, s65, 0
	v_and_b32_e32 v5, 32, v5
	v_and_b32_e32 v2, 24, v2
	v_and_b32_e32 v4, 4, v4
	s_add_i32 m0, s72, 0x10000
	v_or3_b32 v2, v6, v4, v2
	v_add_lshl_u32 v4, v5, v15, 1
	global_load_lds_dwordx4 v132, s[42:43]
	s_add_i32 m0, s72, 0x12000
	v_lshl_add_u32 v136, v2, 12, v4
	s_add_u32 s40, s94, s20
	global_load_lds_dwordx4 v136, s[42:43]
	s_addc_u32 s41, s95, s21
	s_mov_b32 m0, s72
	s_add_i32 s73, s72, 0x2000
	v_lshl_add_u32 v134, v3, 12, v4
	global_load_lds_dwordx4 v130, s[40:41]
	s_mov_b32 m0, s73
	s_add_u32 s20, s42, 0x80000
	global_load_lds_dwordx4 v134, s[40:41]
	s_addc_u32 s21, s43, 0
	s_add_i32 m0, s72, 0x14000
	v_mov_b32_e32 v133, v1
	global_load_lds_dwordx4 v132, s[20:21]
	s_add_i32 m0, s72, 0x16000
	v_mov_b32_e32 v137, v1
	global_load_lds_dwordx4 v136, s[20:21]
	s_add_u32 s20, s40, 0x80000
	s_addc_u32 s21, s41, 0
	s_add_i32 s74, s72, 0x4000
	s_mov_b32 m0, s74
	s_add_i32 s75, s72, 0x6000
	global_load_lds_dwordx4 v130, s[20:21]
	s_mov_b32 m0, s75
	v_mov_b32_e32 v131, v1
	global_load_lds_dwordx4 v134, s[20:21]
	v_mov_b32_e32 v135, v1
	v_readlane_b32 s2, v251, 13
	v_readlane_b32 s12, v254, 58
	v_lshl_add_u64 v[8:9], s[42:43], 0, v[132:133]
	v_lshl_add_u64 v[6:7], s[42:43], 0, v[136:137]
	v_lshl_add_u64 v[4:5], s[40:41], 0, v[130:131]
	s_cmp_lg_u32 s0, 1
	v_lshl_add_u64 v[2:3], s[40:41], 0, v[134:135]
	v_readlane_b32 s3, v251, 14
	s_movk_i32 s4, 0xc1
	s_movk_i32 s5, 0x1fc3
	s_movk_i32 s6, 0x1fd3
	s_movk_i32 s7, 0x1fe3
	s_movk_i32 s8, 0x1ff3
	s_mov_b32 s10, 0x3e0293ee
	v_readlane_b32 s13, v254, 59
	s_cbranch_scc1 .LBB0_263
.LBB0_263:
	v_lshrrev_b32_e32 v16, 1, v0
	v_and_b32_e32 v17, 24, v16
	v_and_b32_e32 v148, 15, v0
	v_lshlrev_b32_e32 v18, 1, v17
	v_lshlrev_b32_e32 v19, 2, v0
	s_lshl_b32 s76, s0, 6
	v_lshl_or_b32 v18, v148, 6, v18
	s_lshl_b32 s0, s0, 13
	v_and_b32_e32 v19, 32, v19
	v_bitop3_b32 v20, v18, s0, v19 bitop3:0xde
	s_lshl_b32 s0, s1, 5
	s_and_b32 s20, s0, 0x60
	s_add_i32 m0, s72, 0x18000
	v_lshl_add_u64 v[8:9], v[8:9], 0, s[92:93]
	s_lshl_b32 s0, s20, 7
	s_waitcnt vmcnt(0)
	s_barrier
	global_load_lds_dwordx4 v[8:9], off
	v_lshl_add_u64 v[6:7], v[6:7], 0, s[92:93]
	s_add_i32 m0, s72, 0x1a000
	s_add_i32 s77, s72, 0x8000
	s_add_i32 s78, s72, 0xa000
	v_bitop3_b32 v149, v18, s0, v19 bitop3:0xde
	global_load_lds_dwordx4 v[6:7], off
	v_lshl_add_u64 v[4:5], v[4:5], 0, s[92:93]
	s_mov_b32 m0, s77
	s_add_u32 s0, s42, 0x80080
	global_load_lds_dwordx4 v[4:5], off
	v_lshl_add_u64 v[2:3], v[2:3], 0, s[92:93]
	s_mov_b32 m0, s78
	s_addc_u32 s1, s43, 0
	global_load_lds_dwordx4 v[2:3], off
	s_add_i32 m0, s72, 0x1c000
	v_lshl_add_u64 v[2:3], s[0:1], 0, v[132:133]
	global_load_lds_dwordx4 v[2:3], off
	v_lshl_add_u64 v[2:3], s[0:1], 0, v[136:137]
	s_add_i32 m0, s72, 0x1e000
	v_lshlrev_b32_e32 v0, 1, v0
	global_load_lds_dwordx4 v[2:3], off
	v_and_b32_e32 v2, 4, v16
	v_and_or_b32 v151, v0, 8, v2
	v_lshlrev_b32_e32 v0, 15, v10
	v_and_b32_e32 v0, 0xffff0000, v0
	v_lshl_add_u32 v0, v11, 12, v0
	v_and_b32_e32 v2, 1, v10
	v_lshl_or_b32 v0, v2, 6, v0
	v_lshl_add_u32 v138, v12, 1, v0
	v_lshlrev_b32_e32 v0, 15, v13
	v_and_b32_e32 v0, 0xffff0000, v0
	s_waitcnt vmcnt(6)
	v_lshl_add_u32 v0, v14, 12, v0
	v_and_b32_e32 v2, 1, v13
	v_or_b32_e32 v150, s20, v17
	v_lshl_or_b32 v0, v2, 6, v0
	v_or_b32_e32 v152, 0x80, v150
	v_mov_b32_e32 v139, v1
	v_lshl_add_u32 v140, v15, 1, v0
	v_mov_b32_e32 v141, v1
	s_mov_b32 s79, 0
	v_add_u32_e32 v153, 0, v20
	s_barrier
	s_branch .LBB0_265

; #define PG8_STAGE(bufoff, gbase, voff) do { _Pragma("unroll") for (int _i = 0; _i < 2; ++_i) \
;         __builtin_amdgcn_global_load_lds((const unsigned*)((const char*)(gbase) + (voff)[_i]), (LAS unsigned*)(lds + (bufoff) + ldsw + _i * 8192), 16, 0, 0); } while (0)
; #define PG8_LDA(dst, b, h) do { _Pragma("unroll") for (int m = 0; m < 4; ++m) _Pragma("unroll") for (int k = 0; k < 2; ++k) dst[m][k] = *(const LAS h16x8*)(lds + PG8_SA(b, h) + aoff + m * 2048 + k * 1024); } while (0)
; #define PG8_LDB(dst, b, h) do { _Pragma("unroll") for (int n = 0; n < 2; ++n) _Pragma("unroll") for (int k = 0; k < 2; ++k) dst[n][k] = *(const LAS h16x8*)(lds + PG8_SB(b, h) + boff + n * 2048 + k * 1024); } while (0)
; #define PG8_WAIT_V(n) asm volatile("s_waitcnt vmcnt(" #n ")" ::: "memory")
; #define PG8_WAIT_L(n) asm volatile("s_waitcnt lgkmcnt(" #n ")" ::: "memory")
; #define PG8_BAR __builtin_amdgcn_s_barrier()
; #define PG8_SCHED __builtin_amdgcn_sched_barrier(0)
; template <class Epi, class AMap>
; __device__ __forceinline__ void gemm_phase(LAS unsigned char* lds, const AMap am, const int lda, const h16* Bt, const int ldb, const int M, const int N, const int K, const Epi& E) {
;     ...
;         const bool has_next = S.next(ui + 1, nxt);
;         const char* nA = has_next ? am(nxt.pn) + (size_t)nxt.pm * tstepA : cA; const char* nB = has_next ? (const char*)Bt + (size_t)nxt.pn * tstepB : cB;
; #pragma unroll 1
;         for (int t = 0; t < nt; t += 2) {
;             const bool last = (t == nt - 2);
;             const char* a1 = cA + (size_t)(t + 1) * kstep;
;             const char* a2 = last ? nA : cA + (size_t)(t + 2) * kstep; const char* b2 = last ? nB : cB + (size_t)(t + 2) * kstep;
;             const char* a3 = a2 + kstep; const char* b3 = b2 + kstep;
;             PG8_LDB(B0, 0, 0); PG8_SCHED; PG8_LDA(At, 0, 0); PG8_STAGE(PG8_SA(1, 1), a1 + hstepA, voffA);
;             PG8_WAIT_L(8); PG8_BAR; PG8_WAIT_L(0); PG8_MMA(0, 0, At, B0); PG8_BAR; PG8_SCHED;
;             PG8_LDB(B1, 0, 1); PG8_STAGE(PG8_SB(0, 0), b2, voffB);
;             PG8_BAR; PG8_WAIT_L(0); PG8_MMA(0, 1, At, B1); PG8_BAR;
;             PG8_LDA(At, 0, 1); PG8_STAGE(PG8_SA(0, 0), a2, voffA);
;             PG8_BAR; PG8_WAIT_L(0); PG8_MMA(1, 0, At, B0); PG8_BAR; PG8_SCHED;
;             PG8_STAGE(PG8_SB(0, 1), b2 + hstepB, voffB);
;             PG8_WAIT_V(6); PG8_BAR; PG8_MMA(1, 1, At, B1); PG8_BAR;
.LBB0_267:
	s_ashr_i32 s45, s44, 31
	s_lshl_b64 s[20:21], s[44:45], 20
	s_add_u32 s68, s94, s20
	v_cmp_lt_i64_e32 vcc, s[48:49], v[218:219]
	s_addc_u32 s69, s95, s21
	s_and_b64 s[20:21], vcc, exec
	s_cselect_b32 s23, s69, s41
	s_cselect_b32 s27, s68, s40
	s_ashr_i32 s1, s0, 31
	s_lshl_b64 s[20:21], s[0:1], 20
	s_add_u32 s70, s9, s20
	s_addc_u32 s71, s11, s21
	s_and_b64 s[20:21], vcc, exec
	s_cselect_b32 s1, s71, s43
	s_cselect_b32 s20, s70, s42
	s_add_u32 s40, s40, 0x80080
	s_addc_u32 s41, s41, 0
	s_add_u32 s21, s42, 0x100
	s_addc_u32 s29, s43, 0
	s_mov_b32 s35, -2
	s_cmpk_lt_u32 s64, 0x100
	s_cbranch_scc1 .Lgy3
	s_barrier
.Lgy3:
.Lg4p_268:
	s_add_u32 s42, s40, 0xfff80080
	s_addc_u32 s43, s41, -1
	s_add_i32 s45, 0, 0x10000
	v_add_u32_e32 v0, s45, v149
	ds_read_b128 v[142:145], v0
	ds_read_b128 v[154:157], v0 offset:1024
	ds_read_b128 v[158:161], v0 offset:2048
	ds_read_b128 v[162:165], v0 offset:3072
	s_cmp_eq_u32 s35, 28
	s_cselect_b32 s49, s23, s43
	s_cselect_b32 s48, s27, s42
	s_cselect_b32 s43, s1, s29
	s_cselect_b32 s42, s20, s21
	v_lshl_add_u64 v[146:147], s[40:41], 0, v[138:139]
	s_add_i32 m0, s72, 0xc000
	ds_read_b128 v[166:169], v153
	ds_read_b128 v[170:173], v153 offset:1024
	ds_read_b128 v[174:177], v153 offset:2048
	ds_read_b128 v[178:181], v153 offset:3072
	ds_read_b128 v[182:185], v153 offset:4096
	ds_read_b128 v[186:189], v153 offset:5120
	ds_read_b128 v[190:193], v153 offset:6144
	ds_read_b128 v[194:197], v153 offset:7168
	global_load_lds_dwordx4 v[146:147], off
	v_lshl_add_u64 v[146:147], s[40:41], 0, v[140:141]
	s_add_i32 m0, s72, 0xe000
	s_nop 0
	global_load_lds_dwordx4 v[146:147], off
	s_waitcnt lgkmcnt(11)
	s_add_i32 s60, 0, 0x14000
	s_add_i32 s45, s45, s65
	v_add_u32_e32 v0, s60, v149
	v_lshl_add_u64 v[146:147], s[42:43], 0, v[132:133]
	s_mov_b32 m0, s45
	ds_read_b128 v[198:201], v0
	ds_read_b128 v[202:205], v0 offset:1024
	ds_read_b128 v[220:223], v0 offset:2048
	ds_read_b128 v[224:227], v0 offset:3072
	s_waitcnt vmcnt(8) lgkmcnt(0)
	s_barrier
	v_mfma_f32_16x16x32_f16 v[126:129], v[142:145], v[166:169], 0
	v_mfma_f32_16x16x32_f16 v[122:125], v[158:161], v[166:169], 0
	v_mfma_f32_16x16x32_f16 v[110:113], v[142:145], v[174:177], 0
	v_mfma_f32_16x16x32_f16 v[106:109], v[158:161], v[174:177], 0
	v_mfma_f32_16x16x32_f16 v[94:97], v[142:145], v[182:185], 0
	v_mfma_f32_16x16x32_f16 v[90:93], v[158:161], v[182:185], 0
	v_mfma_f32_16x16x32_f16 v[78:81], v[142:145], v[190:193], 0
	v_mfma_f32_16x16x32_f16 v[74:77], v[158:161], v[190:193], 0
	v_mfma_f32_16x16x32_f16 v[126:129], v[154:157], v[170:173], v[126:129]
	v_mfma_f32_16x16x32_f16 v[122:125], v[162:165], v[170:173], v[122:125]
	v_mfma_f32_16x16x32_f16 v[110:113], v[154:157], v[178:181], v[110:113]
	v_mfma_f32_16x16x32_f16 v[106:109], v[162:165], v[178:181], v[106:109]
	v_mfma_f32_16x16x32_f16 v[94:97], v[154:157], v[186:189], v[94:97]
	v_mfma_f32_16x16x32_f16 v[90:93], v[162:165], v[186:189], v[90:93]
	v_mfma_f32_16x16x32_f16 v[78:81], v[154:157], v[194:197], v[78:81]
	v_mfma_f32_16x16x32_f16 v[74:77], v[162:165], v[194:197], v[74:77]
	v_mfma_f32_16x16x32_f16 v[118:121], v[198:201], v[166:169], 0
	v_mfma_f32_16x16x32_f16 v[114:117], v[220:223], v[166:169], 0
	v_mfma_f32_16x16x32_f16 v[102:105], v[198:201], v[174:177], 0
	v_mfma_f32_16x16x32_f16 v[98:101], v[220:223], v[174:177], 0
	v_mfma_f32_16x16x32_f16 v[86:89], v[198:201], v[182:185], 0
	v_mfma_f32_16x16x32_f16 v[82:85], v[220:223], v[182:185], 0
	v_mfma_f32_16x16x32_f16 v[70:73], v[198:201], v[190:193], 0
	v_mfma_f32_16x16x32_f16 v[66:69], v[220:223], v[190:193], 0
	v_mfma_f32_16x16x32_f16 v[118:121], v[202:205], v[170:173], v[118:121]
	v_mfma_f32_16x16x32_f16 v[114:117], v[224:227], v[170:173], v[114:117]
	v_mfma_f32_16x16x32_f16 v[102:105], v[202:205], v[178:181], v[102:105]
	v_mfma_f32_16x16x32_f16 v[98:101], v[224:227], v[178:181], v[98:101]
	v_mfma_f32_16x16x32_f16 v[86:89], v[202:205], v[186:189], v[86:89]
	v_mfma_f32_16x16x32_f16 v[82:85], v[224:227], v[186:189], v[82:85]
	v_mfma_f32_16x16x32_f16 v[70:73], v[202:205], v[194:197], v[70:73]
	v_mfma_f32_16x16x32_f16 v[66:69], v[224:227], v[194:197], v[66:69]
	s_barrier
	global_load_lds_dwordx4 v[146:147], off
	v_lshl_add_u64 v[206:207], s[42:43], 0, v[136:137]
	s_add_i32 m0, s45, 0x2000
	s_nop 0
	global_load_lds_dwordx4 v[206:207], off
	s_mov_b32 m0, s72
	v_lshl_add_u64 v[212:213], s[48:49], 0, v[130:131]
	ds_read_b128 v[166:169], v153 offset:16384
	ds_read_b128 v[170:173], v153 offset:17408
	ds_read_b128 v[174:177], v153 offset:18432
	ds_read_b128 v[178:181], v153 offset:19456
	ds_read_b128 v[182:185], v153 offset:20480
	ds_read_b128 v[186:189], v153 offset:21504
	ds_read_b128 v[190:193], v153 offset:22528
	ds_read_b128 v[194:197], v153 offset:23552
	global_load_lds_dwordx4 v[212:213], off
	v_lshl_add_u64 v[228:229], s[48:49], 0, v[134:135]
	s_mov_b32 m0, s73
	s_nop 0
	global_load_lds_dwordx4 v[228:229], off
	s_add_u32 s50, s42, 0x80000
	s_addc_u32 s51, s43, 0
	s_add_i32 s45, s60, s65
	v_lshl_add_u64 v[232:233], s[50:51], 0, v[132:133]
	s_mov_b32 m0, s45
	s_nop 0
	global_load_lds_dwordx4 v[232:233], off
	v_lshl_add_u64 v[232:233], s[50:51], 0, v[136:137]
	s_add_i32 m0, s45, 0x2000
	s_nop 0
	global_load_lds_dwordx4 v[232:233], off
	s_waitcnt vmcnt(8) lgkmcnt(0)
	s_barrier
; #define PG8_STAGE(bufoff, gbase, voff) do { _Pragma("unroll") for (int _i = 0; _i < 2; ++_i) \
;         __builtin_amdgcn_global_load_lds((const unsigned*)((const char*)(gbase) + (voff)[_i]), (LAS unsigned*)(lds + (bufoff) + ldsw + _i * 8192), 16, 0, 0); } while (0)
; #define PG8_LDA(dst, b, h) do { _Pragma("unroll") for (int m = 0; m < 4; ++m) _Pragma("unroll") for (int k = 0; k < 2; ++k) dst[m][k] = *(const LAS h16x8*)(lds + PG8_SA(b, h) + aoff + m * 2048 + k * 1024); } while (0)
; #define PG8_LDB(dst, b, h) do { _Pragma("unroll") for (int n = 0; n < 2; ++n) _Pragma("unroll") for (int k = 0; k < 2; ++k) dst[n][k] = *(const LAS h16x8*)(lds + PG8_SB(b, h) + boff + n * 2048 + k * 1024); } while (0)
; #define PG8_MMA(ai, bj, At, Bt_) do { __builtin_amdgcn_s_setprio(1); _Pragma("unroll") for (int m = 0; m < 4; ++m) _Pragma("unroll") for (int n = 0; n < 2; ++n) _Pragma("unroll") for (int k = 0; k < 2; ++k) \
;         acc[ai][bj][m][n] = __builtin_amdgcn_mfma_f32_16x16x32_f16(Bt_[n][k], At[m][k], acc[ai][bj][m][n], 0, 0, 0); __builtin_amdgcn_s_setprio(0); } while (0)
; #define PG8_WAIT_V(n) asm volatile("s_waitcnt vmcnt(" #n ")" ::: "memory")
; #define PG8_WAIT_L(n) asm volatile("s_waitcnt lgkmcnt(" #n ")" ::: "memory")
; #define PG8_BAR __builtin_amdgcn_s_barrier()
; #define PG8_SCHED __builtin_amdgcn_sched_barrier(0)
; template <class Epi, class AMap>
; __device__ __forceinline__ void gemm_phase(LAS unsigned char* lds, const AMap am, const int lda, const h16* Bt, const int ldb, const int M, const int N, const int K, const Epi& E) {
;     ...
;             PG8_WAIT_V(6); PG8_BAR; PG8_MMA(1, 1, At, B1); PG8_BAR;
;             PG8_LDB(B0, 1, 0); PG8_SCHED; PG8_LDA(At, 1, 0); PG8_STAGE(PG8_SA(0, 1), a2 + hstepA, voffA);
;             PG8_WAIT_L(8); PG8_BAR; PG8_WAIT_L(0); PG8_MMA(0, 0, At, B0); PG8_BAR; PG8_SCHED;
;             PG8_LDB(B1, 1, 1); PG8_STAGE(PG8_SB(1, 0), b3, voffB);
;             PG8_BAR; PG8_WAIT_L(0); PG8_MMA(0, 1, At, B1); PG8_BAR;
;             PG8_LDA(At, 1, 1); PG8_STAGE(PG8_SA(1, 0), a3, voffA);
;             PG8_BAR; PG8_WAIT_L(0); PG8_MMA(1, 0, At, B0); PG8_BAR; PG8_SCHED;
	v_mfma_f32_16x16x32_f16 v[62:65], v[142:145], v[166:169], 0
	v_mfma_f32_16x16x32_f16 v[58:61], v[158:161], v[166:169], 0
	v_mfma_f32_16x16x32_f16 v[46:49], v[142:145], v[174:177], 0
	v_mfma_f32_16x16x32_f16 v[42:45], v[158:161], v[174:177], 0
	v_mfma_f32_16x16x32_f16 v[30:33], v[142:145], v[182:185], 0
	v_mfma_f32_16x16x32_f16 v[26:29], v[158:161], v[182:185], 0
	v_mfma_f32_16x16x32_f16 v[14:17], v[142:145], v[190:193], 0
	v_mfma_f32_16x16x32_f16 v[10:13], v[158:161], v[190:193], 0
	v_mfma_f32_16x16x32_f16 v[62:65], v[154:157], v[170:173], v[62:65]
	v_mfma_f32_16x16x32_f16 v[58:61], v[162:165], v[170:173], v[58:61]
	v_mfma_f32_16x16x32_f16 v[46:49], v[154:157], v[178:181], v[46:49]
	v_mfma_f32_16x16x32_f16 v[42:45], v[162:165], v[178:181], v[42:45]
	v_mfma_f32_16x16x32_f16 v[30:33], v[154:157], v[186:189], v[30:33]
	v_mfma_f32_16x16x32_f16 v[26:29], v[162:165], v[186:189], v[26:29]
	v_mfma_f32_16x16x32_f16 v[14:17], v[154:157], v[194:197], v[14:17]
	v_mfma_f32_16x16x32_f16 v[10:13], v[162:165], v[194:197], v[10:13]
	v_mfma_f32_16x16x32_f16 v[54:57], v[198:201], v[166:169], 0
	v_mfma_f32_16x16x32_f16 v[50:53], v[220:223], v[166:169], 0
	v_mfma_f32_16x16x32_f16 v[38:41], v[198:201], v[174:177], 0
	v_mfma_f32_16x16x32_f16 v[34:37], v[220:223], v[174:177], 0
	v_mfma_f32_16x16x32_f16 v[22:25], v[198:201], v[182:185], 0
	v_mfma_f32_16x16x32_f16 v[18:21], v[220:223], v[182:185], 0
	v_mfma_f32_16x16x32_f16 v[6:9], v[198:201], v[190:193], 0
	v_mfma_f32_16x16x32_f16 v[2:5], v[220:223], v[190:193], 0
	v_mfma_f32_16x16x32_f16 v[54:57], v[202:205], v[170:173], v[54:57]
	v_mfma_f32_16x16x32_f16 v[50:53], v[224:227], v[170:173], v[50:53]
	v_mfma_f32_16x16x32_f16 v[38:41], v[202:205], v[178:181], v[38:41]
	v_mfma_f32_16x16x32_f16 v[34:37], v[224:227], v[178:181], v[34:37]
	v_mfma_f32_16x16x32_f16 v[22:25], v[202:205], v[186:189], v[22:25]
	v_mfma_f32_16x16x32_f16 v[18:21], v[224:227], v[186:189], v[18:21]
	v_mfma_f32_16x16x32_f16 v[6:9], v[202:205], v[194:197], v[6:9]
	v_mfma_f32_16x16x32_f16 v[2:5], v[224:227], v[194:197], v[2:5]
	s_barrier
	s_add_i32 s45, 0, 0x18000
	v_add_u32_e32 v0, s45, v149
	ds_read_b128 v[142:145], v0
	ds_read_b128 v[154:157], v0 offset:1024
	ds_read_b128 v[158:161], v0 offset:2048
	ds_read_b128 v[162:165], v0 offset:3072
	s_add_u32 s48, s48, 0x80000
	s_addc_u32 s49, s49, 0
	s_mov_b32 m0, s74
	v_lshl_add_u64 v[232:233], s[48:49], 0, v[130:131]
	ds_read_b128 v[166:169], v153 offset:32768
	ds_read_b128 v[170:173], v153 offset:33792
	ds_read_b128 v[174:177], v153 offset:34816
	ds_read_b128 v[178:181], v153 offset:35840
	ds_read_b128 v[182:185], v153 offset:36864
	ds_read_b128 v[186:189], v153 offset:37888
	ds_read_b128 v[190:193], v153 offset:38912
	ds_read_b128 v[194:197], v153 offset:39936
	global_load_lds_dwordx4 v[232:233], off
	v_lshl_add_u64 v[232:233], s[48:49], 0, v[134:135]
	s_mov_b32 m0, s75
	s_nop 0
	global_load_lds_dwordx4 v[232:233], off
	s_waitcnt lgkmcnt(11)
	s_add_i32 s48, 0, 0x1c000
	s_add_i32 s45, s45, s65
	v_add_u32_e32 v0, s48, v149
	v_lshl_add_u64 v[146:147], v[146:147], 0, s[92:93]
	s_mov_b32 m0, s45
	ds_read_b128 v[198:201], v0
	ds_read_b128 v[202:205], v0 offset:1024
	ds_read_b128 v[220:223], v0 offset:2048
	ds_read_b128 v[224:227], v0 offset:3072
	s_waitcnt vmcnt(8) lgkmcnt(0)
	s_barrier
	v_mfma_f32_16x16x32_f16 v[126:129], v[142:145], v[166:169], v[126:129]
	v_mfma_f32_16x16x32_f16 v[122:125], v[158:161], v[166:169], v[122:125]
	v_mfma_f32_16x16x32_f16 v[110:113], v[142:145], v[174:177], v[110:113]
	v_mfma_f32_16x16x32_f16 v[106:109], v[158:161], v[174:177], v[106:109]
	v_mfma_f32_16x16x32_f16 v[94:97], v[142:145], v[182:185], v[94:97]
	v_mfma_f32_16x16x32_f16 v[90:93], v[158:161], v[182:185], v[90:93]
	v_mfma_f32_16x16x32_f16 v[78:81], v[142:145], v[190:193], v[78:81]
	v_mfma_f32_16x16x32_f16 v[74:77], v[158:161], v[190:193], v[74:77]
	v_mfma_f32_16x16x32_f16 v[126:129], v[154:157], v[170:173], v[126:129]
	v_mfma_f32_16x16x32_f16 v[122:125], v[162:165], v[170:173], v[122:125]
	v_mfma_f32_16x16x32_f16 v[110:113], v[154:157], v[178:181], v[110:113]
	v_mfma_f32_16x16x32_f16 v[106:109], v[162:165], v[178:181], v[106:109]
	v_mfma_f32_16x16x32_f16 v[94:97], v[154:157], v[186:189], v[94:97]
	v_mfma_f32_16x16x32_f16 v[90:93], v[162:165], v[186:189], v[90:93]
	v_mfma_f32_16x16x32_f16 v[78:81], v[154:157], v[194:197], v[78:81]
	v_mfma_f32_16x16x32_f16 v[74:77], v[162:165], v[194:197], v[74:77]
	v_mfma_f32_16x16x32_f16 v[118:121], v[198:201], v[166:169], v[118:121]
	v_mfma_f32_16x16x32_f16 v[114:117], v[220:223], v[166:169], v[114:117]
	v_mfma_f32_16x16x32_f16 v[102:105], v[198:201], v[174:177], v[102:105]
	v_mfma_f32_16x16x32_f16 v[98:101], v[220:223], v[174:177], v[98:101]
	v_mfma_f32_16x16x32_f16 v[86:89], v[198:201], v[182:185], v[86:89]
	v_mfma_f32_16x16x32_f16 v[82:85], v[220:223], v[182:185], v[82:85]
	v_mfma_f32_16x16x32_f16 v[70:73], v[198:201], v[190:193], v[70:73]
	v_mfma_f32_16x16x32_f16 v[66:69], v[220:223], v[190:193], v[66:69]
	v_mfma_f32_16x16x32_f16 v[118:121], v[202:205], v[170:173], v[118:121]
	v_mfma_f32_16x16x32_f16 v[114:117], v[224:227], v[170:173], v[114:117]
	v_mfma_f32_16x16x32_f16 v[102:105], v[202:205], v[178:181], v[102:105]
	v_mfma_f32_16x16x32_f16 v[98:101], v[224:227], v[178:181], v[98:101]
	v_mfma_f32_16x16x32_f16 v[86:89], v[202:205], v[186:189], v[86:89]
	v_mfma_f32_16x16x32_f16 v[82:85], v[224:227], v[186:189], v[82:85]
	v_mfma_f32_16x16x32_f16 v[70:73], v[202:205], v[194:197], v[70:73]
	v_mfma_f32_16x16x32_f16 v[66:69], v[224:227], v[194:197], v[66:69]
	s_barrier
; #define PG8_STAGE(bufoff, gbase, voff) do { _Pragma("unroll") for (int _i = 0; _i < 2; ++_i) \
;         __builtin_amdgcn_global_load_lds((const unsigned*)((const char*)(gbase) + (voff)[_i]), (LAS unsigned*)(lds + (bufoff) + ldsw + _i * 8192), 16, 0, 0); } while (0)
; #define PG8_MMA(ai, bj, At, Bt_) do { __builtin_amdgcn_s_setprio(1); _Pragma("unroll") for (int m = 0; m < 4; ++m) _Pragma("unroll") for (int n = 0; n < 2; ++n) _Pragma("unroll") for (int k = 0; k < 2; ++k) \
;         acc[ai][bj][m][n] = __builtin_amdgcn_mfma_f32_16x16x32_f16(Bt_[n][k], At[m][k], acc[ai][bj][m][n], 0, 0, 0); __builtin_amdgcn_s_setprio(0); } while (0)
; #define PG8_WAIT_V(n) asm volatile("s_waitcnt vmcnt(" #n ")" ::: "memory")
; #define PG8_WAIT_L(n) asm volatile("s_waitcnt lgkmcnt(" #n ")" ::: "memory")
; #define PG8_BAR __builtin_amdgcn_s_barrier()
; #define PG8_SCHED __builtin_amdgcn_sched_barrier(0)
; template <class Epi, class AMap>
; __device__ __forceinline__ void gemm_phase(LAS unsigned char* lds, const AMap am, const int lda, const h16* Bt, const int ldb, const int M, const int N, const int K, const Epi& E) {
;     ...
;             PG8_BAR; PG8_WAIT_L(0); PG8_MMA(1, 0, At, B0); PG8_BAR; PG8_SCHED;
;             PG8_STAGE(PG8_SB(1, 1), b3 + hstepB, voffB);
;             PG8_WAIT_V(6); PG8_BAR; PG8_MMA(1, 1, At, B1); PG8_BAR;
;         }
	global_load_lds_dwordx4 v[146:147], off
	v_lshl_add_u64 v[146:147], v[206:207], 0, s[92:93]
	s_add_i32 m0, s45, 0x2000
	s_nop 0
	global_load_lds_dwordx4 v[146:147], off
	s_mov_b32 m0, s77
	v_lshl_add_u64 v[146:147], v[212:213], 0, s[92:93]
	ds_read_b128 v[166:169], v153 offset:49152
	ds_read_b128 v[170:173], v153 offset:50176
	ds_read_b128 v[174:177], v153 offset:51200
	ds_read_b128 v[178:181], v153 offset:52224
	ds_read_b128 v[182:185], v153 offset:53248
	ds_read_b128 v[186:189], v153 offset:54272
	ds_read_b128 v[190:193], v153 offset:55296
	ds_read_b128 v[194:197], v153 offset:56320
	global_load_lds_dwordx4 v[146:147], off
	v_lshl_add_u64 v[146:147], v[228:229], 0, s[92:93]
	s_mov_b32 m0, s78
	s_nop 0
	global_load_lds_dwordx4 v[146:147], off
	s_add_u32 s42, s42, 0x80080
	s_addc_u32 s43, s43, 0
	s_add_i32 s45, s48, s65
	v_lshl_add_u64 v[232:233], s[42:43], 0, v[132:133]
	s_mov_b32 m0, s45
	s_nop 0
	global_load_lds_dwordx4 v[232:233], off
	v_lshl_add_u64 v[232:233], s[42:43], 0, v[136:137]
	s_add_i32 m0, s45, 0x2000
	s_nop 0
	global_load_lds_dwordx4 v[232:233], off
	s_add_i32 s35, s35, 2
	s_add_u32 s40, s40, 0x100
	s_addc_u32 s41, s41, 0
	s_add_u32 s21, s21, 0x100
	s_addc_u32 s29, s29, 0
	s_cmp_gt_u32 s35, 29
	s_waitcnt vmcnt(8) lgkmcnt(0)
	s_barrier
	v_mfma_f32_16x16x32_f16 v[62:65], v[142:145], v[166:169], v[62:65]
	v_mfma_f32_16x16x32_f16 v[58:61], v[158:161], v[166:169], v[58:61]
	v_mfma_f32_16x16x32_f16 v[46:49], v[142:145], v[174:177], v[46:49]
	v_mfma_f32_16x16x32_f16 v[42:45], v[158:161], v[174:177], v[42:45]
	v_mfma_f32_16x16x32_f16 v[30:33], v[142:145], v[182:185], v[30:33]
	v_mfma_f32_16x16x32_f16 v[26:29], v[158:161], v[182:185], v[26:29]
	v_mfma_f32_16x16x32_f16 v[14:17], v[142:145], v[190:193], v[14:17]
	v_mfma_f32_16x16x32_f16 v[10:13], v[158:161], v[190:193], v[10:13]
	v_mfma_f32_16x16x32_f16 v[62:65], v[154:157], v[170:173], v[62:65]
	v_mfma_f32_16x16x32_f16 v[58:61], v[162:165], v[170:173], v[58:61]
	v_mfma_f32_16x16x32_f16 v[46:49], v[154:157], v[178:181], v[46:49]
	v_mfma_f32_16x16x32_f16 v[42:45], v[162:165], v[178:181], v[42:45]
	v_mfma_f32_16x16x32_f16 v[30:33], v[154:157], v[186:189], v[30:33]
	v_mfma_f32_16x16x32_f16 v[26:29], v[162:165], v[186:189], v[26:29]
	v_mfma_f32_16x16x32_f16 v[14:17], v[154:157], v[194:197], v[14:17]
	v_mfma_f32_16x16x32_f16 v[10:13], v[162:165], v[194:197], v[10:13]
	v_mfma_f32_16x16x32_f16 v[54:57], v[198:201], v[166:169], v[54:57]
	v_mfma_f32_16x16x32_f16 v[50:53], v[220:223], v[166:169], v[50:53]
	v_mfma_f32_16x16x32_f16 v[38:41], v[198:201], v[174:177], v[38:41]
	v_mfma_f32_16x16x32_f16 v[34:37], v[220:223], v[174:177], v[34:37]
	v_mfma_f32_16x16x32_f16 v[22:25], v[198:201], v[182:185], v[22:25]
	v_mfma_f32_16x16x32_f16 v[18:21], v[220:223], v[182:185], v[18:21]
	v_mfma_f32_16x16x32_f16 v[6:9], v[198:201], v[190:193], v[6:9]
	v_mfma_f32_16x16x32_f16 v[2:5], v[220:223], v[190:193], v[2:5]
	v_mfma_f32_16x16x32_f16 v[54:57], v[202:205], v[170:173], v[54:57]
	v_mfma_f32_16x16x32_f16 v[50:53], v[224:227], v[170:173], v[50:53]
	v_mfma_f32_16x16x32_f16 v[38:41], v[202:205], v[178:181], v[38:41]
	v_mfma_f32_16x16x32_f16 v[34:37], v[224:227], v[178:181], v[34:37]
	v_mfma_f32_16x16x32_f16 v[22:25], v[202:205], v[186:189], v[22:25]
	v_mfma_f32_16x16x32_f16 v[18:21], v[224:227], v[186:189], v[18:21]
	v_mfma_f32_16x16x32_f16 v[6:9], v[202:205], v[194:197], v[6:9]
	v_mfma_f32_16x16x32_f16 v[2:5], v[224:227], v[194:197], v[2:5]
	s_barrier
	s_cbranch_scc1 .Lg4x_268

; #define PG8_WAIT_V(n) asm volatile("s_waitcnt vmcnt(" #n ")" ::: "memory")
; #define PG8_BAR __builtin_amdgcn_s_barrier()
; template <class Epi, class AMap>
; __device__ __forceinline__ void gemm_phase(LAS unsigned char* lds, const AMap am, const int lda, const h16* Bt, const int ldb, const int M, const int N, const int K, const Epi& E) {
;     ...
;     PG8_WAIT_V(0);
;     if (wr == 0) PG8_BAR;
;     PG8_BAR;
.LBB0_397:
	s_waitcnt vmcnt(0)
	s_cmpk_gt_u32 s64, 0xff
	s_cbranch_scc1 .LBB0_399
.LBB0_399:
	v_readlane_b32 s68, v254, 38
	v_readlane_b32 s29, v254, 37
	v_readlane_b32 s69, v254, 39
	v_readlane_b32 s70, v254, 40
	v_readlane_b32 s71, v254, 41
	v_readlane_b32 s72, v254, 42
	v_readlane_b32 s73, v254, 43
	v_readlane_b32 s74, v254, 44
	v_readlane_b32 s75, v254, 45
	v_readlane_b32 s76, v254, 46
	v_readlane_b32 s77, v254, 47
	v_readlane_b32 s80, v254, 50
	v_readlane_b32 s81, v254, 51
	v_readlane_b32 s82, v254, 52
	v_readlane_b32 s83, v254, 53
	v_readlane_b32 s48, v254, 63
	v_readlane_b32 s2, v255, 12
	s_barrier
	v_readlane_b32 s78, v254, 48
	v_readlane_b32 s79, v254, 49
	v_readlane_b32 s49, v255, 0

; __device__ __forceinline__ int otid() { int t = (int)threadIdx.x; asm volatile("" : "+v"(t)); return t; }
; __device__ __forceinline__ int obid() { int t = (int)blockIdx.x; asm volatile("" : "+s"(t)); return t; }
; #define PG8_WAIT_V(n) asm volatile("s_waitcnt vmcnt(" #n ")" ::: "memory")
; #define PG8_BAR __builtin_amdgcn_s_barrier()
; template <class Epi, class AMap>
; __device__ __forceinline__ void gemm_phase(LAS unsigned char* lds, const AMap am, const int lda, const h16* Bt, const int ldb, const int M, const int N, const int K, const Epi& E) {
;     const int tid = otid(), wid = __builtin_amdgcn_readfirstlane(tid >> 6), lane = tid & 63, wr = wid >> 2, wc = wid & 3, fr = lane & 15, fq = lane >> 4;
;     const int nt = K / BK;
;     Order S; S.init(M, N, (int)gridDim.x, obid());
;     unsigned voffA[2], voffB[2];
; #pragma unroll
;     for (int i = 0; i < 2; ++i) { int R, C; stage_rc(tid * 16 + i * 8192, R, C); const int Rb = Epi::PERM ? ((R & ~31) + perm32(R & 31)) : R;
;         voffA[i] = (unsigned)(R * lda + C) * 2u; voffB[i] = (unsigned)(Rb * ldb + C) * 2u; }
;     const size_t kstep = (size_t)(BK * 2);
;     const size_t hstepA = (size_t)HALF * lda * 2, hstepB = (size_t)HALF * ldb * 2;
;     const size_t tstepA = 2 * hstepA, tstepB = 2 * hstepB;
;     const unsigned ldsw = (unsigned)wid * 1024u;
;     const int aoff = lds_byte(wr * 64 + fr, fq * 8), boff = lds_byte(wc * 32 + fr, fq * 8);
;     ...
;     Unit cur, nxt; int ui = 0;
;     if (!S.next(0, cur)) return;
;     f32x4 acc[2][2][4][2];
; #pragma unroll
;     for (int a = 0; a < 2; ++a)
; #pragma unroll
;         for (int b = 0; b < 2; ++b)
; #pragma unroll
;             for (int m = 0; m < 4; ++m)
; #pragma unroll
;                 for (int n = 0; n < 2; ++n) acc[a][b][m][n] = (f32x4){0.f, 0.f, 0.f, 0.f};
;     h16x8 At[4][2], B0[2][2], B1[2][2];
;     const char* cA = am(cur.pn) + (size_t)cur.pm * tstepA; const char* cB = (const char*)Bt + (size_t)cur.pn * tstepB;
;     PG8_STAGE(PG8_SB(0, 0), cB, voffB); PG8_STAGE(PG8_SA(0, 0), cA, voffA); PG8_STAGE(PG8_SB(0, 1), cB + hstepB, voffB); PG8_STAGE(PG8_SA(0, 1), cA + hstepA, voffA);
;     if (wr == 1) PG8_BAR;
;     PG8_WAIT_V(4); PG8_BAR;
;     PG8_STAGE(PG8_SB(1, 0), cB + kstep, voffB); PG8_STAGE(PG8_SA(1, 0), cA + kstep, voffA); PG8_STAGE(PG8_SB(1, 1), cB + hstepB + kstep, voffB);
;     PG8_WAIT_V(6); PG8_BAR;
.LBB0_607:
	v_ashrrev_i32_e32 v0, 31, v18
	v_lshrrev_b32_e32 v0, 26, v0
	v_add_u32_e32 v0, v18, v0
	v_ashrrev_i32_e32 v10, 6, v0
	v_bfe_i32 v0, v18, 27, 1
	s_waitcnt vmcnt(0)
	v_lshlrev_b32_e32 v2, 4, v18
	v_lshrrev_b32_e32 v0, 22, v0
	v_add_u32_e32 v0, v2, v0
	v_and_b32_e32 v0, 0xfffffc00, v0
	v_sub_u32_e32 v0, v2, v0
	v_lshrrev_b32_e32 v3, 4, v0
	v_bitop3_b32 v3, v3, v0, 32 bitop3:0x6c
	v_ashrrev_i32_e32 v0, 31, v0
	v_lshrrev_b32_e32 v0, 26, v0
	v_lshlrev_b32_e32 v4, 3, v10
	v_add_u32_e32 v0, v3, v0
	v_and_b32_e32 v4, -16, v4
	v_ashrrev_i32_e32 v12, 6, v0
	v_add_u32_e32 v0, v12, v4
	v_lshlrev_b32_e32 v4, 5, v10
	v_and_b32_e32 v11, 32, v4
	v_mul_i32_i24_e32 v4, 64, v12
	s_ashr_i32 s1, s71, 6
	v_sub_u32_e32 v3, v3, v4
	v_mov_b32_e32 v7, 1
	v_ashrrev_i16_sdwa v3, v7, sext(v3) dst_sel:DWORD dst_unused:UNUSED_PAD src0_sel:DWORD src1_sel:BYTE_0
	s_ashr_i32 s20, s71, 8
	s_lshl_b32 s73, s1, 10
	v_bfe_i32 v13, v3, 0, 16
	v_and_b32_e32 v6, 3, v12
	s_mov_b32 s4, 0x7fffe0
	s_movk_i32 s3, 0x1c00
	s_add_u32 s74, s10, 0x1c00000
	v_add_u32_e32 v3, v11, v13
	v_lshlrev_b32_e32 v4, 1, v0
	v_lshrrev_b32_e32 v5, 2, v0
	v_and_or_b32 v6, v0, s4, v6
	v_mul_lo_u32 v0, v0, s3
	v_add_u32_e32 v2, 0x2000, v2
	s_addc_u32 s75, s11, 0
	s_add_i32 s0, s21, s0
	v_add_lshl_u32 v138, v3, v0, 1
	v_lshlrev_b32_e32 v0, 1, v3
	v_ashrrev_i32_e32 v3, 31, v2
	s_ashr_i32 s21, s0, 31
	v_lshrrev_b32_e32 v3, 22, v3
	s_lshr_b32 s21, s21, 27
	v_add_u32_e32 v3, v2, v3
	s_add_i32 s21, s0, s21
	v_ashrrev_i32_e32 v14, 10, v3
	s_ashr_i32 s22, s21, 5
	s_and_b32 s21, s21, 0xffe0
	v_mul_i32_i24_e32 v3, 0x400, v14
	s_sub_i32 s21, s0, s21
	v_sub_u32_e32 v2, v2, v3
	s_bfe_i32 s0, s21, 0x80000
	v_and_b32_e32 v4, 24, v4
	v_and_b32_e32 v5, 4, v5
	v_lshrrev_b32_e32 v3, 4, v2
	s_bfe_u32 s0, s0, 0x2000d
	v_or3_b32 v4, v6, v5, v4
	v_bitop3_b32 v2, v3, v2, 32 bitop3:0x6c
	s_add_i32 s23, s21, s0
	v_lshl_add_u32 v0, v4, 9, v0
	v_ashrrev_i32_e32 v4, 31, v2
	s_bfe_i32 s0, s23, 0x80000
	s_and_b32 s23, s23, 0xfc
	v_lshrrev_b32_e32 v4, 26, v4
	s_sext_i32_i16 s0, s0
	s_sub_i32 s21, s21, s23
	v_add_u32_e32 v4, v2, v4
	s_lshl_b32 s22, s22, 2
	s_lshr_b32 s0, s0, 2
	s_sext_i32_i8 s21, s21
	v_lshlrev_b32_e32 v3, 3, v14
	v_ashrrev_i32_e32 v16, 6, v4
	v_and_b32_e32 v4, 0xc0, v4
	s_add_i32 s35, s22, s21
	s_bfe_i64 s[22:23], s[0:1], 0x100000
	v_and_b32_e32 v3, -16, v3
	v_sub_u32_e32 v2, v2, v4
	s_lshl_b64 s[22:23], s[22:23], 17
	v_add_u32_e32 v3, v16, v3
	v_lshlrev_b32_e32 v5, 5, v14
	v_ashrrev_i16_sdwa v2, v7, sext(v2) dst_sel:DWORD dst_unused:UNUSED_PAD src0_sel:DWORD src1_sel:BYTE_0
	s_add_u32 s26, s74, s22
	v_and_b32_e32 v15, 32, v5
	v_bfe_i32 v17, v2, 0, 16
	v_lshlrev_b32_e32 v4, 1, v3
	v_lshrrev_b32_e32 v5, 2, v3
	v_and_b32_e32 v6, 3, v16
	s_addc_u32 s27, s75, s23
	s_add_i32 s76, s73, 0
	v_add_u32_e32 v2, v15, v17
	v_and_b32_e32 v4, 24, v4
	v_and_b32_e32 v5, 4, v5
	v_and_or_b32 v6, v3, s4, v6
	v_mul_lo_u32 v3, v3, s3
	s_add_i32 m0, s76, 0x10000
	v_or3_b32 v4, v6, v5, v4
	v_add_lshl_u32 v140, v2, v3, 1
	v_lshlrev_b32_e32 v2, 1, v2
	s_mul_i32 s29, s35, 0x380000
	global_load_lds_dwordx4 v0, s[26:27]
	s_add_i32 m0, s76, 0x12000
	v_lshl_add_u32 v142, v4, 9, v2
	s_mul_hi_i32 s21, s35, 0x380000
	s_add_u32 s22, s2, s29
	v_readlane_b32 s2, v252, 34
	global_load_lds_dwordx4 v142, s[26:27]
	s_addc_u32 s23, s2, s21
	s_mov_b32 m0, s76
	s_add_i32 s77, s76, 0x2000
	global_load_lds_dwordx4 v138, s[22:23]
	s_mov_b32 m0, s77
	s_add_u32 s38, s26, 0x10000
	global_load_lds_dwordx4 v140, s[22:23]
	s_addc_u32 s39, s27, 0
	s_add_i32 m0, s76, 0x14000
	v_mov_b32_e32 v143, v1
	global_load_lds_dwordx4 v0, s[38:39]
	s_add_i32 m0, s76, 0x16000
	v_mov_b32_e32 v139, v1
	global_load_lds_dwordx4 v142, s[38:39]
	s_add_u32 s38, s22, 0x1c0000
	s_addc_u32 s39, s23, 0
	s_add_i32 s78, s76, 0x4000
	s_mov_b32 m0, s78
	s_add_i32 s79, s76, 0x6000
	global_load_lds_dwordx4 v138, s[38:39]
	s_mov_b32 m0, s79
	v_mov_b32_e32 v141, v1
	global_load_lds_dwordx4 v140, s[38:39]
	v_lshl_add_u64 v[8:9], s[26:27], 0, v[0:1]
	v_lshl_add_u64 v[6:7], s[26:27], 0, v[142:143]
	v_lshl_add_u64 v[4:5], s[22:23], 0, v[138:139]
	s_cmp_lg_u32 s20, 1
	v_lshl_add_u64 v[2:3], s[22:23], 0, v[140:141]
	s_cbranch_scc1 .LBB0_609
.LBB0_609:
	v_lshrrev_b32_e32 v20, 1, v18
	v_and_b32_e32 v20, 24, v20
	v_and_b32_e32 v19, 15, v18
	v_lshlrev_b32_e32 v21, 1, v20
	v_lshlrev_b32_e32 v18, 2, v18
	s_sext_i32_i8 s50, s0
	v_lshl_or_b32 v154, s20, 6, v19
	v_lshl_or_b32 v19, v19, 6, v21
	s_lshl_b32 s0, s20, 13
	v_and_b32_e32 v18, 32, v18
	v_bitop3_b32 v21, v19, s0, v18 bitop3:0xde
	s_lshl_b32 s0, s1, 5
	s_and_b32 s20, s0, 0x60
	s_lshl_b32 s0, s20, 7
	v_bitop3_b32 v155, v19, s0, v18 bitop3:0xde
	v_readlane_b32 s0, v254, 38
	v_readlane_b32 s10, v254, 48
	v_readlane_b32 s11, v254, 49
	s_add_u32 s40, s10, s46
	s_addc_u32 s41, s11, s47
	s_add_i32 m0, s76, 0x18000
	v_lshl_add_u64 v[8:9], v[8:9], 0, s[92:93]
	s_waitcnt vmcnt(0)
	s_barrier
	global_load_lds_dwordx4 v[8:9], off
	v_lshl_add_u64 v[6:7], v[6:7], 0, s[92:93]
	s_add_i32 m0, s76, 0x1a000
	s_add_i32 s80, s76, 0x8000
	s_add_i32 s81, s76, 0xa000
	v_readlane_b32 s1, v254, 39
	global_load_lds_dwordx4 v[6:7], off
	v_lshl_add_u64 v[4:5], v[4:5], 0, s[92:93]
	s_mov_b32 m0, s80
	s_add_u32 s0, s26, 0x10080
	global_load_lds_dwordx4 v[4:5], off
	v_lshl_add_u64 v[2:3], v[2:3], 0, s[92:93]
	s_mov_b32 m0, s81
	s_addc_u32 s1, s27, 0
	global_load_lds_dwordx4 v[2:3], off
	s_add_i32 m0, s76, 0x1c000
	v_lshl_add_u64 v[2:3], s[0:1], 0, v[0:1]
	global_load_lds_dwordx4 v[2:3], off
	v_lshl_add_u64 v[2:3], s[0:1], 0, v[142:143]
	s_add_i32 m0, s76, 0x1e000
	v_readlane_b32 s3, v254, 41
	global_load_lds_dwordx4 v[2:3], off
	v_readlane_b32 s2, v254, 40
	s_movk_i32 s3, 0x1c00
	v_lshrrev_b32_e32 v3, 1, v10
	v_mul_lo_u32 v2, v12, s3
	s_mov_b32 s2, 0x1c000
	v_mad_u64_u32 v[2:3], s[0:1], v3, s2, v[2:3]
	v_readlane_b32 s4, v254, 42
	v_readlane_b32 s5, v254, 43
	v_or_b32_e32 v2, v2, v11
	v_add_lshl_u32 v2, v2, v13, 1
	v_mov_b32_e32 v3, v1
	s_mov_b64 s[4:5], 0x1c0080
	v_lshl_add_u64 v[144:145], v[2:3], 0, s[4:5]
	v_lshrrev_b32_e32 v3, 1, v14
	v_mul_lo_u32 v2, v16, s3
	v_mad_u64_u32 v[2:3], s[0:1], v3, s2, v[2:3]
	v_readlane_b32 s8, v254, 46
	v_readlane_b32 s9, v254, 47
	s_waitcnt vmcnt(6)
	v_or_b32_e32 v2, v2, v15
	v_readlane_b32 s12, v254, 50
	v_readlane_b32 s13, v254, 51
	v_readlane_b32 s14, v254, 52
	v_readlane_b32 s15, v254, 53
	s_cmp_gt_i32 s61, 63
	v_add_lshl_u32 v2, v2, v17, 1
	v_mov_b32_e32 v3, v1
	v_readlane_b32 s8, v254, 58
	s_cselect_b64 s[42:43], -1, 0
	s_add_i32 s82, s24, -2
	v_or_b32_e32 v156, s20, v20
	v_lshl_add_u64 v[146:147], v[2:3], 0, s[4:5]
	s_mov_b32 s83, 0
	v_add_u32_e32 v157, 0, v21
	v_readlane_b32 s9, v254, 59
	v_readlane_b32 s12, v254, 62
	v_readlane_b32 s2, v252, 33
	s_movk_i32 s5, 0x3800
	s_movk_i32 s13, 0x2b00
	s_mov_b64 s[10:11], 0x80000
	s_mov_b64 s[14:15], 0xa0000
	v_readlane_b32 s6, v254, 44
	v_readlane_b32 s7, v254, 45
	s_barrier
	s_branch .LBB0_611

; __device__ __forceinline__ float sigmoidf_(float x) { return 1.0f / (1.0f + __expf(-x)); }
;     template <int GI>
;     __device__ __forceinline__ void body(const f32x4 (&acc)[2][2][4][2], int row0, int colt) const {
;     ...
;         for (int bj = 0; bj < 2; ++bj) {
;             const int c = colt + bj * 128;
;             f32x4 b0 = (f32x4){0.f, 0.f, 0.f, 0.f}, b1 = b0;
;             if (GI == 0) { b0 = *(const f32x4*)(w0 + c); b1 = *(const f32x4*)(w0 + c + 4); }
;             else if (GI == 1) { b0 = *(const f32x4*)(a0 + c); b1 = *(const f32x4*)(a0 + c + 4); }
;             else if (GI == 3) { b0 = *(const f32x4*)(v0 + c); b1 = *(const f32x4*)(v0 + c + 4); }
; #pragma unroll
;             for (int ai = 0; ai < 2; ++ai)
; #pragma unroll
;                 for (int m = 0; m < 4; ++m) {
;                     const size_t row = (size_t)(row0 + ai * 128 + m * 16);
;                     f32x4 x0 = acc[ai][bj][m][0] + b0, x1 = acc[ai][bj][m][1] + b1;
;                     if (GI == 0) {
; #pragma unroll
;                         for (int j = 0; j < 4; ++j) {
;                             x0[j] = 0.6065306597126334f * sigmoidf_(x0[j]); x1[j] = 0.6065306597126334f * sigmoidf_(x1[j]); }
;                         *(u32x4*)(DEC + row * DM + c) = pack8(x0, x1);
.Lgx4:
	s_waitcnt vmcnt(0)
	v_pk_add_f32 v[160:161], v[136:137], v[92:93]
	v_pk_add_f32 v[130:131], v[130:131], v[94:95]
	v_pk_add_f32 v[158:159], v[132:133], v[96:97]
	v_mul_f32_e32 v130, 0xbfb8aa3b, v130
	v_mul_f32_e32 v131, 0xbfb8aa3b, v131
	v_exp_f32_e32 v130, v130
	v_exp_f32_e32 v131, v131
	v_pk_add_f32 v[132:133], v[134:135], v[90:91]
	v_mul_f32_e32 v134, 0xbfb8aa3b, v158
	v_mul_f32_e32 v135, 0xbfb8aa3b, v159
	v_pk_add_f32 v[130:131], v[130:131], 1.0 op_sel_hi:[1,0]
	v_exp_f32_e32 v136, v134
	v_div_scale_f32 v158, s[0:1], v131, v131, 1.0
	v_rcp_f32_e32 v159, v158
	v_mul_f32_e32 v134, 0xbfb8aa3b, v160
	v_exp_f32_e32 v137, v135
	v_mul_f32_e32 v135, 0xbfb8aa3b, v161
	v_fma_f32 v160, -v158, v159, 1.0
	v_fmac_f32_e32 v159, v160, v159
	v_div_scale_f32 v160, vcc, 1.0, v131, 1.0
	v_mul_f32_e32 v161, v160, v159
	v_fma_f32 v162, -v158, v161, v160
	v_fmac_f32_e32 v161, v162, v159
	v_fma_f32 v158, -v158, v161, v160
	v_div_fmas_f32 v158, v158, v159, v161
	v_div_fixup_f32 v131, v158, v131, 1.0
	v_div_scale_f32 v158, s[0:1], v130, v130, 1.0
	v_rcp_f32_e32 v159, v158
	v_pk_add_f32 v[136:137], v[136:137], 1.0 op_sel_hi:[1,0]
	v_mul_f32_e32 v132, 0xbfb8aa3b, v132
	v_mul_f32_e32 v133, 0xbfb8aa3b, v133
	v_fma_f32 v160, -v158, v159, 1.0
	v_fmac_f32_e32 v159, v160, v159
	v_div_scale_f32 v160, vcc, 1.0, v130, 1.0
	v_mul_f32_e32 v161, v160, v159
	v_fma_f32 v162, -v158, v161, v160
	v_fmac_f32_e32 v161, v162, v159
	v_fma_f32 v158, -v158, v161, v160
	v_div_fmas_f32 v158, v158, v159, v161
	v_div_fixup_f32 v130, v158, v130, 1.0
	v_pk_mul_f32 v[130:131], v[130:131], s[4:5] op_sel_hi:[1,0]
	v_exp_f32_e32 v132, v132
	v_cvt_pk_f16_f32 v130, v130, v131
	v_div_scale_f32 v131, s[0:1], v137, v137, 1.0
	v_rcp_f32_e32 v158, v131
	v_exp_f32_e32 v133, v133
	v_exp_f32_e32 v134, v134
	v_exp_f32_e32 v135, v135
	v_fma_f32 v159, -v131, v158, 1.0
	v_fmac_f32_e32 v158, v159, v158
	v_div_scale_f32 v159, vcc, 1.0, v137, 1.0
	v_mul_f32_e32 v160, v159, v158
	v_fma_f32 v161, -v131, v160, v159
	v_fmac_f32_e32 v160, v161, v158
	v_fma_f32 v131, -v131, v160, v159
	v_div_fmas_f32 v131, v131, v158, v160
	v_div_fixup_f32 v137, v131, v137, 1.0
	v_div_scale_f32 v131, s[0:1], v136, v136, 1.0
	v_rcp_f32_e32 v158, v131
	v_pk_add_f32 v[132:133], v[132:133], 1.0 op_sel_hi:[1,0]
	v_pk_add_f32 v[134:135], v[134:135], 1.0 op_sel_hi:[1,0]
	v_fma_f32 v159, -v131, v158, 1.0
	v_fmac_f32_e32 v158, v159, v158
	v_div_scale_f32 v159, vcc, 1.0, v136, 1.0
	v_mul_f32_e32 v160, v159, v158
	v_fma_f32 v161, -v131, v160, v159
	v_fmac_f32_e32 v160, v161, v158
	v_fma_f32 v131, -v131, v160, v159
	v_div_fmas_f32 v131, v131, v158, v160
	v_div_fixup_f32 v136, v131, v136, 1.0
	v_pk_mul_f32 v[136:137], v[136:137], s[4:5] op_sel_hi:[1,0]
	s_nop 0
	v_cvt_pk_f16_f32 v131, v136, v137
	v_div_scale_f32 v136, s[0:1], v133, v133, 1.0
	v_rcp_f32_e32 v137, v136
	s_nop 0
	v_fma_f32 v158, -v136, v137, 1.0
	v_fmac_f32_e32 v137, v158, v137
	v_div_scale_f32 v158, vcc, 1.0, v133, 1.0
	v_mul_f32_e32 v159, v158, v137
	v_fma_f32 v160, -v136, v159, v158
	v_fmac_f32_e32 v159, v160, v137
	v_fma_f32 v136, -v136, v159, v158
	v_div_fmas_f32 v136, v136, v137, v159
	v_div_fixup_f32 v133, v136, v133, 1.0
	v_div_scale_f32 v136, s[0:1], v132, v132, 1.0
	v_rcp_f32_e32 v137, v136
	s_nop 0
	v_fma_f32 v158, -v136, v137, 1.0
	v_fmac_f32_e32 v137, v158, v137
	v_div_scale_f32 v158, vcc, 1.0, v132, 1.0
	v_mul_f32_e32 v159, v158, v137
	v_fma_f32 v160, -v136, v159, v158
	v_fmac_f32_e32 v159, v160, v137
	v_fma_f32 v136, -v136, v159, v158
	v_div_fmas_f32 v136, v136, v137, v159
	v_div_fixup_f32 v132, v136, v132, 1.0
	v_pk_mul_f32 v[132:133], v[132:133], s[4:5] op_sel_hi:[1,0]
	s_nop 0
	v_cvt_pk_f16_f32 v132, v132, v133
	v_div_scale_f32 v133, s[0:1], v135, v135, 1.0
	v_rcp_f32_e32 v136, v133
	s_nop 0
	v_fma_f32 v137, -v133, v136, 1.0
	v_fmac_f32_e32 v136, v137, v136
	v_div_scale_f32 v137, vcc, 1.0, v135, 1.0
	v_mul_f32_e32 v158, v137, v136
	v_fma_f32 v159, -v133, v158, v137
	v_fmac_f32_e32 v158, v159, v136
	v_fma_f32 v133, -v133, v158, v137
	v_div_fmas_f32 v133, v133, v136, v158
	v_div_fixup_f32 v135, v133, v135, 1.0
	v_div_scale_f32 v133, s[0:1], v134, v134, 1.0
	v_rcp_f32_e32 v136, v133
	s_nop 0
	v_fma_f32 v137, -v133, v136, 1.0
	v_fmac_f32_e32 v136, v137, v136
	v_div_scale_f32 v137, vcc, 1.0, v134, 1.0
	v_mul_f32_e32 v158, v137, v136
	v_fma_f32 v159, -v133, v158, v137
	v_fmac_f32_e32 v158, v159, v136
	v_fma_f32 v133, -v133, v158, v137
	v_div_fmas_f32 v133, v133, v136, v158
	v_div_fixup_f32 v134, v133, v134, 1.0
	v_pk_mul_f32 v[134:135], v[134:135], s[4:5] op_sel_hi:[1,0]
	v_lshlrev_b64 v[136:137], 1, v[152:153]
	v_cvt_pk_f16_f32 v133, v134, v135
	v_lshlrev_b64 v[134:135], 12, v[150:151]
	v_lshl_add_u64 v[134:135], s[6:7], 0, v[134:135]
	v_lshl_add_u64 v[134:135], v[134:135], 0, v[136:137]
	global_store_dwordx4 v[134:135], v[130:133], off
	v_pk_add_f32 v[122:123], v[122:123], v[90:91]
	v_pk_add_f32 v[126:127], v[126:127], v[94:95]
	v_mul_f32_e32 v122, 0xbfb8aa3b, v122
	v_exp_f32_e32 v152, v122
	v_mul_f32_e32 v122, 0xbfb8aa3b, v127
	v_pk_add_f32 v[128:129], v[128:129], v[96:97]
	v_mul_f32_e32 v126, 0xbfb8aa3b, v126
	v_exp_f32_e32 v133, v122
	v_mul_f32_e32 v122, 0xbfb8aa3b, v123
	v_pk_add_f32 v[124:125], v[124:125], v[92:93]
	v_exp_f32_e32 v132, v126
	v_exp_f32_e32 v153, v122
	v_mul_f32_e32 v122, 0xbfb8aa3b, v128
	v_exp_f32_e32 v128, v122
	v_mul_f32_e32 v122, 0xbfb8aa3b, v124
	v_exp_f32_e32 v126, v122
	v_mul_f32_e32 v122, 0xbfb8aa3b, v129
	v_exp_f32_e32 v129, v122
	v_mul_f32_e32 v122, 0xbfb8aa3b, v125
	v_exp_f32_e32 v127, v122
	v_pk_add_f32 v[122:123], v[132:133], 1.0 op_sel_hi:[1,0]
	v_or_b32_e32 v130, 16, v150
	v_div_scale_f32 v124, s[0:1], v123, v123, 1.0
; __device__ __forceinline__ float sigmoidf_(float x) { return 1.0f / (1.0f + __expf(-x)); }
;     template <int GI>
;     __device__ __forceinline__ void body(const f32x4 (&acc)[2][2][4][2], int row0, int colt) const {
;     ...
;         for (int bj = 0; bj < 2; ++bj) {
;             const int c = colt + bj * 128;
;             f32x4 b0 = (f32x4){0.f, 0.f, 0.f, 0.f}, b1 = b0;
;             if (GI == 0) { b0 = *(const f32x4*)(w0 + c); b1 = *(const f32x4*)(w0 + c + 4); }
;             else if (GI == 1) { b0 = *(const f32x4*)(a0 + c); b1 = *(const f32x4*)(a0 + c + 4); }
;             else if (GI == 3) { b0 = *(const f32x4*)(v0 + c); b1 = *(const f32x4*)(v0 + c + 4); }
; #pragma unroll
;             for (int ai = 0; ai < 2; ++ai)
; #pragma unroll
;                 for (int m = 0; m < 4; ++m) {
;                     const size_t row = (size_t)(row0 + ai * 128 + m * 16);
;                     f32x4 x0 = acc[ai][bj][m][0] + b0, x1 = acc[ai][bj][m][1] + b1;
;                     if (GI == 0) {
; #pragma unroll
;                         for (int j = 0; j < 4; ++j) {
;                             x0[j] = 0.6065306597126334f * sigmoidf_(x0[j]); x1[j] = 0.6065306597126334f * sigmoidf_(x1[j]); }
;                         *(u32x4*)(DEC + row * DM + c) = pack8(x0, x1);
	v_rcp_f32_e32 v125, v124
	v_pk_add_f32 v[126:127], v[126:127], 1.0 op_sel_hi:[1,0]
	v_ashrrev_i32_e32 v131, 31, v130
	v_fma_f32 v132, -v124, v125, 1.0
	v_fmac_f32_e32 v125, v132, v125
	v_div_scale_f32 v132, vcc, 1.0, v123, 1.0
	v_mul_f32_e32 v133, v132, v125
	v_fma_f32 v151, -v124, v133, v132
	v_fmac_f32_e32 v133, v151, v125
	v_fma_f32 v124, -v124, v133, v132
	v_div_fmas_f32 v124, v124, v125, v133
	v_div_fixup_f32 v123, v124, v123, 1.0
	v_div_scale_f32 v124, s[0:1], v122, v122, 1.0
	v_rcp_f32_e32 v125, v124
	s_nop 0
	v_fma_f32 v132, -v124, v125, 1.0
	v_fmac_f32_e32 v125, v132, v125
	v_div_scale_f32 v132, vcc, 1.0, v122, 1.0
	v_mul_f32_e32 v133, v132, v125
	v_fma_f32 v151, -v124, v133, v132
	v_fmac_f32_e32 v133, v151, v125
	v_fma_f32 v124, -v124, v133, v132
	v_div_fmas_f32 v124, v124, v125, v133
	v_div_fixup_f32 v122, v124, v122, 1.0
	v_pk_mul_f32 v[122:123], v[122:123], s[4:5] op_sel_hi:[1,0]
	v_pk_add_f32 v[124:125], v[128:129], 1.0 op_sel_hi:[1,0]
	v_cvt_pk_f16_f32 v122, v122, v123
	v_div_scale_f32 v123, s[0:1], v125, v125, 1.0
	v_rcp_f32_e32 v128, v123
	s_nop 0
	v_fma_f32 v129, -v123, v128, 1.0
	v_fmac_f32_e32 v128, v129, v128
	v_div_scale_f32 v129, vcc, 1.0, v125, 1.0
	v_mul_f32_e32 v132, v129, v128
	v_fma_f32 v133, -v123, v132, v129
	v_fmac_f32_e32 v132, v133, v128
	v_fma_f32 v123, -v123, v132, v129
	v_div_fmas_f32 v123, v123, v128, v132
	v_div_fixup_f32 v125, v123, v125, 1.0
	v_div_scale_f32 v123, s[0:1], v124, v124, 1.0
	v_rcp_f32_e32 v128, v123
	s_nop 0
	v_fma_f32 v129, -v123, v128, 1.0
	v_fmac_f32_e32 v128, v129, v128
	v_div_scale_f32 v129, vcc, 1.0, v124, 1.0
	v_mul_f32_e32 v132, v129, v128
	v_fma_f32 v133, -v123, v132, v129
	v_fmac_f32_e32 v132, v133, v128
	v_fma_f32 v123, -v123, v132, v129
	v_div_fmas_f32 v123, v123, v128, v132
	v_div_fixup_f32 v124, v123, v124, 1.0
	v_pk_mul_f32 v[124:125], v[124:125], s[4:5] op_sel_hi:[1,0]
	s_nop 0
	v_cvt_pk_f16_f32 v123, v124, v125
	v_pk_add_f32 v[124:125], v[152:153], 1.0 op_sel_hi:[1,0]
	s_nop 0
	v_div_scale_f32 v128, s[0:1], v125, v125, 1.0
	v_rcp_f32_e32 v129, v128
	s_nop 0
	v_fma_f32 v132, -v128, v129, 1.0
	v_fmac_f32_e32 v129, v132, v129
	v_div_scale_f32 v132, vcc, 1.0, v125, 1.0
	v_mul_f32_e32 v133, v132, v129
	v_fma_f32 v151, -v128, v133, v132
	v_fmac_f32_e32 v133, v151, v129
	v_fma_f32 v128, -v128, v133, v132
	v_div_fmas_f32 v128, v128, v129, v133
	v_div_fixup_f32 v125, v128, v125, 1.0
	v_div_scale_f32 v128, s[0:1], v124, v124, 1.0
	v_rcp_f32_e32 v129, v128
	s_nop 0
	v_fma_f32 v132, -v128, v129, 1.0
	v_fmac_f32_e32 v129, v132, v129
	v_div_scale_f32 v132, vcc, 1.0, v124, 1.0
	v_mul_f32_e32 v133, v132, v129
	v_fma_f32 v151, -v128, v133, v132
	v_fmac_f32_e32 v133, v151, v129
	v_fma_f32 v128, -v128, v133, v132
	v_div_fmas_f32 v128, v128, v129, v133
	v_div_fixup_f32 v124, v128, v124, 1.0
	v_pk_mul_f32 v[124:125], v[124:125], s[4:5] op_sel_hi:[1,0]
	s_nop 0
	v_cvt_pk_f16_f32 v124, v124, v125
	v_div_scale_f32 v125, s[0:1], v127, v127, 1.0
	v_rcp_f32_e32 v128, v125
	s_nop 0
	v_fma_f32 v129, -v125, v128, 1.0
	v_fmac_f32_e32 v128, v129, v128
	v_div_scale_f32 v129, vcc, 1.0, v127, 1.0
	v_mul_f32_e32 v132, v129, v128
	v_fma_f32 v133, -v125, v132, v129
	v_fmac_f32_e32 v132, v133, v128
	v_fma_f32 v125, -v125, v132, v129
	v_div_fmas_f32 v125, v125, v128, v132
	v_div_fixup_f32 v127, v125, v127, 1.0
	v_div_scale_f32 v125, s[0:1], v126, v126, 1.0
	v_rcp_f32_e32 v128, v125
	s_nop 0
	v_fma_f32 v129, -v125, v128, 1.0
	v_fmac_f32_e32 v128, v129, v128
	v_div_scale_f32 v129, vcc, 1.0, v126, 1.0
	v_mul_f32_e32 v132, v129, v128
	v_fma_f32 v133, -v125, v132, v129
	v_fmac_f32_e32 v132, v133, v128
	v_fma_f32 v125, -v125, v132, v129
	v_div_fmas_f32 v125, v125, v128, v132
	v_div_fixup_f32 v126, v125, v126, 1.0
	v_pk_mul_f32 v[126:127], v[126:127], s[4:5] op_sel_hi:[1,0]
	s_nop 0
	v_cvt_pk_f16_f32 v125, v126, v127
	v_lshlrev_b64 v[126:127], 12, v[130:131]
	v_lshl_add_u64 v[126:127], s[6:7], 0, v[126:127]
	v_lshl_add_u64 v[126:127], v[126:127], 0, v[136:137]
	global_store_dwordx4 v[126:127], v[122:125], off
	v_pk_add_f32 v[114:115], v[114:115], v[90:91]
	v_pk_add_f32 v[118:119], v[118:119], v[94:95]
	v_mul_f32_e32 v114, 0xbfb8aa3b, v114
	v_exp_f32_e32 v128, v114
	v_mul_f32_e32 v114, 0xbfb8aa3b, v119
	v_pk_add_f32 v[120:121], v[120:121], v[96:97]
	v_mul_f32_e32 v118, 0xbfb8aa3b, v118
	v_exp_f32_e32 v125, v114
	v_mul_f32_e32 v114, 0xbfb8aa3b, v115
	v_pk_add_f32 v[116:117], v[116:117], v[92:93]
	v_exp_f32_e32 v124, v118
	v_exp_f32_e32 v129, v114
	v_mul_f32_e32 v114, 0xbfb8aa3b, v120
	v_exp_f32_e32 v120, v114
	v_mul_f32_e32 v114, 0xbfb8aa3b, v116
	v_exp_f32_e32 v118, v114
	v_mul_f32_e32 v114, 0xbfb8aa3b, v121
	v_exp_f32_e32 v121, v114
	v_mul_f32_e32 v114, 0xbfb8aa3b, v117
	v_exp_f32_e32 v119, v114
	v_pk_add_f32 v[114:115], v[124:125], 1.0 op_sel_hi:[1,0]
	v_or_b32_e32 v122, 32, v150
	v_div_scale_f32 v116, s[0:1], v115, v115, 1.0
	v_rcp_f32_e32 v117, v116
	v_pk_add_f32 v[118:119], v[118:119], 1.0 op_sel_hi:[1,0]
	v_ashrrev_i32_e32 v123, 31, v122
	v_fma_f32 v124, -v116, v117, 1.0
	v_fmac_f32_e32 v117, v124, v117
	v_div_scale_f32 v124, vcc, 1.0, v115, 1.0
	v_mul_f32_e32 v125, v124, v117
	v_fma_f32 v130, -v116, v125, v124
	v_fmac_f32_e32 v125, v130, v117
	v_fma_f32 v116, -v116, v125, v124
	v_div_fmas_f32 v116, v116, v117, v125
	v_div_fixup_f32 v115, v116, v115, 1.0
	v_div_scale_f32 v116, s[0:1], v114, v114, 1.0
	v_rcp_f32_e32 v117, v116
	s_nop 0
	v_fma_f32 v124, -v116, v117, 1.0
	v_fmac_f32_e32 v117, v124, v117
	v_div_scale_f32 v124, vcc, 1.0, v114, 1.0
	v_mul_f32_e32 v125, v124, v117
	v_fma_f32 v130, -v116, v125, v124
	v_fmac_f32_e32 v125, v130, v117
	v_fma_f32 v116, -v116, v125, v124
	v_div_fmas_f32 v116, v116, v117, v125
; __device__ __forceinline__ float sigmoidf_(float x) { return 1.0f / (1.0f + __expf(-x)); }
;     template <int GI>
;     __device__ __forceinline__ void body(const f32x4 (&acc)[2][2][4][2], int row0, int colt) const {
;     ...
;         for (int bj = 0; bj < 2; ++bj) {
;             const int c = colt + bj * 128;
;             f32x4 b0 = (f32x4){0.f, 0.f, 0.f, 0.f}, b1 = b0;
;             if (GI == 0) { b0 = *(const f32x4*)(w0 + c); b1 = *(const f32x4*)(w0 + c + 4); }
;             else if (GI == 1) { b0 = *(const f32x4*)(a0 + c); b1 = *(const f32x4*)(a0 + c + 4); }
;             else if (GI == 3) { b0 = *(const f32x4*)(v0 + c); b1 = *(const f32x4*)(v0 + c + 4); }
; #pragma unroll
;             for (int ai = 0; ai < 2; ++ai)
; #pragma unroll
;                 for (int m = 0; m < 4; ++m) {
;                     const size_t row = (size_t)(row0 + ai * 128 + m * 16);
;                     f32x4 x0 = acc[ai][bj][m][0] + b0, x1 = acc[ai][bj][m][1] + b1;
;                     if (GI == 0) {
; #pragma unroll
;                         for (int j = 0; j < 4; ++j) {
;                             x0[j] = 0.6065306597126334f * sigmoidf_(x0[j]); x1[j] = 0.6065306597126334f * sigmoidf_(x1[j]); }
;                         *(u32x4*)(DEC + row * DM + c) = pack8(x0, x1);
	v_div_fixup_f32 v114, v116, v114, 1.0
	v_pk_mul_f32 v[114:115], v[114:115], s[4:5] op_sel_hi:[1,0]
	v_pk_add_f32 v[116:117], v[120:121], 1.0 op_sel_hi:[1,0]
	v_cvt_pk_f16_f32 v114, v114, v115
	v_div_scale_f32 v115, s[0:1], v117, v117, 1.0
	v_rcp_f32_e32 v120, v115
	s_nop 0
	v_fma_f32 v121, -v115, v120, 1.0
	v_fmac_f32_e32 v120, v121, v120
	v_div_scale_f32 v121, vcc, 1.0, v117, 1.0
	v_mul_f32_e32 v124, v121, v120
	v_fma_f32 v125, -v115, v124, v121
	v_fmac_f32_e32 v124, v125, v120
	v_fma_f32 v115, -v115, v124, v121
	v_div_fmas_f32 v115, v115, v120, v124
	v_div_fixup_f32 v117, v115, v117, 1.0
	v_div_scale_f32 v115, s[0:1], v116, v116, 1.0
	v_rcp_f32_e32 v120, v115
	s_nop 0
	v_fma_f32 v121, -v115, v120, 1.0
	v_fmac_f32_e32 v120, v121, v120
	v_div_scale_f32 v121, vcc, 1.0, v116, 1.0
	v_mul_f32_e32 v124, v121, v120
	v_fma_f32 v125, -v115, v124, v121
	v_fmac_f32_e32 v124, v125, v120
	v_fma_f32 v115, -v115, v124, v121
	v_div_fmas_f32 v115, v115, v120, v124
	v_div_fixup_f32 v116, v115, v116, 1.0
	v_pk_mul_f32 v[116:117], v[116:117], s[4:5] op_sel_hi:[1,0]
	s_nop 0
	v_cvt_pk_f16_f32 v115, v116, v117
	v_pk_add_f32 v[116:117], v[128:129], 1.0 op_sel_hi:[1,0]
	s_nop 0
	v_div_scale_f32 v120, s[0:1], v117, v117, 1.0
	v_rcp_f32_e32 v121, v120
	s_nop 0
	v_fma_f32 v124, -v120, v121, 1.0
	v_fmac_f32_e32 v121, v124, v121
	v_div_scale_f32 v124, vcc, 1.0, v117, 1.0
	v_mul_f32_e32 v125, v124, v121
	v_fma_f32 v128, -v120, v125, v124
	v_fmac_f32_e32 v125, v128, v121
	v_fma_f32 v120, -v120, v125, v124
	v_div_fmas_f32 v120, v120, v121, v125
	v_div_fixup_f32 v117, v120, v117, 1.0
	v_div_scale_f32 v120, s[0:1], v116, v116, 1.0
	v_rcp_f32_e32 v121, v120
	s_nop 0
	v_fma_f32 v124, -v120, v121, 1.0
	v_fmac_f32_e32 v121, v124, v121
	v_div_scale_f32 v124, vcc, 1.0, v116, 1.0
	v_mul_f32_e32 v125, v124, v121
	v_fma_f32 v128, -v120, v125, v124
	v_fmac_f32_e32 v125, v128, v121
	v_fma_f32 v120, -v120, v125, v124
	v_div_fmas_f32 v120, v120, v121, v125
	v_div_fixup_f32 v116, v120, v116, 1.0
	v_pk_mul_f32 v[116:117], v[116:117], s[4:5] op_sel_hi:[1,0]
	s_nop 0
	v_cvt_pk_f16_f32 v116, v116, v117
	v_div_scale_f32 v117, s[0:1], v119, v119, 1.0
	v_rcp_f32_e32 v120, v117
	s_nop 0
	v_fma_f32 v121, -v117, v120, 1.0
	v_fmac_f32_e32 v120, v121, v120
	v_div_scale_f32 v121, vcc, 1.0, v119, 1.0
	v_mul_f32_e32 v124, v121, v120
	v_fma_f32 v125, -v117, v124, v121
	v_fmac_f32_e32 v124, v125, v120
	v_fma_f32 v117, -v117, v124, v121
	v_div_fmas_f32 v117, v117, v120, v124
	v_div_fixup_f32 v119, v117, v119, 1.0
	v_div_scale_f32 v117, s[0:1], v118, v118, 1.0
	v_rcp_f32_e32 v120, v117
	s_nop 0
	v_fma_f32 v121, -v117, v120, 1.0
	v_fmac_f32_e32 v120, v121, v120
	v_div_scale_f32 v121, vcc, 1.0, v118, 1.0
	v_mul_f32_e32 v124, v121, v120
	v_fma_f32 v125, -v117, v124, v121
	v_fmac_f32_e32 v124, v125, v120
	v_fma_f32 v117, -v117, v124, v121
	v_div_fmas_f32 v117, v117, v120, v124
	v_div_fixup_f32 v118, v117, v118, 1.0
	v_pk_mul_f32 v[118:119], v[118:119], s[4:5] op_sel_hi:[1,0]
	s_nop 0
	v_cvt_pk_f16_f32 v117, v118, v119
	v_lshlrev_b64 v[118:119], 12, v[122:123]
	v_lshl_add_u64 v[118:119], s[6:7], 0, v[118:119]
	v_lshl_add_u64 v[118:119], v[118:119], 0, v[136:137]
	global_store_dwordx4 v[118:119], v[114:117], off
	v_pk_add_f32 v[106:107], v[106:107], v[90:91]
	v_pk_add_f32 v[110:111], v[110:111], v[94:95]
	v_mul_f32_e32 v106, 0xbfb8aa3b, v106
	v_exp_f32_e32 v120, v106
	v_mul_f32_e32 v106, 0xbfb8aa3b, v111
	v_pk_add_f32 v[112:113], v[112:113], v[96:97]
	v_mul_f32_e32 v110, 0xbfb8aa3b, v110
	v_exp_f32_e32 v117, v106
	v_mul_f32_e32 v106, 0xbfb8aa3b, v107
	v_pk_add_f32 v[108:109], v[108:109], v[92:93]
	v_exp_f32_e32 v116, v110
	v_exp_f32_e32 v121, v106
	v_mul_f32_e32 v106, 0xbfb8aa3b, v112
	v_exp_f32_e32 v112, v106
	v_mul_f32_e32 v106, 0xbfb8aa3b, v108
	v_exp_f32_e32 v110, v106
	v_mul_f32_e32 v106, 0xbfb8aa3b, v113
	v_exp_f32_e32 v113, v106
	v_mul_f32_e32 v106, 0xbfb8aa3b, v109
	v_exp_f32_e32 v111, v106
	v_pk_add_f32 v[106:107], v[116:117], 1.0 op_sel_hi:[1,0]
	v_or_b32_e32 v114, 48, v150
	v_div_scale_f32 v108, s[0:1], v107, v107, 1.0
	v_rcp_f32_e32 v109, v108
	v_pk_add_f32 v[110:111], v[110:111], 1.0 op_sel_hi:[1,0]
	v_ashrrev_i32_e32 v115, 31, v114
	v_fma_f32 v116, -v108, v109, 1.0
	v_fmac_f32_e32 v109, v116, v109
	v_div_scale_f32 v116, vcc, 1.0, v107, 1.0
	v_mul_f32_e32 v117, v116, v109
	v_fma_f32 v122, -v108, v117, v116
	v_fmac_f32_e32 v117, v122, v109
	v_fma_f32 v108, -v108, v117, v116
	v_div_fmas_f32 v108, v108, v109, v117
	v_div_fixup_f32 v107, v108, v107, 1.0
	v_div_scale_f32 v108, s[0:1], v106, v106, 1.0
	v_rcp_f32_e32 v109, v108
	s_nop 0
	v_fma_f32 v116, -v108, v109, 1.0
	v_fmac_f32_e32 v109, v116, v109
	v_div_scale_f32 v116, vcc, 1.0, v106, 1.0
	v_mul_f32_e32 v117, v116, v109
	v_fma_f32 v122, -v108, v117, v116
	v_fmac_f32_e32 v117, v122, v109
	v_fma_f32 v108, -v108, v117, v116
	v_div_fmas_f32 v108, v108, v109, v117
	v_div_fixup_f32 v106, v108, v106, 1.0
	v_pk_mul_f32 v[106:107], v[106:107], s[4:5] op_sel_hi:[1,0]
	v_pk_add_f32 v[108:109], v[112:113], 1.0 op_sel_hi:[1,0]
	v_cvt_pk_f16_f32 v106, v106, v107
	v_div_scale_f32 v107, s[0:1], v109, v109, 1.0
	v_rcp_f32_e32 v112, v107
	s_nop 0
	v_fma_f32 v113, -v107, v112, 1.0
	v_fmac_f32_e32 v112, v113, v112
	v_div_scale_f32 v113, vcc, 1.0, v109, 1.0
	v_mul_f32_e32 v116, v113, v112
	v_fma_f32 v117, -v107, v116, v113
	v_fmac_f32_e32 v116, v117, v112
	v_fma_f32 v107, -v107, v116, v113
	v_div_fmas_f32 v107, v107, v112, v116
	v_div_fixup_f32 v109, v107, v109, 1.0
	v_div_scale_f32 v107, s[0:1], v108, v108, 1.0
	v_rcp_f32_e32 v112, v107
	s_nop 0
	v_fma_f32 v113, -v107, v112, 1.0
	v_fmac_f32_e32 v112, v113, v112
	v_div_scale_f32 v113, vcc, 1.0, v108, 1.0
; __device__ __forceinline__ float sigmoidf_(float x) { return 1.0f / (1.0f + __expf(-x)); }
;     template <int GI>
;     __device__ __forceinline__ void body(const f32x4 (&acc)[2][2][4][2], int row0, int colt) const {
;     ...
;         for (int bj = 0; bj < 2; ++bj) {
;             const int c = colt + bj * 128;
;             f32x4 b0 = (f32x4){0.f, 0.f, 0.f, 0.f}, b1 = b0;
;             if (GI == 0) { b0 = *(const f32x4*)(w0 + c); b1 = *(const f32x4*)(w0 + c + 4); }
;             else if (GI == 1) { b0 = *(const f32x4*)(a0 + c); b1 = *(const f32x4*)(a0 + c + 4); }
;             else if (GI == 3) { b0 = *(const f32x4*)(v0 + c); b1 = *(const f32x4*)(v0 + c + 4); }
; #pragma unroll
;             for (int ai = 0; ai < 2; ++ai)
; #pragma unroll
;                 for (int m = 0; m < 4; ++m) {
;                     const size_t row = (size_t)(row0 + ai * 128 + m * 16);
;                     f32x4 x0 = acc[ai][bj][m][0] + b0, x1 = acc[ai][bj][m][1] + b1;
;                     if (GI == 0) {
; #pragma unroll
;                         for (int j = 0; j < 4; ++j) {
;                             x0[j] = 0.6065306597126334f * sigmoidf_(x0[j]); x1[j] = 0.6065306597126334f * sigmoidf_(x1[j]); }
;                         *(u32x4*)(DEC + row * DM + c) = pack8(x0, x1);
	v_mul_f32_e32 v116, v113, v112
	v_fma_f32 v117, -v107, v116, v113
	v_fmac_f32_e32 v116, v117, v112
	v_fma_f32 v107, -v107, v116, v113
	v_div_fmas_f32 v107, v107, v112, v116
	v_div_fixup_f32 v108, v107, v108, 1.0
	v_pk_mul_f32 v[108:109], v[108:109], s[4:5] op_sel_hi:[1,0]
	s_nop 0
	v_cvt_pk_f16_f32 v107, v108, v109
	v_pk_add_f32 v[108:109], v[120:121], 1.0 op_sel_hi:[1,0]
	s_nop 0
	v_div_scale_f32 v112, s[0:1], v109, v109, 1.0
	v_rcp_f32_e32 v113, v112
	s_nop 0
	v_fma_f32 v116, -v112, v113, 1.0
	v_fmac_f32_e32 v113, v116, v113
	v_div_scale_f32 v116, vcc, 1.0, v109, 1.0
	v_mul_f32_e32 v117, v116, v113
	v_fma_f32 v120, -v112, v117, v116
	v_fmac_f32_e32 v117, v120, v113
	v_fma_f32 v112, -v112, v117, v116
	v_div_fmas_f32 v112, v112, v113, v117
	v_div_fixup_f32 v109, v112, v109, 1.0
	v_div_scale_f32 v112, s[0:1], v108, v108, 1.0
	v_rcp_f32_e32 v113, v112
	s_nop 0
	v_fma_f32 v116, -v112, v113, 1.0
	v_fmac_f32_e32 v113, v116, v113
	v_div_scale_f32 v116, vcc, 1.0, v108, 1.0
	v_mul_f32_e32 v117, v116, v113
	v_fma_f32 v120, -v112, v117, v116
	v_fmac_f32_e32 v117, v120, v113
	v_fma_f32 v112, -v112, v117, v116
	v_div_fmas_f32 v112, v112, v113, v117
	v_div_fixup_f32 v108, v112, v108, 1.0
	v_pk_mul_f32 v[108:109], v[108:109], s[4:5] op_sel_hi:[1,0]
	s_nop 0
	v_cvt_pk_f16_f32 v108, v108, v109
	v_div_scale_f32 v109, s[0:1], v111, v111, 1.0
	v_rcp_f32_e32 v112, v109
	s_nop 0
	v_fma_f32 v113, -v109, v112, 1.0
	v_fmac_f32_e32 v112, v113, v112
	v_div_scale_f32 v113, vcc, 1.0, v111, 1.0
	v_mul_f32_e32 v116, v113, v112
	v_fma_f32 v117, -v109, v116, v113
	v_fmac_f32_e32 v116, v117, v112
	v_fma_f32 v109, -v109, v116, v113
	v_div_fmas_f32 v109, v109, v112, v116
	v_div_fixup_f32 v111, v109, v111, 1.0
	v_div_scale_f32 v109, s[0:1], v110, v110, 1.0
	v_rcp_f32_e32 v112, v109
	s_nop 0
	v_fma_f32 v113, -v109, v112, 1.0
	v_fmac_f32_e32 v112, v113, v112
	v_div_scale_f32 v113, vcc, 1.0, v110, 1.0
	v_mul_f32_e32 v116, v113, v112
	v_fma_f32 v117, -v109, v116, v113
	v_fmac_f32_e32 v116, v117, v112
	v_fma_f32 v109, -v109, v116, v113
	v_div_fmas_f32 v109, v109, v112, v116
	v_div_fixup_f32 v110, v109, v110, 1.0
	v_pk_mul_f32 v[110:111], v[110:111], s[4:5] op_sel_hi:[1,0]
	s_nop 0
	v_cvt_pk_f16_f32 v109, v110, v111
	v_lshlrev_b64 v[110:111], 12, v[114:115]
	v_lshl_add_u64 v[110:111], s[6:7], 0, v[110:111]
	v_lshl_add_u64 v[110:111], v[110:111], 0, v[136:137]
	global_store_dwordx4 v[110:111], v[106:109], off
	v_pk_add_f32 v[98:99], v[98:99], v[90:91]
	v_pk_add_f32 v[102:103], v[102:103], v[94:95]
	v_mul_f32_e32 v98, 0xbfb8aa3b, v98
	v_exp_f32_e32 v108, v98
	v_mul_f32_e32 v98, 0xbfb8aa3b, v103
	v_pk_add_f32 v[104:105], v[104:105], v[96:97]
	v_mul_f32_e32 v102, 0xbfb8aa3b, v102
	v_exp_f32_e32 v107, v98
	v_mul_f32_e32 v98, 0xbfb8aa3b, v99
	v_pk_add_f32 v[100:101], v[100:101], v[92:93]
	v_exp_f32_e32 v106, v102
	v_exp_f32_e32 v109, v98
	v_mul_f32_e32 v98, 0xbfb8aa3b, v104
	v_exp_f32_e32 v104, v98
	v_mul_f32_e32 v98, 0xbfb8aa3b, v100
	v_exp_f32_e32 v102, v98
	v_mul_f32_e32 v98, 0xbfb8aa3b, v105
	v_exp_f32_e32 v105, v98
	v_mul_f32_e32 v98, 0xbfb8aa3b, v101
	v_exp_f32_e32 v103, v98
	v_pk_add_f32 v[98:99], v[106:107], 1.0 op_sel_hi:[1,0]
	v_pk_add_f32 v[102:103], v[102:103], 1.0 op_sel_hi:[1,0]
	v_div_scale_f32 v100, s[0:1], v99, v99, 1.0
	v_rcp_f32_e32 v101, v100
	s_nop 0
	v_fma_f32 v106, -v100, v101, 1.0
	v_fmac_f32_e32 v101, v106, v101
	v_div_scale_f32 v106, vcc, 1.0, v99, 1.0
	v_mul_f32_e32 v107, v106, v101
	v_fma_f32 v112, -v100, v107, v106
	v_fmac_f32_e32 v107, v112, v101
	v_fma_f32 v100, -v100, v107, v106
	v_div_fmas_f32 v100, v100, v101, v107
	v_div_fixup_f32 v99, v100, v99, 1.0
	v_div_scale_f32 v100, s[0:1], v98, v98, 1.0
	v_rcp_f32_e32 v101, v100
	s_nop 0
	v_fma_f32 v106, -v100, v101, 1.0
	v_fmac_f32_e32 v101, v106, v101
	v_div_scale_f32 v106, vcc, 1.0, v98, 1.0
	v_mul_f32_e32 v107, v106, v101
	v_fma_f32 v112, -v100, v107, v106
	v_fmac_f32_e32 v107, v112, v101
	v_fma_f32 v100, -v100, v107, v106
	v_div_fmas_f32 v100, v100, v101, v107
	v_div_fixup_f32 v98, v100, v98, 1.0
	v_pk_mul_f32 v[98:99], v[98:99], s[4:5] op_sel_hi:[1,0]
	v_pk_add_f32 v[100:101], v[104:105], 1.0 op_sel_hi:[1,0]
	v_cvt_pk_f16_f32 v98, v98, v99
	v_div_scale_f32 v99, s[0:1], v101, v101, 1.0
	v_rcp_f32_e32 v104, v99
	s_nop 0
	v_fma_f32 v105, -v99, v104, 1.0
	v_fmac_f32_e32 v104, v105, v104
	v_div_scale_f32 v105, vcc, 1.0, v101, 1.0
	v_mul_f32_e32 v106, v105, v104
	v_fma_f32 v107, -v99, v106, v105
	v_fmac_f32_e32 v106, v107, v104
	v_fma_f32 v99, -v99, v106, v105
	v_div_fmas_f32 v99, v99, v104, v106
	v_div_fixup_f32 v101, v99, v101, 1.0
	v_div_scale_f32 v99, s[0:1], v100, v100, 1.0
	v_rcp_f32_e32 v104, v99
	s_nop 0
	v_fma_f32 v105, -v99, v104, 1.0
	v_fmac_f32_e32 v104, v105, v104
	v_div_scale_f32 v105, vcc, 1.0, v100, 1.0
	v_mul_f32_e32 v106, v105, v104
	v_fma_f32 v107, -v99, v106, v105
	v_fmac_f32_e32 v106, v107, v104
	v_fma_f32 v99, -v99, v106, v105
	v_div_fmas_f32 v99, v99, v104, v106
	v_div_fixup_f32 v100, v99, v100, 1.0
	v_pk_mul_f32 v[100:101], v[100:101], s[4:5] op_sel_hi:[1,0]
	s_nop 0
	v_cvt_pk_f16_f32 v99, v100, v101
	v_pk_add_f32 v[100:101], v[108:109], 1.0 op_sel_hi:[1,0]
	s_nop 0
	v_div_scale_f32 v104, s[0:1], v101, v101, 1.0
	v_rcp_f32_e32 v105, v104
	s_nop 0
	v_fma_f32 v106, -v104, v105, 1.0
	v_fmac_f32_e32 v105, v106, v105
	v_div_scale_f32 v106, vcc, 1.0, v101, 1.0
	v_mul_f32_e32 v107, v106, v105
	v_fma_f32 v108, -v104, v107, v106
	v_fmac_f32_e32 v107, v108, v105
	v_fma_f32 v104, -v104, v107, v106
	v_div_fmas_f32 v104, v104, v105, v107
	v_div_fixup_f32 v101, v104, v101, 1.0
	v_div_scale_f32 v104, s[0:1], v100, v100, 1.0
	v_rcp_f32_e32 v105, v104
	s_nop 0
	v_fma_f32 v106, -v104, v105, 1.0
; __device__ __forceinline__ float sigmoidf_(float x) { return 1.0f / (1.0f + __expf(-x)); }
;     template <int GI>
;     __device__ __forceinline__ void body(const f32x4 (&acc)[2][2][4][2], int row0, int colt) const {
;     ...
;         for (int bj = 0; bj < 2; ++bj) {
;             const int c = colt + bj * 128;
;             f32x4 b0 = (f32x4){0.f, 0.f, 0.f, 0.f}, b1 = b0;
;             if (GI == 0) { b0 = *(const f32x4*)(w0 + c); b1 = *(const f32x4*)(w0 + c + 4); }
;             else if (GI == 1) { b0 = *(const f32x4*)(a0 + c); b1 = *(const f32x4*)(a0 + c + 4); }
;             else if (GI == 3) { b0 = *(const f32x4*)(v0 + c); b1 = *(const f32x4*)(v0 + c + 4); }
; #pragma unroll
;             for (int ai = 0; ai < 2; ++ai)
; #pragma unroll
;                 for (int m = 0; m < 4; ++m) {
;                     const size_t row = (size_t)(row0 + ai * 128 + m * 16);
;                     f32x4 x0 = acc[ai][bj][m][0] + b0, x1 = acc[ai][bj][m][1] + b1;
;                     if (GI == 0) {
; #pragma unroll
;                         for (int j = 0; j < 4; ++j) {
;                             x0[j] = 0.6065306597126334f * sigmoidf_(x0[j]); x1[j] = 0.6065306597126334f * sigmoidf_(x1[j]); }
;                         *(u32x4*)(DEC + row * DM + c) = pack8(x0, x1);
	v_fmac_f32_e32 v105, v106, v105
	v_div_scale_f32 v106, vcc, 1.0, v100, 1.0
	v_mul_f32_e32 v107, v106, v105
	v_fma_f32 v108, -v104, v107, v106
	v_fmac_f32_e32 v107, v108, v105
	v_fma_f32 v104, -v104, v107, v106
	v_div_fmas_f32 v104, v104, v105, v107
	v_div_fixup_f32 v100, v104, v100, 1.0
	v_pk_mul_f32 v[100:101], v[100:101], s[4:5] op_sel_hi:[1,0]
	s_nop 0
	v_cvt_pk_f16_f32 v100, v100, v101
	v_div_scale_f32 v101, s[0:1], v103, v103, 1.0
	v_rcp_f32_e32 v104, v101
	s_nop 0
	v_fma_f32 v105, -v101, v104, 1.0
	v_fmac_f32_e32 v104, v105, v104
	v_div_scale_f32 v105, vcc, 1.0, v103, 1.0
	v_mul_f32_e32 v106, v105, v104
	v_fma_f32 v107, -v101, v106, v105
	v_fmac_f32_e32 v106, v107, v104
	v_fma_f32 v101, -v101, v106, v105
	v_div_fmas_f32 v101, v101, v104, v106
	v_div_fixup_f32 v103, v101, v103, 1.0
	v_div_scale_f32 v101, s[0:1], v102, v102, 1.0
	v_rcp_f32_e32 v104, v101
	s_mov_b32 s0, 0x80000
	v_fma_f32 v105, -v101, v104, 1.0
	v_fmac_f32_e32 v104, v105, v104
	v_div_scale_f32 v105, vcc, 1.0, v102, 1.0
	v_mul_f32_e32 v106, v105, v104
	v_fma_f32 v107, -v101, v106, v105
	v_fmac_f32_e32 v106, v107, v104
	v_fma_f32 v101, -v101, v106, v105
	v_div_fmas_f32 v101, v101, v104, v106
	v_div_fixup_f32 v102, v101, v102, 1.0
	v_pk_mul_f32 v[102:103], v[102:103], s[4:5] op_sel_hi:[1,0]
	v_add_co_u32_e32 v104, vcc, s0, v134
	v_cvt_pk_f16_f32 v101, v102, v103
	s_nop 0
	v_addc_co_u32_e32 v105, vcc, 0, v135, vcc
	v_lshl_add_u64 v[102:103], v[134:135], 0, s[10:11]
	global_store_dwordx4 v[104:105], v[98:101], off
	v_pk_add_f32 v[82:83], v[82:83], v[90:91]
	v_pk_add_f32 v[86:87], v[86:87], v[94:95]
	v_mul_f32_e32 v82, 0xbfb8aa3b, v82
	v_exp_f32_e32 v100, v82
	v_mul_f32_e32 v82, 0xbfb8aa3b, v87
	v_pk_add_f32 v[88:89], v[88:89], v[96:97]
	v_mul_f32_e32 v86, 0xbfb8aa3b, v86
	v_exp_f32_e32 v99, v82
	v_mul_f32_e32 v82, 0xbfb8aa3b, v83
	v_pk_add_f32 v[84:85], v[84:85], v[92:93]
	v_exp_f32_e32 v98, v86
	v_exp_f32_e32 v101, v82
	v_mul_f32_e32 v82, 0xbfb8aa3b, v88
	v_exp_f32_e32 v88, v82
	v_mul_f32_e32 v82, 0xbfb8aa3b, v84
	v_exp_f32_e32 v86, v82
	v_mul_f32_e32 v82, 0xbfb8aa3b, v89
	v_exp_f32_e32 v89, v82
	v_mul_f32_e32 v82, 0xbfb8aa3b, v85
	v_exp_f32_e32 v87, v82
	v_pk_add_f32 v[82:83], v[98:99], 1.0 op_sel_hi:[1,0]
	v_pk_add_f32 v[86:87], v[86:87], 1.0 op_sel_hi:[1,0]
	v_div_scale_f32 v84, s[0:1], v83, v83, 1.0
	v_rcp_f32_e32 v85, v84
	s_nop 0
	v_fma_f32 v98, -v84, v85, 1.0
	v_fmac_f32_e32 v85, v98, v85
	v_div_scale_f32 v98, vcc, 1.0, v83, 1.0
	v_mul_f32_e32 v99, v98, v85
	v_fma_f32 v104, -v84, v99, v98
	v_fmac_f32_e32 v99, v104, v85
	v_fma_f32 v84, -v84, v99, v98
	v_div_fmas_f32 v84, v84, v85, v99
	v_div_fixup_f32 v83, v84, v83, 1.0
	v_div_scale_f32 v84, s[0:1], v82, v82, 1.0
	v_rcp_f32_e32 v85, v84
	s_nop 0
	v_fma_f32 v98, -v84, v85, 1.0
	v_fmac_f32_e32 v85, v98, v85
	v_div_scale_f32 v98, vcc, 1.0, v82, 1.0
	v_mul_f32_e32 v99, v98, v85
	v_fma_f32 v104, -v84, v99, v98
	v_fmac_f32_e32 v99, v104, v85
	v_fma_f32 v84, -v84, v99, v98
	v_div_fmas_f32 v84, v84, v85, v99
	v_div_fixup_f32 v82, v84, v82, 1.0
	v_pk_mul_f32 v[82:83], v[82:83], s[4:5] op_sel_hi:[1,0]
	v_pk_add_f32 v[84:85], v[88:89], 1.0 op_sel_hi:[1,0]
	v_cvt_pk_f16_f32 v82, v82, v83
	v_div_scale_f32 v83, s[0:1], v85, v85, 1.0
	v_rcp_f32_e32 v88, v83
	s_nop 0
	v_fma_f32 v89, -v83, v88, 1.0
	v_fmac_f32_e32 v88, v89, v88
	v_div_scale_f32 v89, vcc, 1.0, v85, 1.0
	v_mul_f32_e32 v98, v89, v88
	v_fma_f32 v99, -v83, v98, v89
	v_fmac_f32_e32 v98, v99, v88
	v_fma_f32 v83, -v83, v98, v89
	v_div_fmas_f32 v83, v83, v88, v98
	v_div_fixup_f32 v85, v83, v85, 1.0
	v_div_scale_f32 v83, s[0:1], v84, v84, 1.0
	v_rcp_f32_e32 v88, v83
	s_nop 0
	v_fma_f32 v89, -v83, v88, 1.0
	v_fmac_f32_e32 v88, v89, v88
	v_div_scale_f32 v89, vcc, 1.0, v84, 1.0
	v_mul_f32_e32 v98, v89, v88
	v_fma_f32 v99, -v83, v98, v89
	v_fmac_f32_e32 v98, v99, v88
	v_fma_f32 v83, -v83, v98, v89
	v_div_fmas_f32 v83, v83, v88, v98
	v_div_fixup_f32 v84, v83, v84, 1.0
	v_pk_mul_f32 v[84:85], v[84:85], s[4:5] op_sel_hi:[1,0]
	s_nop 0
	v_cvt_pk_f16_f32 v83, v84, v85
	v_pk_add_f32 v[84:85], v[100:101], 1.0 op_sel_hi:[1,0]
	s_nop 0
	v_div_scale_f32 v88, s[0:1], v85, v85, 1.0
	v_rcp_f32_e32 v89, v88
	s_nop 0
	v_fma_f32 v98, -v88, v89, 1.0
	v_fmac_f32_e32 v89, v98, v89
	v_div_scale_f32 v98, vcc, 1.0, v85, 1.0
	v_mul_f32_e32 v99, v98, v89
	v_fma_f32 v100, -v88, v99, v98
	v_fmac_f32_e32 v99, v100, v89
	v_fma_f32 v88, -v88, v99, v98
	v_div_fmas_f32 v88, v88, v89, v99
	v_div_fixup_f32 v85, v88, v85, 1.0
	v_div_scale_f32 v88, s[0:1], v84, v84, 1.0
	v_rcp_f32_e32 v89, v88
	s_nop 0
	v_fma_f32 v98, -v88, v89, 1.0
	v_fmac_f32_e32 v89, v98, v89
	v_div_scale_f32 v98, vcc, 1.0, v84, 1.0
	v_mul_f32_e32 v99, v98, v89
	v_fma_f32 v100, -v88, v99, v98
	v_fmac_f32_e32 v99, v100, v89
	v_fma_f32 v88, -v88, v99, v98
	v_div_fmas_f32 v88, v88, v89, v99
	v_div_fixup_f32 v84, v88, v84, 1.0
	v_pk_mul_f32 v[84:85], v[84:85], s[4:5] op_sel_hi:[1,0]
	s_nop 0
	v_cvt_pk_f16_f32 v84, v84, v85
	v_div_scale_f32 v85, s[0:1], v87, v87, 1.0
	v_rcp_f32_e32 v88, v85
	s_nop 0
	v_fma_f32 v89, -v85, v88, 1.0
	v_fmac_f32_e32 v88, v89, v88
	v_div_scale_f32 v89, vcc, 1.0, v87, 1.0
	v_mul_f32_e32 v98, v89, v88
	v_fma_f32 v99, -v85, v98, v89
	v_fmac_f32_e32 v98, v99, v88
	v_fma_f32 v85, -v85, v98, v89
	v_div_fmas_f32 v85, v85, v88, v98
	v_div_fixup_f32 v87, v85, v87, 1.0
	v_div_scale_f32 v85, s[0:1], v86, v86, 1.0
	v_rcp_f32_e32 v88, v85
	s_mov_b32 s0, 0x90000
	v_fma_f32 v89, -v85, v88, 1.0
	v_fmac_f32_e32 v88, v89, v88
	v_div_scale_f32 v89, vcc, 1.0, v86, 1.0
	v_mul_f32_e32 v98, v89, v88
	v_fma_f32 v99, -v85, v98, v89
	v_fmac_f32_e32 v98, v99, v88
	v_fma_f32 v85, -v85, v98, v89
	v_div_fmas_f32 v85, v85, v88, v98
; __device__ __forceinline__ float sigmoidf_(float x) { return 1.0f / (1.0f + __expf(-x)); }
;     template <int GI>
;     __device__ __forceinline__ void body(const f32x4 (&acc)[2][2][4][2], int row0, int colt) const {
;     ...
;         for (int bj = 0; bj < 2; ++bj) {
;             const int c = colt + bj * 128;
;             f32x4 b0 = (f32x4){0.f, 0.f, 0.f, 0.f}, b1 = b0;
;             if (GI == 0) { b0 = *(const f32x4*)(w0 + c); b1 = *(const f32x4*)(w0 + c + 4); }
;             else if (GI == 1) { b0 = *(const f32x4*)(a0 + c); b1 = *(const f32x4*)(a0 + c + 4); }
;             else if (GI == 3) { b0 = *(const f32x4*)(v0 + c); b1 = *(const f32x4*)(v0 + c + 4); }
; #pragma unroll
;             for (int ai = 0; ai < 2; ++ai)
; #pragma unroll
;                 for (int m = 0; m < 4; ++m) {
;                     const size_t row = (size_t)(row0 + ai * 128 + m * 16);
;                     f32x4 x0 = acc[ai][bj][m][0] + b0, x1 = acc[ai][bj][m][1] + b1;
;                     if (GI == 0) {
; #pragma unroll
;                         for (int j = 0; j < 4; ++j) {
;                             x0[j] = 0.6065306597126334f * sigmoidf_(x0[j]); x1[j] = 0.6065306597126334f * sigmoidf_(x1[j]); }
;                         *(u32x4*)(DEC + row * DM + c) = pack8(x0, x1);
	v_div_fixup_f32 v86, v85, v86, 1.0
	v_pk_mul_f32 v[86:87], v[86:87], s[4:5] op_sel_hi:[1,0]
	v_add_co_u32_e32 v88, vcc, s0, v134
	v_cvt_pk_f16_f32 v85, v86, v87
	s_nop 0
	v_addc_co_u32_e32 v89, vcc, 0, v135, vcc
	v_lshl_add_u64 v[86:87], v[134:135], 0, s[18:19]
	global_store_dwordx4 v[88:89], v[82:85], off
	v_pk_add_f32 v[74:75], v[74:75], v[90:91]
	v_pk_add_f32 v[78:79], v[78:79], v[94:95]
	v_mul_f32_e32 v74, 0xbfb8aa3b, v74
	v_exp_f32_e32 v84, v74
	v_mul_f32_e32 v74, 0xbfb8aa3b, v79
	v_pk_add_f32 v[80:81], v[80:81], v[96:97]
	v_mul_f32_e32 v78, 0xbfb8aa3b, v78
	v_exp_f32_e32 v83, v74
	v_mul_f32_e32 v74, 0xbfb8aa3b, v75
	v_pk_add_f32 v[76:77], v[76:77], v[92:93]
	v_exp_f32_e32 v82, v78
	v_exp_f32_e32 v85, v74
	v_mul_f32_e32 v74, 0xbfb8aa3b, v80
	v_exp_f32_e32 v80, v74
	v_mul_f32_e32 v74, 0xbfb8aa3b, v76
	v_exp_f32_e32 v78, v74
	v_mul_f32_e32 v74, 0xbfb8aa3b, v81
	v_exp_f32_e32 v81, v74
	v_mul_f32_e32 v74, 0xbfb8aa3b, v77
	v_exp_f32_e32 v79, v74
	v_pk_add_f32 v[74:75], v[82:83], 1.0 op_sel_hi:[1,0]
	v_pk_add_f32 v[78:79], v[78:79], 1.0 op_sel_hi:[1,0]
	v_div_scale_f32 v76, s[0:1], v75, v75, 1.0
	v_rcp_f32_e32 v77, v76
	s_nop 0
	v_fma_f32 v82, -v76, v77, 1.0
	v_fmac_f32_e32 v77, v82, v77
	v_div_scale_f32 v82, vcc, 1.0, v75, 1.0
	v_mul_f32_e32 v83, v82, v77
	v_fma_f32 v88, -v76, v83, v82
	v_fmac_f32_e32 v83, v88, v77
	v_fma_f32 v76, -v76, v83, v82
	v_div_fmas_f32 v76, v76, v77, v83
	v_div_fixup_f32 v75, v76, v75, 1.0
	v_div_scale_f32 v76, s[0:1], v74, v74, 1.0
	v_rcp_f32_e32 v77, v76
	s_nop 0
	v_fma_f32 v82, -v76, v77, 1.0
	v_fmac_f32_e32 v77, v82, v77
	v_div_scale_f32 v82, vcc, 1.0, v74, 1.0
	v_mul_f32_e32 v83, v82, v77
	v_fma_f32 v88, -v76, v83, v82
	v_fmac_f32_e32 v83, v88, v77
	v_fma_f32 v76, -v76, v83, v82
	v_div_fmas_f32 v76, v76, v77, v83
	v_div_fixup_f32 v74, v76, v74, 1.0
	v_pk_mul_f32 v[74:75], v[74:75], s[4:5] op_sel_hi:[1,0]
	v_pk_add_f32 v[76:77], v[80:81], 1.0 op_sel_hi:[1,0]
	v_cvt_pk_f16_f32 v74, v74, v75
	v_div_scale_f32 v75, s[0:1], v77, v77, 1.0
	v_rcp_f32_e32 v80, v75
	s_nop 0
	v_fma_f32 v81, -v75, v80, 1.0
	v_fmac_f32_e32 v80, v81, v80
	v_div_scale_f32 v81, vcc, 1.0, v77, 1.0
	v_mul_f32_e32 v82, v81, v80
	v_fma_f32 v83, -v75, v82, v81
	v_fmac_f32_e32 v82, v83, v80
	v_fma_f32 v75, -v75, v82, v81
	v_div_fmas_f32 v75, v75, v80, v82
	v_div_fixup_f32 v77, v75, v77, 1.0
	v_div_scale_f32 v75, s[0:1], v76, v76, 1.0
	v_rcp_f32_e32 v80, v75
	s_nop 0
	v_fma_f32 v81, -v75, v80, 1.0
	v_fmac_f32_e32 v80, v81, v80
	v_div_scale_f32 v81, vcc, 1.0, v76, 1.0
	v_mul_f32_e32 v82, v81, v80
	v_fma_f32 v83, -v75, v82, v81
	v_fmac_f32_e32 v82, v83, v80
	v_fma_f32 v75, -v75, v82, v81
	v_div_fmas_f32 v75, v75, v80, v82
	v_div_fixup_f32 v76, v75, v76, 1.0
	v_pk_mul_f32 v[76:77], v[76:77], s[4:5] op_sel_hi:[1,0]
	s_nop 0
	v_cvt_pk_f16_f32 v75, v76, v77
	v_pk_add_f32 v[76:77], v[84:85], 1.0 op_sel_hi:[1,0]
	s_nop 0
	v_div_scale_f32 v80, s[0:1], v77, v77, 1.0
	v_rcp_f32_e32 v81, v80
	s_nop 0
	v_fma_f32 v82, -v80, v81, 1.0
	v_fmac_f32_e32 v81, v82, v81
	v_div_scale_f32 v82, vcc, 1.0, v77, 1.0
	v_mul_f32_e32 v83, v82, v81
	v_fma_f32 v84, -v80, v83, v82
	v_fmac_f32_e32 v83, v84, v81
	v_fma_f32 v80, -v80, v83, v82
	v_div_fmas_f32 v80, v80, v81, v83
	v_div_fixup_f32 v77, v80, v77, 1.0
	v_div_scale_f32 v80, s[0:1], v76, v76, 1.0
	v_rcp_f32_e32 v81, v80
	s_nop 0
	v_fma_f32 v82, -v80, v81, 1.0
	v_fmac_f32_e32 v81, v82, v81
	v_div_scale_f32 v82, vcc, 1.0, v76, 1.0
	v_mul_f32_e32 v83, v82, v81
	v_fma_f32 v84, -v80, v83, v82
	v_fmac_f32_e32 v83, v84, v81
	v_fma_f32 v80, -v80, v83, v82
	v_div_fmas_f32 v80, v80, v81, v83
	v_div_fixup_f32 v76, v80, v76, 1.0
	v_pk_mul_f32 v[76:77], v[76:77], s[4:5] op_sel_hi:[1,0]
	s_nop 0
	v_cvt_pk_f16_f32 v76, v76, v77
	v_div_scale_f32 v77, s[0:1], v79, v79, 1.0
	v_rcp_f32_e32 v80, v77
	s_nop 0
	v_fma_f32 v81, -v77, v80, 1.0
	v_fmac_f32_e32 v80, v81, v80
	v_div_scale_f32 v81, vcc, 1.0, v79, 1.0
	v_mul_f32_e32 v82, v81, v80
	v_fma_f32 v83, -v77, v82, v81
	v_fmac_f32_e32 v82, v83, v80
	v_fma_f32 v77, -v77, v82, v81
	v_div_fmas_f32 v77, v77, v80, v82
	v_div_fixup_f32 v79, v77, v79, 1.0
	v_div_scale_f32 v77, s[0:1], v78, v78, 1.0
	v_rcp_f32_e32 v80, v77
	s_mov_b32 s0, 0xa0000
	v_fma_f32 v81, -v77, v80, 1.0
	v_fmac_f32_e32 v80, v81, v80
	v_div_scale_f32 v81, vcc, 1.0, v78, 1.0
	v_mul_f32_e32 v82, v81, v80
	v_fma_f32 v83, -v77, v82, v81
	v_fmac_f32_e32 v82, v83, v80
	v_fma_f32 v77, -v77, v82, v81
	v_div_fmas_f32 v77, v77, v80, v82
	v_div_fixup_f32 v78, v77, v78, 1.0
	v_pk_mul_f32 v[78:79], v[78:79], s[4:5] op_sel_hi:[1,0]
	v_add_co_u32_e32 v80, vcc, s0, v134
	v_cvt_pk_f16_f32 v77, v78, v79
	s_nop 0
	v_addc_co_u32_e32 v81, vcc, 0, v135, vcc
	v_lshl_add_u64 v[78:79], v[134:135], 0, s[14:15]
	global_store_dwordx4 v[80:81], v[74:77], off
	v_pk_add_f32 v[66:67], v[66:67], v[90:91]
	v_pk_add_f32 v[70:71], v[70:71], v[94:95]
	v_mul_f32_e32 v66, 0xbfb8aa3b, v66
	v_mul_f32_e32 v70, 0xbfb8aa3b, v70
	v_exp_f32_e32 v74, v66
	v_mul_f32_e32 v66, 0xbfb8aa3b, v71
	v_exp_f32_e32 v70, v70
	v_exp_f32_e32 v71, v66
	v_pk_add_f32 v[72:73], v[72:73], v[96:97]
	v_pk_add_f32 v[68:69], v[68:69], v[92:93]
	v_mul_f32_e32 v66, 0xbfb8aa3b, v67
	v_pk_add_f32 v[70:71], v[70:71], 1.0 op_sel_hi:[1,0]
	v_exp_f32_e32 v75, v66
	v_mul_f32_e32 v66, 0xbfb8aa3b, v72
	v_mul_f32_e32 v67, 0xbfb8aa3b, v68
	v_div_scale_f32 v72, s[0:1], v71, v71, 1.0
	v_exp_f32_e32 v68, v67
	v_mul_f32_e32 v67, 0xbfb8aa3b, v73
	v_rcp_f32_e32 v73, v72
	v_exp_f32_e32 v66, v66
	v_exp_f32_e32 v67, v67
	v_pk_add_f32 v[74:75], v[74:75], 1.0 op_sel_hi:[1,0]
	v_fma_f32 v76, -v72, v73, 1.0
	v_fmac_f32_e32 v73, v76, v73
	v_div_scale_f32 v76, vcc, 1.0, v71, 1.0
	v_mul_f32_e32 v77, v76, v73
; __device__ __forceinline__ float sigmoidf_(float x) { return 1.0f / (1.0f + __expf(-x)); }
;     template <int GI>
;     __device__ __forceinline__ void body(const f32x4 (&acc)[2][2][4][2], int row0, int colt) const {
;     ...
;         for (int bj = 0; bj < 2; ++bj) {
;             const int c = colt + bj * 128;
;             f32x4 b0 = (f32x4){0.f, 0.f, 0.f, 0.f}, b1 = b0;
;             if (GI == 0) { b0 = *(const f32x4*)(w0 + c); b1 = *(const f32x4*)(w0 + c + 4); }
;             else if (GI == 1) { b0 = *(const f32x4*)(a0 + c); b1 = *(const f32x4*)(a0 + c + 4); }
;             else if (GI == 3) { b0 = *(const f32x4*)(v0 + c); b1 = *(const f32x4*)(v0 + c + 4); }
; #pragma unroll
;             for (int ai = 0; ai < 2; ++ai)
; #pragma unroll
;                 for (int m = 0; m < 4; ++m) {
;                     const size_t row = (size_t)(row0 + ai * 128 + m * 16);
;                     f32x4 x0 = acc[ai][bj][m][0] + b0, x1 = acc[ai][bj][m][1] + b1;
;                     if (GI == 0) {
; #pragma unroll
;                         for (int j = 0; j < 4; ++j) {
;                             x0[j] = 0.6065306597126334f * sigmoidf_(x0[j]); x1[j] = 0.6065306597126334f * sigmoidf_(x1[j]); }
;                         *(u32x4*)(DEC + row * DM + c) = pack8(x0, x1);
	v_fma_f32 v80, -v72, v77, v76
	v_fmac_f32_e32 v77, v80, v73
	v_fma_f32 v72, -v72, v77, v76
	v_div_scale_f32 v76, s[0:1], v70, v70, 1.0
	v_rcp_f32_e32 v80, v76
	v_div_fmas_f32 v72, v72, v73, v77
	v_div_fixup_f32 v71, v72, v71, 1.0
	v_mul_f32_e32 v69, 0xbfb8aa3b, v69
	v_fma_f32 v72, -v76, v80, 1.0
	v_fmac_f32_e32 v80, v72, v80
	v_div_scale_f32 v72, vcc, 1.0, v70, 1.0
	v_mul_f32_e32 v73, v72, v80
	v_fma_f32 v77, -v76, v73, v72
	v_fmac_f32_e32 v73, v77, v80
	v_fma_f32 v72, -v76, v73, v72
	v_div_fmas_f32 v76, v72, v80, v73
	v_pk_add_f32 v[72:73], v[66:67], 1.0 op_sel_hi:[1,0]
	v_div_fixup_f32 v70, v76, v70, 1.0
	v_div_scale_f32 v77, s[0:1], v73, v73, 1.0
	v_rcp_f32_e32 v80, v77
	v_pk_mul_f32 v[66:67], v[70:71], s[4:5] op_sel_hi:[1,0]
	v_div_scale_f32 v76, s[0:1], v72, v72, 1.0
	v_cvt_pk_f16_f32 v66, v66, v67
	v_fma_f32 v67, -v77, v80, 1.0
	v_fmac_f32_e32 v80, v67, v80
	v_div_scale_f32 v67, vcc, 1.0, v73, 1.0
	v_mul_f32_e32 v70, v67, v80
	v_fma_f32 v71, -v77, v70, v67
	v_fmac_f32_e32 v70, v71, v80
	v_fma_f32 v67, -v77, v70, v67
	v_rcp_f32_e32 v77, v76
	v_div_fmas_f32 v67, v67, v80, v70
	v_div_fixup_f32 v71, v67, v73, 1.0
	v_exp_f32_e32 v69, v69
	v_fma_f32 v67, -v76, v77, 1.0
	v_fmac_f32_e32 v77, v67, v77
	v_div_scale_f32 v67, vcc, 1.0, v72, 1.0
	v_mul_f32_e32 v70, v67, v77
	v_fma_f32 v73, -v76, v70, v67
	v_fmac_f32_e32 v70, v73, v77
	v_div_scale_f32 v73, s[0:1], v75, v75, 1.0
	v_fma_f32 v67, -v76, v70, v67
	v_rcp_f32_e32 v76, v73
	v_div_fmas_f32 v67, v67, v77, v70
	v_div_fixup_f32 v70, v67, v72, 1.0
	v_pk_mul_f32 v[70:71], v[70:71], s[4:5] op_sel_hi:[1,0]
	s_nop 0
	v_cvt_pk_f16_f32 v67, v70, v71
	v_fma_f32 v70, -v73, v76, 1.0
	v_fmac_f32_e32 v76, v70, v76
	v_div_scale_f32 v70, vcc, 1.0, v75, 1.0
	v_mul_f32_e32 v71, v70, v76
	v_fma_f32 v72, -v73, v71, v70
	v_fmac_f32_e32 v71, v72, v76
	v_div_scale_f32 v72, s[0:1], v74, v74, 1.0
	v_fma_f32 v70, -v73, v71, v70
	v_rcp_f32_e32 v73, v72
	v_div_fmas_f32 v70, v70, v76, v71
	v_div_fixup_f32 v71, v70, v75, 1.0
	v_fma_f32 v70, -v72, v73, 1.0
	v_fmac_f32_e32 v73, v70, v73
	v_div_scale_f32 v70, vcc, 1.0, v74, 1.0
	v_mul_f32_e32 v75, v70, v73
	v_fma_f32 v76, -v72, v75, v70
	v_fmac_f32_e32 v75, v76, v73
	v_fma_f32 v70, -v72, v75, v70
	v_div_fmas_f32 v70, v70, v73, v75
	v_pk_add_f32 v[72:73], v[68:69], 1.0 op_sel_hi:[1,0]
	v_div_fixup_f32 v70, v70, v74, 1.0
	v_div_scale_f32 v75, s[0:1], v73, v73, 1.0
	v_rcp_f32_e32 v76, v75
	v_pk_mul_f32 v[68:69], v[70:71], s[4:5] op_sel_hi:[1,0]
	v_div_scale_f32 v74, s[0:1], v72, v72, 1.0
	v_cvt_pk_f16_f32 v68, v68, v69
	v_fma_f32 v69, -v75, v76, 1.0
	v_fmac_f32_e32 v76, v69, v76
	v_div_scale_f32 v69, vcc, 1.0, v73, 1.0
	v_mul_f32_e32 v70, v69, v76
	v_fma_f32 v71, -v75, v70, v69
	v_fmac_f32_e32 v70, v71, v76
	v_fma_f32 v69, -v75, v70, v69
	v_rcp_f32_e32 v75, v74
	v_div_fmas_f32 v69, v69, v76, v70
	v_div_fixup_f32 v71, v69, v73, 1.0
	s_mov_b32 s0, 0xb0000
	v_fma_f32 v69, -v74, v75, 1.0
	v_fmac_f32_e32 v75, v69, v75
	v_div_scale_f32 v69, vcc, 1.0, v72, 1.0
	v_mul_f32_e32 v70, v69, v75
	v_fma_f32 v73, -v74, v70, v69
	v_fmac_f32_e32 v70, v73, v75
	v_fma_f32 v69, -v74, v70, v69
	v_div_fmas_f32 v69, v69, v75, v70
	v_div_fixup_f32 v70, v69, v72, 1.0
	v_pk_mul_f32 v[70:71], v[70:71], s[4:5] op_sel_hi:[1,0]
	v_lshl_add_u64 v[74:75], v[134:135], 0, s[16:17]
	v_cvt_pk_f16_f32 v69, v70, v71
	v_add_co_u32_e32 v70, vcc, s0, v134
	s_nop 1
	v_addc_co_u32_e32 v71, vcc, 0, v135, vcc
	global_store_dwordx4 v[70:71], v[66:69], off
	global_load_dwordx4 v[66:69], v[148:149], off offset:528
	s_nop 0
	global_load_dwordx4 v[70:73], v[148:149], off offset:512
	s_waitcnt vmcnt(0)
	v_pk_add_f32 v[58:59], v[58:59], v[66:67]
	v_pk_add_f32 v[62:63], v[62:63], v[70:71]
	v_pk_add_f32 v[76:77], v[60:61], v[68:69]
	v_mul_f32_e32 v60, 0xbfb8aa3b, v62
	v_mul_f32_e32 v58, 0xbfb8aa3b, v58
	v_exp_f32_e32 v80, v60
	v_exp_f32_e32 v60, v58
	v_mul_f32_e32 v58, 0xbfb8aa3b, v63
	v_pk_add_f32 v[64:65], v[64:65], v[72:73]
	v_exp_f32_e32 v81, v58
	v_mul_f32_e32 v58, 0xbfb8aa3b, v59
	v_exp_f32_e32 v61, v58
	v_mul_f32_e32 v58, 0xbfb8aa3b, v64
	v_exp_f32_e32 v64, v58
	v_mul_f32_e32 v58, 0xbfb8aa3b, v76
	v_exp_f32_e32 v62, v58
	v_mul_f32_e32 v58, 0xbfb8aa3b, v65
	v_exp_f32_e32 v65, v58
	v_mul_f32_e32 v58, 0xbfb8aa3b, v77
	v_exp_f32_e32 v63, v58
	v_pk_add_f32 v[58:59], v[80:81], 1.0 op_sel_hi:[1,0]
	v_pk_add_f32 v[64:65], v[64:65], 1.0 op_sel_hi:[1,0]
	v_div_scale_f32 v76, s[0:1], v59, v59, 1.0
	v_rcp_f32_e32 v77, v76
	v_pk_add_f32 v[60:61], v[60:61], 1.0 op_sel_hi:[1,0]
	v_pk_add_f32 v[62:63], v[62:63], 1.0 op_sel_hi:[1,0]
	v_fma_f32 v80, -v76, v77, 1.0
	v_fmac_f32_e32 v77, v80, v77
	v_div_scale_f32 v80, vcc, 1.0, v59, 1.0
	v_mul_f32_e32 v81, v80, v77
	v_fma_f32 v82, -v76, v81, v80
	v_fmac_f32_e32 v81, v82, v77
	v_fma_f32 v76, -v76, v81, v80
	v_div_fmas_f32 v76, v76, v77, v81
	v_div_fixup_f32 v59, v76, v59, 1.0
	v_div_scale_f32 v76, s[0:1], v58, v58, 1.0
	v_rcp_f32_e32 v77, v76
	s_nop 0
	v_fma_f32 v80, -v76, v77, 1.0
	v_fmac_f32_e32 v77, v80, v77
	v_div_scale_f32 v80, vcc, 1.0, v58, 1.0
	v_mul_f32_e32 v81, v80, v77
	v_fma_f32 v82, -v76, v81, v80
	v_fmac_f32_e32 v81, v82, v77
	v_fma_f32 v76, -v76, v81, v80
	v_div_fmas_f32 v76, v76, v77, v81
	v_div_fixup_f32 v58, v76, v58, 1.0
	v_pk_mul_f32 v[58:59], v[58:59], s[4:5] op_sel_hi:[1,0]
	s_nop 0
	v_cvt_pk_f16_f32 v58, v58, v59
	v_div_scale_f32 v59, s[0:1], v65, v65, 1.0
	v_rcp_f32_e32 v76, v59
	s_nop 0
	v_fma_f32 v77, -v59, v76, 1.0
	v_fmac_f32_e32 v76, v77, v76
	v_div_scale_f32 v77, vcc, 1.0, v65, 1.0
	v_mul_f32_e32 v80, v77, v76
	v_fma_f32 v81, -v59, v80, v77
	v_fmac_f32_e32 v80, v81, v76
	v_fma_f32 v59, -v59, v80, v77
	v_div_fmas_f32 v59, v59, v76, v80
	v_div_fixup_f32 v65, v59, v65, 1.0
; __device__ __forceinline__ float sigmoidf_(float x) { return 1.0f / (1.0f + __expf(-x)); }
;     template <int GI>
;     __device__ __forceinline__ void body(const f32x4 (&acc)[2][2][4][2], int row0, int colt) const {
; #pragma unroll
;         for (int bj = 0; bj < 2; ++bj) {
;             const int c = colt + bj * 128;
;             f32x4 b0 = (f32x4){0.f, 0.f, 0.f, 0.f}, b1 = b0;
;             if (GI == 0) { b0 = *(const f32x4*)(w0 + c); b1 = *(const f32x4*)(w0 + c + 4); }
;             else if (GI == 1) { b0 = *(const f32x4*)(a0 + c); b1 = *(const f32x4*)(a0 + c + 4); }
;             else if (GI == 3) { b0 = *(const f32x4*)(v0 + c); b1 = *(const f32x4*)(v0 + c + 4); }
; #pragma unroll
;             for (int ai = 0; ai < 2; ++ai)
; #pragma unroll
;                 for (int m = 0; m < 4; ++m) {
;                     const size_t row = (size_t)(row0 + ai * 128 + m * 16);
;                     f32x4 x0 = acc[ai][bj][m][0] + b0, x1 = acc[ai][bj][m][1] + b1;
;                     if (GI == 0) {
; #pragma unroll
;                         for (int j = 0; j < 4; ++j) {
;                             x0[j] = 0.6065306597126334f * sigmoidf_(x0[j]); x1[j] = 0.6065306597126334f * sigmoidf_(x1[j]); }
;                         *(u32x4*)(DEC + row * DM + c) = pack8(x0, x1);
	v_div_scale_f32 v59, s[0:1], v64, v64, 1.0
	v_rcp_f32_e32 v76, v59
	s_nop 0
	v_fma_f32 v77, -v59, v76, 1.0
	v_fmac_f32_e32 v76, v77, v76
	v_div_scale_f32 v77, vcc, 1.0, v64, 1.0
	v_mul_f32_e32 v80, v77, v76
	v_fma_f32 v81, -v59, v80, v77
	v_fmac_f32_e32 v80, v81, v76
	v_fma_f32 v59, -v59, v80, v77
	v_div_fmas_f32 v59, v59, v76, v80
	v_div_fixup_f32 v64, v59, v64, 1.0
	v_pk_mul_f32 v[64:65], v[64:65], s[4:5] op_sel_hi:[1,0]
	s_nop 0
	v_cvt_pk_f16_f32 v59, v64, v65
	v_div_scale_f32 v64, s[0:1], v61, v61, 1.0
	v_rcp_f32_e32 v65, v64
	s_nop 0
	v_fma_f32 v76, -v64, v65, 1.0
	v_fmac_f32_e32 v65, v76, v65
	v_div_scale_f32 v76, vcc, 1.0, v61, 1.0
	v_mul_f32_e32 v77, v76, v65
	v_fma_f32 v80, -v64, v77, v76
	v_fmac_f32_e32 v77, v80, v65
	v_fma_f32 v64, -v64, v77, v76
	v_div_fmas_f32 v64, v64, v65, v77
	v_div_fixup_f32 v61, v64, v61, 1.0
	v_div_scale_f32 v64, s[0:1], v60, v60, 1.0
	v_rcp_f32_e32 v65, v64
	s_nop 0
	v_fma_f32 v76, -v64, v65, 1.0
	v_fmac_f32_e32 v65, v76, v65
	v_div_scale_f32 v76, vcc, 1.0, v60, 1.0
	v_mul_f32_e32 v77, v76, v65
	v_fma_f32 v80, -v64, v77, v76
	v_fmac_f32_e32 v77, v80, v65
	v_fma_f32 v64, -v64, v77, v76
	v_div_fmas_f32 v64, v64, v65, v77
	v_div_fixup_f32 v60, v64, v60, 1.0
	v_pk_mul_f32 v[60:61], v[60:61], s[4:5] op_sel_hi:[1,0]
	s_nop 0
	v_cvt_pk_f16_f32 v60, v60, v61
	v_div_scale_f32 v61, s[0:1], v63, v63, 1.0
	v_rcp_f32_e32 v64, v61
	s_nop 0
	v_fma_f32 v65, -v61, v64, 1.0
	v_fmac_f32_e32 v64, v65, v64
	v_div_scale_f32 v65, vcc, 1.0, v63, 1.0
	v_mul_f32_e32 v76, v65, v64
	v_fma_f32 v77, -v61, v76, v65
	v_fmac_f32_e32 v76, v77, v64
	v_fma_f32 v61, -v61, v76, v65
	v_div_fmas_f32 v61, v61, v64, v76
	v_div_fixup_f32 v63, v61, v63, 1.0
	v_div_scale_f32 v61, s[0:1], v62, v62, 1.0
	v_rcp_f32_e32 v64, v61
	s_nop 0
	v_fma_f32 v65, -v61, v64, 1.0
	v_fmac_f32_e32 v64, v65, v64
	v_div_scale_f32 v65, vcc, 1.0, v62, 1.0
	v_mul_f32_e32 v76, v65, v64
	v_fma_f32 v77, -v61, v76, v65
	v_fmac_f32_e32 v76, v77, v64
	v_fma_f32 v61, -v61, v76, v65
	v_div_fmas_f32 v61, v61, v64, v76
	v_div_fixup_f32 v62, v61, v62, 1.0
	v_pk_mul_f32 v[62:63], v[62:63], s[4:5] op_sel_hi:[1,0]
	s_nop 0
	v_cvt_pk_f16_f32 v61, v62, v63
	global_store_dwordx4 v[134:135], v[58:61], off offset:256
	v_pk_add_f32 v[50:51], v[50:51], v[66:67]
	v_pk_add_f32 v[54:55], v[54:55], v[70:71]
	v_mul_f32_e32 v50, 0xbfb8aa3b, v50
	v_exp_f32_e32 v60, v50
	v_mul_f32_e32 v50, 0xbfb8aa3b, v55
	v_pk_add_f32 v[56:57], v[56:57], v[72:73]
	v_mul_f32_e32 v54, 0xbfb8aa3b, v54
	v_exp_f32_e32 v59, v50
	v_mul_f32_e32 v50, 0xbfb8aa3b, v51
	v_pk_add_f32 v[52:53], v[52:53], v[68:69]
	v_exp_f32_e32 v58, v54
	v_exp_f32_e32 v61, v50
	v_mul_f32_e32 v50, 0xbfb8aa3b, v56
	v_exp_f32_e32 v56, v50
	v_mul_f32_e32 v50, 0xbfb8aa3b, v52
	v_exp_f32_e32 v54, v50
	v_mul_f32_e32 v50, 0xbfb8aa3b, v57
	v_exp_f32_e32 v57, v50
	v_mul_f32_e32 v50, 0xbfb8aa3b, v53
	v_exp_f32_e32 v55, v50
	v_pk_add_f32 v[50:51], v[58:59], 1.0 op_sel_hi:[1,0]
	v_pk_add_f32 v[54:55], v[54:55], 1.0 op_sel_hi:[1,0]
	v_div_scale_f32 v52, s[0:1], v51, v51, 1.0
	v_rcp_f32_e32 v53, v52
	s_nop 0
	v_fma_f32 v58, -v52, v53, 1.0
	v_fmac_f32_e32 v53, v58, v53
	v_div_scale_f32 v58, vcc, 1.0, v51, 1.0
	v_mul_f32_e32 v59, v58, v53
	v_fma_f32 v62, -v52, v59, v58
	v_fmac_f32_e32 v59, v62, v53
	v_fma_f32 v52, -v52, v59, v58
	v_div_fmas_f32 v52, v52, v53, v59
	v_div_fixup_f32 v51, v52, v51, 1.0
	v_div_scale_f32 v52, s[0:1], v50, v50, 1.0
	v_rcp_f32_e32 v53, v52
	s_nop 0
	v_fma_f32 v58, -v52, v53, 1.0
	v_fmac_f32_e32 v53, v58, v53
	v_div_scale_f32 v58, vcc, 1.0, v50, 1.0
	v_mul_f32_e32 v59, v58, v53
	v_fma_f32 v62, -v52, v59, v58
	v_fmac_f32_e32 v59, v62, v53
	v_fma_f32 v52, -v52, v59, v58
	v_div_fmas_f32 v52, v52, v53, v59
	v_div_fixup_f32 v50, v52, v50, 1.0
	v_pk_mul_f32 v[50:51], v[50:51], s[4:5] op_sel_hi:[1,0]
	v_pk_add_f32 v[52:53], v[56:57], 1.0 op_sel_hi:[1,0]
	v_cvt_pk_f16_f32 v50, v50, v51
	v_div_scale_f32 v51, s[0:1], v53, v53, 1.0
	v_rcp_f32_e32 v56, v51
	s_nop 0
	v_fma_f32 v57, -v51, v56, 1.0
	v_fmac_f32_e32 v56, v57, v56
	v_div_scale_f32 v57, vcc, 1.0, v53, 1.0
	v_mul_f32_e32 v58, v57, v56
	v_fma_f32 v59, -v51, v58, v57
	v_fmac_f32_e32 v58, v59, v56
	v_fma_f32 v51, -v51, v58, v57
	v_div_fmas_f32 v51, v51, v56, v58
	v_div_fixup_f32 v53, v51, v53, 1.0
	v_div_scale_f32 v51, s[0:1], v52, v52, 1.0
	v_rcp_f32_e32 v56, v51
	s_nop 0
	v_fma_f32 v57, -v51, v56, 1.0
	v_fmac_f32_e32 v56, v57, v56
	v_div_scale_f32 v57, vcc, 1.0, v52, 1.0
	v_mul_f32_e32 v58, v57, v56
	v_fma_f32 v59, -v51, v58, v57
	v_fmac_f32_e32 v58, v59, v56
	v_fma_f32 v51, -v51, v58, v57
	v_div_fmas_f32 v51, v51, v56, v58
	v_div_fixup_f32 v52, v51, v52, 1.0
	v_pk_mul_f32 v[52:53], v[52:53], s[4:5] op_sel_hi:[1,0]
	s_nop 0
	v_cvt_pk_f16_f32 v51, v52, v53
	v_pk_add_f32 v[52:53], v[60:61], 1.0 op_sel_hi:[1,0]
	s_nop 0
	v_div_scale_f32 v56, s[0:1], v53, v53, 1.0
	v_rcp_f32_e32 v57, v56
	s_nop 0
	v_fma_f32 v58, -v56, v57, 1.0
	v_fmac_f32_e32 v57, v58, v57
	v_div_scale_f32 v58, vcc, 1.0, v53, 1.0
	v_mul_f32_e32 v59, v58, v57
	v_fma_f32 v60, -v56, v59, v58
	v_fmac_f32_e32 v59, v60, v57
	v_fma_f32 v56, -v56, v59, v58
	v_div_fmas_f32 v56, v56, v57, v59
	v_div_fixup_f32 v53, v56, v53, 1.0
	v_div_scale_f32 v56, s[0:1], v52, v52, 1.0
	v_rcp_f32_e32 v57, v56
	s_nop 0
	v_fma_f32 v58, -v56, v57, 1.0
	v_fmac_f32_e32 v57, v58, v57
	v_div_scale_f32 v58, vcc, 1.0, v52, 1.0
	v_mul_f32_e32 v59, v58, v57
	v_fma_f32 v60, -v56, v59, v58
	v_fmac_f32_e32 v59, v60, v57
	v_fma_f32 v56, -v56, v59, v58
	v_div_fmas_f32 v56, v56, v57, v59
	v_div_fixup_f32 v52, v56, v52, 1.0
	v_pk_mul_f32 v[52:53], v[52:53], s[4:5] op_sel_hi:[1,0]
	s_nop 0
	v_cvt_pk_f16_f32 v52, v52, v53
	v_div_scale_f32 v53, s[0:1], v55, v55, 1.0
; __device__ __forceinline__ float sigmoidf_(float x) { return 1.0f / (1.0f + __expf(-x)); }
;     template <int GI>
;     __device__ __forceinline__ void body(const f32x4 (&acc)[2][2][4][2], int row0, int colt) const {
; #pragma unroll
;         for (int bj = 0; bj < 2; ++bj) {
;             const int c = colt + bj * 128;
;             f32x4 b0 = (f32x4){0.f, 0.f, 0.f, 0.f}, b1 = b0;
;             if (GI == 0) { b0 = *(const f32x4*)(w0 + c); b1 = *(const f32x4*)(w0 + c + 4); }
;             else if (GI == 1) { b0 = *(const f32x4*)(a0 + c); b1 = *(const f32x4*)(a0 + c + 4); }
;             else if (GI == 3) { b0 = *(const f32x4*)(v0 + c); b1 = *(const f32x4*)(v0 + c + 4); }
; #pragma unroll
;             for (int ai = 0; ai < 2; ++ai)
; #pragma unroll
;                 for (int m = 0; m < 4; ++m) {
;                     const size_t row = (size_t)(row0 + ai * 128 + m * 16);
;                     f32x4 x0 = acc[ai][bj][m][0] + b0, x1 = acc[ai][bj][m][1] + b1;
;                     if (GI == 0) {
; #pragma unroll
;                         for (int j = 0; j < 4; ++j) {
;                             x0[j] = 0.6065306597126334f * sigmoidf_(x0[j]); x1[j] = 0.6065306597126334f * sigmoidf_(x1[j]); }
;                         *(u32x4*)(DEC + row * DM + c) = pack8(x0, x1);
	v_rcp_f32_e32 v56, v53
	s_nop 0
	v_fma_f32 v57, -v53, v56, 1.0
	v_fmac_f32_e32 v56, v57, v56
	v_div_scale_f32 v57, vcc, 1.0, v55, 1.0
	v_mul_f32_e32 v58, v57, v56
	v_fma_f32 v59, -v53, v58, v57
	v_fmac_f32_e32 v58, v59, v56
	v_fma_f32 v53, -v53, v58, v57
	v_div_fmas_f32 v53, v53, v56, v58
	v_div_fixup_f32 v55, v53, v55, 1.0
	v_div_scale_f32 v53, s[0:1], v54, v54, 1.0
	v_rcp_f32_e32 v56, v53
	s_nop 0
	v_fma_f32 v57, -v53, v56, 1.0
	v_fmac_f32_e32 v56, v57, v56
	v_div_scale_f32 v57, vcc, 1.0, v54, 1.0
	v_mul_f32_e32 v58, v57, v56
	v_fma_f32 v59, -v53, v58, v57
	v_fmac_f32_e32 v58, v59, v56
	v_fma_f32 v53, -v53, v58, v57
	v_div_fmas_f32 v53, v53, v56, v58
	v_div_fixup_f32 v54, v53, v54, 1.0
	v_pk_mul_f32 v[54:55], v[54:55], s[4:5] op_sel_hi:[1,0]
	s_nop 0
	v_cvt_pk_f16_f32 v53, v54, v55
	global_store_dwordx4 v[126:127], v[50:53], off offset:256
	v_pk_add_f32 v[42:43], v[42:43], v[66:67]
	v_pk_add_f32 v[46:47], v[46:47], v[70:71]
	v_mul_f32_e32 v42, 0xbfb8aa3b, v42
	v_exp_f32_e32 v52, v42
	v_mul_f32_e32 v42, 0xbfb8aa3b, v47
	v_pk_add_f32 v[48:49], v[48:49], v[72:73]
	v_mul_f32_e32 v46, 0xbfb8aa3b, v46
	v_exp_f32_e32 v51, v42
	v_mul_f32_e32 v42, 0xbfb8aa3b, v43
	v_pk_add_f32 v[44:45], v[44:45], v[68:69]
	v_exp_f32_e32 v50, v46
	v_exp_f32_e32 v53, v42
	v_mul_f32_e32 v42, 0xbfb8aa3b, v48
	v_exp_f32_e32 v48, v42
	v_mul_f32_e32 v42, 0xbfb8aa3b, v44
	v_exp_f32_e32 v46, v42
	v_mul_f32_e32 v42, 0xbfb8aa3b, v49
	v_exp_f32_e32 v49, v42
	v_mul_f32_e32 v42, 0xbfb8aa3b, v45
	v_exp_f32_e32 v47, v42
	v_pk_add_f32 v[42:43], v[50:51], 1.0 op_sel_hi:[1,0]
	v_pk_add_f32 v[46:47], v[46:47], 1.0 op_sel_hi:[1,0]
	v_div_scale_f32 v44, s[0:1], v43, v43, 1.0
	v_rcp_f32_e32 v45, v44
	s_nop 0
	v_fma_f32 v50, -v44, v45, 1.0
	v_fmac_f32_e32 v45, v50, v45
	v_div_scale_f32 v50, vcc, 1.0, v43, 1.0
	v_mul_f32_e32 v51, v50, v45
	v_fma_f32 v54, -v44, v51, v50
	v_fmac_f32_e32 v51, v54, v45
	v_fma_f32 v44, -v44, v51, v50
	v_div_fmas_f32 v44, v44, v45, v51
	v_div_fixup_f32 v43, v44, v43, 1.0
	v_div_scale_f32 v44, s[0:1], v42, v42, 1.0
	v_rcp_f32_e32 v45, v44
	s_nop 0
	v_fma_f32 v50, -v44, v45, 1.0
	v_fmac_f32_e32 v45, v50, v45
	v_div_scale_f32 v50, vcc, 1.0, v42, 1.0
	v_mul_f32_e32 v51, v50, v45
	v_fma_f32 v54, -v44, v51, v50
	v_fmac_f32_e32 v51, v54, v45
	v_fma_f32 v44, -v44, v51, v50
	v_div_fmas_f32 v44, v44, v45, v51
	v_div_fixup_f32 v42, v44, v42, 1.0
	v_pk_mul_f32 v[42:43], v[42:43], s[4:5] op_sel_hi:[1,0]
	v_pk_add_f32 v[44:45], v[48:49], 1.0 op_sel_hi:[1,0]
	v_cvt_pk_f16_f32 v42, v42, v43
	v_div_scale_f32 v43, s[0:1], v45, v45, 1.0
	v_rcp_f32_e32 v48, v43
	s_nop 0
	v_fma_f32 v49, -v43, v48, 1.0
	v_fmac_f32_e32 v48, v49, v48
	v_div_scale_f32 v49, vcc, 1.0, v45, 1.0
	v_mul_f32_e32 v50, v49, v48
	v_fma_f32 v51, -v43, v50, v49
	v_fmac_f32_e32 v50, v51, v48
	v_fma_f32 v43, -v43, v50, v49
	v_div_fmas_f32 v43, v43, v48, v50
	v_div_fixup_f32 v45, v43, v45, 1.0
	v_div_scale_f32 v43, s[0:1], v44, v44, 1.0
	v_rcp_f32_e32 v48, v43
	s_nop 0
	v_fma_f32 v49, -v43, v48, 1.0
	v_fmac_f32_e32 v48, v49, v48
	v_div_scale_f32 v49, vcc, 1.0, v44, 1.0
	v_mul_f32_e32 v50, v49, v48
	v_fma_f32 v51, -v43, v50, v49
	v_fmac_f32_e32 v50, v51, v48
	v_fma_f32 v43, -v43, v50, v49
	v_div_fmas_f32 v43, v43, v48, v50
	v_div_fixup_f32 v44, v43, v44, 1.0
	v_pk_mul_f32 v[44:45], v[44:45], s[4:5] op_sel_hi:[1,0]
	s_nop 0
	v_cvt_pk_f16_f32 v43, v44, v45
	v_pk_add_f32 v[44:45], v[52:53], 1.0 op_sel_hi:[1,0]
	s_nop 0
	v_div_scale_f32 v48, s[0:1], v45, v45, 1.0
	v_rcp_f32_e32 v49, v48
	s_nop 0
	v_fma_f32 v50, -v48, v49, 1.0
	v_fmac_f32_e32 v49, v50, v49
	v_div_scale_f32 v50, vcc, 1.0, v45, 1.0
	v_mul_f32_e32 v51, v50, v49
	v_fma_f32 v52, -v48, v51, v50
	v_fmac_f32_e32 v51, v52, v49
	v_fma_f32 v48, -v48, v51, v50
	v_div_fmas_f32 v48, v48, v49, v51
	v_div_fixup_f32 v45, v48, v45, 1.0
	v_div_scale_f32 v48, s[0:1], v44, v44, 1.0
	v_rcp_f32_e32 v49, v48
	s_nop 0
	v_fma_f32 v50, -v48, v49, 1.0
	v_fmac_f32_e32 v49, v50, v49
	v_div_scale_f32 v50, vcc, 1.0, v44, 1.0
	v_mul_f32_e32 v51, v50, v49
	v_fma_f32 v52, -v48, v51, v50
	v_fmac_f32_e32 v51, v52, v49
	v_fma_f32 v48, -v48, v51, v50
	v_div_fmas_f32 v48, v48, v49, v51
	v_div_fixup_f32 v44, v48, v44, 1.0
	v_pk_mul_f32 v[44:45], v[44:45], s[4:5] op_sel_hi:[1,0]
	s_nop 0
	v_cvt_pk_f16_f32 v44, v44, v45
	v_div_scale_f32 v45, s[0:1], v47, v47, 1.0
	v_rcp_f32_e32 v48, v45
	s_nop 0
	v_fma_f32 v49, -v45, v48, 1.0
	v_fmac_f32_e32 v48, v49, v48
	v_div_scale_f32 v49, vcc, 1.0, v47, 1.0
	v_mul_f32_e32 v50, v49, v48
	v_fma_f32 v51, -v45, v50, v49
	v_fmac_f32_e32 v50, v51, v48
	v_fma_f32 v45, -v45, v50, v49
	v_div_fmas_f32 v45, v45, v48, v50
	v_div_fixup_f32 v47, v45, v47, 1.0
	v_div_scale_f32 v45, s[0:1], v46, v46, 1.0
	v_rcp_f32_e32 v48, v45
	s_nop 0
	v_fma_f32 v49, -v45, v48, 1.0
	v_fmac_f32_e32 v48, v49, v48
	v_div_scale_f32 v49, vcc, 1.0, v46, 1.0
	v_mul_f32_e32 v50, v49, v48
	v_fma_f32 v51, -v45, v50, v49
	v_fmac_f32_e32 v50, v51, v48
	v_fma_f32 v45, -v45, v50, v49
	v_div_fmas_f32 v45, v45, v48, v50
	v_div_fixup_f32 v46, v45, v46, 1.0
	v_pk_mul_f32 v[46:47], v[46:47], s[4:5] op_sel_hi:[1,0]
	s_nop 0
	v_cvt_pk_f16_f32 v45, v46, v47
	global_store_dwordx4 v[118:119], v[42:45], off offset:256
	v_pk_add_f32 v[34:35], v[34:35], v[66:67]
	v_pk_add_f32 v[38:39], v[38:39], v[70:71]
	v_mul_f32_e32 v34, 0xbfb8aa3b, v34
	v_exp_f32_e32 v44, v34
	v_mul_f32_e32 v34, 0xbfb8aa3b, v39
	v_pk_add_f32 v[40:41], v[40:41], v[72:73]
	v_mul_f32_e32 v38, 0xbfb8aa3b, v38
	v_exp_f32_e32 v43, v34
	v_mul_f32_e32 v34, 0xbfb8aa3b, v35
	v_pk_add_f32 v[36:37], v[36:37], v[68:69]
	v_exp_f32_e32 v42, v38
	v_exp_f32_e32 v45, v34
	v_mul_f32_e32 v34, 0xbfb8aa3b, v40
	v_exp_f32_e32 v40, v34
	v_mul_f32_e32 v34, 0xbfb8aa3b, v36
; __device__ __forceinline__ float sigmoidf_(float x) { return 1.0f / (1.0f + __expf(-x)); }
;     template <int GI>
;     __device__ __forceinline__ void body(const f32x4 (&acc)[2][2][4][2], int row0, int colt) const {
; #pragma unroll
;         for (int bj = 0; bj < 2; ++bj) {
;             const int c = colt + bj * 128;
;             f32x4 b0 = (f32x4){0.f, 0.f, 0.f, 0.f}, b1 = b0;
;             if (GI == 0) { b0 = *(const f32x4*)(w0 + c); b1 = *(const f32x4*)(w0 + c + 4); }
;             else if (GI == 1) { b0 = *(const f32x4*)(a0 + c); b1 = *(const f32x4*)(a0 + c + 4); }
;             else if (GI == 3) { b0 = *(const f32x4*)(v0 + c); b1 = *(const f32x4*)(v0 + c + 4); }
; #pragma unroll
;             for (int ai = 0; ai < 2; ++ai)
; #pragma unroll
;                 for (int m = 0; m < 4; ++m) {
;                     const size_t row = (size_t)(row0 + ai * 128 + m * 16);
;                     f32x4 x0 = acc[ai][bj][m][0] + b0, x1 = acc[ai][bj][m][1] + b1;
;                     if (GI == 0) {
; #pragma unroll
;                         for (int j = 0; j < 4; ++j) {
;                             x0[j] = 0.6065306597126334f * sigmoidf_(x0[j]); x1[j] = 0.6065306597126334f * sigmoidf_(x1[j]); }
;                         *(u32x4*)(DEC + row * DM + c) = pack8(x0, x1);
	v_exp_f32_e32 v38, v34
	v_mul_f32_e32 v34, 0xbfb8aa3b, v41
	v_exp_f32_e32 v41, v34
	v_mul_f32_e32 v34, 0xbfb8aa3b, v37
	v_exp_f32_e32 v39, v34
	v_pk_add_f32 v[34:35], v[42:43], 1.0 op_sel_hi:[1,0]
	v_pk_add_f32 v[38:39], v[38:39], 1.0 op_sel_hi:[1,0]
	v_div_scale_f32 v36, s[0:1], v35, v35, 1.0
	v_rcp_f32_e32 v37, v36
	s_nop 0
	v_fma_f32 v42, -v36, v37, 1.0
	v_fmac_f32_e32 v37, v42, v37
	v_div_scale_f32 v42, vcc, 1.0, v35, 1.0
	v_mul_f32_e32 v43, v42, v37
	v_fma_f32 v46, -v36, v43, v42
	v_fmac_f32_e32 v43, v46, v37
	v_fma_f32 v36, -v36, v43, v42
	v_div_fmas_f32 v36, v36, v37, v43
	v_div_fixup_f32 v35, v36, v35, 1.0
	v_div_scale_f32 v36, s[0:1], v34, v34, 1.0
	v_rcp_f32_e32 v37, v36
	s_nop 0
	v_fma_f32 v42, -v36, v37, 1.0
	v_fmac_f32_e32 v37, v42, v37
	v_div_scale_f32 v42, vcc, 1.0, v34, 1.0
	v_mul_f32_e32 v43, v42, v37
	v_fma_f32 v46, -v36, v43, v42
	v_fmac_f32_e32 v43, v46, v37
	v_fma_f32 v36, -v36, v43, v42
	v_div_fmas_f32 v36, v36, v37, v43
	v_div_fixup_f32 v34, v36, v34, 1.0
	v_pk_mul_f32 v[34:35], v[34:35], s[4:5] op_sel_hi:[1,0]
	v_pk_add_f32 v[36:37], v[40:41], 1.0 op_sel_hi:[1,0]
	v_cvt_pk_f16_f32 v34, v34, v35
	v_div_scale_f32 v35, s[0:1], v37, v37, 1.0
	v_rcp_f32_e32 v40, v35
	s_nop 0
	v_fma_f32 v41, -v35, v40, 1.0
	v_fmac_f32_e32 v40, v41, v40
	v_div_scale_f32 v41, vcc, 1.0, v37, 1.0
	v_mul_f32_e32 v42, v41, v40
	v_fma_f32 v43, -v35, v42, v41
	v_fmac_f32_e32 v42, v43, v40
	v_fma_f32 v35, -v35, v42, v41
	v_div_fmas_f32 v35, v35, v40, v42
	v_div_fixup_f32 v37, v35, v37, 1.0
	v_div_scale_f32 v35, s[0:1], v36, v36, 1.0
	v_rcp_f32_e32 v40, v35
	s_nop 0
	v_fma_f32 v41, -v35, v40, 1.0
	v_fmac_f32_e32 v40, v41, v40
	v_div_scale_f32 v41, vcc, 1.0, v36, 1.0
	v_mul_f32_e32 v42, v41, v40
	v_fma_f32 v43, -v35, v42, v41
	v_fmac_f32_e32 v42, v43, v40
	v_fma_f32 v35, -v35, v42, v41
	v_div_fmas_f32 v35, v35, v40, v42
	v_div_fixup_f32 v36, v35, v36, 1.0
	v_pk_mul_f32 v[36:37], v[36:37], s[4:5] op_sel_hi:[1,0]
	s_nop 0
	v_cvt_pk_f16_f32 v35, v36, v37
	v_pk_add_f32 v[36:37], v[44:45], 1.0 op_sel_hi:[1,0]
	s_nop 0
	v_div_scale_f32 v40, s[0:1], v37, v37, 1.0
	v_rcp_f32_e32 v41, v40
	s_nop 0
	v_fma_f32 v42, -v40, v41, 1.0
	v_fmac_f32_e32 v41, v42, v41
	v_div_scale_f32 v42, vcc, 1.0, v37, 1.0
	v_mul_f32_e32 v43, v42, v41
	v_fma_f32 v44, -v40, v43, v42
	v_fmac_f32_e32 v43, v44, v41
	v_fma_f32 v40, -v40, v43, v42
	v_div_fmas_f32 v40, v40, v41, v43
	v_div_fixup_f32 v37, v40, v37, 1.0
	v_div_scale_f32 v40, s[0:1], v36, v36, 1.0
	v_rcp_f32_e32 v41, v40
	s_nop 0
	v_fma_f32 v42, -v40, v41, 1.0
	v_fmac_f32_e32 v41, v42, v41
	v_div_scale_f32 v42, vcc, 1.0, v36, 1.0
	v_mul_f32_e32 v43, v42, v41
	v_fma_f32 v44, -v40, v43, v42
	v_fmac_f32_e32 v43, v44, v41
	v_fma_f32 v40, -v40, v43, v42
	v_div_fmas_f32 v40, v40, v41, v43
	v_div_fixup_f32 v36, v40, v36, 1.0
	v_pk_mul_f32 v[36:37], v[36:37], s[4:5] op_sel_hi:[1,0]
	s_nop 0
	v_cvt_pk_f16_f32 v36, v36, v37
	v_div_scale_f32 v37, s[0:1], v39, v39, 1.0
	v_rcp_f32_e32 v40, v37
	s_nop 0
	v_fma_f32 v41, -v37, v40, 1.0
	v_fmac_f32_e32 v40, v41, v40
	v_div_scale_f32 v41, vcc, 1.0, v39, 1.0
	v_mul_f32_e32 v42, v41, v40
	v_fma_f32 v43, -v37, v42, v41
	v_fmac_f32_e32 v42, v43, v40
	v_fma_f32 v37, -v37, v42, v41
	v_div_fmas_f32 v37, v37, v40, v42
	v_div_fixup_f32 v39, v37, v39, 1.0
	v_div_scale_f32 v37, s[0:1], v38, v38, 1.0
	v_rcp_f32_e32 v40, v37
	s_nop 0
	v_fma_f32 v41, -v37, v40, 1.0
	v_fmac_f32_e32 v40, v41, v40
	v_div_scale_f32 v41, vcc, 1.0, v38, 1.0
	v_mul_f32_e32 v42, v41, v40
	v_fma_f32 v43, -v37, v42, v41
	v_fmac_f32_e32 v42, v43, v40
	v_fma_f32 v37, -v37, v42, v41
	v_div_fmas_f32 v37, v37, v40, v42
	v_div_fixup_f32 v38, v37, v38, 1.0
	v_pk_mul_f32 v[38:39], v[38:39], s[4:5] op_sel_hi:[1,0]
	s_nop 0
	v_cvt_pk_f16_f32 v37, v38, v39
	global_store_dwordx4 v[110:111], v[34:37], off offset:256
	v_pk_add_f32 v[26:27], v[26:27], v[66:67]
	v_pk_add_f32 v[30:31], v[30:31], v[70:71]
	v_mul_f32_e32 v26, 0xbfb8aa3b, v26
	v_exp_f32_e32 v36, v26
	v_mul_f32_e32 v26, 0xbfb8aa3b, v31
	v_pk_add_f32 v[32:33], v[32:33], v[72:73]
	v_mul_f32_e32 v30, 0xbfb8aa3b, v30
	v_exp_f32_e32 v35, v26
	v_mul_f32_e32 v26, 0xbfb8aa3b, v27
	v_pk_add_f32 v[28:29], v[28:29], v[68:69]
	v_exp_f32_e32 v34, v30
	v_exp_f32_e32 v37, v26
	v_mul_f32_e32 v26, 0xbfb8aa3b, v32
	v_exp_f32_e32 v32, v26
	v_mul_f32_e32 v26, 0xbfb8aa3b, v28
	v_exp_f32_e32 v30, v26
	v_mul_f32_e32 v26, 0xbfb8aa3b, v33
	v_exp_f32_e32 v33, v26
	v_mul_f32_e32 v26, 0xbfb8aa3b, v29
	v_exp_f32_e32 v31, v26
	v_pk_add_f32 v[26:27], v[34:35], 1.0 op_sel_hi:[1,0]
	v_pk_add_f32 v[30:31], v[30:31], 1.0 op_sel_hi:[1,0]
	v_div_scale_f32 v28, s[0:1], v27, v27, 1.0
	v_rcp_f32_e32 v29, v28
	s_nop 0
	v_fma_f32 v34, -v28, v29, 1.0
	v_fmac_f32_e32 v29, v34, v29
	v_div_scale_f32 v34, vcc, 1.0, v27, 1.0
	v_mul_f32_e32 v35, v34, v29
	v_fma_f32 v38, -v28, v35, v34
	v_fmac_f32_e32 v35, v38, v29
	v_fma_f32 v28, -v28, v35, v34
	v_div_fmas_f32 v28, v28, v29, v35
	v_div_fixup_f32 v27, v28, v27, 1.0
	v_div_scale_f32 v28, s[0:1], v26, v26, 1.0
	v_rcp_f32_e32 v29, v28
	s_nop 0
	v_fma_f32 v34, -v28, v29, 1.0
	v_fmac_f32_e32 v29, v34, v29
	v_div_scale_f32 v34, vcc, 1.0, v26, 1.0
	v_mul_f32_e32 v35, v34, v29
	v_fma_f32 v38, -v28, v35, v34
	v_fmac_f32_e32 v35, v38, v29
	v_fma_f32 v28, -v28, v35, v34
	v_div_fmas_f32 v28, v28, v29, v35
	v_div_fixup_f32 v26, v28, v26, 1.0
	v_pk_mul_f32 v[26:27], v[26:27], s[4:5] op_sel_hi:[1,0]
	v_pk_add_f32 v[28:29], v[32:33], 1.0 op_sel_hi:[1,0]
	v_cvt_pk_f16_f32 v26, v26, v27
	v_div_scale_f32 v27, s[0:1], v29, v29, 1.0
	v_rcp_f32_e32 v32, v27
	s_nop 0
	v_fma_f32 v33, -v27, v32, 1.0
	v_fmac_f32_e32 v32, v33, v32
	v_div_scale_f32 v33, vcc, 1.0, v29, 1.0
	v_mul_f32_e32 v34, v33, v32
; __device__ __forceinline__ float sigmoidf_(float x) { return 1.0f / (1.0f + __expf(-x)); }
;     template <int GI>
;     __device__ __forceinline__ void body(const f32x4 (&acc)[2][2][4][2], int row0, int colt) const {
; #pragma unroll
;         for (int bj = 0; bj < 2; ++bj) {
;             const int c = colt + bj * 128;
;             f32x4 b0 = (f32x4){0.f, 0.f, 0.f, 0.f}, b1 = b0;
;             if (GI == 0) { b0 = *(const f32x4*)(w0 + c); b1 = *(const f32x4*)(w0 + c + 4); }
;             else if (GI == 1) { b0 = *(const f32x4*)(a0 + c); b1 = *(const f32x4*)(a0 + c + 4); }
;             else if (GI == 3) { b0 = *(const f32x4*)(v0 + c); b1 = *(const f32x4*)(v0 + c + 4); }
; #pragma unroll
;             for (int ai = 0; ai < 2; ++ai)
; #pragma unroll
;                 for (int m = 0; m < 4; ++m) {
;                     const size_t row = (size_t)(row0 + ai * 128 + m * 16);
;                     f32x4 x0 = acc[ai][bj][m][0] + b0, x1 = acc[ai][bj][m][1] + b1;
;                     if (GI == 0) {
; #pragma unroll
;                         for (int j = 0; j < 4; ++j) {
;                             x0[j] = 0.6065306597126334f * sigmoidf_(x0[j]); x1[j] = 0.6065306597126334f * sigmoidf_(x1[j]); }
;                         *(u32x4*)(DEC + row * DM + c) = pack8(x0, x1);
	v_fma_f32 v35, -v27, v34, v33
	v_fmac_f32_e32 v34, v35, v32
	v_fma_f32 v27, -v27, v34, v33
	v_div_fmas_f32 v27, v27, v32, v34
	v_div_fixup_f32 v29, v27, v29, 1.0
	v_div_scale_f32 v27, s[0:1], v28, v28, 1.0
	v_rcp_f32_e32 v32, v27
	s_nop 0
	v_fma_f32 v33, -v27, v32, 1.0
	v_fmac_f32_e32 v32, v33, v32
	v_div_scale_f32 v33, vcc, 1.0, v28, 1.0
	v_mul_f32_e32 v34, v33, v32
	v_fma_f32 v35, -v27, v34, v33
	v_fmac_f32_e32 v34, v35, v32
	v_fma_f32 v27, -v27, v34, v33
	v_div_fmas_f32 v27, v27, v32, v34
	v_div_fixup_f32 v28, v27, v28, 1.0
	v_pk_mul_f32 v[28:29], v[28:29], s[4:5] op_sel_hi:[1,0]
	s_nop 0
	v_cvt_pk_f16_f32 v27, v28, v29
	v_pk_add_f32 v[28:29], v[36:37], 1.0 op_sel_hi:[1,0]
	s_nop 0
	v_div_scale_f32 v32, s[0:1], v29, v29, 1.0
	v_rcp_f32_e32 v33, v32
	s_nop 0
	v_fma_f32 v34, -v32, v33, 1.0
	v_fmac_f32_e32 v33, v34, v33
	v_div_scale_f32 v34, vcc, 1.0, v29, 1.0
	v_mul_f32_e32 v35, v34, v33
	v_fma_f32 v36, -v32, v35, v34
	v_fmac_f32_e32 v35, v36, v33
	v_fma_f32 v32, -v32, v35, v34
	v_div_fmas_f32 v32, v32, v33, v35
	v_div_fixup_f32 v29, v32, v29, 1.0
	v_div_scale_f32 v32, s[0:1], v28, v28, 1.0
	v_rcp_f32_e32 v33, v32
	s_nop 0
	v_fma_f32 v34, -v32, v33, 1.0
	v_fmac_f32_e32 v33, v34, v33
	v_div_scale_f32 v34, vcc, 1.0, v28, 1.0
	v_mul_f32_e32 v35, v34, v33
	v_fma_f32 v36, -v32, v35, v34
	v_fmac_f32_e32 v35, v36, v33
	v_fma_f32 v32, -v32, v35, v34
	v_div_fmas_f32 v32, v32, v33, v35
	v_div_fixup_f32 v28, v32, v28, 1.0
	v_pk_mul_f32 v[28:29], v[28:29], s[4:5] op_sel_hi:[1,0]
	s_nop 0
	v_cvt_pk_f16_f32 v28, v28, v29
	v_div_scale_f32 v29, s[0:1], v31, v31, 1.0
	v_rcp_f32_e32 v32, v29
	s_nop 0
	v_fma_f32 v33, -v29, v32, 1.0
	v_fmac_f32_e32 v32, v33, v32
	v_div_scale_f32 v33, vcc, 1.0, v31, 1.0
	v_mul_f32_e32 v34, v33, v32
	v_fma_f32 v35, -v29, v34, v33
	v_fmac_f32_e32 v34, v35, v32
	v_fma_f32 v29, -v29, v34, v33
	v_div_fmas_f32 v29, v29, v32, v34
	v_div_fixup_f32 v31, v29, v31, 1.0
	v_div_scale_f32 v29, s[0:1], v30, v30, 1.0
	v_rcp_f32_e32 v32, v29
	s_nop 0
	v_fma_f32 v33, -v29, v32, 1.0
	v_fmac_f32_e32 v32, v33, v32
	v_div_scale_f32 v33, vcc, 1.0, v30, 1.0
	v_mul_f32_e32 v34, v33, v32
	v_fma_f32 v35, -v29, v34, v33
	v_fmac_f32_e32 v34, v35, v32
	v_fma_f32 v29, -v29, v34, v33
	v_div_fmas_f32 v29, v29, v32, v34
	v_div_fixup_f32 v30, v29, v30, 1.0
	v_pk_mul_f32 v[30:31], v[30:31], s[4:5] op_sel_hi:[1,0]
	s_nop 0
	v_cvt_pk_f16_f32 v29, v30, v31
	global_store_dwordx4 v[102:103], v[26:29], off offset:256
	v_pk_add_f32 v[18:19], v[18:19], v[66:67]
	v_pk_add_f32 v[22:23], v[22:23], v[70:71]
	v_mul_f32_e32 v18, 0xbfb8aa3b, v18
	v_exp_f32_e32 v28, v18
	v_mul_f32_e32 v18, 0xbfb8aa3b, v23
	v_pk_add_f32 v[24:25], v[24:25], v[72:73]
	v_mul_f32_e32 v22, 0xbfb8aa3b, v22
	v_exp_f32_e32 v27, v18
	v_mul_f32_e32 v18, 0xbfb8aa3b, v19
	v_pk_add_f32 v[20:21], v[20:21], v[68:69]
	v_exp_f32_e32 v26, v22
	v_exp_f32_e32 v29, v18
	v_mul_f32_e32 v18, 0xbfb8aa3b, v24
	v_exp_f32_e32 v24, v18
	v_mul_f32_e32 v18, 0xbfb8aa3b, v20
	v_exp_f32_e32 v22, v18
	v_mul_f32_e32 v18, 0xbfb8aa3b, v25
	v_exp_f32_e32 v25, v18
	v_mul_f32_e32 v18, 0xbfb8aa3b, v21
	v_exp_f32_e32 v23, v18
	v_pk_add_f32 v[18:19], v[26:27], 1.0 op_sel_hi:[1,0]
	v_pk_add_f32 v[22:23], v[22:23], 1.0 op_sel_hi:[1,0]
	v_div_scale_f32 v20, s[0:1], v19, v19, 1.0
	v_rcp_f32_e32 v21, v20
	s_nop 0
	v_fma_f32 v26, -v20, v21, 1.0
	v_fmac_f32_e32 v21, v26, v21
	v_div_scale_f32 v26, vcc, 1.0, v19, 1.0
	v_mul_f32_e32 v27, v26, v21
	v_fma_f32 v30, -v20, v27, v26
	v_fmac_f32_e32 v27, v30, v21
	v_fma_f32 v20, -v20, v27, v26
	v_div_fmas_f32 v20, v20, v21, v27
	v_div_fixup_f32 v19, v20, v19, 1.0
	v_div_scale_f32 v20, s[0:1], v18, v18, 1.0
	v_rcp_f32_e32 v21, v20
	s_nop 0
	v_fma_f32 v26, -v20, v21, 1.0
	v_fmac_f32_e32 v21, v26, v21
	v_div_scale_f32 v26, vcc, 1.0, v18, 1.0
	v_mul_f32_e32 v27, v26, v21
	v_fma_f32 v30, -v20, v27, v26
	v_fmac_f32_e32 v27, v30, v21
	v_fma_f32 v20, -v20, v27, v26
	v_div_fmas_f32 v20, v20, v21, v27
	v_div_fixup_f32 v18, v20, v18, 1.0
	v_pk_mul_f32 v[18:19], v[18:19], s[4:5] op_sel_hi:[1,0]
	v_pk_add_f32 v[20:21], v[24:25], 1.0 op_sel_hi:[1,0]
	v_cvt_pk_f16_f32 v18, v18, v19
	v_div_scale_f32 v19, s[0:1], v21, v21, 1.0
	v_rcp_f32_e32 v24, v19
	s_nop 0
	v_fma_f32 v25, -v19, v24, 1.0
	v_fmac_f32_e32 v24, v25, v24
	v_div_scale_f32 v25, vcc, 1.0, v21, 1.0
	v_mul_f32_e32 v26, v25, v24
	v_fma_f32 v27, -v19, v26, v25
	v_fmac_f32_e32 v26, v27, v24
	v_fma_f32 v19, -v19, v26, v25
	v_div_fmas_f32 v19, v19, v24, v26
	v_div_fixup_f32 v21, v19, v21, 1.0
	v_div_scale_f32 v19, s[0:1], v20, v20, 1.0
	v_rcp_f32_e32 v24, v19
	s_nop 0
	v_fma_f32 v25, -v19, v24, 1.0
	v_fmac_f32_e32 v24, v25, v24
	v_div_scale_f32 v25, vcc, 1.0, v20, 1.0
	v_mul_f32_e32 v26, v25, v24
	v_fma_f32 v27, -v19, v26, v25
	v_fmac_f32_e32 v26, v27, v24
	v_fma_f32 v19, -v19, v26, v25
	v_div_fmas_f32 v19, v19, v24, v26
	v_div_fixup_f32 v20, v19, v20, 1.0
	v_pk_mul_f32 v[20:21], v[20:21], s[4:5] op_sel_hi:[1,0]
	s_nop 0
	v_cvt_pk_f16_f32 v19, v20, v21
	v_pk_add_f32 v[20:21], v[28:29], 1.0 op_sel_hi:[1,0]
	s_nop 0
	v_div_scale_f32 v24, s[0:1], v21, v21, 1.0
	v_rcp_f32_e32 v25, v24
	s_nop 0
	v_fma_f32 v26, -v24, v25, 1.0
	v_fmac_f32_e32 v25, v26, v25
	v_div_scale_f32 v26, vcc, 1.0, v21, 1.0
	v_mul_f32_e32 v27, v26, v25
	v_fma_f32 v28, -v24, v27, v26
	v_fmac_f32_e32 v27, v28, v25
	v_fma_f32 v24, -v24, v27, v26
	v_div_fmas_f32 v24, v24, v25, v27
	v_div_fixup_f32 v21, v24, v21, 1.0
	v_div_scale_f32 v24, s[0:1], v20, v20, 1.0
	v_rcp_f32_e32 v25, v24
	s_nop 0
	v_fma_f32 v26, -v24, v25, 1.0
	v_fmac_f32_e32 v25, v26, v25
	v_div_scale_f32 v26, vcc, 1.0, v20, 1.0
	v_mul_f32_e32 v27, v26, v25
	v_fma_f32 v28, -v24, v27, v26
	v_fmac_f32_e32 v27, v28, v25
	v_fma_f32 v24, -v24, v27, v26
; __device__ __forceinline__ float sigmoidf_(float x) { return 1.0f / (1.0f + __expf(-x)); }
;     template <int GI>
;     __device__ __forceinline__ void body(const f32x4 (&acc)[2][2][4][2], int row0, int colt) const {
; #pragma unroll
;         for (int bj = 0; bj < 2; ++bj) {
;             const int c = colt + bj * 128;
;             f32x4 b0 = (f32x4){0.f, 0.f, 0.f, 0.f}, b1 = b0;
;             if (GI == 0) { b0 = *(const f32x4*)(w0 + c); b1 = *(const f32x4*)(w0 + c + 4); }
;             else if (GI == 1) { b0 = *(const f32x4*)(a0 + c); b1 = *(const f32x4*)(a0 + c + 4); }
;             else if (GI == 3) { b0 = *(const f32x4*)(v0 + c); b1 = *(const f32x4*)(v0 + c + 4); }
; #pragma unroll
;             for (int ai = 0; ai < 2; ++ai)
; #pragma unroll
;                 for (int m = 0; m < 4; ++m) {
;                     const size_t row = (size_t)(row0 + ai * 128 + m * 16);
;                     f32x4 x0 = acc[ai][bj][m][0] + b0, x1 = acc[ai][bj][m][1] + b1;
;                     if (GI == 0) {
; #pragma unroll
;                         for (int j = 0; j < 4; ++j) {
;                             x0[j] = 0.6065306597126334f * sigmoidf_(x0[j]); x1[j] = 0.6065306597126334f * sigmoidf_(x1[j]); }
;                         *(u32x4*)(DEC + row * DM + c) = pack8(x0, x1);
	v_div_fmas_f32 v24, v24, v25, v27
	v_div_fixup_f32 v20, v24, v20, 1.0
	v_pk_mul_f32 v[20:21], v[20:21], s[4:5] op_sel_hi:[1,0]
	s_nop 0
	v_cvt_pk_f16_f32 v20, v20, v21
	v_div_scale_f32 v21, s[0:1], v23, v23, 1.0
	v_rcp_f32_e32 v24, v21
	s_nop 0
	v_fma_f32 v25, -v21, v24, 1.0
	v_fmac_f32_e32 v24, v25, v24
	v_div_scale_f32 v25, vcc, 1.0, v23, 1.0
	v_mul_f32_e32 v26, v25, v24
	v_fma_f32 v27, -v21, v26, v25
	v_fmac_f32_e32 v26, v27, v24
	v_fma_f32 v21, -v21, v26, v25
	v_div_fmas_f32 v21, v21, v24, v26
	v_div_fixup_f32 v23, v21, v23, 1.0
	v_div_scale_f32 v21, s[0:1], v22, v22, 1.0
	v_rcp_f32_e32 v24, v21
	s_nop 0
	v_fma_f32 v25, -v21, v24, 1.0
	v_fmac_f32_e32 v24, v25, v24
	v_div_scale_f32 v25, vcc, 1.0, v22, 1.0
	v_mul_f32_e32 v26, v25, v24
	v_fma_f32 v27, -v21, v26, v25
	v_fmac_f32_e32 v26, v27, v24
	v_fma_f32 v21, -v21, v26, v25
	v_div_fmas_f32 v21, v21, v24, v26
	v_div_fixup_f32 v22, v21, v22, 1.0
	v_pk_mul_f32 v[22:23], v[22:23], s[4:5] op_sel_hi:[1,0]
	s_nop 0
	v_cvt_pk_f16_f32 v21, v22, v23
	global_store_dwordx4 v[86:87], v[18:21], off offset:256
	v_pk_add_f32 v[10:11], v[10:11], v[66:67]
	v_pk_add_f32 v[14:15], v[14:15], v[70:71]
	v_mul_f32_e32 v10, 0xbfb8aa3b, v10
	v_exp_f32_e32 v20, v10
	v_mul_f32_e32 v10, 0xbfb8aa3b, v15
	v_pk_add_f32 v[16:17], v[16:17], v[72:73]
	v_mul_f32_e32 v14, 0xbfb8aa3b, v14
	v_exp_f32_e32 v19, v10
	v_mul_f32_e32 v10, 0xbfb8aa3b, v11
	v_pk_add_f32 v[12:13], v[12:13], v[68:69]
	v_exp_f32_e32 v18, v14
	v_exp_f32_e32 v21, v10
	v_mul_f32_e32 v10, 0xbfb8aa3b, v16
	v_exp_f32_e32 v16, v10
	v_mul_f32_e32 v10, 0xbfb8aa3b, v12
	v_exp_f32_e32 v14, v10
	v_mul_f32_e32 v10, 0xbfb8aa3b, v17
	v_exp_f32_e32 v17, v10
	v_mul_f32_e32 v10, 0xbfb8aa3b, v13
	v_exp_f32_e32 v15, v10
	v_pk_add_f32 v[10:11], v[18:19], 1.0 op_sel_hi:[1,0]
	v_pk_add_f32 v[14:15], v[14:15], 1.0 op_sel_hi:[1,0]
	v_div_scale_f32 v12, s[0:1], v11, v11, 1.0
	v_rcp_f32_e32 v13, v12
	s_nop 0
	v_fma_f32 v18, -v12, v13, 1.0
	v_fmac_f32_e32 v13, v18, v13
	v_div_scale_f32 v18, vcc, 1.0, v11, 1.0
	v_mul_f32_e32 v19, v18, v13
	v_fma_f32 v22, -v12, v19, v18
	v_fmac_f32_e32 v19, v22, v13
	v_fma_f32 v12, -v12, v19, v18
	v_div_fmas_f32 v12, v12, v13, v19
	v_div_fixup_f32 v11, v12, v11, 1.0
	v_div_scale_f32 v12, s[0:1], v10, v10, 1.0
	v_rcp_f32_e32 v13, v12
	s_nop 0
	v_fma_f32 v18, -v12, v13, 1.0
	v_fmac_f32_e32 v13, v18, v13
	v_div_scale_f32 v18, vcc, 1.0, v10, 1.0
	v_mul_f32_e32 v19, v18, v13
	v_fma_f32 v22, -v12, v19, v18
	v_fmac_f32_e32 v19, v22, v13
	v_fma_f32 v12, -v12, v19, v18
	v_div_fmas_f32 v12, v12, v13, v19
	v_div_fixup_f32 v10, v12, v10, 1.0
	v_pk_mul_f32 v[10:11], v[10:11], s[4:5] op_sel_hi:[1,0]
	v_pk_add_f32 v[12:13], v[16:17], 1.0 op_sel_hi:[1,0]
	v_cvt_pk_f16_f32 v10, v10, v11
	v_div_scale_f32 v11, s[0:1], v13, v13, 1.0
	v_rcp_f32_e32 v16, v11
	s_nop 0
	v_fma_f32 v17, -v11, v16, 1.0
	v_fmac_f32_e32 v16, v17, v16
	v_div_scale_f32 v17, vcc, 1.0, v13, 1.0
	v_mul_f32_e32 v18, v17, v16
	v_fma_f32 v19, -v11, v18, v17
	v_fmac_f32_e32 v18, v19, v16
	v_fma_f32 v11, -v11, v18, v17
	v_div_fmas_f32 v11, v11, v16, v18
	v_div_fixup_f32 v13, v11, v13, 1.0
	v_div_scale_f32 v11, s[0:1], v12, v12, 1.0
	v_rcp_f32_e32 v16, v11
	s_nop 0
	v_fma_f32 v17, -v11, v16, 1.0
	v_fmac_f32_e32 v16, v17, v16
	v_div_scale_f32 v17, vcc, 1.0, v12, 1.0
	v_mul_f32_e32 v18, v17, v16
	v_fma_f32 v19, -v11, v18, v17
	v_fmac_f32_e32 v18, v19, v16
	v_fma_f32 v11, -v11, v18, v17
	v_div_fmas_f32 v11, v11, v16, v18
	v_div_fixup_f32 v12, v11, v12, 1.0
	v_pk_mul_f32 v[12:13], v[12:13], s[4:5] op_sel_hi:[1,0]
	s_nop 0
	v_cvt_pk_f16_f32 v11, v12, v13
	v_pk_add_f32 v[12:13], v[20:21], 1.0 op_sel_hi:[1,0]
	s_nop 0
	v_div_scale_f32 v16, s[0:1], v13, v13, 1.0
	v_rcp_f32_e32 v17, v16
	s_nop 0
	v_fma_f32 v18, -v16, v17, 1.0
	v_fmac_f32_e32 v17, v18, v17
	v_div_scale_f32 v18, vcc, 1.0, v13, 1.0
	v_mul_f32_e32 v19, v18, v17
	v_fma_f32 v20, -v16, v19, v18
	v_fmac_f32_e32 v19, v20, v17
	v_fma_f32 v16, -v16, v19, v18
	v_div_fmas_f32 v16, v16, v17, v19
	v_div_fixup_f32 v13, v16, v13, 1.0
	v_div_scale_f32 v16, s[0:1], v12, v12, 1.0
	v_rcp_f32_e32 v17, v16
	s_nop 0
	v_fma_f32 v18, -v16, v17, 1.0
	v_fmac_f32_e32 v17, v18, v17
	v_div_scale_f32 v18, vcc, 1.0, v12, 1.0
	v_mul_f32_e32 v19, v18, v17
	v_fma_f32 v20, -v16, v19, v18
	v_fmac_f32_e32 v19, v20, v17
	v_fma_f32 v16, -v16, v19, v18
	v_div_fmas_f32 v16, v16, v17, v19
	v_div_fixup_f32 v12, v16, v12, 1.0
	v_pk_mul_f32 v[12:13], v[12:13], s[4:5] op_sel_hi:[1,0]
	s_nop 0
	v_cvt_pk_f16_f32 v12, v12, v13
	v_div_scale_f32 v13, s[0:1], v15, v15, 1.0
	v_rcp_f32_e32 v16, v13
	s_nop 0
	v_fma_f32 v17, -v13, v16, 1.0
	v_fmac_f32_e32 v16, v17, v16
	v_div_scale_f32 v17, vcc, 1.0, v15, 1.0
	v_mul_f32_e32 v18, v17, v16
	v_fma_f32 v19, -v13, v18, v17
	v_fmac_f32_e32 v18, v19, v16
	v_fma_f32 v13, -v13, v18, v17
; __device__ __forceinline__ float sigmoidf_(float x) { return 1.0f / (1.0f + __expf(-x)); }
; template <class Epi, class AMap>
; __device__ __forceinline__ void gemm_phase(LAS unsigned char* lds, const AMap am, const int lda, const h16* Bt, const int ldb, const int M, const int N, const int K, const Epi& E) {
;     ...
;         E(acc, cur, wr, wc, fr, fq);
;         if (!has_next) break;
; #pragma unroll
;         for (int a = 0; a < 2; ++a)
; #pragma unroll
;             for (int b = 0; b < 2; ++b)
; #pragma unroll
;                 for (int m = 0; m < 4; ++m)
; #pragma unroll
;                     for (int n = 0; n < 2; ++n) acc[a][b][m][n] = (f32x4){0.f, 0.f, 0.f, 0.f};
;         cur = nxt; cA = nA; cB = nB; ++ui;
;     template <int GI>
;     __device__ __forceinline__ void body(const f32x4 (&acc)[2][2][4][2], int row0, int colt) const {
;     ...
;                     if (GI == 0) {
; #pragma unroll
;                         for (int j = 0; j < 4; ++j) {
;                             x0[j] = 0.6065306597126334f * sigmoidf_(x0[j]); x1[j] = 0.6065306597126334f * sigmoidf_(x1[j]); }
;                         *(u32x4*)(DEC + row * DM + c) = pack8(x0, x1);
	v_div_fmas_f32 v13, v13, v16, v18
	v_div_fixup_f32 v15, v13, v15, 1.0
	v_div_scale_f32 v13, s[0:1], v14, v14, 1.0
	v_rcp_f32_e32 v16, v13
	s_nop 0
	v_fma_f32 v17, -v13, v16, 1.0
	v_fmac_f32_e32 v16, v17, v16
	v_div_scale_f32 v17, vcc, 1.0, v14, 1.0
	v_mul_f32_e32 v18, v17, v16
	v_fma_f32 v19, -v13, v18, v17
	v_fmac_f32_e32 v18, v19, v16
	v_fma_f32 v13, -v13, v18, v17
	v_div_fmas_f32 v13, v13, v16, v18
	v_div_fixup_f32 v14, v13, v14, 1.0
	v_pk_mul_f32 v[14:15], v[14:15], s[4:5] op_sel_hi:[1,0]
	s_nop 0
	v_cvt_pk_f16_f32 v13, v14, v15
	global_store_dwordx4 v[78:79], v[10:13], off offset:256
	v_pk_add_f32 v[2:3], v[2:3], v[66:67]
	v_pk_add_f32 v[6:7], v[6:7], v[70:71]
	v_mul_f32_e32 v2, 0xbfb8aa3b, v2
	v_exp_f32_e32 v12, v2
	v_mul_f32_e32 v2, 0xbfb8aa3b, v7
	v_pk_add_f32 v[8:9], v[8:9], v[72:73]
	v_mul_f32_e32 v6, 0xbfb8aa3b, v6
	v_exp_f32_e32 v11, v2
	v_mul_f32_e32 v2, 0xbfb8aa3b, v3
	v_pk_add_f32 v[4:5], v[4:5], v[68:69]
	v_exp_f32_e32 v10, v6
	v_exp_f32_e32 v13, v2
	v_mul_f32_e32 v2, 0xbfb8aa3b, v8
	v_exp_f32_e32 v8, v2
	v_mul_f32_e32 v2, 0xbfb8aa3b, v4
	v_exp_f32_e32 v6, v2
	v_mul_f32_e32 v2, 0xbfb8aa3b, v9
	v_exp_f32_e32 v9, v2
	v_mul_f32_e32 v2, 0xbfb8aa3b, v5
	v_exp_f32_e32 v7, v2
	v_pk_add_f32 v[2:3], v[10:11], 1.0 op_sel_hi:[1,0]
	v_pk_add_f32 v[6:7], v[6:7], 1.0 op_sel_hi:[1,0]
	v_div_scale_f32 v4, s[0:1], v3, v3, 1.0
	v_rcp_f32_e32 v5, v4
	s_nop 0
	v_fma_f32 v10, -v4, v5, 1.0
	v_fmac_f32_e32 v5, v10, v5
	v_div_scale_f32 v10, vcc, 1.0, v3, 1.0
	v_mul_f32_e32 v11, v10, v5
	v_fma_f32 v14, -v4, v11, v10
	v_fmac_f32_e32 v11, v14, v5
	v_fma_f32 v4, -v4, v11, v10
	v_div_fmas_f32 v4, v4, v5, v11
	v_div_fixup_f32 v3, v4, v3, 1.0
	v_div_scale_f32 v4, s[0:1], v2, v2, 1.0
	v_rcp_f32_e32 v5, v4
	s_nop 0
	v_fma_f32 v10, -v4, v5, 1.0
	v_fmac_f32_e32 v5, v10, v5
	v_div_scale_f32 v10, vcc, 1.0, v2, 1.0
	v_mul_f32_e32 v11, v10, v5
	v_fma_f32 v14, -v4, v11, v10
	v_fmac_f32_e32 v11, v14, v5
	v_fma_f32 v4, -v4, v11, v10
	v_div_fmas_f32 v4, v4, v5, v11
	v_div_fixup_f32 v2, v4, v2, 1.0
	v_pk_mul_f32 v[2:3], v[2:3], s[4:5] op_sel_hi:[1,0]
	v_pk_add_f32 v[4:5], v[8:9], 1.0 op_sel_hi:[1,0]
	v_cvt_pk_f16_f32 v2, v2, v3
	v_div_scale_f32 v3, s[0:1], v5, v5, 1.0
	v_rcp_f32_e32 v8, v3
	s_nop 0
	v_fma_f32 v9, -v3, v8, 1.0
	v_fmac_f32_e32 v8, v9, v8
	v_div_scale_f32 v9, vcc, 1.0, v5, 1.0
	v_mul_f32_e32 v10, v9, v8
	v_fma_f32 v11, -v3, v10, v9
	v_fmac_f32_e32 v10, v11, v8
	v_fma_f32 v3, -v3, v10, v9
	v_div_fmas_f32 v3, v3, v8, v10
	v_div_fixup_f32 v5, v3, v5, 1.0
	v_div_scale_f32 v3, s[0:1], v4, v4, 1.0
	v_rcp_f32_e32 v8, v3
	s_nop 0
	v_fma_f32 v9, -v3, v8, 1.0
	v_fmac_f32_e32 v8, v9, v8
	v_div_scale_f32 v9, vcc, 1.0, v4, 1.0
	v_mul_f32_e32 v10, v9, v8
	v_fma_f32 v11, -v3, v10, v9
	v_fmac_f32_e32 v10, v11, v8
	v_fma_f32 v3, -v3, v10, v9
	v_div_fmas_f32 v3, v3, v8, v10
	v_div_fixup_f32 v4, v3, v4, 1.0
	v_pk_mul_f32 v[4:5], v[4:5], s[4:5] op_sel_hi:[1,0]
	s_nop 0
	v_cvt_pk_f16_f32 v3, v4, v5
	v_pk_add_f32 v[4:5], v[12:13], 1.0 op_sel_hi:[1,0]
	s_nop 0
	v_div_scale_f32 v8, s[0:1], v5, v5, 1.0
	v_rcp_f32_e32 v9, v8
	s_nop 0
	v_fma_f32 v10, -v8, v9, 1.0
	v_fmac_f32_e32 v9, v10, v9
	v_div_scale_f32 v10, vcc, 1.0, v5, 1.0
	v_mul_f32_e32 v11, v10, v9
	v_fma_f32 v12, -v8, v11, v10
	v_fmac_f32_e32 v11, v12, v9
	v_fma_f32 v8, -v8, v11, v10
	v_div_fmas_f32 v8, v8, v9, v11
	v_div_fixup_f32 v5, v8, v5, 1.0
	v_div_scale_f32 v8, s[0:1], v4, v4, 1.0
	v_rcp_f32_e32 v9, v8
	s_nop 0
	v_fma_f32 v10, -v8, v9, 1.0
	v_fmac_f32_e32 v9, v10, v9
	v_div_scale_f32 v10, vcc, 1.0, v4, 1.0
	v_mul_f32_e32 v11, v10, v9
	v_fma_f32 v12, -v8, v11, v10
	v_fmac_f32_e32 v11, v12, v9
	v_fma_f32 v8, -v8, v11, v10
	v_div_fmas_f32 v8, v8, v9, v11
	v_div_fixup_f32 v4, v8, v4, 1.0
	v_pk_mul_f32 v[4:5], v[4:5], s[4:5] op_sel_hi:[1,0]
	s_nop 0
	v_cvt_pk_f16_f32 v4, v4, v5
	v_div_scale_f32 v5, s[0:1], v7, v7, 1.0
	v_rcp_f32_e32 v8, v5
	s_nop 0
	v_fma_f32 v9, -v5, v8, 1.0
	v_fmac_f32_e32 v8, v9, v8
	v_div_scale_f32 v9, vcc, 1.0, v7, 1.0
	v_mul_f32_e32 v10, v9, v8
	v_fma_f32 v11, -v5, v10, v9
	v_fmac_f32_e32 v10, v11, v8
	v_fma_f32 v5, -v5, v10, v9
	v_div_fmas_f32 v5, v5, v8, v10
	v_div_fixup_f32 v7, v5, v7, 1.0
	v_div_scale_f32 v5, s[0:1], v6, v6, 1.0
	v_rcp_f32_e32 v8, v5
	s_nop 0
	v_fma_f32 v9, -v5, v8, 1.0
	v_fmac_f32_e32 v8, v9, v8
	v_div_scale_f32 v9, vcc, 1.0, v6, 1.0
	v_mul_f32_e32 v10, v9, v8
	v_fma_f32 v11, -v5, v10, v9
	v_fmac_f32_e32 v10, v11, v8
	v_fma_f32 v5, -v5, v10, v9
	v_div_fmas_f32 v5, v5, v8, v10
	v_div_fixup_f32 v6, v5, v6, 1.0
	v_pk_mul_f32 v[6:7], v[6:7], s[4:5] op_sel_hi:[1,0]
	s_nop 0
	v_cvt_pk_f16_f32 v5, v6, v7
	global_store_dwordx4 v[74:75], v[2:5], off offset:256
	s_and_b64 vcc, exec, s[38:39]
	s_mov_b32 s50, s44
	s_mov_b32 s35, s96
	s_mov_b64 s[26:27], s[68:69]
	s_mov_b64 s[22:23], s[64:65]
	s_cbranch_vccnz .LBB0_622

; #define PG8_STAGE(bufoff, gbase, voff) do { _Pragma("unroll") for (int _i = 0; _i < 2; ++_i) \
;         __builtin_amdgcn_global_load_lds((const unsigned*)((const char*)(gbase) + (voff)[_i]), (LAS unsigned*)(lds + (bufoff) + ldsw + _i * 8192), 16, 0, 0); } while (0)
; #define PG8_LDA(dst, b, h) do { _Pragma("unroll") for (int m = 0; m < 4; ++m) _Pragma("unroll") for (int k = 0; k < 2; ++k) dst[m][k] = *(const LAS h16x8*)(lds + PG8_SA(b, h) + aoff + m * 2048 + k * 1024); } while (0)
; #define PG8_LDB(dst, b, h) do { _Pragma("unroll") for (int n = 0; n < 2; ++n) _Pragma("unroll") for (int k = 0; k < 2; ++k) dst[n][k] = *(const LAS h16x8*)(lds + PG8_SB(b, h) + boff + n * 2048 + k * 1024); } while (0)
; #define PG8_WAIT_L(n) asm volatile("s_waitcnt lgkmcnt(" #n ")" ::: "memory")
; #define PG8_BAR __builtin_amdgcn_s_barrier()
; #define PG8_SCHED __builtin_amdgcn_sched_barrier(0)
; template <class Epi, class AMap>
; __device__ __forceinline__ void gemm_phase(LAS unsigned char* lds, const AMap am, const int lda, const h16* Bt, const int ldb, const int M, const int N, const int K, const Epi& E) {
;     ...
;         const bool has_next = S.next(ui + 1, nxt);
;         const char* nA = has_next ? am(nxt.pn) + (size_t)nxt.pm * tstepA : cA; const char* nB = has_next ? (const char*)Bt + (size_t)nxt.pn * tstepB : cB;
; #pragma unroll 1
;         for (int t = 0; t < nt; t += 2) {
;             const bool last = (t == nt - 2);
;             const char* a1 = cA + (size_t)(t + 1) * kstep;
;             const char* a2 = last ? nA : cA + (size_t)(t + 2) * kstep; const char* b2 = last ? nB : cB + (size_t)(t + 2) * kstep;
;             const char* a3 = a2 + kstep; const char* b3 = b2 + kstep;
;             PG8_LDB(B0, 0, 0); PG8_SCHED; PG8_LDA(At, 0, 0); PG8_STAGE(PG8_SA(1, 1), a1 + hstepA, voffA);
;             PG8_WAIT_L(8); PG8_BAR; PG8_WAIT_L(0); PG8_MMA(0, 0, At, B0); PG8_BAR; PG8_SCHED;
;     ...
; #pragma unroll
;         for (int a = 0; a < 2; ++a)
; #pragma unroll
;             for (int b = 0; b < 2; ++b)
; #pragma unroll
;                 for (int m = 0; m < 4; ++m)
; #pragma unroll
;                     for (int n = 0; n < 2; ++n) acc[a][b][m][n] = (f32x4){0.f, 0.f, 0.f, 0.f};
;         cur = nxt; cA = nA; cB = nB; ++ui;
.LBB0_619:
	s_ashr_i32 s45, s44, 31
	s_lshl_b64 s[20:21], s[44:45], 17
	s_add_u32 s68, s74, s20
	v_mov_b32_e32 v133, 0
	s_addc_u32 s69, s75, s21
	s_andn2_b64 vcc, exec, s[42:43]
	v_mov_b32_e32 v132, v133
	v_mov_b32_e32 v131, v133
	v_mov_b32_e32 v130, v133
	v_mov_b32_e32 v137, v133
	v_mov_b32_e32 v136, v133
	v_mov_b32_e32 v135, v133
	v_mov_b32_e32 v134, v133
	v_mov_b32_e32 v129, v133
	v_mov_b32_e32 v128, v133
	v_mov_b32_e32 v127, v133
	v_mov_b32_e32 v126, v133
	v_mov_b32_e32 v125, v133
	v_mov_b32_e32 v124, v133
	v_mov_b32_e32 v123, v133
	v_mov_b32_e32 v122, v133
	v_mov_b32_e32 v121, v133
	v_mov_b32_e32 v120, v133
	v_mov_b32_e32 v119, v133
	v_mov_b32_e32 v118, v133
	v_mov_b32_e32 v117, v133
	v_mov_b32_e32 v116, v133
	v_mov_b32_e32 v115, v133
	v_mov_b32_e32 v114, v133
	v_mov_b32_e32 v113, v133
	v_mov_b32_e32 v112, v133
	v_mov_b32_e32 v111, v133
	v_mov_b32_e32 v110, v133
	v_mov_b32_e32 v109, v133
	v_mov_b32_e32 v108, v133
	v_mov_b32_e32 v107, v133
	v_mov_b32_e32 v106, v133
	v_mov_b32_e32 v65, v133
	v_mov_b32_e32 v64, v133
	v_mov_b32_e32 v63, v133
	v_mov_b32_e32 v62, v133
	v_mov_b32_e32 v61, v133
	v_mov_b32_e32 v60, v133
	v_mov_b32_e32 v59, v133
	v_mov_b32_e32 v58, v133
	v_mov_b32_e32 v57, v133
	v_mov_b32_e32 v56, v133
	v_mov_b32_e32 v55, v133
	v_mov_b32_e32 v54, v133
	v_mov_b32_e32 v53, v133
	v_mov_b32_e32 v52, v133
	v_mov_b32_e32 v51, v133
	v_mov_b32_e32 v50, v133
	v_mov_b32_e32 v49, v133
	v_mov_b32_e32 v48, v133
	v_mov_b32_e32 v47, v133
	v_mov_b32_e32 v46, v133
	v_mov_b32_e32 v45, v133
	v_mov_b32_e32 v44, v133
	v_mov_b32_e32 v43, v133
	v_mov_b32_e32 v42, v133
	v_mov_b32_e32 v41, v133
	v_mov_b32_e32 v40, v133
	v_mov_b32_e32 v39, v133
	v_mov_b32_e32 v38, v133
	v_mov_b32_e32 v37, v133
	v_mov_b32_e32 v36, v133
	v_mov_b32_e32 v35, v133
	v_mov_b32_e32 v34, v133
	v_mov_b32_e32 v105, v133
	v_mov_b32_e32 v104, v133
	v_mov_b32_e32 v103, v133
	v_mov_b32_e32 v102, v133
	v_mov_b32_e32 v101, v133
	v_mov_b32_e32 v100, v133
	v_mov_b32_e32 v99, v133
	v_mov_b32_e32 v98, v133
	v_mov_b32_e32 v89, v133
	v_mov_b32_e32 v88, v133
	v_mov_b32_e32 v87, v133
	v_mov_b32_e32 v86, v133
	v_mov_b32_e32 v85, v133
	v_mov_b32_e32 v84, v133
	v_mov_b32_e32 v83, v133
	v_mov_b32_e32 v82, v133
	v_mov_b32_e32 v81, v133
	v_mov_b32_e32 v80, v133
	v_mov_b32_e32 v79, v133
	v_mov_b32_e32 v78, v133
	v_mov_b32_e32 v77, v133
	v_mov_b32_e32 v76, v133
	v_mov_b32_e32 v75, v133
	v_mov_b32_e32 v74, v133
	v_mov_b32_e32 v73, v133
	v_mov_b32_e32 v72, v133
	v_mov_b32_e32 v71, v133
	v_mov_b32_e32 v70, v133
	v_mov_b32_e32 v69, v133
	v_mov_b32_e32 v68, v133
	v_mov_b32_e32 v67, v133
	v_mov_b32_e32 v66, v133
	v_mov_b32_e32 v33, v133
	v_mov_b32_e32 v32, v133
	v_mov_b32_e32 v31, v133
	v_mov_b32_e32 v30, v133
	v_mov_b32_e32 v29, v133
	v_mov_b32_e32 v28, v133
	v_mov_b32_e32 v27, v133
	v_mov_b32_e32 v26, v133
	v_mov_b32_e32 v25, v133
	v_mov_b32_e32 v24, v133
	v_mov_b32_e32 v23, v133
	v_mov_b32_e32 v22, v133
	v_mov_b32_e32 v21, v133
	v_mov_b32_e32 v20, v133
	v_mov_b32_e32 v19, v133
	v_mov_b32_e32 v18, v133
	v_mov_b32_e32 v17, v133
	v_mov_b32_e32 v16, v133
	v_mov_b32_e32 v15, v133
	v_mov_b32_e32 v14, v133
	v_mov_b32_e32 v13, v133
	v_mov_b32_e32 v12, v133
	v_mov_b32_e32 v11, v133
	v_mov_b32_e32 v10, v133
	v_mov_b32_e32 v9, v133
	v_mov_b32_e32 v8, v133
	v_mov_b32_e32 v7, v133
	v_mov_b32_e32 v6, v133
	v_mov_b32_e32 v5, v133
	v_mov_b32_e32 v4, v133
	v_mov_b32_e32 v3, v133
	v_mov_b32_e32 v2, v133
	s_cbranch_vccnz .LBB0_610
	s_and_b64 s[0:1], s[0:1], exec
	s_cselect_b32 s20, s69, s27
	s_cselect_b32 s21, s68, s26
	s_add_u32 s29, s26, 0x100
	s_addc_u32 s45, s27, 0
	s_mov_b32 s26, 0
	s_cmpk_lt_u32 s71, 0x100
	s_cbranch_scc1 .Lgy4
	s_barrier
.Lgy4:
.LBB0_621:
	s_add_i32 s51, s26, 2
	s_add_u32 s0, s22, 0x100
	s_addc_u32 s1, s23, 0
	s_add_i32 s60, 0, 0x10000
	v_add_u32_e32 v152, s60, v155
	ds_read_b128 v[90:93], v152
	ds_read_b128 v[94:97], v152 offset:1024
	ds_read_b128 v[148:151], v152 offset:2048
	ds_read_b128 v[158:161], v152 offset:3072
	s_cmp_eq_u32 s82, s26
	s_cselect_b32 s26, s21, s29
	s_cselect_b32 s49, s65, s1
	s_cselect_b32 s48, s64, s0
	s_cselect_b32 s27, s20, s45
	v_lshl_add_u64 v[152:153], s[22:23], 0, v[144:145]
	s_add_i32 m0, s76, 0xc000
	ds_read_b128 v[162:165], v157
	ds_read_b128 v[166:169], v157 offset:1024
	ds_read_b128 v[170:173], v157 offset:2048
	ds_read_b128 v[174:177], v157 offset:3072
	ds_read_b128 v[178:181], v157 offset:4096
	ds_read_b128 v[182:185], v157 offset:5120
	ds_read_b128 v[186:189], v157 offset:6144
	ds_read_b128 v[190:193], v157 offset:7168
	global_load_lds_dwordx4 v[152:153], off
	v_lshl_add_u64 v[152:153], s[22:23], 0, v[146:147]
	s_add_i32 m0, s76, 0xe000
	s_nop 0
	global_load_lds_dwordx4 v[152:153], off
	s_waitcnt lgkmcnt(11)
	s_add_i32 s62, 0, 0x14000
	v_add_u32_e32 v152, s62, v155
	s_add_i32 s22, s60, s73
	ds_read_b128 v[194:197], v152
	ds_read_b128 v[198:201], v152 offset:1024
	ds_read_b128 v[202:205], v152 offset:2048
	ds_read_b128 v[220:223], v152 offset:3072
	s_waitcnt vmcnt(8) lgkmcnt(0)
	s_barrier
; #define PG8_STAGE(bufoff, gbase, voff) do { _Pragma("unroll") for (int _i = 0; _i < 2; ++_i) \
;         __builtin_amdgcn_global_load_lds((const unsigned*)((const char*)(gbase) + (voff)[_i]), (LAS unsigned*)(lds + (bufoff) + ldsw + _i * 8192), 16, 0, 0); } while (0)
; #define PG8_LDA(dst, b, h) do { _Pragma("unroll") for (int m = 0; m < 4; ++m) _Pragma("unroll") for (int k = 0; k < 2; ++k) dst[m][k] = *(const LAS h16x8*)(lds + PG8_SA(b, h) + aoff + m * 2048 + k * 1024); } while (0)
; #define PG8_LDB(dst, b, h) do { _Pragma("unroll") for (int n = 0; n < 2; ++n) _Pragma("unroll") for (int k = 0; k < 2; ++k) dst[n][k] = *(const LAS h16x8*)(lds + PG8_SB(b, h) + boff + n * 2048 + k * 1024); } while (0)
; #define PG8_MMA(ai, bj, At, Bt_) do { __builtin_amdgcn_s_setprio(1); _Pragma("unroll") for (int m = 0; m < 4; ++m) _Pragma("unroll") for (int n = 0; n < 2; ++n) _Pragma("unroll") for (int k = 0; k < 2; ++k) \
;         acc[ai][bj][m][n] = __builtin_amdgcn_mfma_f32_16x16x32_f16(Bt_[n][k], At[m][k], acc[ai][bj][m][n], 0, 0, 0); __builtin_amdgcn_s_setprio(0); } while (0)
; #define PG8_WAIT_V(n) asm volatile("s_waitcnt vmcnt(" #n ")" ::: "memory")
; #define PG8_BAR __builtin_amdgcn_s_barrier()
; template <class Epi, class AMap>
; __device__ __forceinline__ void gemm_phase(LAS unsigned char* lds, const AMap am, const int lda, const h16* Bt, const int ldb, const int M, const int N, const int K, const Epi& E) {
;     ...
;             PG8_LDB(B0, 0, 0); PG8_SCHED; PG8_LDA(At, 0, 0); PG8_STAGE(PG8_SA(1, 1), a1 + hstepA, voffA);
;             PG8_WAIT_L(8); PG8_BAR; PG8_WAIT_L(0); PG8_MMA(0, 0, At, B0); PG8_BAR; PG8_SCHED;
;             PG8_LDB(B1, 0, 1); PG8_STAGE(PG8_SB(0, 0), b2, voffB);
;             PG8_BAR; PG8_WAIT_L(0); PG8_MMA(0, 1, At, B1); PG8_BAR;
;             PG8_LDA(At, 0, 1); PG8_STAGE(PG8_SA(0, 0), a2, voffA);
;             PG8_BAR; PG8_WAIT_L(0); PG8_MMA(1, 0, At, B0); PG8_BAR; PG8_SCHED;
;             PG8_STAGE(PG8_SB(0, 1), b2 + hstepB, voffB);
;             PG8_WAIT_V(6); PG8_BAR; PG8_MMA(1, 1, At, B1); PG8_BAR;
;             PG8_LDB(B0, 1, 0); PG8_SCHED; PG8_LDA(At, 1, 0); PG8_STAGE(PG8_SA(0, 1), a2 + hstepA, voffA);
;             PG8_WAIT_L(8); PG8_BAR; PG8_WAIT_L(0); PG8_MMA(0, 0, At, B0); PG8_BAR; PG8_SCHED;
;             PG8_LDB(B1, 1, 1); PG8_STAGE(PG8_SB(1, 0), b3, voffB);
;             PG8_BAR; PG8_WAIT_L(0); PG8_MMA(0, 1, At, B1); PG8_BAR;
	v_mfma_f32_16x16x32_f16 v[130:133], v[90:93], v[162:165], v[130:133]
	v_mfma_f32_16x16x32_f16 v[134:137], v[148:151], v[162:165], v[134:137]
	v_mfma_f32_16x16x32_f16 v[126:129], v[90:93], v[170:173], v[126:129]
	v_mfma_f32_16x16x32_f16 v[122:125], v[148:151], v[170:173], v[122:125]
	v_mfma_f32_16x16x32_f16 v[118:121], v[90:93], v[178:181], v[118:121]
	v_mfma_f32_16x16x32_f16 v[114:117], v[148:151], v[178:181], v[114:117]
	v_mfma_f32_16x16x32_f16 v[110:113], v[90:93], v[186:189], v[110:113]
	v_mfma_f32_16x16x32_f16 v[106:109], v[148:151], v[186:189], v[106:109]
	v_mfma_f32_16x16x32_f16 v[130:133], v[94:97], v[166:169], v[130:133]
	v_mfma_f32_16x16x32_f16 v[134:137], v[158:161], v[166:169], v[134:137]
	v_mfma_f32_16x16x32_f16 v[126:129], v[94:97], v[174:177], v[126:129]
	v_mfma_f32_16x16x32_f16 v[122:125], v[158:161], v[174:177], v[122:125]
	v_mfma_f32_16x16x32_f16 v[118:121], v[94:97], v[182:185], v[118:121]
	v_mfma_f32_16x16x32_f16 v[114:117], v[158:161], v[182:185], v[114:117]
	v_mfma_f32_16x16x32_f16 v[110:113], v[94:97], v[190:193], v[110:113]
	v_mfma_f32_16x16x32_f16 v[106:109], v[158:161], v[190:193], v[106:109]
	v_mfma_f32_16x16x32_f16 v[62:65], v[194:197], v[162:165], v[62:65]
	v_mfma_f32_16x16x32_f16 v[58:61], v[202:205], v[162:165], v[58:61]
	v_mfma_f32_16x16x32_f16 v[54:57], v[194:197], v[170:173], v[54:57]
	v_mfma_f32_16x16x32_f16 v[50:53], v[202:205], v[170:173], v[50:53]
	v_mfma_f32_16x16x32_f16 v[46:49], v[194:197], v[178:181], v[46:49]
	v_mfma_f32_16x16x32_f16 v[42:45], v[202:205], v[178:181], v[42:45]
	v_mfma_f32_16x16x32_f16 v[38:41], v[194:197], v[186:189], v[38:41]
	v_mfma_f32_16x16x32_f16 v[34:37], v[202:205], v[186:189], v[34:37]
	v_mfma_f32_16x16x32_f16 v[62:65], v[198:201], v[166:169], v[62:65]
	v_mfma_f32_16x16x32_f16 v[58:61], v[220:223], v[166:169], v[58:61]
	v_mfma_f32_16x16x32_f16 v[54:57], v[198:201], v[174:177], v[54:57]
	v_mfma_f32_16x16x32_f16 v[50:53], v[220:223], v[174:177], v[50:53]
	v_mfma_f32_16x16x32_f16 v[46:49], v[198:201], v[182:185], v[46:49]
	v_mfma_f32_16x16x32_f16 v[42:45], v[220:223], v[182:185], v[42:45]
	v_mfma_f32_16x16x32_f16 v[38:41], v[198:201], v[190:193], v[38:41]
	v_mfma_f32_16x16x32_f16 v[34:37], v[220:223], v[190:193], v[34:37]
	s_barrier
	v_lshl_add_u64 v[152:153], s[26:27], 0, v[0:1]
	s_mov_b32 m0, s22
	v_lshl_add_u64 v[206:207], s[26:27], 0, v[142:143]
	global_load_lds_dwordx4 v[152:153], off
	s_add_i32 m0, s22, 0x2000
	s_nop 0
	global_load_lds_dwordx4 v[206:207], off
	s_mov_b32 m0, s76
	v_lshl_add_u64 v[212:213], s[48:49], 0, v[138:139]
	ds_read_b128 v[162:165], v157 offset:16384
	ds_read_b128 v[166:169], v157 offset:17408
	ds_read_b128 v[170:173], v157 offset:18432
	ds_read_b128 v[174:177], v157 offset:19456
	ds_read_b128 v[178:181], v157 offset:20480
	ds_read_b128 v[182:185], v157 offset:21504
	ds_read_b128 v[186:189], v157 offset:22528
	ds_read_b128 v[190:193], v157 offset:23552
	global_load_lds_dwordx4 v[212:213], off
	v_lshl_add_u64 v[224:225], s[48:49], 0, v[140:141]
	s_mov_b32 m0, s77
	s_nop 0
	global_load_lds_dwordx4 v[224:225], off
	s_add_u32 s22, s26, 0x10000
	s_addc_u32 s23, s27, 0
	s_add_i32 s60, s62, s73
	v_lshl_add_u64 v[232:233], s[22:23], 0, v[0:1]
	s_mov_b32 m0, s60
	s_nop 0
	global_load_lds_dwordx4 v[232:233], off
	v_lshl_add_u64 v[232:233], s[22:23], 0, v[142:143]
	s_add_i32 m0, s60, 0x2000
	s_nop 0
	global_load_lds_dwordx4 v[232:233], off
	s_waitcnt vmcnt(8) lgkmcnt(0)
	s_barrier
	v_mfma_f32_16x16x32_f16 v[102:105], v[90:93], v[162:165], v[102:105]
	v_mfma_f32_16x16x32_f16 v[98:101], v[148:151], v[162:165], v[98:101]
	v_mfma_f32_16x16x32_f16 v[86:89], v[90:93], v[170:173], v[86:89]
	v_mfma_f32_16x16x32_f16 v[82:85], v[148:151], v[170:173], v[82:85]
	v_mfma_f32_16x16x32_f16 v[78:81], v[90:93], v[178:181], v[78:81]
	v_mfma_f32_16x16x32_f16 v[74:77], v[148:151], v[178:181], v[74:77]
	v_mfma_f32_16x16x32_f16 v[70:73], v[90:93], v[186:189], v[70:73]
	v_mfma_f32_16x16x32_f16 v[66:69], v[148:151], v[186:189], v[66:69]
	v_mfma_f32_16x16x32_f16 v[102:105], v[94:97], v[166:169], v[102:105]
	v_mfma_f32_16x16x32_f16 v[98:101], v[158:161], v[166:169], v[98:101]
	v_mfma_f32_16x16x32_f16 v[86:89], v[94:97], v[174:177], v[86:89]
	v_mfma_f32_16x16x32_f16 v[82:85], v[158:161], v[174:177], v[82:85]
	v_mfma_f32_16x16x32_f16 v[78:81], v[94:97], v[182:185], v[78:81]
	v_mfma_f32_16x16x32_f16 v[74:77], v[158:161], v[182:185], v[74:77]
	v_mfma_f32_16x16x32_f16 v[70:73], v[94:97], v[190:193], v[70:73]
	v_mfma_f32_16x16x32_f16 v[66:69], v[158:161], v[190:193], v[66:69]
	v_mfma_f32_16x16x32_f16 v[30:33], v[194:197], v[162:165], v[30:33]
	v_mfma_f32_16x16x32_f16 v[26:29], v[202:205], v[162:165], v[26:29]
	v_mfma_f32_16x16x32_f16 v[22:25], v[194:197], v[170:173], v[22:25]
	v_mfma_f32_16x16x32_f16 v[18:21], v[202:205], v[170:173], v[18:21]
	v_mfma_f32_16x16x32_f16 v[14:17], v[194:197], v[178:181], v[14:17]
	v_mfma_f32_16x16x32_f16 v[10:13], v[202:205], v[178:181], v[10:13]
	v_mfma_f32_16x16x32_f16 v[6:9], v[194:197], v[186:189], v[6:9]
	v_mfma_f32_16x16x32_f16 v[2:5], v[202:205], v[186:189], v[2:5]
	v_mfma_f32_16x16x32_f16 v[30:33], v[198:201], v[166:169], v[30:33]
	v_mfma_f32_16x16x32_f16 v[26:29], v[220:223], v[166:169], v[26:29]
	v_mfma_f32_16x16x32_f16 v[22:25], v[198:201], v[174:177], v[22:25]
	v_mfma_f32_16x16x32_f16 v[18:21], v[220:223], v[174:177], v[18:21]
	v_mfma_f32_16x16x32_f16 v[14:17], v[198:201], v[182:185], v[14:17]
	v_mfma_f32_16x16x32_f16 v[10:13], v[220:223], v[182:185], v[10:13]
	v_mfma_f32_16x16x32_f16 v[6:9], v[198:201], v[190:193], v[6:9]
	v_mfma_f32_16x16x32_f16 v[2:5], v[220:223], v[190:193], v[2:5]
	s_barrier
; #define PG8_STAGE(bufoff, gbase, voff) do { _Pragma("unroll") for (int _i = 0; _i < 2; ++_i) \
;         __builtin_amdgcn_global_load_lds((const unsigned*)((const char*)(gbase) + (voff)[_i]), (LAS unsigned*)(lds + (bufoff) + ldsw + _i * 8192), 16, 0, 0); } while (0)
; #define PG8_LDA(dst, b, h) do { _Pragma("unroll") for (int m = 0; m < 4; ++m) _Pragma("unroll") for (int k = 0; k < 2; ++k) dst[m][k] = *(const LAS h16x8*)(lds + PG8_SA(b, h) + aoff + m * 2048 + k * 1024); } while (0)
; #define PG8_LDB(dst, b, h) do { _Pragma("unroll") for (int n = 0; n < 2; ++n) _Pragma("unroll") for (int k = 0; k < 2; ++k) dst[n][k] = *(const LAS h16x8*)(lds + PG8_SB(b, h) + boff + n * 2048 + k * 1024); } while (0)
; #define PG8_MMA(ai, bj, At, Bt_) do { __builtin_amdgcn_s_setprio(1); _Pragma("unroll") for (int m = 0; m < 4; ++m) _Pragma("unroll") for (int n = 0; n < 2; ++n) _Pragma("unroll") for (int k = 0; k < 2; ++k) \
;         acc[ai][bj][m][n] = __builtin_amdgcn_mfma_f32_16x16x32_f16(Bt_[n][k], At[m][k], acc[ai][bj][m][n], 0, 0, 0); __builtin_amdgcn_s_setprio(0); } while (0)
; #define PG8_WAIT_V(n) asm volatile("s_waitcnt vmcnt(" #n ")" ::: "memory")
; #define PG8_WAIT_L(n) asm volatile("s_waitcnt lgkmcnt(" #n ")" ::: "memory")
; #define PG8_BAR __builtin_amdgcn_s_barrier()
; #define PG8_SCHED __builtin_amdgcn_sched_barrier(0)
; template <class Epi, class AMap>
; __device__ __forceinline__ void gemm_phase(LAS unsigned char* lds, const AMap am, const int lda, const h16* Bt, const int ldb, const int M, const int N, const int K, const Epi& E) {
;     ...
;             PG8_LDB(B0, 1, 0); PG8_SCHED; PG8_LDA(At, 1, 0); PG8_STAGE(PG8_SA(0, 1), a2 + hstepA, voffA);
;             PG8_WAIT_L(8); PG8_BAR; PG8_WAIT_L(0); PG8_MMA(0, 0, At, B0); PG8_BAR; PG8_SCHED;
;             PG8_LDB(B1, 1, 1); PG8_STAGE(PG8_SB(1, 0), b3, voffB);
;             PG8_BAR; PG8_WAIT_L(0); PG8_MMA(0, 1, At, B1); PG8_BAR;
;             PG8_LDA(At, 1, 1); PG8_STAGE(PG8_SA(1, 0), a3, voffA);
;             PG8_BAR; PG8_WAIT_L(0); PG8_MMA(1, 0, At, B0); PG8_BAR; PG8_SCHED;
;             PG8_STAGE(PG8_SB(1, 1), b3 + hstepB, voffB);
;             PG8_WAIT_V(6); PG8_BAR; PG8_MMA(1, 1, At, B1); PG8_BAR;
	s_add_i32 s60, 0, 0x18000
	v_add_u32_e32 v234, s60, v155
	ds_read_b128 v[90:93], v234
	ds_read_b128 v[94:97], v234 offset:1024
	ds_read_b128 v[148:151], v234 offset:2048
	ds_read_b128 v[158:161], v234 offset:3072
	s_add_u32 s22, s48, 0x1c0000
	s_addc_u32 s23, s49, 0
	s_mov_b32 m0, s78
	v_lshl_add_u64 v[232:233], s[22:23], 0, v[138:139]
	ds_read_b128 v[162:165], v157 offset:32768
	ds_read_b128 v[166:169], v157 offset:33792
	ds_read_b128 v[170:173], v157 offset:34816
	ds_read_b128 v[174:177], v157 offset:35840
	ds_read_b128 v[178:181], v157 offset:36864
	ds_read_b128 v[182:185], v157 offset:37888
	ds_read_b128 v[186:189], v157 offset:38912
	ds_read_b128 v[190:193], v157 offset:39936
	global_load_lds_dwordx4 v[232:233], off
	v_lshl_add_u64 v[232:233], s[22:23], 0, v[140:141]
	s_mov_b32 m0, s79
	s_nop 0
	global_load_lds_dwordx4 v[232:233], off
	s_waitcnt lgkmcnt(11)
	s_add_i32 s48, 0, 0x1c000
	s_add_i32 s22, s60, s73
	v_add_u32_e32 v214, s48, v155
	v_lshl_add_u64 v[152:153], v[152:153], 0, s[92:93]
	s_mov_b32 m0, s22
	ds_read_b128 v[194:197], v214
	ds_read_b128 v[198:201], v214 offset:1024
	ds_read_b128 v[202:205], v214 offset:2048
	ds_read_b128 v[220:223], v214 offset:3072
	s_waitcnt vmcnt(8) lgkmcnt(0)
	s_barrier
	v_mfma_f32_16x16x32_f16 v[130:133], v[90:93], v[162:165], v[130:133]
	v_mfma_f32_16x16x32_f16 v[134:137], v[148:151], v[162:165], v[134:137]
	v_mfma_f32_16x16x32_f16 v[126:129], v[90:93], v[170:173], v[126:129]
	v_mfma_f32_16x16x32_f16 v[122:125], v[148:151], v[170:173], v[122:125]
	v_mfma_f32_16x16x32_f16 v[118:121], v[90:93], v[178:181], v[118:121]
	v_mfma_f32_16x16x32_f16 v[114:117], v[148:151], v[178:181], v[114:117]
	v_mfma_f32_16x16x32_f16 v[110:113], v[90:93], v[186:189], v[110:113]
	v_mfma_f32_16x16x32_f16 v[106:109], v[148:151], v[186:189], v[106:109]
	v_mfma_f32_16x16x32_f16 v[130:133], v[94:97], v[166:169], v[130:133]
	v_mfma_f32_16x16x32_f16 v[134:137], v[158:161], v[166:169], v[134:137]
	v_mfma_f32_16x16x32_f16 v[126:129], v[94:97], v[174:177], v[126:129]
	v_mfma_f32_16x16x32_f16 v[122:125], v[158:161], v[174:177], v[122:125]
	v_mfma_f32_16x16x32_f16 v[118:121], v[94:97], v[182:185], v[118:121]
	v_mfma_f32_16x16x32_f16 v[114:117], v[158:161], v[182:185], v[114:117]
	v_mfma_f32_16x16x32_f16 v[110:113], v[94:97], v[190:193], v[110:113]
	v_mfma_f32_16x16x32_f16 v[106:109], v[158:161], v[190:193], v[106:109]
	v_mfma_f32_16x16x32_f16 v[62:65], v[194:197], v[162:165], v[62:65]
	v_mfma_f32_16x16x32_f16 v[58:61], v[202:205], v[162:165], v[58:61]
	v_mfma_f32_16x16x32_f16 v[54:57], v[194:197], v[170:173], v[54:57]
	v_mfma_f32_16x16x32_f16 v[50:53], v[202:205], v[170:173], v[50:53]
	v_mfma_f32_16x16x32_f16 v[46:49], v[194:197], v[178:181], v[46:49]
	v_mfma_f32_16x16x32_f16 v[42:45], v[202:205], v[178:181], v[42:45]
	v_mfma_f32_16x16x32_f16 v[38:41], v[194:197], v[186:189], v[38:41]
	v_mfma_f32_16x16x32_f16 v[34:37], v[202:205], v[186:189], v[34:37]
	v_mfma_f32_16x16x32_f16 v[62:65], v[198:201], v[166:169], v[62:65]
	v_mfma_f32_16x16x32_f16 v[58:61], v[220:223], v[166:169], v[58:61]
	v_mfma_f32_16x16x32_f16 v[54:57], v[198:201], v[174:177], v[54:57]
	v_mfma_f32_16x16x32_f16 v[50:53], v[220:223], v[174:177], v[50:53]
	v_mfma_f32_16x16x32_f16 v[46:49], v[198:201], v[182:185], v[46:49]
	v_mfma_f32_16x16x32_f16 v[42:45], v[220:223], v[182:185], v[42:45]
	v_mfma_f32_16x16x32_f16 v[38:41], v[198:201], v[190:193], v[38:41]
	v_mfma_f32_16x16x32_f16 v[34:37], v[220:223], v[190:193], v[34:37]
	s_barrier
	global_load_lds_dwordx4 v[152:153], off
	v_lshl_add_u64 v[152:153], v[206:207], 0, s[92:93]
	s_add_i32 m0, s22, 0x2000
	s_nop 0
	global_load_lds_dwordx4 v[152:153], off
	s_mov_b32 m0, s80
	v_lshl_add_u64 v[152:153], v[212:213], 0, s[92:93]
	ds_read_b128 v[162:165], v157 offset:49152
	ds_read_b128 v[166:169], v157 offset:50176
	ds_read_b128 v[170:173], v157 offset:51200
	ds_read_b128 v[174:177], v157 offset:52224
	ds_read_b128 v[178:181], v157 offset:53248
	ds_read_b128 v[182:185], v157 offset:54272
	ds_read_b128 v[186:189], v157 offset:55296
	ds_read_b128 v[190:193], v157 offset:56320
	global_load_lds_dwordx4 v[152:153], off
	v_lshl_add_u64 v[152:153], v[224:225], 0, s[92:93]
	s_mov_b32 m0, s81
	s_nop 0
	global_load_lds_dwordx4 v[152:153], off
	s_add_u32 s22, s26, 0x10080
	s_addc_u32 s23, s27, 0
	s_add_i32 s26, s48, s73
	v_lshl_add_u64 v[232:233], s[22:23], 0, v[0:1]
	s_mov_b32 m0, s26
	s_nop 0
	global_load_lds_dwordx4 v[232:233], off
	v_lshl_add_u64 v[232:233], s[22:23], 0, v[142:143]
	s_add_i32 m0, s26, 0x2000
	s_nop 0
	global_load_lds_dwordx4 v[232:233], off
	s_add_u32 s29, s29, 0x100
	s_addc_u32 s45, s45, 0
	s_cmp_ge_i32 s51, s24
	s_mov_b64 s[22:23], s[0:1]
	s_mov_b32 s26, s51
	s_waitcnt vmcnt(8) lgkmcnt(0)
	s_barrier
	v_mfma_f32_16x16x32_f16 v[102:105], v[90:93], v[162:165], v[102:105]
	v_mfma_f32_16x16x32_f16 v[98:101], v[148:151], v[162:165], v[98:101]
	v_mfma_f32_16x16x32_f16 v[86:89], v[90:93], v[170:173], v[86:89]
	v_mfma_f32_16x16x32_f16 v[82:85], v[148:151], v[170:173], v[82:85]
	v_mfma_f32_16x16x32_f16 v[78:81], v[90:93], v[178:181], v[78:81]
	v_mfma_f32_16x16x32_f16 v[74:77], v[148:151], v[178:181], v[74:77]
	v_mfma_f32_16x16x32_f16 v[70:73], v[90:93], v[186:189], v[70:73]
	v_mfma_f32_16x16x32_f16 v[66:69], v[148:151], v[186:189], v[66:69]
	v_mfma_f32_16x16x32_f16 v[102:105], v[94:97], v[166:169], v[102:105]
	v_mfma_f32_16x16x32_f16 v[98:101], v[158:161], v[166:169], v[98:101]
	v_mfma_f32_16x16x32_f16 v[86:89], v[94:97], v[174:177], v[86:89]
	v_mfma_f32_16x16x32_f16 v[82:85], v[158:161], v[174:177], v[82:85]
	v_mfma_f32_16x16x32_f16 v[78:81], v[94:97], v[182:185], v[78:81]
	v_mfma_f32_16x16x32_f16 v[74:77], v[158:161], v[182:185], v[74:77]
	v_mfma_f32_16x16x32_f16 v[70:73], v[94:97], v[190:193], v[70:73]
	v_mfma_f32_16x16x32_f16 v[66:69], v[158:161], v[190:193], v[66:69]
	v_mfma_f32_16x16x32_f16 v[30:33], v[194:197], v[162:165], v[30:33]
	v_mfma_f32_16x16x32_f16 v[26:29], v[202:205], v[162:165], v[26:29]
	v_mfma_f32_16x16x32_f16 v[22:25], v[194:197], v[170:173], v[22:25]
	v_mfma_f32_16x16x32_f16 v[18:21], v[202:205], v[170:173], v[18:21]
	v_mfma_f32_16x16x32_f16 v[14:17], v[194:197], v[178:181], v[14:17]
	v_mfma_f32_16x16x32_f16 v[10:13], v[202:205], v[178:181], v[10:13]
	v_mfma_f32_16x16x32_f16 v[6:9], v[194:197], v[186:189], v[6:9]
	v_mfma_f32_16x16x32_f16 v[2:5], v[202:205], v[186:189], v[2:5]
	v_mfma_f32_16x16x32_f16 v[30:33], v[198:201], v[166:169], v[30:33]
	v_mfma_f32_16x16x32_f16 v[26:29], v[220:223], v[166:169], v[26:29]
	v_mfma_f32_16x16x32_f16 v[22:25], v[198:201], v[174:177], v[22:25]
	v_mfma_f32_16x16x32_f16 v[18:21], v[220:223], v[174:177], v[18:21]
	v_mfma_f32_16x16x32_f16 v[14:17], v[198:201], v[182:185], v[14:17]
	v_mfma_f32_16x16x32_f16 v[10:13], v[220:223], v[182:185], v[10:13]
	v_mfma_f32_16x16x32_f16 v[6:9], v[198:201], v[190:193], v[6:9]
	v_mfma_f32_16x16x32_f16 v[2:5], v[220:223], v[190:193], v[2:5]
	s_barrier
	s_cbranch_scc0 .LBB0_621
	s_branch .LBB0_610
; #define PG8_WAIT_V(n) asm volatile("s_waitcnt vmcnt(" #n ")" ::: "memory")
; #define PG8_BAR __builtin_amdgcn_s_barrier()
; template <class Epi, class AMap>
; __device__ __forceinline__ void gemm_phase(LAS unsigned char* lds, const AMap am, const int lda, const h16* Bt, const int ldb, const int M, const int N, const int K, const Epi& E) {
;     ...
;     PG8_WAIT_V(0);
;     if (wr == 0) PG8_BAR;
;     PG8_BAR;
.LBB0_622:
	s_waitcnt vmcnt(0)
	s_mov_b64 s[18:19], 0x90000
	s_mov_b64 s[96:97], 0x80000
	s_cmpk_gt_u32 s71, 0xff
	s_cbranch_scc1 .LBB0_624
.LBB0_624:
	v_readlane_b32 s82, v255, 4
	v_readlane_b32 s29, v254, 37
	v_readlane_b32 s16, v252, 35
	v_readlane_b32 s17, v252, 36
	v_readlane_b32 s67, v252, 37
	v_readlane_b32 s89, v252, 38
	s_mov_b32 s63, 0x8000
	v_readlane_b32 s83, v255, 5
	v_readlane_b32 s10, v255, 10
	v_readlane_b32 s11, v255, 11
	s_barrier

; __device__ __forceinline__ int otid() { int t = (int)threadIdx.x; asm volatile("" : "+v"(t)); return t; }
; __device__ __forceinline__ int obid() { int t = (int)blockIdx.x; asm volatile("" : "+s"(t)); return t; }
; #define PG8_WAIT_V(n) asm volatile("s_waitcnt vmcnt(" #n ")" ::: "memory")
; #define PG8_BAR __builtin_amdgcn_s_barrier()
; template <class Epi, class AMap>
; __device__ __forceinline__ void gemm_phase(LAS unsigned char* lds, const AMap am, const int lda, const h16* Bt, const int ldb, const int M, const int N, const int K, const Epi& E) {
;     const int tid = otid(), wid = __builtin_amdgcn_readfirstlane(tid >> 6), lane = tid & 63, wr = wid >> 2, wc = wid & 3, fr = lane & 15, fq = lane >> 4;
;     const int nt = K / BK;
;     Order S; S.init(M, N, (int)gridDim.x, obid());
;     unsigned voffA[2], voffB[2];
; #pragma unroll
;     for (int i = 0; i < 2; ++i) { int R, C; stage_rc(tid * 16 + i * 8192, R, C); const int Rb = Epi::PERM ? ((R & ~31) + perm32(R & 31)) : R;
;         voffA[i] = (unsigned)(R * lda + C) * 2u; voffB[i] = (unsigned)(Rb * ldb + C) * 2u; }
;     const size_t kstep = (size_t)(BK * 2);
;     const size_t hstepA = (size_t)HALF * lda * 2, hstepB = (size_t)HALF * ldb * 2;
;     const size_t tstepA = 2 * hstepA, tstepB = 2 * hstepB;
;     const unsigned ldsw = (unsigned)wid * 1024u;
;     const int aoff = lds_byte(wr * 64 + fr, fq * 8), boff = lds_byte(wc * 32 + fr, fq * 8);
;     ...
;     Unit cur, nxt; int ui = 0;
;     if (!S.next(0, cur)) return;
;     f32x4 acc[2][2][4][2];
; #pragma unroll
;     for (int a = 0; a < 2; ++a)
; #pragma unroll
;         for (int b = 0; b < 2; ++b)
; #pragma unroll
;             for (int m = 0; m < 4; ++m)
; #pragma unroll
;                 for (int n = 0; n < 2; ++n) acc[a][b][m][n] = (f32x4){0.f, 0.f, 0.f, 0.f};
;     h16x8 At[4][2], B0[2][2], B1[2][2];
;     const char* cA = am(cur.pn) + (size_t)cur.pm * tstepA; const char* cB = (const char*)Bt + (size_t)cur.pn * tstepB;
;     PG8_STAGE(PG8_SB(0, 0), cB, voffB); PG8_STAGE(PG8_SA(0, 0), cA, voffA); PG8_STAGE(PG8_SB(0, 1), cB + hstepB, voffB); PG8_STAGE(PG8_SA(0, 1), cA + hstepA, voffA);
;     if (wr == 1) PG8_BAR;
;     PG8_WAIT_V(4); PG8_BAR;
;     PG8_STAGE(PG8_SB(1, 0), cB + kstep, voffB); PG8_STAGE(PG8_SA(1, 0), cA + kstep, voffA); PG8_STAGE(PG8_SB(1, 1), cB + hstepB + kstep, voffB);
;     PG8_WAIT_V(6); PG8_BAR;
.LBB0_630:
	v_ashrrev_i32_e32 v0, 31, v18
	v_lshrrev_b32_e32 v0, 26, v0
	v_add_u32_e32 v0, v18, v0
	v_ashrrev_i32_e32 v10, 6, v0
	v_bfe_i32 v0, v18, 27, 1
	s_waitcnt vmcnt(0)
	v_lshlrev_b32_e32 v2, 4, v18
	v_lshrrev_b32_e32 v0, 22, v0
	v_add_u32_e32 v0, v2, v0
	v_and_b32_e32 v0, 0xfffffc00, v0
	v_sub_u32_e32 v0, v2, v0
	v_lshrrev_b32_e32 v3, 4, v0
	v_bitop3_b32 v3, v3, v0, 32 bitop3:0x6c
	v_ashrrev_i32_e32 v0, 31, v0
	v_lshrrev_b32_e32 v0, 26, v0
	v_lshlrev_b32_e32 v4, 3, v10
	v_add_u32_e32 v0, v3, v0
	v_and_b32_e32 v4, -16, v4
	v_ashrrev_i32_e32 v12, 6, v0
	v_add_u32_e32 v0, v12, v4
	v_lshlrev_b32_e32 v4, 5, v10
	v_and_b32_e32 v11, 32, v4
	v_mul_i32_i24_e32 v4, 64, v12
	v_sub_u32_e32 v3, v3, v4
	v_mov_b32_e32 v7, 1
	s_ashr_i32 s20, s69, 6
	s_ashr_i32 s1, s69, 8
	v_ashrrev_i16_sdwa v3, v7, sext(v3) dst_sel:DWORD dst_unused:UNUSED_PAD src0_sel:DWORD src1_sel:BYTE_0
	s_lshl_b32 s71, s20, 10
	v_bfe_i32 v13, v3, 0, 16
	v_and_b32_e32 v6, 3, v12
	s_mov_b32 s3, 0x7fffe0
	s_movk_i32 s2, 0x1c00
	s_add_u32 s72, s10, 0x1d00000
	v_add_u32_e32 v3, v11, v13
	v_lshlrev_b32_e32 v4, 1, v0
	v_lshrrev_b32_e32 v5, 2, v0
	v_and_or_b32 v6, v0, s3, v6
	v_mul_lo_u32 v0, v0, s2
	v_add_u32_e32 v2, 0x2000, v2
	s_addc_u32 s73, s11, 0
	s_add_i32 s0, s21, s0
	v_add_lshl_u32 v142, v3, v0, 1
	v_lshlrev_b32_e32 v0, 1, v3
	v_ashrrev_i32_e32 v3, 31, v2
	s_ashr_i32 s21, s0, 31
	v_lshrrev_b32_e32 v3, 22, v3
	s_lshr_b32 s21, s21, 27
	v_add_u32_e32 v3, v2, v3
	s_add_i32 s21, s0, s21
	v_ashrrev_i32_e32 v14, 10, v3
	s_ashr_i32 s22, s21, 5
	s_and_b32 s21, s21, 0xffe0
	v_mul_i32_i24_e32 v3, 0x400, v14
	s_sub_i32 s21, s0, s21
	v_sub_u32_e32 v2, v2, v3
	s_bfe_i32 s0, s21, 0x80000
	v_and_b32_e32 v4, 24, v4
	v_and_b32_e32 v5, 4, v5
	v_lshrrev_b32_e32 v3, 4, v2
	s_bfe_u32 s0, s0, 0x2000d
	v_or3_b32 v4, v6, v5, v4
	v_bitop3_b32 v2, v3, v2, 32 bitop3:0x6c
	s_add_i32 s23, s21, s0
	v_lshl_add_u32 v0, v4, 9, v0
	v_ashrrev_i32_e32 v4, 31, v2
	s_bfe_i32 s0, s23, 0x80000
	s_and_b32 s23, s23, 0xfc
	v_lshrrev_b32_e32 v4, 26, v4
	s_sext_i32_i16 s0, s0
	s_sub_i32 s21, s21, s23
	v_add_u32_e32 v4, v2, v4
	s_lshl_b32 s22, s22, 2
	s_lshr_b32 s0, s0, 2
	s_sext_i32_i8 s21, s21
	v_lshlrev_b32_e32 v3, 3, v14
	v_ashrrev_i32_e32 v16, 6, v4
	v_and_b32_e32 v4, 0xc0, v4
	s_add_i32 s35, s22, s21
	s_bfe_i64 s[22:23], s[0:1], 0x100000
	v_and_b32_e32 v3, -16, v3
	v_sub_u32_e32 v2, v2, v4
	s_lshl_b64 s[22:23], s[22:23], 17
	v_add_u32_e32 v3, v16, v3
	v_lshlrev_b32_e32 v5, 5, v14
	v_ashrrev_i16_sdwa v2, v7, sext(v2) dst_sel:DWORD dst_unused:UNUSED_PAD src0_sel:DWORD src1_sel:BYTE_0
	s_add_u32 s26, s72, s22
	v_and_b32_e32 v15, 32, v5
	v_bfe_i32 v17, v2, 0, 16
	v_lshlrev_b32_e32 v4, 1, v3
	v_lshrrev_b32_e32 v5, 2, v3
	v_and_b32_e32 v6, 3, v16
	s_addc_u32 s27, s73, s23
	s_add_i32 s74, s71, 0
	v_add_u32_e32 v2, v15, v17
	v_and_b32_e32 v4, 24, v4
	v_and_b32_e32 v5, 4, v5
	v_and_or_b32 v6, v3, s3, v6
	v_mul_lo_u32 v3, v3, s2
	s_add_i32 m0, s74, 0x10000
	v_or3_b32 v4, v6, v5, v4
	v_add_lshl_u32 v144, v2, v3, 1
	v_lshlrev_b32_e32 v2, 1, v2
	s_mul_i32 s29, s35, 0x380000
	global_load_lds_dwordx4 v0, s[26:27]
	s_add_i32 m0, s74, 0x12000
	v_lshl_add_u32 v146, v4, 9, v2
	s_mul_hi_i32 s21, s35, 0x380000
	s_add_u32 s22, s16, s29
	global_load_lds_dwordx4 v146, s[26:27]
	s_addc_u32 s23, s17, s21
	s_mov_b32 m0, s74
	s_add_i32 s75, s74, 0x2000
	global_load_lds_dwordx4 v142, s[22:23]
	s_mov_b32 m0, s75
	s_add_u32 s38, s26, 0x10000
	global_load_lds_dwordx4 v144, s[22:23]
	s_addc_u32 s39, s27, 0
	s_add_i32 m0, s74, 0x14000
	v_mov_b32_e32 v147, v1
	global_load_lds_dwordx4 v0, s[38:39]
	s_add_i32 m0, s74, 0x16000
	v_mov_b32_e32 v143, v1
	global_load_lds_dwordx4 v146, s[38:39]
	s_add_u32 s38, s22, 0x1c0000
	s_addc_u32 s39, s23, 0
	s_add_i32 s76, s74, 0x4000
	s_mov_b32 m0, s76
	s_add_i32 s77, s74, 0x6000
	global_load_lds_dwordx4 v142, s[38:39]
	s_mov_b32 m0, s77
	v_mov_b32_e32 v145, v1
	global_load_lds_dwordx4 v144, s[38:39]
	v_lshl_add_u64 v[8:9], s[26:27], 0, v[0:1]
	v_lshl_add_u64 v[6:7], s[26:27], 0, v[146:147]
	v_lshl_add_u64 v[4:5], s[22:23], 0, v[142:143]
	s_cmp_lg_u32 s1, 1
	v_lshl_add_u64 v[2:3], s[22:23], 0, v[144:145]
	s_cbranch_scc1 .LBB0_632
.LBB0_632:
	v_lshrrev_b32_e32 v20, 1, v18
	v_and_b32_e32 v20, 24, v20
	v_and_b32_e32 v19, 15, v18
	v_lshlrev_b32_e32 v21, 1, v20
	v_lshlrev_b32_e32 v18, 2, v18
	s_sext_i32_i8 s50, s0
	s_and_b32 s20, s20, 3
	v_lshl_or_b32 v202, s1, 6, v19
	v_lshl_or_b32 v19, v19, 6, v21
	s_lshl_b32 s0, s1, 13
	v_and_b32_e32 v18, 32, v18
	v_bitop3_b32 v21, v19, s0, v18 bitop3:0xde
	s_lshl_b32 s0, s20, 12
	v_bitop3_b32 v203, v19, s0, v18 bitop3:0xde
	v_readlane_b32 s0, v251, 37
	v_readlane_b32 s1, v251, 38
	s_add_u32 s40, s0, s46
	s_addc_u32 s41, s1, s47
	s_add_i32 m0, s74, 0x18000
	v_lshl_add_u64 v[8:9], v[8:9], 0, s[92:93]
	s_waitcnt vmcnt(0)
	s_barrier
	global_load_lds_dwordx4 v[8:9], off
	v_lshl_add_u64 v[6:7], v[6:7], 0, s[92:93]
	s_add_i32 m0, s74, 0x1a000
	s_add_i32 s78, s74, 0x8000
	s_add_i32 s79, s74, 0xa000
	global_load_lds_dwordx4 v[6:7], off
	v_lshl_add_u64 v[4:5], v[4:5], 0, s[92:93]
	s_mov_b32 m0, s78
	s_add_u32 s0, s26, 0x10080
	global_load_lds_dwordx4 v[4:5], off
	v_lshl_add_u64 v[2:3], v[2:3], 0, s[92:93]
	s_mov_b32 m0, s79
	s_addc_u32 s1, s27, 0
	global_load_lds_dwordx4 v[2:3], off
	s_add_i32 m0, s74, 0x1c000
	v_lshl_add_u64 v[2:3], s[0:1], 0, v[0:1]
	global_load_lds_dwordx4 v[2:3], off
	v_lshl_add_u64 v[2:3], s[0:1], 0, v[146:147]
	s_add_i32 m0, s74, 0x1e000
	v_readlane_b32 s3, v251, 40
	global_load_lds_dwordx4 v[2:3], off
	v_readlane_b32 s2, v251, 39
	s_movk_i32 s3, 0x1c00
	v_lshrrev_b32_e32 v3, 1, v10
	v_mul_lo_u32 v2, v12, s3
	s_mov_b32 s2, 0x1c000
	v_mad_u64_u32 v[2:3], s[0:1], v3, s2, v[2:3]
	v_readlane_b32 s4, v251, 41
	v_readlane_b32 s5, v251, 42
	v_or_b32_e32 v2, v2, v11
	v_add_lshl_u32 v2, v2, v13, 1
	v_mov_b32_e32 v3, v1
	s_mov_b64 s[4:5], 0x1c0080
	v_lshl_add_u64 v[148:149], v[2:3], 0, s[4:5]
	v_lshrrev_b32_e32 v3, 1, v14
	v_mul_lo_u32 v2, v16, s3
	v_mad_u64_u32 v[2:3], s[0:1], v3, s2, v[2:3]
	v_readlane_b32 s8, v251, 45
	v_readlane_b32 s9, v251, 46
	s_waitcnt vmcnt(6)
	v_or_b32_e32 v2, v2, v15
	v_readlane_b32 s12, v251, 49
	v_readlane_b32 s13, v251, 50
	v_readlane_b32 s14, v251, 51
	v_readlane_b32 s15, v251, 52
	s_cmp_gt_i32 s61, 63
	v_add_lshl_u32 v2, v2, v17, 1
	v_mov_b32_e32 v3, v1
	v_readlane_b32 s8, v254, 58
	v_readlane_b32 s2, v251, 7
	s_cselect_b64 s[42:43], -1, 0
	s_add_i32 s80, s24, -2
	v_lshl_or_b32 v204, s20, 6, v20
	v_lshl_add_u64 v[150:151], v[2:3], 0, s[4:5]
	s_mov_b32 s81, 0
	v_add_u32_e32 v205, 0, v21
	v_readlane_b32 s9, v254, 59
	v_readlane_b32 s3, v251, 8
	v_readlane_b32 s12, v254, 62
	s_movk_i32 s5, 0x3800
	s_movk_i32 s13, 0x2b00
	s_mov_b64 s[14:15], 0xa0000
	v_readlane_b32 s6, v251, 43
	v_readlane_b32 s7, v251, 44
	v_readlane_b32 s10, v251, 47
	v_readlane_b32 s11, v251, 48
	s_barrier
	s_branch .LBB0_634

; __device__ __forceinline__ float sigmoidf_(float x) { return 1.0f / (1.0f + __expf(-x)); }
;     __device__ __forceinline__ void body_a(const f32x4 (&acc)[2][2][4][2], int row0, int cb0) const {
;     ...
;             for (int m = 0; m < 4; ++m) {
;                 const size_t row = (size_t)(row0 + ai * 128 + m * 16);
;                 asm volatile("" ::: "memory");
;                 float a[2][8], kv[2][8], kk[2][8]; float ss = 0.f;
; #pragma unroll
;                 for (int bj = 0; bj < 2; ++bj) {
;                     const int c = cb0 + 32 * bj;
;                     const f32x4 b0 = *(const f32x4*)(a0 + c), b1 = *(const f32x4*)(a0 + c + 4), q0 = *(const f32x4*)(k_k + c), q1 = *(const f32x4*)(k_k + c + 4);
;                     const h16x8 kh = *(const h16x8*)(C1 + row * LDC1 + 2048 + c);
; #pragma unroll
;                     for (int e = 0; e < 4; ++e) {
;                         a[bj][e] = sigmoidf_(acc[ai][bj][m][0][e] + b0[e]); a[bj][4 + e] = sigmoidf_(acc[ai][bj][m][1][e] + b1[e]);
;                         kv[bj][e] = (float)kh[e]; kv[bj][4 + e] = (float)kh[4 + e];
;                         kk[bj][e] = kv[bj][e] * q0[e]; kk[bj][4 + e] = kv[bj][4 + e] * q1[e];
;                         ss += kk[bj][e] * kk[bj][e] + kk[bj][4 + e] * kk[bj][4 + e];
;                     }
;                 }
.Lgx5:
	s_waitcnt vmcnt(0)
	v_add_f32_e32 v122, v122, v166
	v_mul_f32_e32 v122, 0xbfb8aa3b, v122
	v_exp_f32_e32 v196, v122
	v_add_f32_e32 v122, v126, v162
	v_mul_f32_e32 v122, 0xbfb8aa3b, v122
	v_exp_f32_e32 v192, v122
	v_add_f32_e32 v122, v123, v167
	v_mul_f32_e32 v122, 0xbfb8aa3b, v122
	v_exp_f32_e32 v197, v122
	v_add_f32_e32 v122, v127, v163
	v_mul_f32_e32 v122, 0xbfb8aa3b, v122
	v_exp_f32_e32 v193, v122
	v_add_f32_e32 v122, v124, v168
	v_mul_f32_e32 v122, 0xbfb8aa3b, v122
	v_exp_f32_e32 v194, v122
	v_add_f32_e32 v122, v128, v164
	v_mul_f32_e32 v122, 0xbfb8aa3b, v122
	v_exp_f32_e32 v186, v122
	v_add_f32_e32 v122, v125, v169
	v_mul_f32_e32 v122, 0xbfb8aa3b, v122
	v_exp_f32_e32 v195, v122
	v_add_f32_e32 v122, v129, v165
	v_mul_f32_e32 v122, 0xbfb8aa3b, v122
	v_exp_f32_e32 v187, v122
	v_or_b32_e32 v122, 32, v170
	v_ashrrev_i32_e32 v123, 31, v122
	v_lshlrev_b64 v[128:129], 1, v[122:123]
	v_lshl_add_u64 v[122:123], v[172:173], 0, v[128:129]
	global_load_dwordx4 v[124:127], v[154:155], off offset:144
	global_load_dwordx4 v[162:165], v[154:155], off offset:128
	global_load_dwordx4 v[188:191], v[156:157], off offset:144
	global_load_dwordx4 v[220:223], v[156:157], off offset:128
	global_load_dwordx4 v[166:169], v[122:123], off
	v_pk_add_f32 v[196:197], v[196:197], 1.0 op_sel_hi:[1,0]
	s_waitcnt vmcnt(0)
	v_add_f32_e32 v114, v114, v124
	v_mul_f32_e32 v114, 0xbfb8aa3b, v114
	v_exp_f32_e32 v174, v114
	v_add_f32_e32 v114, v119, v163
	v_cvt_f32_f16_e32 v172, v168
	v_cvt_f32_f16_sdwa v173, v168 dst_sel:DWORD dst_unused:UNUSED_PAD src0_sel:WORD_1
	v_cvt_f32_f16_e32 v180, v166
	v_cvt_f32_f16_sdwa v181, v166 dst_sel:DWORD dst_unused:UNUSED_PAD src0_sel:WORD_1
	v_mul_f32_e32 v114, 0xbfb8aa3b, v114
	v_exp_f32_e32 v183, v114
	v_add_f32_e32 v114, v115, v125
	v_mul_f32_e32 v114, 0xbfb8aa3b, v114
	v_pk_mul_f32 v[124:125], v[188:189], v[172:173]
	v_add_f32_e32 v118, v118, v162
	v_exp_f32_e32 v175, v114
	v_pk_mul_f32 v[162:163], v[220:221], v[180:181]
	v_pk_mul_f32 v[114:115], v[124:125], v[124:125]
	v_cvt_f32_f16_e32 v168, v169
	v_pk_fma_f32 v[188:189], v[162:163], v[162:163], v[114:115]
	v_add_f32_e32 v114, v120, v164
	v_mul_f32_e32 v114, 0xbfb8aa3b, v114
	v_exp_f32_e32 v178, v114
	v_add_f32_e32 v114, v116, v126
	v_mul_f32_e32 v114, 0xbfb8aa3b, v114
	v_cvt_f32_f16_sdwa v169, v169 dst_sel:DWORD dst_unused:UNUSED_PAD src0_sel:WORD_1
	v_exp_f32_e32 v170, v114
	v_add_f32_e32 v114, v121, v165
	v_cvt_f32_f16_e32 v176, v167
	v_cvt_f32_f16_sdwa v177, v167 dst_sel:DWORD dst_unused:UNUSED_PAD src0_sel:WORD_1
	v_mul_f32_e32 v114, 0xbfb8aa3b, v114
	v_exp_f32_e32 v179, v114
	v_add_f32_e32 v114, v117, v127
	v_mul_f32_e32 v114, 0xbfb8aa3b, v114
	v_pk_mul_f32 v[164:165], v[190:191], v[168:169]
	v_exp_f32_e32 v171, v114
	v_pk_mul_f32 v[166:167], v[222:223], v[176:177]
	v_pk_mul_f32 v[114:115], v[164:165], v[164:165]
	v_mul_f32_e32 v118, 0xbfb8aa3b, v118
	v_pk_fma_f32 v[190:191], v[166:167], v[166:167], v[114:115]
	v_and_b32_e32 v115, 64, v246
	v_xor_b32_e32 v114, 16, v246
	v_add_u32_e32 v115, 64, v115
	v_cmp_lt_i32_e32 vcc, v114, v115
	v_lshl_add_u64 v[126:127], s[0:1], 0, v[198:199]
	v_exp_f32_e32 v182, v118
	v_cndmask_b32_e32 v114, v246, v114, vcc
	v_lshlrev_b32_e32 v206, 2, v114
	v_xor_b32_e32 v114, 32, v246
	v_cmp_lt_i32_e32 vcc, v114, v115
	v_cvt_f32_f16_e32 v198, v138
	v_cvt_f32_f16_sdwa v199, v138 dst_sel:DWORD dst_unused:UNUSED_PAD src0_sel:WORD_1
	v_cndmask_b32_e32 v114, v246, v114, vcc
	v_lshlrev_b32_e32 v207, 2, v114
	global_load_dwordx4 v[114:117], v[126:127], off offset:16
	global_load_dwordx4 v[118:121], v[126:127], off
	v_div_scale_f32 v138, s[0:1], v197, v197, 1.0
	v_rcp_f32_e32 v200, v138
	s_nop 0
	v_fma_f32 v201, -v138, v200, 1.0
	v_fmac_f32_e32 v200, v201, v200
	v_div_scale_f32 v201, vcc, 1.0, v197, 1.0
	v_mul_f32_e32 v212, v201, v200
	v_fma_f32 v213, -v138, v212, v201
	v_fmac_f32_e32 v212, v213, v200
	v_fma_f32 v138, -v138, v212, v201
	v_div_fmas_f32 v138, v138, v200, v212
	v_div_fixup_f32 v197, v138, v197, 1.0
	v_div_scale_f32 v138, s[0:1], v196, v196, 1.0
	v_rcp_f32_e32 v200, v138
	s_nop 0
	v_fma_f32 v201, -v138, v200, 1.0
	v_fmac_f32_e32 v200, v201, v200
	v_div_scale_f32 v201, vcc, 1.0, v196, 1.0
	v_mul_f32_e32 v212, v201, v200
	v_fma_f32 v213, -v138, v212, v201
	v_fmac_f32_e32 v212, v213, v200
	v_fma_f32 v138, -v138, v212, v201
	v_div_fmas_f32 v138, v138, v200, v212
	v_div_fixup_f32 v196, v138, v196, 1.0
	v_pk_add_f32 v[200:201], v[196:197], -1.0 op_sel_hi:[1,0]
	s_waitcnt vmcnt(0)
; __device__ __forceinline__ float sigmoidf_(float x) { return 1.0f / (1.0f + __expf(-x)); }
;     __device__ __forceinline__ void body_a(const f32x4 (&acc)[2][2][4][2], int row0, int cb0) const {
;     ...
;                     const f32x4 b0 = *(const f32x4*)(a0 + c), b1 = *(const f32x4*)(a0 + c + 4), q0 = *(const f32x4*)(k_k + c), q1 = *(const f32x4*)(k_k + c + 4);
;                     const h16x8 kh = *(const h16x8*)(C1 + row * LDC1 + 2048 + c);
; #pragma unroll
;                     for (int e = 0; e < 4; ++e) {
;                         a[bj][e] = sigmoidf_(acc[ai][bj][m][0][e] + b0[e]); a[bj][4 + e] = sigmoidf_(acc[ai][bj][m][1][e] + b1[e]);
;                         kv[bj][e] = (float)kh[e]; kv[bj][4 + e] = (float)kh[4 + e];
;                         kk[bj][e] = kv[bj][e] * q0[e]; kk[bj][4 + e] = kv[bj][4 + e] * q1[e];
;                         ss += kk[bj][e] * kk[bj][e] + kk[bj][4 + e] * kk[bj][4 + e];
;                     }
;                 }
;                 ss += __shfl_xor(ss, 16); ss += __shfl_xor(ss, 32);
;                 const float inv = 1.0f / fmaxf(sqrtf(ss), 1e-12f);
; #pragma unroll
;                 for (int bj = 0; bj < 2; ++bj) {
;                     const int c = cb0 + 32 * bj;
;                     const f32x4 p0 = *(const f32x4*)(k_a + c), p1 = *(const f32x4*)(k_a + c + 4);
;                     f32x4 ko0, ko1, ao0, ao1, bo0, bo1;
; #pragma unroll
;                     for (int e = 0; e < 4; ++e) {
;                         ko0[e] = kv[bj][e] * (1.0f + (a[bj][e] - 1.0f) * p0[e]); ko1[e] = kv[bj][4 + e] * (1.0f + (a[bj][4 + e] - 1.0f) * p1[e]);
	v_pk_fma_f32 v[118:119], v[200:201], v[118:119], 1.0 op_sel_hi:[1,1,0]
	s_nop 0
	v_pk_mul_f32 v[118:119], v[118:119], v[198:199]
	v_cvt_f32_f16_e32 v200, v139
	v_cvt_f32_f16_sdwa v201, v139 dst_sel:DWORD dst_unused:UNUSED_PAD src0_sel:WORD_1
	v_pk_add_f32 v[138:139], v[194:195], 1.0 op_sel_hi:[1,0]
	v_cvt_pk_f16_f32 v118, v118, v119
	v_div_scale_f32 v119, s[0:1], v139, v139, 1.0
	v_rcp_f32_e32 v194, v119
	s_nop 0
	v_fma_f32 v195, -v119, v194, 1.0
	v_fmac_f32_e32 v194, v195, v194
	v_div_scale_f32 v195, vcc, 1.0, v139, 1.0
	v_mul_f32_e32 v212, v195, v194
	v_fma_f32 v213, -v119, v212, v195
	v_fmac_f32_e32 v212, v213, v194
	v_fma_f32 v119, -v119, v212, v195
	v_div_fmas_f32 v119, v119, v194, v212
	v_div_fixup_f32 v139, v119, v139, 1.0
	v_div_scale_f32 v119, s[0:1], v138, v138, 1.0
	v_rcp_f32_e32 v194, v119
	s_nop 0
	v_fma_f32 v195, -v119, v194, 1.0
	v_fmac_f32_e32 v194, v195, v194
	v_div_scale_f32 v195, vcc, 1.0, v138, 1.0
	v_mul_f32_e32 v212, v195, v194
	v_fma_f32 v213, -v119, v212, v195
	v_fmac_f32_e32 v212, v213, v194
	v_fma_f32 v119, -v119, v212, v195
	v_div_fmas_f32 v119, v119, v194, v212
	v_div_fixup_f32 v138, v119, v138, 1.0
	v_pk_add_f32 v[194:195], v[138:139], -1.0 op_sel_hi:[1,0]
	s_nop 0
	v_pk_fma_f32 v[120:121], v[194:195], v[120:121], 1.0 op_sel_hi:[1,1,0]
	v_cvt_f32_f16_e32 v194, v140
	v_pk_mul_f32 v[120:121], v[120:121], v[200:201]
	v_cvt_f32_f16_sdwa v195, v140 dst_sel:DWORD dst_unused:UNUSED_PAD src0_sel:WORD_1
	v_cvt_pk_f16_f32 v119, v120, v121
	v_pk_add_f32 v[120:121], v[192:193], 1.0 op_sel_hi:[1,0]
	s_nop 0
	v_div_scale_f32 v140, s[0:1], v121, v121, 1.0
	v_rcp_f32_e32 v192, v140
	s_nop 0
	v_fma_f32 v193, -v140, v192, 1.0
	v_fmac_f32_e32 v192, v193, v192
	v_div_scale_f32 v193, vcc, 1.0, v121, 1.0
	v_mul_f32_e32 v212, v193, v192
	v_fma_f32 v213, -v140, v212, v193
	v_fmac_f32_e32 v212, v213, v192
	v_fma_f32 v140, -v140, v212, v193
	v_div_fmas_f32 v140, v140, v192, v212
	v_div_fixup_f32 v193, v140, v121, 1.0
	v_div_scale_f32 v121, s[0:1], v120, v120, 1.0
	v_rcp_f32_e32 v140, v121
	s_nop 0
	v_fma_f32 v192, -v121, v140, 1.0
	v_fmac_f32_e32 v140, v192, v140
	v_div_scale_f32 v192, vcc, 1.0, v120, 1.0
	v_mul_f32_e32 v212, v192, v140
	v_fma_f32 v213, -v121, v212, v192
	v_fmac_f32_e32 v212, v213, v140
	v_fma_f32 v121, -v121, v212, v192
	v_div_fmas_f32 v121, v121, v140, v212
	v_div_fixup_f32 v192, v121, v120, 1.0
	v_pk_add_f32 v[120:121], v[192:193], -1.0 op_sel_hi:[1,0]
	v_cvt_f32_f16_e32 v140, v141
	v_pk_fma_f32 v[114:115], v[120:121], v[114:115], 1.0 op_sel_hi:[1,1,0]
	v_cvt_f32_f16_sdwa v141, v141 dst_sel:DWORD dst_unused:UNUSED_PAD src0_sel:WORD_1
	v_pk_mul_f32 v[114:115], v[114:115], v[194:195]
	v_pk_mul_f32 v[132:133], v[132:133], v[140:141]
	v_cvt_pk_f16_f32 v120, v114, v115
	v_pk_add_f32 v[114:115], v[186:187], 1.0 op_sel_hi:[1,0]
	s_nop 0
	v_div_scale_f32 v121, s[0:1], v115, v115, 1.0
	v_rcp_f32_e32 v186, v121
	s_nop 0
	v_fma_f32 v187, -v121, v186, 1.0
	v_fmac_f32_e32 v186, v187, v186
	v_div_scale_f32 v187, vcc, 1.0, v115, 1.0
	v_mul_f32_e32 v212, v187, v186
	v_fma_f32 v213, -v121, v212, v187
	v_fmac_f32_e32 v212, v213, v186
	v_fma_f32 v121, -v121, v212, v187
	v_div_fmas_f32 v121, v121, v186, v212
	v_div_fixup_f32 v115, v121, v115, 1.0
	v_div_scale_f32 v121, s[0:1], v114, v114, 1.0
	v_rcp_f32_e32 v186, v121
	s_nop 0
	v_fma_f32 v187, -v121, v186, 1.0
	v_fmac_f32_e32 v186, v187, v186
	v_div_scale_f32 v187, vcc, 1.0, v114, 1.0
	v_mul_f32_e32 v212, v187, v186
	v_fma_f32 v213, -v121, v212, v187
	v_fmac_f32_e32 v212, v213, v186
	v_fma_f32 v121, -v121, v212, v187
	v_div_fmas_f32 v121, v121, v186, v212
	v_div_fixup_f32 v114, v121, v114, 1.0
	v_pk_add_f32 v[186:187], v[114:115], -1.0 op_sel_hi:[1,0]
	s_nop 0
	v_pk_fma_f32 v[116:117], v[186:187], v[116:117], 1.0 op_sel_hi:[1,1,0]
	s_nop 0
	v_pk_mul_f32 v[116:117], v[116:117], v[140:141]
	s_nop 0
	v_cvt_pk_f16_f32 v121, v116, v117
	global_store_dwordx4 v[184:185], v[118:121], off
	v_pk_mul_f32 v[116:117], v[134:135], v[198:199]
	v_pk_mul_f32 v[134:135], v[132:133], v[132:133]
	v_pk_mul_f32 v[120:121], v[130:131], v[194:195]
	v_pk_mul_f32 v[118:119], v[136:137], v[200:201]
	v_pk_mul_f32 v[130:131], v[120:121], v[120:121]
	v_pk_fma_f32 v[134:135], v[118:119], v[118:119], v[134:135]
	v_pk_fma_f32 v[130:131], v[116:117], v[116:117], v[130:131]
	v_lshlrev_b64 v[184:185], 12, v[158:159]
	v_add_f32_e32 v130, v130, v131
	v_add_f32_e32 v130, v134, v130
	v_add_f32_e32 v130, v135, v130
	v_add_f32_e32 v130, v130, v188
	v_add_f32_e32 v130, v189, v130
	v_add_f32_e32 v130, v190, v130
	v_add_f32_e32 v130, v191, v130
	ds_bpermute_b32 v131, v206, v130
	s_waitcnt lgkmcnt(0)
	v_add_f32_e32 v130, v130, v131
	ds_bpermute_b32 v131, v207, v130
	s_waitcnt lgkmcnt(0)
;     __device__ __forceinline__ void body_a(const f32x4 (&acc)[2][2][4][2], int row0, int cb0) const {
;     ...
;                 const float inv = 1.0f / fmaxf(sqrtf(ss), 1e-12f);
; #pragma unroll
;                 for (int bj = 0; bj < 2; ++bj) {
;                     const int c = cb0 + 32 * bj;
;                     const f32x4 p0 = *(const f32x4*)(k_a + c), p1 = *(const f32x4*)(k_a + c + 4);
;                     f32x4 ko0, ko1, ao0, ao1, bo0, bo1;
; #pragma unroll
;                     for (int e = 0; e < 4; ++e) {
;                         ko0[e] = kv[bj][e] * (1.0f + (a[bj][e] - 1.0f) * p0[e]); ko1[e] = kv[bj][4 + e] * (1.0f + (a[bj][4 + e] - 1.0f) * p1[e]);
;                         const float n0_ = kk[bj][e] * inv, n1_ = kk[bj][4 + e] * inv;
;                         ao0[e] = -n0_; ao1[e] = -n1_; bo0[e] = n0_ * a[bj][e]; bo1[e] = n1_ * a[bj][4 + e];
;                     }
;                     *(u32x4*)(C1 + row * LDC1 + 2048 + c) = pack8(ko0, ko1);
;                     *(u32x4*)(AA + row * DM + c) = pack8(ao0, ao1);
;                     *(u32x4*)(Ab + row * DM + c) = pack8(bo0, bo1);
;                 }
	v_add_f32_e32 v130, v130, v131
	v_cmp_gt_f32_e32 vcc, s4, v130
	v_mul_f32_e32 v131, 0x4f800000, v130
	s_nop 0
	v_cndmask_b32_e32 v130, v130, v131, vcc
	v_sqrt_f32_e32 v131, v130
	s_nop 0
	v_add_u32_e32 v134, -1, v131
	v_fma_f32 v135, -v134, v131, v130
	v_cmp_ge_f32_e64 s[0:1], 0, v135
	v_add_u32_e32 v135, 1, v131
	s_nop 0
	v_cndmask_b32_e64 v134, v131, v134, s[0:1]
	v_fma_f32 v131, -v135, v131, v130
	v_cmp_lt_f32_e64 s[0:1], 0, v131
	s_nop 1
	v_cndmask_b32_e64 v131, v134, v135, s[0:1]
	v_mul_f32_e32 v134, 0x37800000, v131
	v_cndmask_b32_e32 v131, v131, v134, vcc
	v_cmp_class_f32_e32 vcc, v130, v244
	s_nop 1
	v_cndmask_b32_e32 v130, v131, v130, vcc
	v_max_f32_e32 v130, 0x2b8cbccc, v130
	v_div_scale_f32 v131, s[0:1], v130, v130, 1.0
	v_rcp_f32_e32 v134, v131
	s_nop 0
	v_fma_f32 v135, -v131, v134, 1.0
	v_fmac_f32_e32 v134, v135, v134
	v_div_scale_f32 v135, vcc, 1.0, v130, 1.0
	v_mul_f32_e32 v136, v135, v134
	v_fma_f32 v137, -v131, v136, v135
	v_fmac_f32_e32 v136, v137, v134
	v_fma_f32 v131, -v131, v136, v135
	v_div_fmas_f32 v131, v131, v134, v136
	v_div_fixup_f32 v134, v131, v130, 1.0
	v_pk_mul_f32 v[140:141], v[118:119], v[134:135] op_sel_hi:[1,0]
	v_pk_mul_f32 v[136:137], v[116:117], v[134:135] op_sel_hi:[1,0]
	v_cvt_pk_f16_f32 v117, v140, v141
	v_cvt_pk_f16_f32 v116, v136, v137
	v_xor_b32_e32 v118, 0x8000, v117
	v_xor_b32_sdwa v117, s63, v117 dst_sel:DWORD dst_unused:UNUSED_PAD src0_sel:DWORD src1_sel:WORD_1
	v_pk_mul_f32 v[120:121], v[120:121], v[134:135] op_sel_hi:[1,0]
	v_pk_mul_f32 v[132:133], v[132:133], v[134:135] op_sel_hi:[1,0]
	v_perm_b32 v117, v117, v118, s33
	v_xor_b32_e32 v118, 0x8000, v116
	v_xor_b32_sdwa v116, s63, v116 dst_sel:DWORD dst_unused:UNUSED_PAD src0_sel:DWORD src1_sel:WORD_1
	v_perm_b32 v116, v116, v118, s33
	v_pk_add_f32 v[118:119], v[120:121], 0 neg_lo:[1,1] neg_hi:[1,1]
	v_pk_add_f32 v[130:131], v[132:133], 0 neg_lo:[1,1] neg_hi:[1,1]
	v_cvt_pk_f16_f32 v118, v118, v119
	v_cvt_pk_f16_f32 v119, v130, v131
	v_lshl_add_u64 v[130:131], s[10:11], 0, v[184:185]
	v_lshl_add_u64 v[130:131], v[130:131], 0, v[152:153]
	global_store_dwordx4 v[130:131], v[116:119], off
	v_fma_mixlo_f16 v135, v196, v136, 0
	v_mul_f32_e32 v159, v162, v134
	v_pk_mov_b32 v[116:117], v[196:197], v[138:139] op_sel:[1,0]
	v_pk_mov_b32 v[118:119], v[136:137], v[140:141] op_sel:[1,0]
	v_pk_mov_b32 v[136:137], v[140:141], v[120:121] op_sel:[1,0]
	v_pk_mul_f32 v[116:117], v[116:117], v[118:119]
	v_pk_mov_b32 v[118:119], v[138:139], v[192:193] op_sel:[1,0]
	v_cvt_pk_f16_f32 v117, v116, v117
	v_pk_mul_f32 v[118:119], v[118:119], v[136:137]
	v_pack_b32_f16 v116, v135, v117
	v_cvt_pk_f16_f32 v135, v118, v119
	v_pk_mov_b32 v[118:119], v[192:193], v[114:115] op_sel:[1,0]
	v_pk_mov_b32 v[120:121], v[120:121], v[132:133] op_sel:[1,0]
	v_alignbit_b32 v117, v135, v117, 16
	v_pk_mul_f32 v[118:119], v[118:119], v[120:121]
	v_pk_add_f32 v[136:137], v[182:183], 1.0 op_sel_hi:[1,0]
	v_cvt_pk_f16_f32 v114, v118, v119
	v_lshrrev_b32_e32 v119, 16, v114
	v_alignbit_b32 v118, v114, v135, 16
	v_fma_mixhi_f16 v119, v115, v133, 0
	v_lshl_add_u64 v[114:115], s[2:3], 0, v[184:185]
	v_lshl_add_u64 v[132:133], v[114:115], 0, v[152:153]
	global_store_dwordx4 v[132:133], v[116:119], off
	global_load_dwordx4 v[114:117], v[126:127], off offset:144
	s_nop 0
	global_load_dwordx4 v[118:121], v[126:127], off offset:128
	v_div_scale_f32 v138, s[0:1], v137, v137, 1.0
	v_rcp_f32_e32 v139, v138
	v_mul_f32_e32 v135, v165, v134
	v_fma_f32 v140, -v138, v139, 1.0
	v_fmac_f32_e32 v139, v140, v139
	v_div_scale_f32 v140, vcc, 1.0, v137, 1.0
	v_mul_f32_e32 v141, v140, v139
	v_fma_f32 v182, -v138, v141, v140
	v_fmac_f32_e32 v141, v182, v139
	v_fma_f32 v138, -v138, v141, v140
	v_div_fmas_f32 v138, v138, v139, v141
	v_div_fixup_f32 v137, v138, v137, 1.0
	v_div_scale_f32 v138, s[0:1], v136, v136, 1.0
	v_rcp_f32_e32 v139, v138
	s_nop 0
	v_fma_f32 v140, -v138, v139, 1.0
	v_fmac_f32_e32 v139, v140, v139
	v_div_scale_f32 v140, vcc, 1.0, v136, 1.0
	v_mul_f32_e32 v141, v140, v139
	v_fma_f32 v182, -v138, v141, v140
	v_fmac_f32_e32 v141, v182, v139
	v_fma_f32 v138, -v138, v141, v140
	v_div_fmas_f32 v138, v138, v139, v141
	v_div_fixup_f32 v136, v138, v136, 1.0
	v_pk_add_f32 v[138:139], v[136:137], -1.0 op_sel_hi:[1,0]
	s_waitcnt vmcnt(0)
;     __device__ __forceinline__ void body_a(const f32x4 (&acc)[2][2][4][2], int row0, int cb0) const {
;     ...
;                 float a[2][8], kv[2][8], kk[2][8]; float ss = 0.f;
; #pragma unroll
;                 for (int bj = 0; bj < 2; ++bj) {
;                     const int c = cb0 + 32 * bj;
;                     const f32x4 b0 = *(const f32x4*)(a0 + c), b1 = *(const f32x4*)(a0 + c + 4), q0 = *(const f32x4*)(k_k + c), q1 = *(const f32x4*)(k_k + c + 4);
;                     const h16x8 kh = *(const h16x8*)(C1 + row * LDC1 + 2048 + c);
;     ...
;                 for (int bj = 0; bj < 2; ++bj) {
;                     const int c = cb0 + 32 * bj;
;                     const f32x4 p0 = *(const f32x4*)(k_a + c), p1 = *(const f32x4*)(k_a + c + 4);
;                     f32x4 ko0, ko1, ao0, ao1, bo0, bo1;
; #pragma unroll
;                     for (int e = 0; e < 4; ++e) {
;                         ko0[e] = kv[bj][e] * (1.0f + (a[bj][e] - 1.0f) * p0[e]); ko1[e] = kv[bj][4 + e] * (1.0f + (a[bj][4 + e] - 1.0f) * p1[e]);
;                         const float n0_ = kk[bj][e] * inv, n1_ = kk[bj][4 + e] * inv;
;                         ao0[e] = -n0_; ao1[e] = -n1_; bo0[e] = n0_ * a[bj][e]; bo1[e] = n1_ * a[bj][4 + e];
;                     }
;                     *(u32x4*)(C1 + row * LDC1 + 2048 + c) = pack8(ko0, ko1);
;                     *(u32x4*)(AA + row * DM + c) = pack8(ao0, ao1);
;                     *(u32x4*)(Ab + row * DM + c) = pack8(bo0, bo1);
;                 }
	v_pk_fma_f32 v[118:119], v[138:139], v[118:119], 1.0 op_sel_hi:[1,1,0]
	s_nop 0
	v_pk_mul_f32 v[118:119], v[118:119], v[180:181]
	v_pk_add_f32 v[138:139], v[178:179], 1.0 op_sel_hi:[1,0]
	v_cvt_pk_f16_f32 v118, v118, v119
	v_div_scale_f32 v119, s[0:1], v139, v139, 1.0
	v_rcp_f32_e32 v140, v119
	s_nop 0
	v_fma_f32 v141, -v119, v140, 1.0
	v_fmac_f32_e32 v140, v141, v140
	v_div_scale_f32 v141, vcc, 1.0, v139, 1.0
	v_mul_f32_e32 v178, v141, v140
	v_fma_f32 v179, -v119, v178, v141
	v_fmac_f32_e32 v178, v179, v140
	v_fma_f32 v119, -v119, v178, v141
	v_div_fmas_f32 v119, v119, v140, v178
	v_div_fixup_f32 v139, v119, v139, 1.0
	v_div_scale_f32 v119, s[0:1], v138, v138, 1.0
	v_rcp_f32_e32 v140, v119
	s_nop 0
	v_fma_f32 v141, -v119, v140, 1.0
	v_fmac_f32_e32 v140, v141, v140
	v_div_scale_f32 v141, vcc, 1.0, v138, 1.0
	v_mul_f32_e32 v178, v141, v140
	v_fma_f32 v179, -v119, v178, v141
	v_fmac_f32_e32 v178, v179, v140
	v_fma_f32 v119, -v119, v178, v141
	v_div_fmas_f32 v119, v119, v140, v178
	v_div_fixup_f32 v138, v119, v138, 1.0
	v_pk_add_f32 v[140:141], v[138:139], -1.0 op_sel_hi:[1,0]
	s_nop 0
	v_pk_fma_f32 v[120:121], v[140:141], v[120:121], 1.0 op_sel_hi:[1,1,0]
	s_nop 0
	v_pk_mul_f32 v[120:121], v[120:121], v[176:177]
	s_nop 0
	v_cvt_pk_f16_f32 v119, v120, v121
	v_pk_add_f32 v[120:121], v[174:175], 1.0 op_sel_hi:[1,0]
	s_nop 0
	v_div_scale_f32 v140, s[0:1], v121, v121, 1.0
	v_rcp_f32_e32 v141, v140
	s_nop 0
	v_fma_f32 v174, -v140, v141, 1.0
	v_fmac_f32_e32 v141, v174, v141
	v_div_scale_f32 v174, vcc, 1.0, v121, 1.0
	v_mul_f32_e32 v175, v174, v141
	v_fma_f32 v176, -v140, v175, v174
	v_fmac_f32_e32 v175, v176, v141
	v_fma_f32 v140, -v140, v175, v174
	v_div_fmas_f32 v140, v140, v141, v175
	v_div_fixup_f32 v141, v140, v121, 1.0
	v_div_scale_f32 v121, s[0:1], v120, v120, 1.0
	v_rcp_f32_e32 v140, v121
	s_nop 0
	v_fma_f32 v174, -v121, v140, 1.0
	v_fmac_f32_e32 v140, v174, v140
	v_div_scale_f32 v174, vcc, 1.0, v120, 1.0
	v_mul_f32_e32 v175, v174, v140
	v_fma_f32 v176, -v121, v175, v174
	v_fmac_f32_e32 v175, v176, v140
	v_fma_f32 v121, -v121, v175, v174
	v_div_fmas_f32 v121, v121, v140, v175
	v_div_fixup_f32 v140, v121, v120, 1.0
	v_pk_add_f32 v[120:121], v[140:141], -1.0 op_sel_hi:[1,0]
	s_nop 0
	v_pk_fma_f32 v[114:115], v[120:121], v[114:115], 1.0 op_sel_hi:[1,1,0]
	s_nop 0
	v_pk_mul_f32 v[114:115], v[114:115], v[172:173]
	s_nop 0
	v_cvt_pk_f16_f32 v120, v114, v115
	v_pk_add_f32 v[114:115], v[170:171], 1.0 op_sel_hi:[1,0]
	s_nop 0
	v_div_scale_f32 v121, s[0:1], v115, v115, 1.0
	v_rcp_f32_e32 v170, v121
	s_nop 0
	v_fma_f32 v171, -v121, v170, 1.0
	v_fmac_f32_e32 v170, v171, v170
	v_div_scale_f32 v171, vcc, 1.0, v115, 1.0
	v_mul_f32_e32 v172, v171, v170
	v_fma_f32 v173, -v121, v172, v171
	v_fmac_f32_e32 v172, v173, v170
	v_fma_f32 v121, -v121, v172, v171
	v_div_fmas_f32 v121, v121, v170, v172
	v_div_fixup_f32 v171, v121, v115, 1.0
	v_div_scale_f32 v115, s[0:1], v114, v114, 1.0
	v_rcp_f32_e32 v121, v115
	s_nop 0
	v_fma_f32 v170, -v115, v121, 1.0
	v_fmac_f32_e32 v121, v170, v121
	v_div_scale_f32 v170, vcc, 1.0, v114, 1.0
	v_mul_f32_e32 v172, v170, v121
	v_fma_f32 v173, -v115, v172, v170
	v_fmac_f32_e32 v172, v173, v121
	v_fma_f32 v115, -v115, v172, v170
	v_div_fmas_f32 v115, v115, v121, v172
	v_div_fixup_f32 v170, v115, v114, 1.0
	v_pk_add_f32 v[114:115], v[170:171], -1.0 op_sel_hi:[1,0]
	s_nop 0
	v_pk_fma_f32 v[114:115], v[114:115], v[116:117], 1.0 op_sel_hi:[1,1,0]
	v_cvt_f16_f32_e64 v116, -v159
	v_pk_mul_f32 v[114:115], v[114:115], v[168:169]
	s_nop 0
	v_cvt_pk_f16_f32 v121, v114, v115
	v_pk_mov_b32 v[114:115], v[162:163], v[166:167] op_sel:[1,0]
	global_store_dwordx4 v[122:123], v[118:121], off
	s_nop 1
	v_pk_mul_f32 v[118:119], v[114:115], v[134:135] op_sel_hi:[1,0]
	s_nop 0
	v_cvt_pk_f16_f32 v115, v118, v119
	v_pack_b32_f16 v114, v116, -v115
	v_pk_mov_b32 v[116:117], v[166:167], v[124:125] op_sel:[1,0]
	v_xor_b32_sdwa v115, s63, v115 dst_sel:DWORD dst_unused:UNUSED_PAD src0_sel:DWORD src1_sel:WORD_1
	v_pk_mul_f32 v[120:121], v[116:117], v[134:135] op_sel_hi:[1,0]
	s_nop 0
	v_cvt_pk_f16_f32 v116, v120, v121
	v_xor_b32_e32 v117, 0x8000, v116
	v_perm_b32 v115, v117, v115, s33
	v_xor_b32_sdwa v162, s63, v116 dst_sel:DWORD dst_unused:UNUSED_PAD src0_sel:DWORD src1_sel:WORD_1
	v_pk_mov_b32 v[116:117], v[124:125], v[164:165] op_sel:[1,0]
	v_cvt_f16_f32_e64 v124, -v135
	v_pk_mul_f32 v[122:123], v[116:117], v[134:135] op_sel_hi:[1,0]
	s_nop 0
	v_cvt_pk_f16_f32 v117, v122, v123
	v_xor_b32_e32 v116, 0x8000, v117
	v_xor_b32_sdwa v117, s63, v117 dst_sel:DWORD dst_unused:UNUSED_PAD src0_sel:DWORD src1_sel:WORD_1
	v_perm_b32 v116, v116, v162, s33
	v_perm_b32 v117, v124, v117, s33
	global_store_dwordx4 v[130:131], v[114:117], off offset:64
	s_nop 1
	v_pk_mov_b32 v[114:115], v[136:137], v[138:139] op_sel:[1,0]
	v_fma_mixlo_f16 v116, v136, v159, 0
	v_pk_mul_f32 v[114:115], v[114:115], v[118:119]
	s_nop 0
	v_cvt_pk_f16_f32 v115, v114, v115
	v_pack_b32_f16 v114, v116, v115
	v_pk_mov_b32 v[116:117], v[138:139], v[140:141] op_sel:[1,0]
	s_nop 0
	v_pk_mul_f32 v[116:117], v[116:117], v[120:121]
	s_nop 0
	v_cvt_pk_f16_f32 v118, v116, v117
	v_pk_mov_b32 v[116:117], v[140:141], v[170:171] op_sel:[1,0]
	v_alignbit_b32 v115, v118, v115, 16
	v_pk_mul_f32 v[116:117], v[116:117], v[122:123]
	s_nop 0
	v_cvt_pk_f16_f32 v117, v116, v117
	v_alignbit_b32 v116, v117, v118, 16
	v_lshrrev_b32_e32 v117, 16, v117
	v_fma_mixhi_f16 v117, v171, v135, 0
	global_store_dwordx4 v[132:133], v[114:117], off offset:64
	v_or_b32_e32 v162, 16, v158
	s_nop 0
	v_mad_i64_i32 v[114:115], s[0:1], v162, s5, v[160:161]
	v_lshl_add_u64 v[138:139], v[114:115], 0, s[6:7]
	global_load_dwordx4 v[130:133], v[154:155], off offset:16
	global_load_dwordx4 v[134:137], v[154:155], off
	global_load_dwordx4 v[114:117], v[156:157], off offset:16
	global_load_dwordx4 v[118:121], v[156:157], off
	v_lshl_add_u64 v[170:171], v[138:139], 0, v[152:153]
	global_load_dwordx4 v[122:125], v[170:171], off
	v_ashrrev_i32_e32 v163, 31, v162
	s_waitcnt vmcnt(4)
; __device__ __forceinline__ float sigmoidf_(float x) { return 1.0f / (1.0f + __expf(-x)); }
;     __device__ __forceinline__ void body_a(const f32x4 (&acc)[2][2][4][2], int row0, int cb0) const {
;     ...
;             for (int m = 0; m < 4; ++m) {
;                 const size_t row = (size_t)(row0 + ai * 128 + m * 16);
;                 asm volatile("" ::: "memory");
;                 float a[2][8], kv[2][8], kk[2][8]; float ss = 0.f;
; #pragma unroll
;                 for (int bj = 0; bj < 2; ++bj) {
;                     const int c = cb0 + 32 * bj;
;                     const f32x4 b0 = *(const f32x4*)(a0 + c), b1 = *(const f32x4*)(a0 + c + 4), q0 = *(const f32x4*)(k_k + c), q1 = *(const f32x4*)(k_k + c + 4);
;                     const h16x8 kh = *(const h16x8*)(C1 + row * LDC1 + 2048 + c);
; #pragma unroll
;                     for (int e = 0; e < 4; ++e) {
;                         a[bj][e] = sigmoidf_(acc[ai][bj][m][0][e] + b0[e]); a[bj][4 + e] = sigmoidf_(acc[ai][bj][m][1][e] + b1[e]);
;                         kv[bj][e] = (float)kh[e]; kv[bj][4 + e] = (float)kh[4 + e];
;                         kk[bj][e] = kv[bj][e] * q0[e]; kk[bj][4 + e] = kv[bj][4 + e] * q1[e];
;                         ss += kk[bj][e] * kk[bj][e] + kk[bj][4 + e] * kk[bj][4 + e];
;                     }
;                 }
;                 ss += __shfl_xor(ss, 16); ss += __shfl_xor(ss, 32);
;                 const float inv = 1.0f / fmaxf(sqrtf(ss), 1e-12f);
	v_add_f32_e32 v106, v106, v130
	v_mul_f32_e32 v106, 0xbfb8aa3b, v106
	v_exp_f32_e32 v178, v106
	s_waitcnt vmcnt(3)
	v_add_f32_e32 v106, v111, v135
	v_mul_f32_e32 v106, 0xbfb8aa3b, v106
	v_exp_f32_e32 v181, v106
	v_add_f32_e32 v106, v107, v131
	v_mul_f32_e32 v106, 0xbfb8aa3b, v106
	v_exp_f32_e32 v179, v106
	v_add_f32_e32 v106, v112, v136
	v_mul_f32_e32 v106, 0xbfb8aa3b, v106
	v_exp_f32_e32 v182, v106
	v_add_f32_e32 v106, v108, v132
	v_mul_f32_e32 v106, 0xbfb8aa3b, v106
	v_exp_f32_e32 v172, v106
	v_add_f32_e32 v106, v113, v137
	v_mul_f32_e32 v106, 0xbfb8aa3b, v106
	v_exp_f32_e32 v183, v106
	v_add_f32_e32 v106, v109, v133
	v_add_f32_e32 v110, v110, v134
	v_mul_f32_e32 v106, 0xbfb8aa3b, v106
	v_mul_f32_e32 v110, 0xbfb8aa3b, v110
	v_exp_f32_e32 v173, v106
	v_lshl_add_u64 v[106:107], v[138:139], 0, v[128:129]
	v_exp_f32_e32 v180, v110
	global_load_dwordx4 v[110:113], v[154:155], off offset:144
	global_load_dwordx4 v[130:133], v[154:155], off offset:128
	global_load_dwordx4 v[174:177], v[156:157], off offset:144
	global_load_dwordx4 v[184:187], v[156:157], off offset:128
	global_load_dwordx4 v[188:191], v[106:107], off
	v_pk_add_f32 v[182:183], v[182:183], 1.0 op_sel_hi:[1,0]
	v_pk_add_f32 v[180:181], v[180:181], 1.0 op_sel_hi:[1,0]
	s_waitcnt vmcnt(4)
	v_add_f32_e32 v98, v98, v110
	v_mul_f32_e32 v98, 0xbfb8aa3b, v98
	v_exp_f32_e32 v138, v98
	s_waitcnt vmcnt(3)
	v_add_f32_e32 v98, v103, v131
	s_waitcnt vmcnt(0)
	v_cvt_f32_f16_e32 v136, v190
	v_cvt_f32_f16_sdwa v137, v190 dst_sel:DWORD dst_unused:UNUSED_PAD src0_sel:WORD_1
	v_cvt_f32_f16_e32 v166, v188
	v_cvt_f32_f16_sdwa v167, v188 dst_sel:DWORD dst_unused:UNUSED_PAD src0_sel:WORD_1
	v_mul_f32_e32 v98, 0xbfb8aa3b, v98
	v_exp_f32_e32 v169, v98
	v_add_f32_e32 v98, v99, v111
	v_mul_f32_e32 v98, 0xbfb8aa3b, v98
	v_pk_mul_f32 v[108:109], v[174:175], v[136:137]
	v_exp_f32_e32 v139, v98
	v_pk_mul_f32 v[110:111], v[184:185], v[166:167]
	v_pk_mul_f32 v[98:99], v[108:109], v[108:109]
	v_cvt_f32_f16_e32 v140, v189
	v_pk_fma_f32 v[174:175], v[110:111], v[110:111], v[98:99]
	v_add_f32_e32 v98, v104, v132
	v_mul_f32_e32 v98, 0xbfb8aa3b, v98
	v_exp_f32_e32 v164, v98
	v_add_f32_e32 v98, v100, v112
	v_mul_f32_e32 v98, 0xbfb8aa3b, v98
	v_exp_f32_e32 v134, v98
	v_add_f32_e32 v98, v105, v133
	v_cvt_f32_f16_e32 v132, v191
	v_cvt_f32_f16_sdwa v133, v191 dst_sel:DWORD dst_unused:UNUSED_PAD src0_sel:WORD_1
	v_cvt_f32_f16_sdwa v141, v189 dst_sel:DWORD dst_unused:UNUSED_PAD src0_sel:WORD_1
	v_mul_f32_e32 v98, 0xbfb8aa3b, v98
	v_exp_f32_e32 v165, v98
	v_add_f32_e32 v98, v101, v113
	v_add_f32_e32 v102, v102, v130
	v_mul_f32_e32 v98, 0xbfb8aa3b, v98
	v_pk_mul_f32 v[112:113], v[176:177], v[132:133]
	v_mul_f32_e32 v102, 0xbfb8aa3b, v102
	v_exp_f32_e32 v135, v98
	v_pk_mul_f32 v[130:131], v[186:187], v[140:141]
	v_pk_mul_f32 v[98:99], v[112:113], v[112:113]
	v_exp_f32_e32 v168, v102
	v_pk_fma_f32 v[176:177], v[130:131], v[130:131], v[98:99]
	global_load_dwordx4 v[98:101], v[126:127], off offset:16
	global_load_dwordx4 v[102:105], v[126:127], off
	v_cvt_f32_f16_e32 v184, v122
	v_cvt_f32_f16_sdwa v185, v122 dst_sel:DWORD dst_unused:UNUSED_PAD src0_sel:WORD_1
	v_div_scale_f32 v122, s[0:1], v181, v181, 1.0
	v_rcp_f32_e32 v159, v122
	s_nop 0
	v_fma_f32 v186, -v122, v159, 1.0
	v_fmac_f32_e32 v159, v186, v159
	v_div_scale_f32 v186, vcc, 1.0, v181, 1.0
	v_mul_f32_e32 v187, v186, v159
	v_fma_f32 v188, -v122, v187, v186
	v_fmac_f32_e32 v187, v188, v159
	v_fma_f32 v122, -v122, v187, v186
	v_div_fmas_f32 v122, v122, v159, v187
	v_div_fixup_f32 v181, v122, v181, 1.0
	v_div_scale_f32 v122, s[0:1], v180, v180, 1.0
	v_rcp_f32_e32 v159, v122
	s_nop 0
	v_fma_f32 v186, -v122, v159, 1.0
	v_fmac_f32_e32 v159, v186, v159
	v_div_scale_f32 v186, vcc, 1.0, v180, 1.0
	v_mul_f32_e32 v187, v186, v159
	v_fma_f32 v188, -v122, v187, v186
	v_fmac_f32_e32 v187, v188, v159
	v_fma_f32 v122, -v122, v187, v186
	v_div_fmas_f32 v122, v122, v159, v187
	v_div_fixup_f32 v180, v122, v180, 1.0
	v_pk_add_f32 v[186:187], v[180:181], -1.0 op_sel_hi:[1,0]
	v_cvt_f32_f16_e32 v122, v123
	v_cvt_f32_f16_sdwa v123, v123 dst_sel:DWORD dst_unused:UNUSED_PAD src0_sel:WORD_1
	s_waitcnt vmcnt(0)
	v_pk_fma_f32 v[102:103], v[186:187], v[102:103], 1.0 op_sel_hi:[1,1,0]
	s_nop 0
	v_pk_mul_f32 v[102:103], v[102:103], v[184:185]
	s_nop 0
	v_cvt_pk_f16_f32 v102, v102, v103
	v_div_scale_f32 v103, s[0:1], v183, v183, 1.0
	v_rcp_f32_e32 v159, v103
	s_nop 0
	v_fma_f32 v186, -v103, v159, 1.0
	v_fmac_f32_e32 v159, v186, v159
	v_div_scale_f32 v186, vcc, 1.0, v183, 1.0
	v_mul_f32_e32 v187, v186, v159
	v_fma_f32 v188, -v103, v187, v186
	v_fmac_f32_e32 v187, v188, v159
	v_fma_f32 v103, -v103, v187, v186
	v_div_fmas_f32 v103, v103, v159, v187
	v_div_fixup_f32 v183, v103, v183, 1.0
	v_div_scale_f32 v103, s[0:1], v182, v182, 1.0
	v_rcp_f32_e32 v159, v103
	s_nop 0
	v_fma_f32 v186, -v103, v159, 1.0
	v_fmac_f32_e32 v159, v186, v159
	v_div_scale_f32 v186, vcc, 1.0, v182, 1.0
	v_mul_f32_e32 v187, v186, v159
	v_fma_f32 v188, -v103, v187, v186
	v_fmac_f32_e32 v187, v188, v159
	v_fma_f32 v103, -v103, v187, v186
	v_div_fmas_f32 v103, v103, v159, v187
	v_div_fixup_f32 v182, v103, v182, 1.0
	v_pk_add_f32 v[186:187], v[182:183], -1.0 op_sel_hi:[1,0]
	s_nop 0
	v_pk_fma_f32 v[104:105], v[186:187], v[104:105], 1.0 op_sel_hi:[1,1,0]
	v_cvt_f32_f16_e32 v186, v124
	v_pk_mul_f32 v[104:105], v[104:105], v[122:123]
	v_cvt_f32_f16_sdwa v187, v124 dst_sel:DWORD dst_unused:UNUSED_PAD src0_sel:WORD_1
	v_cvt_pk_f16_f32 v103, v104, v105
	v_pk_add_f32 v[104:105], v[178:179], 1.0 op_sel_hi:[1,0]
	s_nop 0
	v_div_scale_f32 v124, s[0:1], v105, v105, 1.0
	v_rcp_f32_e32 v159, v124
	s_nop 0
	v_fma_f32 v178, -v124, v159, 1.0
; __device__ __forceinline__ float sigmoidf_(float x) { return 1.0f / (1.0f + __expf(-x)); }
;     __device__ __forceinline__ void body_a(const f32x4 (&acc)[2][2][4][2], int row0, int cb0) const {
;     ...
;                         a[bj][e] = sigmoidf_(acc[ai][bj][m][0][e] + b0[e]); a[bj][4 + e] = sigmoidf_(acc[ai][bj][m][1][e] + b1[e]);
;                         kv[bj][e] = (float)kh[e]; kv[bj][4 + e] = (float)kh[4 + e];
;                         kk[bj][e] = kv[bj][e] * q0[e]; kk[bj][4 + e] = kv[bj][4 + e] * q1[e];
;                         ss += kk[bj][e] * kk[bj][e] + kk[bj][4 + e] * kk[bj][4 + e];
;                     }
;                 }
;                 ss += __shfl_xor(ss, 16); ss += __shfl_xor(ss, 32);
;                 const float inv = 1.0f / fmaxf(sqrtf(ss), 1e-12f);
; #pragma unroll
;                 for (int bj = 0; bj < 2; ++bj) {
;                     const int c = cb0 + 32 * bj;
;                     const f32x4 p0 = *(const f32x4*)(k_a + c), p1 = *(const f32x4*)(k_a + c + 4);
;                     f32x4 ko0, ko1, ao0, ao1, bo0, bo1;
; #pragma unroll
;                     for (int e = 0; e < 4; ++e) {
;                         ko0[e] = kv[bj][e] * (1.0f + (a[bj][e] - 1.0f) * p0[e]); ko1[e] = kv[bj][4 + e] * (1.0f + (a[bj][4 + e] - 1.0f) * p1[e]);
;                         const float n0_ = kk[bj][e] * inv, n1_ = kk[bj][4 + e] * inv;
;                         ao0[e] = -n0_; ao1[e] = -n1_; bo0[e] = n0_ * a[bj][e]; bo1[e] = n1_ * a[bj][4 + e];
;                     }
;                     *(u32x4*)(C1 + row * LDC1 + 2048 + c) = pack8(ko0, ko1);
;                     *(u32x4*)(AA + row * DM + c) = pack8(ao0, ao1);
;                     *(u32x4*)(Ab + row * DM + c) = pack8(bo0, bo1);
;                 }
	v_fmac_f32_e32 v159, v178, v159
	v_div_scale_f32 v178, vcc, 1.0, v105, 1.0
	v_mul_f32_e32 v179, v178, v159
	v_fma_f32 v188, -v124, v179, v178
	v_fmac_f32_e32 v179, v188, v159
	v_fma_f32 v124, -v124, v179, v178
	v_div_fmas_f32 v124, v124, v159, v179
	v_div_fixup_f32 v179, v124, v105, 1.0
	v_div_scale_f32 v105, s[0:1], v104, v104, 1.0
	v_rcp_f32_e32 v124, v105
	s_nop 0
	v_fma_f32 v159, -v105, v124, 1.0
	v_fmac_f32_e32 v124, v159, v124
	v_div_scale_f32 v159, vcc, 1.0, v104, 1.0
	v_mul_f32_e32 v178, v159, v124
	v_fma_f32 v188, -v105, v178, v159
	v_fmac_f32_e32 v178, v188, v124
	v_fma_f32 v105, -v105, v178, v159
	v_div_fmas_f32 v105, v105, v124, v178
	v_div_fixup_f32 v178, v105, v104, 1.0
	v_pk_add_f32 v[104:105], v[178:179], -1.0 op_sel_hi:[1,0]
	v_cvt_f32_f16_e32 v124, v125
	v_pk_fma_f32 v[98:99], v[104:105], v[98:99], 1.0 op_sel_hi:[1,1,0]
	v_cvt_f32_f16_sdwa v125, v125 dst_sel:DWORD dst_unused:UNUSED_PAD src0_sel:WORD_1
	v_pk_mul_f32 v[98:99], v[98:99], v[186:187]
	v_pk_mul_f32 v[116:117], v[116:117], v[124:125]
	v_cvt_pk_f16_f32 v104, v98, v99
	v_pk_add_f32 v[98:99], v[172:173], 1.0 op_sel_hi:[1,0]
	s_nop 0
	v_div_scale_f32 v105, s[0:1], v99, v99, 1.0
	v_rcp_f32_e32 v159, v105
	s_nop 0
	v_fma_f32 v172, -v105, v159, 1.0
	v_fmac_f32_e32 v159, v172, v159
	v_div_scale_f32 v172, vcc, 1.0, v99, 1.0
	v_mul_f32_e32 v173, v172, v159
	v_fma_f32 v188, -v105, v173, v172
	v_fmac_f32_e32 v173, v188, v159
	v_fma_f32 v105, -v105, v173, v172
	v_div_fmas_f32 v105, v105, v159, v173
	v_div_fixup_f32 v99, v105, v99, 1.0
	v_div_scale_f32 v105, s[0:1], v98, v98, 1.0
	v_rcp_f32_e32 v159, v105
	s_nop 0
	v_fma_f32 v172, -v105, v159, 1.0
	v_fmac_f32_e32 v159, v172, v159
	v_div_scale_f32 v172, vcc, 1.0, v98, 1.0
	v_mul_f32_e32 v173, v172, v159
	v_fma_f32 v188, -v105, v173, v172
	v_fmac_f32_e32 v173, v188, v159
	v_fma_f32 v105, -v105, v173, v172
	v_div_fmas_f32 v105, v105, v159, v173
	v_div_fixup_f32 v98, v105, v98, 1.0
	v_pk_add_f32 v[172:173], v[98:99], -1.0 op_sel_hi:[1,0]
	s_nop 0
	v_pk_fma_f32 v[100:101], v[172:173], v[100:101], 1.0 op_sel_hi:[1,1,0]
	s_nop 0
	v_pk_mul_f32 v[100:101], v[100:101], v[124:125]
	v_lshlrev_b64 v[124:125], 12, v[162:163]
	v_cvt_pk_f16_f32 v105, v100, v101
	global_store_dwordx4 v[170:171], v[102:105], off
	v_pk_mul_f32 v[100:101], v[118:119], v[184:185]
	v_pk_mul_f32 v[118:119], v[116:117], v[116:117]
	v_pk_mul_f32 v[104:105], v[114:115], v[186:187]
	v_pk_mul_f32 v[102:103], v[120:121], v[122:123]
	v_pk_mul_f32 v[114:115], v[104:105], v[104:105]
	v_pk_fma_f32 v[118:119], v[102:103], v[102:103], v[118:119]
	v_pk_fma_f32 v[114:115], v[100:101], v[100:101], v[114:115]
	s_nop 0
	v_add_f32_e32 v114, v114, v115
	v_add_f32_e32 v114, v118, v114
	v_add_f32_e32 v114, v119, v114
	v_add_f32_e32 v114, v114, v174
	v_add_f32_e32 v114, v175, v114
	v_add_f32_e32 v114, v176, v114
	v_add_f32_e32 v114, v177, v114
	ds_bpermute_b32 v115, v206, v114
	s_waitcnt lgkmcnt(0)
	v_add_f32_e32 v114, v114, v115
	ds_bpermute_b32 v115, v207, v114
	s_waitcnt lgkmcnt(0)
	v_add_f32_e32 v114, v114, v115
	v_cmp_gt_f32_e32 vcc, s4, v114
	v_mul_f32_e32 v115, 0x4f800000, v114
	s_nop 0
	v_cndmask_b32_e32 v114, v114, v115, vcc
	v_sqrt_f32_e32 v115, v114
	s_nop 0
	v_add_u32_e32 v118, -1, v115
	v_fma_f32 v119, -v118, v115, v114
	v_cmp_ge_f32_e64 s[0:1], 0, v119
	v_add_u32_e32 v119, 1, v115
	s_nop 0
	v_cndmask_b32_e64 v118, v115, v118, s[0:1]
	v_fma_f32 v115, -v119, v115, v114
	v_cmp_lt_f32_e64 s[0:1], 0, v115
	s_nop 1
	v_cndmask_b32_e64 v115, v118, v119, s[0:1]
	v_mul_f32_e32 v118, 0x37800000, v115
	v_cndmask_b32_e32 v115, v115, v118, vcc
	v_cmp_class_f32_e32 vcc, v114, v244
	s_nop 1
	v_cndmask_b32_e32 v114, v115, v114, vcc
	v_max_f32_e32 v114, 0x2b8cbccc, v114
	v_div_scale_f32 v115, s[0:1], v114, v114, 1.0
	v_rcp_f32_e32 v118, v115
	s_nop 0
	v_fma_f32 v119, -v115, v118, 1.0
	v_fmac_f32_e32 v118, v119, v118
	v_div_scale_f32 v119, vcc, 1.0, v114, 1.0
	v_mul_f32_e32 v120, v119, v118
	v_fma_f32 v121, -v115, v120, v119
	v_fmac_f32_e32 v120, v121, v118
	v_fma_f32 v115, -v115, v120, v119
	v_div_fmas_f32 v115, v115, v118, v120
	v_div_fixup_f32 v118, v115, v114, 1.0
	v_pk_mul_f32 v[122:123], v[102:103], v[118:119] op_sel_hi:[1,0]
	v_pk_mul_f32 v[120:121], v[100:101], v[118:119] op_sel_hi:[1,0]
	v_cvt_pk_f16_f32 v101, v122, v123
	v_cvt_pk_f16_f32 v100, v120, v121
	v_xor_b32_e32 v102, 0x8000, v101
	v_xor_b32_sdwa v101, s63, v101 dst_sel:DWORD dst_unused:UNUSED_PAD src0_sel:DWORD src1_sel:WORD_1
	v_pk_mul_f32 v[104:105], v[104:105], v[118:119] op_sel_hi:[1,0]
	v_pk_mul_f32 v[116:117], v[116:117], v[118:119] op_sel_hi:[1,0]
	v_perm_b32 v101, v101, v102, s33
	v_xor_b32_e32 v102, 0x8000, v100
	v_xor_b32_sdwa v100, s63, v100 dst_sel:DWORD dst_unused:UNUSED_PAD src0_sel:DWORD src1_sel:WORD_1
	v_perm_b32 v100, v100, v102, s33
	v_pk_add_f32 v[102:103], v[104:105], 0 neg_lo:[1,1] neg_hi:[1,1]
	v_pk_add_f32 v[114:115], v[116:117], 0 neg_lo:[1,1] neg_hi:[1,1]
	v_cvt_pk_f16_f32 v102, v102, v103
	v_cvt_pk_f16_f32 v103, v114, v115
	v_lshl_add_u64 v[114:115], s[10:11], 0, v[124:125]
	v_lshl_add_u64 v[114:115], v[114:115], 0, v[152:153]
	global_store_dwordx4 v[114:115], v[100:103], off
	v_fma_mixlo_f16 v119, v180, v120, 0
	v_mul_f32_e32 v159, v110, v118
	v_pk_mov_b32 v[100:101], v[180:181], v[182:183] op_sel:[1,0]
	v_pk_mov_b32 v[102:103], v[120:121], v[122:123] op_sel:[1,0]
	v_pk_mov_b32 v[120:121], v[122:123], v[104:105] op_sel:[1,0]
	v_pk_mul_f32 v[100:101], v[100:101], v[102:103]
	v_pk_mov_b32 v[102:103], v[182:183], v[178:179] op_sel:[1,0]
	v_cvt_pk_f16_f32 v101, v100, v101
	v_pk_mul_f32 v[102:103], v[102:103], v[120:121]
	v_pack_b32_f16 v100, v119, v101
	v_cvt_pk_f16_f32 v119, v102, v103
;     __device__ __forceinline__ void body_a(const f32x4 (&acc)[2][2][4][2], int row0, int cb0) const {
;     ...
;                 for (int bj = 0; bj < 2; ++bj) {
;                     const int c = cb0 + 32 * bj;
;                     const f32x4 p0 = *(const f32x4*)(k_a + c), p1 = *(const f32x4*)(k_a + c + 4);
;                     f32x4 ko0, ko1, ao0, ao1, bo0, bo1;
; #pragma unroll
;                     for (int e = 0; e < 4; ++e) {
;                         ko0[e] = kv[bj][e] * (1.0f + (a[bj][e] - 1.0f) * p0[e]); ko1[e] = kv[bj][4 + e] * (1.0f + (a[bj][4 + e] - 1.0f) * p1[e]);
;                         const float n0_ = kk[bj][e] * inv, n1_ = kk[bj][4 + e] * inv;
;                         ao0[e] = -n0_; ao1[e] = -n1_; bo0[e] = n0_ * a[bj][e]; bo1[e] = n1_ * a[bj][4 + e];
;                     }
;                     *(u32x4*)(C1 + row * LDC1 + 2048 + c) = pack8(ko0, ko1);
;                     *(u32x4*)(AA + row * DM + c) = pack8(ao0, ao1);
;                     *(u32x4*)(Ab + row * DM + c) = pack8(bo0, bo1);
;                 }
	v_pk_mov_b32 v[102:103], v[178:179], v[98:99] op_sel:[1,0]
	v_pk_mov_b32 v[104:105], v[104:105], v[116:117] op_sel:[1,0]
	v_alignbit_b32 v101, v119, v101, 16
	v_pk_mul_f32 v[102:103], v[102:103], v[104:105]
	v_pk_add_f32 v[120:121], v[168:169], 1.0 op_sel_hi:[1,0]
	v_cvt_pk_f16_f32 v98, v102, v103
	v_lshrrev_b32_e32 v103, 16, v98
	v_alignbit_b32 v102, v98, v119, 16
	v_fma_mixhi_f16 v103, v99, v117, 0
	v_lshl_add_u64 v[98:99], s[2:3], 0, v[124:125]
	v_lshl_add_u64 v[116:117], v[98:99], 0, v[152:153]
	global_store_dwordx4 v[116:117], v[100:103], off
	global_load_dwordx4 v[98:101], v[126:127], off offset:144
	s_nop 0
	global_load_dwordx4 v[102:105], v[126:127], off offset:128
	v_div_scale_f32 v122, s[0:1], v121, v121, 1.0
	v_rcp_f32_e32 v123, v122
	v_mul_f32_e32 v119, v113, v118
	v_fma_f32 v124, -v122, v123, 1.0
	v_fmac_f32_e32 v123, v124, v123
	v_div_scale_f32 v124, vcc, 1.0, v121, 1.0
	v_mul_f32_e32 v125, v124, v123
	v_fma_f32 v162, -v122, v125, v124
	v_fmac_f32_e32 v125, v162, v123
	v_fma_f32 v122, -v122, v125, v124
	v_div_fmas_f32 v122, v122, v123, v125
	v_div_fixup_f32 v121, v122, v121, 1.0
	v_div_scale_f32 v122, s[0:1], v120, v120, 1.0
	v_rcp_f32_e32 v123, v122
	s_nop 0
	v_fma_f32 v124, -v122, v123, 1.0
	v_fmac_f32_e32 v123, v124, v123
	v_div_scale_f32 v124, vcc, 1.0, v120, 1.0
	v_mul_f32_e32 v125, v124, v123
	v_fma_f32 v162, -v122, v125, v124
	v_fmac_f32_e32 v125, v162, v123
	v_fma_f32 v122, -v122, v125, v124
	v_div_fmas_f32 v122, v122, v123, v125
	v_div_fixup_f32 v120, v122, v120, 1.0
	v_pk_add_f32 v[122:123], v[120:121], -1.0 op_sel_hi:[1,0]
	s_waitcnt vmcnt(0)
	v_pk_fma_f32 v[102:103], v[122:123], v[102:103], 1.0 op_sel_hi:[1,1,0]
	s_nop 0
	v_pk_mul_f32 v[102:103], v[102:103], v[166:167]
	v_pk_add_f32 v[122:123], v[164:165], 1.0 op_sel_hi:[1,0]
	v_cvt_pk_f16_f32 v102, v102, v103
	v_div_scale_f32 v103, s[0:1], v123, v123, 1.0
	v_rcp_f32_e32 v124, v103
	s_nop 0
	v_fma_f32 v125, -v103, v124, 1.0
	v_fmac_f32_e32 v124, v125, v124
	v_div_scale_f32 v125, vcc, 1.0, v123, 1.0
	v_mul_f32_e32 v162, v125, v124
	v_fma_f32 v163, -v103, v162, v125
	v_fmac_f32_e32 v162, v163, v124
	v_fma_f32 v103, -v103, v162, v125
	v_div_fmas_f32 v103, v103, v124, v162
	v_div_fixup_f32 v123, v103, v123, 1.0
	v_div_scale_f32 v103, s[0:1], v122, v122, 1.0
	v_rcp_f32_e32 v124, v103
	s_nop 0
	v_fma_f32 v125, -v103, v124, 1.0
	v_fmac_f32_e32 v124, v125, v124
	v_div_scale_f32 v125, vcc, 1.0, v122, 1.0
	v_mul_f32_e32 v162, v125, v124
	v_fma_f32 v163, -v103, v162, v125
	v_fmac_f32_e32 v162, v163, v124
	v_fma_f32 v103, -v103, v162, v125
	v_div_fmas_f32 v103, v103, v124, v162
	v_div_fixup_f32 v122, v103, v122, 1.0
	v_pk_add_f32 v[124:125], v[122:123], -1.0 op_sel_hi:[1,0]
	s_nop 0
	v_pk_fma_f32 v[104:105], v[124:125], v[104:105], 1.0 op_sel_hi:[1,1,0]
	s_nop 0
	v_pk_mul_f32 v[104:105], v[104:105], v[140:141]
	s_nop 0
	v_cvt_pk_f16_f32 v103, v104, v105
	v_pk_add_f32 v[104:105], v[138:139], 1.0 op_sel_hi:[1,0]
	s_nop 0
	v_div_scale_f32 v124, s[0:1], v105, v105, 1.0
	v_rcp_f32_e32 v125, v124
	s_nop 0
	v_fma_f32 v138, -v124, v125, 1.0
	v_fmac_f32_e32 v125, v138, v125
	v_div_scale_f32 v138, vcc, 1.0, v105, 1.0
	v_mul_f32_e32 v139, v138, v125
	v_fma_f32 v140, -v124, v139, v138
	v_fmac_f32_e32 v139, v140, v125
	v_fma_f32 v124, -v124, v139, v138
	v_div_fmas_f32 v124, v124, v125, v139
	v_div_fixup_f32 v125, v124, v105, 1.0
	v_div_scale_f32 v105, s[0:1], v104, v104, 1.0
	v_rcp_f32_e32 v124, v105
	s_nop 0
	v_fma_f32 v138, -v105, v124, 1.0
	v_fmac_f32_e32 v124, v138, v124
	v_div_scale_f32 v138, vcc, 1.0, v104, 1.0
	v_mul_f32_e32 v139, v138, v124
	v_fma_f32 v140, -v105, v139, v138
	v_fmac_f32_e32 v139, v140, v124
	v_fma_f32 v105, -v105, v139, v138
	v_div_fmas_f32 v105, v105, v124, v139
	v_div_fixup_f32 v124, v105, v104, 1.0
	v_pk_add_f32 v[104:105], v[124:125], -1.0 op_sel_hi:[1,0]
	s_nop 0
	v_pk_fma_f32 v[98:99], v[104:105], v[98:99], 1.0 op_sel_hi:[1,1,0]
	s_nop 0
	v_pk_mul_f32 v[98:99], v[98:99], v[136:137]
	s_nop 0
	v_cvt_pk_f16_f32 v104, v98, v99
	v_pk_add_f32 v[98:99], v[134:135], 1.0 op_sel_hi:[1,0]
	s_nop 0
	v_div_scale_f32 v105, s[0:1], v99, v99, 1.0
	v_rcp_f32_e32 v134, v105
	s_nop 0
	v_fma_f32 v135, -v105, v134, 1.0
	v_fmac_f32_e32 v134, v135, v134
	v_div_scale_f32 v135, vcc, 1.0, v99, 1.0
	v_mul_f32_e32 v136, v135, v134
	v_fma_f32 v137, -v105, v136, v135
	v_fmac_f32_e32 v136, v137, v134
	v_fma_f32 v105, -v105, v136, v135
	v_div_fmas_f32 v105, v105, v134, v136
	v_div_fixup_f32 v135, v105, v99, 1.0
	v_div_scale_f32 v99, s[0:1], v98, v98, 1.0
	v_rcp_f32_e32 v105, v99
	s_nop 0
	v_fma_f32 v134, -v99, v105, 1.0
	v_fmac_f32_e32 v105, v134, v105
	v_div_scale_f32 v134, vcc, 1.0, v98, 1.0
	v_mul_f32_e32 v136, v134, v105
	v_fma_f32 v137, -v99, v136, v134
	v_fmac_f32_e32 v136, v137, v105
	v_fma_f32 v99, -v99, v136, v134
	v_div_fmas_f32 v99, v99, v105, v136
	v_div_fixup_f32 v134, v99, v98, 1.0
	v_pk_add_f32 v[98:99], v[134:135], -1.0 op_sel_hi:[1,0]
	s_nop 0
	v_pk_fma_f32 v[98:99], v[98:99], v[100:101], 1.0 op_sel_hi:[1,1,0]
	v_cvt_f16_f32_e64 v100, -v159
	v_pk_mul_f32 v[98:99], v[98:99], v[132:133]
	s_nop 0
	v_cvt_pk_f16_f32 v105, v98, v99
	v_pk_mov_b32 v[98:99], v[110:111], v[130:131] op_sel:[1,0]
	global_store_dwordx4 v[106:107], v[102:105], off
	s_nop 1
	v_pk_mul_f32 v[102:103], v[98:99], v[118:119] op_sel_hi:[1,0]
	s_nop 0
	v_cvt_pk_f16_f32 v99, v102, v103
	v_pack_b32_f16 v98, v100, -v99
	v_pk_mov_b32 v[100:101], v[130:131], v[108:109] op_sel:[1,0]
	v_xor_b32_sdwa v99, s63, v99 dst_sel:DWORD dst_unused:UNUSED_PAD src0_sel:DWORD src1_sel:WORD_1
	v_pk_mul_f32 v[104:105], v[100:101], v[118:119] op_sel_hi:[1,0]
	s_nop 0
	v_cvt_pk_f16_f32 v100, v104, v105
	v_xor_b32_e32 v101, 0x8000, v100
; __device__ __forceinline__ float sigmoidf_(float x) { return 1.0f / (1.0f + __expf(-x)); }
;     __device__ __forceinline__ void body_a(const f32x4 (&acc)[2][2][4][2], int row0, int cb0) const {
;     ...
;             for (int m = 0; m < 4; ++m) {
;                 const size_t row = (size_t)(row0 + ai * 128 + m * 16);
;                 asm volatile("" ::: "memory");
;                 float a[2][8], kv[2][8], kk[2][8]; float ss = 0.f;
; #pragma unroll
;                 for (int bj = 0; bj < 2; ++bj) {
;                     const int c = cb0 + 32 * bj;
;                     const f32x4 b0 = *(const f32x4*)(a0 + c), b1 = *(const f32x4*)(a0 + c + 4), q0 = *(const f32x4*)(k_k + c), q1 = *(const f32x4*)(k_k + c + 4);
;                     const h16x8 kh = *(const h16x8*)(C1 + row * LDC1 + 2048 + c);
; #pragma unroll
;                     for (int e = 0; e < 4; ++e) {
;                         a[bj][e] = sigmoidf_(acc[ai][bj][m][0][e] + b0[e]); a[bj][4 + e] = sigmoidf_(acc[ai][bj][m][1][e] + b1[e]);
;                         kv[bj][e] = (float)kh[e]; kv[bj][4 + e] = (float)kh[4 + e];
;                         kk[bj][e] = kv[bj][e] * q0[e]; kk[bj][4 + e] = kv[bj][4 + e] * q1[e];
;                         ss += kk[bj][e] * kk[bj][e] + kk[bj][4 + e] * kk[bj][4 + e];
;                     }
;                 }
;     ...
;                         ko0[e] = kv[bj][e] * (1.0f + (a[bj][e] - 1.0f) * p0[e]); ko1[e] = kv[bj][4 + e] * (1.0f + (a[bj][4 + e] - 1.0f) * p1[e]);
;                         const float n0_ = kk[bj][e] * inv, n1_ = kk[bj][4 + e] * inv;
;                         ao0[e] = -n0_; ao1[e] = -n1_; bo0[e] = n0_ * a[bj][e]; bo1[e] = n1_ * a[bj][4 + e];
;                     }
;                     *(u32x4*)(C1 + row * LDC1 + 2048 + c) = pack8(ko0, ko1);
;                     *(u32x4*)(AA + row * DM + c) = pack8(ao0, ao1);
;                     *(u32x4*)(Ab + row * DM + c) = pack8(bo0, bo1);
;                 }
	v_perm_b32 v99, v101, v99, s33
	v_xor_b32_sdwa v110, s63, v100 dst_sel:DWORD dst_unused:UNUSED_PAD src0_sel:DWORD src1_sel:WORD_1
	v_pk_mov_b32 v[100:101], v[108:109], v[112:113] op_sel:[1,0]
	v_cvt_f16_f32_e64 v108, -v119
	v_pk_mul_f32 v[106:107], v[100:101], v[118:119] op_sel_hi:[1,0]
	s_nop 0
	v_cvt_pk_f16_f32 v101, v106, v107
	v_xor_b32_e32 v100, 0x8000, v101
	v_xor_b32_sdwa v101, s63, v101 dst_sel:DWORD dst_unused:UNUSED_PAD src0_sel:DWORD src1_sel:WORD_1
	v_perm_b32 v100, v100, v110, s33
	v_perm_b32 v101, v108, v101, s33
	global_store_dwordx4 v[114:115], v[98:101], off offset:64
	s_nop 1
	v_pk_mov_b32 v[98:99], v[120:121], v[122:123] op_sel:[1,0]
	v_fma_mixlo_f16 v100, v120, v159, 0
	v_pk_mul_f32 v[98:99], v[98:99], v[102:103]
	s_nop 0
	v_cvt_pk_f16_f32 v99, v98, v99
	v_pack_b32_f16 v98, v100, v99
	v_pk_mov_b32 v[100:101], v[122:123], v[124:125] op_sel:[1,0]
	s_nop 0
	v_pk_mul_f32 v[100:101], v[100:101], v[104:105]
	s_nop 0
	v_cvt_pk_f16_f32 v102, v100, v101
	v_pk_mov_b32 v[100:101], v[124:125], v[134:135] op_sel:[1,0]
	v_alignbit_b32 v99, v102, v99, 16
	v_pk_mul_f32 v[100:101], v[100:101], v[106:107]
	s_nop 0
	v_cvt_pk_f16_f32 v101, v100, v101
	v_alignbit_b32 v100, v101, v102, 16
	v_lshrrev_b32_e32 v101, 16, v101
	v_fma_mixhi_f16 v101, v135, v119, 0
	global_store_dwordx4 v[116:117], v[98:101], off offset:64
	v_or_b32_e32 v122, 32, v158
	s_nop 0
	v_mad_i64_i32 v[98:99], s[0:1], v122, s5, v[160:161]
	v_lshl_add_u64 v[118:119], v[98:99], 0, s[6:7]
	global_load_dwordx4 v[110:113], v[154:155], off offset:16
	global_load_dwordx4 v[114:117], v[154:155], off
	global_load_dwordx4 v[98:101], v[156:157], off offset:16
	global_load_dwordx4 v[102:105], v[156:157], off
	v_lshl_add_u64 v[134:135], v[118:119], 0, v[152:153]
	global_load_dwordx4 v[106:109], v[134:135], off
	v_ashrrev_i32_e32 v123, 31, v122
	s_waitcnt vmcnt(4)
	v_add_f32_e32 v90, v90, v110
	v_mul_f32_e32 v90, 0xbfb8aa3b, v90
	v_exp_f32_e32 v162, v90
	s_waitcnt vmcnt(3)
	v_add_f32_e32 v90, v95, v115
	v_mul_f32_e32 v90, 0xbfb8aa3b, v90
	v_exp_f32_e32 v165, v90
	v_add_f32_e32 v90, v91, v111
	v_mul_f32_e32 v90, 0xbfb8aa3b, v90
	v_exp_f32_e32 v163, v90
	v_add_f32_e32 v90, v96, v116
	v_mul_f32_e32 v90, 0xbfb8aa3b, v90
	v_exp_f32_e32 v166, v90
	v_add_f32_e32 v90, v92, v112
	v_mul_f32_e32 v90, 0xbfb8aa3b, v90
	v_exp_f32_e32 v136, v90
	v_add_f32_e32 v90, v97, v117
	v_mul_f32_e32 v90, 0xbfb8aa3b, v90
	v_exp_f32_e32 v167, v90
	v_add_f32_e32 v90, v93, v113
	v_add_f32_e32 v94, v94, v114
	v_mul_f32_e32 v90, 0xbfb8aa3b, v90
	v_mul_f32_e32 v94, 0xbfb8aa3b, v94
	v_exp_f32_e32 v137, v90
	v_lshl_add_u64 v[90:91], v[118:119], 0, v[128:129]
	v_exp_f32_e32 v164, v94
	global_load_dwordx4 v[94:97], v[154:155], off offset:144
	global_load_dwordx4 v[110:113], v[154:155], off offset:128
	global_load_dwordx4 v[138:141], v[156:157], off offset:144
	global_load_dwordx4 v[168:171], v[156:157], off offset:128
	global_load_dwordx4 v[172:175], v[90:91], off
	v_pk_add_f32 v[166:167], v[166:167], 1.0 op_sel_hi:[1,0]
	v_pk_add_f32 v[164:165], v[164:165], 1.0 op_sel_hi:[1,0]
	s_waitcnt vmcnt(4)
	v_add_f32_e32 v82, v82, v94
	v_mul_f32_e32 v82, 0xbfb8aa3b, v82
	v_exp_f32_e32 v118, v82
	s_waitcnt vmcnt(3)
	v_add_f32_e32 v82, v87, v111
	s_waitcnt vmcnt(0)
	v_cvt_f32_f16_e32 v116, v174
	v_cvt_f32_f16_sdwa v117, v174 dst_sel:DWORD dst_unused:UNUSED_PAD src0_sel:WORD_1
	v_cvt_f32_f16_e32 v130, v172
	v_cvt_f32_f16_sdwa v131, v172 dst_sel:DWORD dst_unused:UNUSED_PAD src0_sel:WORD_1
	v_mul_f32_e32 v82, 0xbfb8aa3b, v82
	v_exp_f32_e32 v133, v82
	v_add_f32_e32 v82, v83, v95
	v_mul_f32_e32 v82, 0xbfb8aa3b, v82
	v_pk_mul_f32 v[92:93], v[138:139], v[116:117]
	v_exp_f32_e32 v119, v82
	v_pk_mul_f32 v[94:95], v[168:169], v[130:131]
	v_pk_mul_f32 v[82:83], v[92:93], v[92:93]
	v_cvt_f32_f16_e32 v120, v173
	v_pk_fma_f32 v[138:139], v[94:95], v[94:95], v[82:83]
	v_add_f32_e32 v82, v88, v112
	v_mul_f32_e32 v82, 0xbfb8aa3b, v82
	v_exp_f32_e32 v124, v82
	v_add_f32_e32 v82, v84, v96
	v_mul_f32_e32 v82, 0xbfb8aa3b, v82
	v_exp_f32_e32 v114, v82
	v_add_f32_e32 v82, v89, v113
	v_cvt_f32_f16_e32 v112, v175
	v_cvt_f32_f16_sdwa v113, v175 dst_sel:DWORD dst_unused:UNUSED_PAD src0_sel:WORD_1
	v_cvt_f32_f16_sdwa v121, v173 dst_sel:DWORD dst_unused:UNUSED_PAD src0_sel:WORD_1
	v_mul_f32_e32 v82, 0xbfb8aa3b, v82
	v_exp_f32_e32 v125, v82
	v_add_f32_e32 v82, v85, v97
	v_add_f32_e32 v86, v86, v110
	v_mul_f32_e32 v82, 0xbfb8aa3b, v82
	v_pk_mul_f32 v[96:97], v[140:141], v[112:113]
	v_mul_f32_e32 v86, 0xbfb8aa3b, v86
	v_exp_f32_e32 v115, v82
	v_pk_mul_f32 v[110:111], v[170:171], v[120:121]
	v_pk_mul_f32 v[82:83], v[96:97], v[96:97]
	v_exp_f32_e32 v132, v86
	v_pk_fma_f32 v[140:141], v[110:111], v[110:111], v[82:83]
	global_load_dwordx4 v[82:85], v[126:127], off offset:16
	global_load_dwordx4 v[86:89], v[126:127], off
	v_cvt_f32_f16_e32 v168, v106
	v_cvt_f32_f16_sdwa v169, v106 dst_sel:DWORD dst_unused:UNUSED_PAD src0_sel:WORD_1
	v_div_scale_f32 v106, s[0:1], v165, v165, 1.0
	v_rcp_f32_e32 v159, v106
	s_nop 0
	v_fma_f32 v170, -v106, v159, 1.0
	v_fmac_f32_e32 v159, v170, v159
	v_div_scale_f32 v170, vcc, 1.0, v165, 1.0
	v_mul_f32_e32 v171, v170, v159
	v_fma_f32 v172, -v106, v171, v170
	v_fmac_f32_e32 v171, v172, v159
	v_fma_f32 v106, -v106, v171, v170
	v_div_fmas_f32 v106, v106, v159, v171
	v_div_fixup_f32 v165, v106, v165, 1.0
	v_div_scale_f32 v106, s[0:1], v164, v164, 1.0
	v_rcp_f32_e32 v159, v106
	s_nop 0
	v_fma_f32 v170, -v106, v159, 1.0
	v_fmac_f32_e32 v159, v170, v159
	v_div_scale_f32 v170, vcc, 1.0, v164, 1.0
	v_mul_f32_e32 v171, v170, v159
	v_fma_f32 v172, -v106, v171, v170
	v_fmac_f32_e32 v171, v172, v159
	v_fma_f32 v106, -v106, v171, v170
	v_div_fmas_f32 v106, v106, v159, v171
	v_div_fixup_f32 v164, v106, v164, 1.0
	v_pk_add_f32 v[170:171], v[164:165], -1.0 op_sel_hi:[1,0]
	v_cvt_f32_f16_e32 v106, v107
	v_cvt_f32_f16_sdwa v107, v107 dst_sel:DWORD dst_unused:UNUSED_PAD src0_sel:WORD_1
	s_waitcnt vmcnt(0)
; __device__ __forceinline__ float sigmoidf_(float x) { return 1.0f / (1.0f + __expf(-x)); }
;     __device__ __forceinline__ void body_a(const f32x4 (&acc)[2][2][4][2], int row0, int cb0) const {
;     ...
;                         a[bj][e] = sigmoidf_(acc[ai][bj][m][0][e] + b0[e]); a[bj][4 + e] = sigmoidf_(acc[ai][bj][m][1][e] + b1[e]);
;                         kv[bj][e] = (float)kh[e]; kv[bj][4 + e] = (float)kh[4 + e];
;                         kk[bj][e] = kv[bj][e] * q0[e]; kk[bj][4 + e] = kv[bj][4 + e] * q1[e];
;                         ss += kk[bj][e] * kk[bj][e] + kk[bj][4 + e] * kk[bj][4 + e];
;                     }
;                 }
;                 ss += __shfl_xor(ss, 16); ss += __shfl_xor(ss, 32);
	v_pk_fma_f32 v[86:87], v[170:171], v[86:87], 1.0 op_sel_hi:[1,1,0]
	s_nop 0
	v_pk_mul_f32 v[86:87], v[86:87], v[168:169]
	s_nop 0
	v_cvt_pk_f16_f32 v86, v86, v87
	v_div_scale_f32 v87, s[0:1], v167, v167, 1.0
	v_rcp_f32_e32 v159, v87
	s_nop 0
	v_fma_f32 v170, -v87, v159, 1.0
	v_fmac_f32_e32 v159, v170, v159
	v_div_scale_f32 v170, vcc, 1.0, v167, 1.0
	v_mul_f32_e32 v171, v170, v159
	v_fma_f32 v172, -v87, v171, v170
	v_fmac_f32_e32 v171, v172, v159
	v_fma_f32 v87, -v87, v171, v170
	v_div_fmas_f32 v87, v87, v159, v171
	v_div_fixup_f32 v167, v87, v167, 1.0
	v_div_scale_f32 v87, s[0:1], v166, v166, 1.0
	v_rcp_f32_e32 v159, v87
	s_nop 0
	v_fma_f32 v170, -v87, v159, 1.0
	v_fmac_f32_e32 v159, v170, v159
	v_div_scale_f32 v170, vcc, 1.0, v166, 1.0
	v_mul_f32_e32 v171, v170, v159
	v_fma_f32 v172, -v87, v171, v170
	v_fmac_f32_e32 v171, v172, v159
	v_fma_f32 v87, -v87, v171, v170
	v_div_fmas_f32 v87, v87, v159, v171
	v_div_fixup_f32 v166, v87, v166, 1.0
	v_pk_add_f32 v[170:171], v[166:167], -1.0 op_sel_hi:[1,0]
	s_nop 0
	v_pk_fma_f32 v[88:89], v[170:171], v[88:89], 1.0 op_sel_hi:[1,1,0]
	v_cvt_f32_f16_e32 v170, v108
	v_pk_mul_f32 v[88:89], v[88:89], v[106:107]
	v_cvt_f32_f16_sdwa v171, v108 dst_sel:DWORD dst_unused:UNUSED_PAD src0_sel:WORD_1
	v_cvt_pk_f16_f32 v87, v88, v89
	v_pk_add_f32 v[88:89], v[162:163], 1.0 op_sel_hi:[1,0]
	s_nop 0
	v_div_scale_f32 v108, s[0:1], v89, v89, 1.0
	v_rcp_f32_e32 v159, v108
	s_nop 0
	v_fma_f32 v162, -v108, v159, 1.0
	v_fmac_f32_e32 v159, v162, v159
	v_div_scale_f32 v162, vcc, 1.0, v89, 1.0
	v_mul_f32_e32 v163, v162, v159
	v_fma_f32 v172, -v108, v163, v162
	v_fmac_f32_e32 v163, v172, v159
	v_fma_f32 v108, -v108, v163, v162
	v_div_fmas_f32 v108, v108, v159, v163
	v_div_fixup_f32 v163, v108, v89, 1.0
	v_div_scale_f32 v89, s[0:1], v88, v88, 1.0
	v_rcp_f32_e32 v108, v89
	s_nop 0
	v_fma_f32 v159, -v89, v108, 1.0
	v_fmac_f32_e32 v108, v159, v108
	v_div_scale_f32 v159, vcc, 1.0, v88, 1.0
	v_mul_f32_e32 v162, v159, v108
	v_fma_f32 v172, -v89, v162, v159
	v_fmac_f32_e32 v162, v172, v108
	v_fma_f32 v89, -v89, v162, v159
	v_div_fmas_f32 v89, v89, v108, v162
	v_div_fixup_f32 v162, v89, v88, 1.0
	v_pk_add_f32 v[88:89], v[162:163], -1.0 op_sel_hi:[1,0]
	v_cvt_f32_f16_e32 v108, v109
	v_pk_fma_f32 v[82:83], v[88:89], v[82:83], 1.0 op_sel_hi:[1,1,0]
	v_cvt_f32_f16_sdwa v109, v109 dst_sel:DWORD dst_unused:UNUSED_PAD src0_sel:WORD_1
	v_pk_mul_f32 v[82:83], v[82:83], v[170:171]
	v_pk_mul_f32 v[100:101], v[100:101], v[108:109]
	v_cvt_pk_f16_f32 v88, v82, v83
	v_pk_add_f32 v[82:83], v[136:137], 1.0 op_sel_hi:[1,0]
	s_nop 0
	v_div_scale_f32 v89, s[0:1], v83, v83, 1.0
	v_rcp_f32_e32 v136, v89
	s_nop 0
	v_fma_f32 v137, -v89, v136, 1.0
	v_fmac_f32_e32 v136, v137, v136
	v_div_scale_f32 v137, vcc, 1.0, v83, 1.0
	v_mul_f32_e32 v159, v137, v136
	v_fma_f32 v172, -v89, v159, v137
	v_fmac_f32_e32 v159, v172, v136
	v_fma_f32 v89, -v89, v159, v137
	v_div_fmas_f32 v89, v89, v136, v159
	v_div_fixup_f32 v83, v89, v83, 1.0
	v_div_scale_f32 v89, s[0:1], v82, v82, 1.0
	v_rcp_f32_e32 v136, v89
	s_nop 0
	v_fma_f32 v137, -v89, v136, 1.0
	v_fmac_f32_e32 v136, v137, v136
	v_div_scale_f32 v137, vcc, 1.0, v82, 1.0
	v_mul_f32_e32 v159, v137, v136
	v_fma_f32 v172, -v89, v159, v137
	v_fmac_f32_e32 v159, v172, v136
	v_fma_f32 v89, -v89, v159, v137
	v_div_fmas_f32 v89, v89, v136, v159
	v_div_fixup_f32 v82, v89, v82, 1.0
	v_pk_add_f32 v[136:137], v[82:83], -1.0 op_sel_hi:[1,0]
	s_nop 0
	v_pk_fma_f32 v[84:85], v[136:137], v[84:85], 1.0 op_sel_hi:[1,1,0]
	s_nop 0
	v_pk_mul_f32 v[84:85], v[84:85], v[108:109]
	v_lshlrev_b64 v[108:109], 12, v[122:123]
	v_cvt_pk_f16_f32 v89, v84, v85
	global_store_dwordx4 v[134:135], v[86:89], off
	v_pk_mul_f32 v[84:85], v[102:103], v[168:169]
	v_pk_mul_f32 v[102:103], v[100:101], v[100:101]
	v_pk_mul_f32 v[88:89], v[98:99], v[170:171]
	v_pk_mul_f32 v[86:87], v[104:105], v[106:107]
	v_pk_mul_f32 v[98:99], v[88:89], v[88:89]
	v_pk_fma_f32 v[102:103], v[86:87], v[86:87], v[102:103]
	v_pk_fma_f32 v[98:99], v[84:85], v[84:85], v[98:99]
	s_nop 0
	v_add_f32_e32 v98, v98, v99
	v_add_f32_e32 v98, v102, v98
	v_add_f32_e32 v98, v103, v98
	v_add_f32_e32 v98, v98, v138
	v_add_f32_e32 v98, v139, v98
	v_add_f32_e32 v98, v140, v98
	v_add_f32_e32 v98, v141, v98
	ds_bpermute_b32 v99, v206, v98
	s_waitcnt lgkmcnt(0)
	v_add_f32_e32 v98, v98, v99
	ds_bpermute_b32 v99, v207, v98
	s_waitcnt lgkmcnt(0)
;     __device__ __forceinline__ void body_a(const f32x4 (&acc)[2][2][4][2], int row0, int cb0) const {
;     ...
;                 ss += __shfl_xor(ss, 16); ss += __shfl_xor(ss, 32);
;                 const float inv = 1.0f / fmaxf(sqrtf(ss), 1e-12f);
; #pragma unroll
;                 for (int bj = 0; bj < 2; ++bj) {
;                     const int c = cb0 + 32 * bj;
;                     const f32x4 p0 = *(const f32x4*)(k_a + c), p1 = *(const f32x4*)(k_a + c + 4);
;                     f32x4 ko0, ko1, ao0, ao1, bo0, bo1;
; #pragma unroll
;                     for (int e = 0; e < 4; ++e) {
;                         ko0[e] = kv[bj][e] * (1.0f + (a[bj][e] - 1.0f) * p0[e]); ko1[e] = kv[bj][4 + e] * (1.0f + (a[bj][4 + e] - 1.0f) * p1[e]);
;                         const float n0_ = kk[bj][e] * inv, n1_ = kk[bj][4 + e] * inv;
;                         ao0[e] = -n0_; ao1[e] = -n1_; bo0[e] = n0_ * a[bj][e]; bo1[e] = n1_ * a[bj][4 + e];
;                     }
;                     *(u32x4*)(C1 + row * LDC1 + 2048 + c) = pack8(ko0, ko1);
;                     *(u32x4*)(AA + row * DM + c) = pack8(ao0, ao1);
;                     *(u32x4*)(Ab + row * DM + c) = pack8(bo0, bo1);
;                 }
	v_add_f32_e32 v98, v98, v99
	v_cmp_gt_f32_e32 vcc, s4, v98
	v_mul_f32_e32 v99, 0x4f800000, v98
	s_nop 0
	v_cndmask_b32_e32 v98, v98, v99, vcc
	v_sqrt_f32_e32 v99, v98
	s_nop 0
	v_add_u32_e32 v102, -1, v99
	v_fma_f32 v103, -v102, v99, v98
	v_cmp_ge_f32_e64 s[0:1], 0, v103
	v_add_u32_e32 v103, 1, v99
	s_nop 0
	v_cndmask_b32_e64 v102, v99, v102, s[0:1]
	v_fma_f32 v99, -v103, v99, v98
	v_cmp_lt_f32_e64 s[0:1], 0, v99
	s_nop 1
	v_cndmask_b32_e64 v99, v102, v103, s[0:1]
	v_mul_f32_e32 v102, 0x37800000, v99
	v_cndmask_b32_e32 v99, v99, v102, vcc
	v_cmp_class_f32_e32 vcc, v98, v244
	s_nop 1
	v_cndmask_b32_e32 v98, v99, v98, vcc
	v_max_f32_e32 v98, 0x2b8cbccc, v98
	v_div_scale_f32 v99, s[0:1], v98, v98, 1.0
	v_rcp_f32_e32 v102, v99
	s_nop 0
	v_fma_f32 v103, -v99, v102, 1.0
	v_fmac_f32_e32 v102, v103, v102
	v_div_scale_f32 v103, vcc, 1.0, v98, 1.0
	v_mul_f32_e32 v104, v103, v102
	v_fma_f32 v105, -v99, v104, v103
	v_fmac_f32_e32 v104, v105, v102
	v_fma_f32 v99, -v99, v104, v103
	v_div_fmas_f32 v99, v99, v102, v104
	v_div_fixup_f32 v102, v99, v98, 1.0
	v_pk_mul_f32 v[106:107], v[86:87], v[102:103] op_sel_hi:[1,0]
	v_pk_mul_f32 v[104:105], v[84:85], v[102:103] op_sel_hi:[1,0]
	v_cvt_pk_f16_f32 v85, v106, v107
	v_cvt_pk_f16_f32 v84, v104, v105
	v_xor_b32_e32 v86, 0x8000, v85
	v_xor_b32_sdwa v85, s63, v85 dst_sel:DWORD dst_unused:UNUSED_PAD src0_sel:DWORD src1_sel:WORD_1
	v_pk_mul_f32 v[88:89], v[88:89], v[102:103] op_sel_hi:[1,0]
	v_pk_mul_f32 v[100:101], v[100:101], v[102:103] op_sel_hi:[1,0]
	v_perm_b32 v85, v85, v86, s33
	v_xor_b32_e32 v86, 0x8000, v84
	v_xor_b32_sdwa v84, s63, v84 dst_sel:DWORD dst_unused:UNUSED_PAD src0_sel:DWORD src1_sel:WORD_1
	v_perm_b32 v84, v84, v86, s33
	v_pk_add_f32 v[86:87], v[88:89], 0 neg_lo:[1,1] neg_hi:[1,1]
	v_pk_add_f32 v[98:99], v[100:101], 0 neg_lo:[1,1] neg_hi:[1,1]
	v_cvt_pk_f16_f32 v86, v86, v87
	v_cvt_pk_f16_f32 v87, v98, v99
	v_lshl_add_u64 v[98:99], s[10:11], 0, v[108:109]
	v_lshl_add_u64 v[98:99], v[98:99], 0, v[152:153]
	global_store_dwordx4 v[98:99], v[84:87], off
	v_fma_mixlo_f16 v103, v164, v104, 0
	v_mul_f32_e32 v122, v94, v102
	v_pk_mov_b32 v[84:85], v[164:165], v[166:167] op_sel:[1,0]
	v_pk_mov_b32 v[86:87], v[104:105], v[106:107] op_sel:[1,0]
	v_pk_mov_b32 v[104:105], v[106:107], v[88:89] op_sel:[1,0]
	v_pk_mul_f32 v[84:85], v[84:85], v[86:87]
	v_pk_mov_b32 v[86:87], v[166:167], v[162:163] op_sel:[1,0]
	v_cvt_pk_f16_f32 v85, v84, v85
	v_pk_mul_f32 v[86:87], v[86:87], v[104:105]
	v_pack_b32_f16 v84, v103, v85
	v_cvt_pk_f16_f32 v103, v86, v87
	v_pk_mov_b32 v[86:87], v[162:163], v[82:83] op_sel:[1,0]
	v_pk_mov_b32 v[88:89], v[88:89], v[100:101] op_sel:[1,0]
	v_alignbit_b32 v85, v103, v85, 16
	v_pk_mul_f32 v[86:87], v[86:87], v[88:89]
	v_pk_add_f32 v[104:105], v[132:133], 1.0 op_sel_hi:[1,0]
	v_cvt_pk_f16_f32 v82, v86, v87
	v_lshrrev_b32_e32 v87, 16, v82
	v_alignbit_b32 v86, v82, v103, 16
	v_fma_mixhi_f16 v87, v83, v101, 0
	v_lshl_add_u64 v[82:83], s[2:3], 0, v[108:109]
	v_lshl_add_u64 v[100:101], v[82:83], 0, v[152:153]
	global_store_dwordx4 v[100:101], v[84:87], off
	global_load_dwordx4 v[82:85], v[126:127], off offset:144
	s_nop 0
	global_load_dwordx4 v[86:89], v[126:127], off offset:128
	v_div_scale_f32 v106, s[0:1], v105, v105, 1.0
	v_rcp_f32_e32 v107, v106
	v_mul_f32_e32 v103, v97, v102
	v_fma_f32 v108, -v106, v107, 1.0
	v_fmac_f32_e32 v107, v108, v107
	v_div_scale_f32 v108, vcc, 1.0, v105, 1.0
	v_mul_f32_e32 v109, v108, v107
	v_fma_f32 v123, -v106, v109, v108
	v_fmac_f32_e32 v109, v123, v107
	v_fma_f32 v106, -v106, v109, v108
	v_div_fmas_f32 v106, v106, v107, v109
	v_div_fixup_f32 v105, v106, v105, 1.0
	v_div_scale_f32 v106, s[0:1], v104, v104, 1.0
	v_rcp_f32_e32 v107, v106
	s_nop 0
	v_fma_f32 v108, -v106, v107, 1.0
	v_fmac_f32_e32 v107, v108, v107
	v_div_scale_f32 v108, vcc, 1.0, v104, 1.0
	v_mul_f32_e32 v109, v108, v107
	v_fma_f32 v123, -v106, v109, v108
	v_fmac_f32_e32 v109, v123, v107
	v_fma_f32 v106, -v106, v109, v108
	v_div_fmas_f32 v106, v106, v107, v109
	v_div_fixup_f32 v104, v106, v104, 1.0
	v_pk_add_f32 v[106:107], v[104:105], -1.0 op_sel_hi:[1,0]
	s_waitcnt vmcnt(0)
	v_pk_fma_f32 v[86:87], v[106:107], v[86:87], 1.0 op_sel_hi:[1,1,0]
	s_nop 0
	v_pk_mul_f32 v[86:87], v[86:87], v[130:131]
	v_pk_add_f32 v[106:107], v[124:125], 1.0 op_sel_hi:[1,0]
	v_cvt_pk_f16_f32 v86, v86, v87
	v_div_scale_f32 v87, s[0:1], v107, v107, 1.0
	v_rcp_f32_e32 v108, v87
	s_nop 0
	v_fma_f32 v109, -v87, v108, 1.0
	v_fmac_f32_e32 v108, v109, v108
	v_div_scale_f32 v109, vcc, 1.0, v107, 1.0
	v_mul_f32_e32 v123, v109, v108
	v_fma_f32 v124, -v87, v123, v109
	v_fmac_f32_e32 v123, v124, v108
	v_fma_f32 v87, -v87, v123, v109
	v_div_fmas_f32 v87, v87, v108, v123
	v_div_fixup_f32 v107, v87, v107, 1.0
	v_div_scale_f32 v87, s[0:1], v106, v106, 1.0
	v_rcp_f32_e32 v108, v87
	s_nop 0
	v_fma_f32 v109, -v87, v108, 1.0
	v_fmac_f32_e32 v108, v109, v108
	v_div_scale_f32 v109, vcc, 1.0, v106, 1.0
	v_mul_f32_e32 v123, v109, v108
	v_fma_f32 v124, -v87, v123, v109
	v_fmac_f32_e32 v123, v124, v108
	v_fma_f32 v87, -v87, v123, v109
	v_div_fmas_f32 v87, v87, v108, v123
	v_div_fixup_f32 v106, v87, v106, 1.0
	v_pk_add_f32 v[108:109], v[106:107], -1.0 op_sel_hi:[1,0]
	s_nop 0
	v_pk_fma_f32 v[88:89], v[108:109], v[88:89], 1.0 op_sel_hi:[1,1,0]
	s_nop 0
	v_pk_mul_f32 v[88:89], v[88:89], v[120:121]
	s_nop 0
	v_cvt_pk_f16_f32 v87, v88, v89
	v_pk_add_f32 v[88:89], v[118:119], 1.0 op_sel_hi:[1,0]
	s_nop 0
	v_div_scale_f32 v108, s[0:1], v89, v89, 1.0
	v_rcp_f32_e32 v109, v108
	s_nop 0
	v_fma_f32 v118, -v108, v109, 1.0
	v_fmac_f32_e32 v109, v118, v109
	v_div_scale_f32 v118, vcc, 1.0, v89, 1.0
	v_mul_f32_e32 v119, v118, v109
	v_fma_f32 v120, -v108, v119, v118
; __device__ __forceinline__ float sigmoidf_(float x) { return 1.0f / (1.0f + __expf(-x)); }
;     __device__ __forceinline__ void body_a(const f32x4 (&acc)[2][2][4][2], int row0, int cb0) const {
;     ...
;             for (int m = 0; m < 4; ++m) {
;                 const size_t row = (size_t)(row0 + ai * 128 + m * 16);
;                 asm volatile("" ::: "memory");
;                 float a[2][8], kv[2][8], kk[2][8]; float ss = 0.f;
; #pragma unroll
;                 for (int bj = 0; bj < 2; ++bj) {
;                     const int c = cb0 + 32 * bj;
;                     const f32x4 b0 = *(const f32x4*)(a0 + c), b1 = *(const f32x4*)(a0 + c + 4), q0 = *(const f32x4*)(k_k + c), q1 = *(const f32x4*)(k_k + c + 4);
;                     const h16x8 kh = *(const h16x8*)(C1 + row * LDC1 + 2048 + c);
; #pragma unroll
;                     for (int e = 0; e < 4; ++e) {
;                         a[bj][e] = sigmoidf_(acc[ai][bj][m][0][e] + b0[e]); a[bj][4 + e] = sigmoidf_(acc[ai][bj][m][1][e] + b1[e]);
;                         kv[bj][e] = (float)kh[e]; kv[bj][4 + e] = (float)kh[4 + e];
;                         kk[bj][e] = kv[bj][e] * q0[e]; kk[bj][4 + e] = kv[bj][4 + e] * q1[e];
;                         ss += kk[bj][e] * kk[bj][e] + kk[bj][4 + e] * kk[bj][4 + e];
;                     }
;                 }
;     ...
;                         ko0[e] = kv[bj][e] * (1.0f + (a[bj][e] - 1.0f) * p0[e]); ko1[e] = kv[bj][4 + e] * (1.0f + (a[bj][4 + e] - 1.0f) * p1[e]);
;                         const float n0_ = kk[bj][e] * inv, n1_ = kk[bj][4 + e] * inv;
;                         ao0[e] = -n0_; ao1[e] = -n1_; bo0[e] = n0_ * a[bj][e]; bo1[e] = n1_ * a[bj][4 + e];
;                     }
;                     *(u32x4*)(C1 + row * LDC1 + 2048 + c) = pack8(ko0, ko1);
;                     *(u32x4*)(AA + row * DM + c) = pack8(ao0, ao1);
;                     *(u32x4*)(Ab + row * DM + c) = pack8(bo0, bo1);
;                 }
	v_fmac_f32_e32 v119, v120, v109
	v_fma_f32 v108, -v108, v119, v118
	v_div_fmas_f32 v108, v108, v109, v119
	v_div_fixup_f32 v109, v108, v89, 1.0
	v_div_scale_f32 v89, s[0:1], v88, v88, 1.0
	v_rcp_f32_e32 v108, v89
	s_nop 0
	v_fma_f32 v118, -v89, v108, 1.0
	v_fmac_f32_e32 v108, v118, v108
	v_div_scale_f32 v118, vcc, 1.0, v88, 1.0
	v_mul_f32_e32 v119, v118, v108
	v_fma_f32 v120, -v89, v119, v118
	v_fmac_f32_e32 v119, v120, v108
	v_fma_f32 v89, -v89, v119, v118
	v_div_fmas_f32 v89, v89, v108, v119
	v_div_fixup_f32 v108, v89, v88, 1.0
	v_pk_add_f32 v[88:89], v[108:109], -1.0 op_sel_hi:[1,0]
	s_nop 0
	v_pk_fma_f32 v[82:83], v[88:89], v[82:83], 1.0 op_sel_hi:[1,1,0]
	s_nop 0
	v_pk_mul_f32 v[82:83], v[82:83], v[116:117]
	s_nop 0
	v_cvt_pk_f16_f32 v88, v82, v83
	v_pk_add_f32 v[82:83], v[114:115], 1.0 op_sel_hi:[1,0]
	s_nop 0
	v_div_scale_f32 v89, s[0:1], v83, v83, 1.0
	v_rcp_f32_e32 v114, v89
	s_nop 0
	v_fma_f32 v115, -v89, v114, 1.0
	v_fmac_f32_e32 v114, v115, v114
	v_div_scale_f32 v115, vcc, 1.0, v83, 1.0
	v_mul_f32_e32 v116, v115, v114
	v_fma_f32 v117, -v89, v116, v115
	v_fmac_f32_e32 v116, v117, v114
	v_fma_f32 v89, -v89, v116, v115
	v_div_fmas_f32 v89, v89, v114, v116
	v_div_fixup_f32 v115, v89, v83, 1.0
	v_div_scale_f32 v83, s[0:1], v82, v82, 1.0
	v_rcp_f32_e32 v89, v83
	s_nop 0
	v_fma_f32 v114, -v83, v89, 1.0
	v_fmac_f32_e32 v89, v114, v89
	v_div_scale_f32 v114, vcc, 1.0, v82, 1.0
	v_mul_f32_e32 v116, v114, v89
	v_fma_f32 v117, -v83, v116, v114
	v_fmac_f32_e32 v116, v117, v89
	v_fma_f32 v83, -v83, v116, v114
	v_div_fmas_f32 v83, v83, v89, v116
	v_div_fixup_f32 v114, v83, v82, 1.0
	v_pk_add_f32 v[82:83], v[114:115], -1.0 op_sel_hi:[1,0]
	s_nop 0
	v_pk_fma_f32 v[82:83], v[82:83], v[84:85], 1.0 op_sel_hi:[1,1,0]
	v_cvt_f16_f32_e64 v84, -v122
	v_pk_mul_f32 v[82:83], v[82:83], v[112:113]
	s_nop 0
	v_cvt_pk_f16_f32 v89, v82, v83
	v_pk_mov_b32 v[82:83], v[94:95], v[110:111] op_sel:[1,0]
	global_store_dwordx4 v[90:91], v[86:89], off
	s_nop 1
	v_pk_mul_f32 v[86:87], v[82:83], v[102:103] op_sel_hi:[1,0]
	s_nop 0
	v_cvt_pk_f16_f32 v83, v86, v87
	v_pack_b32_f16 v82, v84, -v83
	v_pk_mov_b32 v[84:85], v[110:111], v[92:93] op_sel:[1,0]
	v_xor_b32_sdwa v83, s63, v83 dst_sel:DWORD dst_unused:UNUSED_PAD src0_sel:DWORD src1_sel:WORD_1
	v_pk_mul_f32 v[88:89], v[84:85], v[102:103] op_sel_hi:[1,0]
	s_nop 0
	v_cvt_pk_f16_f32 v84, v88, v89
	v_xor_b32_e32 v85, 0x8000, v84
	v_perm_b32 v83, v85, v83, s33
	v_xor_b32_sdwa v94, s63, v84 dst_sel:DWORD dst_unused:UNUSED_PAD src0_sel:DWORD src1_sel:WORD_1
	v_pk_mov_b32 v[84:85], v[92:93], v[96:97] op_sel:[1,0]
	v_cvt_f16_f32_e64 v92, -v103
	v_pk_mul_f32 v[90:91], v[84:85], v[102:103] op_sel_hi:[1,0]
	s_nop 0
	v_cvt_pk_f16_f32 v85, v90, v91
	v_xor_b32_e32 v84, 0x8000, v85
	v_xor_b32_sdwa v85, s63, v85 dst_sel:DWORD dst_unused:UNUSED_PAD src0_sel:DWORD src1_sel:WORD_1
	v_perm_b32 v84, v84, v94, s33
	v_perm_b32 v85, v92, v85, s33
	global_store_dwordx4 v[98:99], v[82:85], off offset:64
	s_nop 1
	v_pk_mov_b32 v[82:83], v[104:105], v[106:107] op_sel:[1,0]
	v_fma_mixlo_f16 v84, v104, v122, 0
	v_pk_mul_f32 v[82:83], v[82:83], v[86:87]
	s_nop 0
	v_cvt_pk_f16_f32 v83, v82, v83
	v_pack_b32_f16 v82, v84, v83
	v_pk_mov_b32 v[84:85], v[106:107], v[108:109] op_sel:[1,0]
	s_nop 0
	v_pk_mul_f32 v[84:85], v[84:85], v[88:89]
	s_nop 0
	v_cvt_pk_f16_f32 v86, v84, v85
	v_pk_mov_b32 v[84:85], v[108:109], v[114:115] op_sel:[1,0]
	v_alignbit_b32 v83, v86, v83, 16
	v_pk_mul_f32 v[84:85], v[84:85], v[90:91]
	s_nop 0
	v_cvt_pk_f16_f32 v85, v84, v85
	v_alignbit_b32 v84, v85, v86, 16
	v_lshrrev_b32_e32 v85, 16, v85
	v_fma_mixhi_f16 v85, v115, v103, 0
	global_store_dwordx4 v[100:101], v[82:85], off offset:64
	v_or_b32_e32 v106, 48, v158
	s_nop 0
	v_mad_i64_i32 v[82:83], s[0:1], v106, s5, v[160:161]
	v_lshl_add_u64 v[102:103], v[82:83], 0, s[6:7]
	global_load_dwordx4 v[94:97], v[154:155], off offset:16
	global_load_dwordx4 v[98:101], v[154:155], off
	global_load_dwordx4 v[82:85], v[156:157], off offset:16
	global_load_dwordx4 v[86:89], v[156:157], off
	v_lshl_add_u64 v[114:115], v[102:103], 0, v[152:153]
	global_load_dwordx4 v[90:93], v[114:115], off
	v_ashrrev_i32_e32 v107, 31, v106
	s_waitcnt vmcnt(4)
	v_add_f32_e32 v74, v74, v94
	v_mul_f32_e32 v74, 0xbfb8aa3b, v74
	v_exp_f32_e32 v122, v74
	s_waitcnt vmcnt(3)
	v_add_f32_e32 v74, v79, v99
	v_mul_f32_e32 v74, 0xbfb8aa3b, v74
	v_exp_f32_e32 v125, v74
	v_add_f32_e32 v74, v75, v95
	v_mul_f32_e32 v74, 0xbfb8aa3b, v74
	v_exp_f32_e32 v123, v74
	v_add_f32_e32 v74, v80, v100
	v_mul_f32_e32 v74, 0xbfb8aa3b, v74
	v_exp_f32_e32 v130, v74
	v_add_f32_e32 v74, v76, v96
	v_mul_f32_e32 v74, 0xbfb8aa3b, v74
	v_exp_f32_e32 v116, v74
	v_add_f32_e32 v74, v81, v101
	v_mul_f32_e32 v74, 0xbfb8aa3b, v74
	v_exp_f32_e32 v131, v74
	v_add_f32_e32 v74, v77, v97
	v_add_f32_e32 v78, v78, v98
	v_mul_f32_e32 v74, 0xbfb8aa3b, v74
	v_mul_f32_e32 v78, 0xbfb8aa3b, v78
	v_exp_f32_e32 v117, v74
	v_lshl_add_u64 v[74:75], v[102:103], 0, v[128:129]
	v_exp_f32_e32 v124, v78
	global_load_dwordx4 v[78:81], v[154:155], off offset:144
	global_load_dwordx4 v[94:97], v[154:155], off offset:128
	global_load_dwordx4 v[118:121], v[156:157], off offset:144
	global_load_dwordx4 v[132:135], v[156:157], off offset:128
	global_load_dwordx4 v[136:139], v[74:75], off
	v_pk_add_f32 v[130:131], v[130:131], 1.0 op_sel_hi:[1,0]
	v_pk_add_f32 v[124:125], v[124:125], 1.0 op_sel_hi:[1,0]
	s_waitcnt vmcnt(4)
	v_add_f32_e32 v66, v66, v78
	v_mul_f32_e32 v66, 0xbfb8aa3b, v66
	v_exp_f32_e32 v102, v66
	s_waitcnt vmcnt(3)
	v_add_f32_e32 v66, v71, v95
	s_waitcnt vmcnt(0)
; __device__ __forceinline__ float sigmoidf_(float x) { return 1.0f / (1.0f + __expf(-x)); }
;     __device__ __forceinline__ void body_a(const f32x4 (&acc)[2][2][4][2], int row0, int cb0) const {
;     ...
;                     const f32x4 b0 = *(const f32x4*)(a0 + c), b1 = *(const f32x4*)(a0 + c + 4), q0 = *(const f32x4*)(k_k + c), q1 = *(const f32x4*)(k_k + c + 4);
;                     const h16x8 kh = *(const h16x8*)(C1 + row * LDC1 + 2048 + c);
; #pragma unroll
;                     for (int e = 0; e < 4; ++e) {
;                         a[bj][e] = sigmoidf_(acc[ai][bj][m][0][e] + b0[e]); a[bj][4 + e] = sigmoidf_(acc[ai][bj][m][1][e] + b1[e]);
;                         kv[bj][e] = (float)kh[e]; kv[bj][4 + e] = (float)kh[4 + e];
;                         kk[bj][e] = kv[bj][e] * q0[e]; kk[bj][4 + e] = kv[bj][4 + e] * q1[e];
;                         ss += kk[bj][e] * kk[bj][e] + kk[bj][4 + e] * kk[bj][4 + e];
;                     }
;                 }
;                 ss += __shfl_xor(ss, 16); ss += __shfl_xor(ss, 32);
	v_cvt_f32_f16_e32 v100, v138
	v_cvt_f32_f16_sdwa v101, v138 dst_sel:DWORD dst_unused:UNUSED_PAD src0_sel:WORD_1
	v_cvt_f32_f16_e32 v110, v136
	v_cvt_f32_f16_sdwa v111, v136 dst_sel:DWORD dst_unused:UNUSED_PAD src0_sel:WORD_1
	v_mul_f32_e32 v66, 0xbfb8aa3b, v66
	v_exp_f32_e32 v113, v66
	v_add_f32_e32 v66, v67, v79
	v_mul_f32_e32 v66, 0xbfb8aa3b, v66
	v_pk_mul_f32 v[76:77], v[118:119], v[100:101]
	v_exp_f32_e32 v103, v66
	v_pk_mul_f32 v[78:79], v[132:133], v[110:111]
	v_pk_mul_f32 v[66:67], v[76:77], v[76:77]
	v_cvt_f32_f16_e32 v104, v137
	v_pk_fma_f32 v[118:119], v[78:79], v[78:79], v[66:67]
	v_add_f32_e32 v66, v72, v96
	v_mul_f32_e32 v66, 0xbfb8aa3b, v66
	v_exp_f32_e32 v108, v66
	v_add_f32_e32 v66, v68, v80
	v_mul_f32_e32 v66, 0xbfb8aa3b, v66
	v_exp_f32_e32 v98, v66
	v_add_f32_e32 v66, v73, v97
	v_cvt_f32_f16_e32 v96, v139
	v_cvt_f32_f16_sdwa v97, v139 dst_sel:DWORD dst_unused:UNUSED_PAD src0_sel:WORD_1
	v_cvt_f32_f16_sdwa v105, v137 dst_sel:DWORD dst_unused:UNUSED_PAD src0_sel:WORD_1
	v_mul_f32_e32 v66, 0xbfb8aa3b, v66
	v_exp_f32_e32 v109, v66
	v_add_f32_e32 v66, v69, v81
	v_add_f32_e32 v70, v70, v94
	v_mul_f32_e32 v66, 0xbfb8aa3b, v66
	v_pk_mul_f32 v[80:81], v[120:121], v[96:97]
	v_mul_f32_e32 v70, 0xbfb8aa3b, v70
	v_exp_f32_e32 v99, v66
	v_pk_mul_f32 v[94:95], v[134:135], v[104:105]
	v_pk_mul_f32 v[66:67], v[80:81], v[80:81]
	v_exp_f32_e32 v112, v70
	v_pk_fma_f32 v[120:121], v[94:95], v[94:95], v[66:67]
	global_load_dwordx4 v[66:69], v[126:127], off offset:16
	global_load_dwordx4 v[70:73], v[126:127], off
	v_cvt_f32_f16_e32 v132, v90
	v_cvt_f32_f16_sdwa v133, v90 dst_sel:DWORD dst_unused:UNUSED_PAD src0_sel:WORD_1
	v_div_scale_f32 v90, s[0:1], v125, v125, 1.0
	v_rcp_f32_e32 v134, v90
	s_nop 0
	v_fma_f32 v135, -v90, v134, 1.0
	v_fmac_f32_e32 v134, v135, v134
	v_div_scale_f32 v135, vcc, 1.0, v125, 1.0
	v_mul_f32_e32 v136, v135, v134
	v_fma_f32 v137, -v90, v136, v135
	v_fmac_f32_e32 v136, v137, v134
	v_fma_f32 v90, -v90, v136, v135
	v_div_fmas_f32 v90, v90, v134, v136
	v_div_fixup_f32 v125, v90, v125, 1.0
	v_div_scale_f32 v90, s[0:1], v124, v124, 1.0
	v_rcp_f32_e32 v134, v90
	s_nop 0
	v_fma_f32 v135, -v90, v134, 1.0
	v_fmac_f32_e32 v134, v135, v134
	v_div_scale_f32 v135, vcc, 1.0, v124, 1.0
	v_mul_f32_e32 v136, v135, v134
	v_fma_f32 v137, -v90, v136, v135
	v_fmac_f32_e32 v136, v137, v134
	v_fma_f32 v90, -v90, v136, v135
	v_div_fmas_f32 v90, v90, v134, v136
	v_div_fixup_f32 v124, v90, v124, 1.0
	v_pk_add_f32 v[134:135], v[124:125], -1.0 op_sel_hi:[1,0]
	v_cvt_f32_f16_e32 v90, v91
	v_cvt_f32_f16_sdwa v91, v91 dst_sel:DWORD dst_unused:UNUSED_PAD src0_sel:WORD_1
	s_waitcnt vmcnt(0)
	v_pk_fma_f32 v[70:71], v[134:135], v[70:71], 1.0 op_sel_hi:[1,1,0]
	s_nop 0
	v_pk_mul_f32 v[70:71], v[70:71], v[132:133]
	s_nop 0
	v_cvt_pk_f16_f32 v70, v70, v71
	v_div_scale_f32 v71, s[0:1], v131, v131, 1.0
	v_rcp_f32_e32 v134, v71
	s_nop 0
	v_fma_f32 v135, -v71, v134, 1.0
	v_fmac_f32_e32 v134, v135, v134
	v_div_scale_f32 v135, vcc, 1.0, v131, 1.0
	v_mul_f32_e32 v136, v135, v134
	v_fma_f32 v137, -v71, v136, v135
	v_fmac_f32_e32 v136, v137, v134
	v_fma_f32 v71, -v71, v136, v135
	v_div_fmas_f32 v71, v71, v134, v136
	v_div_fixup_f32 v131, v71, v131, 1.0
	v_div_scale_f32 v71, s[0:1], v130, v130, 1.0
	v_rcp_f32_e32 v134, v71
	s_nop 0
	v_fma_f32 v135, -v71, v134, 1.0
	v_fmac_f32_e32 v134, v135, v134
	v_div_scale_f32 v135, vcc, 1.0, v130, 1.0
	v_mul_f32_e32 v136, v135, v134
	v_fma_f32 v137, -v71, v136, v135
	v_fmac_f32_e32 v136, v137, v134
	v_fma_f32 v71, -v71, v136, v135
	v_div_fmas_f32 v71, v71, v134, v136
	v_div_fixup_f32 v130, v71, v130, 1.0
	v_pk_add_f32 v[134:135], v[130:131], -1.0 op_sel_hi:[1,0]
	s_nop 0
	v_pk_fma_f32 v[72:73], v[134:135], v[72:73], 1.0 op_sel_hi:[1,1,0]
	v_cvt_f32_f16_e32 v134, v92
	v_pk_mul_f32 v[72:73], v[72:73], v[90:91]
	v_cvt_f32_f16_sdwa v135, v92 dst_sel:DWORD dst_unused:UNUSED_PAD src0_sel:WORD_1
	v_cvt_pk_f16_f32 v71, v72, v73
	v_pk_add_f32 v[72:73], v[122:123], 1.0 op_sel_hi:[1,0]
	s_nop 0
	v_div_scale_f32 v92, s[0:1], v73, v73, 1.0
	v_rcp_f32_e32 v122, v92
	s_nop 0
	v_fma_f32 v123, -v92, v122, 1.0
	v_fmac_f32_e32 v122, v123, v122
	v_div_scale_f32 v123, vcc, 1.0, v73, 1.0
	v_mul_f32_e32 v136, v123, v122
	v_fma_f32 v137, -v92, v136, v123
	v_fmac_f32_e32 v136, v137, v122
	v_fma_f32 v92, -v92, v136, v123
	v_div_fmas_f32 v92, v92, v122, v136
	v_div_fixup_f32 v123, v92, v73, 1.0
	v_div_scale_f32 v73, s[0:1], v72, v72, 1.0
	v_rcp_f32_e32 v92, v73
	s_nop 0
	v_fma_f32 v122, -v73, v92, 1.0
	v_fmac_f32_e32 v92, v122, v92
	v_div_scale_f32 v122, vcc, 1.0, v72, 1.0
	v_mul_f32_e32 v136, v122, v92
	v_fma_f32 v137, -v73, v136, v122
	v_fmac_f32_e32 v136, v137, v92
	v_fma_f32 v73, -v73, v136, v122
	v_div_fmas_f32 v73, v73, v92, v136
	v_div_fixup_f32 v122, v73, v72, 1.0
	v_pk_add_f32 v[72:73], v[122:123], -1.0 op_sel_hi:[1,0]
	v_cvt_f32_f16_e32 v92, v93
	v_pk_fma_f32 v[66:67], v[72:73], v[66:67], 1.0 op_sel_hi:[1,1,0]
	v_cvt_f32_f16_sdwa v93, v93 dst_sel:DWORD dst_unused:UNUSED_PAD src0_sel:WORD_1
	v_pk_mul_f32 v[66:67], v[66:67], v[134:135]
	v_pk_mul_f32 v[84:85], v[84:85], v[92:93]
	v_cvt_pk_f16_f32 v72, v66, v67
	v_pk_add_f32 v[66:67], v[116:117], 1.0 op_sel_hi:[1,0]
	s_nop 0
	v_div_scale_f32 v73, s[0:1], v67, v67, 1.0
	v_rcp_f32_e32 v116, v73
	s_nop 0
	v_fma_f32 v117, -v73, v116, 1.0
	v_fmac_f32_e32 v116, v117, v116
	v_div_scale_f32 v117, vcc, 1.0, v67, 1.0
	v_mul_f32_e32 v136, v117, v116
	v_fma_f32 v137, -v73, v136, v117
	v_fmac_f32_e32 v136, v137, v116
	v_fma_f32 v73, -v73, v136, v117
	v_div_fmas_f32 v73, v73, v116, v136
	v_div_fixup_f32 v67, v73, v67, 1.0
	v_div_scale_f32 v73, s[0:1], v66, v66, 1.0
	v_rcp_f32_e32 v116, v73
	s_nop 0
	v_fma_f32 v117, -v73, v116, 1.0
	v_fmac_f32_e32 v116, v117, v116
	v_div_scale_f32 v117, vcc, 1.0, v66, 1.0
	v_mul_f32_e32 v136, v117, v116
	v_fma_f32 v137, -v73, v136, v117
	v_fmac_f32_e32 v136, v137, v116
	v_fma_f32 v73, -v73, v136, v117
	v_div_fmas_f32 v73, v73, v116, v136
	v_div_fixup_f32 v66, v73, v66, 1.0
	v_pk_add_f32 v[116:117], v[66:67], -1.0 op_sel_hi:[1,0]
	s_nop 0
	v_pk_fma_f32 v[68:69], v[116:117], v[68:69], 1.0 op_sel_hi:[1,1,0]
	s_nop 0
	v_pk_mul_f32 v[68:69], v[68:69], v[92:93]
	v_lshlrev_b64 v[92:93], 12, v[106:107]
	v_cvt_pk_f16_f32 v73, v68, v69
	global_store_dwordx4 v[114:115], v[70:73], off
	v_pk_mul_f32 v[68:69], v[86:87], v[132:133]
	v_pk_mul_f32 v[86:87], v[84:85], v[84:85]
	v_pk_mul_f32 v[72:73], v[82:83], v[134:135]
	v_pk_mul_f32 v[70:71], v[88:89], v[90:91]
	v_pk_mul_f32 v[82:83], v[72:73], v[72:73]
	v_pk_fma_f32 v[86:87], v[70:71], v[70:71], v[86:87]
	v_pk_fma_f32 v[82:83], v[68:69], v[68:69], v[82:83]
	s_nop 0
	v_add_f32_e32 v82, v82, v83
	v_add_f32_e32 v82, v86, v82
	v_add_f32_e32 v82, v87, v82
	v_add_f32_e32 v82, v82, v118
	v_add_f32_e32 v82, v119, v82
	v_add_f32_e32 v82, v120, v82
	v_add_f32_e32 v82, v121, v82
	ds_bpermute_b32 v83, v206, v82
	s_waitcnt lgkmcnt(0)
;     __device__ __forceinline__ void body_a(const f32x4 (&acc)[2][2][4][2], int row0, int cb0) const {
;     ...
;                 ss += __shfl_xor(ss, 16); ss += __shfl_xor(ss, 32);
;                 const float inv = 1.0f / fmaxf(sqrtf(ss), 1e-12f);
; #pragma unroll
;                 for (int bj = 0; bj < 2; ++bj) {
;                     const int c = cb0 + 32 * bj;
;                     const f32x4 p0 = *(const f32x4*)(k_a + c), p1 = *(const f32x4*)(k_a + c + 4);
;                     f32x4 ko0, ko1, ao0, ao1, bo0, bo1;
; #pragma unroll
;                     for (int e = 0; e < 4; ++e) {
;                         ko0[e] = kv[bj][e] * (1.0f + (a[bj][e] - 1.0f) * p0[e]); ko1[e] = kv[bj][4 + e] * (1.0f + (a[bj][4 + e] - 1.0f) * p1[e]);
;                         const float n0_ = kk[bj][e] * inv, n1_ = kk[bj][4 + e] * inv;
;                         ao0[e] = -n0_; ao1[e] = -n1_; bo0[e] = n0_ * a[bj][e]; bo1[e] = n1_ * a[bj][4 + e];
;                     }
;                     *(u32x4*)(C1 + row * LDC1 + 2048 + c) = pack8(ko0, ko1);
;                     *(u32x4*)(AA + row * DM + c) = pack8(ao0, ao1);
;                     *(u32x4*)(Ab + row * DM + c) = pack8(bo0, bo1);
	v_add_f32_e32 v82, v82, v83
	ds_bpermute_b32 v83, v207, v82
	s_waitcnt lgkmcnt(0)
	v_add_f32_e32 v82, v82, v83
	v_cmp_gt_f32_e32 vcc, s4, v82
	v_mul_f32_e32 v83, 0x4f800000, v82
	s_nop 0
	v_cndmask_b32_e32 v82, v82, v83, vcc
	v_sqrt_f32_e32 v83, v82
	s_nop 0
	v_add_u32_e32 v86, -1, v83
	v_fma_f32 v87, -v86, v83, v82
	v_cmp_ge_f32_e64 s[0:1], 0, v87
	v_add_u32_e32 v87, 1, v83
	s_nop 0
	v_cndmask_b32_e64 v86, v83, v86, s[0:1]
	v_fma_f32 v83, -v87, v83, v82
	v_cmp_lt_f32_e64 s[0:1], 0, v83
	s_nop 1
	v_cndmask_b32_e64 v83, v86, v87, s[0:1]
	v_mul_f32_e32 v86, 0x37800000, v83
	v_cndmask_b32_e32 v83, v83, v86, vcc
	v_cmp_class_f32_e32 vcc, v82, v244
	s_nop 1
	v_cndmask_b32_e32 v82, v83, v82, vcc
	v_max_f32_e32 v82, 0x2b8cbccc, v82
	v_div_scale_f32 v83, s[0:1], v82, v82, 1.0
	v_rcp_f32_e32 v86, v83
	s_nop 0
	v_fma_f32 v87, -v83, v86, 1.0
	v_fmac_f32_e32 v86, v87, v86
	v_div_scale_f32 v87, vcc, 1.0, v82, 1.0
	v_mul_f32_e32 v88, v87, v86
	v_fma_f32 v89, -v83, v88, v87
	v_fmac_f32_e32 v88, v89, v86
	v_fma_f32 v83, -v83, v88, v87
	v_div_fmas_f32 v83, v83, v86, v88
	v_div_fixup_f32 v86, v83, v82, 1.0
	v_pk_mul_f32 v[90:91], v[70:71], v[86:87] op_sel_hi:[1,0]
	v_pk_mul_f32 v[88:89], v[68:69], v[86:87] op_sel_hi:[1,0]
	v_cvt_pk_f16_f32 v69, v90, v91
	v_cvt_pk_f16_f32 v68, v88, v89
	v_xor_b32_e32 v70, 0x8000, v69
	v_xor_b32_sdwa v69, s63, v69 dst_sel:DWORD dst_unused:UNUSED_PAD src0_sel:DWORD src1_sel:WORD_1
	v_pk_mul_f32 v[72:73], v[72:73], v[86:87] op_sel_hi:[1,0]
	v_pk_mul_f32 v[84:85], v[84:85], v[86:87] op_sel_hi:[1,0]
	v_perm_b32 v69, v69, v70, s33
	v_xor_b32_e32 v70, 0x8000, v68
	v_xor_b32_sdwa v68, s63, v68 dst_sel:DWORD dst_unused:UNUSED_PAD src0_sel:DWORD src1_sel:WORD_1
	v_perm_b32 v68, v68, v70, s33
	v_pk_add_f32 v[70:71], v[72:73], 0 neg_lo:[1,1] neg_hi:[1,1]
	v_pk_add_f32 v[82:83], v[84:85], 0 neg_lo:[1,1] neg_hi:[1,1]
	v_cvt_pk_f16_f32 v70, v70, v71
	v_cvt_pk_f16_f32 v71, v82, v83
	v_lshl_add_u64 v[82:83], s[10:11], 0, v[92:93]
	v_lshl_add_u64 v[82:83], v[82:83], 0, v[152:153]
	global_store_dwordx4 v[82:83], v[68:71], off
	v_fma_mixlo_f16 v87, v124, v88, 0
	v_mul_f32_e32 v106, v78, v86
	v_pk_mov_b32 v[68:69], v[124:125], v[130:131] op_sel:[1,0]
	v_pk_mov_b32 v[70:71], v[88:89], v[90:91] op_sel:[1,0]
	v_pk_mov_b32 v[88:89], v[90:91], v[72:73] op_sel:[1,0]
	v_pk_mul_f32 v[68:69], v[68:69], v[70:71]
	v_pk_mov_b32 v[70:71], v[130:131], v[122:123] op_sel:[1,0]
	v_cvt_pk_f16_f32 v69, v68, v69
	v_pk_mul_f32 v[70:71], v[70:71], v[88:89]
	v_pack_b32_f16 v68, v87, v69
	v_cvt_pk_f16_f32 v87, v70, v71
	v_pk_mov_b32 v[70:71], v[122:123], v[66:67] op_sel:[1,0]
	v_pk_mov_b32 v[72:73], v[72:73], v[84:85] op_sel:[1,0]
	v_alignbit_b32 v69, v87, v69, 16
	v_pk_mul_f32 v[70:71], v[70:71], v[72:73]
	v_pk_add_f32 v[88:89], v[112:113], 1.0 op_sel_hi:[1,0]
	v_cvt_pk_f16_f32 v66, v70, v71
	v_lshrrev_b32_e32 v71, 16, v66
	v_alignbit_b32 v70, v66, v87, 16
	v_fma_mixhi_f16 v71, v67, v85, 0
	v_lshl_add_u64 v[66:67], s[2:3], 0, v[92:93]
	v_lshl_add_u64 v[84:85], v[66:67], 0, v[152:153]
	global_store_dwordx4 v[84:85], v[68:71], off
	global_load_dwordx4 v[66:69], v[126:127], off offset:144
	s_nop 0
	global_load_dwordx4 v[70:73], v[126:127], off offset:128
	v_div_scale_f32 v90, s[0:1], v89, v89, 1.0
	v_rcp_f32_e32 v91, v90
	v_mul_f32_e32 v87, v81, v86
	v_fma_f32 v92, -v90, v91, 1.0
	v_fmac_f32_e32 v91, v92, v91
	v_div_scale_f32 v92, vcc, 1.0, v89, 1.0
	v_mul_f32_e32 v93, v92, v91
	v_fma_f32 v107, -v90, v93, v92
	v_fmac_f32_e32 v93, v107, v91
	v_fma_f32 v90, -v90, v93, v92
	v_div_fmas_f32 v90, v90, v91, v93
	v_div_fixup_f32 v89, v90, v89, 1.0
	v_div_scale_f32 v90, s[0:1], v88, v88, 1.0
	v_rcp_f32_e32 v91, v90
	s_nop 0
	v_fma_f32 v92, -v90, v91, 1.0
	v_fmac_f32_e32 v91, v92, v91
	v_div_scale_f32 v92, vcc, 1.0, v88, 1.0
	v_mul_f32_e32 v93, v92, v91
	v_fma_f32 v107, -v90, v93, v92
	v_fmac_f32_e32 v93, v107, v91
	v_fma_f32 v90, -v90, v93, v92
	v_div_fmas_f32 v90, v90, v91, v93
	v_div_fixup_f32 v88, v90, v88, 1.0
	v_pk_add_f32 v[90:91], v[88:89], -1.0 op_sel_hi:[1,0]
	s_waitcnt vmcnt(0)
	v_pk_fma_f32 v[70:71], v[90:91], v[70:71], 1.0 op_sel_hi:[1,1,0]
	s_nop 0
	v_pk_mul_f32 v[70:71], v[70:71], v[110:111]
	v_pk_add_f32 v[90:91], v[108:109], 1.0 op_sel_hi:[1,0]
	v_cvt_pk_f16_f32 v70, v70, v71
	v_div_scale_f32 v71, s[0:1], v91, v91, 1.0
	v_rcp_f32_e32 v92, v71
	s_nop 0
	v_fma_f32 v93, -v71, v92, 1.0
	v_fmac_f32_e32 v92, v93, v92
	v_div_scale_f32 v93, vcc, 1.0, v91, 1.0
	v_mul_f32_e32 v107, v93, v92
	v_fma_f32 v108, -v71, v107, v93
	v_fmac_f32_e32 v107, v108, v92
	v_fma_f32 v71, -v71, v107, v93
	v_div_fmas_f32 v71, v71, v92, v107
	v_div_fixup_f32 v91, v71, v91, 1.0
	v_div_scale_f32 v71, s[0:1], v90, v90, 1.0
	v_rcp_f32_e32 v92, v71
	s_nop 0
	v_fma_f32 v93, -v71, v92, 1.0
	v_fmac_f32_e32 v92, v93, v92
	v_div_scale_f32 v93, vcc, 1.0, v90, 1.0
	v_mul_f32_e32 v107, v93, v92
	v_fma_f32 v108, -v71, v107, v93
	v_fmac_f32_e32 v107, v108, v92
	v_fma_f32 v71, -v71, v107, v93
	v_div_fmas_f32 v71, v71, v92, v107
	v_div_fixup_f32 v90, v71, v90, 1.0
	v_pk_add_f32 v[92:93], v[90:91], -1.0 op_sel_hi:[1,0]
	s_nop 0
	v_pk_fma_f32 v[72:73], v[92:93], v[72:73], 1.0 op_sel_hi:[1,1,0]
	s_nop 0
	v_pk_mul_f32 v[72:73], v[72:73], v[104:105]
	s_nop 0
	v_cvt_pk_f16_f32 v71, v72, v73
	v_pk_add_f32 v[72:73], v[102:103], 1.0 op_sel_hi:[1,0]
	s_nop 0
	v_div_scale_f32 v92, s[0:1], v73, v73, 1.0
	v_rcp_f32_e32 v93, v92
	s_nop 0
	v_fma_f32 v102, -v92, v93, 1.0
	v_fmac_f32_e32 v93, v102, v93
	v_div_scale_f32 v102, vcc, 1.0, v73, 1.0
	v_mul_f32_e32 v103, v102, v93
	v_fma_f32 v104, -v92, v103, v102
	v_fmac_f32_e32 v103, v104, v93
	v_fma_f32 v92, -v92, v103, v102
	v_div_fmas_f32 v92, v92, v93, v103
; __device__ __forceinline__ float sigmoidf_(float x) { return 1.0f / (1.0f + __expf(-x)); }
;     __device__ __forceinline__ void body_a(const f32x4 (&acc)[2][2][4][2], int row0, int cb0) const {
;     ...
;                     const int c = cb0 + 32 * bj;
;                     const f32x4 b0 = *(const f32x4*)(a0 + c), b1 = *(const f32x4*)(a0 + c + 4), q0 = *(const f32x4*)(k_k + c), q1 = *(const f32x4*)(k_k + c + 4);
;                     const h16x8 kh = *(const h16x8*)(C1 + row * LDC1 + 2048 + c);
; #pragma unroll
;                     for (int e = 0; e < 4; ++e) {
;                         a[bj][e] = sigmoidf_(acc[ai][bj][m][0][e] + b0[e]); a[bj][4 + e] = sigmoidf_(acc[ai][bj][m][1][e] + b1[e]);
;     ...
;                     const f32x4 p0 = *(const f32x4*)(k_a + c), p1 = *(const f32x4*)(k_a + c + 4);
;                     f32x4 ko0, ko1, ao0, ao1, bo0, bo1;
; #pragma unroll
;                     for (int e = 0; e < 4; ++e) {
;                         ko0[e] = kv[bj][e] * (1.0f + (a[bj][e] - 1.0f) * p0[e]); ko1[e] = kv[bj][4 + e] * (1.0f + (a[bj][4 + e] - 1.0f) * p1[e]);
;                         const float n0_ = kk[bj][e] * inv, n1_ = kk[bj][4 + e] * inv;
;                         ao0[e] = -n0_; ao1[e] = -n1_; bo0[e] = n0_ * a[bj][e]; bo1[e] = n1_ * a[bj][4 + e];
;                     }
;                     *(u32x4*)(C1 + row * LDC1 + 2048 + c) = pack8(ko0, ko1);
;                     *(u32x4*)(AA + row * DM + c) = pack8(ao0, ao1);
;                     *(u32x4*)(Ab + row * DM + c) = pack8(bo0, bo1);
;                 }
	v_div_fixup_f32 v93, v92, v73, 1.0
	v_div_scale_f32 v73, s[0:1], v72, v72, 1.0
	v_rcp_f32_e32 v92, v73
	s_nop 0
	v_fma_f32 v102, -v73, v92, 1.0
	v_fmac_f32_e32 v92, v102, v92
	v_div_scale_f32 v102, vcc, 1.0, v72, 1.0
	v_mul_f32_e32 v103, v102, v92
	v_fma_f32 v104, -v73, v103, v102
	v_fmac_f32_e32 v103, v104, v92
	v_fma_f32 v73, -v73, v103, v102
	v_div_fmas_f32 v73, v73, v92, v103
	v_div_fixup_f32 v92, v73, v72, 1.0
	v_pk_add_f32 v[72:73], v[92:93], -1.0 op_sel_hi:[1,0]
	s_nop 0
	v_pk_fma_f32 v[66:67], v[72:73], v[66:67], 1.0 op_sel_hi:[1,1,0]
	s_nop 0
	v_pk_mul_f32 v[66:67], v[66:67], v[100:101]
	s_nop 0
	v_cvt_pk_f16_f32 v72, v66, v67
	v_pk_add_f32 v[66:67], v[98:99], 1.0 op_sel_hi:[1,0]
	s_nop 0
	v_div_scale_f32 v73, s[0:1], v67, v67, 1.0
	v_rcp_f32_e32 v98, v73
	s_nop 0
	v_fma_f32 v99, -v73, v98, 1.0
	v_fmac_f32_e32 v98, v99, v98
	v_div_scale_f32 v99, vcc, 1.0, v67, 1.0
	v_mul_f32_e32 v100, v99, v98
	v_fma_f32 v101, -v73, v100, v99
	v_fmac_f32_e32 v100, v101, v98
	v_fma_f32 v73, -v73, v100, v99
	v_div_fmas_f32 v73, v73, v98, v100
	v_div_fixup_f32 v99, v73, v67, 1.0
	v_div_scale_f32 v67, s[0:1], v66, v66, 1.0
	v_rcp_f32_e32 v73, v67
	s_nop 0
	v_fma_f32 v98, -v67, v73, 1.0
	v_fmac_f32_e32 v73, v98, v73
	v_div_scale_f32 v98, vcc, 1.0, v66, 1.0
	v_mul_f32_e32 v100, v98, v73
	v_fma_f32 v101, -v67, v100, v98
	v_fmac_f32_e32 v100, v101, v73
	v_fma_f32 v67, -v67, v100, v98
	v_div_fmas_f32 v67, v67, v73, v100
	v_div_fixup_f32 v98, v67, v66, 1.0
	v_pk_add_f32 v[66:67], v[98:99], -1.0 op_sel_hi:[1,0]
	s_nop 0
	v_pk_fma_f32 v[66:67], v[66:67], v[68:69], 1.0 op_sel_hi:[1,1,0]
	v_cvt_f16_f32_e64 v68, -v106
	v_pk_mul_f32 v[66:67], v[66:67], v[96:97]
	s_nop 0
	v_cvt_pk_f16_f32 v73, v66, v67
	v_pk_mov_b32 v[66:67], v[78:79], v[94:95] op_sel:[1,0]
	global_store_dwordx4 v[74:75], v[70:73], off
	s_nop 1
	v_pk_mul_f32 v[70:71], v[66:67], v[86:87] op_sel_hi:[1,0]
	s_nop 0
	v_cvt_pk_f16_f32 v67, v70, v71
	v_pack_b32_f16 v66, v68, -v67
	v_pk_mov_b32 v[68:69], v[94:95], v[76:77] op_sel:[1,0]
	v_xor_b32_sdwa v67, s63, v67 dst_sel:DWORD dst_unused:UNUSED_PAD src0_sel:DWORD src1_sel:WORD_1
	v_pk_mul_f32 v[72:73], v[68:69], v[86:87] op_sel_hi:[1,0]
	s_nop 0
	v_cvt_pk_f16_f32 v68, v72, v73
	v_xor_b32_e32 v69, 0x8000, v68
	v_perm_b32 v67, v69, v67, s33
	v_xor_b32_sdwa v78, s63, v68 dst_sel:DWORD dst_unused:UNUSED_PAD src0_sel:DWORD src1_sel:WORD_1
	v_pk_mov_b32 v[68:69], v[76:77], v[80:81] op_sel:[1,0]
	v_cvt_f16_f32_e64 v76, -v87
	v_pk_mul_f32 v[74:75], v[68:69], v[86:87] op_sel_hi:[1,0]
	s_nop 0
	v_cvt_pk_f16_f32 v69, v74, v75
	v_xor_b32_e32 v68, 0x8000, v69
	v_xor_b32_sdwa v69, s63, v69 dst_sel:DWORD dst_unused:UNUSED_PAD src0_sel:DWORD src1_sel:WORD_1
	v_perm_b32 v68, v68, v78, s33
	v_perm_b32 v69, v76, v69, s33
	global_store_dwordx4 v[82:83], v[66:69], off offset:64
	s_nop 1
	v_pk_mov_b32 v[66:67], v[88:89], v[90:91] op_sel:[1,0]
	v_fma_mixlo_f16 v68, v88, v106, 0
	v_pk_mul_f32 v[66:67], v[66:67], v[70:71]
	s_nop 0
	v_cvt_pk_f16_f32 v67, v66, v67
	v_pack_b32_f16 v66, v68, v67
	v_pk_mov_b32 v[68:69], v[90:91], v[92:93] op_sel:[1,0]
	s_nop 0
	v_pk_mul_f32 v[68:69], v[68:69], v[72:73]
	s_nop 0
	v_cvt_pk_f16_f32 v70, v68, v69
	v_pk_mov_b32 v[68:69], v[92:93], v[98:99] op_sel:[1,0]
	v_alignbit_b32 v67, v70, v67, 16
	v_pk_mul_f32 v[68:69], v[68:69], v[74:75]
	s_nop 0
	v_cvt_pk_f16_f32 v69, v68, v69
	v_alignbit_b32 v68, v69, v70, 16
	v_lshrrev_b32_e32 v69, 16, v69
	v_fma_mixhi_f16 v69, v99, v87, 0
	global_store_dwordx4 v[84:85], v[66:69], off offset:64
	v_add_u32_e32 v90, 0x80, v158
	s_nop 0
	v_mad_i64_i32 v[66:67], s[0:1], v90, s5, v[160:161]
	v_lshl_add_u64 v[86:87], v[66:67], 0, s[6:7]
	global_load_dwordx4 v[78:81], v[154:155], off offset:16
	global_load_dwordx4 v[82:85], v[154:155], off
	global_load_dwordx4 v[66:69], v[156:157], off offset:16
	global_load_dwordx4 v[70:73], v[156:157], off
	v_lshl_add_u64 v[98:99], v[86:87], 0, v[152:153]
	global_load_dwordx4 v[74:77], v[98:99], off
	v_ashrrev_i32_e32 v91, 31, v90
	s_waitcnt vmcnt(4)
	v_add_f32_e32 v58, v58, v78
	v_mul_f32_e32 v58, 0xbfb8aa3b, v58
	v_exp_f32_e32 v106, v58
	s_waitcnt vmcnt(3)
	v_add_f32_e32 v58, v63, v83
	v_mul_f32_e32 v58, 0xbfb8aa3b, v58
	v_exp_f32_e32 v109, v58
	v_add_f32_e32 v58, v59, v79
	v_mul_f32_e32 v58, 0xbfb8aa3b, v58
	v_exp_f32_e32 v107, v58
	v_add_f32_e32 v58, v64, v84
	v_mul_f32_e32 v58, 0xbfb8aa3b, v58
	v_exp_f32_e32 v110, v58
	v_add_f32_e32 v58, v60, v80
	v_mul_f32_e32 v58, 0xbfb8aa3b, v58
	v_exp_f32_e32 v100, v58
	v_add_f32_e32 v58, v65, v85
	v_mul_f32_e32 v58, 0xbfb8aa3b, v58
	v_exp_f32_e32 v111, v58
	v_add_f32_e32 v58, v61, v81
	v_add_f32_e32 v62, v62, v82
	v_mul_f32_e32 v58, 0xbfb8aa3b, v58
	v_mul_f32_e32 v62, 0xbfb8aa3b, v62
	v_exp_f32_e32 v101, v58
	v_lshl_add_u64 v[58:59], v[86:87], 0, v[128:129]
	v_exp_f32_e32 v108, v62
	global_load_dwordx4 v[62:65], v[154:155], off offset:144
	global_load_dwordx4 v[78:81], v[154:155], off offset:128
	global_load_dwordx4 v[102:105], v[156:157], off offset:144
	global_load_dwordx4 v[112:115], v[156:157], off offset:128
	global_load_dwordx4 v[116:119], v[58:59], off
	v_pk_add_f32 v[110:111], v[110:111], 1.0 op_sel_hi:[1,0]
	v_pk_add_f32 v[108:109], v[108:109], 1.0 op_sel_hi:[1,0]
	s_waitcnt vmcnt(4)
	v_add_f32_e32 v50, v50, v62
	v_mul_f32_e32 v50, 0xbfb8aa3b, v50
	v_exp_f32_e32 v86, v50
	s_waitcnt vmcnt(3)
	v_add_f32_e32 v50, v55, v79
	s_waitcnt vmcnt(0)
; __device__ __forceinline__ float sigmoidf_(float x) { return 1.0f / (1.0f + __expf(-x)); }
;     __device__ __forceinline__ void body_a(const f32x4 (&acc)[2][2][4][2], int row0, int cb0) const {
;     ...
;                     const int c = cb0 + 32 * bj;
;                     const f32x4 b0 = *(const f32x4*)(a0 + c), b1 = *(const f32x4*)(a0 + c + 4), q0 = *(const f32x4*)(k_k + c), q1 = *(const f32x4*)(k_k + c + 4);
;                     const h16x8 kh = *(const h16x8*)(C1 + row * LDC1 + 2048 + c);
; #pragma unroll
;                     for (int e = 0; e < 4; ++e) {
;                         a[bj][e] = sigmoidf_(acc[ai][bj][m][0][e] + b0[e]); a[bj][4 + e] = sigmoidf_(acc[ai][bj][m][1][e] + b1[e]);
;                         kv[bj][e] = (float)kh[e]; kv[bj][4 + e] = (float)kh[4 + e];
;                         kk[bj][e] = kv[bj][e] * q0[e]; kk[bj][4 + e] = kv[bj][4 + e] * q1[e];
;                         ss += kk[bj][e] * kk[bj][e] + kk[bj][4 + e] * kk[bj][4 + e];
;                     }
;     ...
;                         ko0[e] = kv[bj][e] * (1.0f + (a[bj][e] - 1.0f) * p0[e]); ko1[e] = kv[bj][4 + e] * (1.0f + (a[bj][4 + e] - 1.0f) * p1[e]);
;                         const float n0_ = kk[bj][e] * inv, n1_ = kk[bj][4 + e] * inv;
;                         ao0[e] = -n0_; ao1[e] = -n1_; bo0[e] = n0_ * a[bj][e]; bo1[e] = n1_ * a[bj][4 + e];
;                     }
;                     *(u32x4*)(C1 + row * LDC1 + 2048 + c) = pack8(ko0, ko1);
	v_cvt_f32_f16_e32 v84, v118
	v_cvt_f32_f16_sdwa v85, v118 dst_sel:DWORD dst_unused:UNUSED_PAD src0_sel:WORD_1
	v_cvt_f32_f16_e32 v94, v116
	v_cvt_f32_f16_sdwa v95, v116 dst_sel:DWORD dst_unused:UNUSED_PAD src0_sel:WORD_1
	v_mul_f32_e32 v50, 0xbfb8aa3b, v50
	v_exp_f32_e32 v97, v50
	v_add_f32_e32 v50, v51, v63
	v_mul_f32_e32 v50, 0xbfb8aa3b, v50
	v_pk_mul_f32 v[60:61], v[102:103], v[84:85]
	v_exp_f32_e32 v87, v50
	v_pk_mul_f32 v[62:63], v[112:113], v[94:95]
	v_pk_mul_f32 v[50:51], v[60:61], v[60:61]
	v_cvt_f32_f16_e32 v88, v117
	v_pk_fma_f32 v[102:103], v[62:63], v[62:63], v[50:51]
	v_add_f32_e32 v50, v56, v80
	v_mul_f32_e32 v50, 0xbfb8aa3b, v50
	v_exp_f32_e32 v92, v50
	v_add_f32_e32 v50, v52, v64
	v_mul_f32_e32 v50, 0xbfb8aa3b, v50
	v_exp_f32_e32 v82, v50
	v_add_f32_e32 v50, v57, v81
	v_cvt_f32_f16_e32 v80, v119
	v_cvt_f32_f16_sdwa v81, v119 dst_sel:DWORD dst_unused:UNUSED_PAD src0_sel:WORD_1
	v_cvt_f32_f16_sdwa v89, v117 dst_sel:DWORD dst_unused:UNUSED_PAD src0_sel:WORD_1
	v_mul_f32_e32 v50, 0xbfb8aa3b, v50
	v_exp_f32_e32 v93, v50
	v_add_f32_e32 v50, v53, v65
	v_add_f32_e32 v54, v54, v78
	v_mul_f32_e32 v50, 0xbfb8aa3b, v50
	v_pk_mul_f32 v[64:65], v[104:105], v[80:81]
	v_mul_f32_e32 v54, 0xbfb8aa3b, v54
	v_exp_f32_e32 v83, v50
	v_pk_mul_f32 v[78:79], v[114:115], v[88:89]
	v_pk_mul_f32 v[50:51], v[64:65], v[64:65]
	v_exp_f32_e32 v96, v54
	v_pk_fma_f32 v[104:105], v[78:79], v[78:79], v[50:51]
	global_load_dwordx4 v[50:53], v[126:127], off offset:16
	global_load_dwordx4 v[54:57], v[126:127], off
	v_cvt_f32_f16_e32 v112, v74
	v_cvt_f32_f16_sdwa v113, v74 dst_sel:DWORD dst_unused:UNUSED_PAD src0_sel:WORD_1
	v_div_scale_f32 v74, s[0:1], v109, v109, 1.0
	v_rcp_f32_e32 v114, v74
	s_nop 0
	v_fma_f32 v115, -v74, v114, 1.0
	v_fmac_f32_e32 v114, v115, v114
	v_div_scale_f32 v115, vcc, 1.0, v109, 1.0
	v_mul_f32_e32 v116, v115, v114
	v_fma_f32 v117, -v74, v116, v115
	v_fmac_f32_e32 v116, v117, v114
	v_fma_f32 v74, -v74, v116, v115
	v_div_fmas_f32 v74, v74, v114, v116
	v_div_fixup_f32 v109, v74, v109, 1.0
	v_div_scale_f32 v74, s[0:1], v108, v108, 1.0
	v_rcp_f32_e32 v114, v74
	s_nop 0
	v_fma_f32 v115, -v74, v114, 1.0
	v_fmac_f32_e32 v114, v115, v114
	v_div_scale_f32 v115, vcc, 1.0, v108, 1.0
	v_mul_f32_e32 v116, v115, v114
	v_fma_f32 v117, -v74, v116, v115
	v_fmac_f32_e32 v116, v117, v114
	v_fma_f32 v74, -v74, v116, v115
	v_div_fmas_f32 v74, v74, v114, v116
	v_div_fixup_f32 v108, v74, v108, 1.0
	v_pk_add_f32 v[114:115], v[108:109], -1.0 op_sel_hi:[1,0]
	v_cvt_f32_f16_e32 v74, v75
	v_cvt_f32_f16_sdwa v75, v75 dst_sel:DWORD dst_unused:UNUSED_PAD src0_sel:WORD_1
	s_waitcnt vmcnt(0)
	v_pk_fma_f32 v[54:55], v[114:115], v[54:55], 1.0 op_sel_hi:[1,1,0]
	s_nop 0
	v_pk_mul_f32 v[54:55], v[54:55], v[112:113]
	s_nop 0
	v_cvt_pk_f16_f32 v54, v54, v55
	v_div_scale_f32 v55, s[0:1], v111, v111, 1.0
	v_rcp_f32_e32 v114, v55
	s_nop 0
	v_fma_f32 v115, -v55, v114, 1.0
	v_fmac_f32_e32 v114, v115, v114
	v_div_scale_f32 v115, vcc, 1.0, v111, 1.0
	v_mul_f32_e32 v116, v115, v114
	v_fma_f32 v117, -v55, v116, v115
	v_fmac_f32_e32 v116, v117, v114
	v_fma_f32 v55, -v55, v116, v115
	v_div_fmas_f32 v55, v55, v114, v116
	v_div_fixup_f32 v111, v55, v111, 1.0
	v_div_scale_f32 v55, s[0:1], v110, v110, 1.0
	v_rcp_f32_e32 v114, v55
	s_nop 0
	v_fma_f32 v115, -v55, v114, 1.0
	v_fmac_f32_e32 v114, v115, v114
	v_div_scale_f32 v115, vcc, 1.0, v110, 1.0
	v_mul_f32_e32 v116, v115, v114
	v_fma_f32 v117, -v55, v116, v115
	v_fmac_f32_e32 v116, v117, v114
	v_fma_f32 v55, -v55, v116, v115
	v_div_fmas_f32 v55, v55, v114, v116
	v_div_fixup_f32 v110, v55, v110, 1.0
	v_pk_add_f32 v[114:115], v[110:111], -1.0 op_sel_hi:[1,0]
	s_nop 0
	v_pk_fma_f32 v[56:57], v[114:115], v[56:57], 1.0 op_sel_hi:[1,1,0]
	v_cvt_f32_f16_e32 v114, v76
	v_pk_mul_f32 v[56:57], v[56:57], v[74:75]
	v_cvt_f32_f16_sdwa v115, v76 dst_sel:DWORD dst_unused:UNUSED_PAD src0_sel:WORD_1
	v_cvt_pk_f16_f32 v55, v56, v57
	v_pk_add_f32 v[56:57], v[106:107], 1.0 op_sel_hi:[1,0]
	s_nop 0
	v_div_scale_f32 v76, s[0:1], v57, v57, 1.0
	v_rcp_f32_e32 v106, v76
	s_nop 0
	v_fma_f32 v107, -v76, v106, 1.0
	v_fmac_f32_e32 v106, v107, v106
	v_div_scale_f32 v107, vcc, 1.0, v57, 1.0
	v_mul_f32_e32 v116, v107, v106
	v_fma_f32 v117, -v76, v116, v107
	v_fmac_f32_e32 v116, v117, v106
	v_fma_f32 v76, -v76, v116, v107
	v_div_fmas_f32 v76, v76, v106, v116
	v_div_fixup_f32 v107, v76, v57, 1.0
	v_div_scale_f32 v57, s[0:1], v56, v56, 1.0
	v_rcp_f32_e32 v76, v57
	s_nop 0
	v_fma_f32 v106, -v57, v76, 1.0
	v_fmac_f32_e32 v76, v106, v76
	v_div_scale_f32 v106, vcc, 1.0, v56, 1.0
	v_mul_f32_e32 v116, v106, v76
	v_fma_f32 v117, -v57, v116, v106
	v_fmac_f32_e32 v116, v117, v76
	v_fma_f32 v57, -v57, v116, v106
	v_div_fmas_f32 v57, v57, v76, v116
	v_div_fixup_f32 v106, v57, v56, 1.0
	v_pk_add_f32 v[56:57], v[106:107], -1.0 op_sel_hi:[1,0]
	v_cvt_f32_f16_e32 v76, v77
	v_pk_fma_f32 v[50:51], v[56:57], v[50:51], 1.0 op_sel_hi:[1,1,0]
	v_cvt_f32_f16_sdwa v77, v77 dst_sel:DWORD dst_unused:UNUSED_PAD src0_sel:WORD_1
	v_pk_mul_f32 v[50:51], v[50:51], v[114:115]
	v_pk_mul_f32 v[68:69], v[68:69], v[76:77]
	v_cvt_pk_f16_f32 v56, v50, v51
	v_pk_add_f32 v[50:51], v[100:101], 1.0 op_sel_hi:[1,0]
	s_nop 0
	v_div_scale_f32 v57, s[0:1], v51, v51, 1.0
	v_rcp_f32_e32 v100, v57
	s_nop 0
	v_fma_f32 v101, -v57, v100, 1.0
	v_fmac_f32_e32 v100, v101, v100
	v_div_scale_f32 v101, vcc, 1.0, v51, 1.0
	v_mul_f32_e32 v116, v101, v100
	v_fma_f32 v117, -v57, v116, v101
	v_fmac_f32_e32 v116, v117, v100
	v_fma_f32 v57, -v57, v116, v101
	v_div_fmas_f32 v57, v57, v100, v116
	v_div_fixup_f32 v51, v57, v51, 1.0
	v_div_scale_f32 v57, s[0:1], v50, v50, 1.0
	v_rcp_f32_e32 v100, v57
	s_nop 0
	v_fma_f32 v101, -v57, v100, 1.0
	v_fmac_f32_e32 v100, v101, v100
	v_div_scale_f32 v101, vcc, 1.0, v50, 1.0
	v_mul_f32_e32 v116, v101, v100
	v_fma_f32 v117, -v57, v116, v101
	v_fmac_f32_e32 v116, v117, v100
	v_fma_f32 v57, -v57, v116, v101
	v_div_fmas_f32 v57, v57, v100, v116
	v_div_fixup_f32 v50, v57, v50, 1.0
	v_pk_add_f32 v[100:101], v[50:51], -1.0 op_sel_hi:[1,0]
	s_nop 0
	v_pk_fma_f32 v[52:53], v[100:101], v[52:53], 1.0 op_sel_hi:[1,1,0]
	s_nop 0
	v_pk_mul_f32 v[52:53], v[52:53], v[76:77]
	v_lshlrev_b64 v[76:77], 12, v[90:91]
	v_cvt_pk_f16_f32 v57, v52, v53
	global_store_dwordx4 v[98:99], v[54:57], off
	v_pk_mul_f32 v[52:53], v[70:71], v[112:113]
	v_pk_mul_f32 v[70:71], v[68:69], v[68:69]
	v_pk_mul_f32 v[56:57], v[66:67], v[114:115]
	v_pk_mul_f32 v[54:55], v[72:73], v[74:75]
	v_pk_mul_f32 v[66:67], v[56:57], v[56:57]
	v_pk_fma_f32 v[70:71], v[54:55], v[54:55], v[70:71]
	v_pk_fma_f32 v[66:67], v[52:53], v[52:53], v[66:67]
	s_nop 0
	v_add_f32_e32 v66, v66, v67
	v_add_f32_e32 v66, v70, v66
	v_add_f32_e32 v66, v71, v66
	v_add_f32_e32 v66, v66, v102
	v_add_f32_e32 v66, v103, v66
	v_add_f32_e32 v66, v104, v66
	v_add_f32_e32 v66, v105, v66
	ds_bpermute_b32 v67, v206, v66
	s_waitcnt lgkmcnt(0)
;     __device__ __forceinline__ void body_a(const f32x4 (&acc)[2][2][4][2], int row0, int cb0) const {
;     ...
;                 ss += __shfl_xor(ss, 16); ss += __shfl_xor(ss, 32);
;                 const float inv = 1.0f / fmaxf(sqrtf(ss), 1e-12f);
; #pragma unroll
;                 for (int bj = 0; bj < 2; ++bj) {
;                     const int c = cb0 + 32 * bj;
;                     const f32x4 p0 = *(const f32x4*)(k_a + c), p1 = *(const f32x4*)(k_a + c + 4);
;                     f32x4 ko0, ko1, ao0, ao1, bo0, bo1;
; #pragma unroll
;                     for (int e = 0; e < 4; ++e) {
;                         ko0[e] = kv[bj][e] * (1.0f + (a[bj][e] - 1.0f) * p0[e]); ko1[e] = kv[bj][4 + e] * (1.0f + (a[bj][4 + e] - 1.0f) * p1[e]);
;                         const float n0_ = kk[bj][e] * inv, n1_ = kk[bj][4 + e] * inv;
;                         ao0[e] = -n0_; ao1[e] = -n1_; bo0[e] = n0_ * a[bj][e]; bo1[e] = n1_ * a[bj][4 + e];
;                     }
;                     *(u32x4*)(C1 + row * LDC1 + 2048 + c) = pack8(ko0, ko1);
;                     *(u32x4*)(AA + row * DM + c) = pack8(ao0, ao1);
;                     *(u32x4*)(Ab + row * DM + c) = pack8(bo0, bo1);
	v_add_f32_e32 v66, v66, v67
	ds_bpermute_b32 v67, v207, v66
	s_waitcnt lgkmcnt(0)
	v_add_f32_e32 v66, v66, v67
	v_cmp_gt_f32_e32 vcc, s4, v66
	v_mul_f32_e32 v67, 0x4f800000, v66
	s_nop 0
	v_cndmask_b32_e32 v66, v66, v67, vcc
	v_sqrt_f32_e32 v67, v66
	s_nop 0
	v_add_u32_e32 v70, -1, v67
	v_fma_f32 v71, -v70, v67, v66
	v_cmp_ge_f32_e64 s[0:1], 0, v71
	v_add_u32_e32 v71, 1, v67
	s_nop 0
	v_cndmask_b32_e64 v70, v67, v70, s[0:1]
	v_fma_f32 v67, -v71, v67, v66
	v_cmp_lt_f32_e64 s[0:1], 0, v67
	s_nop 1
	v_cndmask_b32_e64 v67, v70, v71, s[0:1]
	v_mul_f32_e32 v70, 0x37800000, v67
	v_cndmask_b32_e32 v67, v67, v70, vcc
	v_cmp_class_f32_e32 vcc, v66, v244
	s_nop 1
	v_cndmask_b32_e32 v66, v67, v66, vcc
	v_max_f32_e32 v66, 0x2b8cbccc, v66
	v_div_scale_f32 v67, s[0:1], v66, v66, 1.0
	v_rcp_f32_e32 v70, v67
	s_nop 0
	v_fma_f32 v71, -v67, v70, 1.0
	v_fmac_f32_e32 v70, v71, v70
	v_div_scale_f32 v71, vcc, 1.0, v66, 1.0
	v_mul_f32_e32 v72, v71, v70
	v_fma_f32 v73, -v67, v72, v71
	v_fmac_f32_e32 v72, v73, v70
	v_fma_f32 v67, -v67, v72, v71
	v_div_fmas_f32 v67, v67, v70, v72
	v_div_fixup_f32 v70, v67, v66, 1.0
	v_pk_mul_f32 v[74:75], v[54:55], v[70:71] op_sel_hi:[1,0]
	v_pk_mul_f32 v[72:73], v[52:53], v[70:71] op_sel_hi:[1,0]
	v_cvt_pk_f16_f32 v53, v74, v75
	v_cvt_pk_f16_f32 v52, v72, v73
	v_xor_b32_e32 v54, 0x8000, v53
	v_xor_b32_sdwa v53, s63, v53 dst_sel:DWORD dst_unused:UNUSED_PAD src0_sel:DWORD src1_sel:WORD_1
	v_pk_mul_f32 v[56:57], v[56:57], v[70:71] op_sel_hi:[1,0]
	v_pk_mul_f32 v[68:69], v[68:69], v[70:71] op_sel_hi:[1,0]
	v_perm_b32 v53, v53, v54, s33
	v_xor_b32_e32 v54, 0x8000, v52
	v_xor_b32_sdwa v52, s63, v52 dst_sel:DWORD dst_unused:UNUSED_PAD src0_sel:DWORD src1_sel:WORD_1
	v_perm_b32 v52, v52, v54, s33
	v_pk_add_f32 v[54:55], v[56:57], 0 neg_lo:[1,1] neg_hi:[1,1]
	v_pk_add_f32 v[66:67], v[68:69], 0 neg_lo:[1,1] neg_hi:[1,1]
	v_cvt_pk_f16_f32 v54, v54, v55
	v_cvt_pk_f16_f32 v55, v66, v67
	v_lshl_add_u64 v[66:67], s[10:11], 0, v[76:77]
	v_lshl_add_u64 v[66:67], v[66:67], 0, v[152:153]
	global_store_dwordx4 v[66:67], v[52:55], off
	v_fma_mixlo_f16 v71, v108, v72, 0
	v_mul_f32_e32 v90, v62, v70
	v_pk_mov_b32 v[52:53], v[108:109], v[110:111] op_sel:[1,0]
	v_pk_mov_b32 v[54:55], v[72:73], v[74:75] op_sel:[1,0]
	v_pk_mov_b32 v[72:73], v[74:75], v[56:57] op_sel:[1,0]
	v_pk_mul_f32 v[52:53], v[52:53], v[54:55]
	v_pk_mov_b32 v[54:55], v[110:111], v[106:107] op_sel:[1,0]
	v_cvt_pk_f16_f32 v53, v52, v53
	v_pk_mul_f32 v[54:55], v[54:55], v[72:73]
	v_pack_b32_f16 v52, v71, v53
	v_cvt_pk_f16_f32 v71, v54, v55
	v_pk_mov_b32 v[54:55], v[106:107], v[50:51] op_sel:[1,0]
	v_pk_mov_b32 v[56:57], v[56:57], v[68:69] op_sel:[1,0]
	v_alignbit_b32 v53, v71, v53, 16
	v_pk_mul_f32 v[54:55], v[54:55], v[56:57]
	v_pk_add_f32 v[72:73], v[96:97], 1.0 op_sel_hi:[1,0]
	v_cvt_pk_f16_f32 v50, v54, v55
	v_lshrrev_b32_e32 v55, 16, v50
	v_alignbit_b32 v54, v50, v71, 16
	v_fma_mixhi_f16 v55, v51, v69, 0
	v_lshl_add_u64 v[50:51], s[2:3], 0, v[76:77]
	v_lshl_add_u64 v[68:69], v[50:51], 0, v[152:153]
	global_store_dwordx4 v[68:69], v[52:55], off
	global_load_dwordx4 v[50:53], v[126:127], off offset:144
	s_nop 0
	global_load_dwordx4 v[54:57], v[126:127], off offset:128
	v_div_scale_f32 v74, s[0:1], v73, v73, 1.0
	v_rcp_f32_e32 v75, v74
	v_mul_f32_e32 v71, v65, v70
	v_fma_f32 v76, -v74, v75, 1.0
	v_fmac_f32_e32 v75, v76, v75
	v_div_scale_f32 v76, vcc, 1.0, v73, 1.0
	v_mul_f32_e32 v77, v76, v75
	v_fma_f32 v91, -v74, v77, v76
	v_fmac_f32_e32 v77, v91, v75
	v_fma_f32 v74, -v74, v77, v76
	v_div_fmas_f32 v74, v74, v75, v77
	v_div_fixup_f32 v73, v74, v73, 1.0
	v_div_scale_f32 v74, s[0:1], v72, v72, 1.0
	v_rcp_f32_e32 v75, v74
	s_nop 0
	v_fma_f32 v76, -v74, v75, 1.0
	v_fmac_f32_e32 v75, v76, v75
	v_div_scale_f32 v76, vcc, 1.0, v72, 1.0
	v_mul_f32_e32 v77, v76, v75
	v_fma_f32 v91, -v74, v77, v76
	v_fmac_f32_e32 v77, v91, v75
	v_fma_f32 v74, -v74, v77, v76
	v_div_fmas_f32 v74, v74, v75, v77
	v_div_fixup_f32 v72, v74, v72, 1.0
	v_pk_add_f32 v[74:75], v[72:73], -1.0 op_sel_hi:[1,0]
	s_waitcnt vmcnt(0)
	v_pk_fma_f32 v[54:55], v[74:75], v[54:55], 1.0 op_sel_hi:[1,1,0]
	s_nop 0
	v_pk_mul_f32 v[54:55], v[54:55], v[94:95]
	v_pk_add_f32 v[74:75], v[92:93], 1.0 op_sel_hi:[1,0]
	v_cvt_pk_f16_f32 v54, v54, v55
	v_div_scale_f32 v55, s[0:1], v75, v75, 1.0
	v_rcp_f32_e32 v76, v55
	s_nop 0
	v_fma_f32 v77, -v55, v76, 1.0
	v_fmac_f32_e32 v76, v77, v76
	v_div_scale_f32 v77, vcc, 1.0, v75, 1.0
	v_mul_f32_e32 v91, v77, v76
	v_fma_f32 v92, -v55, v91, v77
	v_fmac_f32_e32 v91, v92, v76
	v_fma_f32 v55, -v55, v91, v77
	v_div_fmas_f32 v55, v55, v76, v91
	v_div_fixup_f32 v75, v55, v75, 1.0
	v_div_scale_f32 v55, s[0:1], v74, v74, 1.0
	v_rcp_f32_e32 v76, v55
	s_nop 0
	v_fma_f32 v77, -v55, v76, 1.0
	v_fmac_f32_e32 v76, v77, v76
	v_div_scale_f32 v77, vcc, 1.0, v74, 1.0
	v_mul_f32_e32 v91, v77, v76
	v_fma_f32 v92, -v55, v91, v77
	v_fmac_f32_e32 v91, v92, v76
	v_fma_f32 v55, -v55, v91, v77
	v_div_fmas_f32 v55, v55, v76, v91
	v_div_fixup_f32 v74, v55, v74, 1.0
	v_pk_add_f32 v[76:77], v[74:75], -1.0 op_sel_hi:[1,0]
	s_nop 0
	v_pk_fma_f32 v[56:57], v[76:77], v[56:57], 1.0 op_sel_hi:[1,1,0]
	s_nop 0
	v_pk_mul_f32 v[56:57], v[56:57], v[88:89]
	s_nop 0
	v_cvt_pk_f16_f32 v55, v56, v57
	v_pk_add_f32 v[56:57], v[86:87], 1.0 op_sel_hi:[1,0]
	s_nop 0
	v_div_scale_f32 v76, s[0:1], v57, v57, 1.0
	v_rcp_f32_e32 v77, v76
	s_nop 0
	v_fma_f32 v86, -v76, v77, 1.0
	v_fmac_f32_e32 v77, v86, v77
	v_div_scale_f32 v86, vcc, 1.0, v57, 1.0
	v_mul_f32_e32 v87, v86, v77
	v_fma_f32 v88, -v76, v87, v86
	v_fmac_f32_e32 v87, v88, v77
	v_fma_f32 v76, -v76, v87, v86
	v_div_fmas_f32 v76, v76, v77, v87
	v_div_fixup_f32 v77, v76, v57, 1.0
; __device__ __forceinline__ float sigmoidf_(float x) { return 1.0f / (1.0f + __expf(-x)); }
;     __device__ __forceinline__ void body_a(const f32x4 (&acc)[2][2][4][2], int row0, int cb0) const {
;     ...
;                     const int c = cb0 + 32 * bj;
;                     const f32x4 b0 = *(const f32x4*)(a0 + c), b1 = *(const f32x4*)(a0 + c + 4), q0 = *(const f32x4*)(k_k + c), q1 = *(const f32x4*)(k_k + c + 4);
;                     const h16x8 kh = *(const h16x8*)(C1 + row * LDC1 + 2048 + c);
; #pragma unroll
;                     for (int e = 0; e < 4; ++e) {
;                         a[bj][e] = sigmoidf_(acc[ai][bj][m][0][e] + b0[e]); a[bj][4 + e] = sigmoidf_(acc[ai][bj][m][1][e] + b1[e]);
;     ...
;                     const f32x4 p0 = *(const f32x4*)(k_a + c), p1 = *(const f32x4*)(k_a + c + 4);
;                     f32x4 ko0, ko1, ao0, ao1, bo0, bo1;
; #pragma unroll
;                     for (int e = 0; e < 4; ++e) {
;                         ko0[e] = kv[bj][e] * (1.0f + (a[bj][e] - 1.0f) * p0[e]); ko1[e] = kv[bj][4 + e] * (1.0f + (a[bj][4 + e] - 1.0f) * p1[e]);
;                         const float n0_ = kk[bj][e] * inv, n1_ = kk[bj][4 + e] * inv;
;                         ao0[e] = -n0_; ao1[e] = -n1_; bo0[e] = n0_ * a[bj][e]; bo1[e] = n1_ * a[bj][4 + e];
;                     }
;                     *(u32x4*)(C1 + row * LDC1 + 2048 + c) = pack8(ko0, ko1);
;                     *(u32x4*)(AA + row * DM + c) = pack8(ao0, ao1);
;                     *(u32x4*)(Ab + row * DM + c) = pack8(bo0, bo1);
;                 }
	v_div_scale_f32 v57, s[0:1], v56, v56, 1.0
	v_rcp_f32_e32 v76, v57
	s_nop 0
	v_fma_f32 v86, -v57, v76, 1.0
	v_fmac_f32_e32 v76, v86, v76
	v_div_scale_f32 v86, vcc, 1.0, v56, 1.0
	v_mul_f32_e32 v87, v86, v76
	v_fma_f32 v88, -v57, v87, v86
	v_fmac_f32_e32 v87, v88, v76
	v_fma_f32 v57, -v57, v87, v86
	v_div_fmas_f32 v57, v57, v76, v87
	v_div_fixup_f32 v76, v57, v56, 1.0
	v_pk_add_f32 v[56:57], v[76:77], -1.0 op_sel_hi:[1,0]
	s_nop 0
	v_pk_fma_f32 v[50:51], v[56:57], v[50:51], 1.0 op_sel_hi:[1,1,0]
	s_nop 0
	v_pk_mul_f32 v[50:51], v[50:51], v[84:85]
	s_nop 0
	v_cvt_pk_f16_f32 v56, v50, v51
	v_pk_add_f32 v[50:51], v[82:83], 1.0 op_sel_hi:[1,0]
	s_nop 0
	v_div_scale_f32 v57, s[0:1], v51, v51, 1.0
	v_rcp_f32_e32 v82, v57
	s_nop 0
	v_fma_f32 v83, -v57, v82, 1.0
	v_fmac_f32_e32 v82, v83, v82
	v_div_scale_f32 v83, vcc, 1.0, v51, 1.0
	v_mul_f32_e32 v84, v83, v82
	v_fma_f32 v85, -v57, v84, v83
	v_fmac_f32_e32 v84, v85, v82
	v_fma_f32 v57, -v57, v84, v83
	v_div_fmas_f32 v57, v57, v82, v84
	v_div_fixup_f32 v83, v57, v51, 1.0
	v_div_scale_f32 v51, s[0:1], v50, v50, 1.0
	v_rcp_f32_e32 v57, v51
	s_nop 0
	v_fma_f32 v82, -v51, v57, 1.0
	v_fmac_f32_e32 v57, v82, v57
	v_div_scale_f32 v82, vcc, 1.0, v50, 1.0
	v_mul_f32_e32 v84, v82, v57
	v_fma_f32 v85, -v51, v84, v82
	v_fmac_f32_e32 v84, v85, v57
	v_fma_f32 v51, -v51, v84, v82
	v_div_fmas_f32 v51, v51, v57, v84
	v_div_fixup_f32 v82, v51, v50, 1.0
	v_pk_add_f32 v[50:51], v[82:83], -1.0 op_sel_hi:[1,0]
	s_nop 0
	v_pk_fma_f32 v[50:51], v[50:51], v[52:53], 1.0 op_sel_hi:[1,1,0]
	v_cvt_f16_f32_e64 v52, -v90
	v_pk_mul_f32 v[50:51], v[50:51], v[80:81]
	s_nop 0
	v_cvt_pk_f16_f32 v57, v50, v51
	v_pk_mov_b32 v[50:51], v[62:63], v[78:79] op_sel:[1,0]
	global_store_dwordx4 v[58:59], v[54:57], off
	s_nop 1
	v_pk_mul_f32 v[54:55], v[50:51], v[70:71] op_sel_hi:[1,0]
	s_nop 0
	v_cvt_pk_f16_f32 v51, v54, v55
	v_pack_b32_f16 v50, v52, -v51
	v_pk_mov_b32 v[52:53], v[78:79], v[60:61] op_sel:[1,0]
	v_xor_b32_sdwa v51, s63, v51 dst_sel:DWORD dst_unused:UNUSED_PAD src0_sel:DWORD src1_sel:WORD_1
	v_pk_mul_f32 v[56:57], v[52:53], v[70:71] op_sel_hi:[1,0]
	s_nop 0
	v_cvt_pk_f16_f32 v52, v56, v57
	v_xor_b32_e32 v53, 0x8000, v52
	v_perm_b32 v51, v53, v51, s33
	v_xor_b32_sdwa v62, s63, v52 dst_sel:DWORD dst_unused:UNUSED_PAD src0_sel:DWORD src1_sel:WORD_1
	v_pk_mov_b32 v[52:53], v[60:61], v[64:65] op_sel:[1,0]
	v_cvt_f16_f32_e64 v60, -v71
	v_pk_mul_f32 v[58:59], v[52:53], v[70:71] op_sel_hi:[1,0]
	s_nop 0
	v_cvt_pk_f16_f32 v53, v58, v59
	v_xor_b32_e32 v52, 0x8000, v53
	v_xor_b32_sdwa v53, s63, v53 dst_sel:DWORD dst_unused:UNUSED_PAD src0_sel:DWORD src1_sel:WORD_1
	v_perm_b32 v52, v52, v62, s33
	v_perm_b32 v53, v60, v53, s33
	global_store_dwordx4 v[66:67], v[50:53], off offset:64
	s_nop 1
	v_pk_mov_b32 v[50:51], v[72:73], v[74:75] op_sel:[1,0]
	v_fma_mixlo_f16 v52, v72, v90, 0
	v_pk_mul_f32 v[50:51], v[50:51], v[54:55]
	s_nop 0
	v_cvt_pk_f16_f32 v51, v50, v51
	v_pack_b32_f16 v50, v52, v51
	v_pk_mov_b32 v[52:53], v[74:75], v[76:77] op_sel:[1,0]
	s_nop 0
	v_pk_mul_f32 v[52:53], v[52:53], v[56:57]
	s_nop 0
	v_cvt_pk_f16_f32 v54, v52, v53
	v_pk_mov_b32 v[52:53], v[76:77], v[82:83] op_sel:[1,0]
	v_alignbit_b32 v51, v54, v51, 16
	v_pk_mul_f32 v[52:53], v[52:53], v[58:59]
	s_nop 0
	v_cvt_pk_f16_f32 v53, v52, v53
	v_alignbit_b32 v52, v53, v54, 16
	v_lshrrev_b32_e32 v53, 16, v53
	v_fma_mixhi_f16 v53, v83, v71, 0
	global_store_dwordx4 v[68:69], v[50:53], off offset:64
	v_add_u32_e32 v74, 0x90, v158
	s_nop 0
	v_mad_i64_i32 v[50:51], s[0:1], v74, s5, v[160:161]
	v_lshl_add_u64 v[70:71], v[50:51], 0, s[6:7]
	global_load_dwordx4 v[62:65], v[154:155], off offset:16
	global_load_dwordx4 v[66:69], v[154:155], off
	global_load_dwordx4 v[50:53], v[156:157], off offset:16
	global_load_dwordx4 v[54:57], v[156:157], off
	v_lshl_add_u64 v[82:83], v[70:71], 0, v[152:153]
	global_load_dwordx4 v[58:61], v[82:83], off
	v_ashrrev_i32_e32 v75, 31, v74
	s_waitcnt vmcnt(4)
	v_add_f32_e32 v42, v42, v62
	v_mul_f32_e32 v42, 0xbfb8aa3b, v42
	v_exp_f32_e32 v90, v42
	s_waitcnt vmcnt(3)
	v_add_f32_e32 v42, v47, v67
	v_mul_f32_e32 v42, 0xbfb8aa3b, v42
	v_exp_f32_e32 v93, v42
	v_add_f32_e32 v42, v43, v63
	v_mul_f32_e32 v42, 0xbfb8aa3b, v42
	v_exp_f32_e32 v91, v42
	v_add_f32_e32 v42, v48, v68
	v_mul_f32_e32 v42, 0xbfb8aa3b, v42
	v_exp_f32_e32 v94, v42
	v_add_f32_e32 v42, v44, v64
	v_mul_f32_e32 v42, 0xbfb8aa3b, v42
	v_exp_f32_e32 v84, v42
	v_add_f32_e32 v42, v49, v69
	v_mul_f32_e32 v42, 0xbfb8aa3b, v42
	v_exp_f32_e32 v95, v42
	v_add_f32_e32 v42, v45, v65
	v_add_f32_e32 v46, v46, v66
	v_mul_f32_e32 v42, 0xbfb8aa3b, v42
	v_mul_f32_e32 v46, 0xbfb8aa3b, v46
	v_exp_f32_e32 v85, v42
	v_lshl_add_u64 v[42:43], v[70:71], 0, v[128:129]
	v_exp_f32_e32 v92, v46
	global_load_dwordx4 v[46:49], v[154:155], off offset:144
	global_load_dwordx4 v[62:65], v[154:155], off offset:128
	global_load_dwordx4 v[86:89], v[156:157], off offset:144
	global_load_dwordx4 v[96:99], v[156:157], off offset:128
	global_load_dwordx4 v[100:103], v[42:43], off
	v_pk_add_f32 v[94:95], v[94:95], 1.0 op_sel_hi:[1,0]
	v_pk_add_f32 v[92:93], v[92:93], 1.0 op_sel_hi:[1,0]
	s_waitcnt vmcnt(4)
	v_add_f32_e32 v34, v34, v46
	v_mul_f32_e32 v34, 0xbfb8aa3b, v34
	v_exp_f32_e32 v70, v34
	s_waitcnt vmcnt(3)
	v_add_f32_e32 v34, v39, v63
	s_waitcnt vmcnt(0)
; __device__ __forceinline__ float sigmoidf_(float x) { return 1.0f / (1.0f + __expf(-x)); }
;     __device__ __forceinline__ void body_a(const f32x4 (&acc)[2][2][4][2], int row0, int cb0) const {
;     ...
;                     const int c = cb0 + 32 * bj;
;                     const f32x4 b0 = *(const f32x4*)(a0 + c), b1 = *(const f32x4*)(a0 + c + 4), q0 = *(const f32x4*)(k_k + c), q1 = *(const f32x4*)(k_k + c + 4);
;                     const h16x8 kh = *(const h16x8*)(C1 + row * LDC1 + 2048 + c);
; #pragma unroll
;                     for (int e = 0; e < 4; ++e) {
;                         a[bj][e] = sigmoidf_(acc[ai][bj][m][0][e] + b0[e]); a[bj][4 + e] = sigmoidf_(acc[ai][bj][m][1][e] + b1[e]);
;                         kv[bj][e] = (float)kh[e]; kv[bj][4 + e] = (float)kh[4 + e];
;                         kk[bj][e] = kv[bj][e] * q0[e]; kk[bj][4 + e] = kv[bj][4 + e] * q1[e];
;                         ss += kk[bj][e] * kk[bj][e] + kk[bj][4 + e] * kk[bj][4 + e];
;                     }
;     ...
;                         ko0[e] = kv[bj][e] * (1.0f + (a[bj][e] - 1.0f) * p0[e]); ko1[e] = kv[bj][4 + e] * (1.0f + (a[bj][4 + e] - 1.0f) * p1[e]);
;                         const float n0_ = kk[bj][e] * inv, n1_ = kk[bj][4 + e] * inv;
;                         ao0[e] = -n0_; ao1[e] = -n1_; bo0[e] = n0_ * a[bj][e]; bo1[e] = n1_ * a[bj][4 + e];
;                     }
;                     *(u32x4*)(C1 + row * LDC1 + 2048 + c) = pack8(ko0, ko1);
	v_cvt_f32_f16_e32 v68, v102
	v_cvt_f32_f16_sdwa v69, v102 dst_sel:DWORD dst_unused:UNUSED_PAD src0_sel:WORD_1
	v_cvt_f32_f16_e32 v78, v100
	v_cvt_f32_f16_sdwa v79, v100 dst_sel:DWORD dst_unused:UNUSED_PAD src0_sel:WORD_1
	v_mul_f32_e32 v34, 0xbfb8aa3b, v34
	v_exp_f32_e32 v81, v34
	v_add_f32_e32 v34, v35, v47
	v_mul_f32_e32 v34, 0xbfb8aa3b, v34
	v_pk_mul_f32 v[44:45], v[86:87], v[68:69]
	v_exp_f32_e32 v71, v34
	v_pk_mul_f32 v[46:47], v[96:97], v[78:79]
	v_pk_mul_f32 v[34:35], v[44:45], v[44:45]
	v_cvt_f32_f16_e32 v72, v101
	v_pk_fma_f32 v[86:87], v[46:47], v[46:47], v[34:35]
	v_add_f32_e32 v34, v40, v64
	v_mul_f32_e32 v34, 0xbfb8aa3b, v34
	v_exp_f32_e32 v76, v34
	v_add_f32_e32 v34, v36, v48
	v_mul_f32_e32 v34, 0xbfb8aa3b, v34
	v_exp_f32_e32 v66, v34
	v_add_f32_e32 v34, v41, v65
	v_cvt_f32_f16_e32 v64, v103
	v_cvt_f32_f16_sdwa v65, v103 dst_sel:DWORD dst_unused:UNUSED_PAD src0_sel:WORD_1
	v_cvt_f32_f16_sdwa v73, v101 dst_sel:DWORD dst_unused:UNUSED_PAD src0_sel:WORD_1
	v_mul_f32_e32 v34, 0xbfb8aa3b, v34
	v_exp_f32_e32 v77, v34
	v_add_f32_e32 v34, v37, v49
	v_add_f32_e32 v38, v38, v62
	v_mul_f32_e32 v34, 0xbfb8aa3b, v34
	v_pk_mul_f32 v[48:49], v[88:89], v[64:65]
	v_mul_f32_e32 v38, 0xbfb8aa3b, v38
	v_exp_f32_e32 v67, v34
	v_pk_mul_f32 v[62:63], v[98:99], v[72:73]
	v_pk_mul_f32 v[34:35], v[48:49], v[48:49]
	v_exp_f32_e32 v80, v38
	v_pk_fma_f32 v[88:89], v[62:63], v[62:63], v[34:35]
	global_load_dwordx4 v[34:37], v[126:127], off offset:16
	global_load_dwordx4 v[38:41], v[126:127], off
	v_cvt_f32_f16_e32 v96, v58
	v_cvt_f32_f16_sdwa v97, v58 dst_sel:DWORD dst_unused:UNUSED_PAD src0_sel:WORD_1
	v_div_scale_f32 v58, s[0:1], v93, v93, 1.0
	v_rcp_f32_e32 v98, v58
	s_nop 0
	v_fma_f32 v99, -v58, v98, 1.0
	v_fmac_f32_e32 v98, v99, v98
	v_div_scale_f32 v99, vcc, 1.0, v93, 1.0
	v_mul_f32_e32 v100, v99, v98
	v_fma_f32 v101, -v58, v100, v99
	v_fmac_f32_e32 v100, v101, v98
	v_fma_f32 v58, -v58, v100, v99
	v_div_fmas_f32 v58, v58, v98, v100
	v_div_fixup_f32 v93, v58, v93, 1.0
	v_div_scale_f32 v58, s[0:1], v92, v92, 1.0
	v_rcp_f32_e32 v98, v58
	s_nop 0
	v_fma_f32 v99, -v58, v98, 1.0
	v_fmac_f32_e32 v98, v99, v98
	v_div_scale_f32 v99, vcc, 1.0, v92, 1.0
	v_mul_f32_e32 v100, v99, v98
	v_fma_f32 v101, -v58, v100, v99
	v_fmac_f32_e32 v100, v101, v98
	v_fma_f32 v58, -v58, v100, v99
	v_div_fmas_f32 v58, v58, v98, v100
	v_div_fixup_f32 v92, v58, v92, 1.0
	v_pk_add_f32 v[98:99], v[92:93], -1.0 op_sel_hi:[1,0]
	v_cvt_f32_f16_e32 v58, v59
	v_cvt_f32_f16_sdwa v59, v59 dst_sel:DWORD dst_unused:UNUSED_PAD src0_sel:WORD_1
	s_waitcnt vmcnt(0)
	v_pk_fma_f32 v[38:39], v[98:99], v[38:39], 1.0 op_sel_hi:[1,1,0]
	s_nop 0
	v_pk_mul_f32 v[38:39], v[38:39], v[96:97]
	s_nop 0
	v_cvt_pk_f16_f32 v38, v38, v39
	v_div_scale_f32 v39, s[0:1], v95, v95, 1.0
	v_rcp_f32_e32 v98, v39
	s_nop 0
	v_fma_f32 v99, -v39, v98, 1.0
	v_fmac_f32_e32 v98, v99, v98
	v_div_scale_f32 v99, vcc, 1.0, v95, 1.0
	v_mul_f32_e32 v100, v99, v98
	v_fma_f32 v101, -v39, v100, v99
	v_fmac_f32_e32 v100, v101, v98
	v_fma_f32 v39, -v39, v100, v99
	v_div_fmas_f32 v39, v39, v98, v100
	v_div_fixup_f32 v95, v39, v95, 1.0
	v_div_scale_f32 v39, s[0:1], v94, v94, 1.0
	v_rcp_f32_e32 v98, v39
	s_nop 0
	v_fma_f32 v99, -v39, v98, 1.0
	v_fmac_f32_e32 v98, v99, v98
	v_div_scale_f32 v99, vcc, 1.0, v94, 1.0
	v_mul_f32_e32 v100, v99, v98
	v_fma_f32 v101, -v39, v100, v99
	v_fmac_f32_e32 v100, v101, v98
	v_fma_f32 v39, -v39, v100, v99
	v_div_fmas_f32 v39, v39, v98, v100
	v_div_fixup_f32 v94, v39, v94, 1.0
	v_pk_add_f32 v[98:99], v[94:95], -1.0 op_sel_hi:[1,0]
	s_nop 0
	v_pk_fma_f32 v[40:41], v[98:99], v[40:41], 1.0 op_sel_hi:[1,1,0]
	v_cvt_f32_f16_e32 v98, v60
	v_pk_mul_f32 v[40:41], v[40:41], v[58:59]
	v_cvt_f32_f16_sdwa v99, v60 dst_sel:DWORD dst_unused:UNUSED_PAD src0_sel:WORD_1
	v_cvt_pk_f16_f32 v39, v40, v41
	v_pk_add_f32 v[40:41], v[90:91], 1.0 op_sel_hi:[1,0]
	s_nop 0
	v_div_scale_f32 v60, s[0:1], v41, v41, 1.0
	v_rcp_f32_e32 v90, v60
	s_nop 0
	v_fma_f32 v91, -v60, v90, 1.0
	v_fmac_f32_e32 v90, v91, v90
	v_div_scale_f32 v91, vcc, 1.0, v41, 1.0
	v_mul_f32_e32 v100, v91, v90
	v_fma_f32 v101, -v60, v100, v91
	v_fmac_f32_e32 v100, v101, v90
	v_fma_f32 v60, -v60, v100, v91
	v_div_fmas_f32 v60, v60, v90, v100
	v_div_fixup_f32 v91, v60, v41, 1.0
	v_div_scale_f32 v41, s[0:1], v40, v40, 1.0
	v_rcp_f32_e32 v60, v41
	s_nop 0
	v_fma_f32 v90, -v41, v60, 1.0
	v_fmac_f32_e32 v60, v90, v60
	v_div_scale_f32 v90, vcc, 1.0, v40, 1.0
	v_mul_f32_e32 v100, v90, v60
	v_fma_f32 v101, -v41, v100, v90
	v_fmac_f32_e32 v100, v101, v60
	v_fma_f32 v41, -v41, v100, v90
	v_div_fmas_f32 v41, v41, v60, v100
	v_div_fixup_f32 v90, v41, v40, 1.0
	v_pk_add_f32 v[40:41], v[90:91], -1.0 op_sel_hi:[1,0]
	v_cvt_f32_f16_e32 v60, v61
	v_pk_fma_f32 v[34:35], v[40:41], v[34:35], 1.0 op_sel_hi:[1,1,0]
	v_cvt_f32_f16_sdwa v61, v61 dst_sel:DWORD dst_unused:UNUSED_PAD src0_sel:WORD_1
	v_pk_mul_f32 v[34:35], v[34:35], v[98:99]
	v_pk_mul_f32 v[52:53], v[52:53], v[60:61]
	v_cvt_pk_f16_f32 v40, v34, v35
	v_pk_add_f32 v[34:35], v[84:85], 1.0 op_sel_hi:[1,0]
	s_nop 0
	v_div_scale_f32 v41, s[0:1], v35, v35, 1.0
	v_rcp_f32_e32 v84, v41
	s_nop 0
	v_fma_f32 v85, -v41, v84, 1.0
	v_fmac_f32_e32 v84, v85, v84
	v_div_scale_f32 v85, vcc, 1.0, v35, 1.0
	v_mul_f32_e32 v100, v85, v84
	v_fma_f32 v101, -v41, v100, v85
	v_fmac_f32_e32 v100, v101, v84
	v_fma_f32 v41, -v41, v100, v85
	v_div_fmas_f32 v41, v41, v84, v100
	v_div_fixup_f32 v35, v41, v35, 1.0
	v_div_scale_f32 v41, s[0:1], v34, v34, 1.0
	v_rcp_f32_e32 v84, v41
	s_nop 0
	v_fma_f32 v85, -v41, v84, 1.0
	v_fmac_f32_e32 v84, v85, v84
	v_div_scale_f32 v85, vcc, 1.0, v34, 1.0
	v_mul_f32_e32 v100, v85, v84
	v_fma_f32 v101, -v41, v100, v85
	v_fmac_f32_e32 v100, v101, v84
	v_fma_f32 v41, -v41, v100, v85
	v_div_fmas_f32 v41, v41, v84, v100
	v_div_fixup_f32 v34, v41, v34, 1.0
	v_pk_add_f32 v[84:85], v[34:35], -1.0 op_sel_hi:[1,0]
	s_nop 0
	v_pk_fma_f32 v[36:37], v[84:85], v[36:37], 1.0 op_sel_hi:[1,1,0]
	s_nop 0
	v_pk_mul_f32 v[36:37], v[36:37], v[60:61]
	v_lshlrev_b64 v[60:61], 12, v[74:75]
	v_cvt_pk_f16_f32 v41, v36, v37
	global_store_dwordx4 v[82:83], v[38:41], off
	v_pk_mul_f32 v[36:37], v[54:55], v[96:97]
	v_pk_mul_f32 v[54:55], v[52:53], v[52:53]
	v_pk_mul_f32 v[40:41], v[50:51], v[98:99]
	v_pk_mul_f32 v[38:39], v[56:57], v[58:59]
	v_pk_mul_f32 v[50:51], v[40:41], v[40:41]
	v_pk_fma_f32 v[54:55], v[38:39], v[38:39], v[54:55]
	v_pk_fma_f32 v[50:51], v[36:37], v[36:37], v[50:51]
	s_nop 0
	v_add_f32_e32 v50, v50, v51
	v_add_f32_e32 v50, v54, v50
	v_add_f32_e32 v50, v55, v50
	v_add_f32_e32 v50, v50, v86
	v_add_f32_e32 v50, v87, v50
	v_add_f32_e32 v50, v88, v50
	v_add_f32_e32 v50, v89, v50
	ds_bpermute_b32 v51, v206, v50
	s_waitcnt lgkmcnt(0)
;     __device__ __forceinline__ void body_a(const f32x4 (&acc)[2][2][4][2], int row0, int cb0) const {
;     ...
;                 ss += __shfl_xor(ss, 16); ss += __shfl_xor(ss, 32);
;                 const float inv = 1.0f / fmaxf(sqrtf(ss), 1e-12f);
; #pragma unroll
;                 for (int bj = 0; bj < 2; ++bj) {
;                     const int c = cb0 + 32 * bj;
;                     const f32x4 p0 = *(const f32x4*)(k_a + c), p1 = *(const f32x4*)(k_a + c + 4);
;                     f32x4 ko0, ko1, ao0, ao1, bo0, bo1;
; #pragma unroll
;                     for (int e = 0; e < 4; ++e) {
;                         ko0[e] = kv[bj][e] * (1.0f + (a[bj][e] - 1.0f) * p0[e]); ko1[e] = kv[bj][4 + e] * (1.0f + (a[bj][4 + e] - 1.0f) * p1[e]);
;                         const float n0_ = kk[bj][e] * inv, n1_ = kk[bj][4 + e] * inv;
;                         ao0[e] = -n0_; ao1[e] = -n1_; bo0[e] = n0_ * a[bj][e]; bo1[e] = n1_ * a[bj][4 + e];
;                     }
;                     *(u32x4*)(C1 + row * LDC1 + 2048 + c) = pack8(ko0, ko1);
;                     *(u32x4*)(AA + row * DM + c) = pack8(ao0, ao1);
;                     *(u32x4*)(Ab + row * DM + c) = pack8(bo0, bo1);
	v_add_f32_e32 v50, v50, v51
	ds_bpermute_b32 v51, v207, v50
	s_waitcnt lgkmcnt(0)
	v_add_f32_e32 v50, v50, v51
	v_cmp_gt_f32_e32 vcc, s4, v50
	v_mul_f32_e32 v51, 0x4f800000, v50
	s_nop 0
	v_cndmask_b32_e32 v50, v50, v51, vcc
	v_sqrt_f32_e32 v51, v50
	s_nop 0
	v_add_u32_e32 v54, -1, v51
	v_fma_f32 v55, -v54, v51, v50
	v_cmp_ge_f32_e64 s[0:1], 0, v55
	v_add_u32_e32 v55, 1, v51
	s_nop 0
	v_cndmask_b32_e64 v54, v51, v54, s[0:1]
	v_fma_f32 v51, -v55, v51, v50
	v_cmp_lt_f32_e64 s[0:1], 0, v51
	s_nop 1
	v_cndmask_b32_e64 v51, v54, v55, s[0:1]
	v_mul_f32_e32 v54, 0x37800000, v51
	v_cndmask_b32_e32 v51, v51, v54, vcc
	v_cmp_class_f32_e32 vcc, v50, v244
	s_nop 1
	v_cndmask_b32_e32 v50, v51, v50, vcc
	v_max_f32_e32 v50, 0x2b8cbccc, v50
	v_div_scale_f32 v51, s[0:1], v50, v50, 1.0
	v_rcp_f32_e32 v54, v51
	s_nop 0
	v_fma_f32 v55, -v51, v54, 1.0
	v_fmac_f32_e32 v54, v55, v54
	v_div_scale_f32 v55, vcc, 1.0, v50, 1.0
	v_mul_f32_e32 v56, v55, v54
	v_fma_f32 v57, -v51, v56, v55
	v_fmac_f32_e32 v56, v57, v54
	v_fma_f32 v51, -v51, v56, v55
	v_div_fmas_f32 v51, v51, v54, v56
	v_div_fixup_f32 v54, v51, v50, 1.0
	v_pk_mul_f32 v[58:59], v[38:39], v[54:55] op_sel_hi:[1,0]
	v_pk_mul_f32 v[56:57], v[36:37], v[54:55] op_sel_hi:[1,0]
	v_cvt_pk_f16_f32 v37, v58, v59
	v_cvt_pk_f16_f32 v36, v56, v57
	v_xor_b32_e32 v38, 0x8000, v37
	v_xor_b32_sdwa v37, s63, v37 dst_sel:DWORD dst_unused:UNUSED_PAD src0_sel:DWORD src1_sel:WORD_1
	v_pk_mul_f32 v[40:41], v[40:41], v[54:55] op_sel_hi:[1,0]
	v_pk_mul_f32 v[52:53], v[52:53], v[54:55] op_sel_hi:[1,0]
	v_perm_b32 v37, v37, v38, s33
	v_xor_b32_e32 v38, 0x8000, v36
	v_xor_b32_sdwa v36, s63, v36 dst_sel:DWORD dst_unused:UNUSED_PAD src0_sel:DWORD src1_sel:WORD_1
	v_perm_b32 v36, v36, v38, s33
	v_pk_add_f32 v[38:39], v[40:41], 0 neg_lo:[1,1] neg_hi:[1,1]
	v_pk_add_f32 v[50:51], v[52:53], 0 neg_lo:[1,1] neg_hi:[1,1]
	v_cvt_pk_f16_f32 v38, v38, v39
	v_cvt_pk_f16_f32 v39, v50, v51
	v_lshl_add_u64 v[50:51], s[10:11], 0, v[60:61]
	v_lshl_add_u64 v[50:51], v[50:51], 0, v[152:153]
	global_store_dwordx4 v[50:51], v[36:39], off
	v_fma_mixlo_f16 v55, v92, v56, 0
	v_mul_f32_e32 v74, v46, v54
	v_pk_mov_b32 v[36:37], v[92:93], v[94:95] op_sel:[1,0]
	v_pk_mov_b32 v[38:39], v[56:57], v[58:59] op_sel:[1,0]
	v_pk_mov_b32 v[56:57], v[58:59], v[40:41] op_sel:[1,0]
	v_pk_mul_f32 v[36:37], v[36:37], v[38:39]
	v_pk_mov_b32 v[38:39], v[94:95], v[90:91] op_sel:[1,0]
	v_cvt_pk_f16_f32 v37, v36, v37
	v_pk_mul_f32 v[38:39], v[38:39], v[56:57]
	v_pack_b32_f16 v36, v55, v37
	v_cvt_pk_f16_f32 v55, v38, v39
	v_pk_mov_b32 v[38:39], v[90:91], v[34:35] op_sel:[1,0]
	v_pk_mov_b32 v[40:41], v[40:41], v[52:53] op_sel:[1,0]
	v_alignbit_b32 v37, v55, v37, 16
	v_pk_mul_f32 v[38:39], v[38:39], v[40:41]
	v_pk_add_f32 v[56:57], v[80:81], 1.0 op_sel_hi:[1,0]
	v_cvt_pk_f16_f32 v34, v38, v39
	v_lshrrev_b32_e32 v39, 16, v34
	v_alignbit_b32 v38, v34, v55, 16
	v_fma_mixhi_f16 v39, v35, v53, 0
	v_lshl_add_u64 v[34:35], s[2:3], 0, v[60:61]
	v_lshl_add_u64 v[52:53], v[34:35], 0, v[152:153]
	global_store_dwordx4 v[52:53], v[36:39], off
	global_load_dwordx4 v[34:37], v[126:127], off offset:144
	s_nop 0
	global_load_dwordx4 v[38:41], v[126:127], off offset:128
	v_div_scale_f32 v58, s[0:1], v57, v57, 1.0
	v_rcp_f32_e32 v59, v58
	v_mul_f32_e32 v55, v49, v54
	v_fma_f32 v60, -v58, v59, 1.0
	v_fmac_f32_e32 v59, v60, v59
	v_div_scale_f32 v60, vcc, 1.0, v57, 1.0
	v_mul_f32_e32 v61, v60, v59
	v_fma_f32 v75, -v58, v61, v60
	v_fmac_f32_e32 v61, v75, v59
	v_fma_f32 v58, -v58, v61, v60
	v_div_fmas_f32 v58, v58, v59, v61
	v_div_fixup_f32 v57, v58, v57, 1.0
	v_div_scale_f32 v58, s[0:1], v56, v56, 1.0
	v_rcp_f32_e32 v59, v58
	s_nop 0
	v_fma_f32 v60, -v58, v59, 1.0
	v_fmac_f32_e32 v59, v60, v59
	v_div_scale_f32 v60, vcc, 1.0, v56, 1.0
	v_mul_f32_e32 v61, v60, v59
	v_fma_f32 v75, -v58, v61, v60
	v_fmac_f32_e32 v61, v75, v59
	v_fma_f32 v58, -v58, v61, v60
	v_div_fmas_f32 v58, v58, v59, v61
	v_div_fixup_f32 v56, v58, v56, 1.0
	v_pk_add_f32 v[58:59], v[56:57], -1.0 op_sel_hi:[1,0]
	s_waitcnt vmcnt(0)
	v_pk_fma_f32 v[38:39], v[58:59], v[38:39], 1.0 op_sel_hi:[1,1,0]
	s_nop 0
	v_pk_mul_f32 v[38:39], v[38:39], v[78:79]
	v_pk_add_f32 v[58:59], v[76:77], 1.0 op_sel_hi:[1,0]
	v_cvt_pk_f16_f32 v38, v38, v39
	v_div_scale_f32 v39, s[0:1], v59, v59, 1.0
	v_rcp_f32_e32 v60, v39
	s_nop 0
	v_fma_f32 v61, -v39, v60, 1.0
	v_fmac_f32_e32 v60, v61, v60
	v_div_scale_f32 v61, vcc, 1.0, v59, 1.0
	v_mul_f32_e32 v75, v61, v60
	v_fma_f32 v76, -v39, v75, v61
	v_fmac_f32_e32 v75, v76, v60
	v_fma_f32 v39, -v39, v75, v61
	v_div_fmas_f32 v39, v39, v60, v75
	v_div_fixup_f32 v59, v39, v59, 1.0
	v_div_scale_f32 v39, s[0:1], v58, v58, 1.0
	v_rcp_f32_e32 v60, v39
	s_nop 0
	v_fma_f32 v61, -v39, v60, 1.0
	v_fmac_f32_e32 v60, v61, v60
	v_div_scale_f32 v61, vcc, 1.0, v58, 1.0
	v_mul_f32_e32 v75, v61, v60
	v_fma_f32 v76, -v39, v75, v61
	v_fmac_f32_e32 v75, v76, v60
	v_fma_f32 v39, -v39, v75, v61
	v_div_fmas_f32 v39, v39, v60, v75
	v_div_fixup_f32 v58, v39, v58, 1.0
	v_pk_add_f32 v[60:61], v[58:59], -1.0 op_sel_hi:[1,0]
	s_nop 0
	v_pk_fma_f32 v[40:41], v[60:61], v[40:41], 1.0 op_sel_hi:[1,1,0]
	s_nop 0
	v_pk_mul_f32 v[40:41], v[40:41], v[72:73]
	s_nop 0
	v_cvt_pk_f16_f32 v39, v40, v41
	v_pk_add_f32 v[40:41], v[70:71], 1.0 op_sel_hi:[1,0]
	s_nop 0
	v_div_scale_f32 v60, s[0:1], v41, v41, 1.0
	v_rcp_f32_e32 v61, v60
	s_nop 0
	v_fma_f32 v70, -v60, v61, 1.0
	v_fmac_f32_e32 v61, v70, v61
	v_div_scale_f32 v70, vcc, 1.0, v41, 1.0
	v_mul_f32_e32 v71, v70, v61
	v_fma_f32 v72, -v60, v71, v70
	v_fmac_f32_e32 v71, v72, v61
	v_fma_f32 v60, -v60, v71, v70
	v_div_fmas_f32 v60, v60, v61, v71
	v_div_fixup_f32 v61, v60, v41, 1.0
	v_div_scale_f32 v41, s[0:1], v40, v40, 1.0
; __device__ __forceinline__ float sigmoidf_(float x) { return 1.0f / (1.0f + __expf(-x)); }
;     __device__ __forceinline__ void body_a(const f32x4 (&acc)[2][2][4][2], int row0, int cb0) const {
;     ...
;                     const int c = cb0 + 32 * bj;
;                     const f32x4 b0 = *(const f32x4*)(a0 + c), b1 = *(const f32x4*)(a0 + c + 4), q0 = *(const f32x4*)(k_k + c), q1 = *(const f32x4*)(k_k + c + 4);
;                     const h16x8 kh = *(const h16x8*)(C1 + row * LDC1 + 2048 + c);
; #pragma unroll
;                     for (int e = 0; e < 4; ++e) {
;                         a[bj][e] = sigmoidf_(acc[ai][bj][m][0][e] + b0[e]); a[bj][4 + e] = sigmoidf_(acc[ai][bj][m][1][e] + b1[e]);
;     ...
;                     const f32x4 p0 = *(const f32x4*)(k_a + c), p1 = *(const f32x4*)(k_a + c + 4);
;                     f32x4 ko0, ko1, ao0, ao1, bo0, bo1;
; #pragma unroll
;                     for (int e = 0; e < 4; ++e) {
;                         ko0[e] = kv[bj][e] * (1.0f + (a[bj][e] - 1.0f) * p0[e]); ko1[e] = kv[bj][4 + e] * (1.0f + (a[bj][4 + e] - 1.0f) * p1[e]);
;                         const float n0_ = kk[bj][e] * inv, n1_ = kk[bj][4 + e] * inv;
;                         ao0[e] = -n0_; ao1[e] = -n1_; bo0[e] = n0_ * a[bj][e]; bo1[e] = n1_ * a[bj][4 + e];
;                     }
;                     *(u32x4*)(C1 + row * LDC1 + 2048 + c) = pack8(ko0, ko1);
;                     *(u32x4*)(AA + row * DM + c) = pack8(ao0, ao1);
;                     *(u32x4*)(Ab + row * DM + c) = pack8(bo0, bo1);
;                 }
	v_rcp_f32_e32 v60, v41
	s_nop 0
	v_fma_f32 v70, -v41, v60, 1.0
	v_fmac_f32_e32 v60, v70, v60
	v_div_scale_f32 v70, vcc, 1.0, v40, 1.0
	v_mul_f32_e32 v71, v70, v60
	v_fma_f32 v72, -v41, v71, v70
	v_fmac_f32_e32 v71, v72, v60
	v_fma_f32 v41, -v41, v71, v70
	v_div_fmas_f32 v41, v41, v60, v71
	v_div_fixup_f32 v60, v41, v40, 1.0
	v_pk_add_f32 v[40:41], v[60:61], -1.0 op_sel_hi:[1,0]
	s_nop 0
	v_pk_fma_f32 v[34:35], v[40:41], v[34:35], 1.0 op_sel_hi:[1,1,0]
	s_nop 0
	v_pk_mul_f32 v[34:35], v[34:35], v[68:69]
	s_nop 0
	v_cvt_pk_f16_f32 v40, v34, v35
	v_pk_add_f32 v[34:35], v[66:67], 1.0 op_sel_hi:[1,0]
	s_nop 0
	v_div_scale_f32 v41, s[0:1], v35, v35, 1.0
	v_rcp_f32_e32 v66, v41
	s_nop 0
	v_fma_f32 v67, -v41, v66, 1.0
	v_fmac_f32_e32 v66, v67, v66
	v_div_scale_f32 v67, vcc, 1.0, v35, 1.0
	v_mul_f32_e32 v68, v67, v66
	v_fma_f32 v69, -v41, v68, v67
	v_fmac_f32_e32 v68, v69, v66
	v_fma_f32 v41, -v41, v68, v67
	v_div_fmas_f32 v41, v41, v66, v68
	v_div_fixup_f32 v67, v41, v35, 1.0
	v_div_scale_f32 v35, s[0:1], v34, v34, 1.0
	v_rcp_f32_e32 v41, v35
	s_nop 0
	v_fma_f32 v66, -v35, v41, 1.0
	v_fmac_f32_e32 v41, v66, v41
	v_div_scale_f32 v66, vcc, 1.0, v34, 1.0
	v_mul_f32_e32 v68, v66, v41
	v_fma_f32 v69, -v35, v68, v66
	v_fmac_f32_e32 v68, v69, v41
	v_fma_f32 v35, -v35, v68, v66
	v_div_fmas_f32 v35, v35, v41, v68
	v_div_fixup_f32 v66, v35, v34, 1.0
	v_pk_add_f32 v[34:35], v[66:67], -1.0 op_sel_hi:[1,0]
	s_nop 0
	v_pk_fma_f32 v[34:35], v[34:35], v[36:37], 1.0 op_sel_hi:[1,1,0]
	v_cvt_f16_f32_e64 v36, -v74
	v_pk_mul_f32 v[34:35], v[34:35], v[64:65]
	s_nop 0
	v_cvt_pk_f16_f32 v41, v34, v35
	v_pk_mov_b32 v[34:35], v[46:47], v[62:63] op_sel:[1,0]
	global_store_dwordx4 v[42:43], v[38:41], off
	s_nop 1
	v_pk_mul_f32 v[38:39], v[34:35], v[54:55] op_sel_hi:[1,0]
	s_nop 0
	v_cvt_pk_f16_f32 v35, v38, v39
	v_pack_b32_f16 v34, v36, -v35
	v_pk_mov_b32 v[36:37], v[62:63], v[44:45] op_sel:[1,0]
	v_xor_b32_sdwa v35, s63, v35 dst_sel:DWORD dst_unused:UNUSED_PAD src0_sel:DWORD src1_sel:WORD_1
	v_pk_mul_f32 v[40:41], v[36:37], v[54:55] op_sel_hi:[1,0]
	s_nop 0
	v_cvt_pk_f16_f32 v36, v40, v41
	v_xor_b32_e32 v37, 0x8000, v36
	v_perm_b32 v35, v37, v35, s33
	v_xor_b32_sdwa v46, s63, v36 dst_sel:DWORD dst_unused:UNUSED_PAD src0_sel:DWORD src1_sel:WORD_1
	v_pk_mov_b32 v[36:37], v[44:45], v[48:49] op_sel:[1,0]
	v_cvt_f16_f32_e64 v44, -v55
	v_pk_mul_f32 v[42:43], v[36:37], v[54:55] op_sel_hi:[1,0]
	s_nop 0
	v_cvt_pk_f16_f32 v37, v42, v43
	v_xor_b32_e32 v36, 0x8000, v37
	v_xor_b32_sdwa v37, s63, v37 dst_sel:DWORD dst_unused:UNUSED_PAD src0_sel:DWORD src1_sel:WORD_1
	v_perm_b32 v36, v36, v46, s33
	v_perm_b32 v37, v44, v37, s33
	global_store_dwordx4 v[50:51], v[34:37], off offset:64
	s_nop 1
	v_pk_mov_b32 v[34:35], v[56:57], v[58:59] op_sel:[1,0]
	v_fma_mixlo_f16 v36, v56, v74, 0
	v_pk_mul_f32 v[34:35], v[34:35], v[38:39]
	s_nop 0
	v_cvt_pk_f16_f32 v35, v34, v35
	v_pack_b32_f16 v34, v36, v35
	v_pk_mov_b32 v[36:37], v[58:59], v[60:61] op_sel:[1,0]
	s_nop 0
	v_pk_mul_f32 v[36:37], v[36:37], v[40:41]
	s_nop 0
	v_cvt_pk_f16_f32 v38, v36, v37
	v_pk_mov_b32 v[36:37], v[60:61], v[66:67] op_sel:[1,0]
	v_alignbit_b32 v35, v38, v35, 16
	v_pk_mul_f32 v[36:37], v[36:37], v[42:43]
	s_nop 0
	v_cvt_pk_f16_f32 v37, v36, v37
	v_alignbit_b32 v36, v37, v38, 16
	v_lshrrev_b32_e32 v37, 16, v37
	v_fma_mixhi_f16 v37, v67, v55, 0
	global_store_dwordx4 v[52:53], v[34:37], off offset:64
	v_add_u32_e32 v58, 0xa0, v158
	s_nop 0
	v_mad_i64_i32 v[34:35], s[0:1], v58, s5, v[160:161]
	v_lshl_add_u64 v[54:55], v[34:35], 0, s[6:7]
	global_load_dwordx4 v[46:49], v[154:155], off offset:16
	global_load_dwordx4 v[50:53], v[154:155], off
	global_load_dwordx4 v[34:37], v[156:157], off offset:16
	global_load_dwordx4 v[38:41], v[156:157], off
	v_lshl_add_u64 v[66:67], v[54:55], 0, v[152:153]
	global_load_dwordx4 v[42:45], v[66:67], off
	v_ashrrev_i32_e32 v59, 31, v58
	s_waitcnt vmcnt(4)
	v_add_f32_e32 v26, v26, v46
	v_mul_f32_e32 v26, 0xbfb8aa3b, v26
	v_exp_f32_e32 v74, v26
	s_waitcnt vmcnt(3)
	v_add_f32_e32 v26, v31, v51
	v_mul_f32_e32 v26, 0xbfb8aa3b, v26
	v_exp_f32_e32 v77, v26
	v_add_f32_e32 v26, v27, v47
	v_mul_f32_e32 v26, 0xbfb8aa3b, v26
	v_exp_f32_e32 v75, v26
	v_add_f32_e32 v26, v32, v52
	v_mul_f32_e32 v26, 0xbfb8aa3b, v26
	v_exp_f32_e32 v78, v26
	v_add_f32_e32 v26, v28, v48
	v_mul_f32_e32 v26, 0xbfb8aa3b, v26
	v_exp_f32_e32 v68, v26
	v_add_f32_e32 v26, v33, v53
	v_mul_f32_e32 v26, 0xbfb8aa3b, v26
	v_exp_f32_e32 v79, v26
	v_add_f32_e32 v26, v29, v49
	v_add_f32_e32 v30, v30, v50
	v_mul_f32_e32 v26, 0xbfb8aa3b, v26
	v_mul_f32_e32 v30, 0xbfb8aa3b, v30
	v_exp_f32_e32 v69, v26
	v_lshl_add_u64 v[26:27], v[54:55], 0, v[128:129]
	v_exp_f32_e32 v76, v30
	global_load_dwordx4 v[30:33], v[154:155], off offset:144
	global_load_dwordx4 v[46:49], v[154:155], off offset:128
	global_load_dwordx4 v[70:73], v[156:157], off offset:144
	global_load_dwordx4 v[80:83], v[156:157], off offset:128
	global_load_dwordx4 v[84:87], v[26:27], off
	v_pk_add_f32 v[78:79], v[78:79], 1.0 op_sel_hi:[1,0]
	v_pk_add_f32 v[76:77], v[76:77], 1.0 op_sel_hi:[1,0]
	s_waitcnt vmcnt(4)
	v_add_f32_e32 v18, v18, v30
	v_mul_f32_e32 v18, 0xbfb8aa3b, v18
	v_exp_f32_e32 v54, v18
	s_waitcnt vmcnt(3)
	v_add_f32_e32 v18, v23, v47
	s_waitcnt vmcnt(0)
; __device__ __forceinline__ float sigmoidf_(float x) { return 1.0f / (1.0f + __expf(-x)); }
;     __device__ __forceinline__ void body_a(const f32x4 (&acc)[2][2][4][2], int row0, int cb0) const {
;     ...
;                     const int c = cb0 + 32 * bj;
;                     const f32x4 b0 = *(const f32x4*)(a0 + c), b1 = *(const f32x4*)(a0 + c + 4), q0 = *(const f32x4*)(k_k + c), q1 = *(const f32x4*)(k_k + c + 4);
;                     const h16x8 kh = *(const h16x8*)(C1 + row * LDC1 + 2048 + c);
; #pragma unroll
;                     for (int e = 0; e < 4; ++e) {
;                         a[bj][e] = sigmoidf_(acc[ai][bj][m][0][e] + b0[e]); a[bj][4 + e] = sigmoidf_(acc[ai][bj][m][1][e] + b1[e]);
;                         kv[bj][e] = (float)kh[e]; kv[bj][4 + e] = (float)kh[4 + e];
;                         kk[bj][e] = kv[bj][e] * q0[e]; kk[bj][4 + e] = kv[bj][4 + e] * q1[e];
;                         ss += kk[bj][e] * kk[bj][e] + kk[bj][4 + e] * kk[bj][4 + e];
;                     }
;     ...
;                         ko0[e] = kv[bj][e] * (1.0f + (a[bj][e] - 1.0f) * p0[e]); ko1[e] = kv[bj][4 + e] * (1.0f + (a[bj][4 + e] - 1.0f) * p1[e]);
;                         const float n0_ = kk[bj][e] * inv, n1_ = kk[bj][4 + e] * inv;
;                         ao0[e] = -n0_; ao1[e] = -n1_; bo0[e] = n0_ * a[bj][e]; bo1[e] = n1_ * a[bj][4 + e];
;                     }
;                     *(u32x4*)(C1 + row * LDC1 + 2048 + c) = pack8(ko0, ko1);
	v_cvt_f32_f16_e32 v52, v86
	v_cvt_f32_f16_sdwa v53, v86 dst_sel:DWORD dst_unused:UNUSED_PAD src0_sel:WORD_1
	v_cvt_f32_f16_e32 v62, v84
	v_cvt_f32_f16_sdwa v63, v84 dst_sel:DWORD dst_unused:UNUSED_PAD src0_sel:WORD_1
	v_mul_f32_e32 v18, 0xbfb8aa3b, v18
	v_exp_f32_e32 v65, v18
	v_add_f32_e32 v18, v19, v31
	v_mul_f32_e32 v18, 0xbfb8aa3b, v18
	v_pk_mul_f32 v[28:29], v[70:71], v[52:53]
	v_exp_f32_e32 v55, v18
	v_pk_mul_f32 v[30:31], v[80:81], v[62:63]
	v_pk_mul_f32 v[18:19], v[28:29], v[28:29]
	v_cvt_f32_f16_e32 v56, v85
	v_pk_fma_f32 v[70:71], v[30:31], v[30:31], v[18:19]
	v_add_f32_e32 v18, v24, v48
	v_mul_f32_e32 v18, 0xbfb8aa3b, v18
	v_exp_f32_e32 v60, v18
	v_add_f32_e32 v18, v20, v32
	v_mul_f32_e32 v18, 0xbfb8aa3b, v18
	v_exp_f32_e32 v50, v18
	v_add_f32_e32 v18, v25, v49
	v_cvt_f32_f16_e32 v48, v87
	v_cvt_f32_f16_sdwa v49, v87 dst_sel:DWORD dst_unused:UNUSED_PAD src0_sel:WORD_1
	v_cvt_f32_f16_sdwa v57, v85 dst_sel:DWORD dst_unused:UNUSED_PAD src0_sel:WORD_1
	v_mul_f32_e32 v18, 0xbfb8aa3b, v18
	v_exp_f32_e32 v61, v18
	v_add_f32_e32 v18, v21, v33
	v_add_f32_e32 v22, v22, v46
	v_mul_f32_e32 v18, 0xbfb8aa3b, v18
	v_pk_mul_f32 v[32:33], v[72:73], v[48:49]
	v_mul_f32_e32 v22, 0xbfb8aa3b, v22
	v_exp_f32_e32 v51, v18
	v_pk_mul_f32 v[46:47], v[82:83], v[56:57]
	v_pk_mul_f32 v[18:19], v[32:33], v[32:33]
	v_exp_f32_e32 v64, v22
	v_pk_fma_f32 v[72:73], v[46:47], v[46:47], v[18:19]
	global_load_dwordx4 v[18:21], v[126:127], off offset:16
	global_load_dwordx4 v[22:25], v[126:127], off
	v_cvt_f32_f16_e32 v80, v42
	v_cvt_f32_f16_sdwa v81, v42 dst_sel:DWORD dst_unused:UNUSED_PAD src0_sel:WORD_1
	v_div_scale_f32 v42, s[0:1], v77, v77, 1.0
	v_rcp_f32_e32 v82, v42
	s_nop 0
	v_fma_f32 v83, -v42, v82, 1.0
	v_fmac_f32_e32 v82, v83, v82
	v_div_scale_f32 v83, vcc, 1.0, v77, 1.0
	v_mul_f32_e32 v84, v83, v82
	v_fma_f32 v85, -v42, v84, v83
	v_fmac_f32_e32 v84, v85, v82
	v_fma_f32 v42, -v42, v84, v83
	v_div_fmas_f32 v42, v42, v82, v84
	v_div_fixup_f32 v77, v42, v77, 1.0
	v_div_scale_f32 v42, s[0:1], v76, v76, 1.0
	v_rcp_f32_e32 v82, v42
	s_nop 0
	v_fma_f32 v83, -v42, v82, 1.0
	v_fmac_f32_e32 v82, v83, v82
	v_div_scale_f32 v83, vcc, 1.0, v76, 1.0
	v_mul_f32_e32 v84, v83, v82
	v_fma_f32 v85, -v42, v84, v83
	v_fmac_f32_e32 v84, v85, v82
	v_fma_f32 v42, -v42, v84, v83
	v_div_fmas_f32 v42, v42, v82, v84
	v_div_fixup_f32 v76, v42, v76, 1.0
	v_pk_add_f32 v[82:83], v[76:77], -1.0 op_sel_hi:[1,0]
	v_cvt_f32_f16_e32 v42, v43
	v_cvt_f32_f16_sdwa v43, v43 dst_sel:DWORD dst_unused:UNUSED_PAD src0_sel:WORD_1
	s_waitcnt vmcnt(0)
	v_pk_fma_f32 v[22:23], v[82:83], v[22:23], 1.0 op_sel_hi:[1,1,0]
	s_nop 0
	v_pk_mul_f32 v[22:23], v[22:23], v[80:81]
	s_nop 0
	v_cvt_pk_f16_f32 v22, v22, v23
	v_div_scale_f32 v23, s[0:1], v79, v79, 1.0
	v_rcp_f32_e32 v82, v23
	s_nop 0
	v_fma_f32 v83, -v23, v82, 1.0
	v_fmac_f32_e32 v82, v83, v82
	v_div_scale_f32 v83, vcc, 1.0, v79, 1.0
	v_mul_f32_e32 v84, v83, v82
	v_fma_f32 v85, -v23, v84, v83
	v_fmac_f32_e32 v84, v85, v82
	v_fma_f32 v23, -v23, v84, v83
	v_div_fmas_f32 v23, v23, v82, v84
	v_div_fixup_f32 v79, v23, v79, 1.0
	v_div_scale_f32 v23, s[0:1], v78, v78, 1.0
	v_rcp_f32_e32 v82, v23
	s_nop 0
	v_fma_f32 v83, -v23, v82, 1.0
	v_fmac_f32_e32 v82, v83, v82
	v_div_scale_f32 v83, vcc, 1.0, v78, 1.0
	v_mul_f32_e32 v84, v83, v82
	v_fma_f32 v85, -v23, v84, v83
	v_fmac_f32_e32 v84, v85, v82
	v_fma_f32 v23, -v23, v84, v83
	v_div_fmas_f32 v23, v23, v82, v84
	v_div_fixup_f32 v78, v23, v78, 1.0
	v_pk_add_f32 v[82:83], v[78:79], -1.0 op_sel_hi:[1,0]
	s_nop 0
	v_pk_fma_f32 v[24:25], v[82:83], v[24:25], 1.0 op_sel_hi:[1,1,0]
	v_cvt_f32_f16_e32 v82, v44
	v_pk_mul_f32 v[24:25], v[24:25], v[42:43]
	v_cvt_f32_f16_sdwa v83, v44 dst_sel:DWORD dst_unused:UNUSED_PAD src0_sel:WORD_1
	v_cvt_pk_f16_f32 v23, v24, v25
	v_pk_add_f32 v[24:25], v[74:75], 1.0 op_sel_hi:[1,0]
	s_nop 0
	v_div_scale_f32 v44, s[0:1], v25, v25, 1.0
	v_rcp_f32_e32 v74, v44
	s_nop 0
	v_fma_f32 v75, -v44, v74, 1.0
	v_fmac_f32_e32 v74, v75, v74
	v_div_scale_f32 v75, vcc, 1.0, v25, 1.0
	v_mul_f32_e32 v84, v75, v74
	v_fma_f32 v85, -v44, v84, v75
	v_fmac_f32_e32 v84, v85, v74
	v_fma_f32 v44, -v44, v84, v75
	v_div_fmas_f32 v44, v44, v74, v84
	v_div_fixup_f32 v75, v44, v25, 1.0
	v_div_scale_f32 v25, s[0:1], v24, v24, 1.0
	v_rcp_f32_e32 v44, v25
	s_nop 0
	v_fma_f32 v74, -v25, v44, 1.0
	v_fmac_f32_e32 v44, v74, v44
	v_div_scale_f32 v74, vcc, 1.0, v24, 1.0
	v_mul_f32_e32 v84, v74, v44
	v_fma_f32 v85, -v25, v84, v74
	v_fmac_f32_e32 v84, v85, v44
	v_fma_f32 v25, -v25, v84, v74
	v_div_fmas_f32 v25, v25, v44, v84
	v_div_fixup_f32 v74, v25, v24, 1.0
	v_pk_add_f32 v[24:25], v[74:75], -1.0 op_sel_hi:[1,0]
	v_cvt_f32_f16_e32 v44, v45
	v_pk_fma_f32 v[18:19], v[24:25], v[18:19], 1.0 op_sel_hi:[1,1,0]
	v_cvt_f32_f16_sdwa v45, v45 dst_sel:DWORD dst_unused:UNUSED_PAD src0_sel:WORD_1
	v_pk_mul_f32 v[18:19], v[18:19], v[82:83]
	v_pk_mul_f32 v[36:37], v[36:37], v[44:45]
	v_cvt_pk_f16_f32 v24, v18, v19
	v_pk_add_f32 v[18:19], v[68:69], 1.0 op_sel_hi:[1,0]
	s_nop 0
	v_div_scale_f32 v25, s[0:1], v19, v19, 1.0
	v_rcp_f32_e32 v68, v25
	s_nop 0
	v_fma_f32 v69, -v25, v68, 1.0
	v_fmac_f32_e32 v68, v69, v68
	v_div_scale_f32 v69, vcc, 1.0, v19, 1.0
	v_mul_f32_e32 v84, v69, v68
	v_fma_f32 v85, -v25, v84, v69
	v_fmac_f32_e32 v84, v85, v68
	v_fma_f32 v25, -v25, v84, v69
	v_div_fmas_f32 v25, v25, v68, v84
	v_div_fixup_f32 v19, v25, v19, 1.0
	v_div_scale_f32 v25, s[0:1], v18, v18, 1.0
	v_rcp_f32_e32 v68, v25
	s_nop 0
	v_fma_f32 v69, -v25, v68, 1.0
	v_fmac_f32_e32 v68, v69, v68
	v_div_scale_f32 v69, vcc, 1.0, v18, 1.0
	v_mul_f32_e32 v84, v69, v68
	v_fma_f32 v85, -v25, v84, v69
	v_fmac_f32_e32 v84, v85, v68
	v_fma_f32 v25, -v25, v84, v69
	v_div_fmas_f32 v25, v25, v68, v84
	v_div_fixup_f32 v18, v25, v18, 1.0
	v_pk_add_f32 v[68:69], v[18:19], -1.0 op_sel_hi:[1,0]
	s_nop 0
	v_pk_fma_f32 v[20:21], v[68:69], v[20:21], 1.0 op_sel_hi:[1,1,0]
	s_nop 0
	v_pk_mul_f32 v[20:21], v[20:21], v[44:45]
	v_lshlrev_b64 v[44:45], 12, v[58:59]
	v_cvt_pk_f16_f32 v25, v20, v21
	global_store_dwordx4 v[66:67], v[22:25], off
	v_pk_mul_f32 v[20:21], v[38:39], v[80:81]
	v_pk_mul_f32 v[38:39], v[36:37], v[36:37]
	v_pk_mul_f32 v[24:25], v[34:35], v[82:83]
	v_pk_mul_f32 v[22:23], v[40:41], v[42:43]
	v_pk_mul_f32 v[34:35], v[24:25], v[24:25]
	v_pk_fma_f32 v[38:39], v[22:23], v[22:23], v[38:39]
	v_pk_fma_f32 v[34:35], v[20:21], v[20:21], v[34:35]
	s_nop 0
	v_add_f32_e32 v34, v34, v35
	v_add_f32_e32 v34, v38, v34
	v_add_f32_e32 v34, v39, v34
	v_add_f32_e32 v34, v34, v70
	v_add_f32_e32 v34, v71, v34
	v_add_f32_e32 v34, v72, v34
	v_add_f32_e32 v34, v73, v34
	ds_bpermute_b32 v35, v206, v34
	s_waitcnt lgkmcnt(0)
;     __device__ __forceinline__ void body_a(const f32x4 (&acc)[2][2][4][2], int row0, int cb0) const {
;     ...
;                 ss += __shfl_xor(ss, 16); ss += __shfl_xor(ss, 32);
;                 const float inv = 1.0f / fmaxf(sqrtf(ss), 1e-12f);
; #pragma unroll
;                 for (int bj = 0; bj < 2; ++bj) {
;                     const int c = cb0 + 32 * bj;
;                     const f32x4 p0 = *(const f32x4*)(k_a + c), p1 = *(const f32x4*)(k_a + c + 4);
;                     f32x4 ko0, ko1, ao0, ao1, bo0, bo1;
; #pragma unroll
;                     for (int e = 0; e < 4; ++e) {
;                         ko0[e] = kv[bj][e] * (1.0f + (a[bj][e] - 1.0f) * p0[e]); ko1[e] = kv[bj][4 + e] * (1.0f + (a[bj][4 + e] - 1.0f) * p1[e]);
;                         const float n0_ = kk[bj][e] * inv, n1_ = kk[bj][4 + e] * inv;
;                         ao0[e] = -n0_; ao1[e] = -n1_; bo0[e] = n0_ * a[bj][e]; bo1[e] = n1_ * a[bj][4 + e];
;                     }
;                     *(u32x4*)(C1 + row * LDC1 + 2048 + c) = pack8(ko0, ko1);
;                     *(u32x4*)(AA + row * DM + c) = pack8(ao0, ao1);
;                     *(u32x4*)(Ab + row * DM + c) = pack8(bo0, bo1);
;                 }
	v_add_f32_e32 v34, v34, v35
	ds_bpermute_b32 v35, v207, v34
	s_waitcnt lgkmcnt(0)
	v_add_f32_e32 v34, v34, v35
	v_cmp_gt_f32_e32 vcc, s4, v34
	v_mul_f32_e32 v35, 0x4f800000, v34
	s_nop 0
	v_cndmask_b32_e32 v34, v34, v35, vcc
	v_sqrt_f32_e32 v35, v34
	s_nop 0
	v_add_u32_e32 v38, -1, v35
	v_fma_f32 v39, -v38, v35, v34
	v_cmp_ge_f32_e64 s[0:1], 0, v39
	v_add_u32_e32 v39, 1, v35
	s_nop 0
	v_cndmask_b32_e64 v38, v35, v38, s[0:1]
	v_fma_f32 v35, -v39, v35, v34
	v_cmp_lt_f32_e64 s[0:1], 0, v35
	s_nop 1
	v_cndmask_b32_e64 v35, v38, v39, s[0:1]
	v_mul_f32_e32 v38, 0x37800000, v35
	v_cndmask_b32_e32 v35, v35, v38, vcc
	v_cmp_class_f32_e32 vcc, v34, v244
	s_nop 1
	v_cndmask_b32_e32 v34, v35, v34, vcc
	v_max_f32_e32 v34, 0x2b8cbccc, v34
	v_div_scale_f32 v35, s[0:1], v34, v34, 1.0
	v_rcp_f32_e32 v38, v35
	s_nop 0
	v_fma_f32 v39, -v35, v38, 1.0
	v_fmac_f32_e32 v38, v39, v38
	v_div_scale_f32 v39, vcc, 1.0, v34, 1.0
	v_mul_f32_e32 v40, v39, v38
	v_fma_f32 v41, -v35, v40, v39
	v_fmac_f32_e32 v40, v41, v38
	v_fma_f32 v35, -v35, v40, v39
	v_div_fmas_f32 v35, v35, v38, v40
	v_div_fixup_f32 v38, v35, v34, 1.0
	v_pk_mul_f32 v[42:43], v[22:23], v[38:39] op_sel_hi:[1,0]
	v_pk_mul_f32 v[40:41], v[20:21], v[38:39] op_sel_hi:[1,0]
	v_cvt_pk_f16_f32 v21, v42, v43
	v_cvt_pk_f16_f32 v20, v40, v41
	v_xor_b32_e32 v22, 0x8000, v21
	v_xor_b32_sdwa v21, s63, v21 dst_sel:DWORD dst_unused:UNUSED_PAD src0_sel:DWORD src1_sel:WORD_1
	v_pk_mul_f32 v[24:25], v[24:25], v[38:39] op_sel_hi:[1,0]
	v_pk_mul_f32 v[36:37], v[36:37], v[38:39] op_sel_hi:[1,0]
	v_perm_b32 v21, v21, v22, s33
	v_xor_b32_e32 v22, 0x8000, v20
	v_xor_b32_sdwa v20, s63, v20 dst_sel:DWORD dst_unused:UNUSED_PAD src0_sel:DWORD src1_sel:WORD_1
	v_perm_b32 v20, v20, v22, s33
	v_pk_add_f32 v[22:23], v[24:25], 0 neg_lo:[1,1] neg_hi:[1,1]
	v_pk_add_f32 v[34:35], v[36:37], 0 neg_lo:[1,1] neg_hi:[1,1]
	v_cvt_pk_f16_f32 v22, v22, v23
	v_cvt_pk_f16_f32 v23, v34, v35
	v_lshl_add_u64 v[34:35], s[10:11], 0, v[44:45]
	v_lshl_add_u64 v[34:35], v[34:35], 0, v[152:153]
	global_store_dwordx4 v[34:35], v[20:23], off
	v_fma_mixlo_f16 v39, v76, v40, 0
	v_mul_f32_e32 v58, v30, v38
	v_pk_mov_b32 v[20:21], v[76:77], v[78:79] op_sel:[1,0]
	v_pk_mov_b32 v[22:23], v[40:41], v[42:43] op_sel:[1,0]
	v_pk_mov_b32 v[40:41], v[42:43], v[24:25] op_sel:[1,0]
	v_pk_mul_f32 v[20:21], v[20:21], v[22:23]
	v_pk_mov_b32 v[22:23], v[78:79], v[74:75] op_sel:[1,0]
	v_cvt_pk_f16_f32 v21, v20, v21
	v_pk_mul_f32 v[22:23], v[22:23], v[40:41]
	v_pack_b32_f16 v20, v39, v21
	v_cvt_pk_f16_f32 v39, v22, v23
	v_pk_mov_b32 v[22:23], v[74:75], v[18:19] op_sel:[1,0]
	v_pk_mov_b32 v[24:25], v[24:25], v[36:37] op_sel:[1,0]
	v_alignbit_b32 v21, v39, v21, 16
	v_pk_mul_f32 v[22:23], v[22:23], v[24:25]
	v_pk_add_f32 v[40:41], v[64:65], 1.0 op_sel_hi:[1,0]
	v_cvt_pk_f16_f32 v18, v22, v23
	v_lshrrev_b32_e32 v23, 16, v18
	v_alignbit_b32 v22, v18, v39, 16
	v_fma_mixhi_f16 v23, v19, v37, 0
	v_lshl_add_u64 v[18:19], s[2:3], 0, v[44:45]
	v_lshl_add_u64 v[36:37], v[18:19], 0, v[152:153]
	global_store_dwordx4 v[36:37], v[20:23], off
	global_load_dwordx4 v[18:21], v[126:127], off offset:144
	s_nop 0
	global_load_dwordx4 v[22:25], v[126:127], off offset:128
	v_div_scale_f32 v42, s[0:1], v41, v41, 1.0
	v_rcp_f32_e32 v43, v42
	v_mul_f32_e32 v39, v33, v38
	v_fma_f32 v44, -v42, v43, 1.0
	v_fmac_f32_e32 v43, v44, v43
	v_div_scale_f32 v44, vcc, 1.0, v41, 1.0
	v_mul_f32_e32 v45, v44, v43
	v_fma_f32 v59, -v42, v45, v44
	v_fmac_f32_e32 v45, v59, v43
	v_fma_f32 v42, -v42, v45, v44
	v_div_fmas_f32 v42, v42, v43, v45
	v_div_fixup_f32 v41, v42, v41, 1.0
	v_div_scale_f32 v42, s[0:1], v40, v40, 1.0
	v_rcp_f32_e32 v43, v42
	s_nop 0
	v_fma_f32 v44, -v42, v43, 1.0
	v_fmac_f32_e32 v43, v44, v43
	v_div_scale_f32 v44, vcc, 1.0, v40, 1.0
	v_mul_f32_e32 v45, v44, v43
	v_fma_f32 v59, -v42, v45, v44
	v_fmac_f32_e32 v45, v59, v43
	v_fma_f32 v42, -v42, v45, v44
	v_div_fmas_f32 v42, v42, v43, v45
	v_div_fixup_f32 v40, v42, v40, 1.0
	v_pk_add_f32 v[42:43], v[40:41], -1.0 op_sel_hi:[1,0]
	s_waitcnt vmcnt(0)
	v_pk_fma_f32 v[22:23], v[42:43], v[22:23], 1.0 op_sel_hi:[1,1,0]
	s_nop 0
	v_pk_mul_f32 v[22:23], v[22:23], v[62:63]
	v_pk_add_f32 v[42:43], v[60:61], 1.0 op_sel_hi:[1,0]
	v_cvt_pk_f16_f32 v22, v22, v23
	v_div_scale_f32 v23, s[0:1], v43, v43, 1.0
	v_rcp_f32_e32 v44, v23
	s_nop 0
	v_fma_f32 v45, -v23, v44, 1.0
	v_fmac_f32_e32 v44, v45, v44
	v_div_scale_f32 v45, vcc, 1.0, v43, 1.0
	v_mul_f32_e32 v59, v45, v44
	v_fma_f32 v60, -v23, v59, v45
	v_fmac_f32_e32 v59, v60, v44
	v_fma_f32 v23, -v23, v59, v45
	v_div_fmas_f32 v23, v23, v44, v59
	v_div_fixup_f32 v43, v23, v43, 1.0
	v_div_scale_f32 v23, s[0:1], v42, v42, 1.0
	v_rcp_f32_e32 v44, v23
	s_nop 0
	v_fma_f32 v45, -v23, v44, 1.0
	v_fmac_f32_e32 v44, v45, v44
	v_div_scale_f32 v45, vcc, 1.0, v42, 1.0
	v_mul_f32_e32 v59, v45, v44
	v_fma_f32 v60, -v23, v59, v45
	v_fmac_f32_e32 v59, v60, v44
	v_fma_f32 v23, -v23, v59, v45
	v_div_fmas_f32 v23, v23, v44, v59
	v_div_fixup_f32 v42, v23, v42, 1.0
	v_pk_add_f32 v[44:45], v[42:43], -1.0 op_sel_hi:[1,0]
	s_nop 0
	v_pk_fma_f32 v[24:25], v[44:45], v[24:25], 1.0 op_sel_hi:[1,1,0]
	s_nop 0
	v_pk_mul_f32 v[24:25], v[24:25], v[56:57]
	s_nop 0
	v_cvt_pk_f16_f32 v23, v24, v25
	v_pk_add_f32 v[24:25], v[54:55], 1.0 op_sel_hi:[1,0]
	s_nop 0
	v_div_scale_f32 v44, s[0:1], v25, v25, 1.0
	v_rcp_f32_e32 v45, v44
	s_nop 0
	v_fma_f32 v54, -v44, v45, 1.0
	v_fmac_f32_e32 v45, v54, v45
	v_div_scale_f32 v54, vcc, 1.0, v25, 1.0
	v_mul_f32_e32 v55, v54, v45
	v_fma_f32 v56, -v44, v55, v54
	v_fmac_f32_e32 v55, v56, v45
	v_fma_f32 v44, -v44, v55, v54
	v_div_fmas_f32 v44, v44, v45, v55
	v_div_fixup_f32 v45, v44, v25, 1.0
	v_div_scale_f32 v25, s[0:1], v24, v24, 1.0
; __device__ __forceinline__ float sigmoidf_(float x) { return 1.0f / (1.0f + __expf(-x)); }
;     __device__ __forceinline__ void body_a(const f32x4 (&acc)[2][2][4][2], int row0, int cb0) const {
;     ...
;                     const int c = cb0 + 32 * bj;
;                     const f32x4 b0 = *(const f32x4*)(a0 + c), b1 = *(const f32x4*)(a0 + c + 4), q0 = *(const f32x4*)(k_k + c), q1 = *(const f32x4*)(k_k + c + 4);
;                     const h16x8 kh = *(const h16x8*)(C1 + row * LDC1 + 2048 + c);
; #pragma unroll
;                     for (int e = 0; e < 4; ++e) {
;                         a[bj][e] = sigmoidf_(acc[ai][bj][m][0][e] + b0[e]); a[bj][4 + e] = sigmoidf_(acc[ai][bj][m][1][e] + b1[e]);
;     ...
;                     const f32x4 p0 = *(const f32x4*)(k_a + c), p1 = *(const f32x4*)(k_a + c + 4);
;                     f32x4 ko0, ko1, ao0, ao1, bo0, bo1;
; #pragma unroll
;                     for (int e = 0; e < 4; ++e) {
;                         ko0[e] = kv[bj][e] * (1.0f + (a[bj][e] - 1.0f) * p0[e]); ko1[e] = kv[bj][4 + e] * (1.0f + (a[bj][4 + e] - 1.0f) * p1[e]);
;                         const float n0_ = kk[bj][e] * inv, n1_ = kk[bj][4 + e] * inv;
;                         ao0[e] = -n0_; ao1[e] = -n1_; bo0[e] = n0_ * a[bj][e]; bo1[e] = n1_ * a[bj][4 + e];
;                     }
;                     *(u32x4*)(C1 + row * LDC1 + 2048 + c) = pack8(ko0, ko1);
;                     *(u32x4*)(AA + row * DM + c) = pack8(ao0, ao1);
;                     *(u32x4*)(Ab + row * DM + c) = pack8(bo0, bo1);
;                 }
	v_rcp_f32_e32 v44, v25
	s_nop 0
	v_fma_f32 v54, -v25, v44, 1.0
	v_fmac_f32_e32 v44, v54, v44
	v_div_scale_f32 v54, vcc, 1.0, v24, 1.0
	v_mul_f32_e32 v55, v54, v44
	v_fma_f32 v56, -v25, v55, v54
	v_fmac_f32_e32 v55, v56, v44
	v_fma_f32 v25, -v25, v55, v54
	v_div_fmas_f32 v25, v25, v44, v55
	v_div_fixup_f32 v44, v25, v24, 1.0
	v_pk_add_f32 v[24:25], v[44:45], -1.0 op_sel_hi:[1,0]
	s_nop 0
	v_pk_fma_f32 v[18:19], v[24:25], v[18:19], 1.0 op_sel_hi:[1,1,0]
	s_nop 0
	v_pk_mul_f32 v[18:19], v[18:19], v[52:53]
	s_nop 0
	v_cvt_pk_f16_f32 v24, v18, v19
	v_pk_add_f32 v[18:19], v[50:51], 1.0 op_sel_hi:[1,0]
	s_nop 0
	v_div_scale_f32 v25, s[0:1], v19, v19, 1.0
	v_rcp_f32_e32 v50, v25
	s_nop 0
	v_fma_f32 v51, -v25, v50, 1.0
	v_fmac_f32_e32 v50, v51, v50
	v_div_scale_f32 v51, vcc, 1.0, v19, 1.0
	v_mul_f32_e32 v52, v51, v50
	v_fma_f32 v53, -v25, v52, v51
	v_fmac_f32_e32 v52, v53, v50
	v_fma_f32 v25, -v25, v52, v51
	v_div_fmas_f32 v25, v25, v50, v52
	v_div_fixup_f32 v51, v25, v19, 1.0
	v_div_scale_f32 v19, s[0:1], v18, v18, 1.0
	v_rcp_f32_e32 v25, v19
	s_nop 0
	v_fma_f32 v50, -v19, v25, 1.0
	v_fmac_f32_e32 v25, v50, v25
	v_div_scale_f32 v50, vcc, 1.0, v18, 1.0
	v_mul_f32_e32 v52, v50, v25
	v_fma_f32 v53, -v19, v52, v50
	v_fmac_f32_e32 v52, v53, v25
	v_fma_f32 v19, -v19, v52, v50
	v_div_fmas_f32 v19, v19, v25, v52
	v_div_fixup_f32 v50, v19, v18, 1.0
	v_pk_add_f32 v[18:19], v[50:51], -1.0 op_sel_hi:[1,0]
	s_nop 0
	v_pk_fma_f32 v[18:19], v[18:19], v[20:21], 1.0 op_sel_hi:[1,1,0]
	v_cvt_f16_f32_e64 v20, -v58
	v_pk_mul_f32 v[18:19], v[18:19], v[48:49]
	s_nop 0
	v_cvt_pk_f16_f32 v25, v18, v19
	v_pk_mov_b32 v[18:19], v[30:31], v[46:47] op_sel:[1,0]
	global_store_dwordx4 v[26:27], v[22:25], off
	s_nop 1
	v_pk_mul_f32 v[22:23], v[18:19], v[38:39] op_sel_hi:[1,0]
	s_nop 0
	v_cvt_pk_f16_f32 v19, v22, v23
	v_pack_b32_f16 v18, v20, -v19
	v_pk_mov_b32 v[20:21], v[46:47], v[28:29] op_sel:[1,0]
	v_xor_b32_sdwa v19, s63, v19 dst_sel:DWORD dst_unused:UNUSED_PAD src0_sel:DWORD src1_sel:WORD_1
	v_pk_mul_f32 v[24:25], v[20:21], v[38:39] op_sel_hi:[1,0]
	s_nop 0
	v_cvt_pk_f16_f32 v20, v24, v25
	v_xor_b32_e32 v21, 0x8000, v20
	v_perm_b32 v19, v21, v19, s33
	v_xor_b32_sdwa v30, s63, v20 dst_sel:DWORD dst_unused:UNUSED_PAD src0_sel:DWORD src1_sel:WORD_1
	v_pk_mov_b32 v[20:21], v[28:29], v[32:33] op_sel:[1,0]
	v_cvt_f16_f32_e64 v28, -v39
	v_pk_mul_f32 v[26:27], v[20:21], v[38:39] op_sel_hi:[1,0]
	s_nop 0
	v_cvt_pk_f16_f32 v21, v26, v27
	v_xor_b32_e32 v20, 0x8000, v21
	v_xor_b32_sdwa v21, s63, v21 dst_sel:DWORD dst_unused:UNUSED_PAD src0_sel:DWORD src1_sel:WORD_1
	v_perm_b32 v20, v20, v30, s33
	v_perm_b32 v21, v28, v21, s33
	global_store_dwordx4 v[34:35], v[18:21], off offset:64
	s_nop 1
	v_pk_mov_b32 v[18:19], v[40:41], v[42:43] op_sel:[1,0]
	v_fma_mixlo_f16 v20, v40, v58, 0
	v_pk_mul_f32 v[18:19], v[18:19], v[22:23]
	s_nop 0
	v_cvt_pk_f16_f32 v19, v18, v19
	v_pack_b32_f16 v18, v20, v19
	v_pk_mov_b32 v[20:21], v[42:43], v[44:45] op_sel:[1,0]
	s_nop 0
	v_pk_mul_f32 v[20:21], v[20:21], v[24:25]
	s_nop 0
	v_cvt_pk_f16_f32 v22, v20, v21
	v_pk_mov_b32 v[20:21], v[44:45], v[50:51] op_sel:[1,0]
	v_alignbit_b32 v19, v22, v19, 16
	v_pk_mul_f32 v[20:21], v[20:21], v[26:27]
	s_nop 0
	v_cvt_pk_f16_f32 v21, v20, v21
	v_alignbit_b32 v20, v21, v22, 16
	v_lshrrev_b32_e32 v21, 16, v21
	v_fma_mixhi_f16 v21, v51, v39, 0
	global_store_dwordx4 v[36:37], v[18:21], off offset:64
	v_add_u32_e32 v42, 0xb0, v158
	s_nop 0
	v_mad_i64_i32 v[18:19], s[0:1], v42, s5, v[160:161]
	v_lshl_add_u64 v[38:39], v[18:19], 0, s[6:7]
	global_load_dwordx4 v[30:33], v[154:155], off offset:16
	global_load_dwordx4 v[34:37], v[154:155], off
	global_load_dwordx4 v[18:21], v[156:157], off offset:16
	global_load_dwordx4 v[22:25], v[156:157], off
	v_lshl_add_u64 v[50:51], v[38:39], 0, v[152:153]
	global_load_dwordx4 v[26:29], v[50:51], off
	v_ashrrev_i32_e32 v43, 31, v42
	s_waitcnt vmcnt(4)
	v_add_f32_e32 v10, v10, v30
	v_mul_f32_e32 v10, 0xbfb8aa3b, v10
	v_exp_f32_e32 v58, v10
	s_waitcnt vmcnt(3)
	v_add_f32_e32 v10, v15, v35
	v_mul_f32_e32 v10, 0xbfb8aa3b, v10
	v_exp_f32_e32 v61, v10
	v_add_f32_e32 v10, v11, v31
	v_mul_f32_e32 v10, 0xbfb8aa3b, v10
	v_exp_f32_e32 v59, v10
	v_add_f32_e32 v10, v16, v36
	v_mul_f32_e32 v10, 0xbfb8aa3b, v10
	v_exp_f32_e32 v62, v10
	v_add_f32_e32 v10, v12, v32
	v_mul_f32_e32 v10, 0xbfb8aa3b, v10
	v_exp_f32_e32 v52, v10
	v_add_f32_e32 v10, v17, v37
	v_mul_f32_e32 v10, 0xbfb8aa3b, v10
	v_exp_f32_e32 v63, v10
	v_add_f32_e32 v10, v13, v33
	v_add_f32_e32 v14, v14, v34
	v_mul_f32_e32 v10, 0xbfb8aa3b, v10
	v_mul_f32_e32 v14, 0xbfb8aa3b, v14
	v_exp_f32_e32 v53, v10
	v_lshl_add_u64 v[10:11], v[38:39], 0, v[128:129]
	v_exp_f32_e32 v60, v14
	global_load_dwordx4 v[14:17], v[154:155], off offset:144
	global_load_dwordx4 v[30:33], v[154:155], off offset:128
	global_load_dwordx4 v[54:57], v[156:157], off offset:144
	global_load_dwordx4 v[64:67], v[156:157], off offset:128
	global_load_dwordx4 v[68:71], v[10:11], off
	v_pk_add_f32 v[62:63], v[62:63], 1.0 op_sel_hi:[1,0]
	v_pk_add_f32 v[60:61], v[60:61], 1.0 op_sel_hi:[1,0]
	s_waitcnt vmcnt(4)
	v_add_f32_e32 v2, v2, v14
	v_mul_f32_e32 v2, 0xbfb8aa3b, v2
	v_exp_f32_e32 v38, v2
	s_waitcnt vmcnt(3)
	v_add_f32_e32 v2, v7, v31
	s_waitcnt vmcnt(0)
; __device__ __forceinline__ float sigmoidf_(float x) { return 1.0f / (1.0f + __expf(-x)); }
;     __device__ __forceinline__ void body_a(const f32x4 (&acc)[2][2][4][2], int row0, int cb0) const {
;     ...
;                     const int c = cb0 + 32 * bj;
;                     const f32x4 b0 = *(const f32x4*)(a0 + c), b1 = *(const f32x4*)(a0 + c + 4), q0 = *(const f32x4*)(k_k + c), q1 = *(const f32x4*)(k_k + c + 4);
;                     const h16x8 kh = *(const h16x8*)(C1 + row * LDC1 + 2048 + c);
; #pragma unroll
;                     for (int e = 0; e < 4; ++e) {
;                         a[bj][e] = sigmoidf_(acc[ai][bj][m][0][e] + b0[e]); a[bj][4 + e] = sigmoidf_(acc[ai][bj][m][1][e] + b1[e]);
;                         kv[bj][e] = (float)kh[e]; kv[bj][4 + e] = (float)kh[4 + e];
;                         kk[bj][e] = kv[bj][e] * q0[e]; kk[bj][4 + e] = kv[bj][4 + e] * q1[e];
;                         ss += kk[bj][e] * kk[bj][e] + kk[bj][4 + e] * kk[bj][4 + e];
;                     }
;     ...
;                         ko0[e] = kv[bj][e] * (1.0f + (a[bj][e] - 1.0f) * p0[e]); ko1[e] = kv[bj][4 + e] * (1.0f + (a[bj][4 + e] - 1.0f) * p1[e]);
;                         const float n0_ = kk[bj][e] * inv, n1_ = kk[bj][4 + e] * inv;
;                         ao0[e] = -n0_; ao1[e] = -n1_; bo0[e] = n0_ * a[bj][e]; bo1[e] = n1_ * a[bj][4 + e];
;                     }
;                     *(u32x4*)(C1 + row * LDC1 + 2048 + c) = pack8(ko0, ko1);
	v_cvt_f32_f16_e32 v36, v70
	v_cvt_f32_f16_sdwa v37, v70 dst_sel:DWORD dst_unused:UNUSED_PAD src0_sel:WORD_1
	v_cvt_f32_f16_e32 v46, v68
	v_cvt_f32_f16_sdwa v47, v68 dst_sel:DWORD dst_unused:UNUSED_PAD src0_sel:WORD_1
	v_mul_f32_e32 v2, 0xbfb8aa3b, v2
	v_exp_f32_e32 v49, v2
	v_add_f32_e32 v2, v3, v15
	v_mul_f32_e32 v2, 0xbfb8aa3b, v2
	v_pk_mul_f32 v[12:13], v[54:55], v[36:37]
	v_exp_f32_e32 v39, v2
	v_pk_mul_f32 v[14:15], v[64:65], v[46:47]
	v_pk_mul_f32 v[2:3], v[12:13], v[12:13]
	v_cvt_f32_f16_e32 v40, v69
	v_pk_fma_f32 v[54:55], v[14:15], v[14:15], v[2:3]
	v_add_f32_e32 v2, v8, v32
	v_mul_f32_e32 v2, 0xbfb8aa3b, v2
	v_exp_f32_e32 v44, v2
	v_add_f32_e32 v2, v4, v16
	v_mul_f32_e32 v2, 0xbfb8aa3b, v2
	v_exp_f32_e32 v34, v2
	v_add_f32_e32 v2, v9, v33
	v_cvt_f32_f16_e32 v32, v71
	v_cvt_f32_f16_sdwa v33, v71 dst_sel:DWORD dst_unused:UNUSED_PAD src0_sel:WORD_1
	v_cvt_f32_f16_sdwa v41, v69 dst_sel:DWORD dst_unused:UNUSED_PAD src0_sel:WORD_1
	v_mul_f32_e32 v2, 0xbfb8aa3b, v2
	v_exp_f32_e32 v45, v2
	v_add_f32_e32 v2, v5, v17
	v_add_f32_e32 v6, v6, v30
	v_mul_f32_e32 v2, 0xbfb8aa3b, v2
	v_pk_mul_f32 v[16:17], v[56:57], v[32:33]
	v_mul_f32_e32 v6, 0xbfb8aa3b, v6
	v_exp_f32_e32 v35, v2
	v_pk_mul_f32 v[30:31], v[66:67], v[40:41]
	v_pk_mul_f32 v[2:3], v[16:17], v[16:17]
	v_exp_f32_e32 v48, v6
	v_pk_fma_f32 v[56:57], v[30:31], v[30:31], v[2:3]
	global_load_dwordx4 v[2:5], v[126:127], off offset:16
	global_load_dwordx4 v[6:9], v[126:127], off
	v_cvt_f32_f16_e32 v64, v26
	v_cvt_f32_f16_sdwa v65, v26 dst_sel:DWORD dst_unused:UNUSED_PAD src0_sel:WORD_1
	v_div_scale_f32 v26, s[0:1], v61, v61, 1.0
	v_rcp_f32_e32 v66, v26
	s_nop 0
	v_fma_f32 v67, -v26, v66, 1.0
	v_fmac_f32_e32 v66, v67, v66
	v_div_scale_f32 v67, vcc, 1.0, v61, 1.0
	v_mul_f32_e32 v68, v67, v66
	v_fma_f32 v69, -v26, v68, v67
	v_fmac_f32_e32 v68, v69, v66
	v_fma_f32 v26, -v26, v68, v67
	v_div_fmas_f32 v26, v26, v66, v68
	v_div_fixup_f32 v61, v26, v61, 1.0
	v_div_scale_f32 v26, s[0:1], v60, v60, 1.0
	v_rcp_f32_e32 v66, v26
	s_nop 0
	v_fma_f32 v67, -v26, v66, 1.0
	v_fmac_f32_e32 v66, v67, v66
	v_div_scale_f32 v67, vcc, 1.0, v60, 1.0
	v_mul_f32_e32 v68, v67, v66
	v_fma_f32 v69, -v26, v68, v67
	v_fmac_f32_e32 v68, v69, v66
	v_fma_f32 v26, -v26, v68, v67
	v_div_fmas_f32 v26, v26, v66, v68
	v_div_fixup_f32 v60, v26, v60, 1.0
	v_pk_add_f32 v[66:67], v[60:61], -1.0 op_sel_hi:[1,0]
	v_cvt_f32_f16_e32 v26, v27
	v_cvt_f32_f16_sdwa v27, v27 dst_sel:DWORD dst_unused:UNUSED_PAD src0_sel:WORD_1
	s_waitcnt vmcnt(0)
	v_pk_fma_f32 v[6:7], v[66:67], v[6:7], 1.0 op_sel_hi:[1,1,0]
	s_nop 0
	v_pk_mul_f32 v[6:7], v[6:7], v[64:65]
	s_nop 0
	v_cvt_pk_f16_f32 v6, v6, v7
	v_div_scale_f32 v7, s[0:1], v63, v63, 1.0
	v_rcp_f32_e32 v66, v7
	s_nop 0
	v_fma_f32 v67, -v7, v66, 1.0
	v_fmac_f32_e32 v66, v67, v66
	v_div_scale_f32 v67, vcc, 1.0, v63, 1.0
	v_mul_f32_e32 v68, v67, v66
	v_fma_f32 v69, -v7, v68, v67
	v_fmac_f32_e32 v68, v69, v66
	v_fma_f32 v7, -v7, v68, v67
	v_div_fmas_f32 v7, v7, v66, v68
	v_div_fixup_f32 v63, v7, v63, 1.0
	v_div_scale_f32 v7, s[0:1], v62, v62, 1.0
	v_rcp_f32_e32 v66, v7
	s_nop 0
	v_fma_f32 v67, -v7, v66, 1.0
	v_fmac_f32_e32 v66, v67, v66
	v_div_scale_f32 v67, vcc, 1.0, v62, 1.0
	v_mul_f32_e32 v68, v67, v66
	v_fma_f32 v69, -v7, v68, v67
	v_fmac_f32_e32 v68, v69, v66
	v_fma_f32 v7, -v7, v68, v67
	v_div_fmas_f32 v7, v7, v66, v68
	v_div_fixup_f32 v62, v7, v62, 1.0
	v_pk_add_f32 v[66:67], v[62:63], -1.0 op_sel_hi:[1,0]
	s_nop 0
	v_pk_fma_f32 v[8:9], v[66:67], v[8:9], 1.0 op_sel_hi:[1,1,0]
	v_cvt_f32_f16_e32 v66, v28
	v_pk_mul_f32 v[8:9], v[8:9], v[26:27]
	v_cvt_f32_f16_sdwa v67, v28 dst_sel:DWORD dst_unused:UNUSED_PAD src0_sel:WORD_1
	v_cvt_pk_f16_f32 v7, v8, v9
	v_pk_add_f32 v[8:9], v[58:59], 1.0 op_sel_hi:[1,0]
	s_nop 0
	v_div_scale_f32 v28, s[0:1], v9, v9, 1.0
	v_rcp_f32_e32 v58, v28
	s_nop 0
	v_fma_f32 v59, -v28, v58, 1.0
	v_fmac_f32_e32 v58, v59, v58
	v_div_scale_f32 v59, vcc, 1.0, v9, 1.0
	v_mul_f32_e32 v68, v59, v58
	v_fma_f32 v69, -v28, v68, v59
	v_fmac_f32_e32 v68, v69, v58
	v_fma_f32 v28, -v28, v68, v59
	v_div_fmas_f32 v28, v28, v58, v68
	v_div_fixup_f32 v59, v28, v9, 1.0
	v_div_scale_f32 v9, s[0:1], v8, v8, 1.0
	v_rcp_f32_e32 v28, v9
	s_nop 0
	v_fma_f32 v58, -v9, v28, 1.0
	v_fmac_f32_e32 v28, v58, v28
	v_div_scale_f32 v58, vcc, 1.0, v8, 1.0
	v_mul_f32_e32 v68, v58, v28
	v_fma_f32 v69, -v9, v68, v58
	v_fmac_f32_e32 v68, v69, v28
	v_fma_f32 v9, -v9, v68, v58
	v_div_fmas_f32 v9, v9, v28, v68
	v_div_fixup_f32 v58, v9, v8, 1.0
	v_pk_add_f32 v[8:9], v[58:59], -1.0 op_sel_hi:[1,0]
	v_cvt_f32_f16_e32 v28, v29
	v_pk_fma_f32 v[2:3], v[8:9], v[2:3], 1.0 op_sel_hi:[1,1,0]
	v_cvt_f32_f16_sdwa v29, v29 dst_sel:DWORD dst_unused:UNUSED_PAD src0_sel:WORD_1
	v_pk_mul_f32 v[2:3], v[2:3], v[66:67]
	v_pk_mul_f32 v[20:21], v[20:21], v[28:29]
	v_cvt_pk_f16_f32 v8, v2, v3
	v_pk_add_f32 v[2:3], v[52:53], 1.0 op_sel_hi:[1,0]
	s_nop 0
	v_div_scale_f32 v9, s[0:1], v3, v3, 1.0
	v_rcp_f32_e32 v52, v9
	s_nop 0
	v_fma_f32 v53, -v9, v52, 1.0
	v_fmac_f32_e32 v52, v53, v52
	v_div_scale_f32 v53, vcc, 1.0, v3, 1.0
	v_mul_f32_e32 v68, v53, v52
	v_fma_f32 v69, -v9, v68, v53
	v_fmac_f32_e32 v68, v69, v52
	v_fma_f32 v9, -v9, v68, v53
	v_div_fmas_f32 v9, v9, v52, v68
	v_div_fixup_f32 v3, v9, v3, 1.0
	v_div_scale_f32 v9, s[0:1], v2, v2, 1.0
	v_rcp_f32_e32 v52, v9
	s_nop 0
	v_fma_f32 v53, -v9, v52, 1.0
	v_fmac_f32_e32 v52, v53, v52
	v_div_scale_f32 v53, vcc, 1.0, v2, 1.0
	v_mul_f32_e32 v68, v53, v52
	v_fma_f32 v69, -v9, v68, v53
	v_fmac_f32_e32 v68, v69, v52
	v_fma_f32 v9, -v9, v68, v53
	v_div_fmas_f32 v9, v9, v52, v68
	v_div_fixup_f32 v2, v9, v2, 1.0
	v_pk_add_f32 v[52:53], v[2:3], -1.0 op_sel_hi:[1,0]
	s_nop 0
	v_pk_fma_f32 v[4:5], v[52:53], v[4:5], 1.0 op_sel_hi:[1,1,0]
	s_nop 0
	v_pk_mul_f32 v[4:5], v[4:5], v[28:29]
	v_lshlrev_b64 v[28:29], 12, v[42:43]
	v_cvt_pk_f16_f32 v9, v4, v5
	global_store_dwordx4 v[50:51], v[6:9], off
	v_pk_mul_f32 v[4:5], v[22:23], v[64:65]
	v_pk_mul_f32 v[22:23], v[20:21], v[20:21]
	v_pk_mul_f32 v[8:9], v[18:19], v[66:67]
	v_pk_mul_f32 v[6:7], v[24:25], v[26:27]
	v_pk_mul_f32 v[18:19], v[8:9], v[8:9]
	v_pk_fma_f32 v[22:23], v[6:7], v[6:7], v[22:23]
	v_pk_fma_f32 v[18:19], v[4:5], v[4:5], v[18:19]
	s_nop 0
	v_add_f32_e32 v18, v18, v19
	v_add_f32_e32 v18, v22, v18
	v_add_f32_e32 v18, v23, v18
	v_add_f32_e32 v18, v18, v54
	v_add_f32_e32 v18, v55, v18
	v_add_f32_e32 v18, v56, v18
	v_add_f32_e32 v18, v57, v18
	ds_bpermute_b32 v19, v206, v18
	s_waitcnt lgkmcnt(0)
;     __device__ __forceinline__ void body_a(const f32x4 (&acc)[2][2][4][2], int row0, int cb0) const {
;     ...
;                 ss += __shfl_xor(ss, 16); ss += __shfl_xor(ss, 32);
;                 const float inv = 1.0f / fmaxf(sqrtf(ss), 1e-12f);
; #pragma unroll
;                 for (int bj = 0; bj < 2; ++bj) {
;                     const int c = cb0 + 32 * bj;
;                     const f32x4 p0 = *(const f32x4*)(k_a + c), p1 = *(const f32x4*)(k_a + c + 4);
;                     f32x4 ko0, ko1, ao0, ao1, bo0, bo1;
; #pragma unroll
;                     for (int e = 0; e < 4; ++e) {
;                         ko0[e] = kv[bj][e] * (1.0f + (a[bj][e] - 1.0f) * p0[e]); ko1[e] = kv[bj][4 + e] * (1.0f + (a[bj][4 + e] - 1.0f) * p1[e]);
;                         const float n0_ = kk[bj][e] * inv, n1_ = kk[bj][4 + e] * inv;
;                         ao0[e] = -n0_; ao1[e] = -n1_; bo0[e] = n0_ * a[bj][e]; bo1[e] = n1_ * a[bj][4 + e];
;                     }
;                     *(u32x4*)(C1 + row * LDC1 + 2048 + c) = pack8(ko0, ko1);
;                     *(u32x4*)(AA + row * DM + c) = pack8(ao0, ao1);
;                     *(u32x4*)(Ab + row * DM + c) = pack8(bo0, bo1);
	v_add_f32_e32 v18, v18, v19
	ds_bpermute_b32 v19, v207, v18
	s_waitcnt lgkmcnt(0)
	v_add_f32_e32 v18, v18, v19
	v_cmp_gt_f32_e32 vcc, s4, v18
	v_mul_f32_e32 v19, 0x4f800000, v18
	s_nop 0
	v_cndmask_b32_e32 v18, v18, v19, vcc
	v_sqrt_f32_e32 v19, v18
	s_nop 0
	v_add_u32_e32 v22, -1, v19
	v_fma_f32 v23, -v22, v19, v18
	v_cmp_ge_f32_e64 s[0:1], 0, v23
	v_add_u32_e32 v23, 1, v19
	s_nop 0
	v_cndmask_b32_e64 v22, v19, v22, s[0:1]
	v_fma_f32 v19, -v23, v19, v18
	v_cmp_lt_f32_e64 s[0:1], 0, v19
	s_nop 1
	v_cndmask_b32_e64 v19, v22, v23, s[0:1]
	v_mul_f32_e32 v22, 0x37800000, v19
	v_cndmask_b32_e32 v19, v19, v22, vcc
	v_cmp_class_f32_e32 vcc, v18, v244
	s_nop 1
	v_cndmask_b32_e32 v18, v19, v18, vcc
	v_max_f32_e32 v18, 0x2b8cbccc, v18
	v_div_scale_f32 v19, s[0:1], v18, v18, 1.0
	v_rcp_f32_e32 v22, v19
	s_nop 0
	v_fma_f32 v23, -v19, v22, 1.0
	v_fmac_f32_e32 v22, v23, v22
	v_div_scale_f32 v23, vcc, 1.0, v18, 1.0
	v_mul_f32_e32 v24, v23, v22
	v_fma_f32 v25, -v19, v24, v23
	v_fmac_f32_e32 v24, v25, v22
	v_fma_f32 v19, -v19, v24, v23
	v_div_fmas_f32 v19, v19, v22, v24
	v_div_fixup_f32 v22, v19, v18, 1.0
	v_pk_mul_f32 v[26:27], v[6:7], v[22:23] op_sel_hi:[1,0]
	v_pk_mul_f32 v[24:25], v[4:5], v[22:23] op_sel_hi:[1,0]
	v_cvt_pk_f16_f32 v5, v26, v27
	v_cvt_pk_f16_f32 v4, v24, v25
	v_xor_b32_e32 v6, 0x8000, v5
	v_xor_b32_sdwa v5, s63, v5 dst_sel:DWORD dst_unused:UNUSED_PAD src0_sel:DWORD src1_sel:WORD_1
	v_pk_mul_f32 v[8:9], v[8:9], v[22:23] op_sel_hi:[1,0]
	v_pk_mul_f32 v[20:21], v[20:21], v[22:23] op_sel_hi:[1,0]
	v_perm_b32 v5, v5, v6, s33
	v_xor_b32_e32 v6, 0x8000, v4
	v_xor_b32_sdwa v4, s63, v4 dst_sel:DWORD dst_unused:UNUSED_PAD src0_sel:DWORD src1_sel:WORD_1
	v_perm_b32 v4, v4, v6, s33
	v_pk_add_f32 v[6:7], v[8:9], 0 neg_lo:[1,1] neg_hi:[1,1]
	v_pk_add_f32 v[18:19], v[20:21], 0 neg_lo:[1,1] neg_hi:[1,1]
	v_cvt_pk_f16_f32 v6, v6, v7
	v_cvt_pk_f16_f32 v7, v18, v19
	v_lshl_add_u64 v[18:19], s[10:11], 0, v[28:29]
	v_lshl_add_u64 v[18:19], v[18:19], 0, v[152:153]
	global_store_dwordx4 v[18:19], v[4:7], off
	v_fma_mixlo_f16 v23, v60, v24, 0
	v_mul_f32_e32 v42, v14, v22
	v_pk_mov_b32 v[4:5], v[60:61], v[62:63] op_sel:[1,0]
	v_pk_mov_b32 v[6:7], v[24:25], v[26:27] op_sel:[1,0]
	v_pk_mov_b32 v[24:25], v[26:27], v[8:9] op_sel:[1,0]
	v_pk_mul_f32 v[4:5], v[4:5], v[6:7]
	v_pk_mov_b32 v[6:7], v[62:63], v[58:59] op_sel:[1,0]
	v_cvt_pk_f16_f32 v5, v4, v5
	v_pk_mul_f32 v[6:7], v[6:7], v[24:25]
	v_pack_b32_f16 v4, v23, v5
	v_cvt_pk_f16_f32 v23, v6, v7
	v_pk_mov_b32 v[6:7], v[58:59], v[2:3] op_sel:[1,0]
	v_pk_mov_b32 v[8:9], v[8:9], v[20:21] op_sel:[1,0]
	v_alignbit_b32 v5, v23, v5, 16
	v_pk_mul_f32 v[6:7], v[6:7], v[8:9]
	v_pk_add_f32 v[24:25], v[48:49], 1.0 op_sel_hi:[1,0]
	v_cvt_pk_f16_f32 v2, v6, v7
	v_lshrrev_b32_e32 v7, 16, v2
	v_alignbit_b32 v6, v2, v23, 16
	v_fma_mixhi_f16 v7, v3, v21, 0
	v_lshl_add_u64 v[2:3], s[2:3], 0, v[28:29]
	v_lshl_add_u64 v[20:21], v[2:3], 0, v[152:153]
	global_store_dwordx4 v[20:21], v[4:7], off
	global_load_dwordx4 v[2:5], v[126:127], off offset:144
	s_nop 0
	global_load_dwordx4 v[6:9], v[126:127], off offset:128
	v_div_scale_f32 v26, s[0:1], v25, v25, 1.0
	v_rcp_f32_e32 v27, v26
	v_mul_f32_e32 v23, v17, v22
	v_fma_f32 v28, -v26, v27, 1.0
	v_fmac_f32_e32 v27, v28, v27
	v_div_scale_f32 v28, vcc, 1.0, v25, 1.0
	v_mul_f32_e32 v29, v28, v27
	v_fma_f32 v43, -v26, v29, v28
	v_fmac_f32_e32 v29, v43, v27
	v_fma_f32 v26, -v26, v29, v28
	v_div_fmas_f32 v26, v26, v27, v29
	v_div_fixup_f32 v25, v26, v25, 1.0
	v_div_scale_f32 v26, s[0:1], v24, v24, 1.0
	v_rcp_f32_e32 v27, v26
	s_nop 0
	v_fma_f32 v28, -v26, v27, 1.0
	v_fmac_f32_e32 v27, v28, v27
	v_div_scale_f32 v28, vcc, 1.0, v24, 1.0
	v_mul_f32_e32 v29, v28, v27
	v_fma_f32 v43, -v26, v29, v28
	v_fmac_f32_e32 v29, v43, v27
	v_fma_f32 v26, -v26, v29, v28
	v_div_fmas_f32 v26, v26, v27, v29
	v_div_fixup_f32 v24, v26, v24, 1.0
	v_pk_add_f32 v[26:27], v[24:25], -1.0 op_sel_hi:[1,0]
	s_waitcnt vmcnt(0)
;     __device__ __forceinline__ void body_a(const f32x4 (&acc)[2][2][4][2], int row0, int cb0) const {
;     ...
;                     const f32x4 p0 = *(const f32x4*)(k_a + c), p1 = *(const f32x4*)(k_a + c + 4);
;                     f32x4 ko0, ko1, ao0, ao1, bo0, bo1;
; #pragma unroll
;                     for (int e = 0; e < 4; ++e) {
;                         ko0[e] = kv[bj][e] * (1.0f + (a[bj][e] - 1.0f) * p0[e]); ko1[e] = kv[bj][4 + e] * (1.0f + (a[bj][4 + e] - 1.0f) * p1[e]);
;                         const float n0_ = kk[bj][e] * inv, n1_ = kk[bj][4 + e] * inv;
;                         ao0[e] = -n0_; ao1[e] = -n1_; bo0[e] = n0_ * a[bj][e]; bo1[e] = n1_ * a[bj][4 + e];
;                     }
;                     *(u32x4*)(C1 + row * LDC1 + 2048 + c) = pack8(ko0, ko1);
;                     *(u32x4*)(AA + row * DM + c) = pack8(ao0, ao1);
;                     *(u32x4*)(Ab + row * DM + c) = pack8(bo0, bo1);
;                 }
;                 __builtin_amdgcn_sched_barrier(0);
	v_pk_fma_f32 v[6:7], v[26:27], v[6:7], 1.0 op_sel_hi:[1,1,0]
	s_nop 0
	v_pk_mul_f32 v[6:7], v[6:7], v[46:47]
	v_pk_add_f32 v[26:27], v[44:45], 1.0 op_sel_hi:[1,0]
	v_cvt_pk_f16_f32 v6, v6, v7
	v_div_scale_f32 v7, s[0:1], v27, v27, 1.0
	v_rcp_f32_e32 v28, v7
	s_nop 0
	v_fma_f32 v29, -v7, v28, 1.0
	v_fmac_f32_e32 v28, v29, v28
	v_div_scale_f32 v29, vcc, 1.0, v27, 1.0
	v_mul_f32_e32 v43, v29, v28
	v_fma_f32 v44, -v7, v43, v29
	v_fmac_f32_e32 v43, v44, v28
	v_fma_f32 v7, -v7, v43, v29
	v_div_fmas_f32 v7, v7, v28, v43
	v_div_fixup_f32 v27, v7, v27, 1.0
	v_div_scale_f32 v7, s[0:1], v26, v26, 1.0
	v_rcp_f32_e32 v28, v7
	s_nop 0
	v_fma_f32 v29, -v7, v28, 1.0
	v_fmac_f32_e32 v28, v29, v28
	v_div_scale_f32 v29, vcc, 1.0, v26, 1.0
	v_mul_f32_e32 v43, v29, v28
	v_fma_f32 v44, -v7, v43, v29
	v_fmac_f32_e32 v43, v44, v28
	v_fma_f32 v7, -v7, v43, v29
	v_div_fmas_f32 v7, v7, v28, v43
	v_div_fixup_f32 v26, v7, v26, 1.0
	v_pk_add_f32 v[28:29], v[26:27], -1.0 op_sel_hi:[1,0]
	s_nop 0
	v_pk_fma_f32 v[8:9], v[28:29], v[8:9], 1.0 op_sel_hi:[1,1,0]
	s_nop 0
	v_pk_mul_f32 v[8:9], v[8:9], v[40:41]
	s_nop 0
	v_cvt_pk_f16_f32 v7, v8, v9
	v_pk_add_f32 v[8:9], v[38:39], 1.0 op_sel_hi:[1,0]
	s_nop 0
	v_div_scale_f32 v28, s[0:1], v9, v9, 1.0
	v_rcp_f32_e32 v29, v28
	s_nop 0
	v_fma_f32 v38, -v28, v29, 1.0
	v_fmac_f32_e32 v29, v38, v29
	v_div_scale_f32 v38, vcc, 1.0, v9, 1.0
	v_mul_f32_e32 v39, v38, v29
	v_fma_f32 v40, -v28, v39, v38
	v_fmac_f32_e32 v39, v40, v29
	v_fma_f32 v28, -v28, v39, v38
	v_div_fmas_f32 v28, v28, v29, v39
	v_div_fixup_f32 v29, v28, v9, 1.0
	v_div_scale_f32 v9, s[0:1], v8, v8, 1.0
	v_rcp_f32_e32 v28, v9
	s_nop 0
	v_fma_f32 v38, -v9, v28, 1.0
	v_fmac_f32_e32 v28, v38, v28
	v_div_scale_f32 v38, vcc, 1.0, v8, 1.0
	v_mul_f32_e32 v39, v38, v28
	v_fma_f32 v40, -v9, v39, v38
	v_fmac_f32_e32 v39, v40, v28
	v_fma_f32 v9, -v9, v39, v38
	v_div_fmas_f32 v9, v9, v28, v39
	v_div_fixup_f32 v28, v9, v8, 1.0
	v_pk_add_f32 v[8:9], v[28:29], -1.0 op_sel_hi:[1,0]
	s_nop 0
	v_pk_fma_f32 v[2:3], v[8:9], v[2:3], 1.0 op_sel_hi:[1,1,0]
	s_nop 0
	v_pk_mul_f32 v[2:3], v[2:3], v[36:37]
	s_nop 0
	v_cvt_pk_f16_f32 v8, v2, v3
	v_pk_add_f32 v[2:3], v[34:35], 1.0 op_sel_hi:[1,0]
	s_nop 0
	v_div_scale_f32 v9, s[0:1], v3, v3, 1.0
	v_rcp_f32_e32 v34, v9
	s_nop 0
	v_fma_f32 v35, -v9, v34, 1.0
	v_fmac_f32_e32 v34, v35, v34
	v_div_scale_f32 v35, vcc, 1.0, v3, 1.0
	v_mul_f32_e32 v36, v35, v34
	v_fma_f32 v37, -v9, v36, v35
	v_fmac_f32_e32 v36, v37, v34
	v_fma_f32 v9, -v9, v36, v35
	v_div_fmas_f32 v9, v9, v34, v36
	v_div_fixup_f32 v35, v9, v3, 1.0
	v_div_scale_f32 v3, s[0:1], v2, v2, 1.0
	v_rcp_f32_e32 v9, v3
	s_nop 0
	v_fma_f32 v34, -v3, v9, 1.0
	v_fmac_f32_e32 v9, v34, v9
	v_div_scale_f32 v34, vcc, 1.0, v2, 1.0
	v_mul_f32_e32 v36, v34, v9
	v_fma_f32 v37, -v3, v36, v34
	v_fmac_f32_e32 v36, v37, v9
	v_fma_f32 v3, -v3, v36, v34
	v_div_fmas_f32 v3, v3, v9, v36
	v_div_fixup_f32 v34, v3, v2, 1.0
	v_pk_add_f32 v[2:3], v[34:35], -1.0 op_sel_hi:[1,0]
	s_nop 0
	v_pk_fma_f32 v[2:3], v[2:3], v[4:5], 1.0 op_sel_hi:[1,1,0]
	v_cvt_f16_f32_e64 v4, -v42
	v_pk_mul_f32 v[2:3], v[2:3], v[32:33]
	s_nop 0
	v_cvt_pk_f16_f32 v9, v2, v3
	v_pk_mov_b32 v[2:3], v[14:15], v[30:31] op_sel:[1,0]
	global_store_dwordx4 v[10:11], v[6:9], off
	s_nop 1
	v_pk_mul_f32 v[6:7], v[2:3], v[22:23] op_sel_hi:[1,0]
	s_nop 0
	v_cvt_pk_f16_f32 v3, v6, v7
	v_pack_b32_f16 v2, v4, -v3
	v_pk_mov_b32 v[4:5], v[30:31], v[12:13] op_sel:[1,0]
	v_xor_b32_sdwa v3, s63, v3 dst_sel:DWORD dst_unused:UNUSED_PAD src0_sel:DWORD src1_sel:WORD_1
	v_pk_mul_f32 v[8:9], v[4:5], v[22:23] op_sel_hi:[1,0]
	s_nop 0
	v_cvt_pk_f16_f32 v4, v8, v9
	v_xor_b32_e32 v5, 0x8000, v4
	v_perm_b32 v3, v5, v3, s33
	v_xor_b32_sdwa v14, s63, v4 dst_sel:DWORD dst_unused:UNUSED_PAD src0_sel:DWORD src1_sel:WORD_1
	v_pk_mov_b32 v[4:5], v[12:13], v[16:17] op_sel:[1,0]
	v_cvt_f16_f32_e64 v12, -v23
	v_pk_mul_f32 v[10:11], v[4:5], v[22:23] op_sel_hi:[1,0]
	s_nop 0
	v_cvt_pk_f16_f32 v5, v10, v11
	v_xor_b32_e32 v4, 0x8000, v5
	v_xor_b32_sdwa v5, s63, v5 dst_sel:DWORD dst_unused:UNUSED_PAD src0_sel:DWORD src1_sel:WORD_1
	v_perm_b32 v4, v4, v14, s33
	v_perm_b32 v5, v12, v5, s33
	global_store_dwordx4 v[18:19], v[2:5], off offset:64
	s_nop 1
	v_pk_mov_b32 v[2:3], v[24:25], v[26:27] op_sel:[1,0]
	v_fma_mixlo_f16 v4, v24, v42, 0
	v_pk_mul_f32 v[2:3], v[2:3], v[6:7]
	s_nop 0
	v_cvt_pk_f16_f32 v3, v2, v3
	v_pack_b32_f16 v2, v4, v3
	v_pk_mov_b32 v[4:5], v[26:27], v[28:29] op_sel:[1,0]
	s_nop 0
	v_pk_mul_f32 v[4:5], v[4:5], v[8:9]
	s_nop 0
	v_cvt_pk_f16_f32 v6, v4, v5
	v_pk_mov_b32 v[4:5], v[28:29], v[34:35] op_sel:[1,0]
	v_alignbit_b32 v3, v6, v3, 16
	v_pk_mul_f32 v[4:5], v[4:5], v[10:11]
	s_nop 0
	v_cvt_pk_f16_f32 v5, v4, v5
	v_alignbit_b32 v4, v5, v6, 16
	v_lshrrev_b32_e32 v5, 16, v5
	v_fma_mixhi_f16 v5, v35, v23, 0
	global_store_dwordx4 v[20:21], v[2:5], off offset:64
	s_and_b64 vcc, exec, s[38:39]
	s_mov_b32 s50, s44
	s_mov_b32 s35, s82
	s_mov_b64 s[26:27], s[64:65]
	s_mov_b64 s[22:23], s[46:47]
	s_cbranch_vccnz .LBB0_645

; #define PG8_STAGE(bufoff, gbase, voff) do { _Pragma("unroll") for (int _i = 0; _i < 2; ++_i) \
;         __builtin_amdgcn_global_load_lds((const unsigned*)((const char*)(gbase) + (voff)[_i]), (LAS unsigned*)(lds + (bufoff) + ldsw + _i * 8192), 16, 0, 0); } while (0)
; #define PG8_LDA(dst, b, h) do { _Pragma("unroll") for (int m = 0; m < 4; ++m) _Pragma("unroll") for (int k = 0; k < 2; ++k) dst[m][k] = *(const LAS h16x8*)(lds + PG8_SA(b, h) + aoff + m * 2048 + k * 1024); } while (0)
; #define PG8_LDB(dst, b, h) do { _Pragma("unroll") for (int n = 0; n < 2; ++n) _Pragma("unroll") for (int k = 0; k < 2; ++k) dst[n][k] = *(const LAS h16x8*)(lds + PG8_SB(b, h) + boff + n * 2048 + k * 1024); } while (0)
; #define PG8_WAIT_L(n) asm volatile("s_waitcnt lgkmcnt(" #n ")" ::: "memory")
; #define PG8_BAR __builtin_amdgcn_s_barrier()
; #define PG8_SCHED __builtin_amdgcn_sched_barrier(0)
; template <class Epi, class AMap>
; __device__ __forceinline__ void gemm_phase(LAS unsigned char* lds, const AMap am, const int lda, const h16* Bt, const int ldb, const int M, const int N, const int K, const Epi& E) {
;     ...
;         const bool has_next = S.next(ui + 1, nxt);
;         const char* nA = has_next ? am(nxt.pn) + (size_t)nxt.pm * tstepA : cA; const char* nB = has_next ? (const char*)Bt + (size_t)nxt.pn * tstepB : cB;
; #pragma unroll 1
;         for (int t = 0; t < nt; t += 2) {
;             const bool last = (t == nt - 2);
;             const char* a1 = cA + (size_t)(t + 1) * kstep;
;             const char* a2 = last ? nA : cA + (size_t)(t + 2) * kstep; const char* b2 = last ? nB : cB + (size_t)(t + 2) * kstep;
;             const char* a3 = a2 + kstep; const char* b3 = b2 + kstep;
;             PG8_LDB(B0, 0, 0); PG8_SCHED; PG8_LDA(At, 0, 0); PG8_STAGE(PG8_SA(1, 1), a1 + hstepA, voffA);
;             PG8_WAIT_L(8); PG8_BAR; PG8_WAIT_L(0); PG8_MMA(0, 0, At, B0); PG8_BAR; PG8_SCHED;
;     ...
; #pragma unroll
;         for (int a = 0; a < 2; ++a)
; #pragma unroll
;             for (int b = 0; b < 2; ++b)
; #pragma unroll
;                 for (int m = 0; m < 4; ++m)
; #pragma unroll
;                     for (int n = 0; n < 2; ++n) acc[a][b][m][n] = (f32x4){0.f, 0.f, 0.f, 0.f};
;         cur = nxt; cA = nA; cB = nB; ++ui;
.LBB0_642:
	s_ashr_i32 s45, s44, 31
	s_lshl_b64 s[20:21], s[44:45], 17
	s_add_u32 s64, s72, s20
	v_mov_b32_e32 v125, 0
	s_addc_u32 s65, s73, s21
	s_andn2_b64 vcc, exec, s[42:43]
	v_mov_b32_e32 v124, v125
	v_mov_b32_e32 v123, v125
	v_mov_b32_e32 v122, v125
	v_mov_b32_e32 v129, v125
	v_mov_b32_e32 v128, v125
	v_mov_b32_e32 v127, v125
	v_mov_b32_e32 v126, v125
	v_mov_b32_e32 v113, v125
	v_mov_b32_e32 v112, v125
	v_mov_b32_e32 v111, v125
	v_mov_b32_e32 v110, v125
	v_mov_b32_e32 v109, v125
	v_mov_b32_e32 v108, v125
	v_mov_b32_e32 v107, v125
	v_mov_b32_e32 v106, v125
	v_mov_b32_e32 v97, v125
	v_mov_b32_e32 v96, v125
	v_mov_b32_e32 v95, v125
	v_mov_b32_e32 v94, v125
	v_mov_b32_e32 v93, v125
	v_mov_b32_e32 v92, v125
	v_mov_b32_e32 v91, v125
	v_mov_b32_e32 v90, v125
	v_mov_b32_e32 v81, v125
	v_mov_b32_e32 v80, v125
	v_mov_b32_e32 v79, v125
	v_mov_b32_e32 v78, v125
	v_mov_b32_e32 v77, v125
	v_mov_b32_e32 v76, v125
	v_mov_b32_e32 v75, v125
	v_mov_b32_e32 v74, v125
	v_mov_b32_e32 v121, v125
	v_mov_b32_e32 v120, v125
	v_mov_b32_e32 v119, v125
	v_mov_b32_e32 v118, v125
	v_mov_b32_e32 v117, v125
	v_mov_b32_e32 v116, v125
	v_mov_b32_e32 v115, v125
	v_mov_b32_e32 v114, v125
	v_mov_b32_e32 v105, v125
	v_mov_b32_e32 v104, v125
	v_mov_b32_e32 v103, v125
	v_mov_b32_e32 v102, v125
	v_mov_b32_e32 v101, v125
	v_mov_b32_e32 v100, v125
	v_mov_b32_e32 v99, v125
	v_mov_b32_e32 v98, v125
	v_mov_b32_e32 v89, v125
	v_mov_b32_e32 v88, v125
	v_mov_b32_e32 v87, v125
	v_mov_b32_e32 v86, v125
	v_mov_b32_e32 v85, v125
	v_mov_b32_e32 v84, v125
	v_mov_b32_e32 v83, v125
	v_mov_b32_e32 v82, v125
	v_mov_b32_e32 v73, v125
	v_mov_b32_e32 v72, v125
	v_mov_b32_e32 v71, v125
	v_mov_b32_e32 v70, v125
	v_mov_b32_e32 v69, v125
	v_mov_b32_e32 v68, v125
	v_mov_b32_e32 v67, v125
	v_mov_b32_e32 v66, v125
	v_mov_b32_e32 v65, v125
	v_mov_b32_e32 v64, v125
	v_mov_b32_e32 v63, v125
	v_mov_b32_e32 v62, v125
	v_mov_b32_e32 v61, v125
	v_mov_b32_e32 v60, v125
	v_mov_b32_e32 v59, v125
	v_mov_b32_e32 v58, v125
	v_mov_b32_e32 v49, v125
	v_mov_b32_e32 v48, v125
	v_mov_b32_e32 v47, v125
	v_mov_b32_e32 v46, v125
	v_mov_b32_e32 v45, v125
	v_mov_b32_e32 v44, v125
	v_mov_b32_e32 v43, v125
	v_mov_b32_e32 v42, v125
	v_mov_b32_e32 v33, v125
	v_mov_b32_e32 v32, v125
	v_mov_b32_e32 v31, v125
	v_mov_b32_e32 v30, v125
	v_mov_b32_e32 v29, v125
	v_mov_b32_e32 v28, v125
	v_mov_b32_e32 v27, v125
	v_mov_b32_e32 v26, v125
	v_mov_b32_e32 v17, v125
	v_mov_b32_e32 v16, v125
	v_mov_b32_e32 v15, v125
	v_mov_b32_e32 v14, v125
	v_mov_b32_e32 v13, v125
	v_mov_b32_e32 v12, v125
	v_mov_b32_e32 v11, v125
	v_mov_b32_e32 v10, v125
	v_mov_b32_e32 v57, v125
	v_mov_b32_e32 v56, v125
	v_mov_b32_e32 v55, v125
	v_mov_b32_e32 v54, v125
	v_mov_b32_e32 v53, v125
	v_mov_b32_e32 v52, v125
	v_mov_b32_e32 v51, v125
	v_mov_b32_e32 v50, v125
	v_mov_b32_e32 v41, v125
	v_mov_b32_e32 v40, v125
	v_mov_b32_e32 v39, v125
	v_mov_b32_e32 v38, v125
	v_mov_b32_e32 v37, v125
	v_mov_b32_e32 v36, v125
	v_mov_b32_e32 v35, v125
	v_mov_b32_e32 v34, v125
	v_mov_b32_e32 v25, v125
	v_mov_b32_e32 v24, v125
	v_mov_b32_e32 v23, v125
	v_mov_b32_e32 v22, v125
	v_mov_b32_e32 v21, v125
	v_mov_b32_e32 v20, v125
	v_mov_b32_e32 v19, v125
	v_mov_b32_e32 v18, v125
	v_mov_b32_e32 v9, v125
	v_mov_b32_e32 v8, v125
	v_mov_b32_e32 v7, v125
	v_mov_b32_e32 v6, v125
	v_mov_b32_e32 v5, v125
	v_mov_b32_e32 v4, v125
	v_mov_b32_e32 v3, v125
	v_mov_b32_e32 v2, v125
	s_cbranch_vccnz .LBB0_633
	s_and_b64 s[0:1], s[0:1], exec
	s_cselect_b32 s20, s65, s27
	s_cselect_b32 s21, s64, s26
	s_add_u32 s29, s26, 0x100
	s_addc_u32 s45, s27, 0
	s_mov_b32 s26, 0
	s_cmpk_lt_u32 s69, 0x100
	s_cbranch_scc1 .Lgy5
	s_barrier
.Lgy5:
.LBB0_644:
	s_add_i32 s51, s26, 2
	s_add_u32 s0, s22, 0x100
	s_addc_u32 s1, s23, 0
	s_add_i32 s60, 0, 0x10000
	v_add_u32_e32 v234, s60, v203
	ds_read_b128 v[130:133], v234
	ds_read_b128 v[134:137], v234 offset:1024
	ds_read_b128 v[138:141], v234 offset:2048
	ds_read_b128 v[152:155], v234 offset:3072
	s_cmp_eq_u32 s80, s26
	s_cselect_b32 s26, s21, s29
	s_cselect_b32 s49, s47, s1
	s_cselect_b32 s48, s46, s0
	s_cselect_b32 s27, s20, s45
	v_lshl_add_u64 v[232:233], s[22:23], 0, v[148:149]
	s_add_i32 m0, s74, 0xc000
	ds_read_b128 v[156:159], v205
	ds_read_b128 v[160:163], v205 offset:1024
	ds_read_b128 v[164:167], v205 offset:2048
	ds_read_b128 v[168:171], v205 offset:3072
	ds_read_b128 v[172:175], v205 offset:4096
	ds_read_b128 v[176:179], v205 offset:5120
	ds_read_b128 v[180:183], v205 offset:6144
	ds_read_b128 v[184:187], v205 offset:7168
	global_load_lds_dwordx4 v[232:233], off
	v_lshl_add_u64 v[232:233], s[22:23], 0, v[150:151]
	s_add_i32 m0, s74, 0xe000
	s_nop 0
	global_load_lds_dwordx4 v[232:233], off
	s_waitcnt lgkmcnt(11)
	s_add_i32 s62, 0, 0x14000
	v_add_u32_e32 v200, s62, v203
	s_add_i32 s22, s60, s71
	ds_read_b128 v[188:191], v200
	ds_read_b128 v[192:195], v200 offset:1024
	ds_read_b128 v[196:199], v200 offset:2048
	ds_read_b128 v[220:223], v200 offset:3072
	s_waitcnt vmcnt(8) lgkmcnt(0)
	s_barrier
; #define PG8_STAGE(bufoff, gbase, voff) do { _Pragma("unroll") for (int _i = 0; _i < 2; ++_i) \
;         __builtin_amdgcn_global_load_lds((const unsigned*)((const char*)(gbase) + (voff)[_i]), (LAS unsigned*)(lds + (bufoff) + ldsw + _i * 8192), 16, 0, 0); } while (0)
; #define PG8_LDA(dst, b, h) do { _Pragma("unroll") for (int m = 0; m < 4; ++m) _Pragma("unroll") for (int k = 0; k < 2; ++k) dst[m][k] = *(const LAS h16x8*)(lds + PG8_SA(b, h) + aoff + m * 2048 + k * 1024); } while (0)
; #define PG8_LDB(dst, b, h) do { _Pragma("unroll") for (int n = 0; n < 2; ++n) _Pragma("unroll") for (int k = 0; k < 2; ++k) dst[n][k] = *(const LAS h16x8*)(lds + PG8_SB(b, h) + boff + n * 2048 + k * 1024); } while (0)
; #define PG8_MMA(ai, bj, At, Bt_) do { __builtin_amdgcn_s_setprio(1); _Pragma("unroll") for (int m = 0; m < 4; ++m) _Pragma("unroll") for (int n = 0; n < 2; ++n) _Pragma("unroll") for (int k = 0; k < 2; ++k) \
;         acc[ai][bj][m][n] = __builtin_amdgcn_mfma_f32_16x16x32_f16(Bt_[n][k], At[m][k], acc[ai][bj][m][n], 0, 0, 0); __builtin_amdgcn_s_setprio(0); } while (0)
; #define PG8_WAIT_V(n) asm volatile("s_waitcnt vmcnt(" #n ")" ::: "memory")
; #define PG8_WAIT_L(n) asm volatile("s_waitcnt lgkmcnt(" #n ")" ::: "memory")
; #define PG8_BAR __builtin_amdgcn_s_barrier()
; #define PG8_SCHED __builtin_amdgcn_sched_barrier(0)
; template <class Epi, class AMap>
; __device__ __forceinline__ void gemm_phase(LAS unsigned char* lds, const AMap am, const int lda, const h16* Bt, const int ldb, const int M, const int N, const int K, const Epi& E) {
;     ...
;             PG8_LDB(B0, 0, 0); PG8_SCHED; PG8_LDA(At, 0, 0); PG8_STAGE(PG8_SA(1, 1), a1 + hstepA, voffA);
;             PG8_WAIT_L(8); PG8_BAR; PG8_WAIT_L(0); PG8_MMA(0, 0, At, B0); PG8_BAR; PG8_SCHED;
;             PG8_LDB(B1, 0, 1); PG8_STAGE(PG8_SB(0, 0), b2, voffB);
;             PG8_BAR; PG8_WAIT_L(0); PG8_MMA(0, 1, At, B1); PG8_BAR;
;             PG8_LDA(At, 0, 1); PG8_STAGE(PG8_SA(0, 0), a2, voffA);
;             PG8_BAR; PG8_WAIT_L(0); PG8_MMA(1, 0, At, B0); PG8_BAR; PG8_SCHED;
;             PG8_STAGE(PG8_SB(0, 1), b2 + hstepB, voffB);
;             PG8_WAIT_V(6); PG8_BAR; PG8_MMA(1, 1, At, B1); PG8_BAR;
	v_mfma_f32_16x16x32_f16 v[122:125], v[130:133], v[156:159], v[122:125]
	v_mfma_f32_16x16x32_f16 v[126:129], v[138:141], v[156:159], v[126:129]
	v_mfma_f32_16x16x32_f16 v[110:113], v[130:133], v[164:167], v[110:113]
	v_mfma_f32_16x16x32_f16 v[106:109], v[138:141], v[164:167], v[106:109]
	v_mfma_f32_16x16x32_f16 v[94:97], v[130:133], v[172:175], v[94:97]
	v_mfma_f32_16x16x32_f16 v[90:93], v[138:141], v[172:175], v[90:93]
	v_mfma_f32_16x16x32_f16 v[78:81], v[130:133], v[180:183], v[78:81]
	v_mfma_f32_16x16x32_f16 v[74:77], v[138:141], v[180:183], v[74:77]
	v_mfma_f32_16x16x32_f16 v[122:125], v[134:137], v[160:163], v[122:125]
	v_mfma_f32_16x16x32_f16 v[126:129], v[152:155], v[160:163], v[126:129]
	v_mfma_f32_16x16x32_f16 v[110:113], v[134:137], v[168:171], v[110:113]
	v_mfma_f32_16x16x32_f16 v[106:109], v[152:155], v[168:171], v[106:109]
	v_mfma_f32_16x16x32_f16 v[94:97], v[134:137], v[176:179], v[94:97]
	v_mfma_f32_16x16x32_f16 v[90:93], v[152:155], v[176:179], v[90:93]
	v_mfma_f32_16x16x32_f16 v[78:81], v[134:137], v[184:187], v[78:81]
	v_mfma_f32_16x16x32_f16 v[74:77], v[152:155], v[184:187], v[74:77]
	v_mfma_f32_16x16x32_f16 v[118:121], v[188:191], v[156:159], v[118:121]
	v_mfma_f32_16x16x32_f16 v[114:117], v[196:199], v[156:159], v[114:117]
	v_mfma_f32_16x16x32_f16 v[102:105], v[188:191], v[164:167], v[102:105]
	v_mfma_f32_16x16x32_f16 v[98:101], v[196:199], v[164:167], v[98:101]
	v_mfma_f32_16x16x32_f16 v[86:89], v[188:191], v[172:175], v[86:89]
	v_mfma_f32_16x16x32_f16 v[82:85], v[196:199], v[172:175], v[82:85]
	v_mfma_f32_16x16x32_f16 v[70:73], v[188:191], v[180:183], v[70:73]
	v_mfma_f32_16x16x32_f16 v[66:69], v[196:199], v[180:183], v[66:69]
	v_mfma_f32_16x16x32_f16 v[118:121], v[192:195], v[160:163], v[118:121]
	v_mfma_f32_16x16x32_f16 v[114:117], v[220:223], v[160:163], v[114:117]
	v_mfma_f32_16x16x32_f16 v[102:105], v[192:195], v[168:171], v[102:105]
	v_mfma_f32_16x16x32_f16 v[98:101], v[220:223], v[168:171], v[98:101]
	v_mfma_f32_16x16x32_f16 v[86:89], v[192:195], v[176:179], v[86:89]
	v_mfma_f32_16x16x32_f16 v[82:85], v[220:223], v[176:179], v[82:85]
	v_mfma_f32_16x16x32_f16 v[70:73], v[192:195], v[184:187], v[70:73]
	v_mfma_f32_16x16x32_f16 v[66:69], v[220:223], v[184:187], v[66:69]
	s_barrier
	v_lshl_add_u64 v[200:201], s[26:27], 0, v[0:1]
	s_mov_b32 m0, s22
	v_lshl_add_u64 v[206:207], s[26:27], 0, v[146:147]
	global_load_lds_dwordx4 v[200:201], off
	s_add_i32 m0, s22, 0x2000
	s_nop 0
	global_load_lds_dwordx4 v[206:207], off
	s_mov_b32 m0, s74
	v_lshl_add_u64 v[212:213], s[48:49], 0, v[142:143]
	ds_read_b128 v[156:159], v205 offset:16384
	ds_read_b128 v[160:163], v205 offset:17408
	ds_read_b128 v[164:167], v205 offset:18432
	ds_read_b128 v[168:171], v205 offset:19456
	ds_read_b128 v[172:175], v205 offset:20480
	ds_read_b128 v[176:179], v205 offset:21504
	ds_read_b128 v[180:183], v205 offset:22528
	ds_read_b128 v[184:187], v205 offset:23552
	global_load_lds_dwordx4 v[212:213], off
	v_lshl_add_u64 v[224:225], s[48:49], 0, v[144:145]
	s_mov_b32 m0, s75
	s_nop 0
	global_load_lds_dwordx4 v[224:225], off
	s_add_u32 s22, s26, 0x10000
	s_addc_u32 s23, s27, 0
	s_add_i32 s60, s62, s71
	v_lshl_add_u64 v[232:233], s[22:23], 0, v[0:1]
	s_mov_b32 m0, s60
	s_nop 0
	global_load_lds_dwordx4 v[232:233], off
	v_lshl_add_u64 v[232:233], s[22:23], 0, v[146:147]
	s_add_i32 m0, s60, 0x2000
	s_nop 0
	global_load_lds_dwordx4 v[232:233], off
	s_waitcnt vmcnt(8) lgkmcnt(0)
	s_barrier
	v_mfma_f32_16x16x32_f16 v[62:65], v[130:133], v[156:159], v[62:65]
	v_mfma_f32_16x16x32_f16 v[58:61], v[138:141], v[156:159], v[58:61]
	v_mfma_f32_16x16x32_f16 v[46:49], v[130:133], v[164:167], v[46:49]
	v_mfma_f32_16x16x32_f16 v[42:45], v[138:141], v[164:167], v[42:45]
	v_mfma_f32_16x16x32_f16 v[30:33], v[130:133], v[172:175], v[30:33]
	v_mfma_f32_16x16x32_f16 v[26:29], v[138:141], v[172:175], v[26:29]
	v_mfma_f32_16x16x32_f16 v[14:17], v[130:133], v[180:183], v[14:17]
	v_mfma_f32_16x16x32_f16 v[10:13], v[138:141], v[180:183], v[10:13]
	v_mfma_f32_16x16x32_f16 v[62:65], v[134:137], v[160:163], v[62:65]
	v_mfma_f32_16x16x32_f16 v[58:61], v[152:155], v[160:163], v[58:61]
	v_mfma_f32_16x16x32_f16 v[46:49], v[134:137], v[168:171], v[46:49]
	v_mfma_f32_16x16x32_f16 v[42:45], v[152:155], v[168:171], v[42:45]
	v_mfma_f32_16x16x32_f16 v[30:33], v[134:137], v[176:179], v[30:33]
	v_mfma_f32_16x16x32_f16 v[26:29], v[152:155], v[176:179], v[26:29]
	v_mfma_f32_16x16x32_f16 v[14:17], v[134:137], v[184:187], v[14:17]
	v_mfma_f32_16x16x32_f16 v[10:13], v[152:155], v[184:187], v[10:13]
	v_mfma_f32_16x16x32_f16 v[54:57], v[188:191], v[156:159], v[54:57]
	v_mfma_f32_16x16x32_f16 v[50:53], v[196:199], v[156:159], v[50:53]
	v_mfma_f32_16x16x32_f16 v[38:41], v[188:191], v[164:167], v[38:41]
	v_mfma_f32_16x16x32_f16 v[34:37], v[196:199], v[164:167], v[34:37]
	v_mfma_f32_16x16x32_f16 v[22:25], v[188:191], v[172:175], v[22:25]
	v_mfma_f32_16x16x32_f16 v[18:21], v[196:199], v[172:175], v[18:21]
	v_mfma_f32_16x16x32_f16 v[6:9], v[188:191], v[180:183], v[6:9]
	v_mfma_f32_16x16x32_f16 v[2:5], v[196:199], v[180:183], v[2:5]
	v_mfma_f32_16x16x32_f16 v[54:57], v[192:195], v[160:163], v[54:57]
	v_mfma_f32_16x16x32_f16 v[50:53], v[220:223], v[160:163], v[50:53]
	v_mfma_f32_16x16x32_f16 v[38:41], v[192:195], v[168:171], v[38:41]
	v_mfma_f32_16x16x32_f16 v[34:37], v[220:223], v[168:171], v[34:37]
	v_mfma_f32_16x16x32_f16 v[22:25], v[192:195], v[176:179], v[22:25]
	v_mfma_f32_16x16x32_f16 v[18:21], v[220:223], v[176:179], v[18:21]
	v_mfma_f32_16x16x32_f16 v[6:9], v[192:195], v[184:187], v[6:9]
	v_mfma_f32_16x16x32_f16 v[2:5], v[220:223], v[184:187], v[2:5]
	s_barrier
; #define PG8_STAGE(bufoff, gbase, voff) do { _Pragma("unroll") for (int _i = 0; _i < 2; ++_i) \
;         __builtin_amdgcn_global_load_lds((const unsigned*)((const char*)(gbase) + (voff)[_i]), (LAS unsigned*)(lds + (bufoff) + ldsw + _i * 8192), 16, 0, 0); } while (0)
; #define PG8_LDA(dst, b, h) do { _Pragma("unroll") for (int m = 0; m < 4; ++m) _Pragma("unroll") for (int k = 0; k < 2; ++k) dst[m][k] = *(const LAS h16x8*)(lds + PG8_SA(b, h) + aoff + m * 2048 + k * 1024); } while (0)
; #define PG8_LDB(dst, b, h) do { _Pragma("unroll") for (int n = 0; n < 2; ++n) _Pragma("unroll") for (int k = 0; k < 2; ++k) dst[n][k] = *(const LAS h16x8*)(lds + PG8_SB(b, h) + boff + n * 2048 + k * 1024); } while (0)
; #define PG8_MMA(ai, bj, At, Bt_) do { __builtin_amdgcn_s_setprio(1); _Pragma("unroll") for (int m = 0; m < 4; ++m) _Pragma("unroll") for (int n = 0; n < 2; ++n) _Pragma("unroll") for (int k = 0; k < 2; ++k) \
;         acc[ai][bj][m][n] = __builtin_amdgcn_mfma_f32_16x16x32_f16(Bt_[n][k], At[m][k], acc[ai][bj][m][n], 0, 0, 0); __builtin_amdgcn_s_setprio(0); } while (0)
; #define PG8_WAIT_V(n) asm volatile("s_waitcnt vmcnt(" #n ")" ::: "memory")
; #define PG8_WAIT_L(n) asm volatile("s_waitcnt lgkmcnt(" #n ")" ::: "memory")
; #define PG8_BAR __builtin_amdgcn_s_barrier()
; #define PG8_SCHED __builtin_amdgcn_sched_barrier(0)
; template <class Epi, class AMap>
; __device__ __forceinline__ void gemm_phase(LAS unsigned char* lds, const AMap am, const int lda, const h16* Bt, const int ldb, const int M, const int N, const int K, const Epi& E) {
;     ...
;             PG8_LDB(B0, 1, 0); PG8_SCHED; PG8_LDA(At, 1, 0); PG8_STAGE(PG8_SA(0, 1), a2 + hstepA, voffA);
;             PG8_WAIT_L(8); PG8_BAR; PG8_WAIT_L(0); PG8_MMA(0, 0, At, B0); PG8_BAR; PG8_SCHED;
;             PG8_LDB(B1, 1, 1); PG8_STAGE(PG8_SB(1, 0), b3, voffB);
;             PG8_BAR; PG8_WAIT_L(0); PG8_MMA(0, 1, At, B1); PG8_BAR;
;             PG8_LDA(At, 1, 1); PG8_STAGE(PG8_SA(1, 0), a3, voffA);
;             PG8_BAR; PG8_WAIT_L(0); PG8_MMA(1, 0, At, B0); PG8_BAR; PG8_SCHED;
;             PG8_STAGE(PG8_SB(1, 1), b3 + hstepB, voffB);
;             PG8_WAIT_V(6); PG8_BAR; PG8_MMA(1, 1, At, B1); PG8_BAR;
	s_add_i32 s60, 0, 0x18000
	v_add_u32_e32 v234, s60, v203
	ds_read_b128 v[130:133], v234
	ds_read_b128 v[134:137], v234 offset:1024
	ds_read_b128 v[138:141], v234 offset:2048
	ds_read_b128 v[152:155], v234 offset:3072
	s_add_u32 s22, s48, 0x1c0000
	s_addc_u32 s23, s49, 0
	s_mov_b32 m0, s76
	v_lshl_add_u64 v[232:233], s[22:23], 0, v[142:143]
	ds_read_b128 v[156:159], v205 offset:32768
	ds_read_b128 v[160:163], v205 offset:33792
	ds_read_b128 v[164:167], v205 offset:34816
	ds_read_b128 v[168:171], v205 offset:35840
	ds_read_b128 v[172:175], v205 offset:36864
	ds_read_b128 v[176:179], v205 offset:37888
	ds_read_b128 v[180:183], v205 offset:38912
	ds_read_b128 v[184:187], v205 offset:39936
	global_load_lds_dwordx4 v[232:233], off
	v_lshl_add_u64 v[232:233], s[22:23], 0, v[144:145]
	s_mov_b32 m0, s77
	s_nop 0
	global_load_lds_dwordx4 v[232:233], off
	s_waitcnt lgkmcnt(11)
	s_add_i32 s48, 0, 0x1c000
	s_add_i32 s22, s60, s71
	v_add_u32_e32 v214, s48, v203
	v_lshl_add_u64 v[200:201], v[200:201], 0, s[92:93]
	s_mov_b32 m0, s22
	ds_read_b128 v[188:191], v214
	ds_read_b128 v[192:195], v214 offset:1024
	ds_read_b128 v[196:199], v214 offset:2048
	ds_read_b128 v[220:223], v214 offset:3072
	s_waitcnt vmcnt(8) lgkmcnt(0)
	s_barrier
	v_mfma_f32_16x16x32_f16 v[122:125], v[130:133], v[156:159], v[122:125]
	v_mfma_f32_16x16x32_f16 v[126:129], v[138:141], v[156:159], v[126:129]
	v_mfma_f32_16x16x32_f16 v[110:113], v[130:133], v[164:167], v[110:113]
	v_mfma_f32_16x16x32_f16 v[106:109], v[138:141], v[164:167], v[106:109]
	v_mfma_f32_16x16x32_f16 v[94:97], v[130:133], v[172:175], v[94:97]
	v_mfma_f32_16x16x32_f16 v[90:93], v[138:141], v[172:175], v[90:93]
	v_mfma_f32_16x16x32_f16 v[78:81], v[130:133], v[180:183], v[78:81]
	v_mfma_f32_16x16x32_f16 v[74:77], v[138:141], v[180:183], v[74:77]
	v_mfma_f32_16x16x32_f16 v[122:125], v[134:137], v[160:163], v[122:125]
	v_mfma_f32_16x16x32_f16 v[126:129], v[152:155], v[160:163], v[126:129]
	v_mfma_f32_16x16x32_f16 v[110:113], v[134:137], v[168:171], v[110:113]
	v_mfma_f32_16x16x32_f16 v[106:109], v[152:155], v[168:171], v[106:109]
	v_mfma_f32_16x16x32_f16 v[94:97], v[134:137], v[176:179], v[94:97]
	v_mfma_f32_16x16x32_f16 v[90:93], v[152:155], v[176:179], v[90:93]
	v_mfma_f32_16x16x32_f16 v[78:81], v[134:137], v[184:187], v[78:81]
	v_mfma_f32_16x16x32_f16 v[74:77], v[152:155], v[184:187], v[74:77]
	v_mfma_f32_16x16x32_f16 v[118:121], v[188:191], v[156:159], v[118:121]
	v_mfma_f32_16x16x32_f16 v[114:117], v[196:199], v[156:159], v[114:117]
	v_mfma_f32_16x16x32_f16 v[102:105], v[188:191], v[164:167], v[102:105]
	v_mfma_f32_16x16x32_f16 v[98:101], v[196:199], v[164:167], v[98:101]
	v_mfma_f32_16x16x32_f16 v[86:89], v[188:191], v[172:175], v[86:89]
	v_mfma_f32_16x16x32_f16 v[82:85], v[196:199], v[172:175], v[82:85]
	v_mfma_f32_16x16x32_f16 v[70:73], v[188:191], v[180:183], v[70:73]
	v_mfma_f32_16x16x32_f16 v[66:69], v[196:199], v[180:183], v[66:69]
	v_mfma_f32_16x16x32_f16 v[118:121], v[192:195], v[160:163], v[118:121]
	v_mfma_f32_16x16x32_f16 v[114:117], v[220:223], v[160:163], v[114:117]
	v_mfma_f32_16x16x32_f16 v[102:105], v[192:195], v[168:171], v[102:105]
	v_mfma_f32_16x16x32_f16 v[98:101], v[220:223], v[168:171], v[98:101]
	v_mfma_f32_16x16x32_f16 v[86:89], v[192:195], v[176:179], v[86:89]
	v_mfma_f32_16x16x32_f16 v[82:85], v[220:223], v[176:179], v[82:85]
	v_mfma_f32_16x16x32_f16 v[70:73], v[192:195], v[184:187], v[70:73]
	v_mfma_f32_16x16x32_f16 v[66:69], v[220:223], v[184:187], v[66:69]
	s_barrier
	global_load_lds_dwordx4 v[200:201], off
	v_lshl_add_u64 v[200:201], v[206:207], 0, s[92:93]
	s_add_i32 m0, s22, 0x2000
	s_nop 0
	global_load_lds_dwordx4 v[200:201], off
	s_mov_b32 m0, s78
	v_lshl_add_u64 v[200:201], v[212:213], 0, s[92:93]
	ds_read_b128 v[156:159], v205 offset:49152
	ds_read_b128 v[160:163], v205 offset:50176
	ds_read_b128 v[164:167], v205 offset:51200
	ds_read_b128 v[168:171], v205 offset:52224
	ds_read_b128 v[172:175], v205 offset:53248
	ds_read_b128 v[176:179], v205 offset:54272
	ds_read_b128 v[180:183], v205 offset:55296
	ds_read_b128 v[184:187], v205 offset:56320
	global_load_lds_dwordx4 v[200:201], off
	v_lshl_add_u64 v[200:201], v[224:225], 0, s[92:93]
	s_mov_b32 m0, s79
	s_nop 0
	global_load_lds_dwordx4 v[200:201], off
	s_add_u32 s22, s26, 0x10080
	s_addc_u32 s23, s27, 0
	s_add_i32 s26, s48, s71
	v_lshl_add_u64 v[232:233], s[22:23], 0, v[0:1]
	s_mov_b32 m0, s26
	s_nop 0
	global_load_lds_dwordx4 v[232:233], off
	v_lshl_add_u64 v[232:233], s[22:23], 0, v[146:147]
	s_add_i32 m0, s26, 0x2000
	s_nop 0
	global_load_lds_dwordx4 v[232:233], off
	s_add_u32 s29, s29, 0x100
	s_addc_u32 s45, s45, 0
	s_cmp_ge_i32 s51, s24
	s_mov_b64 s[22:23], s[0:1]
	s_mov_b32 s26, s51
	s_waitcnt vmcnt(8) lgkmcnt(0)
	s_barrier
	v_mfma_f32_16x16x32_f16 v[62:65], v[130:133], v[156:159], v[62:65]
	v_mfma_f32_16x16x32_f16 v[58:61], v[138:141], v[156:159], v[58:61]
	v_mfma_f32_16x16x32_f16 v[46:49], v[130:133], v[164:167], v[46:49]
	v_mfma_f32_16x16x32_f16 v[42:45], v[138:141], v[164:167], v[42:45]
	v_mfma_f32_16x16x32_f16 v[30:33], v[130:133], v[172:175], v[30:33]
	v_mfma_f32_16x16x32_f16 v[26:29], v[138:141], v[172:175], v[26:29]
	v_mfma_f32_16x16x32_f16 v[14:17], v[130:133], v[180:183], v[14:17]
	v_mfma_f32_16x16x32_f16 v[10:13], v[138:141], v[180:183], v[10:13]
	v_mfma_f32_16x16x32_f16 v[62:65], v[134:137], v[160:163], v[62:65]
	v_mfma_f32_16x16x32_f16 v[58:61], v[152:155], v[160:163], v[58:61]
	v_mfma_f32_16x16x32_f16 v[46:49], v[134:137], v[168:171], v[46:49]
	v_mfma_f32_16x16x32_f16 v[42:45], v[152:155], v[168:171], v[42:45]
	v_mfma_f32_16x16x32_f16 v[30:33], v[134:137], v[176:179], v[30:33]
	v_mfma_f32_16x16x32_f16 v[26:29], v[152:155], v[176:179], v[26:29]
	v_mfma_f32_16x16x32_f16 v[14:17], v[134:137], v[184:187], v[14:17]
	v_mfma_f32_16x16x32_f16 v[10:13], v[152:155], v[184:187], v[10:13]
	v_mfma_f32_16x16x32_f16 v[54:57], v[188:191], v[156:159], v[54:57]
	v_mfma_f32_16x16x32_f16 v[50:53], v[196:199], v[156:159], v[50:53]
	v_mfma_f32_16x16x32_f16 v[38:41], v[188:191], v[164:167], v[38:41]
	v_mfma_f32_16x16x32_f16 v[34:37], v[196:199], v[164:167], v[34:37]
	v_mfma_f32_16x16x32_f16 v[22:25], v[188:191], v[172:175], v[22:25]
	v_mfma_f32_16x16x32_f16 v[18:21], v[196:199], v[172:175], v[18:21]
	v_mfma_f32_16x16x32_f16 v[6:9], v[188:191], v[180:183], v[6:9]
	v_mfma_f32_16x16x32_f16 v[2:5], v[196:199], v[180:183], v[2:5]
	v_mfma_f32_16x16x32_f16 v[54:57], v[192:195], v[160:163], v[54:57]
	v_mfma_f32_16x16x32_f16 v[50:53], v[220:223], v[160:163], v[50:53]
	v_mfma_f32_16x16x32_f16 v[38:41], v[192:195], v[168:171], v[38:41]
	v_mfma_f32_16x16x32_f16 v[34:37], v[220:223], v[168:171], v[34:37]
	v_mfma_f32_16x16x32_f16 v[22:25], v[192:195], v[176:179], v[22:25]
	v_mfma_f32_16x16x32_f16 v[18:21], v[220:223], v[176:179], v[18:21]
	v_mfma_f32_16x16x32_f16 v[6:9], v[192:195], v[184:187], v[6:9]
	v_mfma_f32_16x16x32_f16 v[2:5], v[220:223], v[184:187], v[2:5]
	s_barrier
	s_cbranch_scc0 .LBB0_644
	s_branch .LBB0_633
; #define PG8_WAIT_V(n) asm volatile("s_waitcnt vmcnt(" #n ")" ::: "memory")
; #define PG8_BAR __builtin_amdgcn_s_barrier()
; template <class Epi, class AMap>
; __device__ __forceinline__ void gemm_phase(LAS unsigned char* lds, const AMap am, const int lda, const h16* Bt, const int ldb, const int M, const int N, const int K, const Epi& E) {
;     ...
;     PG8_WAIT_V(0);
;     if (wr == 0) PG8_BAR;
;     PG8_BAR;
.LBB0_645:
	s_waitcnt vmcnt(0)
	s_cmpk_gt_u32 s69, 0xff
	s_cbranch_scc1 .LBB0_647
.LBB0_647:
	v_readlane_b32 s82, v255, 4
	v_readlane_b32 s29, v254, 37
	v_readlane_b32 s83, v255, 5
	v_readlane_b32 s10, v255, 10
	v_readlane_b32 s11, v255, 11
	s_barrier

; __device__ __forceinline__ int otid() { int t = (int)threadIdx.x; asm volatile("" : "+v"(t)); return t; }
; __device__ __forceinline__ int obid() { int t = (int)blockIdx.x; asm volatile("" : "+s"(t)); return t; }
; #define PG8_WAIT_V(n) asm volatile("s_waitcnt vmcnt(" #n ")" ::: "memory")
; #define PG8_BAR __builtin_amdgcn_s_barrier()
; template <class Epi, class AMap>
; __device__ __forceinline__ void gemm_phase(LAS unsigned char* lds, const AMap am, const int lda, const h16* Bt, const int ldb, const int M, const int N, const int K, const Epi& E) {
;     const int tid = otid(), wid = __builtin_amdgcn_readfirstlane(tid >> 6), lane = tid & 63, wr = wid >> 2, wc = wid & 3, fr = lane & 15, fq = lane >> 4;
;     const int nt = K / BK;
;     Order S; S.init(M, N, (int)gridDim.x, obid());
;     unsigned voffA[2], voffB[2];
; #pragma unroll
;     for (int i = 0; i < 2; ++i) { int R, C; stage_rc(tid * 16 + i * 8192, R, C); const int Rb = Epi::PERM ? ((R & ~31) + perm32(R & 31)) : R;
;         voffA[i] = (unsigned)(R * lda + C) * 2u; voffB[i] = (unsigned)(Rb * ldb + C) * 2u; }
;     const size_t kstep = (size_t)(BK * 2);
;     const size_t hstepA = (size_t)HALF * lda * 2, hstepB = (size_t)HALF * ldb * 2;
;     const size_t tstepA = 2 * hstepA, tstepB = 2 * hstepB;
;     const unsigned ldsw = (unsigned)wid * 1024u;
;     const int aoff = lds_byte(wr * 64 + fr, fq * 8), boff = lds_byte(wc * 32 + fr, fq * 8);
;     ...
;     Unit cur, nxt; int ui = 0;
;     if (!S.next(0, cur)) return;
;     f32x4 acc[2][2][4][2];
; #pragma unroll
;     for (int a = 0; a < 2; ++a)
; #pragma unroll
;         for (int b = 0; b < 2; ++b)
; #pragma unroll
;             for (int m = 0; m < 4; ++m)
; #pragma unroll
;                 for (int n = 0; n < 2; ++n) acc[a][b][m][n] = (f32x4){0.f, 0.f, 0.f, 0.f};
;     h16x8 At[4][2], B0[2][2], B1[2][2];
;     const char* cA = am(cur.pn) + (size_t)cur.pm * tstepA; const char* cB = (const char*)Bt + (size_t)cur.pn * tstepB;
;     PG8_STAGE(PG8_SB(0, 0), cB, voffB); PG8_STAGE(PG8_SA(0, 0), cA, voffA); PG8_STAGE(PG8_SB(0, 1), cB + hstepB, voffB); PG8_STAGE(PG8_SA(0, 1), cA + hstepA, voffA);
;     if (wr == 1) PG8_BAR;
;     PG8_WAIT_V(4); PG8_BAR;
;     PG8_STAGE(PG8_SB(1, 0), cB + kstep, voffB); PG8_STAGE(PG8_SA(1, 0), cA + kstep, voffA); PG8_STAGE(PG8_SB(1, 1), cB + hstepB + kstep, voffB);
;     PG8_WAIT_V(6); PG8_BAR;
.LBB0_653:
	v_ashrrev_i32_e32 v0, 31, v18
	v_lshrrev_b32_e32 v0, 26, v0
	v_add_u32_e32 v0, v18, v0
	v_ashrrev_i32_e32 v10, 6, v0
	v_bfe_i32 v0, v18, 27, 1
	s_waitcnt vmcnt(0)
	v_lshlrev_b32_e32 v2, 4, v18
	v_lshrrev_b32_e32 v0, 22, v0
	v_add_u32_e32 v0, v2, v0
	v_and_b32_e32 v0, 0xfffffc00, v0
	v_sub_u32_e32 v0, v2, v0
	v_lshrrev_b32_e32 v3, 4, v0
	v_bitop3_b32 v3, v3, v0, 32 bitop3:0x6c
	v_ashrrev_i32_e32 v0, 31, v0
	v_lshrrev_b32_e32 v0, 26, v0
	v_lshlrev_b32_e32 v4, 3, v10
	v_add_u32_e32 v0, v3, v0
	v_and_b32_e32 v4, -16, v4
	v_ashrrev_i32_e32 v12, 6, v0
	v_add_u32_e32 v0, v12, v4
	v_lshlrev_b32_e32 v4, 5, v10
	v_and_b32_e32 v11, 32, v4
	v_mul_i32_i24_e32 v4, 64, v12
	s_ashr_i32 s1, s50, 6
	v_sub_u32_e32 v3, v3, v4
	v_mov_b32_e32 v7, 1
	v_ashrrev_i16_sdwa v3, v7, sext(v3) dst_sel:DWORD dst_unused:UNUSED_PAD src0_sel:DWORD src1_sel:BYTE_0
	s_ashr_i32 s20, s50, 8
	s_lshl_b32 s62, s1, 10
	v_bfe_i32 v13, v3, 0, 16
	v_and_b32_e32 v6, 3, v12
	s_mov_b32 s6, 0x7fffe0
	s_movk_i32 s4, 0x1c00
	s_add_u32 s63, s10, 0x1e00000
	v_add_u32_e32 v3, v11, v13
	v_lshlrev_b32_e32 v4, 1, v0
	v_lshrrev_b32_e32 v5, 2, v0
	v_and_or_b32 v6, v0, s6, v6
	v_mul_lo_u32 v0, v0, s4
	v_add_u32_e32 v2, 0x2000, v2
	s_addc_u32 s64, s11, 0
	s_add_i32 s0, s21, s0
	v_add_lshl_u32 v130, v3, v0, 1
	v_lshlrev_b32_e32 v0, 1, v3
	v_ashrrev_i32_e32 v3, 31, v2
	s_ashr_i32 s21, s0, 31
	v_lshrrev_b32_e32 v3, 22, v3
	s_lshr_b32 s21, s21, 27
	v_add_u32_e32 v3, v2, v3
	s_add_i32 s21, s0, s21
	v_ashrrev_i32_e32 v14, 10, v3
	s_ashr_i32 s22, s21, 5
	s_and_b32 s21, s21, 0xffe0
	v_mul_i32_i24_e32 v3, 0x400, v14
	s_sub_i32 s21, s0, s21
	v_sub_u32_e32 v2, v2, v3
	s_bfe_i32 s0, s21, 0x80000
	v_and_b32_e32 v4, 24, v4
	v_and_b32_e32 v5, 4, v5
	v_lshrrev_b32_e32 v3, 4, v2
	s_bfe_u32 s0, s0, 0x2000d
	v_or3_b32 v4, v6, v5, v4
	v_bitop3_b32 v2, v3, v2, 32 bitop3:0x6c
	s_add_i32 s23, s21, s0
	v_lshl_add_u32 v0, v4, 9, v0
	v_ashrrev_i32_e32 v4, 31, v2
	s_bfe_i32 s0, s23, 0x80000
	s_and_b32 s23, s23, 0xfc
	v_lshrrev_b32_e32 v4, 26, v4
	s_sext_i32_i16 s0, s0
	s_sub_i32 s21, s21, s23
	v_add_u32_e32 v4, v2, v4
	s_lshl_b32 s22, s22, 2
	s_lshr_b32 s0, s0, 2
	s_sext_i32_i8 s21, s21
	v_lshlrev_b32_e32 v3, 3, v14
	v_ashrrev_i32_e32 v16, 6, v4
	v_and_b32_e32 v4, 0xc0, v4
	s_add_i32 s74, s22, s21
	s_bfe_i64 s[22:23], s[0:1], 0x100000
	v_and_b32_e32 v3, -16, v3
	v_sub_u32_e32 v2, v2, v4
	s_lshl_b64 s[22:23], s[22:23], 17
	v_add_u32_e32 v3, v16, v3
	v_lshlrev_b32_e32 v5, 5, v14
	v_ashrrev_i16_sdwa v2, v7, sext(v2) dst_sel:DWORD dst_unused:UNUSED_PAD src0_sel:DWORD src1_sel:BYTE_0
	s_add_u32 s46, s63, s22
	v_and_b32_e32 v15, 32, v5
	v_bfe_i32 v17, v2, 0, 16
	v_lshlrev_b32_e32 v4, 1, v3
	v_lshrrev_b32_e32 v5, 2, v3
	v_and_b32_e32 v6, 3, v16
	s_addc_u32 s47, s64, s23
	s_add_i32 s65, s62, 0
	v_add_u32_e32 v2, v15, v17
	v_and_b32_e32 v4, 24, v4
	v_and_b32_e32 v5, 4, v5
	v_and_or_b32 v6, v3, s6, v6
	v_mul_lo_u32 v3, v3, s4
	s_add_i32 m0, s65, 0x10000
	v_or3_b32 v4, v6, v5, v4
	v_add_lshl_u32 v132, v2, v3, 1
	v_lshlrev_b32_e32 v2, 1, v2
	s_mul_i32 s26, s74, 0x380000
	global_load_lds_dwordx4 v0, s[46:47]
	s_add_i32 m0, s65, 0x12000
	v_lshl_add_u32 v134, v4, 9, v2
	s_mul_hi_i32 s21, s74, 0x380000
	s_add_u32 s44, s67, s26
	global_load_lds_dwordx4 v134, s[46:47]
	s_addc_u32 s45, s89, s21
	s_mov_b32 m0, s65
	s_add_i32 s68, s65, 0x2000
	global_load_lds_dwordx4 v130, s[44:45]
	s_mov_b32 m0, s68
	s_add_u32 s22, s46, 0x10000
	global_load_lds_dwordx4 v132, s[44:45]
	s_addc_u32 s23, s47, 0
	s_add_i32 m0, s65, 0x14000
	v_mov_b32_e32 v135, v1
	global_load_lds_dwordx4 v0, s[22:23]
	s_add_i32 m0, s65, 0x16000
	v_mov_b32_e32 v131, v1
	global_load_lds_dwordx4 v134, s[22:23]
	s_add_u32 s22, s44, 0x1c0000
	s_addc_u32 s23, s45, 0
	s_add_i32 s69, s65, 0x4000
	s_mov_b32 m0, s69
	s_add_i32 s70, s65, 0x6000
	global_load_lds_dwordx4 v130, s[22:23]
	s_mov_b32 m0, s70
	v_mov_b32_e32 v133, v1
	global_load_lds_dwordx4 v132, s[22:23]
	v_lshl_add_u64 v[8:9], s[46:47], 0, v[0:1]
	v_lshl_add_u64 v[6:7], s[46:47], 0, v[134:135]
	v_lshl_add_u64 v[4:5], s[44:45], 0, v[130:131]
	s_cmp_lg_u32 s20, 1
	v_lshl_add_u64 v[2:3], s[44:45], 0, v[132:133]
	s_cbranch_scc1 .LBB0_655
.LBB0_655:
	v_lshrrev_b32_e32 v20, 1, v18
	v_and_b32_e32 v20, 24, v20
	v_and_b32_e32 v19, 15, v18
	v_lshlrev_b32_e32 v21, 1, v20
	v_lshlrev_b32_e32 v18, 2, v18
	s_sext_i32_i8 s76, s0
	v_lshl_or_b32 v160, s20, 6, v19
	v_lshl_or_b32 v19, v19, 6, v21
	s_lshl_b32 s0, s20, 13
	v_and_b32_e32 v18, 32, v18
	v_bitop3_b32 v21, v19, s0, v18 bitop3:0xde
	s_lshl_b32 s0, s1, 5
	s_and_b32 s20, s0, 0x60
	s_add_i32 m0, s65, 0x18000
	v_lshl_add_u64 v[8:9], v[8:9], 0, s[92:93]
	s_lshl_b32 s0, s20, 7
	s_waitcnt vmcnt(0)
	s_barrier
	global_load_lds_dwordx4 v[8:9], off
	v_lshl_add_u64 v[6:7], v[6:7], 0, s[92:93]
	s_add_i32 m0, s65, 0x1a000
	s_add_i32 s71, s65, 0x8000
	s_add_i32 s72, s65, 0xa000
	v_bitop3_b32 v161, v19, s0, v18 bitop3:0xde
	global_load_lds_dwordx4 v[6:7], off
	v_lshl_add_u64 v[4:5], v[4:5], 0, s[92:93]
	s_mov_b32 m0, s71
	s_add_u32 s0, s46, 0x10080
	global_load_lds_dwordx4 v[4:5], off
	v_lshl_add_u64 v[2:3], v[2:3], 0, s[92:93]
	s_mov_b32 m0, s72
	s_addc_u32 s1, s47, 0
	global_load_lds_dwordx4 v[2:3], off
	s_add_i32 m0, s65, 0x1c000
	v_lshl_add_u64 v[2:3], s[0:1], 0, v[0:1]
	global_load_lds_dwordx4 v[2:3], off
	v_lshl_add_u64 v[2:3], s[0:1], 0, v[134:135]
	s_add_i32 m0, s65, 0x1e000
	s_movk_i32 s6, 0x1c00
	global_load_lds_dwordx4 v[2:3], off
	v_lshrrev_b32_e32 v3, 1, v10
	v_mul_lo_u32 v2, v12, s6
	s_mov_b32 s4, 0x1c000
	v_mad_u64_u32 v[2:3], s[0:1], v3, s4, v[2:3]
	v_or_b32_e32 v2, v2, v11
	v_or_b32_e32 v162, s20, v20
	v_add_lshl_u32 v2, v2, v13, 1
	v_mov_b32_e32 v3, v1
	s_mov_b64 s[20:21], 0x1c0080
	v_lshl_add_u64 v[136:137], v[2:3], 0, s[20:21]
	v_lshrrev_b32_e32 v3, 1, v14
	v_mul_lo_u32 v2, v16, s6
	v_mad_u64_u32 v[2:3], s[0:1], v3, s4, v[2:3]
	s_waitcnt vmcnt(6)
	v_or_b32_e32 v2, v2, v15
	s_cmp_gt_i32 s61, 63
	v_add_lshl_u32 v2, v2, v17, 1
	v_mov_b32_e32 v3, v1
	s_cselect_b64 s[22:23], -1, 0
	s_add_i32 s73, s24, -2
	v_lshl_add_u64 v[138:139], v[2:3], 0, s[20:21]
	s_mov_b32 s75, 0
	v_add_u32_e32 v163, 0, v21
	s_barrier
	s_branch .LBB0_657

; template <class Epi, class AMap>
; __device__ __forceinline__ void gemm_phase(LAS unsigned char* lds, const AMap am, const int lda, const h16* Bt, const int ldb, const int M, const int N, const int K, const Epi& E) {
;     ...
;         const bool has_next = S.next(ui + 1, nxt);
;         const char* nA = has_next ? am(nxt.pn) + (size_t)nxt.pm * tstepA : cA; const char* nB = has_next ? (const char*)Bt + (size_t)nxt.pn * tstepB : cB;
; #pragma unroll 1
;         for (int t = 0; t < nt; t += 2) {
;             const bool last = (t == nt - 2);
;             const char* a1 = cA + (size_t)(t + 1) * kstep;
;             const char* a2 = last ? nA : cA + (size_t)(t + 2) * kstep; const char* b2 = last ? nB : cB + (size_t)(t + 2) * kstep;
;             const char* a3 = a2 + kstep; const char* b3 = b2 + kstep;
;     ...
; #pragma unroll
;         for (int a = 0; a < 2; ++a)
; #pragma unroll
;             for (int b = 0; b < 2; ++b)
; #pragma unroll
;                 for (int m = 0; m < 4; ++m)
; #pragma unroll
;                     for (int n = 0; n < 2; ++n) acc[a][b][m][n] = (f32x4){0.f, 0.f, 0.f, 0.f};
;         cur = nxt; cA = nA; cB = nB; ++ui;
.LBB0_665:
	s_ashr_i32 s27, s26, 31
	s_lshl_b64 s[20:21], s[26:27], 17
	s_add_u32 s42, s63, s20
	s_addc_u32 s43, s64, s21
	v_mov_b32_e32 v129, 0
	s_andn2_b64 vcc, exec, s[22:23]
	v_mov_b32_e32 v128, 0
	v_mov_b32_e32 v127, 0
	v_mov_b32_e32 v126, 0
	v_mov_b32_e32 v125, 0
	v_mov_b32_e32 v124, 0
	v_mov_b32_e32 v123, 0
	v_mov_b32_e32 v122, 0
	v_mov_b32_e32 v121, 0
	v_mov_b32_e32 v120, 0
	v_mov_b32_e32 v119, 0
	v_mov_b32_e32 v118, 0
	v_mov_b32_e32 v117, 0
	v_mov_b32_e32 v116, 0
	v_mov_b32_e32 v115, 0
	v_mov_b32_e32 v114, 0
	v_mov_b32_e32 v113, 0
	v_mov_b32_e32 v112, 0
	v_mov_b32_e32 v111, 0
	v_mov_b32_e32 v110, 0
	v_mov_b32_e32 v109, 0
	v_mov_b32_e32 v108, 0
	v_mov_b32_e32 v107, 0
	v_mov_b32_e32 v106, 0
	v_mov_b32_e32 v105, 0
	v_mov_b32_e32 v104, 0
	v_mov_b32_e32 v103, 0
	v_mov_b32_e32 v102, 0
	v_mov_b32_e32 v101, 0
	v_mov_b32_e32 v100, 0
	v_mov_b32_e32 v99, 0
	v_mov_b32_e32 v98, 0
	v_mov_b32_e32 v35, 0
	v_mov_b32_e32 v34, 0
	v_mov_b32_e32 v37, 0
	v_mov_b32_e32 v36, 0
	v_mov_b32_e32 v51, 0
	v_mov_b32_e32 v50, 0
	v_mov_b32_e32 v53, 0
	v_mov_b32_e32 v52, 0
	v_mov_b32_e32 v43, 0
	v_mov_b32_e32 v42, 0
	v_mov_b32_e32 v45, 0
	v_mov_b32_e32 v44, 0
	v_mov_b32_e32 v67, 0
	v_mov_b32_e32 v66, 0
	v_mov_b32_e32 v69, 0
	v_mov_b32_e32 v68, 0
	v_mov_b32_e32 v59, 0
	v_mov_b32_e32 v58, 0
	v_mov_b32_e32 v61, 0
	v_mov_b32_e32 v60, 0
	v_mov_b32_e32 v57, 0
	v_mov_b32_e32 v56, 0
	v_mov_b32_e32 v55, 0
	v_mov_b32_e32 v54, 0
	v_mov_b32_e32 v49, 0
	v_mov_b32_e32 v48, 0
	v_mov_b32_e32 v47, 0
	v_mov_b32_e32 v46, 0
	v_mov_b32_e32 v41, 0
	v_mov_b32_e32 v40, 0
	v_mov_b32_e32 v39, 0
	v_mov_b32_e32 v38, 0
	v_mov_b32_e32 v93, 0
	v_mov_b32_e32 v92, 0
	v_mov_b32_e32 v91, 0
	v_mov_b32_e32 v90, 0
	v_mov_b32_e32 v145, 0
	v_mov_b32_e32 v144, 0
	v_mov_b32_e32 v153, 0
	v_mov_b32_e32 v152, 0
	v_mov_b32_e32 v77, 0
	v_mov_b32_e32 v76, 0
	v_mov_b32_e32 v85, 0
	v_mov_b32_e32 v84, 0
	v_mov_b32_e32 v147, 0
	v_mov_b32_e32 v146, 0
	v_mov_b32_e32 v155, 0
	v_mov_b32_e32 v154, 0
	v_mov_b32_e32 v75, 0
	v_mov_b32_e32 v74, 0
	v_mov_b32_e32 v141, 0
	v_mov_b32_e32 v140, 0
	v_mov_b32_e32 v149, 0
	v_mov_b32_e32 v148, 0
	v_mov_b32_e32 v157, 0
	v_mov_b32_e32 v156, 0
	v_mov_b32_e32 v83, 0
	v_mov_b32_e32 v82, 0
	v_mov_b32_e32 v143, 0
	v_mov_b32_e32 v142, 0
	v_mov_b32_e32 v151, 0
	v_mov_b32_e32 v150, 0
	v_mov_b32_e32 v159, 0
	v_mov_b32_e32 v158, 0
	v_mov_b32_e32 v33, 0
	v_mov_b32_e32 v32, 0
	v_mov_b32_e32 v31, 0
	v_mov_b32_e32 v30, 0
	v_mov_b32_e32 v29, 0
	v_mov_b32_e32 v28, 0
	v_mov_b32_e32 v27, 0
	v_mov_b32_e32 v26, 0
	v_mov_b32_e32 v25, 0
	v_mov_b32_e32 v24, 0
	v_mov_b32_e32 v23, 0
	v_mov_b32_e32 v22, 0
	v_mov_b32_e32 v21, 0
	v_mov_b32_e32 v20, 0
	v_mov_b32_e32 v19, 0
	v_mov_b32_e32 v18, 0
	v_mov_b32_e32 v17, 0
	v_mov_b32_e32 v16, 0
	v_mov_b32_e32 v15, 0
	v_mov_b32_e32 v14, 0
	v_mov_b32_e32 v13, 0
	v_mov_b32_e32 v12, 0
	v_mov_b32_e32 v11, 0
	v_mov_b32_e32 v10, 0
	v_mov_b32_e32 v9, 0
	v_mov_b32_e32 v8, 0
	v_mov_b32_e32 v7, 0
	v_mov_b32_e32 v6, 0
	v_mov_b32_e32 v5, 0
	v_mov_b32_e32 v4, 0
	v_mov_b32_e32 v3, 0
	v_mov_b32_e32 v2, 0
	s_cbranch_vccnz .LBB0_656
	s_and_b64 s[0:1], s[0:1], exec
	s_cselect_b32 s20, s43, s47
	s_cselect_b32 s21, s42, s46
	s_add_u32 s27, s46, 0x100
	v_mov_b32_e32 v2, 0
	s_addc_u32 s29, s47, 0
	s_mov_b32 s46, 0
	v_mov_b32_e32 v3, v2
	v_mov_b32_e32 v4, v2
	v_mov_b32_e32 v5, v2
	v_mov_b32_e32 v6, v2
	v_mov_b32_e32 v7, v2
	v_mov_b32_e32 v8, v2
	v_mov_b32_e32 v9, v2
	v_mov_b32_e32 v10, v2
	v_mov_b32_e32 v11, v2
	v_mov_b32_e32 v12, v2
	v_mov_b32_e32 v13, v2
	v_mov_b32_e32 v14, v2
	v_mov_b32_e32 v15, v2
	v_mov_b32_e32 v16, v2
	v_mov_b32_e32 v17, v2
	v_mov_b32_e32 v18, v2
	v_mov_b32_e32 v19, v2
	v_mov_b32_e32 v20, v2
	v_mov_b32_e32 v21, v2
	v_mov_b32_e32 v22, v2
	v_mov_b32_e32 v23, v2
	v_mov_b32_e32 v24, v2
	v_mov_b32_e32 v25, v2
	v_mov_b32_e32 v26, v2
	v_mov_b32_e32 v27, v2
	v_mov_b32_e32 v28, v2
	v_mov_b32_e32 v29, v2
	v_mov_b32_e32 v30, v2
	v_mov_b32_e32 v31, v2
	v_mov_b32_e32 v32, v2
	v_mov_b32_e32 v33, v2
	v_mov_b32_e32 v34, v2
	v_mov_b32_e32 v35, v2
	v_mov_b32_e32 v36, v2
	v_mov_b32_e32 v37, v2
	v_mov_b32_e32 v42, v2
	v_mov_b32_e32 v43, v2
	v_mov_b32_e32 v44, v2
	v_mov_b32_e32 v45, v2
	v_mov_b32_e32 v50, v2
	v_mov_b32_e32 v51, v2
	v_mov_b32_e32 v52, v2
	v_mov_b32_e32 v53, v2
	v_mov_b32_e32 v58, v2
	v_mov_b32_e32 v59, v2
	v_mov_b32_e32 v60, v2
	v_mov_b32_e32 v61, v2
	v_mov_b32_e32 v66, v2
	v_mov_b32_e32 v67, v2
	v_mov_b32_e32 v68, v2
	v_mov_b32_e32 v69, v2
	v_mov_b32_e32 v74, v2
	v_mov_b32_e32 v75, v2
	v_mov_b32_e32 v76, v2
	v_mov_b32_e32 v77, v2
	v_mov_b32_e32 v82, v2
	v_mov_b32_e32 v83, v2
	v_mov_b32_e32 v84, v2
	v_mov_b32_e32 v85, v2
	v_mov_b32_e32 v90, v2
	v_mov_b32_e32 v91, v2
	v_mov_b32_e32 v92, v2
	v_mov_b32_e32 v93, v2
	v_mov_b32_e32 v38, v2
	v_mov_b32_e32 v39, v2
	v_mov_b32_e32 v40, v2
	v_mov_b32_e32 v41, v2
	v_mov_b32_e32 v46, v2
	v_mov_b32_e32 v47, v2
	v_mov_b32_e32 v48, v2
	v_mov_b32_e32 v49, v2
	v_mov_b32_e32 v54, v2
	v_mov_b32_e32 v55, v2
	v_mov_b32_e32 v56, v2
	v_mov_b32_e32 v57, v2
	v_mov_b32_e32 v62, v2
	v_mov_b32_e32 v63, v2
	v_mov_b32_e32 v64, v2
	v_mov_b32_e32 v65, v2
	v_mov_b32_e32 v70, v2
	v_mov_b32_e32 v71, v2
	v_mov_b32_e32 v72, v2
	v_mov_b32_e32 v73, v2
	v_mov_b32_e32 v78, v2
	v_mov_b32_e32 v79, v2
	v_mov_b32_e32 v80, v2
	v_mov_b32_e32 v81, v2
	v_mov_b32_e32 v86, v2
	v_mov_b32_e32 v87, v2
	v_mov_b32_e32 v88, v2
	v_mov_b32_e32 v89, v2
	v_mov_b32_e32 v94, v2
	v_mov_b32_e32 v95, v2
	v_mov_b32_e32 v96, v2
	v_mov_b32_e32 v97, v2
	v_mov_b32_e32 v98, v2
	v_mov_b32_e32 v99, v2
	v_mov_b32_e32 v100, v2
	v_mov_b32_e32 v101, v2
	v_mov_b32_e32 v102, v2
	v_mov_b32_e32 v103, v2
	v_mov_b32_e32 v104, v2
	v_mov_b32_e32 v105, v2
	v_mov_b32_e32 v106, v2
	v_mov_b32_e32 v107, v2
	v_mov_b32_e32 v108, v2
	v_mov_b32_e32 v109, v2
	v_mov_b32_e32 v110, v2
	v_mov_b32_e32 v111, v2
	v_mov_b32_e32 v112, v2
	v_mov_b32_e32 v113, v2
	v_mov_b32_e32 v114, v2
	v_mov_b32_e32 v115, v2
	v_mov_b32_e32 v116, v2
	v_mov_b32_e32 v117, v2
	v_mov_b32_e32 v118, v2
	v_mov_b32_e32 v119, v2
	v_mov_b32_e32 v120, v2
	v_mov_b32_e32 v121, v2
	v_mov_b32_e32 v122, v2
	v_mov_b32_e32 v123, v2
	v_mov_b32_e32 v124, v2
	v_mov_b32_e32 v125, v2
	v_mov_b32_e32 v126, v2
	v_mov_b32_e32 v127, v2
	v_mov_b32_e32 v128, v2
	v_mov_b32_e32 v129, v2
	s_cmpk_lt_u32 s50, 0x100
	s_cbranch_scc1 .Lgy6
	s_barrier
; #define PG8_STAGE(bufoff, gbase, voff) do { _Pragma("unroll") for (int _i = 0; _i < 2; ++_i) \
;         __builtin_amdgcn_global_load_lds((const unsigned*)((const char*)(gbase) + (voff)[_i]), (LAS unsigned*)(lds + (bufoff) + ldsw + _i * 8192), 16, 0, 0); } while (0)
; #define PG8_LDA(dst, b, h) do { _Pragma("unroll") for (int m = 0; m < 4; ++m) _Pragma("unroll") for (int k = 0; k < 2; ++k) dst[m][k] = *(const LAS h16x8*)(lds + PG8_SA(b, h) + aoff + m * 2048 + k * 1024); } while (0)
; #define PG8_LDB(dst, b, h) do { _Pragma("unroll") for (int n = 0; n < 2; ++n) _Pragma("unroll") for (int k = 0; k < 2; ++k) dst[n][k] = *(const LAS h16x8*)(lds + PG8_SB(b, h) + boff + n * 2048 + k * 1024); } while (0)
; #define PG8_MMA(ai, bj, At, Bt_) do { __builtin_amdgcn_s_setprio(1); _Pragma("unroll") for (int m = 0; m < 4; ++m) _Pragma("unroll") for (int n = 0; n < 2; ++n) _Pragma("unroll") for (int k = 0; k < 2; ++k) \
;         acc[ai][bj][m][n] = __builtin_amdgcn_mfma_f32_16x16x32_f16(Bt_[n][k], At[m][k], acc[ai][bj][m][n], 0, 0, 0); __builtin_amdgcn_s_setprio(0); } while (0)
; #define PG8_WAIT_V(n) asm volatile("s_waitcnt vmcnt(" #n ")" ::: "memory")
; #define PG8_WAIT_L(n) asm volatile("s_waitcnt lgkmcnt(" #n ")" ::: "memory")
; #define PG8_BAR __builtin_amdgcn_s_barrier()
; #define PG8_SCHED __builtin_amdgcn_sched_barrier(0)
; template <class Epi, class AMap>
; __device__ __forceinline__ void gemm_phase(LAS unsigned char* lds, const AMap am, const int lda, const h16* Bt, const int ldb, const int M, const int N, const int K, const Epi& E) {
;     ...
;             PG8_LDB(B0, 0, 0); PG8_SCHED; PG8_LDA(At, 0, 0); PG8_STAGE(PG8_SA(1, 1), a1 + hstepA, voffA);
;             PG8_WAIT_L(8); PG8_BAR; PG8_WAIT_L(0); PG8_MMA(0, 0, At, B0); PG8_BAR; PG8_SCHED;
;             PG8_LDB(B1, 0, 1); PG8_STAGE(PG8_SB(0, 0), b2, voffB);
;             PG8_BAR; PG8_WAIT_L(0); PG8_MMA(0, 1, At, B1); PG8_BAR;
;             PG8_LDA(At, 0, 1); PG8_STAGE(PG8_SA(0, 0), a2, voffA);
;             PG8_BAR; PG8_WAIT_L(0); PG8_MMA(1, 0, At, B0); PG8_BAR; PG8_SCHED;
;             PG8_STAGE(PG8_SB(0, 1), b2 + hstepB, voffB);
;             PG8_WAIT_V(6); PG8_BAR; PG8_MMA(1, 1, At, B1); PG8_BAR;
.Lgy6:
.LBB0_667:
	s_add_i32 s60, s46, 2
	s_add_u32 s0, s44, 0x100
	s_addc_u32 s1, s45, 0
	s_add_i32 s66, 0, 0x10000
	v_add_u32_e32 v234, s66, v161
	ds_read_b128 v[140:143], v234
	ds_read_b128 v[144:147], v234 offset:1024
	ds_read_b128 v[148:151], v234 offset:2048
	ds_read_b128 v[152:155], v234 offset:3072
	s_cmp_eq_u32 s73, s46
	s_cselect_b32 s46, s21, s27
	s_cselect_b32 s49, s41, s1
	s_cselect_b32 s48, s40, s0
	s_cselect_b32 s47, s20, s29
	v_lshl_add_u64 v[232:233], s[44:45], 0, v[136:137]
	s_add_i32 m0, s65, 0xc000
	ds_read_b128 v[156:159], v163
	ds_read_b128 v[164:167], v163 offset:1024
	ds_read_b128 v[168:171], v163 offset:2048
	ds_read_b128 v[172:175], v163 offset:3072
	ds_read_b128 v[176:179], v163 offset:4096
	ds_read_b128 v[180:183], v163 offset:5120
	ds_read_b128 v[184:187], v163 offset:6144
	ds_read_b128 v[188:191], v163 offset:7168
	global_load_lds_dwordx4 v[232:233], off
	v_lshl_add_u64 v[232:233], s[44:45], 0, v[138:139]
	s_add_i32 m0, s65, 0xe000
	s_nop 0
	global_load_lds_dwordx4 v[232:233], off
	s_waitcnt lgkmcnt(11)
	s_add_i32 s78, 0, 0x14000
	s_add_i32 s44, s66, s62
	v_add_u32_e32 v234, s78, v161
	v_lshl_add_u64 v[212:213], s[46:47], 0, v[0:1]
	s_mov_b32 m0, s44
	ds_read_b128 v[192:195], v234
	ds_read_b128 v[196:199], v234 offset:1024
	ds_read_b128 v[200:203], v234 offset:2048
	ds_read_b128 v[204:207], v234 offset:3072
	s_waitcnt vmcnt(8) lgkmcnt(0)
	s_barrier
	v_mfma_f32_16x16x32_f16 v[126:129], v[140:143], v[156:159], v[126:129]
	v_mfma_f32_16x16x32_f16 v[122:125], v[148:151], v[156:159], v[122:125]
	v_mfma_f32_16x16x32_f16 v[118:121], v[140:143], v[168:171], v[118:121]
	v_mfma_f32_16x16x32_f16 v[114:117], v[148:151], v[168:171], v[114:117]
	v_mfma_f32_16x16x32_f16 v[110:113], v[140:143], v[176:179], v[110:113]
	v_mfma_f32_16x16x32_f16 v[106:109], v[148:151], v[176:179], v[106:109]
	v_mfma_f32_16x16x32_f16 v[102:105], v[140:143], v[184:187], v[102:105]
	v_mfma_f32_16x16x32_f16 v[98:101], v[148:151], v[184:187], v[98:101]
	v_mfma_f32_16x16x32_f16 v[126:129], v[144:147], v[164:167], v[126:129]
	v_mfma_f32_16x16x32_f16 v[122:125], v[152:155], v[164:167], v[122:125]
	v_mfma_f32_16x16x32_f16 v[118:121], v[144:147], v[172:175], v[118:121]
	v_mfma_f32_16x16x32_f16 v[114:117], v[152:155], v[172:175], v[114:117]
	v_mfma_f32_16x16x32_f16 v[110:113], v[144:147], v[180:183], v[110:113]
	v_mfma_f32_16x16x32_f16 v[106:109], v[152:155], v[180:183], v[106:109]
	v_mfma_f32_16x16x32_f16 v[102:105], v[144:147], v[188:191], v[102:105]
	v_mfma_f32_16x16x32_f16 v[98:101], v[152:155], v[188:191], v[98:101]
	v_mfma_f32_16x16x32_f16 v[94:97], v[192:195], v[156:159], v[94:97]
	v_mfma_f32_16x16x32_f16 v[86:89], v[200:203], v[156:159], v[86:89]
	v_mfma_f32_16x16x32_f16 v[78:81], v[192:195], v[168:171], v[78:81]
	v_mfma_f32_16x16x32_f16 v[70:73], v[200:203], v[168:171], v[70:73]
	v_mfma_f32_16x16x32_f16 v[62:65], v[192:195], v[176:179], v[62:65]
	v_mfma_f32_16x16x32_f16 v[54:57], v[200:203], v[176:179], v[54:57]
	v_mfma_f32_16x16x32_f16 v[46:49], v[192:195], v[184:187], v[46:49]
	v_mfma_f32_16x16x32_f16 v[38:41], v[200:203], v[184:187], v[38:41]
	v_mfma_f32_16x16x32_f16 v[94:97], v[196:199], v[164:167], v[94:97]
	v_mfma_f32_16x16x32_f16 v[86:89], v[204:207], v[164:167], v[86:89]
	v_mfma_f32_16x16x32_f16 v[78:81], v[196:199], v[172:175], v[78:81]
	v_mfma_f32_16x16x32_f16 v[70:73], v[204:207], v[172:175], v[70:73]
	v_mfma_f32_16x16x32_f16 v[62:65], v[196:199], v[180:183], v[62:65]
	v_mfma_f32_16x16x32_f16 v[54:57], v[204:207], v[180:183], v[54:57]
	v_mfma_f32_16x16x32_f16 v[46:49], v[196:199], v[188:191], v[46:49]
	v_mfma_f32_16x16x32_f16 v[38:41], v[204:207], v[188:191], v[38:41]
	s_barrier
	global_load_lds_dwordx4 v[212:213], off
	v_lshl_add_u64 v[220:221], s[46:47], 0, v[134:135]
	s_add_i32 m0, s44, 0x2000
	s_nop 0
	global_load_lds_dwordx4 v[220:221], off
	s_mov_b32 m0, s65
	v_lshl_add_u64 v[222:223], s[48:49], 0, v[130:131]
	ds_read_b128 v[156:159], v163 offset:16384
	ds_read_b128 v[164:167], v163 offset:17408
	ds_read_b128 v[168:171], v163 offset:18432
	ds_read_b128 v[172:175], v163 offset:19456
	ds_read_b128 v[176:179], v163 offset:20480
	ds_read_b128 v[180:183], v163 offset:21504
	ds_read_b128 v[184:187], v163 offset:22528
	ds_read_b128 v[188:191], v163 offset:23552
	global_load_lds_dwordx4 v[222:223], off
	v_lshl_add_u64 v[224:225], s[48:49], 0, v[132:133]
	s_mov_b32 m0, s68
	s_nop 0
	global_load_lds_dwordx4 v[224:225], off
	s_add_u32 s44, s46, 0x10000
	s_addc_u32 s45, s47, 0
	s_add_i32 s66, s78, s62
	v_lshl_add_u64 v[232:233], s[44:45], 0, v[0:1]
	s_mov_b32 m0, s66
	s_nop 0
	global_load_lds_dwordx4 v[232:233], off
	v_lshl_add_u64 v[232:233], s[44:45], 0, v[134:135]
	s_add_i32 m0, s66, 0x2000
	s_nop 0
	global_load_lds_dwordx4 v[232:233], off
	s_waitcnt vmcnt(8) lgkmcnt(0)
	s_barrier
; #define PG8_STAGE(bufoff, gbase, voff) do { _Pragma("unroll") for (int _i = 0; _i < 2; ++_i) \
;         __builtin_amdgcn_global_load_lds((const unsigned*)((const char*)(gbase) + (voff)[_i]), (LAS unsigned*)(lds + (bufoff) + ldsw + _i * 8192), 16, 0, 0); } while (0)
; #define PG8_LDA(dst, b, h) do { _Pragma("unroll") for (int m = 0; m < 4; ++m) _Pragma("unroll") for (int k = 0; k < 2; ++k) dst[m][k] = *(const LAS h16x8*)(lds + PG8_SA(b, h) + aoff + m * 2048 + k * 1024); } while (0)
; #define PG8_LDB(dst, b, h) do { _Pragma("unroll") for (int n = 0; n < 2; ++n) _Pragma("unroll") for (int k = 0; k < 2; ++k) dst[n][k] = *(const LAS h16x8*)(lds + PG8_SB(b, h) + boff + n * 2048 + k * 1024); } while (0)
; #define PG8_MMA(ai, bj, At, Bt_) do { __builtin_amdgcn_s_setprio(1); _Pragma("unroll") for (int m = 0; m < 4; ++m) _Pragma("unroll") for (int n = 0; n < 2; ++n) _Pragma("unroll") for (int k = 0; k < 2; ++k) \
;         acc[ai][bj][m][n] = __builtin_amdgcn_mfma_f32_16x16x32_f16(Bt_[n][k], At[m][k], acc[ai][bj][m][n], 0, 0, 0); __builtin_amdgcn_s_setprio(0); } while (0)
; #define PG8_WAIT_V(n) asm volatile("s_waitcnt vmcnt(" #n ")" ::: "memory")
; #define PG8_WAIT_L(n) asm volatile("s_waitcnt lgkmcnt(" #n ")" ::: "memory")
; #define PG8_BAR __builtin_amdgcn_s_barrier()
; #define PG8_SCHED __builtin_amdgcn_sched_barrier(0)
; template <class Epi, class AMap>
; __device__ __forceinline__ void gemm_phase(LAS unsigned char* lds, const AMap am, const int lda, const h16* Bt, const int ldb, const int M, const int N, const int K, const Epi& E) {
;     ...
;             PG8_WAIT_V(6); PG8_BAR; PG8_MMA(1, 1, At, B1); PG8_BAR;
;             PG8_LDB(B0, 1, 0); PG8_SCHED; PG8_LDA(At, 1, 0); PG8_STAGE(PG8_SA(0, 1), a2 + hstepA, voffA);
;             PG8_WAIT_L(8); PG8_BAR; PG8_WAIT_L(0); PG8_MMA(0, 0, At, B0); PG8_BAR; PG8_SCHED;
;             PG8_LDB(B1, 1, 1); PG8_STAGE(PG8_SB(1, 0), b3, voffB);
;             PG8_BAR; PG8_WAIT_L(0); PG8_MMA(0, 1, At, B1); PG8_BAR;
;             PG8_LDA(At, 1, 1); PG8_STAGE(PG8_SA(1, 0), a3, voffA);
;             PG8_BAR; PG8_WAIT_L(0); PG8_MMA(1, 0, At, B0); PG8_BAR; PG8_SCHED;
	v_mfma_f32_16x16x32_f16 v[90:93], v[140:143], v[156:159], v[90:93]
	v_mfma_f32_16x16x32_f16 v[82:85], v[148:151], v[156:159], v[82:85]
	v_mfma_f32_16x16x32_f16 v[74:77], v[140:143], v[168:171], v[74:77]
	v_mfma_f32_16x16x32_f16 v[66:69], v[148:151], v[168:171], v[66:69]
	v_mfma_f32_16x16x32_f16 v[58:61], v[140:143], v[176:179], v[58:61]
	v_mfma_f32_16x16x32_f16 v[50:53], v[148:151], v[176:179], v[50:53]
	v_mfma_f32_16x16x32_f16 v[42:45], v[140:143], v[184:187], v[42:45]
	v_mfma_f32_16x16x32_f16 v[34:37], v[148:151], v[184:187], v[34:37]
	v_mfma_f32_16x16x32_f16 v[90:93], v[144:147], v[164:167], v[90:93]
	v_mfma_f32_16x16x32_f16 v[82:85], v[152:155], v[164:167], v[82:85]
	v_mfma_f32_16x16x32_f16 v[74:77], v[144:147], v[172:175], v[74:77]
	v_mfma_f32_16x16x32_f16 v[66:69], v[152:155], v[172:175], v[66:69]
	v_mfma_f32_16x16x32_f16 v[58:61], v[144:147], v[180:183], v[58:61]
	v_mfma_f32_16x16x32_f16 v[50:53], v[152:155], v[180:183], v[50:53]
	v_mfma_f32_16x16x32_f16 v[42:45], v[144:147], v[188:191], v[42:45]
	v_mfma_f32_16x16x32_f16 v[34:37], v[152:155], v[188:191], v[34:37]
	v_mfma_f32_16x16x32_f16 v[30:33], v[192:195], v[156:159], v[30:33]
	v_mfma_f32_16x16x32_f16 v[26:29], v[200:203], v[156:159], v[26:29]
	v_mfma_f32_16x16x32_f16 v[22:25], v[192:195], v[168:171], v[22:25]
	v_mfma_f32_16x16x32_f16 v[18:21], v[200:203], v[168:171], v[18:21]
	v_mfma_f32_16x16x32_f16 v[14:17], v[192:195], v[176:179], v[14:17]
	v_mfma_f32_16x16x32_f16 v[10:13], v[200:203], v[176:179], v[10:13]
	v_mfma_f32_16x16x32_f16 v[6:9], v[192:195], v[184:187], v[6:9]
	v_mfma_f32_16x16x32_f16 v[2:5], v[200:203], v[184:187], v[2:5]
	v_mfma_f32_16x16x32_f16 v[30:33], v[196:199], v[164:167], v[30:33]
	v_mfma_f32_16x16x32_f16 v[26:29], v[204:207], v[164:167], v[26:29]
	v_mfma_f32_16x16x32_f16 v[22:25], v[196:199], v[172:175], v[22:25]
	v_mfma_f32_16x16x32_f16 v[18:21], v[204:207], v[172:175], v[18:21]
	v_mfma_f32_16x16x32_f16 v[14:17], v[196:199], v[180:183], v[14:17]
	v_mfma_f32_16x16x32_f16 v[10:13], v[204:207], v[180:183], v[10:13]
	v_mfma_f32_16x16x32_f16 v[6:9], v[196:199], v[188:191], v[6:9]
	v_mfma_f32_16x16x32_f16 v[2:5], v[204:207], v[188:191], v[2:5]
	s_barrier
	s_add_i32 s66, 0, 0x18000
	v_add_u32_e32 v234, s66, v161
	ds_read_b128 v[140:143], v234
	ds_read_b128 v[144:147], v234 offset:1024
	ds_read_b128 v[148:151], v234 offset:2048
	ds_read_b128 v[152:155], v234 offset:3072
	s_add_u32 s44, s48, 0x1c0000
	s_addc_u32 s45, s49, 0
	s_mov_b32 m0, s69
	v_lshl_add_u64 v[232:233], s[44:45], 0, v[130:131]
	ds_read_b128 v[156:159], v163 offset:32768
	ds_read_b128 v[164:167], v163 offset:33792
	ds_read_b128 v[168:171], v163 offset:34816
	ds_read_b128 v[172:175], v163 offset:35840
	ds_read_b128 v[176:179], v163 offset:36864
	ds_read_b128 v[180:183], v163 offset:37888
	ds_read_b128 v[184:187], v163 offset:38912
	ds_read_b128 v[188:191], v163 offset:39936
	global_load_lds_dwordx4 v[232:233], off
	v_lshl_add_u64 v[232:233], s[44:45], 0, v[132:133]
	s_mov_b32 m0, s70
	s_nop 0
	global_load_lds_dwordx4 v[232:233], off
	s_waitcnt lgkmcnt(11)
	s_add_i32 s48, 0, 0x1c000
	s_add_i32 s44, s66, s62
	v_add_u32_e32 v234, s48, v161
	v_lshl_add_u64 v[212:213], v[212:213], 0, s[92:93]
	s_mov_b32 m0, s44
	ds_read_b128 v[192:195], v234
	ds_read_b128 v[196:199], v234 offset:1024
	ds_read_b128 v[200:203], v234 offset:2048
	ds_read_b128 v[204:207], v234 offset:3072
	s_waitcnt vmcnt(8) lgkmcnt(0)
	s_barrier
	v_mfma_f32_16x16x32_f16 v[126:129], v[140:143], v[156:159], v[126:129]
	v_mfma_f32_16x16x32_f16 v[122:125], v[148:151], v[156:159], v[122:125]
	v_mfma_f32_16x16x32_f16 v[118:121], v[140:143], v[168:171], v[118:121]
	v_mfma_f32_16x16x32_f16 v[114:117], v[148:151], v[168:171], v[114:117]
	v_mfma_f32_16x16x32_f16 v[110:113], v[140:143], v[176:179], v[110:113]
	v_mfma_f32_16x16x32_f16 v[106:109], v[148:151], v[176:179], v[106:109]
	v_mfma_f32_16x16x32_f16 v[102:105], v[140:143], v[184:187], v[102:105]
	v_mfma_f32_16x16x32_f16 v[98:101], v[148:151], v[184:187], v[98:101]
	v_mfma_f32_16x16x32_f16 v[126:129], v[144:147], v[164:167], v[126:129]
	v_mfma_f32_16x16x32_f16 v[122:125], v[152:155], v[164:167], v[122:125]
	v_mfma_f32_16x16x32_f16 v[118:121], v[144:147], v[172:175], v[118:121]
	v_mfma_f32_16x16x32_f16 v[114:117], v[152:155], v[172:175], v[114:117]
	v_mfma_f32_16x16x32_f16 v[110:113], v[144:147], v[180:183], v[110:113]
	v_mfma_f32_16x16x32_f16 v[106:109], v[152:155], v[180:183], v[106:109]
	v_mfma_f32_16x16x32_f16 v[102:105], v[144:147], v[188:191], v[102:105]
	v_mfma_f32_16x16x32_f16 v[98:101], v[152:155], v[188:191], v[98:101]
	v_mfma_f32_16x16x32_f16 v[94:97], v[192:195], v[156:159], v[94:97]
	v_mfma_f32_16x16x32_f16 v[86:89], v[200:203], v[156:159], v[86:89]
	v_mfma_f32_16x16x32_f16 v[78:81], v[192:195], v[168:171], v[78:81]
	v_mfma_f32_16x16x32_f16 v[70:73], v[200:203], v[168:171], v[70:73]
	v_mfma_f32_16x16x32_f16 v[62:65], v[192:195], v[176:179], v[62:65]
	v_mfma_f32_16x16x32_f16 v[54:57], v[200:203], v[176:179], v[54:57]
	v_mfma_f32_16x16x32_f16 v[46:49], v[192:195], v[184:187], v[46:49]
	v_mfma_f32_16x16x32_f16 v[38:41], v[200:203], v[184:187], v[38:41]
	v_mfma_f32_16x16x32_f16 v[94:97], v[196:199], v[164:167], v[94:97]
	v_mfma_f32_16x16x32_f16 v[86:89], v[204:207], v[164:167], v[86:89]
	v_mfma_f32_16x16x32_f16 v[78:81], v[196:199], v[172:175], v[78:81]
	v_mfma_f32_16x16x32_f16 v[70:73], v[204:207], v[172:175], v[70:73]
	v_mfma_f32_16x16x32_f16 v[62:65], v[196:199], v[180:183], v[62:65]
	v_mfma_f32_16x16x32_f16 v[54:57], v[204:207], v[180:183], v[54:57]
	v_mfma_f32_16x16x32_f16 v[46:49], v[196:199], v[188:191], v[46:49]
	v_mfma_f32_16x16x32_f16 v[38:41], v[204:207], v[188:191], v[38:41]
	s_barrier
; #define PG8_STAGE(bufoff, gbase, voff) do { _Pragma("unroll") for (int _i = 0; _i < 2; ++_i) \
;         __builtin_amdgcn_global_load_lds((const unsigned*)((const char*)(gbase) + (voff)[_i]), (LAS unsigned*)(lds + (bufoff) + ldsw + _i * 8192), 16, 0, 0); } while (0)
; #define PG8_LDA(dst, b, h) do { _Pragma("unroll") for (int m = 0; m < 4; ++m) _Pragma("unroll") for (int k = 0; k < 2; ++k) dst[m][k] = *(const LAS h16x8*)(lds + PG8_SA(b, h) + aoff + m * 2048 + k * 1024); } while (0)
; #define PG8_MMA(ai, bj, At, Bt_) do { __builtin_amdgcn_s_setprio(1); _Pragma("unroll") for (int m = 0; m < 4; ++m) _Pragma("unroll") for (int n = 0; n < 2; ++n) _Pragma("unroll") for (int k = 0; k < 2; ++k) \
;         acc[ai][bj][m][n] = __builtin_amdgcn_mfma_f32_16x16x32_f16(Bt_[n][k], At[m][k], acc[ai][bj][m][n], 0, 0, 0); __builtin_amdgcn_s_setprio(0); } while (0)
; #define PG8_WAIT_V(n) asm volatile("s_waitcnt vmcnt(" #n ")" ::: "memory")
; #define PG8_WAIT_L(n) asm volatile("s_waitcnt lgkmcnt(" #n ")" ::: "memory")
; #define PG8_BAR __builtin_amdgcn_s_barrier()
; #define PG8_SCHED __builtin_amdgcn_sched_barrier(0)
; template <class Epi, class AMap>
; __device__ __forceinline__ void gemm_phase(LAS unsigned char* lds, const AMap am, const int lda, const h16* Bt, const int ldb, const int M, const int N, const int K, const Epi& E) {
;     ...
;             PG8_LDA(At, 1, 1); PG8_STAGE(PG8_SA(1, 0), a3, voffA);
;             PG8_BAR; PG8_WAIT_L(0); PG8_MMA(1, 0, At, B0); PG8_BAR; PG8_SCHED;
;             PG8_STAGE(PG8_SB(1, 1), b3 + hstepB, voffB);
;             PG8_WAIT_V(6); PG8_BAR; PG8_MMA(1, 1, At, B1); PG8_BAR;
	global_load_lds_dwordx4 v[212:213], off
	v_lshl_add_u64 v[212:213], v[220:221], 0, s[92:93]
	s_add_i32 m0, s44, 0x2000
	s_nop 0
	global_load_lds_dwordx4 v[212:213], off
	s_mov_b32 m0, s71
	v_lshl_add_u64 v[212:213], v[222:223], 0, s[92:93]
	ds_read_b128 v[156:159], v163 offset:49152
	ds_read_b128 v[164:167], v163 offset:50176
	ds_read_b128 v[168:171], v163 offset:51200
	ds_read_b128 v[172:175], v163 offset:52224
	ds_read_b128 v[176:179], v163 offset:53248
	ds_read_b128 v[180:183], v163 offset:54272
	ds_read_b128 v[184:187], v163 offset:55296
	ds_read_b128 v[188:191], v163 offset:56320
	global_load_lds_dwordx4 v[212:213], off
	v_lshl_add_u64 v[212:213], v[224:225], 0, s[92:93]
	s_mov_b32 m0, s72
	s_nop 0
	global_load_lds_dwordx4 v[212:213], off
	s_add_u32 s44, s46, 0x10080
	s_addc_u32 s45, s47, 0
	s_add_i32 s46, s48, s62
	v_lshl_add_u64 v[232:233], s[44:45], 0, v[0:1]
	s_mov_b32 m0, s46
	s_nop 0
	global_load_lds_dwordx4 v[232:233], off
	v_lshl_add_u64 v[232:233], s[44:45], 0, v[134:135]
	s_add_i32 m0, s46, 0x2000
	s_nop 0
	global_load_lds_dwordx4 v[232:233], off
	s_add_u32 s27, s27, 0x100
	s_addc_u32 s29, s29, 0
	s_cmp_ge_i32 s60, s24
	s_mov_b64 s[44:45], s[0:1]
	s_mov_b32 s46, s60
	s_waitcnt vmcnt(8) lgkmcnt(0)
	s_barrier
	v_mfma_f32_16x16x32_f16 v[90:93], v[140:143], v[156:159], v[90:93]
	v_mfma_f32_16x16x32_f16 v[82:85], v[148:151], v[156:159], v[82:85]
	v_mfma_f32_16x16x32_f16 v[74:77], v[140:143], v[168:171], v[74:77]
	v_mfma_f32_16x16x32_f16 v[66:69], v[148:151], v[168:171], v[66:69]
	v_mfma_f32_16x16x32_f16 v[58:61], v[140:143], v[176:179], v[58:61]
	v_mfma_f32_16x16x32_f16 v[50:53], v[148:151], v[176:179], v[50:53]
	v_mfma_f32_16x16x32_f16 v[42:45], v[140:143], v[184:187], v[42:45]
	v_mfma_f32_16x16x32_f16 v[34:37], v[148:151], v[184:187], v[34:37]
	v_mfma_f32_16x16x32_f16 v[90:93], v[144:147], v[164:167], v[90:93]
	v_mfma_f32_16x16x32_f16 v[82:85], v[152:155], v[164:167], v[82:85]
	v_mfma_f32_16x16x32_f16 v[74:77], v[144:147], v[172:175], v[74:77]
	v_mfma_f32_16x16x32_f16 v[66:69], v[152:155], v[172:175], v[66:69]
	v_mfma_f32_16x16x32_f16 v[58:61], v[144:147], v[180:183], v[58:61]
	v_mfma_f32_16x16x32_f16 v[50:53], v[152:155], v[180:183], v[50:53]
	v_mfma_f32_16x16x32_f16 v[42:45], v[144:147], v[188:191], v[42:45]
	v_mfma_f32_16x16x32_f16 v[34:37], v[152:155], v[188:191], v[34:37]
	v_mfma_f32_16x16x32_f16 v[30:33], v[192:195], v[156:159], v[30:33]
	v_mfma_f32_16x16x32_f16 v[26:29], v[200:203], v[156:159], v[26:29]
	v_mfma_f32_16x16x32_f16 v[22:25], v[192:195], v[168:171], v[22:25]
	v_mfma_f32_16x16x32_f16 v[18:21], v[200:203], v[168:171], v[18:21]
	v_mfma_f32_16x16x32_f16 v[14:17], v[192:195], v[176:179], v[14:17]
	v_mfma_f32_16x16x32_f16 v[10:13], v[200:203], v[176:179], v[10:13]
	v_mfma_f32_16x16x32_f16 v[6:9], v[192:195], v[184:187], v[6:9]
	v_mfma_f32_16x16x32_f16 v[2:5], v[200:203], v[184:187], v[2:5]
	v_mfma_f32_16x16x32_f16 v[30:33], v[196:199], v[164:167], v[30:33]
	v_mfma_f32_16x16x32_f16 v[26:29], v[204:207], v[164:167], v[26:29]
	v_mfma_f32_16x16x32_f16 v[22:25], v[196:199], v[172:175], v[22:25]
	v_mfma_f32_16x16x32_f16 v[18:21], v[204:207], v[172:175], v[18:21]
	v_mfma_f32_16x16x32_f16 v[14:17], v[196:199], v[180:183], v[14:17]
	v_mfma_f32_16x16x32_f16 v[10:13], v[204:207], v[180:183], v[10:13]
	v_mfma_f32_16x16x32_f16 v[6:9], v[196:199], v[188:191], v[6:9]
	v_mfma_f32_16x16x32_f16 v[2:5], v[204:207], v[188:191], v[2:5]
	s_barrier
	s_cbranch_scc0 .LBB0_667
	s_cmpk_gt_u32 s50, 0xff
	s_cbranch_scc1 .Lgx6
	s_barrier

; #define PG8_WAIT_V(n) asm volatile("s_waitcnt vmcnt(" #n ")" ::: "memory")
; #define PG8_BAR __builtin_amdgcn_s_barrier()
; template <class Epi, class AMap>
; __device__ __forceinline__ void gemm_phase(LAS unsigned char* lds, const AMap am, const int lda, const h16* Bt, const int ldb, const int M, const int N, const int K, const Epi& E) {
;     ...
;     PG8_WAIT_V(0);
;     if (wr == 0) PG8_BAR;
;     PG8_BAR;
.LBB0_669:
	s_waitcnt vmcnt(0)
	s_cmpk_gt_u32 s50, 0xff
	s_cbranch_scc1 .LBB0_671
.LBB0_671:
	v_readlane_b32 s29, v254, 37
	s_barrier

; __device__ __forceinline__ int otid() { int t = (int)threadIdx.x; asm volatile("" : "+v"(t)); return t; }
; __device__ __forceinline__ int obid() { int t = (int)blockIdx.x; asm volatile("" : "+s"(t)); return t; }
; #define PG8_WAIT_V(n) asm volatile("s_waitcnt vmcnt(" #n ")" ::: "memory")
; #define PG8_BAR __builtin_amdgcn_s_barrier()
; template <class Epi, class AMap>
; __device__ __forceinline__ void gemm_phase(LAS unsigned char* lds, const AMap am, const int lda, const h16* Bt, const int ldb, const int M, const int N, const int K, const Epi& E) {
;     const int tid = otid(), wid = __builtin_amdgcn_readfirstlane(tid >> 6), lane = tid & 63, wr = wid >> 2, wc = wid & 3, fr = lane & 15, fq = lane >> 4;
;     const int nt = K / BK;
;     Order S; S.init(M, N, (int)gridDim.x, obid());
;     unsigned voffA[2], voffB[2];
; #pragma unroll
;     for (int i = 0; i < 2; ++i) { int R, C; stage_rc(tid * 16 + i * 8192, R, C); const int Rb = Epi::PERM ? ((R & ~31) + perm32(R & 31)) : R;
;         voffA[i] = (unsigned)(R * lda + C) * 2u; voffB[i] = (unsigned)(Rb * ldb + C) * 2u; }
;     const size_t kstep = (size_t)(BK * 2);
;     const size_t hstepA = (size_t)HALF * lda * 2, hstepB = (size_t)HALF * ldb * 2;
;     const size_t tstepA = 2 * hstepA, tstepB = 2 * hstepB;
;     const unsigned ldsw = (unsigned)wid * 1024u;
;     const int aoff = lds_byte(wr * 64 + fr, fq * 8), boff = lds_byte(wc * 32 + fr, fq * 8);
;     ...
;     Unit cur, nxt; int ui = 0;
;     if (!S.next(0, cur)) return;
;     f32x4 acc[2][2][4][2];
; #pragma unroll
;     for (int a = 0; a < 2; ++a)
; #pragma unroll
;         for (int b = 0; b < 2; ++b)
; #pragma unroll
;             for (int m = 0; m < 4; ++m)
; #pragma unroll
;                 for (int n = 0; n < 2; ++n) acc[a][b][m][n] = (f32x4){0.f, 0.f, 0.f, 0.f};
;     h16x8 At[4][2], B0[2][2], B1[2][2];
;     const char* cA = am(cur.pn) + (size_t)cur.pm * tstepA; const char* cB = (const char*)Bt + (size_t)cur.pn * tstepB;
;     PG8_STAGE(PG8_SB(0, 0), cB, voffB); PG8_STAGE(PG8_SA(0, 0), cA, voffA); PG8_STAGE(PG8_SB(0, 1), cB + hstepB, voffB); PG8_STAGE(PG8_SA(0, 1), cA + hstepA, voffA);
;     if (wr == 1) PG8_BAR;
;     PG8_WAIT_V(4); PG8_BAR;
;     PG8_STAGE(PG8_SB(1, 0), cB + kstep, voffB); PG8_STAGE(PG8_SA(1, 0), cA + kstep, voffA); PG8_STAGE(PG8_SB(1, 1), cB + hstepB + kstep, voffB);
.LBB0_678:
	v_ashrrev_i32_e32 v0, 31, v18
	v_lshrrev_b32_e32 v0, 26, v0
	v_add_u32_e32 v0, v18, v0
	v_ashrrev_i32_e32 v10, 6, v0
	v_bfe_i32 v0, v18, 27, 1
	s_waitcnt vmcnt(0)
	v_lshlrev_b32_e32 v2, 4, v18
	v_lshrrev_b32_e32 v0, 22, v0
	v_add_u32_e32 v0, v2, v0
	v_and_b32_e32 v0, 0xfffffc00, v0
	v_sub_u32_e32 v0, v2, v0
	v_lshrrev_b32_e32 v3, 4, v0
	v_bitop3_b32 v3, v3, v0, 32 bitop3:0x6c
	v_ashrrev_i32_e32 v0, 31, v0
	v_lshrrev_b32_e32 v0, 26, v0
	v_lshlrev_b32_e32 v4, 3, v10
	v_add_u32_e32 v0, v3, v0
	v_and_b32_e32 v4, -16, v4
	v_ashrrev_i32_e32 v12, 6, v0
	v_add_u32_e32 v0, v12, v4
	v_lshlrev_b32_e32 v4, 5, v10
	v_and_b32_e32 v11, 32, v4
	v_mul_i32_i24_e32 v4, 64, v12
	s_ashr_i32 s1, s69, 6
	v_sub_u32_e32 v3, v3, v4
	v_mov_b32_e32 v7, 1
	v_ashrrev_i16_sdwa v3, v7, sext(v3) dst_sel:DWORD dst_unused:UNUSED_PAD src0_sel:DWORD src1_sel:BYTE_0
	s_ashr_i32 s20, s69, 8
	s_lshl_b32 s71, s1, 10
	v_bfe_i32 v13, v3, 0, 16
	v_and_b32_e32 v6, 3, v12
	s_mov_b32 s5, 0x7fffe0
	s_movk_i32 s4, 0x1c00
	s_add_u32 s72, s10, 0x1f00000
	v_add_u32_e32 v3, v11, v13
	v_lshlrev_b32_e32 v4, 1, v0
	v_lshrrev_b32_e32 v5, 2, v0
	v_and_or_b32 v6, v0, s5, v6
	v_mul_lo_u32 v0, v0, s4
	v_add_u32_e32 v2, 0x2000, v2
	s_addc_u32 s73, s11, 0
	s_add_i32 s0, s21, s0
	v_add_lshl_u32 v146, v3, v0, 1
	v_lshlrev_b32_e32 v0, 1, v3
	v_ashrrev_i32_e32 v3, 31, v2
	s_ashr_i32 s21, s0, 31
	v_lshrrev_b32_e32 v3, 22, v3
	s_lshr_b32 s21, s21, 27
	v_add_u32_e32 v3, v2, v3
	s_add_i32 s21, s0, s21
	v_ashrrev_i32_e32 v14, 10, v3
	s_ashr_i32 s22, s21, 5
	s_and_b32 s21, s21, 0xffe0
	v_mul_i32_i24_e32 v3, 0x400, v14
	s_sub_i32 s21, s0, s21
	v_sub_u32_e32 v2, v2, v3
	s_bfe_i32 s0, s21, 0x80000
	v_and_b32_e32 v4, 24, v4
	v_and_b32_e32 v5, 4, v5
	v_lshrrev_b32_e32 v3, 4, v2
	s_bfe_u32 s0, s0, 0x2000d
	v_or3_b32 v4, v6, v5, v4
	v_bitop3_b32 v2, v3, v2, 32 bitop3:0x6c
	s_add_i32 s23, s21, s0
	v_lshl_add_u32 v0, v4, 9, v0
	v_ashrrev_i32_e32 v4, 31, v2
	s_bfe_i32 s0, s23, 0x80000
	s_and_b32 s23, s23, 0xfc
	v_lshrrev_b32_e32 v4, 26, v4
	s_sext_i32_i16 s0, s0
	s_sub_i32 s21, s21, s23
	v_add_u32_e32 v4, v2, v4
	s_lshl_b32 s22, s22, 2
	s_lshr_b32 s0, s0, 2
	s_sext_i32_i8 s21, s21
	v_lshlrev_b32_e32 v3, 3, v14
	v_ashrrev_i32_e32 v16, 6, v4
	v_and_b32_e32 v4, 0xc0, v4
	s_add_i32 s35, s22, s21
	s_bfe_i64 s[22:23], s[0:1], 0x100000
	v_and_b32_e32 v3, -16, v3
	v_sub_u32_e32 v2, v2, v4
	s_lshl_b64 s[22:23], s[22:23], 17
	v_add_u32_e32 v3, v16, v3
	v_lshlrev_b32_e32 v5, 5, v14
	v_ashrrev_i16_sdwa v2, v7, sext(v2) dst_sel:DWORD dst_unused:UNUSED_PAD src0_sel:DWORD src1_sel:BYTE_0
	s_add_u32 s26, s72, s22
	v_and_b32_e32 v15, 32, v5
	v_bfe_i32 v17, v2, 0, 16
	v_lshlrev_b32_e32 v4, 1, v3
	v_lshrrev_b32_e32 v5, 2, v3
	v_and_b32_e32 v6, 3, v16
	s_addc_u32 s27, s73, s23
	s_add_i32 s74, s71, 0
	v_add_u32_e32 v2, v15, v17
	v_and_b32_e32 v4, 24, v4
	v_and_b32_e32 v5, 4, v5
	v_and_or_b32 v6, v3, s5, v6
	v_mul_lo_u32 v3, v3, s4
	s_add_i32 m0, s74, 0x10000
	v_or3_b32 v4, v6, v5, v4
	v_add_lshl_u32 v148, v2, v3, 1
	v_lshlrev_b32_e32 v2, 1, v2
	s_mul_i32 s29, s35, 0x380000
	global_load_lds_dwordx4 v0, s[26:27]
	s_add_i32 m0, s74, 0x12000
	v_readlane_b32 s4, v252, 39
	v_lshl_add_u32 v150, v4, 9, v2
	s_mul_hi_i32 s21, s35, 0x380000
	s_add_u32 s22, s4, s29
	v_readlane_b32 s4, v252, 40
	global_load_lds_dwordx4 v150, s[26:27]
	s_addc_u32 s23, s4, s21
	s_mov_b32 m0, s74
	s_add_i32 s75, s74, 0x2000
	global_load_lds_dwordx4 v146, s[22:23]
	s_mov_b32 m0, s75
	s_add_u32 s38, s26, 0x10000
	global_load_lds_dwordx4 v148, s[22:23]
	s_addc_u32 s39, s27, 0
	s_add_i32 m0, s74, 0x14000
	v_mov_b32_e32 v151, v1
	global_load_lds_dwordx4 v0, s[38:39]
	s_add_i32 m0, s74, 0x16000
	v_mov_b32_e32 v147, v1
	global_load_lds_dwordx4 v150, s[38:39]
	s_add_u32 s38, s22, 0x1c0000
	s_addc_u32 s39, s23, 0
	s_add_i32 s76, s74, 0x4000
	s_mov_b32 m0, s76
	s_add_i32 s77, s74, 0x6000
	global_load_lds_dwordx4 v146, s[38:39]
	s_mov_b32 m0, s77
	v_mov_b32_e32 v149, v1
	global_load_lds_dwordx4 v148, s[38:39]
	v_lshl_add_u64 v[8:9], s[26:27], 0, v[0:1]
	v_lshl_add_u64 v[6:7], s[26:27], 0, v[150:151]
	v_lshl_add_u64 v[4:5], s[22:23], 0, v[146:147]
	s_cmp_lg_u32 s20, 1
	v_lshl_add_u64 v[2:3], s[22:23], 0, v[148:149]
	s_cbranch_scc1 .LBB0_680
; #define PG8_STAGE(bufoff, gbase, voff) do { _Pragma("unroll") for (int _i = 0; _i < 2; ++_i) \
;         __builtin_amdgcn_global_load_lds((const unsigned*)((const char*)(gbase) + (voff)[_i]), (LAS unsigned*)(lds + (bufoff) + ldsw + _i * 8192), 16, 0, 0); } while (0)
; #define PG8_WAIT_V(n) asm volatile("s_waitcnt vmcnt(" #n ")" ::: "memory")
; #define PG8_BAR __builtin_amdgcn_s_barrier()
; template <class Epi, class AMap>
; __device__ __forceinline__ void gemm_phase(LAS unsigned char* lds, const AMap am, const int lda, const h16* Bt, const int ldb, const int M, const int N, const int K, const Epi& E) {
;     ...
;     if (wr == 1) PG8_BAR;
;     PG8_WAIT_V(4); PG8_BAR;
;     PG8_STAGE(PG8_SB(1, 0), cB + kstep, voffB); PG8_STAGE(PG8_SA(1, 0), cA + kstep, voffA); PG8_STAGE(PG8_SB(1, 1), cB + hstepB + kstep, voffB);
;     PG8_WAIT_V(6); PG8_BAR;
;     for (;;) {
;         const bool has_next = S.next(ui + 1, nxt);
;         const char* nA = has_next ? am(nxt.pn) + (size_t)nxt.pm * tstepA : cA; const char* nB = has_next ? (const char*)Bt + (size_t)nxt.pn * tstepB : cB;
; #pragma unroll 1
;         for (int t = 0; t < nt; t += 2) {
;             const bool last = (t == nt - 2);
;             const char* a1 = cA + (size_t)(t + 1) * kstep;
;             const char* a2 = last ? nA : cA + (size_t)(t + 2) * kstep; const char* b2 = last ? nB : cB + (size_t)(t + 2) * kstep;
.LBB0_680:
	v_lshrrev_b32_e32 v20, 1, v18
	v_and_b32_e32 v20, 24, v20
	v_and_b32_e32 v19, 15, v18
	v_lshlrev_b32_e32 v21, 1, v20
	v_lshlrev_b32_e32 v18, 2, v18
	s_sext_i32_i8 s50, s0
	v_lshl_or_b32 v174, s20, 6, v19
	v_lshl_or_b32 v19, v19, 6, v21
	s_lshl_b32 s0, s20, 13
	v_and_b32_e32 v18, 32, v18
	v_bitop3_b32 v21, v19, s0, v18 bitop3:0xde
	s_lshl_b32 s0, s1, 5
	s_and_b32 s20, s0, 0x60
	s_lshl_b32 s0, s20, 7
	v_bitop3_b32 v175, v19, s0, v18 bitop3:0xde
	v_readlane_b32 s0, v255, 7
	v_readlane_b32 s1, v255, 8
	s_mov_b32 s1, s25
	s_lshl_b64 s[0:1], s[0:1], 11
	s_add_u32 s21, s0, 0xfffff800
	s_addc_u32 s29, s1, -1
	s_and_b64 s[0:1], s[82:83], exec
	s_cselect_b32 s1, 0, s29
	s_cselect_b32 s0, 0, s21
	v_readlane_b32 s4, v251, 37
	s_lshl_b64 s[0:1], s[0:1], 2
	v_readlane_b32 s10, v251, 43
	v_readlane_b32 s11, v251, 44
	s_add_u32 s40, s10, s0
	s_addc_u32 s41, s11, s1
	s_add_i32 m0, s74, 0x18000
	v_lshl_add_u64 v[8:9], v[8:9], 0, s[92:93]
	s_waitcnt vmcnt(0)
	s_barrier
	global_load_lds_dwordx4 v[8:9], off
	v_lshl_add_u64 v[6:7], v[6:7], 0, s[92:93]
	s_add_i32 m0, s74, 0x1a000
	s_add_i32 s79, s74, 0x8000
	s_add_i32 s80, s74, 0xa000
	global_load_lds_dwordx4 v[6:7], off
	v_lshl_add_u64 v[4:5], v[4:5], 0, s[92:93]
	s_mov_b32 m0, s79
	s_add_u32 s0, s26, 0x10080
	global_load_lds_dwordx4 v[4:5], off
	v_lshl_add_u64 v[2:3], v[2:3], 0, s[92:93]
	s_mov_b32 m0, s80
	s_addc_u32 s1, s27, 0
	global_load_lds_dwordx4 v[2:3], off
	s_add_i32 m0, s74, 0x1c000
	v_lshl_add_u64 v[2:3], s[0:1], 0, v[0:1]
	global_load_lds_dwordx4 v[2:3], off
	v_lshl_add_u64 v[2:3], s[0:1], 0, v[150:151]
	s_add_i32 m0, s74, 0x1e000
	v_readlane_b32 s5, v251, 38
	global_load_lds_dwordx4 v[2:3], off
	s_movk_i32 s5, 0x1c00
	v_lshrrev_b32_e32 v3, 1, v10
	v_mul_lo_u32 v2, v12, s5
	s_mov_b32 s4, 0x1c000
	v_mad_u64_u32 v[2:3], s[0:1], v3, s4, v[2:3]
	v_readlane_b32 s6, v251, 39
	v_readlane_b32 s7, v251, 40
	v_or_b32_e32 v2, v2, v11
	v_add_lshl_u32 v2, v2, v13, 1
	v_mov_b32_e32 v3, v1
	s_mov_b64 s[6:7], 0x1c0080
	v_lshl_add_u64 v[152:153], v[2:3], 0, s[6:7]
	v_lshrrev_b32_e32 v3, 1, v14
	v_mul_lo_u32 v2, v16, s5
	v_mad_u64_u32 v[2:3], s[0:1], v3, s4, v[2:3]
	v_readlane_b32 s8, v251, 41
	v_readlane_b32 s9, v251, 42
	s_waitcnt vmcnt(6)
	v_or_b32_e32 v2, v2, v15
	v_readlane_b32 s12, v251, 45
	v_readlane_b32 s13, v251, 46
	s_cmp_gt_i32 s61, 63
	v_add_lshl_u32 v2, v2, v17, 1
	v_mov_b32_e32 v3, v1
	v_readlane_b32 s8, v254, 58
	s_mov_b32 s78, 0
	s_cselect_b64 s[42:43], -1, 0
	s_add_i32 s61, s24, -2
	v_or_b32_e32 v176, s20, v20
	v_lshl_add_u64 v[154:155], v[2:3], 0, s[6:7]
	v_add_u32_e32 v177, 0, v21
	v_readlane_b32 s9, v254, 59
	v_readlane_b32 s12, v254, 62
	s_movk_i32 s5, 0x3800
	s_movk_i32 s13, 0x2b00
	v_readlane_b32 s14, v251, 47
	v_readlane_b32 s15, v251, 48
	v_readlane_b32 s16, v251, 49
	v_readlane_b32 s17, v251, 50
	v_readlane_b32 s18, v251, 51
	v_readlane_b32 s19, v251, 52
	s_barrier
	s_branch .LBB0_682

; __device__ __forceinline__ float sigmoidf_(float x) { return 1.0f / (1.0f + __expf(-x)); }
;     template <int GI>
;     __device__ __forceinline__ void body(const f32x4 (&acc)[2][2][4][2], int row0, int colt) const {
; #pragma unroll
;         for (int bj = 0; bj < 2; ++bj) {
;             const int c = colt + bj * 128;
;             f32x4 b0 = (f32x4){0.f, 0.f, 0.f, 0.f}, b1 = b0;
;             if (GI == 0) { b0 = *(const f32x4*)(w0 + c); b1 = *(const f32x4*)(w0 + c + 4); }
;             else if (GI == 1) { b0 = *(const f32x4*)(a0 + c); b1 = *(const f32x4*)(a0 + c + 4); }
;             else if (GI == 3) { b0 = *(const f32x4*)(v0 + c); b1 = *(const f32x4*)(v0 + c + 4); }
; #pragma unroll
;             for (int ai = 0; ai < 2; ++ai)
; #pragma unroll
;                 for (int m = 0; m < 4; ++m) {
;                     const size_t row = (size_t)(row0 + ai * 128 + m * 16);
;                     f32x4 x0 = acc[ai][bj][m][0] + b0, x1 = acc[ai][bj][m][1] + b1;
;                     if (GI == 0) {
; #pragma unroll
;                         for (int j = 0; j < 4; ++j) {
;                             x0[j] = 0.6065306597126334f * sigmoidf_(x0[j]); x1[j] = 0.6065306597126334f * sigmoidf_(x1[j]); }
;                         *(u32x4*)(DEC + row * DM + c) = pack8(x0, x1);
;                     } else if (GI == 1) {
; #pragma unroll
;                         for (int j = 0; j < 4; ++j) { x0[j] = sigmoidf_(x0[j]); x1[j] = sigmoidf_(x1[j]); }
;                         *(u32x4*)(Ab + row * DM + c) = pack8(x0, x1);
;                     } else if (GI == 2) {
;                         *(u32x4*)(Gb + row * DM + c) = pack8(x0, x1);
;                     } else {
;                         h16* vp = C1 + row * LDC1 + 4096 + c;
;                         const h16x8 vv = *(const h16x8*)vp; const h16x8 vf = *(const h16x8*)(VF + row * DM + c);
;                         f32x4 o0, o1;
; #pragma unroll
;                         for (int j = 0; j < 4; ++j) { float v = (float)vv[j], f = (float)vf[j]; o0[j] = v + (f - v) * sigmoidf_(x0[j]); v = (float)vv[4 + j]; f = (float)vf[4 + j]; o1[j] = v + (f - v) * sigmoidf_(x1[j]); }
;                         *(u32x4*)vp = pack8(o0, o1);
;                     }
;                     __builtin_amdgcn_sched_barrier(0);
;                 }
.Lgx7:
	s_waitcnt vmcnt(0)
	v_add_f32_e32 v130, v130, v82
	v_mul_f32_e32 v130, 0xbfb8aa3b, v130
	v_exp_f32_e32 v172, v130
	v_add_f32_e32 v130, v135, v87
	v_mul_f32_e32 v130, 0xbfb8aa3b, v130
	v_exp_f32_e32 v179, v130
	v_add_f32_e32 v130, v131, v83
	v_mul_f32_e32 v130, 0xbfb8aa3b, v130
	v_exp_f32_e32 v173, v130
	v_add_f32_e32 v130, v136, v88
	v_add_f32_e32 v134, v134, v86
	v_mul_f32_e32 v130, 0xbfb8aa3b, v130
	v_mul_f32_e32 v134, 0xbfb8aa3b, v134
	v_exp_f32_e32 v136, v130
	v_add_f32_e32 v130, v132, v84
	v_exp_f32_e32 v178, v134
	v_mul_f32_e32 v130, 0xbfb8aa3b, v130
	v_exp_f32_e32 v134, v130
	v_add_f32_e32 v130, v137, v89
	v_mul_f32_e32 v130, 0xbfb8aa3b, v130
	v_exp_f32_e32 v137, v130
	v_add_f32_e32 v130, v133, v85
	v_mul_f32_e32 v130, 0xbfb8aa3b, v130
	v_pk_add_f32 v[178:179], v[178:179], 1.0 op_sel_hi:[1,0]
	v_exp_f32_e32 v135, v130
	v_cvt_f32_f16_e32 v130, v138
	v_cvt_f32_f16_sdwa v131, v138 dst_sel:DWORD dst_unused:UNUSED_PAD src0_sel:WORD_1
	v_div_scale_f32 v138, s[0:1], v179, v179, 1.0
	v_cvt_f32_f16_e32 v132, v142
	v_cvt_f32_f16_sdwa v133, v142 dst_sel:DWORD dst_unused:UNUSED_PAD src0_sel:WORD_1
	v_rcp_f32_e32 v142, v138
	v_pk_add_f32 v[136:137], v[136:137], 1.0 op_sel_hi:[1,0]
	v_pk_add_f32 v[134:135], v[134:135], 1.0 op_sel_hi:[1,0]
	v_pk_add_f32 v[132:133], v[132:133], v[130:131] neg_lo:[0,1] neg_hi:[0,1]
	v_fma_f32 v159, -v138, v142, 1.0
	v_fmac_f32_e32 v142, v159, v142
	v_div_scale_f32 v159, vcc, 1.0, v179, 1.0
	v_mul_f32_e32 v165, v159, v142
	v_fma_f32 v180, -v138, v165, v159
	v_fmac_f32_e32 v165, v180, v142
	v_fma_f32 v138, -v138, v165, v159
	v_div_fmas_f32 v138, v138, v142, v165
	v_div_fixup_f32 v179, v138, v179, 1.0
	v_div_scale_f32 v138, s[0:1], v178, v178, 1.0
	v_rcp_f32_e32 v142, v138
	s_nop 0
	v_fma_f32 v159, -v138, v142, 1.0
	v_fmac_f32_e32 v142, v159, v142
	v_div_scale_f32 v159, vcc, 1.0, v178, 1.0
	v_mul_f32_e32 v165, v159, v142
	v_fma_f32 v180, -v138, v165, v159
	v_fmac_f32_e32 v165, v180, v142
	v_fma_f32 v138, -v138, v165, v159
	v_div_fmas_f32 v138, v138, v142, v165
	v_div_fixup_f32 v178, v138, v178, 1.0
	v_pk_fma_f32 v[130:131], v[178:179], v[132:133], v[130:131]
	v_cvt_f32_f16_e32 v132, v139
	v_cvt_pk_f16_f32 v130, v130, v131
	v_div_scale_f32 v131, s[0:1], v137, v137, 1.0
	v_rcp_f32_e32 v142, v131
	v_cvt_f32_f16_sdwa v133, v139 dst_sel:DWORD dst_unused:UNUSED_PAD src0_sel:WORD_1
	v_cvt_f32_f16_e32 v138, v143
	v_cvt_f32_f16_sdwa v139, v143 dst_sel:DWORD dst_unused:UNUSED_PAD src0_sel:WORD_1
	v_fma_f32 v143, -v131, v142, 1.0
	v_fmac_f32_e32 v142, v143, v142
	v_div_scale_f32 v143, vcc, 1.0, v137, 1.0
	v_mul_f32_e32 v159, v143, v142
	v_fma_f32 v165, -v131, v159, v143
	v_fmac_f32_e32 v159, v165, v142
	v_fma_f32 v131, -v131, v159, v143
	v_div_fmas_f32 v131, v131, v142, v159
	v_div_fixup_f32 v137, v131, v137, 1.0
	v_div_scale_f32 v131, s[0:1], v136, v136, 1.0
	v_rcp_f32_e32 v142, v131
	v_pk_add_f32 v[138:139], v[138:139], v[132:133] neg_lo:[0,1] neg_hi:[0,1]
	v_fma_f32 v143, -v131, v142, 1.0
	v_fmac_f32_e32 v142, v143, v142
	v_div_scale_f32 v143, vcc, 1.0, v136, 1.0
	v_mul_f32_e32 v159, v143, v142
	v_fma_f32 v165, -v131, v159, v143
	v_fmac_f32_e32 v159, v165, v142
	v_fma_f32 v131, -v131, v159, v143
	v_div_fmas_f32 v131, v131, v142, v159
	v_div_fixup_f32 v136, v131, v136, 1.0
	v_pk_fma_f32 v[132:133], v[136:137], v[138:139], v[132:133]
	v_pk_add_f32 v[138:139], v[172:173], 1.0 op_sel_hi:[1,0]
	v_cvt_pk_f16_f32 v131, v132, v133
	v_cvt_f32_f16_e32 v132, v140
	v_cvt_f32_f16_sdwa v133, v140 dst_sel:DWORD dst_unused:UNUSED_PAD src0_sel:WORD_1
	v_div_scale_f32 v140, s[0:1], v139, v139, 1.0
	v_rcp_f32_e32 v142, v140
	v_cvt_f32_f16_e32 v136, v144
	v_cvt_f32_f16_sdwa v137, v144 dst_sel:DWORD dst_unused:UNUSED_PAD src0_sel:WORD_1
	v_fma_f32 v143, -v140, v142, 1.0
	v_fmac_f32_e32 v142, v143, v142
	v_div_scale_f32 v143, vcc, 1.0, v139, 1.0
	v_mul_f32_e32 v144, v143, v142
	v_fma_f32 v159, -v140, v144, v143
	v_fmac_f32_e32 v144, v159, v142
	v_fma_f32 v140, -v140, v144, v143
	v_div_fmas_f32 v140, v140, v142, v144
	v_div_fixup_f32 v139, v140, v139, 1.0
	v_div_scale_f32 v140, s[0:1], v138, v138, 1.0
	v_rcp_f32_e32 v142, v140
	v_pk_add_f32 v[136:137], v[136:137], v[132:133] neg_lo:[0,1] neg_hi:[0,1]
	v_fma_f32 v143, -v140, v142, 1.0
	v_fmac_f32_e32 v142, v143, v142
	v_div_scale_f32 v143, vcc, 1.0, v138, 1.0
	v_mul_f32_e32 v144, v143, v142
	v_fma_f32 v159, -v140, v144, v143
	v_fmac_f32_e32 v144, v159, v142
	v_fma_f32 v140, -v140, v144, v143
	v_div_fmas_f32 v140, v140, v142, v144
	v_div_fixup_f32 v138, v140, v138, 1.0
	v_pk_fma_f32 v[132:133], v[136:137], v[138:139], v[132:133]
	v_cvt_f32_f16_e32 v136, v141
	v_cvt_pk_f16_f32 v132, v132, v133
	v_div_scale_f32 v133, s[0:1], v135, v135, 1.0
	v_rcp_f32_e32 v140, v133
	v_cvt_f32_f16_sdwa v137, v141 dst_sel:DWORD dst_unused:UNUSED_PAD src0_sel:WORD_1
	v_cvt_f32_f16_e32 v138, v145
	v_cvt_f32_f16_sdwa v139, v145 dst_sel:DWORD dst_unused:UNUSED_PAD src0_sel:WORD_1
	v_fma_f32 v141, -v133, v140, 1.0
	v_fmac_f32_e32 v140, v141, v140
	v_div_scale_f32 v141, vcc, 1.0, v135, 1.0
	v_mul_f32_e32 v142, v141, v140
	v_fma_f32 v143, -v133, v142, v141
	v_fmac_f32_e32 v142, v143, v140
	v_fma_f32 v133, -v133, v142, v141
	v_div_fmas_f32 v133, v133, v140, v142
	v_div_fixup_f32 v135, v133, v135, 1.0
	v_div_scale_f32 v133, s[0:1], v134, v134, 1.0
	v_rcp_f32_e32 v140, v133
	v_pk_add_f32 v[138:139], v[138:139], v[136:137] neg_lo:[0,1] neg_hi:[0,1]
	v_fma_f32 v141, -v133, v140, 1.0
	v_fmac_f32_e32 v140, v141, v140
	v_div_scale_f32 v141, vcc, 1.0, v134, 1.0
	v_mul_f32_e32 v142, v141, v140
	v_fma_f32 v143, -v133, v142, v141
	v_fmac_f32_e32 v142, v143, v140
	v_fma_f32 v133, -v133, v142, v141
	v_div_fmas_f32 v133, v133, v140, v142
; __device__ __forceinline__ float sigmoidf_(float x) { return 1.0f / (1.0f + __expf(-x)); }
;     template <int GI>
;     __device__ __forceinline__ void body(const f32x4 (&acc)[2][2][4][2], int row0, int colt) const {
;     ...
;                         *(u32x4*)(Gb + row * DM + c) = pack8(x0, x1);
;                     } else {
;                         h16* vp = C1 + row * LDC1 + 4096 + c;
;                         const h16x8 vv = *(const h16x8*)vp; const h16x8 vf = *(const h16x8*)(VF + row * DM + c);
;                         f32x4 o0, o1;
; #pragma unroll
;                         for (int j = 0; j < 4; ++j) { float v = (float)vv[j], f = (float)vf[j]; o0[j] = v + (f - v) * sigmoidf_(x0[j]); v = (float)vv[4 + j]; f = (float)vf[4 + j]; o1[j] = v + (f - v) * sigmoidf_(x1[j]); }
;                         *(u32x4*)vp = pack8(o0, o1);
;                     }
;                     __builtin_amdgcn_sched_barrier(0);
	v_div_fixup_f32 v134, v133, v134, 1.0
	v_pk_fma_f32 v[134:135], v[138:139], v[134:135], v[136:137]
	s_nop 0
	v_cvt_pk_f16_f32 v133, v134, v135
	global_store_dwordx4 v[170:171], v[130:133], off
	v_or_b32_e32 v134, 16, v164
	v_ashrrev_i32_e32 v135, 31, v134
	v_mad_i64_i32 v[130:131], s[0:1], v134, s5, v[168:169]
	v_lshl_add_u64 v[138:139], v[130:131], 0, s[90:91]
	v_lshlrev_b64 v[134:135], 12, v[134:135]
	v_lshl_add_u64 v[142:143], v[138:139], 0, v[166:167]
	v_lshl_add_u64 v[134:135], s[2:3], 0, v[134:135]
	global_load_dwordx4 v[130:133], v[142:143], off
	v_lshl_add_u64 v[140:141], v[134:135], 0, v[166:167]
	global_load_dwordx4 v[134:137], v[140:141], off
	v_add_f32_e32 v122, v122, v82
	v_mul_f32_e32 v122, 0xbfb8aa3b, v122
	v_exp_f32_e32 v144, v122
	v_add_f32_e32 v122, v127, v87
	v_mul_f32_e32 v122, 0xbfb8aa3b, v122
	v_exp_f32_e32 v173, v122
	v_add_f32_e32 v122, v123, v83
	v_mul_f32_e32 v122, 0xbfb8aa3b, v122
	v_exp_f32_e32 v145, v122
	v_add_f32_e32 v122, v128, v88
	v_add_f32_e32 v126, v126, v86
	v_mul_f32_e32 v122, 0xbfb8aa3b, v122
	v_mul_f32_e32 v126, 0xbfb8aa3b, v126
	v_exp_f32_e32 v170, v122
	v_add_f32_e32 v122, v124, v84
	v_exp_f32_e32 v172, v126
	v_mul_f32_e32 v122, 0xbfb8aa3b, v122
	v_exp_f32_e32 v126, v122
	v_add_f32_e32 v122, v129, v89
	v_mul_f32_e32 v122, 0xbfb8aa3b, v122
	v_exp_f32_e32 v171, v122
	v_add_f32_e32 v122, v125, v85
	v_mul_f32_e32 v122, 0xbfb8aa3b, v122
	v_pk_add_f32 v[128:129], v[172:173], 1.0 op_sel_hi:[1,0]
	v_exp_f32_e32 v127, v122
	s_waitcnt vmcnt(0)
	v_cvt_f32_f16_e32 v122, v130
	v_cvt_f32_f16_sdwa v123, v130 dst_sel:DWORD dst_unused:UNUSED_PAD src0_sel:WORD_1
	v_div_scale_f32 v130, s[0:1], v129, v129, 1.0
	v_cvt_f32_f16_e32 v124, v134
	v_cvt_f32_f16_sdwa v125, v134 dst_sel:DWORD dst_unused:UNUSED_PAD src0_sel:WORD_1
	v_rcp_f32_e32 v134, v130
	v_pk_add_f32 v[126:127], v[126:127], 1.0 op_sel_hi:[1,0]
	v_pk_add_f32 v[124:125], v[124:125], v[122:123] neg_lo:[0,1] neg_hi:[0,1]
	v_fma_f32 v159, -v130, v134, 1.0
	v_fmac_f32_e32 v134, v159, v134
	v_div_scale_f32 v159, vcc, 1.0, v129, 1.0
	v_mul_f32_e32 v165, v159, v134
	v_fma_f32 v172, -v130, v165, v159
	v_fmac_f32_e32 v165, v172, v134
	v_fma_f32 v130, -v130, v165, v159
	v_div_fmas_f32 v130, v130, v134, v165
	v_div_fixup_f32 v129, v130, v129, 1.0
	v_div_scale_f32 v130, s[0:1], v128, v128, 1.0
	v_rcp_f32_e32 v134, v130
	s_nop 0
	v_fma_f32 v159, -v130, v134, 1.0
	v_fmac_f32_e32 v134, v159, v134
	v_div_scale_f32 v159, vcc, 1.0, v128, 1.0
	v_mul_f32_e32 v165, v159, v134
	v_fma_f32 v172, -v130, v165, v159
	v_fmac_f32_e32 v165, v172, v134
	v_fma_f32 v130, -v130, v165, v159
	v_div_fmas_f32 v130, v130, v134, v165
	v_div_fixup_f32 v128, v130, v128, 1.0
	v_pk_fma_f32 v[122:123], v[128:129], v[124:125], v[122:123]
	v_cvt_f32_f16_e32 v124, v131
	v_cvt_f32_f16_sdwa v125, v131 dst_sel:DWORD dst_unused:UNUSED_PAD src0_sel:WORD_1
	v_pk_add_f32 v[130:131], v[170:171], 1.0 op_sel_hi:[1,0]
	v_cvt_pk_f16_f32 v122, v122, v123
	v_div_scale_f32 v123, s[0:1], v131, v131, 1.0
	v_rcp_f32_e32 v134, v123
	v_cvt_f32_f16_e32 v128, v135
	v_cvt_f32_f16_sdwa v129, v135 dst_sel:DWORD dst_unused:UNUSED_PAD src0_sel:WORD_1
	v_fma_f32 v135, -v123, v134, 1.0
	v_fmac_f32_e32 v134, v135, v134
	v_div_scale_f32 v135, vcc, 1.0, v131, 1.0
	v_mul_f32_e32 v159, v135, v134
	v_fma_f32 v165, -v123, v159, v135
	v_fmac_f32_e32 v159, v165, v134
	v_fma_f32 v123, -v123, v159, v135
	v_div_fmas_f32 v123, v123, v134, v159
	v_div_fixup_f32 v131, v123, v131, 1.0
	v_div_scale_f32 v123, s[0:1], v130, v130, 1.0
	v_rcp_f32_e32 v134, v123
	v_pk_add_f32 v[128:129], v[128:129], v[124:125] neg_lo:[0,1] neg_hi:[0,1]
	v_fma_f32 v135, -v123, v134, 1.0
	v_fmac_f32_e32 v134, v135, v134
	v_div_scale_f32 v135, vcc, 1.0, v130, 1.0
	v_mul_f32_e32 v159, v135, v134
	v_fma_f32 v165, -v123, v159, v135
	v_fmac_f32_e32 v159, v165, v134
	v_fma_f32 v123, -v123, v159, v135
	v_div_fmas_f32 v123, v123, v134, v159
	v_div_fixup_f32 v130, v123, v130, 1.0
	v_pk_fma_f32 v[124:125], v[130:131], v[128:129], v[124:125]
	v_pk_add_f32 v[130:131], v[144:145], 1.0 op_sel_hi:[1,0]
	v_cvt_pk_f16_f32 v123, v124, v125
	v_cvt_f32_f16_e32 v124, v132
	v_cvt_f32_f16_sdwa v125, v132 dst_sel:DWORD dst_unused:UNUSED_PAD src0_sel:WORD_1
	v_div_scale_f32 v132, s[0:1], v131, v131, 1.0
	v_rcp_f32_e32 v134, v132
	v_cvt_f32_f16_e32 v128, v136
	v_cvt_f32_f16_sdwa v129, v136 dst_sel:DWORD dst_unused:UNUSED_PAD src0_sel:WORD_1
	v_fma_f32 v135, -v132, v134, 1.0
	v_fmac_f32_e32 v134, v135, v134
	v_div_scale_f32 v135, vcc, 1.0, v131, 1.0
	v_mul_f32_e32 v136, v135, v134
	v_fma_f32 v144, -v132, v136, v135
	v_fmac_f32_e32 v136, v144, v134
	v_fma_f32 v132, -v132, v136, v135
	v_div_fmas_f32 v132, v132, v134, v136
	v_div_fixup_f32 v131, v132, v131, 1.0
	v_div_scale_f32 v132, s[0:1], v130, v130, 1.0
	v_rcp_f32_e32 v134, v132
	v_pk_add_f32 v[128:129], v[128:129], v[124:125] neg_lo:[0,1] neg_hi:[0,1]
	v_fma_f32 v135, -v132, v134, 1.0
	v_fmac_f32_e32 v134, v135, v134
	v_div_scale_f32 v135, vcc, 1.0, v130, 1.0
	v_mul_f32_e32 v136, v135, v134
	v_fma_f32 v144, -v132, v136, v135
	v_fmac_f32_e32 v136, v144, v134
	v_fma_f32 v132, -v132, v136, v135
	v_div_fmas_f32 v132, v132, v134, v136
	v_div_fixup_f32 v130, v132, v130, 1.0
	v_pk_fma_f32 v[124:125], v[130:131], v[128:129], v[124:125]
	v_cvt_f32_f16_e32 v128, v133
	v_cvt_pk_f16_f32 v124, v124, v125
	v_div_scale_f32 v125, s[0:1], v127, v127, 1.0
	v_rcp_f32_e32 v132, v125
	v_cvt_f32_f16_sdwa v129, v133 dst_sel:DWORD dst_unused:UNUSED_PAD src0_sel:WORD_1
	v_cvt_f32_f16_e32 v130, v137
	v_cvt_f32_f16_sdwa v131, v137 dst_sel:DWORD dst_unused:UNUSED_PAD src0_sel:WORD_1
	v_fma_f32 v133, -v125, v132, 1.0
	v_fmac_f32_e32 v132, v133, v132
	v_div_scale_f32 v133, vcc, 1.0, v127, 1.0
; __device__ __forceinline__ float sigmoidf_(float x) { return 1.0f / (1.0f + __expf(-x)); }
;     template <int GI>
;     __device__ __forceinline__ void body(const f32x4 (&acc)[2][2][4][2], int row0, int colt) const {
;     ...
;                         *(u32x4*)(Gb + row * DM + c) = pack8(x0, x1);
;                     } else {
;                         h16* vp = C1 + row * LDC1 + 4096 + c;
;                         const h16x8 vv = *(const h16x8*)vp; const h16x8 vf = *(const h16x8*)(VF + row * DM + c);
;                         f32x4 o0, o1;
; #pragma unroll
;                         for (int j = 0; j < 4; ++j) { float v = (float)vv[j], f = (float)vf[j]; o0[j] = v + (f - v) * sigmoidf_(x0[j]); v = (float)vv[4 + j]; f = (float)vf[4 + j]; o1[j] = v + (f - v) * sigmoidf_(x1[j]); }
;                         *(u32x4*)vp = pack8(o0, o1);
;                     }
;                     __builtin_amdgcn_sched_barrier(0);
	v_mul_f32_e32 v134, v133, v132
	v_fma_f32 v135, -v125, v134, v133
	v_fmac_f32_e32 v134, v135, v132
	v_fma_f32 v125, -v125, v134, v133
	v_div_fmas_f32 v125, v125, v132, v134
	v_div_fixup_f32 v127, v125, v127, 1.0
	v_div_scale_f32 v125, s[0:1], v126, v126, 1.0
	v_rcp_f32_e32 v132, v125
	v_pk_add_f32 v[130:131], v[130:131], v[128:129] neg_lo:[0,1] neg_hi:[0,1]
	v_fma_f32 v133, -v125, v132, 1.0
	v_fmac_f32_e32 v132, v133, v132
	v_div_scale_f32 v133, vcc, 1.0, v126, 1.0
	v_mul_f32_e32 v134, v133, v132
	v_fma_f32 v135, -v125, v134, v133
	v_fmac_f32_e32 v134, v135, v132
	v_fma_f32 v125, -v125, v134, v133
	v_div_fmas_f32 v125, v125, v132, v134
	v_div_fixup_f32 v126, v125, v126, 1.0
	v_pk_fma_f32 v[126:127], v[126:127], v[130:131], v[128:129]
	s_nop 0
	v_cvt_pk_f16_f32 v125, v126, v127
	global_store_dwordx4 v[142:143], v[122:125], off
	v_or_b32_e32 v126, 32, v164
	v_ashrrev_i32_e32 v127, 31, v126
	v_mad_i64_i32 v[122:123], s[0:1], v126, s5, v[168:169]
	v_lshl_add_u64 v[130:131], v[122:123], 0, s[90:91]
	v_lshlrev_b64 v[126:127], 12, v[126:127]
	v_lshl_add_u64 v[134:135], v[130:131], 0, v[166:167]
	v_lshl_add_u64 v[126:127], s[2:3], 0, v[126:127]
	global_load_dwordx4 v[122:125], v[134:135], off
	v_lshl_add_u64 v[132:133], v[126:127], 0, v[166:167]
	global_load_dwordx4 v[126:129], v[132:133], off
	v_add_f32_e32 v114, v114, v82
	v_mul_f32_e32 v114, 0xbfb8aa3b, v114
	v_exp_f32_e32 v136, v114
	v_add_f32_e32 v114, v119, v87
	v_mul_f32_e32 v114, 0xbfb8aa3b, v114
	v_exp_f32_e32 v145, v114
	v_add_f32_e32 v114, v115, v83
	v_mul_f32_e32 v114, 0xbfb8aa3b, v114
	v_exp_f32_e32 v137, v114
	v_add_f32_e32 v114, v120, v88
	v_add_f32_e32 v118, v118, v86
	v_mul_f32_e32 v114, 0xbfb8aa3b, v114
	v_mul_f32_e32 v118, 0xbfb8aa3b, v118
	v_exp_f32_e32 v142, v114
	v_add_f32_e32 v114, v116, v84
	v_exp_f32_e32 v144, v118
	v_mul_f32_e32 v114, 0xbfb8aa3b, v114
	v_exp_f32_e32 v118, v114
	v_add_f32_e32 v114, v121, v89
	v_mul_f32_e32 v114, 0xbfb8aa3b, v114
	v_exp_f32_e32 v143, v114
	v_add_f32_e32 v114, v117, v85
	v_mul_f32_e32 v114, 0xbfb8aa3b, v114
	v_pk_add_f32 v[120:121], v[144:145], 1.0 op_sel_hi:[1,0]
	v_exp_f32_e32 v119, v114
	s_waitcnt vmcnt(0)
	v_cvt_f32_f16_e32 v114, v122
	v_cvt_f32_f16_sdwa v115, v122 dst_sel:DWORD dst_unused:UNUSED_PAD src0_sel:WORD_1
	v_div_scale_f32 v122, s[0:1], v121, v121, 1.0
	v_cvt_f32_f16_e32 v116, v126
	v_cvt_f32_f16_sdwa v117, v126 dst_sel:DWORD dst_unused:UNUSED_PAD src0_sel:WORD_1
	v_rcp_f32_e32 v126, v122
	v_pk_add_f32 v[118:119], v[118:119], 1.0 op_sel_hi:[1,0]
	v_pk_add_f32 v[116:117], v[116:117], v[114:115] neg_lo:[0,1] neg_hi:[0,1]
	v_fma_f32 v144, -v122, v126, 1.0
	v_fmac_f32_e32 v126, v144, v126
	v_div_scale_f32 v144, vcc, 1.0, v121, 1.0
	v_mul_f32_e32 v145, v144, v126
	v_fma_f32 v159, -v122, v145, v144
	v_fmac_f32_e32 v145, v159, v126
	v_fma_f32 v122, -v122, v145, v144
	v_div_fmas_f32 v122, v122, v126, v145
	v_div_fixup_f32 v121, v122, v121, 1.0
	v_div_scale_f32 v122, s[0:1], v120, v120, 1.0
	v_rcp_f32_e32 v126, v122
	s_nop 0
	v_fma_f32 v144, -v122, v126, 1.0
	v_fmac_f32_e32 v126, v144, v126
	v_div_scale_f32 v144, vcc, 1.0, v120, 1.0
	v_mul_f32_e32 v145, v144, v126
	v_fma_f32 v159, -v122, v145, v144
	v_fmac_f32_e32 v145, v159, v126
	v_fma_f32 v122, -v122, v145, v144
	v_div_fmas_f32 v122, v122, v126, v145
	v_div_fixup_f32 v120, v122, v120, 1.0
	v_pk_fma_f32 v[114:115], v[120:121], v[116:117], v[114:115]
	v_cvt_f32_f16_e32 v116, v123
	v_cvt_f32_f16_sdwa v117, v123 dst_sel:DWORD dst_unused:UNUSED_PAD src0_sel:WORD_1
	v_pk_add_f32 v[122:123], v[142:143], 1.0 op_sel_hi:[1,0]
	v_cvt_pk_f16_f32 v114, v114, v115
	v_div_scale_f32 v115, s[0:1], v123, v123, 1.0
	v_rcp_f32_e32 v126, v115
	v_cvt_f32_f16_e32 v120, v127
	v_cvt_f32_f16_sdwa v121, v127 dst_sel:DWORD dst_unused:UNUSED_PAD src0_sel:WORD_1
	v_fma_f32 v127, -v115, v126, 1.0
	v_fmac_f32_e32 v126, v127, v126
	v_div_scale_f32 v127, vcc, 1.0, v123, 1.0
	v_mul_f32_e32 v142, v127, v126
	v_fma_f32 v143, -v115, v142, v127
	v_fmac_f32_e32 v142, v143, v126
	v_fma_f32 v115, -v115, v142, v127
	v_div_fmas_f32 v115, v115, v126, v142
	v_div_fixup_f32 v123, v115, v123, 1.0
	v_div_scale_f32 v115, s[0:1], v122, v122, 1.0
	v_rcp_f32_e32 v126, v115
	v_pk_add_f32 v[120:121], v[120:121], v[116:117] neg_lo:[0,1] neg_hi:[0,1]
	v_fma_f32 v127, -v115, v126, 1.0
	v_fmac_f32_e32 v126, v127, v126
	v_div_scale_f32 v127, vcc, 1.0, v122, 1.0
	v_mul_f32_e32 v142, v127, v126
	v_fma_f32 v143, -v115, v142, v127
	v_fmac_f32_e32 v142, v143, v126
	v_fma_f32 v115, -v115, v142, v127
	v_div_fmas_f32 v115, v115, v126, v142
	v_div_fixup_f32 v122, v115, v122, 1.0
	v_pk_fma_f32 v[116:117], v[122:123], v[120:121], v[116:117]
	v_pk_add_f32 v[122:123], v[136:137], 1.0 op_sel_hi:[1,0]
	v_cvt_pk_f16_f32 v115, v116, v117
	v_cvt_f32_f16_e32 v116, v124
	v_cvt_f32_f16_sdwa v117, v124 dst_sel:DWORD dst_unused:UNUSED_PAD src0_sel:WORD_1
	v_div_scale_f32 v124, s[0:1], v123, v123, 1.0
	v_rcp_f32_e32 v126, v124
	v_cvt_f32_f16_e32 v120, v128
	v_cvt_f32_f16_sdwa v121, v128 dst_sel:DWORD dst_unused:UNUSED_PAD src0_sel:WORD_1
	v_fma_f32 v127, -v124, v126, 1.0
	v_fmac_f32_e32 v126, v127, v126
	v_div_scale_f32 v127, vcc, 1.0, v123, 1.0
	v_mul_f32_e32 v128, v127, v126
	v_fma_f32 v136, -v124, v128, v127
	v_fmac_f32_e32 v128, v136, v126
	v_fma_f32 v124, -v124, v128, v127
	v_div_fmas_f32 v124, v124, v126, v128
	v_div_fixup_f32 v123, v124, v123, 1.0
	v_div_scale_f32 v124, s[0:1], v122, v122, 1.0
	v_rcp_f32_e32 v126, v124
	v_pk_add_f32 v[120:121], v[120:121], v[116:117] neg_lo:[0,1] neg_hi:[0,1]
	v_fma_f32 v127, -v124, v126, 1.0
	v_fmac_f32_e32 v126, v127, v126
	v_div_scale_f32 v127, vcc, 1.0, v122, 1.0
	v_mul_f32_e32 v128, v127, v126
	v_fma_f32 v136, -v124, v128, v127
; __device__ __forceinline__ float sigmoidf_(float x) { return 1.0f / (1.0f + __expf(-x)); }
;     template <int GI>
;     __device__ __forceinline__ void body(const f32x4 (&acc)[2][2][4][2], int row0, int colt) const {
;     ...
;                         *(u32x4*)(Gb + row * DM + c) = pack8(x0, x1);
;                     } else {
;                         h16* vp = C1 + row * LDC1 + 4096 + c;
;                         const h16x8 vv = *(const h16x8*)vp; const h16x8 vf = *(const h16x8*)(VF + row * DM + c);
;                         f32x4 o0, o1;
; #pragma unroll
;                         for (int j = 0; j < 4; ++j) { float v = (float)vv[j], f = (float)vf[j]; o0[j] = v + (f - v) * sigmoidf_(x0[j]); v = (float)vv[4 + j]; f = (float)vf[4 + j]; o1[j] = v + (f - v) * sigmoidf_(x1[j]); }
;                         *(u32x4*)vp = pack8(o0, o1);
;                     }
;                     __builtin_amdgcn_sched_barrier(0);
	v_fmac_f32_e32 v128, v136, v126
	v_fma_f32 v124, -v124, v128, v127
	v_div_fmas_f32 v124, v124, v126, v128
	v_div_fixup_f32 v122, v124, v122, 1.0
	v_pk_fma_f32 v[116:117], v[122:123], v[120:121], v[116:117]
	v_cvt_f32_f16_e32 v120, v125
	v_cvt_pk_f16_f32 v116, v116, v117
	v_div_scale_f32 v117, s[0:1], v119, v119, 1.0
	v_rcp_f32_e32 v124, v117
	v_cvt_f32_f16_sdwa v121, v125 dst_sel:DWORD dst_unused:UNUSED_PAD src0_sel:WORD_1
	v_cvt_f32_f16_e32 v122, v129
	v_cvt_f32_f16_sdwa v123, v129 dst_sel:DWORD dst_unused:UNUSED_PAD src0_sel:WORD_1
	v_fma_f32 v125, -v117, v124, 1.0
	v_fmac_f32_e32 v124, v125, v124
	v_div_scale_f32 v125, vcc, 1.0, v119, 1.0
	v_mul_f32_e32 v126, v125, v124
	v_fma_f32 v127, -v117, v126, v125
	v_fmac_f32_e32 v126, v127, v124
	v_fma_f32 v117, -v117, v126, v125
	v_div_fmas_f32 v117, v117, v124, v126
	v_div_fixup_f32 v119, v117, v119, 1.0
	v_div_scale_f32 v117, s[0:1], v118, v118, 1.0
	v_rcp_f32_e32 v124, v117
	v_pk_add_f32 v[122:123], v[122:123], v[120:121] neg_lo:[0,1] neg_hi:[0,1]
	v_fma_f32 v125, -v117, v124, 1.0
	v_fmac_f32_e32 v124, v125, v124
	v_div_scale_f32 v125, vcc, 1.0, v118, 1.0
	v_mul_f32_e32 v126, v125, v124
	v_fma_f32 v127, -v117, v126, v125
	v_fmac_f32_e32 v126, v127, v124
	v_fma_f32 v117, -v117, v126, v125
	v_div_fmas_f32 v117, v117, v124, v126
	v_div_fixup_f32 v118, v117, v118, 1.0
	v_pk_fma_f32 v[118:119], v[118:119], v[122:123], v[120:121]
	s_nop 0
	v_cvt_pk_f16_f32 v117, v118, v119
	global_store_dwordx4 v[134:135], v[114:117], off
	v_or_b32_e32 v118, 48, v164
	v_ashrrev_i32_e32 v119, 31, v118
	v_mad_i64_i32 v[114:115], s[0:1], v118, s5, v[168:169]
	v_lshl_add_u64 v[122:123], v[114:115], 0, s[90:91]
	v_lshlrev_b64 v[118:119], 12, v[118:119]
	v_lshl_add_u64 v[126:127], v[122:123], 0, v[166:167]
	v_lshl_add_u64 v[118:119], s[2:3], 0, v[118:119]
	global_load_dwordx4 v[114:117], v[126:127], off
	v_lshl_add_u64 v[124:125], v[118:119], 0, v[166:167]
	global_load_dwordx4 v[118:121], v[124:125], off
	v_add_f32_e32 v106, v106, v82
	v_mul_f32_e32 v106, 0xbfb8aa3b, v106
	v_exp_f32_e32 v128, v106
	v_add_f32_e32 v106, v111, v87
	v_mul_f32_e32 v106, 0xbfb8aa3b, v106
	v_exp_f32_e32 v137, v106
	v_add_f32_e32 v106, v107, v83
	v_mul_f32_e32 v106, 0xbfb8aa3b, v106
	v_exp_f32_e32 v129, v106
	v_add_f32_e32 v106, v112, v88
	v_add_f32_e32 v110, v110, v86
	v_mul_f32_e32 v106, 0xbfb8aa3b, v106
	v_mul_f32_e32 v110, 0xbfb8aa3b, v110
	v_exp_f32_e32 v134, v106
	v_add_f32_e32 v106, v108, v84
	v_exp_f32_e32 v136, v110
	v_mul_f32_e32 v106, 0xbfb8aa3b, v106
	v_exp_f32_e32 v110, v106
	v_add_f32_e32 v106, v113, v89
	v_mul_f32_e32 v106, 0xbfb8aa3b, v106
	v_exp_f32_e32 v135, v106
	v_add_f32_e32 v106, v109, v85
	v_mul_f32_e32 v106, 0xbfb8aa3b, v106
	v_pk_add_f32 v[112:113], v[136:137], 1.0 op_sel_hi:[1,0]
	v_exp_f32_e32 v111, v106
	s_waitcnt vmcnt(0)
	v_cvt_f32_f16_e32 v106, v114
	v_cvt_f32_f16_sdwa v107, v114 dst_sel:DWORD dst_unused:UNUSED_PAD src0_sel:WORD_1
	v_div_scale_f32 v114, s[0:1], v113, v113, 1.0
	v_cvt_f32_f16_e32 v108, v118
	v_cvt_f32_f16_sdwa v109, v118 dst_sel:DWORD dst_unused:UNUSED_PAD src0_sel:WORD_1
	v_rcp_f32_e32 v118, v114
	v_pk_add_f32 v[110:111], v[110:111], 1.0 op_sel_hi:[1,0]
	v_pk_add_f32 v[108:109], v[108:109], v[106:107] neg_lo:[0,1] neg_hi:[0,1]
	v_fma_f32 v136, -v114, v118, 1.0
	v_fmac_f32_e32 v118, v136, v118
	v_div_scale_f32 v136, vcc, 1.0, v113, 1.0
	v_mul_f32_e32 v137, v136, v118
	v_fma_f32 v142, -v114, v137, v136
	v_fmac_f32_e32 v137, v142, v118
	v_fma_f32 v114, -v114, v137, v136
	v_div_fmas_f32 v114, v114, v118, v137
	v_div_fixup_f32 v113, v114, v113, 1.0
	v_div_scale_f32 v114, s[0:1], v112, v112, 1.0
	v_rcp_f32_e32 v118, v114
	s_nop 0
	v_fma_f32 v136, -v114, v118, 1.0
	v_fmac_f32_e32 v118, v136, v118
	v_div_scale_f32 v136, vcc, 1.0, v112, 1.0
	v_mul_f32_e32 v137, v136, v118
	v_fma_f32 v142, -v114, v137, v136
	v_fmac_f32_e32 v137, v142, v118
	v_fma_f32 v114, -v114, v137, v136
	v_div_fmas_f32 v114, v114, v118, v137
	v_div_fixup_f32 v112, v114, v112, 1.0
	v_pk_fma_f32 v[106:107], v[112:113], v[108:109], v[106:107]
	v_cvt_f32_f16_e32 v108, v115
	v_cvt_f32_f16_sdwa v109, v115 dst_sel:DWORD dst_unused:UNUSED_PAD src0_sel:WORD_1
	v_pk_add_f32 v[114:115], v[134:135], 1.0 op_sel_hi:[1,0]
	v_cvt_pk_f16_f32 v106, v106, v107
	v_div_scale_f32 v107, s[0:1], v115, v115, 1.0
	v_rcp_f32_e32 v118, v107
	v_cvt_f32_f16_e32 v112, v119
	v_cvt_f32_f16_sdwa v113, v119 dst_sel:DWORD dst_unused:UNUSED_PAD src0_sel:WORD_1
	v_fma_f32 v119, -v107, v118, 1.0
	v_fmac_f32_e32 v118, v119, v118
	v_div_scale_f32 v119, vcc, 1.0, v115, 1.0
	v_mul_f32_e32 v134, v119, v118
	v_fma_f32 v135, -v107, v134, v119
	v_fmac_f32_e32 v134, v135, v118
	v_fma_f32 v107, -v107, v134, v119
	v_div_fmas_f32 v107, v107, v118, v134
	v_div_fixup_f32 v115, v107, v115, 1.0
	v_div_scale_f32 v107, s[0:1], v114, v114, 1.0
	v_rcp_f32_e32 v118, v107
	v_pk_add_f32 v[112:113], v[112:113], v[108:109] neg_lo:[0,1] neg_hi:[0,1]
	v_fma_f32 v119, -v107, v118, 1.0
	v_fmac_f32_e32 v118, v119, v118
	v_div_scale_f32 v119, vcc, 1.0, v114, 1.0
	v_mul_f32_e32 v134, v119, v118
	v_fma_f32 v135, -v107, v134, v119
	v_fmac_f32_e32 v134, v135, v118
	v_fma_f32 v107, -v107, v134, v119
	v_div_fmas_f32 v107, v107, v118, v134
	v_div_fixup_f32 v114, v107, v114, 1.0
	v_pk_fma_f32 v[108:109], v[114:115], v[112:113], v[108:109]
	v_pk_add_f32 v[114:115], v[128:129], 1.0 op_sel_hi:[1,0]
	v_cvt_pk_f16_f32 v107, v108, v109
	v_cvt_f32_f16_e32 v108, v116
	v_cvt_f32_f16_sdwa v109, v116 dst_sel:DWORD dst_unused:UNUSED_PAD src0_sel:WORD_1
	v_div_scale_f32 v116, s[0:1], v115, v115, 1.0
	v_rcp_f32_e32 v118, v116
	v_cvt_f32_f16_e32 v112, v120
	v_cvt_f32_f16_sdwa v113, v120 dst_sel:DWORD dst_unused:UNUSED_PAD src0_sel:WORD_1
; __device__ __forceinline__ float sigmoidf_(float x) { return 1.0f / (1.0f + __expf(-x)); }
;     template <int GI>
;     __device__ __forceinline__ void body(const f32x4 (&acc)[2][2][4][2], int row0, int colt) const {
;     ...
;                         *(u32x4*)(Gb + row * DM + c) = pack8(x0, x1);
;                     } else {
;                         h16* vp = C1 + row * LDC1 + 4096 + c;
;                         const h16x8 vv = *(const h16x8*)vp; const h16x8 vf = *(const h16x8*)(VF + row * DM + c);
;                         f32x4 o0, o1;
; #pragma unroll
;                         for (int j = 0; j < 4; ++j) { float v = (float)vv[j], f = (float)vf[j]; o0[j] = v + (f - v) * sigmoidf_(x0[j]); v = (float)vv[4 + j]; f = (float)vf[4 + j]; o1[j] = v + (f - v) * sigmoidf_(x1[j]); }
;                         *(u32x4*)vp = pack8(o0, o1);
;                     }
;                     __builtin_amdgcn_sched_barrier(0);
	v_fma_f32 v119, -v116, v118, 1.0
	v_fmac_f32_e32 v118, v119, v118
	v_div_scale_f32 v119, vcc, 1.0, v115, 1.0
	v_mul_f32_e32 v120, v119, v118
	v_fma_f32 v128, -v116, v120, v119
	v_fmac_f32_e32 v120, v128, v118
	v_fma_f32 v116, -v116, v120, v119
	v_div_fmas_f32 v116, v116, v118, v120
	v_div_fixup_f32 v115, v116, v115, 1.0
	v_div_scale_f32 v116, s[0:1], v114, v114, 1.0
	v_rcp_f32_e32 v118, v116
	v_pk_add_f32 v[112:113], v[112:113], v[108:109] neg_lo:[0,1] neg_hi:[0,1]
	v_fma_f32 v119, -v116, v118, 1.0
	v_fmac_f32_e32 v118, v119, v118
	v_div_scale_f32 v119, vcc, 1.0, v114, 1.0
	v_mul_f32_e32 v120, v119, v118
	v_fma_f32 v128, -v116, v120, v119
	v_fmac_f32_e32 v120, v128, v118
	v_fma_f32 v116, -v116, v120, v119
	v_div_fmas_f32 v116, v116, v118, v120
	v_div_fixup_f32 v114, v116, v114, 1.0
	v_pk_fma_f32 v[108:109], v[114:115], v[112:113], v[108:109]
	v_cvt_f32_f16_e32 v112, v117
	v_cvt_pk_f16_f32 v108, v108, v109
	v_div_scale_f32 v109, s[0:1], v111, v111, 1.0
	v_rcp_f32_e32 v116, v109
	v_cvt_f32_f16_sdwa v113, v117 dst_sel:DWORD dst_unused:UNUSED_PAD src0_sel:WORD_1
	v_cvt_f32_f16_e32 v114, v121
	v_cvt_f32_f16_sdwa v115, v121 dst_sel:DWORD dst_unused:UNUSED_PAD src0_sel:WORD_1
	v_fma_f32 v117, -v109, v116, 1.0
	v_fmac_f32_e32 v116, v117, v116
	v_div_scale_f32 v117, vcc, 1.0, v111, 1.0
	v_mul_f32_e32 v118, v117, v116
	v_fma_f32 v119, -v109, v118, v117
	v_fmac_f32_e32 v118, v119, v116
	v_fma_f32 v109, -v109, v118, v117
	v_div_fmas_f32 v109, v109, v116, v118
	v_div_fixup_f32 v111, v109, v111, 1.0
	v_div_scale_f32 v109, s[0:1], v110, v110, 1.0
	v_rcp_f32_e32 v116, v109
	v_pk_add_f32 v[114:115], v[114:115], v[112:113] neg_lo:[0,1] neg_hi:[0,1]
	v_fma_f32 v117, -v109, v116, 1.0
	v_fmac_f32_e32 v116, v117, v116
	v_div_scale_f32 v117, vcc, 1.0, v110, 1.0
	v_mul_f32_e32 v118, v117, v116
	v_fma_f32 v119, -v109, v118, v117
	v_fmac_f32_e32 v118, v119, v116
	v_fma_f32 v109, -v109, v118, v117
	v_div_fmas_f32 v109, v109, v116, v118
	v_div_fixup_f32 v110, v109, v110, 1.0
	v_pk_fma_f32 v[110:111], v[110:111], v[114:115], v[112:113]
	s_nop 0
	v_cvt_pk_f16_f32 v109, v110, v111
	global_store_dwordx4 v[126:127], v[106:109], off
	v_add_u32_e32 v110, 0x80, v164
	v_ashrrev_i32_e32 v111, 31, v110
	v_mad_i64_i32 v[106:107], s[0:1], v110, s5, v[168:169]
	v_lshl_add_u64 v[114:115], v[106:107], 0, s[90:91]
	v_lshlrev_b64 v[110:111], 12, v[110:111]
	v_lshl_add_u64 v[118:119], v[114:115], 0, v[166:167]
	v_lshl_add_u64 v[110:111], s[2:3], 0, v[110:111]
	global_load_dwordx4 v[106:109], v[118:119], off
	v_lshl_add_u64 v[116:117], v[110:111], 0, v[166:167]
	global_load_dwordx4 v[110:113], v[116:117], off
	v_add_f32_e32 v98, v98, v82
	v_mul_f32_e32 v98, 0xbfb8aa3b, v98
	v_exp_f32_e32 v120, v98
	v_add_f32_e32 v98, v103, v87
	v_mul_f32_e32 v98, 0xbfb8aa3b, v98
	v_exp_f32_e32 v129, v98
	v_add_f32_e32 v98, v99, v83
	v_mul_f32_e32 v98, 0xbfb8aa3b, v98
	v_exp_f32_e32 v121, v98
	v_add_f32_e32 v98, v104, v88
	v_add_f32_e32 v102, v102, v86
	v_mul_f32_e32 v98, 0xbfb8aa3b, v98
	v_mul_f32_e32 v102, 0xbfb8aa3b, v102
	v_exp_f32_e32 v126, v98
	v_add_f32_e32 v98, v100, v84
	v_exp_f32_e32 v128, v102
	v_mul_f32_e32 v98, 0xbfb8aa3b, v98
	v_exp_f32_e32 v102, v98
	v_add_f32_e32 v98, v105, v89
	v_mul_f32_e32 v98, 0xbfb8aa3b, v98
	v_exp_f32_e32 v127, v98
	v_add_f32_e32 v98, v101, v85
	v_mul_f32_e32 v98, 0xbfb8aa3b, v98
	v_pk_add_f32 v[104:105], v[128:129], 1.0 op_sel_hi:[1,0]
	v_exp_f32_e32 v103, v98
	s_waitcnt vmcnt(0)
	v_cvt_f32_f16_e32 v98, v106
	v_cvt_f32_f16_sdwa v99, v106 dst_sel:DWORD dst_unused:UNUSED_PAD src0_sel:WORD_1
	v_div_scale_f32 v106, s[0:1], v105, v105, 1.0
	v_cvt_f32_f16_e32 v100, v110
	v_cvt_f32_f16_sdwa v101, v110 dst_sel:DWORD dst_unused:UNUSED_PAD src0_sel:WORD_1
	v_rcp_f32_e32 v110, v106
	v_pk_add_f32 v[102:103], v[102:103], 1.0 op_sel_hi:[1,0]
	v_pk_add_f32 v[100:101], v[100:101], v[98:99] neg_lo:[0,1] neg_hi:[0,1]
	v_fma_f32 v128, -v106, v110, 1.0
	v_fmac_f32_e32 v110, v128, v110
	v_div_scale_f32 v128, vcc, 1.0, v105, 1.0
	v_mul_f32_e32 v129, v128, v110
	v_fma_f32 v134, -v106, v129, v128
	v_fmac_f32_e32 v129, v134, v110
	v_fma_f32 v106, -v106, v129, v128
	v_div_fmas_f32 v106, v106, v110, v129
	v_div_fixup_f32 v105, v106, v105, 1.0
	v_div_scale_f32 v106, s[0:1], v104, v104, 1.0
	v_rcp_f32_e32 v110, v106
	s_nop 0
	v_fma_f32 v128, -v106, v110, 1.0
	v_fmac_f32_e32 v110, v128, v110
	v_div_scale_f32 v128, vcc, 1.0, v104, 1.0
	v_mul_f32_e32 v129, v128, v110
	v_fma_f32 v134, -v106, v129, v128
	v_fmac_f32_e32 v129, v134, v110
	v_fma_f32 v106, -v106, v129, v128
	v_div_fmas_f32 v106, v106, v110, v129
	v_div_fixup_f32 v104, v106, v104, 1.0
	v_pk_fma_f32 v[98:99], v[104:105], v[100:101], v[98:99]
	v_cvt_f32_f16_e32 v100, v107
	v_cvt_f32_f16_sdwa v101, v107 dst_sel:DWORD dst_unused:UNUSED_PAD src0_sel:WORD_1
	v_pk_add_f32 v[106:107], v[126:127], 1.0 op_sel_hi:[1,0]
	v_cvt_pk_f16_f32 v98, v98, v99
	v_div_scale_f32 v99, s[0:1], v107, v107, 1.0
	v_rcp_f32_e32 v110, v99
	v_cvt_f32_f16_e32 v104, v111
	v_cvt_f32_f16_sdwa v105, v111 dst_sel:DWORD dst_unused:UNUSED_PAD src0_sel:WORD_1
	v_fma_f32 v111, -v99, v110, 1.0
	v_fmac_f32_e32 v110, v111, v110
	v_div_scale_f32 v111, vcc, 1.0, v107, 1.0
	v_mul_f32_e32 v126, v111, v110
	v_fma_f32 v127, -v99, v126, v111
	v_fmac_f32_e32 v126, v127, v110
	v_fma_f32 v99, -v99, v126, v111
	v_div_fmas_f32 v99, v99, v110, v126
	v_div_fixup_f32 v107, v99, v107, 1.0
	v_div_scale_f32 v99, s[0:1], v106, v106, 1.0
	v_rcp_f32_e32 v110, v99
	v_pk_add_f32 v[104:105], v[104:105], v[100:101] neg_lo:[0,1] neg_hi:[0,1]
	v_fma_f32 v111, -v99, v110, 1.0
	v_fmac_f32_e32 v110, v111, v110
	v_div_scale_f32 v111, vcc, 1.0, v106, 1.0
	v_mul_f32_e32 v126, v111, v110
	v_fma_f32 v127, -v99, v126, v111
; __device__ __forceinline__ float sigmoidf_(float x) { return 1.0f / (1.0f + __expf(-x)); }
;     template <int GI>
;     __device__ __forceinline__ void body(const f32x4 (&acc)[2][2][4][2], int row0, int colt) const {
;     ...
;                         *(u32x4*)(Gb + row * DM + c) = pack8(x0, x1);
;                     } else {
;                         h16* vp = C1 + row * LDC1 + 4096 + c;
;                         const h16x8 vv = *(const h16x8*)vp; const h16x8 vf = *(const h16x8*)(VF + row * DM + c);
;                         f32x4 o0, o1;
; #pragma unroll
;                         for (int j = 0; j < 4; ++j) { float v = (float)vv[j], f = (float)vf[j]; o0[j] = v + (f - v) * sigmoidf_(x0[j]); v = (float)vv[4 + j]; f = (float)vf[4 + j]; o1[j] = v + (f - v) * sigmoidf_(x1[j]); }
;                         *(u32x4*)vp = pack8(o0, o1);
;                     }
;                     __builtin_amdgcn_sched_barrier(0);
	v_fmac_f32_e32 v126, v127, v110
	v_fma_f32 v99, -v99, v126, v111
	v_div_fmas_f32 v99, v99, v110, v126
	v_div_fixup_f32 v106, v99, v106, 1.0
	v_pk_fma_f32 v[100:101], v[106:107], v[104:105], v[100:101]
	v_pk_add_f32 v[106:107], v[120:121], 1.0 op_sel_hi:[1,0]
	v_cvt_pk_f16_f32 v99, v100, v101
	v_cvt_f32_f16_e32 v100, v108
	v_cvt_f32_f16_sdwa v101, v108 dst_sel:DWORD dst_unused:UNUSED_PAD src0_sel:WORD_1
	v_div_scale_f32 v108, s[0:1], v107, v107, 1.0
	v_rcp_f32_e32 v110, v108
	v_cvt_f32_f16_e32 v104, v112
	v_cvt_f32_f16_sdwa v105, v112 dst_sel:DWORD dst_unused:UNUSED_PAD src0_sel:WORD_1
	v_fma_f32 v111, -v108, v110, 1.0
	v_fmac_f32_e32 v110, v111, v110
	v_div_scale_f32 v111, vcc, 1.0, v107, 1.0
	v_mul_f32_e32 v112, v111, v110
	v_fma_f32 v120, -v108, v112, v111
	v_fmac_f32_e32 v112, v120, v110
	v_fma_f32 v108, -v108, v112, v111
	v_div_fmas_f32 v108, v108, v110, v112
	v_div_fixup_f32 v107, v108, v107, 1.0
	v_div_scale_f32 v108, s[0:1], v106, v106, 1.0
	v_rcp_f32_e32 v110, v108
	v_pk_add_f32 v[104:105], v[104:105], v[100:101] neg_lo:[0,1] neg_hi:[0,1]
	v_fma_f32 v111, -v108, v110, 1.0
	v_fmac_f32_e32 v110, v111, v110
	v_div_scale_f32 v111, vcc, 1.0, v106, 1.0
	v_mul_f32_e32 v112, v111, v110
	v_fma_f32 v120, -v108, v112, v111
	v_fmac_f32_e32 v112, v120, v110
	v_fma_f32 v108, -v108, v112, v111
	v_div_fmas_f32 v108, v108, v110, v112
	v_div_fixup_f32 v106, v108, v106, 1.0
	v_pk_fma_f32 v[100:101], v[106:107], v[104:105], v[100:101]
	v_cvt_f32_f16_e32 v104, v109
	v_cvt_pk_f16_f32 v100, v100, v101
	v_div_scale_f32 v101, s[0:1], v103, v103, 1.0
	v_rcp_f32_e32 v108, v101
	v_cvt_f32_f16_sdwa v105, v109 dst_sel:DWORD dst_unused:UNUSED_PAD src0_sel:WORD_1
	v_cvt_f32_f16_e32 v106, v113
	v_cvt_f32_f16_sdwa v107, v113 dst_sel:DWORD dst_unused:UNUSED_PAD src0_sel:WORD_1
	v_fma_f32 v109, -v101, v108, 1.0
	v_fmac_f32_e32 v108, v109, v108
	v_div_scale_f32 v109, vcc, 1.0, v103, 1.0
	v_mul_f32_e32 v110, v109, v108
	v_fma_f32 v111, -v101, v110, v109
	v_fmac_f32_e32 v110, v111, v108
	v_fma_f32 v101, -v101, v110, v109
	v_div_fmas_f32 v101, v101, v108, v110
	v_div_fixup_f32 v103, v101, v103, 1.0
	v_div_scale_f32 v101, s[0:1], v102, v102, 1.0
	v_rcp_f32_e32 v108, v101
	v_pk_add_f32 v[106:107], v[106:107], v[104:105] neg_lo:[0,1] neg_hi:[0,1]
	v_fma_f32 v109, -v101, v108, 1.0
	v_fmac_f32_e32 v108, v109, v108
	v_div_scale_f32 v109, vcc, 1.0, v102, 1.0
	v_mul_f32_e32 v110, v109, v108
	v_fma_f32 v111, -v101, v110, v109
	v_fmac_f32_e32 v110, v111, v108
	v_fma_f32 v101, -v101, v110, v109
	v_div_fmas_f32 v101, v101, v108, v110
	v_div_fixup_f32 v102, v101, v102, 1.0
	v_pk_fma_f32 v[102:103], v[102:103], v[106:107], v[104:105]
	s_nop 0
	v_cvt_pk_f16_f32 v101, v102, v103
	global_store_dwordx4 v[118:119], v[98:101], off
	v_add_u32_e32 v102, 0x90, v164
	v_ashrrev_i32_e32 v103, 31, v102
	v_mad_i64_i32 v[98:99], s[0:1], v102, s5, v[168:169]
	v_lshl_add_u64 v[106:107], v[98:99], 0, s[90:91]
	v_lshlrev_b64 v[102:103], 12, v[102:103]
	v_lshl_add_u64 v[110:111], v[106:107], 0, v[166:167]
	v_lshl_add_u64 v[102:103], s[2:3], 0, v[102:103]
	global_load_dwordx4 v[98:101], v[110:111], off
	v_lshl_add_u64 v[108:109], v[102:103], 0, v[166:167]
	global_load_dwordx4 v[102:105], v[108:109], off
	v_add_f32_e32 v90, v90, v82
	v_mul_f32_e32 v90, 0xbfb8aa3b, v90
	v_exp_f32_e32 v112, v90
	v_add_f32_e32 v90, v95, v87
	v_mul_f32_e32 v90, 0xbfb8aa3b, v90
	v_exp_f32_e32 v121, v90
	v_add_f32_e32 v90, v91, v83
	v_mul_f32_e32 v90, 0xbfb8aa3b, v90
	v_exp_f32_e32 v113, v90
	v_add_f32_e32 v90, v96, v88
	v_add_f32_e32 v94, v94, v86
	v_mul_f32_e32 v90, 0xbfb8aa3b, v90
	v_mul_f32_e32 v94, 0xbfb8aa3b, v94
	v_exp_f32_e32 v118, v90
	v_add_f32_e32 v90, v92, v84
	v_exp_f32_e32 v120, v94
	v_mul_f32_e32 v90, 0xbfb8aa3b, v90
	v_exp_f32_e32 v94, v90
	v_add_f32_e32 v90, v97, v89
	v_mul_f32_e32 v90, 0xbfb8aa3b, v90
	v_exp_f32_e32 v119, v90
	v_add_f32_e32 v90, v93, v85
	v_mul_f32_e32 v90, 0xbfb8aa3b, v90
	v_pk_add_f32 v[96:97], v[120:121], 1.0 op_sel_hi:[1,0]
	v_exp_f32_e32 v95, v90
	s_waitcnt vmcnt(0)
	v_cvt_f32_f16_e32 v90, v98
	v_cvt_f32_f16_sdwa v91, v98 dst_sel:DWORD dst_unused:UNUSED_PAD src0_sel:WORD_1
	v_div_scale_f32 v98, s[0:1], v97, v97, 1.0
	v_cvt_f32_f16_e32 v92, v102
	v_cvt_f32_f16_sdwa v93, v102 dst_sel:DWORD dst_unused:UNUSED_PAD src0_sel:WORD_1
	v_rcp_f32_e32 v102, v98
	v_pk_add_f32 v[94:95], v[94:95], 1.0 op_sel_hi:[1,0]
	v_pk_add_f32 v[92:93], v[92:93], v[90:91] neg_lo:[0,1] neg_hi:[0,1]
	v_fma_f32 v120, -v98, v102, 1.0
	v_fmac_f32_e32 v102, v120, v102
	v_div_scale_f32 v120, vcc, 1.0, v97, 1.0
	v_mul_f32_e32 v121, v120, v102
	v_fma_f32 v126, -v98, v121, v120
	v_fmac_f32_e32 v121, v126, v102
	v_fma_f32 v98, -v98, v121, v120
	v_div_fmas_f32 v98, v98, v102, v121
	v_div_fixup_f32 v97, v98, v97, 1.0
	v_div_scale_f32 v98, s[0:1], v96, v96, 1.0
	v_rcp_f32_e32 v102, v98
	s_nop 0
	v_fma_f32 v120, -v98, v102, 1.0
	v_fmac_f32_e32 v102, v120, v102
	v_div_scale_f32 v120, vcc, 1.0, v96, 1.0
	v_mul_f32_e32 v121, v120, v102
	v_fma_f32 v126, -v98, v121, v120
	v_fmac_f32_e32 v121, v126, v102
	v_fma_f32 v98, -v98, v121, v120
	v_div_fmas_f32 v98, v98, v102, v121
	v_div_fixup_f32 v96, v98, v96, 1.0
	v_pk_fma_f32 v[90:91], v[96:97], v[92:93], v[90:91]
	v_cvt_f32_f16_e32 v92, v99
	v_cvt_f32_f16_sdwa v93, v99 dst_sel:DWORD dst_unused:UNUSED_PAD src0_sel:WORD_1
	v_pk_add_f32 v[98:99], v[118:119], 1.0 op_sel_hi:[1,0]
	v_cvt_pk_f16_f32 v90, v90, v91
	v_div_scale_f32 v91, s[0:1], v99, v99, 1.0
	v_rcp_f32_e32 v102, v91
	v_cvt_f32_f16_e32 v96, v103
	v_cvt_f32_f16_sdwa v97, v103 dst_sel:DWORD dst_unused:UNUSED_PAD src0_sel:WORD_1
	v_fma_f32 v103, -v91, v102, 1.0
	v_fmac_f32_e32 v102, v103, v102
	v_div_scale_f32 v103, vcc, 1.0, v99, 1.0
; __device__ __forceinline__ float sigmoidf_(float x) { return 1.0f / (1.0f + __expf(-x)); }
;     template <int GI>
;     __device__ __forceinline__ void body(const f32x4 (&acc)[2][2][4][2], int row0, int colt) const {
;     ...
;                         *(u32x4*)(Gb + row * DM + c) = pack8(x0, x1);
;                     } else {
;                         h16* vp = C1 + row * LDC1 + 4096 + c;
;                         const h16x8 vv = *(const h16x8*)vp; const h16x8 vf = *(const h16x8*)(VF + row * DM + c);
;                         f32x4 o0, o1;
; #pragma unroll
;                         for (int j = 0; j < 4; ++j) { float v = (float)vv[j], f = (float)vf[j]; o0[j] = v + (f - v) * sigmoidf_(x0[j]); v = (float)vv[4 + j]; f = (float)vf[4 + j]; o1[j] = v + (f - v) * sigmoidf_(x1[j]); }
;                         *(u32x4*)vp = pack8(o0, o1);
;                     }
;                     __builtin_amdgcn_sched_barrier(0);
	v_mul_f32_e32 v118, v103, v102
	v_fma_f32 v119, -v91, v118, v103
	v_fmac_f32_e32 v118, v119, v102
	v_fma_f32 v91, -v91, v118, v103
	v_div_fmas_f32 v91, v91, v102, v118
	v_div_fixup_f32 v99, v91, v99, 1.0
	v_div_scale_f32 v91, s[0:1], v98, v98, 1.0
	v_rcp_f32_e32 v102, v91
	v_pk_add_f32 v[96:97], v[96:97], v[92:93] neg_lo:[0,1] neg_hi:[0,1]
	v_fma_f32 v103, -v91, v102, 1.0
	v_fmac_f32_e32 v102, v103, v102
	v_div_scale_f32 v103, vcc, 1.0, v98, 1.0
	v_mul_f32_e32 v118, v103, v102
	v_fma_f32 v119, -v91, v118, v103
	v_fmac_f32_e32 v118, v119, v102
	v_fma_f32 v91, -v91, v118, v103
	v_div_fmas_f32 v91, v91, v102, v118
	v_div_fixup_f32 v98, v91, v98, 1.0
	v_pk_fma_f32 v[92:93], v[98:99], v[96:97], v[92:93]
	v_pk_add_f32 v[98:99], v[112:113], 1.0 op_sel_hi:[1,0]
	v_cvt_pk_f16_f32 v91, v92, v93
	v_cvt_f32_f16_e32 v92, v100
	v_cvt_f32_f16_sdwa v93, v100 dst_sel:DWORD dst_unused:UNUSED_PAD src0_sel:WORD_1
	v_div_scale_f32 v100, s[0:1], v99, v99, 1.0
	v_rcp_f32_e32 v102, v100
	v_cvt_f32_f16_e32 v96, v104
	v_cvt_f32_f16_sdwa v97, v104 dst_sel:DWORD dst_unused:UNUSED_PAD src0_sel:WORD_1
	v_fma_f32 v103, -v100, v102, 1.0
	v_fmac_f32_e32 v102, v103, v102
	v_div_scale_f32 v103, vcc, 1.0, v99, 1.0
	v_mul_f32_e32 v104, v103, v102
	v_fma_f32 v112, -v100, v104, v103
	v_fmac_f32_e32 v104, v112, v102
	v_fma_f32 v100, -v100, v104, v103
	v_div_fmas_f32 v100, v100, v102, v104
	v_div_fixup_f32 v99, v100, v99, 1.0
	v_div_scale_f32 v100, s[0:1], v98, v98, 1.0
	v_rcp_f32_e32 v102, v100
	v_pk_add_f32 v[96:97], v[96:97], v[92:93] neg_lo:[0,1] neg_hi:[0,1]
	v_fma_f32 v103, -v100, v102, 1.0
	v_fmac_f32_e32 v102, v103, v102
	v_div_scale_f32 v103, vcc, 1.0, v98, 1.0
	v_mul_f32_e32 v104, v103, v102
	v_fma_f32 v112, -v100, v104, v103
	v_fmac_f32_e32 v104, v112, v102
	v_fma_f32 v100, -v100, v104, v103
	v_div_fmas_f32 v100, v100, v102, v104
	v_div_fixup_f32 v98, v100, v98, 1.0
	v_pk_fma_f32 v[92:93], v[98:99], v[96:97], v[92:93]
	v_cvt_f32_f16_e32 v96, v101
	v_cvt_pk_f16_f32 v92, v92, v93
	v_div_scale_f32 v93, s[0:1], v95, v95, 1.0
	v_rcp_f32_e32 v100, v93
	v_cvt_f32_f16_sdwa v97, v101 dst_sel:DWORD dst_unused:UNUSED_PAD src0_sel:WORD_1
	v_cvt_f32_f16_e32 v98, v105
	v_cvt_f32_f16_sdwa v99, v105 dst_sel:DWORD dst_unused:UNUSED_PAD src0_sel:WORD_1
	v_fma_f32 v101, -v93, v100, 1.0
	v_fmac_f32_e32 v100, v101, v100
	v_div_scale_f32 v101, vcc, 1.0, v95, 1.0
	v_mul_f32_e32 v102, v101, v100
	v_fma_f32 v103, -v93, v102, v101
	v_fmac_f32_e32 v102, v103, v100
	v_fma_f32 v93, -v93, v102, v101
	v_div_fmas_f32 v93, v93, v100, v102
	v_div_fixup_f32 v95, v93, v95, 1.0
	v_div_scale_f32 v93, s[0:1], v94, v94, 1.0
	v_rcp_f32_e32 v100, v93
	v_pk_add_f32 v[98:99], v[98:99], v[96:97] neg_lo:[0,1] neg_hi:[0,1]
	v_fma_f32 v101, -v93, v100, 1.0
	v_fmac_f32_e32 v100, v101, v100
	v_div_scale_f32 v101, vcc, 1.0, v94, 1.0
	v_mul_f32_e32 v102, v101, v100
	v_fma_f32 v103, -v93, v102, v101
	v_fmac_f32_e32 v102, v103, v100
	v_fma_f32 v93, -v93, v102, v101
	v_div_fmas_f32 v93, v93, v100, v102
	v_div_fixup_f32 v94, v93, v94, 1.0
	v_pk_fma_f32 v[94:95], v[94:95], v[98:99], v[96:97]
	s_nop 0
	v_cvt_pk_f16_f32 v93, v94, v95
	global_store_dwordx4 v[110:111], v[90:93], off
	v_add_u32_e32 v94, 0xa0, v164
	v_ashrrev_i32_e32 v95, 31, v94
	v_mad_i64_i32 v[90:91], s[0:1], v94, s5, v[168:169]
	v_lshl_add_u64 v[98:99], v[90:91], 0, s[90:91]
	v_lshlrev_b64 v[94:95], 12, v[94:95]
	v_lshl_add_u64 v[102:103], v[98:99], 0, v[166:167]
	v_lshl_add_u64 v[94:95], s[2:3], 0, v[94:95]
	global_load_dwordx4 v[90:93], v[102:103], off
	v_lshl_add_u64 v[100:101], v[94:95], 0, v[166:167]
	global_load_dwordx4 v[94:97], v[100:101], off
	v_add_f32_e32 v74, v74, v82
	v_mul_f32_e32 v74, 0xbfb8aa3b, v74
	v_exp_f32_e32 v104, v74
	v_add_f32_e32 v74, v79, v87
	v_mul_f32_e32 v74, 0xbfb8aa3b, v74
	v_exp_f32_e32 v113, v74
	v_add_f32_e32 v74, v75, v83
	v_mul_f32_e32 v74, 0xbfb8aa3b, v74
	v_exp_f32_e32 v105, v74
	v_add_f32_e32 v74, v80, v88
	v_add_f32_e32 v78, v78, v86
	v_mul_f32_e32 v74, 0xbfb8aa3b, v74
	v_mul_f32_e32 v78, 0xbfb8aa3b, v78
	v_exp_f32_e32 v110, v74
	v_add_f32_e32 v74, v76, v84
	v_exp_f32_e32 v112, v78
	v_mul_f32_e32 v74, 0xbfb8aa3b, v74
	v_exp_f32_e32 v78, v74
	v_add_f32_e32 v74, v81, v89
	v_mul_f32_e32 v74, 0xbfb8aa3b, v74
	v_exp_f32_e32 v111, v74
	v_add_f32_e32 v74, v77, v85
	v_mul_f32_e32 v74, 0xbfb8aa3b, v74
	v_pk_add_f32 v[80:81], v[112:113], 1.0 op_sel_hi:[1,0]
	v_exp_f32_e32 v79, v74
	s_waitcnt vmcnt(0)
; __device__ __forceinline__ float sigmoidf_(float x) { return 1.0f / (1.0f + __expf(-x)); }
;     template <int GI>
;     __device__ __forceinline__ void body(const f32x4 (&acc)[2][2][4][2], int row0, int colt) const {
;     ...
;                         *(u32x4*)(Gb + row * DM + c) = pack8(x0, x1);
;                     } else {
;                         h16* vp = C1 + row * LDC1 + 4096 + c;
;                         const h16x8 vv = *(const h16x8*)vp; const h16x8 vf = *(const h16x8*)(VF + row * DM + c);
;                         f32x4 o0, o1;
; #pragma unroll
;                         for (int j = 0; j < 4; ++j) { float v = (float)vv[j], f = (float)vf[j]; o0[j] = v + (f - v) * sigmoidf_(x0[j]); v = (float)vv[4 + j]; f = (float)vf[4 + j]; o1[j] = v + (f - v) * sigmoidf_(x1[j]); }
;                         *(u32x4*)vp = pack8(o0, o1);
;                     }
;                     __builtin_amdgcn_sched_barrier(0);
	v_cvt_f32_f16_e32 v74, v90
	v_cvt_f32_f16_sdwa v75, v90 dst_sel:DWORD dst_unused:UNUSED_PAD src0_sel:WORD_1
	v_div_scale_f32 v90, s[0:1], v81, v81, 1.0
	v_cvt_f32_f16_e32 v76, v94
	v_cvt_f32_f16_sdwa v77, v94 dst_sel:DWORD dst_unused:UNUSED_PAD src0_sel:WORD_1
	v_rcp_f32_e32 v94, v90
	v_pk_add_f32 v[78:79], v[78:79], 1.0 op_sel_hi:[1,0]
	v_pk_add_f32 v[76:77], v[76:77], v[74:75] neg_lo:[0,1] neg_hi:[0,1]
	v_fma_f32 v112, -v90, v94, 1.0
	v_fmac_f32_e32 v94, v112, v94
	v_div_scale_f32 v112, vcc, 1.0, v81, 1.0
	v_mul_f32_e32 v113, v112, v94
	v_fma_f32 v118, -v90, v113, v112
	v_fmac_f32_e32 v113, v118, v94
	v_fma_f32 v90, -v90, v113, v112
	v_div_fmas_f32 v90, v90, v94, v113
	v_div_fixup_f32 v81, v90, v81, 1.0
	v_div_scale_f32 v90, s[0:1], v80, v80, 1.0
	v_rcp_f32_e32 v94, v90
	s_nop 0
	v_fma_f32 v112, -v90, v94, 1.0
	v_fmac_f32_e32 v94, v112, v94
	v_div_scale_f32 v112, vcc, 1.0, v80, 1.0
	v_mul_f32_e32 v113, v112, v94
	v_fma_f32 v118, -v90, v113, v112
	v_fmac_f32_e32 v113, v118, v94
	v_fma_f32 v90, -v90, v113, v112
	v_div_fmas_f32 v90, v90, v94, v113
	v_div_fixup_f32 v80, v90, v80, 1.0
	v_pk_fma_f32 v[74:75], v[80:81], v[76:77], v[74:75]
	v_cvt_f32_f16_e32 v76, v91
	v_cvt_f32_f16_sdwa v77, v91 dst_sel:DWORD dst_unused:UNUSED_PAD src0_sel:WORD_1
	v_pk_add_f32 v[90:91], v[110:111], 1.0 op_sel_hi:[1,0]
	v_cvt_pk_f16_f32 v74, v74, v75
	v_div_scale_f32 v75, s[0:1], v91, v91, 1.0
	v_rcp_f32_e32 v94, v75
	v_cvt_f32_f16_e32 v80, v95
	v_cvt_f32_f16_sdwa v81, v95 dst_sel:DWORD dst_unused:UNUSED_PAD src0_sel:WORD_1
	v_fma_f32 v95, -v75, v94, 1.0
	v_fmac_f32_e32 v94, v95, v94
	v_div_scale_f32 v95, vcc, 1.0, v91, 1.0
	v_mul_f32_e32 v110, v95, v94
	v_fma_f32 v111, -v75, v110, v95
	v_fmac_f32_e32 v110, v111, v94
	v_fma_f32 v75, -v75, v110, v95
	v_div_fmas_f32 v75, v75, v94, v110
	v_div_fixup_f32 v91, v75, v91, 1.0
	v_div_scale_f32 v75, s[0:1], v90, v90, 1.0
	v_rcp_f32_e32 v94, v75
	v_pk_add_f32 v[80:81], v[80:81], v[76:77] neg_lo:[0,1] neg_hi:[0,1]
	v_fma_f32 v95, -v75, v94, 1.0
	v_fmac_f32_e32 v94, v95, v94
	v_div_scale_f32 v95, vcc, 1.0, v90, 1.0
	v_mul_f32_e32 v110, v95, v94
	v_fma_f32 v111, -v75, v110, v95
	v_fmac_f32_e32 v110, v111, v94
	v_fma_f32 v75, -v75, v110, v95
	v_div_fmas_f32 v75, v75, v94, v110
	v_div_fixup_f32 v90, v75, v90, 1.0
	v_pk_fma_f32 v[76:77], v[90:91], v[80:81], v[76:77]
	v_pk_add_f32 v[90:91], v[104:105], 1.0 op_sel_hi:[1,0]
	v_cvt_pk_f16_f32 v75, v76, v77
	v_cvt_f32_f16_e32 v76, v92
	v_cvt_f32_f16_sdwa v77, v92 dst_sel:DWORD dst_unused:UNUSED_PAD src0_sel:WORD_1
	v_div_scale_f32 v92, s[0:1], v91, v91, 1.0
	v_rcp_f32_e32 v94, v92
	v_cvt_f32_f16_e32 v80, v96
	v_cvt_f32_f16_sdwa v81, v96 dst_sel:DWORD dst_unused:UNUSED_PAD src0_sel:WORD_1
	v_fma_f32 v95, -v92, v94, 1.0
	v_fmac_f32_e32 v94, v95, v94
	v_div_scale_f32 v95, vcc, 1.0, v91, 1.0
	v_mul_f32_e32 v96, v95, v94
	v_fma_f32 v104, -v92, v96, v95
	v_fmac_f32_e32 v96, v104, v94
	v_fma_f32 v92, -v92, v96, v95
	v_div_fmas_f32 v92, v92, v94, v96
	v_div_fixup_f32 v91, v92, v91, 1.0
	v_div_scale_f32 v92, s[0:1], v90, v90, 1.0
	v_rcp_f32_e32 v94, v92
	v_pk_add_f32 v[80:81], v[80:81], v[76:77] neg_lo:[0,1] neg_hi:[0,1]
	v_fma_f32 v95, -v92, v94, 1.0
	v_fmac_f32_e32 v94, v95, v94
	v_div_scale_f32 v95, vcc, 1.0, v90, 1.0
	v_mul_f32_e32 v96, v95, v94
	v_fma_f32 v104, -v92, v96, v95
	v_fmac_f32_e32 v96, v104, v94
	v_fma_f32 v92, -v92, v96, v95
	v_div_fmas_f32 v92, v92, v94, v96
	v_div_fixup_f32 v90, v92, v90, 1.0
	v_pk_fma_f32 v[76:77], v[90:91], v[80:81], v[76:77]
	v_cvt_f32_f16_e32 v80, v93
	v_cvt_pk_f16_f32 v76, v76, v77
	v_div_scale_f32 v77, s[0:1], v79, v79, 1.0
	v_rcp_f32_e32 v92, v77
	v_cvt_f32_f16_sdwa v81, v93 dst_sel:DWORD dst_unused:UNUSED_PAD src0_sel:WORD_1
	v_cvt_f32_f16_e32 v90, v97
	v_cvt_f32_f16_sdwa v91, v97 dst_sel:DWORD dst_unused:UNUSED_PAD src0_sel:WORD_1
	v_fma_f32 v93, -v77, v92, 1.0
	v_fmac_f32_e32 v92, v93, v92
	v_div_scale_f32 v93, vcc, 1.0, v79, 1.0
	v_mul_f32_e32 v94, v93, v92
	v_fma_f32 v95, -v77, v94, v93
	v_fmac_f32_e32 v94, v95, v92
	v_fma_f32 v77, -v77, v94, v93
	v_div_fmas_f32 v77, v77, v92, v94
	v_div_fixup_f32 v79, v77, v79, 1.0
	v_div_scale_f32 v77, s[0:1], v78, v78, 1.0
	v_rcp_f32_e32 v92, v77
	v_pk_add_f32 v[90:91], v[90:91], v[80:81] neg_lo:[0,1] neg_hi:[0,1]
	v_fma_f32 v93, -v77, v92, 1.0
	v_fmac_f32_e32 v92, v93, v92
	v_div_scale_f32 v93, vcc, 1.0, v78, 1.0
	v_mul_f32_e32 v94, v93, v92
	v_fma_f32 v95, -v77, v94, v93
	v_fmac_f32_e32 v94, v95, v92
	v_fma_f32 v77, -v77, v94, v93
	v_div_fmas_f32 v77, v77, v92, v94
	v_div_fixup_f32 v78, v77, v78, 1.0
	v_pk_fma_f32 v[78:79], v[78:79], v[90:91], v[80:81]
	s_nop 0
	v_cvt_pk_f16_f32 v77, v78, v79
	global_store_dwordx4 v[102:103], v[74:77], off
	v_add_u32_e32 v78, 0xb0, v164
	v_ashrrev_i32_e32 v79, 31, v78
	v_mad_i64_i32 v[74:75], s[0:1], v78, s5, v[168:169]
	v_lshl_add_u64 v[90:91], v[74:75], 0, s[90:91]
	v_lshlrev_b64 v[78:79], 12, v[78:79]
	v_lshl_add_u64 v[94:95], v[90:91], 0, v[166:167]
	v_lshl_add_u64 v[78:79], s[2:3], 0, v[78:79]
	global_load_dwordx4 v[74:77], v[94:95], off
	v_lshl_add_u64 v[92:93], v[78:79], 0, v[166:167]
	global_load_dwordx4 v[78:81], v[92:93], off
	v_add_f32_e32 v66, v66, v82
	v_mul_f32_e32 v66, 0xbfb8aa3b, v66
	v_exp_f32_e32 v82, v66
	v_add_f32_e32 v66, v71, v87
	v_mul_f32_e32 v66, 0xbfb8aa3b, v66
	v_exp_f32_e32 v97, v66
	v_add_f32_e32 v66, v67, v83
	v_mul_f32_e32 v66, 0xbfb8aa3b, v66
	v_exp_f32_e32 v83, v66
	v_add_f32_e32 v66, v72, v88
	v_add_f32_e32 v70, v70, v86
	v_mul_f32_e32 v66, 0xbfb8aa3b, v66
	v_mul_f32_e32 v70, 0xbfb8aa3b, v70
	v_exp_f32_e32 v86, v66
	v_add_f32_e32 v66, v68, v84
	v_exp_f32_e32 v96, v70
	v_mul_f32_e32 v66, 0xbfb8aa3b, v66
	v_exp_f32_e32 v70, v66
	v_add_f32_e32 v66, v73, v89
	v_mul_f32_e32 v66, 0xbfb8aa3b, v66
	v_exp_f32_e32 v87, v66
	v_add_f32_e32 v66, v69, v85
	v_mul_f32_e32 v66, 0xbfb8aa3b, v66
	v_pk_add_f32 v[72:73], v[96:97], 1.0 op_sel_hi:[1,0]
	v_exp_f32_e32 v71, v66
	s_waitcnt vmcnt(0)
; __device__ __forceinline__ float sigmoidf_(float x) { return 1.0f / (1.0f + __expf(-x)); }
;     template <int GI>
;     __device__ __forceinline__ void body(const f32x4 (&acc)[2][2][4][2], int row0, int colt) const {
;     ...
;         for (int bj = 0; bj < 2; ++bj) {
;             const int c = colt + bj * 128;
;             f32x4 b0 = (f32x4){0.f, 0.f, 0.f, 0.f}, b1 = b0;
;             if (GI == 0) { b0 = *(const f32x4*)(w0 + c); b1 = *(const f32x4*)(w0 + c + 4); }
;             else if (GI == 1) { b0 = *(const f32x4*)(a0 + c); b1 = *(const f32x4*)(a0 + c + 4); }
;             else if (GI == 3) { b0 = *(const f32x4*)(v0 + c); b1 = *(const f32x4*)(v0 + c + 4); }
; #pragma unroll
;             for (int ai = 0; ai < 2; ++ai)
; #pragma unroll
;                 for (int m = 0; m < 4; ++m) {
;                     const size_t row = (size_t)(row0 + ai * 128 + m * 16);
;                     f32x4 x0 = acc[ai][bj][m][0] + b0, x1 = acc[ai][bj][m][1] + b1;
;                     if (GI == 0) {
; #pragma unroll
;                         for (int j = 0; j < 4; ++j) {
;                             x0[j] = 0.6065306597126334f * sigmoidf_(x0[j]); x1[j] = 0.6065306597126334f * sigmoidf_(x1[j]); }
;                         *(u32x4*)(DEC + row * DM + c) = pack8(x0, x1);
;                     } else if (GI == 1) {
; #pragma unroll
;                         for (int j = 0; j < 4; ++j) { x0[j] = sigmoidf_(x0[j]); x1[j] = sigmoidf_(x1[j]); }
;                         *(u32x4*)(Ab + row * DM + c) = pack8(x0, x1);
;                     } else if (GI == 2) {
;                         *(u32x4*)(Gb + row * DM + c) = pack8(x0, x1);
;                     } else {
;                         h16* vp = C1 + row * LDC1 + 4096 + c;
;                         const h16x8 vv = *(const h16x8*)vp; const h16x8 vf = *(const h16x8*)(VF + row * DM + c);
;                         f32x4 o0, o1;
; #pragma unroll
;                         for (int j = 0; j < 4; ++j) { float v = (float)vv[j], f = (float)vf[j]; o0[j] = v + (f - v) * sigmoidf_(x0[j]); v = (float)vv[4 + j]; f = (float)vf[4 + j]; o1[j] = v + (f - v) * sigmoidf_(x1[j]); }
;                         *(u32x4*)vp = pack8(o0, o1);
;                     }
;                     __builtin_amdgcn_sched_barrier(0);
;                 }
	v_cvt_f32_f16_e32 v66, v74
	v_cvt_f32_f16_sdwa v67, v74 dst_sel:DWORD dst_unused:UNUSED_PAD src0_sel:WORD_1
	v_div_scale_f32 v74, s[0:1], v73, v73, 1.0
	v_cvt_f32_f16_e32 v68, v78
	v_cvt_f32_f16_sdwa v69, v78 dst_sel:DWORD dst_unused:UNUSED_PAD src0_sel:WORD_1
	v_rcp_f32_e32 v78, v74
	v_pk_add_f32 v[70:71], v[70:71], 1.0 op_sel_hi:[1,0]
	v_pk_add_f32 v[68:69], v[68:69], v[66:67] neg_lo:[0,1] neg_hi:[0,1]
	v_fma_f32 v84, -v74, v78, 1.0
	v_fmac_f32_e32 v78, v84, v78
	v_div_scale_f32 v84, vcc, 1.0, v73, 1.0
	v_mul_f32_e32 v85, v84, v78
	v_fma_f32 v88, -v74, v85, v84
	v_fmac_f32_e32 v85, v88, v78
	v_fma_f32 v74, -v74, v85, v84
	v_div_fmas_f32 v74, v74, v78, v85
	v_div_fixup_f32 v73, v74, v73, 1.0
	v_div_scale_f32 v74, s[0:1], v72, v72, 1.0
	v_rcp_f32_e32 v78, v74
	s_nop 0
	v_fma_f32 v84, -v74, v78, 1.0
	v_fmac_f32_e32 v78, v84, v78
	v_div_scale_f32 v84, vcc, 1.0, v72, 1.0
	v_mul_f32_e32 v85, v84, v78
	v_fma_f32 v88, -v74, v85, v84
	v_fmac_f32_e32 v85, v88, v78
	v_fma_f32 v74, -v74, v85, v84
	v_div_fmas_f32 v74, v74, v78, v85
	v_div_fixup_f32 v72, v74, v72, 1.0
	v_pk_fma_f32 v[66:67], v[72:73], v[68:69], v[66:67]
	v_cvt_f32_f16_e32 v68, v75
	v_cvt_f32_f16_sdwa v69, v75 dst_sel:DWORD dst_unused:UNUSED_PAD src0_sel:WORD_1
	v_pk_add_f32 v[74:75], v[86:87], 1.0 op_sel_hi:[1,0]
	v_cvt_pk_f16_f32 v66, v66, v67
	v_div_scale_f32 v67, s[0:1], v75, v75, 1.0
	v_rcp_f32_e32 v78, v67
	v_cvt_f32_f16_e32 v72, v79
	v_cvt_f32_f16_sdwa v73, v79 dst_sel:DWORD dst_unused:UNUSED_PAD src0_sel:WORD_1
	v_fma_f32 v79, -v67, v78, 1.0
	v_fmac_f32_e32 v78, v79, v78
	v_div_scale_f32 v79, vcc, 1.0, v75, 1.0
	v_mul_f32_e32 v84, v79, v78
	v_fma_f32 v85, -v67, v84, v79
	v_fmac_f32_e32 v84, v85, v78
	v_fma_f32 v67, -v67, v84, v79
	v_div_fmas_f32 v67, v67, v78, v84
	v_div_fixup_f32 v75, v67, v75, 1.0
	v_div_scale_f32 v67, s[0:1], v74, v74, 1.0
	v_rcp_f32_e32 v78, v67
	v_pk_add_f32 v[72:73], v[72:73], v[68:69] neg_lo:[0,1] neg_hi:[0,1]
	v_fma_f32 v79, -v67, v78, 1.0
	v_fmac_f32_e32 v78, v79, v78
	v_div_scale_f32 v79, vcc, 1.0, v74, 1.0
	v_mul_f32_e32 v84, v79, v78
	v_fma_f32 v85, -v67, v84, v79
	v_fmac_f32_e32 v84, v85, v78
	v_fma_f32 v67, -v67, v84, v79
	v_div_fmas_f32 v67, v67, v78, v84
	v_div_fixup_f32 v74, v67, v74, 1.0
	v_pk_fma_f32 v[68:69], v[74:75], v[72:73], v[68:69]
	v_pk_add_f32 v[74:75], v[82:83], 1.0 op_sel_hi:[1,0]
	v_cvt_pk_f16_f32 v67, v68, v69
	v_cvt_f32_f16_e32 v68, v76
	v_cvt_f32_f16_sdwa v69, v76 dst_sel:DWORD dst_unused:UNUSED_PAD src0_sel:WORD_1
	v_div_scale_f32 v76, s[0:1], v75, v75, 1.0
	v_rcp_f32_e32 v78, v76
	v_cvt_f32_f16_e32 v72, v80
	v_cvt_f32_f16_sdwa v73, v80 dst_sel:DWORD dst_unused:UNUSED_PAD src0_sel:WORD_1
	v_fma_f32 v79, -v76, v78, 1.0
	v_fmac_f32_e32 v78, v79, v78
	v_div_scale_f32 v79, vcc, 1.0, v75, 1.0
	v_mul_f32_e32 v80, v79, v78
	v_fma_f32 v82, -v76, v80, v79
	v_fmac_f32_e32 v80, v82, v78
	v_fma_f32 v76, -v76, v80, v79
	v_div_fmas_f32 v76, v76, v78, v80
	v_div_fixup_f32 v75, v76, v75, 1.0
	v_div_scale_f32 v76, s[0:1], v74, v74, 1.0
	v_rcp_f32_e32 v78, v76
	v_pk_add_f32 v[72:73], v[72:73], v[68:69] neg_lo:[0,1] neg_hi:[0,1]
	v_fma_f32 v79, -v76, v78, 1.0
	v_fmac_f32_e32 v78, v79, v78
	v_div_scale_f32 v79, vcc, 1.0, v74, 1.0
	v_mul_f32_e32 v80, v79, v78
	v_fma_f32 v82, -v76, v80, v79
	v_fmac_f32_e32 v80, v82, v78
	v_fma_f32 v76, -v76, v80, v79
	v_div_fmas_f32 v76, v76, v78, v80
	v_div_fixup_f32 v74, v76, v74, 1.0
	v_pk_fma_f32 v[68:69], v[74:75], v[72:73], v[68:69]
	v_cvt_f32_f16_e32 v72, v77
	v_cvt_pk_f16_f32 v68, v68, v69
	v_div_scale_f32 v69, s[0:1], v71, v71, 1.0
	v_rcp_f32_e32 v76, v69
	v_cvt_f32_f16_sdwa v73, v77 dst_sel:DWORD dst_unused:UNUSED_PAD src0_sel:WORD_1
	v_cvt_f32_f16_e32 v74, v81
	v_cvt_f32_f16_sdwa v75, v81 dst_sel:DWORD dst_unused:UNUSED_PAD src0_sel:WORD_1
	v_fma_f32 v77, -v69, v76, 1.0
	v_fmac_f32_e32 v76, v77, v76
	v_div_scale_f32 v77, vcc, 1.0, v71, 1.0
	v_mul_f32_e32 v78, v77, v76
	v_fma_f32 v79, -v69, v78, v77
	v_fmac_f32_e32 v78, v79, v76
	v_fma_f32 v69, -v69, v78, v77
	v_div_fmas_f32 v69, v69, v76, v78
	v_div_fixup_f32 v71, v69, v71, 1.0
	v_div_scale_f32 v69, s[0:1], v70, v70, 1.0
	v_rcp_f32_e32 v76, v69
	v_pk_add_f32 v[74:75], v[74:75], v[72:73] neg_lo:[0,1] neg_hi:[0,1]
	v_fma_f32 v77, -v69, v76, 1.0
	v_fmac_f32_e32 v76, v77, v76
	v_div_scale_f32 v77, vcc, 1.0, v70, 1.0
	v_mul_f32_e32 v78, v77, v76
	v_fma_f32 v79, -v69, v78, v77
	v_fmac_f32_e32 v78, v79, v76
	v_fma_f32 v69, -v69, v78, v77
	v_div_fmas_f32 v69, v69, v76, v78
	v_div_fixup_f32 v70, v69, v70, 1.0
	v_pk_fma_f32 v[70:71], v[70:71], v[74:75], v[72:73]
	s_nop 0
	v_cvt_pk_f16_f32 v69, v70, v71
	global_store_dwordx4 v[94:95], v[66:69], off
	global_load_dwordx4 v[66:69], v[156:157], off offset:528
	s_nop 0
	global_load_dwordx4 v[70:73], v[156:157], off offset:512
	v_or_b32_e32 v74, 0x80, v158
	v_ashrrev_i32_e32 v75, 31, v74
	v_lshlrev_b64 v[82:83], 1, v[74:75]
	v_lshl_add_u64 v[84:85], v[160:161], 0, v[82:83]
	global_load_dwordx4 v[74:77], v[84:85], off
	global_load_dwordx4 v[78:81], v[162:163], off offset:256
	s_waitcnt vmcnt(0)
; __device__ __forceinline__ float sigmoidf_(float x) { return 1.0f / (1.0f + __expf(-x)); }
;     template <int GI>
;     __device__ __forceinline__ void body(const f32x4 (&acc)[2][2][4][2], int row0, int colt) const {
;     ...
;                         *(u32x4*)(Gb + row * DM + c) = pack8(x0, x1);
;                     } else {
;                         h16* vp = C1 + row * LDC1 + 4096 + c;
;                         const h16x8 vv = *(const h16x8*)vp; const h16x8 vf = *(const h16x8*)(VF + row * DM + c);
;                         f32x4 o0, o1;
; #pragma unroll
;                         for (int j = 0; j < 4; ++j) { float v = (float)vv[j], f = (float)vf[j]; o0[j] = v + (f - v) * sigmoidf_(x0[j]); v = (float)vv[4 + j]; f = (float)vf[4 + j]; o1[j] = v + (f - v) * sigmoidf_(x1[j]); }
;                         *(u32x4*)vp = pack8(o0, o1);
;                     }
;                     __builtin_amdgcn_sched_barrier(0);
	v_add_f32_e32 v58, v58, v66
	v_mul_f32_e32 v58, 0xbfb8aa3b, v58
	v_exp_f32_e32 v86, v58
	v_add_f32_e32 v58, v63, v71
	v_mul_f32_e32 v58, 0xbfb8aa3b, v58
	v_exp_f32_e32 v89, v58
	v_add_f32_e32 v58, v59, v67
	v_mul_f32_e32 v58, 0xbfb8aa3b, v58
	v_exp_f32_e32 v87, v58
	v_add_f32_e32 v58, v64, v72
	v_add_f32_e32 v62, v62, v70
	v_mul_f32_e32 v58, 0xbfb8aa3b, v58
	v_mul_f32_e32 v62, 0xbfb8aa3b, v62
	v_exp_f32_e32 v64, v58
	v_add_f32_e32 v58, v60, v68
	v_exp_f32_e32 v88, v62
	v_mul_f32_e32 v58, 0xbfb8aa3b, v58
	v_exp_f32_e32 v62, v58
	v_add_f32_e32 v58, v65, v73
	v_mul_f32_e32 v58, 0xbfb8aa3b, v58
	v_exp_f32_e32 v65, v58
	v_add_f32_e32 v58, v61, v69
	v_mul_f32_e32 v58, 0xbfb8aa3b, v58
	v_pk_add_f32 v[88:89], v[88:89], 1.0 op_sel_hi:[1,0]
	v_exp_f32_e32 v63, v58
	v_cvt_f32_f16_e32 v58, v74
	v_cvt_f32_f16_sdwa v59, v74 dst_sel:DWORD dst_unused:UNUSED_PAD src0_sel:WORD_1
	v_div_scale_f32 v74, s[0:1], v89, v89, 1.0
	v_cvt_f32_f16_e32 v60, v78
	v_cvt_f32_f16_sdwa v61, v78 dst_sel:DWORD dst_unused:UNUSED_PAD src0_sel:WORD_1
	v_rcp_f32_e32 v78, v74
	v_pk_add_f32 v[64:65], v[64:65], 1.0 op_sel_hi:[1,0]
	v_pk_add_f32 v[62:63], v[62:63], 1.0 op_sel_hi:[1,0]
	v_pk_add_f32 v[60:61], v[60:61], v[58:59] neg_lo:[0,1] neg_hi:[0,1]
	v_fma_f32 v94, -v74, v78, 1.0
	v_fmac_f32_e32 v78, v94, v78
	v_div_scale_f32 v94, vcc, 1.0, v89, 1.0
	v_mul_f32_e32 v95, v94, v78
	v_fma_f32 v96, -v74, v95, v94
	v_fmac_f32_e32 v95, v96, v78
	v_fma_f32 v74, -v74, v95, v94
	v_div_fmas_f32 v74, v74, v78, v95
	v_div_fixup_f32 v89, v74, v89, 1.0
	v_div_scale_f32 v74, s[0:1], v88, v88, 1.0
	v_rcp_f32_e32 v78, v74
	s_nop 0
	v_fma_f32 v94, -v74, v78, 1.0
	v_fmac_f32_e32 v78, v94, v78
	v_div_scale_f32 v94, vcc, 1.0, v88, 1.0
	v_mul_f32_e32 v95, v94, v78
	v_fma_f32 v96, -v74, v95, v94
	v_fmac_f32_e32 v95, v96, v78
	v_fma_f32 v74, -v74, v95, v94
	v_div_fmas_f32 v74, v74, v78, v95
	v_div_fixup_f32 v88, v74, v88, 1.0
	v_pk_fma_f32 v[58:59], v[88:89], v[60:61], v[58:59]
	v_cvt_f32_f16_e32 v60, v75
	v_cvt_pk_f16_f32 v58, v58, v59
	v_div_scale_f32 v59, s[0:1], v65, v65, 1.0
	v_rcp_f32_e32 v78, v59
	v_cvt_f32_f16_sdwa v61, v75 dst_sel:DWORD dst_unused:UNUSED_PAD src0_sel:WORD_1
	v_cvt_f32_f16_e32 v74, v79
	v_cvt_f32_f16_sdwa v75, v79 dst_sel:DWORD dst_unused:UNUSED_PAD src0_sel:WORD_1
	v_fma_f32 v79, -v59, v78, 1.0
	v_fmac_f32_e32 v78, v79, v78
	v_div_scale_f32 v79, vcc, 1.0, v65, 1.0
	v_mul_f32_e32 v88, v79, v78
	v_fma_f32 v89, -v59, v88, v79
	v_fmac_f32_e32 v88, v89, v78
	v_fma_f32 v59, -v59, v88, v79
	v_div_fmas_f32 v59, v59, v78, v88
	v_div_fixup_f32 v65, v59, v65, 1.0
	v_div_scale_f32 v59, s[0:1], v64, v64, 1.0
	v_rcp_f32_e32 v78, v59
	v_pk_add_f32 v[74:75], v[74:75], v[60:61] neg_lo:[0,1] neg_hi:[0,1]
	v_fma_f32 v79, -v59, v78, 1.0
	v_fmac_f32_e32 v78, v79, v78
	v_div_scale_f32 v79, vcc, 1.0, v64, 1.0
	v_mul_f32_e32 v88, v79, v78
	v_fma_f32 v89, -v59, v88, v79
	v_fmac_f32_e32 v88, v89, v78
	v_fma_f32 v59, -v59, v88, v79
	v_div_fmas_f32 v59, v59, v78, v88
	v_div_fixup_f32 v64, v59, v64, 1.0
	v_pk_fma_f32 v[60:61], v[64:65], v[74:75], v[60:61]
	v_pk_add_f32 v[74:75], v[86:87], 1.0 op_sel_hi:[1,0]
	v_cvt_pk_f16_f32 v59, v60, v61
	v_cvt_f32_f16_e32 v60, v76
	v_cvt_f32_f16_sdwa v61, v76 dst_sel:DWORD dst_unused:UNUSED_PAD src0_sel:WORD_1
	v_div_scale_f32 v76, s[0:1], v75, v75, 1.0
	v_rcp_f32_e32 v78, v76
	v_cvt_f32_f16_e32 v64, v80
	v_cvt_f32_f16_sdwa v65, v80 dst_sel:DWORD dst_unused:UNUSED_PAD src0_sel:WORD_1
	v_fma_f32 v79, -v76, v78, 1.0
	v_fmac_f32_e32 v78, v79, v78
	v_div_scale_f32 v79, vcc, 1.0, v75, 1.0
	v_mul_f32_e32 v80, v79, v78
	v_fma_f32 v86, -v76, v80, v79
	v_fmac_f32_e32 v80, v86, v78
	v_fma_f32 v76, -v76, v80, v79
	v_div_fmas_f32 v76, v76, v78, v80
	v_div_fixup_f32 v75, v76, v75, 1.0
	v_div_scale_f32 v76, s[0:1], v74, v74, 1.0
	v_rcp_f32_e32 v78, v76
	v_pk_add_f32 v[64:65], v[64:65], v[60:61] neg_lo:[0,1] neg_hi:[0,1]
	v_fma_f32 v79, -v76, v78, 1.0
	v_fmac_f32_e32 v78, v79, v78
	v_div_scale_f32 v79, vcc, 1.0, v74, 1.0
	v_mul_f32_e32 v80, v79, v78
	v_fma_f32 v86, -v76, v80, v79
	v_fmac_f32_e32 v80, v86, v78
	v_fma_f32 v76, -v76, v80, v79
	v_div_fmas_f32 v76, v76, v78, v80
	v_div_fixup_f32 v74, v76, v74, 1.0
	v_pk_fma_f32 v[60:61], v[64:65], v[74:75], v[60:61]
	v_cvt_f32_f16_e32 v64, v77
	v_cvt_pk_f16_f32 v60, v60, v61
	v_div_scale_f32 v61, s[0:1], v63, v63, 1.0
	v_rcp_f32_e32 v76, v61
	v_cvt_f32_f16_sdwa v65, v77 dst_sel:DWORD dst_unused:UNUSED_PAD src0_sel:WORD_1
	v_cvt_f32_f16_e32 v74, v81
	v_cvt_f32_f16_sdwa v75, v81 dst_sel:DWORD dst_unused:UNUSED_PAD src0_sel:WORD_1
	v_fma_f32 v77, -v61, v76, 1.0
	v_fmac_f32_e32 v76, v77, v76
	v_div_scale_f32 v77, vcc, 1.0, v63, 1.0
	v_mul_f32_e32 v78, v77, v76
	v_fma_f32 v79, -v61, v78, v77
	v_fmac_f32_e32 v78, v79, v76
	v_fma_f32 v61, -v61, v78, v77
	v_div_fmas_f32 v61, v61, v76, v78
	v_div_fixup_f32 v63, v61, v63, 1.0
	v_div_scale_f32 v61, s[0:1], v62, v62, 1.0
	v_rcp_f32_e32 v76, v61
	v_pk_add_f32 v[74:75], v[74:75], v[64:65] neg_lo:[0,1] neg_hi:[0,1]
	v_fma_f32 v77, -v61, v76, 1.0
	v_fmac_f32_e32 v76, v77, v76
	v_div_scale_f32 v77, vcc, 1.0, v62, 1.0
	v_mul_f32_e32 v78, v77, v76
	v_fma_f32 v79, -v61, v78, v77
	v_fmac_f32_e32 v78, v79, v76
	v_fma_f32 v61, -v61, v78, v77
	v_div_fmas_f32 v61, v61, v76, v78
	v_div_fixup_f32 v62, v61, v62, 1.0
	v_pk_fma_f32 v[62:63], v[74:75], v[62:63], v[64:65]
	s_nop 0
	v_cvt_pk_f16_f32 v61, v62, v63
	global_store_dwordx4 v[84:85], v[58:61], off
	v_lshl_add_u64 v[74:75], v[138:139], 0, v[82:83]
	global_load_dwordx4 v[62:65], v[74:75], off
	global_load_dwordx4 v[58:61], v[140:141], off offset:256
	v_add_f32_e32 v50, v50, v66
	v_mul_f32_e32 v50, 0xbfb8aa3b, v50
	v_exp_f32_e32 v76, v50
	v_add_f32_e32 v50, v55, v71
	v_mul_f32_e32 v50, 0xbfb8aa3b, v50
	v_exp_f32_e32 v81, v50
	v_add_f32_e32 v50, v51, v67
	v_mul_f32_e32 v50, 0xbfb8aa3b, v50
	v_add_f32_e32 v54, v54, v70
	v_exp_f32_e32 v77, v50
	v_add_f32_e32 v50, v56, v72
	v_mul_f32_e32 v54, 0xbfb8aa3b, v54
	v_mul_f32_e32 v50, 0xbfb8aa3b, v50
	v_exp_f32_e32 v80, v54
	v_exp_f32_e32 v78, v50
	v_add_f32_e32 v50, v52, v68
	v_mul_f32_e32 v50, 0xbfb8aa3b, v50
	v_exp_f32_e32 v54, v50
	v_add_f32_e32 v50, v57, v73
	v_mul_f32_e32 v50, 0xbfb8aa3b, v50
	v_exp_f32_e32 v79, v50
	v_add_f32_e32 v50, v53, v69
	v_pk_add_f32 v[56:57], v[80:81], 1.0 op_sel_hi:[1,0]
	v_mul_f32_e32 v50, 0xbfb8aa3b, v50
	v_exp_f32_e32 v55, v50
	s_waitcnt vmcnt(0)
; __device__ __forceinline__ float sigmoidf_(float x) { return 1.0f / (1.0f + __expf(-x)); }
;     template <int GI>
;     __device__ __forceinline__ void body(const f32x4 (&acc)[2][2][4][2], int row0, int colt) const {
;     ...
;                         *(u32x4*)(Gb + row * DM + c) = pack8(x0, x1);
;                     } else {
;                         h16* vp = C1 + row * LDC1 + 4096 + c;
;                         const h16x8 vv = *(const h16x8*)vp; const h16x8 vf = *(const h16x8*)(VF + row * DM + c);
;                         f32x4 o0, o1;
; #pragma unroll
;                         for (int j = 0; j < 4; ++j) { float v = (float)vv[j], f = (float)vf[j]; o0[j] = v + (f - v) * sigmoidf_(x0[j]); v = (float)vv[4 + j]; f = (float)vf[4 + j]; o1[j] = v + (f - v) * sigmoidf_(x1[j]); }
;                         *(u32x4*)vp = pack8(o0, o1);
;                     }
;                     __builtin_amdgcn_sched_barrier(0);
	v_cvt_f32_f16_e32 v50, v62
	v_cvt_f32_f16_e32 v52, v58
	v_cvt_f32_f16_sdwa v53, v58 dst_sel:DWORD dst_unused:UNUSED_PAD src0_sel:WORD_1
	v_div_scale_f32 v58, s[0:1], v57, v57, 1.0
	v_cvt_f32_f16_sdwa v51, v62 dst_sel:DWORD dst_unused:UNUSED_PAD src0_sel:WORD_1
	v_rcp_f32_e32 v62, v58
	v_pk_add_f32 v[54:55], v[54:55], 1.0 op_sel_hi:[1,0]
	v_pk_add_f32 v[52:53], v[52:53], v[50:51] neg_lo:[0,1] neg_hi:[0,1]
	v_fma_f32 v80, -v58, v62, 1.0
	v_fmac_f32_e32 v62, v80, v62
	v_div_scale_f32 v80, vcc, 1.0, v57, 1.0
	v_mul_f32_e32 v81, v80, v62
	v_fma_f32 v84, -v58, v81, v80
	v_fmac_f32_e32 v81, v84, v62
	v_fma_f32 v58, -v58, v81, v80
	v_div_fmas_f32 v58, v58, v62, v81
	v_div_fixup_f32 v57, v58, v57, 1.0
	v_div_scale_f32 v58, s[0:1], v56, v56, 1.0
	v_rcp_f32_e32 v62, v58
	s_nop 0
	v_fma_f32 v80, -v58, v62, 1.0
	v_fmac_f32_e32 v62, v80, v62
	v_div_scale_f32 v80, vcc, 1.0, v56, 1.0
	v_mul_f32_e32 v81, v80, v62
	v_fma_f32 v84, -v58, v81, v80
	v_fmac_f32_e32 v81, v84, v62
	v_fma_f32 v58, -v58, v81, v80
	v_div_fmas_f32 v58, v58, v62, v81
	v_div_fixup_f32 v56, v58, v56, 1.0
	v_pk_fma_f32 v[50:51], v[56:57], v[52:53], v[50:51]
	v_cvt_f32_f16_e32 v56, v59
	v_cvt_f32_f16_sdwa v57, v59 dst_sel:DWORD dst_unused:UNUSED_PAD src0_sel:WORD_1
	v_pk_add_f32 v[58:59], v[78:79], 1.0 op_sel_hi:[1,0]
	v_cvt_pk_f16_f32 v50, v50, v51
	v_div_scale_f32 v51, s[0:1], v59, v59, 1.0
	v_rcp_f32_e32 v62, v51
	v_cvt_f32_f16_e32 v52, v63
	v_cvt_f32_f16_sdwa v53, v63 dst_sel:DWORD dst_unused:UNUSED_PAD src0_sel:WORD_1
	v_fma_f32 v63, -v51, v62, 1.0
	v_fmac_f32_e32 v62, v63, v62
	v_div_scale_f32 v63, vcc, 1.0, v59, 1.0
	v_mul_f32_e32 v78, v63, v62
	v_fma_f32 v79, -v51, v78, v63
	v_fmac_f32_e32 v78, v79, v62
	v_fma_f32 v51, -v51, v78, v63
	v_div_fmas_f32 v51, v51, v62, v78
	v_div_fixup_f32 v59, v51, v59, 1.0
	v_div_scale_f32 v51, s[0:1], v58, v58, 1.0
	v_rcp_f32_e32 v62, v51
	v_pk_add_f32 v[56:57], v[56:57], v[52:53] neg_lo:[0,1] neg_hi:[0,1]
	v_fma_f32 v63, -v51, v62, 1.0
	v_fmac_f32_e32 v62, v63, v62
	v_div_scale_f32 v63, vcc, 1.0, v58, 1.0
	v_mul_f32_e32 v78, v63, v62
	v_fma_f32 v79, -v51, v78, v63
	v_fmac_f32_e32 v78, v79, v62
	v_fma_f32 v51, -v51, v78, v63
	v_div_fmas_f32 v51, v51, v62, v78
	v_div_fixup_f32 v58, v51, v58, 1.0
	v_pk_fma_f32 v[52:53], v[58:59], v[56:57], v[52:53]
	v_pk_add_f32 v[58:59], v[76:77], 1.0 op_sel_hi:[1,0]
	v_cvt_f32_f16_e32 v56, v60
	v_cvt_f32_f16_sdwa v57, v60 dst_sel:DWORD dst_unused:UNUSED_PAD src0_sel:WORD_1
	v_div_scale_f32 v60, s[0:1], v59, v59, 1.0
	v_rcp_f32_e32 v62, v60
	v_cvt_pk_f16_f32 v51, v52, v53
	v_cvt_f32_f16_e32 v52, v64
	v_cvt_f32_f16_sdwa v53, v64 dst_sel:DWORD dst_unused:UNUSED_PAD src0_sel:WORD_1
	v_fma_f32 v63, -v60, v62, 1.0
	v_fmac_f32_e32 v62, v63, v62
	v_div_scale_f32 v63, vcc, 1.0, v59, 1.0
	v_mul_f32_e32 v64, v63, v62
	v_fma_f32 v76, -v60, v64, v63
	v_fmac_f32_e32 v64, v76, v62
	v_fma_f32 v60, -v60, v64, v63
	v_div_fmas_f32 v60, v60, v62, v64
	v_div_fixup_f32 v59, v60, v59, 1.0
	v_div_scale_f32 v60, s[0:1], v58, v58, 1.0
	v_rcp_f32_e32 v62, v60
	v_pk_add_f32 v[56:57], v[56:57], v[52:53] neg_lo:[0,1] neg_hi:[0,1]
	v_fma_f32 v63, -v60, v62, 1.0
	v_fmac_f32_e32 v62, v63, v62
	v_div_scale_f32 v63, vcc, 1.0, v58, 1.0
	v_mul_f32_e32 v64, v63, v62
	v_fma_f32 v76, -v60, v64, v63
	v_fmac_f32_e32 v64, v76, v62
	v_fma_f32 v60, -v60, v64, v63
	v_div_fmas_f32 v60, v60, v62, v64
	v_div_fixup_f32 v58, v60, v58, 1.0
	v_pk_fma_f32 v[52:53], v[58:59], v[56:57], v[52:53]
	v_cvt_f32_f16_e32 v58, v61
	v_cvt_pk_f16_f32 v52, v52, v53
	v_div_scale_f32 v53, s[0:1], v55, v55, 1.0
	v_rcp_f32_e32 v60, v53
	v_cvt_f32_f16_sdwa v59, v61 dst_sel:DWORD dst_unused:UNUSED_PAD src0_sel:WORD_1
	v_cvt_f32_f16_e32 v56, v65
	v_cvt_f32_f16_sdwa v57, v65 dst_sel:DWORD dst_unused:UNUSED_PAD src0_sel:WORD_1
	v_fma_f32 v61, -v53, v60, 1.0
	v_fmac_f32_e32 v60, v61, v60
	v_div_scale_f32 v61, vcc, 1.0, v55, 1.0
	v_mul_f32_e32 v62, v61, v60
	v_fma_f32 v63, -v53, v62, v61
	v_fmac_f32_e32 v62, v63, v60
	v_fma_f32 v53, -v53, v62, v61
	v_div_fmas_f32 v53, v53, v60, v62
	v_div_fixup_f32 v55, v53, v55, 1.0
	v_div_scale_f32 v53, s[0:1], v54, v54, 1.0
	v_rcp_f32_e32 v60, v53
	v_pk_add_f32 v[58:59], v[58:59], v[56:57] neg_lo:[0,1] neg_hi:[0,1]
	v_fma_f32 v61, -v53, v60, 1.0
	v_fmac_f32_e32 v60, v61, v60
	v_div_scale_f32 v61, vcc, 1.0, v54, 1.0
	v_mul_f32_e32 v62, v61, v60
	v_fma_f32 v63, -v53, v62, v61
	v_fmac_f32_e32 v62, v63, v60
	v_fma_f32 v53, -v53, v62, v61
	v_div_fmas_f32 v53, v53, v60, v62
	v_div_fixup_f32 v54, v53, v54, 1.0
	v_pk_fma_f32 v[54:55], v[54:55], v[58:59], v[56:57]
	s_nop 0
	v_cvt_pk_f16_f32 v53, v54, v55
	global_store_dwordx4 v[74:75], v[50:53], off
	v_lshl_add_u64 v[58:59], v[130:131], 0, v[82:83]
	global_load_dwordx4 v[54:57], v[58:59], off
	global_load_dwordx4 v[50:53], v[132:133], off offset:256
	v_add_f32_e32 v42, v42, v66
	v_mul_f32_e32 v42, 0xbfb8aa3b, v42
	v_exp_f32_e32 v60, v42
	v_add_f32_e32 v42, v47, v71
	v_mul_f32_e32 v42, 0xbfb8aa3b, v42
	v_exp_f32_e32 v65, v42
	v_add_f32_e32 v42, v43, v67
	v_mul_f32_e32 v42, 0xbfb8aa3b, v42
	v_add_f32_e32 v46, v46, v70
	v_exp_f32_e32 v61, v42
	v_add_f32_e32 v42, v48, v72
	v_mul_f32_e32 v46, 0xbfb8aa3b, v46
	v_mul_f32_e32 v42, 0xbfb8aa3b, v42
	v_exp_f32_e32 v64, v46
	v_exp_f32_e32 v62, v42
	v_add_f32_e32 v42, v44, v68
	v_mul_f32_e32 v42, 0xbfb8aa3b, v42
	v_exp_f32_e32 v46, v42
	v_add_f32_e32 v42, v49, v73
	v_mul_f32_e32 v42, 0xbfb8aa3b, v42
	v_exp_f32_e32 v63, v42
	v_add_f32_e32 v42, v45, v69
	v_pk_add_f32 v[48:49], v[64:65], 1.0 op_sel_hi:[1,0]
	v_mul_f32_e32 v42, 0xbfb8aa3b, v42
	v_exp_f32_e32 v47, v42
	s_waitcnt vmcnt(0)
; __device__ __forceinline__ float sigmoidf_(float x) { return 1.0f / (1.0f + __expf(-x)); }
;     template <int GI>
;     __device__ __forceinline__ void body(const f32x4 (&acc)[2][2][4][2], int row0, int colt) const {
;     ...
;                         *(u32x4*)(Gb + row * DM + c) = pack8(x0, x1);
;                     } else {
;                         h16* vp = C1 + row * LDC1 + 4096 + c;
;                         const h16x8 vv = *(const h16x8*)vp; const h16x8 vf = *(const h16x8*)(VF + row * DM + c);
;                         f32x4 o0, o1;
; #pragma unroll
;                         for (int j = 0; j < 4; ++j) { float v = (float)vv[j], f = (float)vf[j]; o0[j] = v + (f - v) * sigmoidf_(x0[j]); v = (float)vv[4 + j]; f = (float)vf[4 + j]; o1[j] = v + (f - v) * sigmoidf_(x1[j]); }
;                         *(u32x4*)vp = pack8(o0, o1);
;                     }
;                     __builtin_amdgcn_sched_barrier(0);
	v_cvt_f32_f16_e32 v42, v54
	v_cvt_f32_f16_e32 v44, v50
	v_cvt_f32_f16_sdwa v45, v50 dst_sel:DWORD dst_unused:UNUSED_PAD src0_sel:WORD_1
	v_div_scale_f32 v50, s[0:1], v49, v49, 1.0
	v_cvt_f32_f16_sdwa v43, v54 dst_sel:DWORD dst_unused:UNUSED_PAD src0_sel:WORD_1
	v_rcp_f32_e32 v54, v50
	v_pk_add_f32 v[46:47], v[46:47], 1.0 op_sel_hi:[1,0]
	v_pk_add_f32 v[44:45], v[44:45], v[42:43] neg_lo:[0,1] neg_hi:[0,1]
	v_fma_f32 v64, -v50, v54, 1.0
	v_fmac_f32_e32 v54, v64, v54
	v_div_scale_f32 v64, vcc, 1.0, v49, 1.0
	v_mul_f32_e32 v65, v64, v54
	v_fma_f32 v74, -v50, v65, v64
	v_fmac_f32_e32 v65, v74, v54
	v_fma_f32 v50, -v50, v65, v64
	v_div_fmas_f32 v50, v50, v54, v65
	v_div_fixup_f32 v49, v50, v49, 1.0
	v_div_scale_f32 v50, s[0:1], v48, v48, 1.0
	v_rcp_f32_e32 v54, v50
	s_nop 0
	v_fma_f32 v64, -v50, v54, 1.0
	v_fmac_f32_e32 v54, v64, v54
	v_div_scale_f32 v64, vcc, 1.0, v48, 1.0
	v_mul_f32_e32 v65, v64, v54
	v_fma_f32 v74, -v50, v65, v64
	v_fmac_f32_e32 v65, v74, v54
	v_fma_f32 v50, -v50, v65, v64
	v_div_fmas_f32 v50, v50, v54, v65
	v_div_fixup_f32 v48, v50, v48, 1.0
	v_pk_fma_f32 v[42:43], v[48:49], v[44:45], v[42:43]
	v_cvt_f32_f16_e32 v48, v51
	v_cvt_f32_f16_sdwa v49, v51 dst_sel:DWORD dst_unused:UNUSED_PAD src0_sel:WORD_1
	v_pk_add_f32 v[50:51], v[62:63], 1.0 op_sel_hi:[1,0]
	v_cvt_pk_f16_f32 v42, v42, v43
	v_div_scale_f32 v43, s[0:1], v51, v51, 1.0
	v_rcp_f32_e32 v54, v43
	v_cvt_f32_f16_e32 v44, v55
	v_cvt_f32_f16_sdwa v45, v55 dst_sel:DWORD dst_unused:UNUSED_PAD src0_sel:WORD_1
	v_fma_f32 v55, -v43, v54, 1.0
	v_fmac_f32_e32 v54, v55, v54
	v_div_scale_f32 v55, vcc, 1.0, v51, 1.0
	v_mul_f32_e32 v62, v55, v54
	v_fma_f32 v63, -v43, v62, v55
	v_fmac_f32_e32 v62, v63, v54
	v_fma_f32 v43, -v43, v62, v55
	v_div_fmas_f32 v43, v43, v54, v62
	v_div_fixup_f32 v51, v43, v51, 1.0
	v_div_scale_f32 v43, s[0:1], v50, v50, 1.0
	v_rcp_f32_e32 v54, v43
	v_pk_add_f32 v[48:49], v[48:49], v[44:45] neg_lo:[0,1] neg_hi:[0,1]
	v_fma_f32 v55, -v43, v54, 1.0
	v_fmac_f32_e32 v54, v55, v54
	v_div_scale_f32 v55, vcc, 1.0, v50, 1.0
	v_mul_f32_e32 v62, v55, v54
	v_fma_f32 v63, -v43, v62, v55
	v_fmac_f32_e32 v62, v63, v54
	v_fma_f32 v43, -v43, v62, v55
	v_div_fmas_f32 v43, v43, v54, v62
	v_div_fixup_f32 v50, v43, v50, 1.0
	v_pk_fma_f32 v[44:45], v[50:51], v[48:49], v[44:45]
	v_pk_add_f32 v[50:51], v[60:61], 1.0 op_sel_hi:[1,0]
	v_cvt_f32_f16_e32 v48, v52
	v_cvt_f32_f16_sdwa v49, v52 dst_sel:DWORD dst_unused:UNUSED_PAD src0_sel:WORD_1
	v_div_scale_f32 v52, s[0:1], v51, v51, 1.0
	v_rcp_f32_e32 v54, v52
	v_cvt_pk_f16_f32 v43, v44, v45
	v_cvt_f32_f16_e32 v44, v56
	v_cvt_f32_f16_sdwa v45, v56 dst_sel:DWORD dst_unused:UNUSED_PAD src0_sel:WORD_1
	v_fma_f32 v55, -v52, v54, 1.0
	v_fmac_f32_e32 v54, v55, v54
	v_div_scale_f32 v55, vcc, 1.0, v51, 1.0
	v_mul_f32_e32 v56, v55, v54
	v_fma_f32 v60, -v52, v56, v55
	v_fmac_f32_e32 v56, v60, v54
	v_fma_f32 v52, -v52, v56, v55
	v_div_fmas_f32 v52, v52, v54, v56
	v_div_fixup_f32 v51, v52, v51, 1.0
	v_div_scale_f32 v52, s[0:1], v50, v50, 1.0
	v_rcp_f32_e32 v54, v52
	v_pk_add_f32 v[48:49], v[48:49], v[44:45] neg_lo:[0,1] neg_hi:[0,1]
	v_fma_f32 v55, -v52, v54, 1.0
	v_fmac_f32_e32 v54, v55, v54
	v_div_scale_f32 v55, vcc, 1.0, v50, 1.0
	v_mul_f32_e32 v56, v55, v54
	v_fma_f32 v60, -v52, v56, v55
	v_fmac_f32_e32 v56, v60, v54
	v_fma_f32 v52, -v52, v56, v55
	v_div_fmas_f32 v52, v52, v54, v56
	v_div_fixup_f32 v50, v52, v50, 1.0
	v_pk_fma_f32 v[44:45], v[50:51], v[48:49], v[44:45]
	v_cvt_f32_f16_e32 v50, v53
	v_cvt_pk_f16_f32 v44, v44, v45
	v_div_scale_f32 v45, s[0:1], v47, v47, 1.0
	v_rcp_f32_e32 v52, v45
	v_cvt_f32_f16_sdwa v51, v53 dst_sel:DWORD dst_unused:UNUSED_PAD src0_sel:WORD_1
	v_cvt_f32_f16_e32 v48, v57
	v_cvt_f32_f16_sdwa v49, v57 dst_sel:DWORD dst_unused:UNUSED_PAD src0_sel:WORD_1
	v_fma_f32 v53, -v45, v52, 1.0
	v_fmac_f32_e32 v52, v53, v52
	v_div_scale_f32 v53, vcc, 1.0, v47, 1.0
	v_mul_f32_e32 v54, v53, v52
	v_fma_f32 v55, -v45, v54, v53
	v_fmac_f32_e32 v54, v55, v52
	v_fma_f32 v45, -v45, v54, v53
	v_div_fmas_f32 v45, v45, v52, v54
	v_div_fixup_f32 v47, v45, v47, 1.0
	v_div_scale_f32 v45, s[0:1], v46, v46, 1.0
	v_rcp_f32_e32 v52, v45
	v_pk_add_f32 v[50:51], v[50:51], v[48:49] neg_lo:[0,1] neg_hi:[0,1]
	v_fma_f32 v53, -v45, v52, 1.0
	v_fmac_f32_e32 v52, v53, v52
	v_div_scale_f32 v53, vcc, 1.0, v46, 1.0
	v_mul_f32_e32 v54, v53, v52
	v_fma_f32 v55, -v45, v54, v53
	v_fmac_f32_e32 v54, v55, v52
	v_fma_f32 v45, -v45, v54, v53
	v_div_fmas_f32 v45, v45, v52, v54
	v_div_fixup_f32 v46, v45, v46, 1.0
	v_pk_fma_f32 v[46:47], v[46:47], v[50:51], v[48:49]
	s_nop 0
	v_cvt_pk_f16_f32 v45, v46, v47
	global_store_dwordx4 v[58:59], v[42:45], off
	v_lshl_add_u64 v[50:51], v[122:123], 0, v[82:83]
	global_load_dwordx4 v[46:49], v[50:51], off
	global_load_dwordx4 v[42:45], v[124:125], off offset:256
	v_add_f32_e32 v34, v34, v66
	v_mul_f32_e32 v34, 0xbfb8aa3b, v34
	v_exp_f32_e32 v52, v34
	v_add_f32_e32 v34, v39, v71
	v_mul_f32_e32 v34, 0xbfb8aa3b, v34
	v_exp_f32_e32 v57, v34
	v_add_f32_e32 v34, v35, v67
	v_mul_f32_e32 v34, 0xbfb8aa3b, v34
	v_add_f32_e32 v38, v38, v70
	v_exp_f32_e32 v53, v34
	v_add_f32_e32 v34, v40, v72
	v_mul_f32_e32 v38, 0xbfb8aa3b, v38
	v_mul_f32_e32 v34, 0xbfb8aa3b, v34
	v_exp_f32_e32 v56, v38
	v_exp_f32_e32 v54, v34
	v_add_f32_e32 v34, v36, v68
	v_mul_f32_e32 v34, 0xbfb8aa3b, v34
	v_exp_f32_e32 v38, v34
	v_add_f32_e32 v34, v41, v73
	v_mul_f32_e32 v34, 0xbfb8aa3b, v34
	v_exp_f32_e32 v55, v34
	v_add_f32_e32 v34, v37, v69
	v_pk_add_f32 v[40:41], v[56:57], 1.0 op_sel_hi:[1,0]
	v_mul_f32_e32 v34, 0xbfb8aa3b, v34
	v_exp_f32_e32 v39, v34
	s_waitcnt vmcnt(0)
; __device__ __forceinline__ float sigmoidf_(float x) { return 1.0f / (1.0f + __expf(-x)); }
;     template <int GI>
;     __device__ __forceinline__ void body(const f32x4 (&acc)[2][2][4][2], int row0, int colt) const {
;     ...
;                         *(u32x4*)(Gb + row * DM + c) = pack8(x0, x1);
;                     } else {
;                         h16* vp = C1 + row * LDC1 + 4096 + c;
;                         const h16x8 vv = *(const h16x8*)vp; const h16x8 vf = *(const h16x8*)(VF + row * DM + c);
;                         f32x4 o0, o1;
; #pragma unroll
;                         for (int j = 0; j < 4; ++j) { float v = (float)vv[j], f = (float)vf[j]; o0[j] = v + (f - v) * sigmoidf_(x0[j]); v = (float)vv[4 + j]; f = (float)vf[4 + j]; o1[j] = v + (f - v) * sigmoidf_(x1[j]); }
;                         *(u32x4*)vp = pack8(o0, o1);
;                     }
;                     __builtin_amdgcn_sched_barrier(0);
	v_cvt_f32_f16_e32 v34, v46
	v_cvt_f32_f16_e32 v36, v42
	v_cvt_f32_f16_sdwa v37, v42 dst_sel:DWORD dst_unused:UNUSED_PAD src0_sel:WORD_1
	v_div_scale_f32 v42, s[0:1], v41, v41, 1.0
	v_cvt_f32_f16_sdwa v35, v46 dst_sel:DWORD dst_unused:UNUSED_PAD src0_sel:WORD_1
	v_rcp_f32_e32 v46, v42
	v_pk_add_f32 v[38:39], v[38:39], 1.0 op_sel_hi:[1,0]
	v_pk_add_f32 v[36:37], v[36:37], v[34:35] neg_lo:[0,1] neg_hi:[0,1]
	v_fma_f32 v56, -v42, v46, 1.0
	v_fmac_f32_e32 v46, v56, v46
	v_div_scale_f32 v56, vcc, 1.0, v41, 1.0
	v_mul_f32_e32 v57, v56, v46
	v_fma_f32 v58, -v42, v57, v56
	v_fmac_f32_e32 v57, v58, v46
	v_fma_f32 v42, -v42, v57, v56
	v_div_fmas_f32 v42, v42, v46, v57
	v_div_fixup_f32 v41, v42, v41, 1.0
	v_div_scale_f32 v42, s[0:1], v40, v40, 1.0
	v_rcp_f32_e32 v46, v42
	s_nop 0
	v_fma_f32 v56, -v42, v46, 1.0
	v_fmac_f32_e32 v46, v56, v46
	v_div_scale_f32 v56, vcc, 1.0, v40, 1.0
	v_mul_f32_e32 v57, v56, v46
	v_fma_f32 v58, -v42, v57, v56
	v_fmac_f32_e32 v57, v58, v46
	v_fma_f32 v42, -v42, v57, v56
	v_div_fmas_f32 v42, v42, v46, v57
	v_div_fixup_f32 v40, v42, v40, 1.0
	v_pk_fma_f32 v[34:35], v[40:41], v[36:37], v[34:35]
	v_cvt_f32_f16_e32 v40, v43
	v_cvt_f32_f16_sdwa v41, v43 dst_sel:DWORD dst_unused:UNUSED_PAD src0_sel:WORD_1
	v_pk_add_f32 v[42:43], v[54:55], 1.0 op_sel_hi:[1,0]
	v_cvt_pk_f16_f32 v34, v34, v35
	v_div_scale_f32 v35, s[0:1], v43, v43, 1.0
	v_rcp_f32_e32 v46, v35
	v_cvt_f32_f16_e32 v36, v47
	v_cvt_f32_f16_sdwa v37, v47 dst_sel:DWORD dst_unused:UNUSED_PAD src0_sel:WORD_1
	v_fma_f32 v47, -v35, v46, 1.0
	v_fmac_f32_e32 v46, v47, v46
	v_div_scale_f32 v47, vcc, 1.0, v43, 1.0
	v_mul_f32_e32 v54, v47, v46
	v_fma_f32 v55, -v35, v54, v47
	v_fmac_f32_e32 v54, v55, v46
	v_fma_f32 v35, -v35, v54, v47
	v_div_fmas_f32 v35, v35, v46, v54
	v_div_fixup_f32 v43, v35, v43, 1.0
	v_div_scale_f32 v35, s[0:1], v42, v42, 1.0
	v_rcp_f32_e32 v46, v35
	v_pk_add_f32 v[40:41], v[40:41], v[36:37] neg_lo:[0,1] neg_hi:[0,1]
	v_fma_f32 v47, -v35, v46, 1.0
	v_fmac_f32_e32 v46, v47, v46
	v_div_scale_f32 v47, vcc, 1.0, v42, 1.0
	v_mul_f32_e32 v54, v47, v46
	v_fma_f32 v55, -v35, v54, v47
	v_fmac_f32_e32 v54, v55, v46
	v_fma_f32 v35, -v35, v54, v47
	v_div_fmas_f32 v35, v35, v46, v54
	v_div_fixup_f32 v42, v35, v42, 1.0
	v_pk_fma_f32 v[36:37], v[42:43], v[40:41], v[36:37]
	v_pk_add_f32 v[42:43], v[52:53], 1.0 op_sel_hi:[1,0]
	v_cvt_f32_f16_e32 v40, v44
	v_cvt_f32_f16_sdwa v41, v44 dst_sel:DWORD dst_unused:UNUSED_PAD src0_sel:WORD_1
	v_div_scale_f32 v44, s[0:1], v43, v43, 1.0
	v_rcp_f32_e32 v46, v44
	v_cvt_pk_f16_f32 v35, v36, v37
	v_cvt_f32_f16_e32 v36, v48
	v_cvt_f32_f16_sdwa v37, v48 dst_sel:DWORD dst_unused:UNUSED_PAD src0_sel:WORD_1
	v_fma_f32 v47, -v44, v46, 1.0
	v_fmac_f32_e32 v46, v47, v46
	v_div_scale_f32 v47, vcc, 1.0, v43, 1.0
	v_mul_f32_e32 v48, v47, v46
	v_fma_f32 v52, -v44, v48, v47
	v_fmac_f32_e32 v48, v52, v46
	v_fma_f32 v44, -v44, v48, v47
	v_div_fmas_f32 v44, v44, v46, v48
	v_div_fixup_f32 v43, v44, v43, 1.0
	v_div_scale_f32 v44, s[0:1], v42, v42, 1.0
	v_rcp_f32_e32 v46, v44
	v_pk_add_f32 v[40:41], v[40:41], v[36:37] neg_lo:[0,1] neg_hi:[0,1]
	v_fma_f32 v47, -v44, v46, 1.0
	v_fmac_f32_e32 v46, v47, v46
	v_div_scale_f32 v47, vcc, 1.0, v42, 1.0
	v_mul_f32_e32 v48, v47, v46
	v_fma_f32 v52, -v44, v48, v47
	v_fmac_f32_e32 v48, v52, v46
	v_fma_f32 v44, -v44, v48, v47
	v_div_fmas_f32 v44, v44, v46, v48
	v_div_fixup_f32 v42, v44, v42, 1.0
	v_pk_fma_f32 v[36:37], v[42:43], v[40:41], v[36:37]
	v_cvt_f32_f16_e32 v42, v45
	v_cvt_pk_f16_f32 v36, v36, v37
	v_div_scale_f32 v37, s[0:1], v39, v39, 1.0
	v_rcp_f32_e32 v44, v37
	v_cvt_f32_f16_sdwa v43, v45 dst_sel:DWORD dst_unused:UNUSED_PAD src0_sel:WORD_1
	v_cvt_f32_f16_e32 v40, v49
	v_cvt_f32_f16_sdwa v41, v49 dst_sel:DWORD dst_unused:UNUSED_PAD src0_sel:WORD_1
	v_fma_f32 v45, -v37, v44, 1.0
	v_fmac_f32_e32 v44, v45, v44
	v_div_scale_f32 v45, vcc, 1.0, v39, 1.0
	v_mul_f32_e32 v46, v45, v44
	v_fma_f32 v47, -v37, v46, v45
	v_fmac_f32_e32 v46, v47, v44
	v_fma_f32 v37, -v37, v46, v45
	v_div_fmas_f32 v37, v37, v44, v46
	v_div_fixup_f32 v39, v37, v39, 1.0
	v_div_scale_f32 v37, s[0:1], v38, v38, 1.0
	v_rcp_f32_e32 v44, v37
	v_pk_add_f32 v[42:43], v[42:43], v[40:41] neg_lo:[0,1] neg_hi:[0,1]
	v_fma_f32 v45, -v37, v44, 1.0
	v_fmac_f32_e32 v44, v45, v44
	v_div_scale_f32 v45, vcc, 1.0, v38, 1.0
	v_mul_f32_e32 v46, v45, v44
	v_fma_f32 v47, -v37, v46, v45
	v_fmac_f32_e32 v46, v47, v44
	v_fma_f32 v37, -v37, v46, v45
	v_div_fmas_f32 v37, v37, v44, v46
	v_div_fixup_f32 v38, v37, v38, 1.0
	v_pk_fma_f32 v[38:39], v[38:39], v[42:43], v[40:41]
	s_nop 0
	v_cvt_pk_f16_f32 v37, v38, v39
	global_store_dwordx4 v[50:51], v[34:37], off
	v_lshl_add_u64 v[42:43], v[114:115], 0, v[82:83]
	global_load_dwordx4 v[38:41], v[42:43], off
	global_load_dwordx4 v[34:37], v[116:117], off offset:256
	v_add_f32_e32 v26, v26, v66
	v_mul_f32_e32 v26, 0xbfb8aa3b, v26
	v_exp_f32_e32 v44, v26
	v_add_f32_e32 v26, v31, v71
	v_mul_f32_e32 v26, 0xbfb8aa3b, v26
	v_exp_f32_e32 v49, v26
	v_add_f32_e32 v26, v27, v67
	v_mul_f32_e32 v26, 0xbfb8aa3b, v26
	v_add_f32_e32 v30, v30, v70
	v_exp_f32_e32 v45, v26
	v_add_f32_e32 v26, v32, v72
	v_mul_f32_e32 v30, 0xbfb8aa3b, v30
	v_mul_f32_e32 v26, 0xbfb8aa3b, v26
	v_exp_f32_e32 v48, v30
	v_exp_f32_e32 v46, v26
	v_add_f32_e32 v26, v28, v68
	v_mul_f32_e32 v26, 0xbfb8aa3b, v26
	v_exp_f32_e32 v30, v26
	v_add_f32_e32 v26, v33, v73
	v_mul_f32_e32 v26, 0xbfb8aa3b, v26
	v_exp_f32_e32 v47, v26
	v_add_f32_e32 v26, v29, v69
	v_pk_add_f32 v[32:33], v[48:49], 1.0 op_sel_hi:[1,0]
	v_mul_f32_e32 v26, 0xbfb8aa3b, v26
	v_exp_f32_e32 v31, v26
	s_waitcnt vmcnt(0)
; __device__ __forceinline__ float sigmoidf_(float x) { return 1.0f / (1.0f + __expf(-x)); }
;     template <int GI>
;     __device__ __forceinline__ void body(const f32x4 (&acc)[2][2][4][2], int row0, int colt) const {
;     ...
;                         *(u32x4*)(Gb + row * DM + c) = pack8(x0, x1);
;                     } else {
;                         h16* vp = C1 + row * LDC1 + 4096 + c;
;                         const h16x8 vv = *(const h16x8*)vp; const h16x8 vf = *(const h16x8*)(VF + row * DM + c);
;                         f32x4 o0, o1;
; #pragma unroll
;                         for (int j = 0; j < 4; ++j) { float v = (float)vv[j], f = (float)vf[j]; o0[j] = v + (f - v) * sigmoidf_(x0[j]); v = (float)vv[4 + j]; f = (float)vf[4 + j]; o1[j] = v + (f - v) * sigmoidf_(x1[j]); }
;                         *(u32x4*)vp = pack8(o0, o1);
;                     }
;                     __builtin_amdgcn_sched_barrier(0);
	v_cvt_f32_f16_e32 v26, v38
	v_cvt_f32_f16_e32 v28, v34
	v_cvt_f32_f16_sdwa v29, v34 dst_sel:DWORD dst_unused:UNUSED_PAD src0_sel:WORD_1
	v_div_scale_f32 v34, s[0:1], v33, v33, 1.0
	v_cvt_f32_f16_sdwa v27, v38 dst_sel:DWORD dst_unused:UNUSED_PAD src0_sel:WORD_1
	v_rcp_f32_e32 v38, v34
	v_pk_add_f32 v[30:31], v[30:31], 1.0 op_sel_hi:[1,0]
	v_pk_add_f32 v[28:29], v[28:29], v[26:27] neg_lo:[0,1] neg_hi:[0,1]
	v_fma_f32 v48, -v34, v38, 1.0
	v_fmac_f32_e32 v38, v48, v38
	v_div_scale_f32 v48, vcc, 1.0, v33, 1.0
	v_mul_f32_e32 v49, v48, v38
	v_fma_f32 v50, -v34, v49, v48
	v_fmac_f32_e32 v49, v50, v38
	v_fma_f32 v34, -v34, v49, v48
	v_div_fmas_f32 v34, v34, v38, v49
	v_div_fixup_f32 v33, v34, v33, 1.0
	v_div_scale_f32 v34, s[0:1], v32, v32, 1.0
	v_rcp_f32_e32 v38, v34
	s_nop 0
	v_fma_f32 v48, -v34, v38, 1.0
	v_fmac_f32_e32 v38, v48, v38
	v_div_scale_f32 v48, vcc, 1.0, v32, 1.0
	v_mul_f32_e32 v49, v48, v38
	v_fma_f32 v50, -v34, v49, v48
	v_fmac_f32_e32 v49, v50, v38
	v_fma_f32 v34, -v34, v49, v48
	v_div_fmas_f32 v34, v34, v38, v49
	v_div_fixup_f32 v32, v34, v32, 1.0
	v_pk_fma_f32 v[26:27], v[32:33], v[28:29], v[26:27]
	v_cvt_f32_f16_e32 v32, v35
	v_cvt_f32_f16_sdwa v33, v35 dst_sel:DWORD dst_unused:UNUSED_PAD src0_sel:WORD_1
	v_pk_add_f32 v[34:35], v[46:47], 1.0 op_sel_hi:[1,0]
	v_cvt_pk_f16_f32 v26, v26, v27
	v_div_scale_f32 v27, s[0:1], v35, v35, 1.0
	v_rcp_f32_e32 v38, v27
	v_cvt_f32_f16_e32 v28, v39
	v_cvt_f32_f16_sdwa v29, v39 dst_sel:DWORD dst_unused:UNUSED_PAD src0_sel:WORD_1
	v_fma_f32 v39, -v27, v38, 1.0
	v_fmac_f32_e32 v38, v39, v38
	v_div_scale_f32 v39, vcc, 1.0, v35, 1.0
	v_mul_f32_e32 v46, v39, v38
	v_fma_f32 v47, -v27, v46, v39
	v_fmac_f32_e32 v46, v47, v38
	v_fma_f32 v27, -v27, v46, v39
	v_div_fmas_f32 v27, v27, v38, v46
	v_div_fixup_f32 v35, v27, v35, 1.0
	v_div_scale_f32 v27, s[0:1], v34, v34, 1.0
	v_rcp_f32_e32 v38, v27
	v_pk_add_f32 v[32:33], v[32:33], v[28:29] neg_lo:[0,1] neg_hi:[0,1]
	v_fma_f32 v39, -v27, v38, 1.0
	v_fmac_f32_e32 v38, v39, v38
	v_div_scale_f32 v39, vcc, 1.0, v34, 1.0
	v_mul_f32_e32 v46, v39, v38
	v_fma_f32 v47, -v27, v46, v39
	v_fmac_f32_e32 v46, v47, v38
	v_fma_f32 v27, -v27, v46, v39
	v_div_fmas_f32 v27, v27, v38, v46
	v_div_fixup_f32 v34, v27, v34, 1.0
	v_pk_fma_f32 v[28:29], v[34:35], v[32:33], v[28:29]
	v_pk_add_f32 v[34:35], v[44:45], 1.0 op_sel_hi:[1,0]
	v_cvt_f32_f16_e32 v32, v36
	v_cvt_f32_f16_sdwa v33, v36 dst_sel:DWORD dst_unused:UNUSED_PAD src0_sel:WORD_1
	v_div_scale_f32 v36, s[0:1], v35, v35, 1.0
	v_rcp_f32_e32 v38, v36
	v_cvt_pk_f16_f32 v27, v28, v29
	v_cvt_f32_f16_e32 v28, v40
	v_cvt_f32_f16_sdwa v29, v40 dst_sel:DWORD dst_unused:UNUSED_PAD src0_sel:WORD_1
	v_fma_f32 v39, -v36, v38, 1.0
	v_fmac_f32_e32 v38, v39, v38
	v_div_scale_f32 v39, vcc, 1.0, v35, 1.0
	v_mul_f32_e32 v40, v39, v38
	v_fma_f32 v44, -v36, v40, v39
	v_fmac_f32_e32 v40, v44, v38
	v_fma_f32 v36, -v36, v40, v39
	v_div_fmas_f32 v36, v36, v38, v40
	v_div_fixup_f32 v35, v36, v35, 1.0
	v_div_scale_f32 v36, s[0:1], v34, v34, 1.0
	v_rcp_f32_e32 v38, v36
	v_pk_add_f32 v[32:33], v[32:33], v[28:29] neg_lo:[0,1] neg_hi:[0,1]
	v_fma_f32 v39, -v36, v38, 1.0
	v_fmac_f32_e32 v38, v39, v38
	v_div_scale_f32 v39, vcc, 1.0, v34, 1.0
	v_mul_f32_e32 v40, v39, v38
	v_fma_f32 v44, -v36, v40, v39
	v_fmac_f32_e32 v40, v44, v38
	v_fma_f32 v36, -v36, v40, v39
	v_div_fmas_f32 v36, v36, v38, v40
	v_div_fixup_f32 v34, v36, v34, 1.0
	v_pk_fma_f32 v[28:29], v[34:35], v[32:33], v[28:29]
	v_cvt_f32_f16_e32 v34, v37
	v_cvt_pk_f16_f32 v28, v28, v29
	v_div_scale_f32 v29, s[0:1], v31, v31, 1.0
	v_rcp_f32_e32 v36, v29
	v_cvt_f32_f16_sdwa v35, v37 dst_sel:DWORD dst_unused:UNUSED_PAD src0_sel:WORD_1
	v_cvt_f32_f16_e32 v32, v41
	v_cvt_f32_f16_sdwa v33, v41 dst_sel:DWORD dst_unused:UNUSED_PAD src0_sel:WORD_1
	v_fma_f32 v37, -v29, v36, 1.0
	v_fmac_f32_e32 v36, v37, v36
	v_div_scale_f32 v37, vcc, 1.0, v31, 1.0
	v_mul_f32_e32 v38, v37, v36
	v_fma_f32 v39, -v29, v38, v37
	v_fmac_f32_e32 v38, v39, v36
	v_fma_f32 v29, -v29, v38, v37
	v_div_fmas_f32 v29, v29, v36, v38
	v_div_fixup_f32 v31, v29, v31, 1.0
	v_div_scale_f32 v29, s[0:1], v30, v30, 1.0
	v_rcp_f32_e32 v36, v29
	v_pk_add_f32 v[34:35], v[34:35], v[32:33] neg_lo:[0,1] neg_hi:[0,1]
	v_fma_f32 v37, -v29, v36, 1.0
	v_fmac_f32_e32 v36, v37, v36
	v_div_scale_f32 v37, vcc, 1.0, v30, 1.0
	v_mul_f32_e32 v38, v37, v36
	v_fma_f32 v39, -v29, v38, v37
	v_fmac_f32_e32 v38, v39, v36
	v_fma_f32 v29, -v29, v38, v37
	v_div_fmas_f32 v29, v29, v36, v38
	v_div_fixup_f32 v30, v29, v30, 1.0
	v_pk_fma_f32 v[30:31], v[30:31], v[34:35], v[32:33]
	s_nop 0
	v_cvt_pk_f16_f32 v29, v30, v31
	global_store_dwordx4 v[42:43], v[26:29], off
	v_lshl_add_u64 v[34:35], v[106:107], 0, v[82:83]
	global_load_dwordx4 v[30:33], v[34:35], off
	global_load_dwordx4 v[26:29], v[108:109], off offset:256
	v_add_f32_e32 v18, v18, v66
	v_mul_f32_e32 v18, 0xbfb8aa3b, v18
	v_exp_f32_e32 v36, v18
	v_add_f32_e32 v18, v23, v71
	v_mul_f32_e32 v18, 0xbfb8aa3b, v18
	v_exp_f32_e32 v41, v18
	v_add_f32_e32 v18, v19, v67
	v_mul_f32_e32 v18, 0xbfb8aa3b, v18
	v_add_f32_e32 v22, v22, v70
	v_exp_f32_e32 v37, v18
	v_add_f32_e32 v18, v24, v72
	v_mul_f32_e32 v22, 0xbfb8aa3b, v22
	v_mul_f32_e32 v18, 0xbfb8aa3b, v18
	v_exp_f32_e32 v40, v22
	v_exp_f32_e32 v38, v18
	v_add_f32_e32 v18, v20, v68
	v_mul_f32_e32 v18, 0xbfb8aa3b, v18
	v_exp_f32_e32 v22, v18
	v_add_f32_e32 v18, v25, v73
	v_mul_f32_e32 v18, 0xbfb8aa3b, v18
	v_exp_f32_e32 v39, v18
	v_add_f32_e32 v18, v21, v69
	v_pk_add_f32 v[24:25], v[40:41], 1.0 op_sel_hi:[1,0]
	v_mul_f32_e32 v18, 0xbfb8aa3b, v18
	v_exp_f32_e32 v23, v18
	s_waitcnt vmcnt(0)
; __device__ __forceinline__ float sigmoidf_(float x) { return 1.0f / (1.0f + __expf(-x)); }
;     template <int GI>
;     __device__ __forceinline__ void body(const f32x4 (&acc)[2][2][4][2], int row0, int colt) const {
;     ...
;                         *(u32x4*)(Gb + row * DM + c) = pack8(x0, x1);
;                     } else {
;                         h16* vp = C1 + row * LDC1 + 4096 + c;
;                         const h16x8 vv = *(const h16x8*)vp; const h16x8 vf = *(const h16x8*)(VF + row * DM + c);
;                         f32x4 o0, o1;
; #pragma unroll
;                         for (int j = 0; j < 4; ++j) { float v = (float)vv[j], f = (float)vf[j]; o0[j] = v + (f - v) * sigmoidf_(x0[j]); v = (float)vv[4 + j]; f = (float)vf[4 + j]; o1[j] = v + (f - v) * sigmoidf_(x1[j]); }
;                         *(u32x4*)vp = pack8(o0, o1);
;                     }
;                     __builtin_amdgcn_sched_barrier(0);
	v_cvt_f32_f16_e32 v18, v30
	v_cvt_f32_f16_e32 v20, v26
	v_cvt_f32_f16_sdwa v21, v26 dst_sel:DWORD dst_unused:UNUSED_PAD src0_sel:WORD_1
	v_div_scale_f32 v26, s[0:1], v25, v25, 1.0
	v_cvt_f32_f16_sdwa v19, v30 dst_sel:DWORD dst_unused:UNUSED_PAD src0_sel:WORD_1
	v_rcp_f32_e32 v30, v26
	v_pk_add_f32 v[22:23], v[22:23], 1.0 op_sel_hi:[1,0]
	v_pk_add_f32 v[20:21], v[20:21], v[18:19] neg_lo:[0,1] neg_hi:[0,1]
	v_fma_f32 v40, -v26, v30, 1.0
	v_fmac_f32_e32 v30, v40, v30
	v_div_scale_f32 v40, vcc, 1.0, v25, 1.0
	v_mul_f32_e32 v41, v40, v30
	v_fma_f32 v42, -v26, v41, v40
	v_fmac_f32_e32 v41, v42, v30
	v_fma_f32 v26, -v26, v41, v40
	v_div_fmas_f32 v26, v26, v30, v41
	v_div_fixup_f32 v25, v26, v25, 1.0
	v_div_scale_f32 v26, s[0:1], v24, v24, 1.0
	v_rcp_f32_e32 v30, v26
	s_nop 0
	v_fma_f32 v40, -v26, v30, 1.0
	v_fmac_f32_e32 v30, v40, v30
	v_div_scale_f32 v40, vcc, 1.0, v24, 1.0
	v_mul_f32_e32 v41, v40, v30
	v_fma_f32 v42, -v26, v41, v40
	v_fmac_f32_e32 v41, v42, v30
	v_fma_f32 v26, -v26, v41, v40
	v_div_fmas_f32 v26, v26, v30, v41
	v_div_fixup_f32 v24, v26, v24, 1.0
	v_pk_fma_f32 v[18:19], v[24:25], v[20:21], v[18:19]
	v_cvt_f32_f16_e32 v24, v27
	v_cvt_f32_f16_sdwa v25, v27 dst_sel:DWORD dst_unused:UNUSED_PAD src0_sel:WORD_1
	v_pk_add_f32 v[26:27], v[38:39], 1.0 op_sel_hi:[1,0]
	v_cvt_pk_f16_f32 v18, v18, v19
	v_div_scale_f32 v19, s[0:1], v27, v27, 1.0
	v_rcp_f32_e32 v30, v19
	v_cvt_f32_f16_e32 v20, v31
	v_cvt_f32_f16_sdwa v21, v31 dst_sel:DWORD dst_unused:UNUSED_PAD src0_sel:WORD_1
	v_fma_f32 v31, -v19, v30, 1.0
	v_fmac_f32_e32 v30, v31, v30
	v_div_scale_f32 v31, vcc, 1.0, v27, 1.0
	v_mul_f32_e32 v38, v31, v30
	v_fma_f32 v39, -v19, v38, v31
	v_fmac_f32_e32 v38, v39, v30
	v_fma_f32 v19, -v19, v38, v31
	v_div_fmas_f32 v19, v19, v30, v38
	v_div_fixup_f32 v27, v19, v27, 1.0
	v_div_scale_f32 v19, s[0:1], v26, v26, 1.0
	v_rcp_f32_e32 v30, v19
	v_pk_add_f32 v[24:25], v[24:25], v[20:21] neg_lo:[0,1] neg_hi:[0,1]
	v_fma_f32 v31, -v19, v30, 1.0
	v_fmac_f32_e32 v30, v31, v30
	v_div_scale_f32 v31, vcc, 1.0, v26, 1.0
	v_mul_f32_e32 v38, v31, v30
	v_fma_f32 v39, -v19, v38, v31
	v_fmac_f32_e32 v38, v39, v30
	v_fma_f32 v19, -v19, v38, v31
	v_div_fmas_f32 v19, v19, v30, v38
	v_div_fixup_f32 v26, v19, v26, 1.0
	v_pk_fma_f32 v[20:21], v[26:27], v[24:25], v[20:21]
	v_pk_add_f32 v[26:27], v[36:37], 1.0 op_sel_hi:[1,0]
	v_cvt_f32_f16_e32 v24, v28
	v_cvt_f32_f16_sdwa v25, v28 dst_sel:DWORD dst_unused:UNUSED_PAD src0_sel:WORD_1
	v_div_scale_f32 v28, s[0:1], v27, v27, 1.0
	v_rcp_f32_e32 v30, v28
	v_cvt_pk_f16_f32 v19, v20, v21
	v_cvt_f32_f16_e32 v20, v32
	v_cvt_f32_f16_sdwa v21, v32 dst_sel:DWORD dst_unused:UNUSED_PAD src0_sel:WORD_1
	v_fma_f32 v31, -v28, v30, 1.0
	v_fmac_f32_e32 v30, v31, v30
	v_div_scale_f32 v31, vcc, 1.0, v27, 1.0
	v_mul_f32_e32 v32, v31, v30
	v_fma_f32 v36, -v28, v32, v31
	v_fmac_f32_e32 v32, v36, v30
	v_fma_f32 v28, -v28, v32, v31
	v_div_fmas_f32 v28, v28, v30, v32
	v_div_fixup_f32 v27, v28, v27, 1.0
	v_div_scale_f32 v28, s[0:1], v26, v26, 1.0
	v_rcp_f32_e32 v30, v28
	v_pk_add_f32 v[24:25], v[24:25], v[20:21] neg_lo:[0,1] neg_hi:[0,1]
	v_fma_f32 v31, -v28, v30, 1.0
	v_fmac_f32_e32 v30, v31, v30
	v_div_scale_f32 v31, vcc, 1.0, v26, 1.0
	v_mul_f32_e32 v32, v31, v30
	v_fma_f32 v36, -v28, v32, v31
	v_fmac_f32_e32 v32, v36, v30
	v_fma_f32 v28, -v28, v32, v31
	v_div_fmas_f32 v28, v28, v30, v32
	v_div_fixup_f32 v26, v28, v26, 1.0
	v_pk_fma_f32 v[20:21], v[26:27], v[24:25], v[20:21]
	v_cvt_f32_f16_e32 v26, v29
	v_cvt_pk_f16_f32 v20, v20, v21
	v_div_scale_f32 v21, s[0:1], v23, v23, 1.0
	v_rcp_f32_e32 v28, v21
	v_cvt_f32_f16_sdwa v27, v29 dst_sel:DWORD dst_unused:UNUSED_PAD src0_sel:WORD_1
	v_cvt_f32_f16_e32 v24, v33
	v_cvt_f32_f16_sdwa v25, v33 dst_sel:DWORD dst_unused:UNUSED_PAD src0_sel:WORD_1
	v_fma_f32 v29, -v21, v28, 1.0
	v_fmac_f32_e32 v28, v29, v28
	v_div_scale_f32 v29, vcc, 1.0, v23, 1.0
	v_mul_f32_e32 v30, v29, v28
	v_fma_f32 v31, -v21, v30, v29
	v_fmac_f32_e32 v30, v31, v28
	v_fma_f32 v21, -v21, v30, v29
	v_div_fmas_f32 v21, v21, v28, v30
	v_div_fixup_f32 v23, v21, v23, 1.0
	v_div_scale_f32 v21, s[0:1], v22, v22, 1.0
	v_rcp_f32_e32 v28, v21
	v_pk_add_f32 v[26:27], v[26:27], v[24:25] neg_lo:[0,1] neg_hi:[0,1]
	v_fma_f32 v29, -v21, v28, 1.0
	v_fmac_f32_e32 v28, v29, v28
	v_div_scale_f32 v29, vcc, 1.0, v22, 1.0
	v_mul_f32_e32 v30, v29, v28
	v_fma_f32 v31, -v21, v30, v29
	v_fmac_f32_e32 v30, v31, v28
	v_fma_f32 v21, -v21, v30, v29
	v_div_fmas_f32 v21, v21, v28, v30
	v_div_fixup_f32 v22, v21, v22, 1.0
	v_pk_fma_f32 v[22:23], v[22:23], v[26:27], v[24:25]
	s_nop 0
	v_cvt_pk_f16_f32 v21, v22, v23
	global_store_dwordx4 v[34:35], v[18:21], off
	v_lshl_add_u64 v[26:27], v[98:99], 0, v[82:83]
	global_load_dwordx4 v[22:25], v[26:27], off
	global_load_dwordx4 v[18:21], v[100:101], off offset:256
	v_add_f32_e32 v10, v10, v66
	v_mul_f32_e32 v10, 0xbfb8aa3b, v10
	v_exp_f32_e32 v28, v10
	v_add_f32_e32 v10, v15, v71
	v_mul_f32_e32 v10, 0xbfb8aa3b, v10
	v_exp_f32_e32 v33, v10
	v_add_f32_e32 v10, v11, v67
	v_mul_f32_e32 v10, 0xbfb8aa3b, v10
	v_add_f32_e32 v14, v14, v70
	v_exp_f32_e32 v29, v10
	v_add_f32_e32 v10, v16, v72
	v_mul_f32_e32 v14, 0xbfb8aa3b, v14
	v_mul_f32_e32 v10, 0xbfb8aa3b, v10
	v_exp_f32_e32 v32, v14
	v_exp_f32_e32 v30, v10
	v_add_f32_e32 v10, v12, v68
	v_mul_f32_e32 v10, 0xbfb8aa3b, v10
	v_exp_f32_e32 v14, v10
	v_add_f32_e32 v10, v17, v73
	v_mul_f32_e32 v10, 0xbfb8aa3b, v10
	v_exp_f32_e32 v31, v10
	v_add_f32_e32 v10, v13, v69
	v_pk_add_f32 v[16:17], v[32:33], 1.0 op_sel_hi:[1,0]
	v_mul_f32_e32 v10, 0xbfb8aa3b, v10
	v_exp_f32_e32 v15, v10
	s_waitcnt vmcnt(0)
; __device__ __forceinline__ float sigmoidf_(float x) { return 1.0f / (1.0f + __expf(-x)); }
;     template <int GI>
;     __device__ __forceinline__ void body(const f32x4 (&acc)[2][2][4][2], int row0, int colt) const {
;     ...
;                         *(u32x4*)(Gb + row * DM + c) = pack8(x0, x1);
;                     } else {
;                         h16* vp = C1 + row * LDC1 + 4096 + c;
;                         const h16x8 vv = *(const h16x8*)vp; const h16x8 vf = *(const h16x8*)(VF + row * DM + c);
;                         f32x4 o0, o1;
; #pragma unroll
;                         for (int j = 0; j < 4; ++j) { float v = (float)vv[j], f = (float)vf[j]; o0[j] = v + (f - v) * sigmoidf_(x0[j]); v = (float)vv[4 + j]; f = (float)vf[4 + j]; o1[j] = v + (f - v) * sigmoidf_(x1[j]); }
;                         *(u32x4*)vp = pack8(o0, o1);
;                     }
;                     __builtin_amdgcn_sched_barrier(0);
	v_cvt_f32_f16_e32 v10, v22
	v_cvt_f32_f16_e32 v12, v18
	v_cvt_f32_f16_sdwa v13, v18 dst_sel:DWORD dst_unused:UNUSED_PAD src0_sel:WORD_1
	v_div_scale_f32 v18, s[0:1], v17, v17, 1.0
	v_cvt_f32_f16_sdwa v11, v22 dst_sel:DWORD dst_unused:UNUSED_PAD src0_sel:WORD_1
	v_rcp_f32_e32 v22, v18
	v_pk_add_f32 v[14:15], v[14:15], 1.0 op_sel_hi:[1,0]
	v_pk_add_f32 v[12:13], v[12:13], v[10:11] neg_lo:[0,1] neg_hi:[0,1]
	v_fma_f32 v32, -v18, v22, 1.0
	v_fmac_f32_e32 v22, v32, v22
	v_div_scale_f32 v32, vcc, 1.0, v17, 1.0
	v_mul_f32_e32 v33, v32, v22
	v_fma_f32 v34, -v18, v33, v32
	v_fmac_f32_e32 v33, v34, v22
	v_fma_f32 v18, -v18, v33, v32
	v_div_fmas_f32 v18, v18, v22, v33
	v_div_fixup_f32 v17, v18, v17, 1.0
	v_div_scale_f32 v18, s[0:1], v16, v16, 1.0
	v_rcp_f32_e32 v22, v18
	s_nop 0
	v_fma_f32 v32, -v18, v22, 1.0
	v_fmac_f32_e32 v22, v32, v22
	v_div_scale_f32 v32, vcc, 1.0, v16, 1.0
	v_mul_f32_e32 v33, v32, v22
	v_fma_f32 v34, -v18, v33, v32
	v_fmac_f32_e32 v33, v34, v22
	v_fma_f32 v18, -v18, v33, v32
	v_div_fmas_f32 v18, v18, v22, v33
	v_div_fixup_f32 v16, v18, v16, 1.0
	v_pk_fma_f32 v[10:11], v[16:17], v[12:13], v[10:11]
	v_cvt_f32_f16_e32 v16, v19
	v_cvt_f32_f16_sdwa v17, v19 dst_sel:DWORD dst_unused:UNUSED_PAD src0_sel:WORD_1
	v_pk_add_f32 v[18:19], v[30:31], 1.0 op_sel_hi:[1,0]
	v_cvt_pk_f16_f32 v10, v10, v11
	v_div_scale_f32 v11, s[0:1], v19, v19, 1.0
	v_rcp_f32_e32 v22, v11
	v_cvt_f32_f16_e32 v12, v23
	v_cvt_f32_f16_sdwa v13, v23 dst_sel:DWORD dst_unused:UNUSED_PAD src0_sel:WORD_1
	v_fma_f32 v23, -v11, v22, 1.0
	v_fmac_f32_e32 v22, v23, v22
	v_div_scale_f32 v23, vcc, 1.0, v19, 1.0
	v_mul_f32_e32 v30, v23, v22
	v_fma_f32 v31, -v11, v30, v23
	v_fmac_f32_e32 v30, v31, v22
	v_fma_f32 v11, -v11, v30, v23
	v_div_fmas_f32 v11, v11, v22, v30
	v_div_fixup_f32 v19, v11, v19, 1.0
	v_div_scale_f32 v11, s[0:1], v18, v18, 1.0
	v_rcp_f32_e32 v22, v11
	v_pk_add_f32 v[16:17], v[16:17], v[12:13] neg_lo:[0,1] neg_hi:[0,1]
	v_fma_f32 v23, -v11, v22, 1.0
	v_fmac_f32_e32 v22, v23, v22
	v_div_scale_f32 v23, vcc, 1.0, v18, 1.0
	v_mul_f32_e32 v30, v23, v22
	v_fma_f32 v31, -v11, v30, v23
	v_fmac_f32_e32 v30, v31, v22
	v_fma_f32 v11, -v11, v30, v23
	v_div_fmas_f32 v11, v11, v22, v30
	v_div_fixup_f32 v18, v11, v18, 1.0
	v_pk_fma_f32 v[12:13], v[18:19], v[16:17], v[12:13]
	v_pk_add_f32 v[18:19], v[28:29], 1.0 op_sel_hi:[1,0]
	v_cvt_f32_f16_e32 v16, v20
	v_cvt_f32_f16_sdwa v17, v20 dst_sel:DWORD dst_unused:UNUSED_PAD src0_sel:WORD_1
	v_div_scale_f32 v20, s[0:1], v19, v19, 1.0
	v_rcp_f32_e32 v22, v20
	v_cvt_pk_f16_f32 v11, v12, v13
	v_cvt_f32_f16_e32 v12, v24
	v_cvt_f32_f16_sdwa v13, v24 dst_sel:DWORD dst_unused:UNUSED_PAD src0_sel:WORD_1
	v_fma_f32 v23, -v20, v22, 1.0
	v_fmac_f32_e32 v22, v23, v22
	v_div_scale_f32 v23, vcc, 1.0, v19, 1.0
	v_mul_f32_e32 v24, v23, v22
	v_fma_f32 v28, -v20, v24, v23
	v_fmac_f32_e32 v24, v28, v22
	v_fma_f32 v20, -v20, v24, v23
	v_div_fmas_f32 v20, v20, v22, v24
	v_div_fixup_f32 v19, v20, v19, 1.0
	v_div_scale_f32 v20, s[0:1], v18, v18, 1.0
	v_rcp_f32_e32 v22, v20
	v_pk_add_f32 v[16:17], v[16:17], v[12:13] neg_lo:[0,1] neg_hi:[0,1]
	v_fma_f32 v23, -v20, v22, 1.0
	v_fmac_f32_e32 v22, v23, v22
	v_div_scale_f32 v23, vcc, 1.0, v18, 1.0
	v_mul_f32_e32 v24, v23, v22
	v_fma_f32 v28, -v20, v24, v23
	v_fmac_f32_e32 v24, v28, v22
	v_fma_f32 v20, -v20, v24, v23
	v_div_fmas_f32 v20, v20, v22, v24
	v_div_fixup_f32 v18, v20, v18, 1.0
	v_pk_fma_f32 v[12:13], v[18:19], v[16:17], v[12:13]
	v_cvt_f32_f16_e32 v18, v21
	v_cvt_pk_f16_f32 v12, v12, v13
	v_div_scale_f32 v13, s[0:1], v15, v15, 1.0
	v_rcp_f32_e32 v20, v13
	v_cvt_f32_f16_sdwa v19, v21 dst_sel:DWORD dst_unused:UNUSED_PAD src0_sel:WORD_1
	v_cvt_f32_f16_e32 v16, v25
	v_cvt_f32_f16_sdwa v17, v25 dst_sel:DWORD dst_unused:UNUSED_PAD src0_sel:WORD_1
	v_fma_f32 v21, -v13, v20, 1.0
	v_fmac_f32_e32 v20, v21, v20
	v_div_scale_f32 v21, vcc, 1.0, v15, 1.0
	v_mul_f32_e32 v22, v21, v20
	v_fma_f32 v23, -v13, v22, v21
	v_fmac_f32_e32 v22, v23, v20
	v_fma_f32 v13, -v13, v22, v21
	v_div_fmas_f32 v13, v13, v20, v22
	v_div_fixup_f32 v15, v13, v15, 1.0
	v_div_scale_f32 v13, s[0:1], v14, v14, 1.0
	v_rcp_f32_e32 v20, v13
	v_pk_add_f32 v[18:19], v[18:19], v[16:17] neg_lo:[0,1] neg_hi:[0,1]
	v_fma_f32 v21, -v13, v20, 1.0
	v_fmac_f32_e32 v20, v21, v20
	v_div_scale_f32 v21, vcc, 1.0, v14, 1.0
	v_mul_f32_e32 v22, v21, v20
	v_fma_f32 v23, -v13, v22, v21
	v_fmac_f32_e32 v22, v23, v20
	v_fma_f32 v13, -v13, v22, v21
	v_div_fmas_f32 v13, v13, v20, v22
	v_div_fixup_f32 v14, v13, v14, 1.0
	v_pk_fma_f32 v[14:15], v[14:15], v[18:19], v[16:17]
	s_nop 0
	v_cvt_pk_f16_f32 v13, v14, v15
	global_store_dwordx4 v[26:27], v[10:13], off
	v_lshl_add_u64 v[18:19], v[90:91], 0, v[82:83]
	global_load_dwordx4 v[14:17], v[18:19], off
	global_load_dwordx4 v[10:13], v[92:93], off offset:256
	v_add_f32_e32 v2, v2, v66
	v_mul_f32_e32 v2, 0xbfb8aa3b, v2
	v_exp_f32_e32 v20, v2
	v_add_f32_e32 v2, v7, v71
	v_mul_f32_e32 v2, 0xbfb8aa3b, v2
	v_exp_f32_e32 v25, v2
	v_add_f32_e32 v2, v3, v67
	v_mul_f32_e32 v2, 0xbfb8aa3b, v2
	v_add_f32_e32 v6, v6, v70
	v_exp_f32_e32 v21, v2
	v_add_f32_e32 v2, v8, v72
	v_mul_f32_e32 v6, 0xbfb8aa3b, v6
	v_mul_f32_e32 v2, 0xbfb8aa3b, v2
	v_exp_f32_e32 v24, v6
	v_exp_f32_e32 v22, v2
	v_add_f32_e32 v2, v4, v68
	v_mul_f32_e32 v2, 0xbfb8aa3b, v2
	v_exp_f32_e32 v6, v2
	v_add_f32_e32 v2, v9, v73
	v_mul_f32_e32 v2, 0xbfb8aa3b, v2
	v_exp_f32_e32 v23, v2
	v_add_f32_e32 v2, v5, v69
	v_pk_add_f32 v[8:9], v[24:25], 1.0 op_sel_hi:[1,0]
	v_mul_f32_e32 v2, 0xbfb8aa3b, v2
	v_exp_f32_e32 v7, v2
	s_waitcnt vmcnt(0)
; __device__ __forceinline__ float sigmoidf_(float x) { return 1.0f / (1.0f + __expf(-x)); }
; template <class Epi, class AMap>
; __device__ __forceinline__ void gemm_phase(LAS unsigned char* lds, const AMap am, const int lda, const h16* Bt, const int ldb, const int M, const int N, const int K, const Epi& E) {
;     ...
;         if (!has_next) break;
; #pragma unroll
;         for (int a = 0; a < 2; ++a)
; #pragma unroll
;             for (int b = 0; b < 2; ++b)
; #pragma unroll
;                 for (int m = 0; m < 4; ++m)
; #pragma unroll
;                     for (int n = 0; n < 2; ++n) acc[a][b][m][n] = (f32x4){0.f, 0.f, 0.f, 0.f};
;         cur = nxt; cA = nA; cB = nB; ++ui;
;     template <int GI>
;     __device__ __forceinline__ void body(const f32x4 (&acc)[2][2][4][2], int row0, int colt) const {
;     ...
;                         *(u32x4*)(Gb + row * DM + c) = pack8(x0, x1);
;                     } else {
;                         h16* vp = C1 + row * LDC1 + 4096 + c;
;                         const h16x8 vv = *(const h16x8*)vp; const h16x8 vf = *(const h16x8*)(VF + row * DM + c);
;                         f32x4 o0, o1;
; #pragma unroll
;                         for (int j = 0; j < 4; ++j) { float v = (float)vv[j], f = (float)vf[j]; o0[j] = v + (f - v) * sigmoidf_(x0[j]); v = (float)vv[4 + j]; f = (float)vf[4 + j]; o1[j] = v + (f - v) * sigmoidf_(x1[j]); }
;                         *(u32x4*)vp = pack8(o0, o1);
;                     }
;                     __builtin_amdgcn_sched_barrier(0);
	v_cvt_f32_f16_e32 v2, v14
	v_cvt_f32_f16_e32 v4, v10
	v_cvt_f32_f16_sdwa v5, v10 dst_sel:DWORD dst_unused:UNUSED_PAD src0_sel:WORD_1
	v_div_scale_f32 v10, s[0:1], v9, v9, 1.0
	v_cvt_f32_f16_sdwa v3, v14 dst_sel:DWORD dst_unused:UNUSED_PAD src0_sel:WORD_1
	v_rcp_f32_e32 v14, v10
	v_pk_add_f32 v[6:7], v[6:7], 1.0 op_sel_hi:[1,0]
	v_pk_add_f32 v[4:5], v[4:5], v[2:3] neg_lo:[0,1] neg_hi:[0,1]
	v_fma_f32 v24, -v10, v14, 1.0
	v_fmac_f32_e32 v14, v24, v14
	v_div_scale_f32 v24, vcc, 1.0, v9, 1.0
	v_mul_f32_e32 v25, v24, v14
	v_fma_f32 v26, -v10, v25, v24
	v_fmac_f32_e32 v25, v26, v14
	v_fma_f32 v10, -v10, v25, v24
	v_div_fmas_f32 v10, v10, v14, v25
	v_div_fixup_f32 v9, v10, v9, 1.0
	v_div_scale_f32 v10, s[0:1], v8, v8, 1.0
	v_rcp_f32_e32 v14, v10
	s_nop 0
	v_fma_f32 v24, -v10, v14, 1.0
	v_fmac_f32_e32 v14, v24, v14
	v_div_scale_f32 v24, vcc, 1.0, v8, 1.0
	v_mul_f32_e32 v25, v24, v14
	v_fma_f32 v26, -v10, v25, v24
	v_fmac_f32_e32 v25, v26, v14
	v_fma_f32 v10, -v10, v25, v24
	v_div_fmas_f32 v10, v10, v14, v25
	v_div_fixup_f32 v8, v10, v8, 1.0
	v_pk_fma_f32 v[2:3], v[8:9], v[4:5], v[2:3]
	v_cvt_f32_f16_e32 v8, v11
	v_cvt_f32_f16_sdwa v9, v11 dst_sel:DWORD dst_unused:UNUSED_PAD src0_sel:WORD_1
	v_pk_add_f32 v[10:11], v[22:23], 1.0 op_sel_hi:[1,0]
	v_cvt_pk_f16_f32 v2, v2, v3
	v_div_scale_f32 v3, s[0:1], v11, v11, 1.0
	v_rcp_f32_e32 v14, v3
	v_cvt_f32_f16_e32 v4, v15
	v_cvt_f32_f16_sdwa v5, v15 dst_sel:DWORD dst_unused:UNUSED_PAD src0_sel:WORD_1
	v_fma_f32 v15, -v3, v14, 1.0
	v_fmac_f32_e32 v14, v15, v14
	v_div_scale_f32 v15, vcc, 1.0, v11, 1.0
	v_mul_f32_e32 v22, v15, v14
	v_fma_f32 v23, -v3, v22, v15
	v_fmac_f32_e32 v22, v23, v14
	v_fma_f32 v3, -v3, v22, v15
	v_div_fmas_f32 v3, v3, v14, v22
	v_div_fixup_f32 v11, v3, v11, 1.0
	v_div_scale_f32 v3, s[0:1], v10, v10, 1.0
	v_rcp_f32_e32 v14, v3
	v_pk_add_f32 v[8:9], v[8:9], v[4:5] neg_lo:[0,1] neg_hi:[0,1]
	v_fma_f32 v15, -v3, v14, 1.0
	v_fmac_f32_e32 v14, v15, v14
	v_div_scale_f32 v15, vcc, 1.0, v10, 1.0
	v_mul_f32_e32 v22, v15, v14
	v_fma_f32 v23, -v3, v22, v15
	v_fmac_f32_e32 v22, v23, v14
	v_fma_f32 v3, -v3, v22, v15
	v_div_fmas_f32 v3, v3, v14, v22
	v_div_fixup_f32 v10, v3, v10, 1.0
	v_pk_fma_f32 v[4:5], v[10:11], v[8:9], v[4:5]
	v_pk_add_f32 v[10:11], v[20:21], 1.0 op_sel_hi:[1,0]
	v_cvt_f32_f16_e32 v8, v12
	v_cvt_f32_f16_sdwa v9, v12 dst_sel:DWORD dst_unused:UNUSED_PAD src0_sel:WORD_1
	v_div_scale_f32 v12, s[0:1], v11, v11, 1.0
	v_rcp_f32_e32 v14, v12
	v_cvt_pk_f16_f32 v3, v4, v5
	v_cvt_f32_f16_e32 v4, v16
	v_cvt_f32_f16_sdwa v5, v16 dst_sel:DWORD dst_unused:UNUSED_PAD src0_sel:WORD_1
	v_fma_f32 v15, -v12, v14, 1.0
	v_fmac_f32_e32 v14, v15, v14
	v_div_scale_f32 v15, vcc, 1.0, v11, 1.0
	v_mul_f32_e32 v16, v15, v14
	v_fma_f32 v20, -v12, v16, v15
	v_fmac_f32_e32 v16, v20, v14
	v_fma_f32 v12, -v12, v16, v15
	v_div_fmas_f32 v12, v12, v14, v16
	v_div_fixup_f32 v11, v12, v11, 1.0
	v_div_scale_f32 v12, s[0:1], v10, v10, 1.0
	v_rcp_f32_e32 v14, v12
	v_pk_add_f32 v[8:9], v[8:9], v[4:5] neg_lo:[0,1] neg_hi:[0,1]
	v_fma_f32 v15, -v12, v14, 1.0
	v_fmac_f32_e32 v14, v15, v14
	v_div_scale_f32 v15, vcc, 1.0, v10, 1.0
	v_mul_f32_e32 v16, v15, v14
	v_fma_f32 v20, -v12, v16, v15
	v_fmac_f32_e32 v16, v20, v14
	v_fma_f32 v12, -v12, v16, v15
	v_div_fmas_f32 v12, v12, v14, v16
	v_div_fixup_f32 v10, v12, v10, 1.0
	v_pk_fma_f32 v[4:5], v[10:11], v[8:9], v[4:5]
	v_cvt_f32_f16_e32 v10, v13
	v_cvt_pk_f16_f32 v4, v4, v5
	v_div_scale_f32 v5, s[0:1], v7, v7, 1.0
	v_rcp_f32_e32 v12, v5
	v_cvt_f32_f16_sdwa v11, v13 dst_sel:DWORD dst_unused:UNUSED_PAD src0_sel:WORD_1
	v_cvt_f32_f16_e32 v8, v17
	v_cvt_f32_f16_sdwa v9, v17 dst_sel:DWORD dst_unused:UNUSED_PAD src0_sel:WORD_1
	v_fma_f32 v13, -v5, v12, 1.0
	v_fmac_f32_e32 v12, v13, v12
	v_div_scale_f32 v13, vcc, 1.0, v7, 1.0
	v_mul_f32_e32 v14, v13, v12
	v_fma_f32 v15, -v5, v14, v13
	v_fmac_f32_e32 v14, v15, v12
	v_fma_f32 v5, -v5, v14, v13
	v_div_fmas_f32 v5, v5, v12, v14
	v_div_fixup_f32 v7, v5, v7, 1.0
	v_div_scale_f32 v5, s[0:1], v6, v6, 1.0
	v_rcp_f32_e32 v12, v5
	v_pk_add_f32 v[10:11], v[10:11], v[8:9] neg_lo:[0,1] neg_hi:[0,1]
	v_fma_f32 v13, -v5, v12, 1.0
	v_fmac_f32_e32 v12, v13, v12
	v_div_scale_f32 v13, vcc, 1.0, v6, 1.0
	v_mul_f32_e32 v14, v13, v12
	v_fma_f32 v15, -v5, v14, v13
	v_fmac_f32_e32 v14, v15, v12
	v_fma_f32 v5, -v5, v14, v13
	v_div_fmas_f32 v5, v5, v12, v14
	v_div_fixup_f32 v6, v5, v6, 1.0
	v_pk_fma_f32 v[6:7], v[6:7], v[10:11], v[8:9]
	s_nop 0
	v_cvt_pk_f16_f32 v5, v6, v7
	global_store_dwordx4 v[18:19], v[2:5], off
	s_and_b64 vcc, exec, s[38:39]
	s_mov_b32 s50, s44
	s_mov_b32 s35, s81
	s_mov_b64 s[26:27], s[64:65]
	s_mov_b64 s[22:23], s[46:47]
	s_cbranch_vccnz .LBB0_694

; #define PG8_STAGE(bufoff, gbase, voff) do { _Pragma("unroll") for (int _i = 0; _i < 2; ++_i) \
;         __builtin_amdgcn_global_load_lds((const unsigned*)((const char*)(gbase) + (voff)[_i]), (LAS unsigned*)(lds + (bufoff) + ldsw + _i * 8192), 16, 0, 0); } while (0)
; #define PG8_LDA(dst, b, h) do { _Pragma("unroll") for (int m = 0; m < 4; ++m) _Pragma("unroll") for (int k = 0; k < 2; ++k) dst[m][k] = *(const LAS h16x8*)(lds + PG8_SA(b, h) + aoff + m * 2048 + k * 1024); } while (0)
; #define PG8_LDB(dst, b, h) do { _Pragma("unroll") for (int n = 0; n < 2; ++n) _Pragma("unroll") for (int k = 0; k < 2; ++k) dst[n][k] = *(const LAS h16x8*)(lds + PG8_SB(b, h) + boff + n * 2048 + k * 1024); } while (0)
; #define PG8_WAIT_L(n) asm volatile("s_waitcnt lgkmcnt(" #n ")" ::: "memory")
; #define PG8_BAR __builtin_amdgcn_s_barrier()
; #define PG8_SCHED __builtin_amdgcn_sched_barrier(0)
; template <class Epi, class AMap>
; __device__ __forceinline__ void gemm_phase(LAS unsigned char* lds, const AMap am, const int lda, const h16* Bt, const int ldb, const int M, const int N, const int K, const Epi& E) {
;     ...
;         const bool has_next = S.next(ui + 1, nxt);
;         const char* nA = has_next ? am(nxt.pn) + (size_t)nxt.pm * tstepA : cA; const char* nB = has_next ? (const char*)Bt + (size_t)nxt.pn * tstepB : cB;
; #pragma unroll 1
;         for (int t = 0; t < nt; t += 2) {
;             const bool last = (t == nt - 2);
;             const char* a1 = cA + (size_t)(t + 1) * kstep;
;             const char* a2 = last ? nA : cA + (size_t)(t + 2) * kstep; const char* b2 = last ? nB : cB + (size_t)(t + 2) * kstep;
;             const char* a3 = a2 + kstep; const char* b3 = b2 + kstep;
;             PG8_LDB(B0, 0, 0); PG8_SCHED; PG8_LDA(At, 0, 0); PG8_STAGE(PG8_SA(1, 1), a1 + hstepA, voffA);
;             PG8_WAIT_L(8); PG8_BAR; PG8_WAIT_L(0); PG8_MMA(0, 0, At, B0); PG8_BAR; PG8_SCHED;
;     ...
; #pragma unroll
;         for (int a = 0; a < 2; ++a)
; #pragma unroll
;             for (int b = 0; b < 2; ++b)
; #pragma unroll
;                 for (int m = 0; m < 4; ++m)
; #pragma unroll
;                     for (int n = 0; n < 2; ++n) acc[a][b][m][n] = (f32x4){0.f, 0.f, 0.f, 0.f};
;         cur = nxt; cA = nA; cB = nB; ++ui;
.LBB0_690:
	s_ashr_i32 s45, s44, 31
	s_lshl_b64 s[20:21], s[44:45], 17
	s_add_u32 s64, s72, s20
	v_mov_b32_e32 v137, 0
	s_addc_u32 s65, s73, s21
	s_andn2_b64 vcc, exec, s[42:43]
	v_mov_b32_e32 v136, v137
	v_mov_b32_e32 v135, v137
	v_mov_b32_e32 v134, v137
	v_mov_b32_e32 v133, v137
	v_mov_b32_e32 v132, v137
	v_mov_b32_e32 v131, v137
	v_mov_b32_e32 v130, v137
	v_mov_b32_e32 v129, v137
	v_mov_b32_e32 v128, v137
	v_mov_b32_e32 v127, v137
	v_mov_b32_e32 v126, v137
	v_mov_b32_e32 v125, v137
	v_mov_b32_e32 v124, v137
	v_mov_b32_e32 v123, v137
	v_mov_b32_e32 v122, v137
	v_mov_b32_e32 v121, v137
	v_mov_b32_e32 v120, v137
	v_mov_b32_e32 v119, v137
	v_mov_b32_e32 v118, v137
	v_mov_b32_e32 v117, v137
	v_mov_b32_e32 v116, v137
	v_mov_b32_e32 v115, v137
	v_mov_b32_e32 v114, v137
	v_mov_b32_e32 v113, v137
	v_mov_b32_e32 v112, v137
	v_mov_b32_e32 v111, v137
	v_mov_b32_e32 v110, v137
	v_mov_b32_e32 v109, v137
	v_mov_b32_e32 v108, v137
	v_mov_b32_e32 v107, v137
	v_mov_b32_e32 v106, v137
	v_mov_b32_e32 v65, v137
	v_mov_b32_e32 v64, v137
	v_mov_b32_e32 v63, v137
	v_mov_b32_e32 v62, v137
	v_mov_b32_e32 v61, v137
	v_mov_b32_e32 v60, v137
	v_mov_b32_e32 v59, v137
	v_mov_b32_e32 v58, v137
	v_mov_b32_e32 v57, v137
	v_mov_b32_e32 v56, v137
	v_mov_b32_e32 v55, v137
	v_mov_b32_e32 v54, v137
	v_mov_b32_e32 v53, v137
	v_mov_b32_e32 v52, v137
	v_mov_b32_e32 v51, v137
	v_mov_b32_e32 v50, v137
	v_mov_b32_e32 v49, v137
	v_mov_b32_e32 v48, v137
	v_mov_b32_e32 v47, v137
	v_mov_b32_e32 v46, v137
	v_mov_b32_e32 v45, v137
	v_mov_b32_e32 v44, v137
	v_mov_b32_e32 v43, v137
	v_mov_b32_e32 v42, v137
	v_mov_b32_e32 v41, v137
	v_mov_b32_e32 v40, v137
	v_mov_b32_e32 v39, v137
	v_mov_b32_e32 v38, v137
	v_mov_b32_e32 v37, v137
	v_mov_b32_e32 v36, v137
	v_mov_b32_e32 v35, v137
	v_mov_b32_e32 v34, v137
	v_mov_b32_e32 v105, v137
	v_mov_b32_e32 v104, v137
	v_mov_b32_e32 v103, v137
	v_mov_b32_e32 v102, v137
	v_mov_b32_e32 v101, v137
	v_mov_b32_e32 v100, v137
	v_mov_b32_e32 v99, v137
	v_mov_b32_e32 v98, v137
	v_mov_b32_e32 v97, v137
	v_mov_b32_e32 v96, v137
	v_mov_b32_e32 v95, v137
	v_mov_b32_e32 v94, v137
	v_mov_b32_e32 v93, v137
	v_mov_b32_e32 v92, v137
	v_mov_b32_e32 v91, v137
	v_mov_b32_e32 v90, v137
	v_mov_b32_e32 v81, v137
	v_mov_b32_e32 v80, v137
	v_mov_b32_e32 v79, v137
	v_mov_b32_e32 v78, v137
	v_mov_b32_e32 v77, v137
	v_mov_b32_e32 v76, v137
	v_mov_b32_e32 v75, v137
	v_mov_b32_e32 v74, v137
	v_mov_b32_e32 v73, v137
	v_mov_b32_e32 v72, v137
	v_mov_b32_e32 v71, v137
	v_mov_b32_e32 v70, v137
	v_mov_b32_e32 v69, v137
	v_mov_b32_e32 v68, v137
	v_mov_b32_e32 v67, v137
	v_mov_b32_e32 v66, v137
	v_mov_b32_e32 v33, v137
	v_mov_b32_e32 v32, v137
	v_mov_b32_e32 v31, v137
	v_mov_b32_e32 v30, v137
	v_mov_b32_e32 v29, v137
	v_mov_b32_e32 v28, v137
	v_mov_b32_e32 v27, v137
	v_mov_b32_e32 v26, v137
	v_mov_b32_e32 v25, v137
	v_mov_b32_e32 v24, v137
	v_mov_b32_e32 v23, v137
	v_mov_b32_e32 v22, v137
	v_mov_b32_e32 v21, v137
	v_mov_b32_e32 v20, v137
	v_mov_b32_e32 v19, v137
	v_mov_b32_e32 v18, v137
	v_mov_b32_e32 v17, v137
	v_mov_b32_e32 v16, v137
	v_mov_b32_e32 v15, v137
	v_mov_b32_e32 v14, v137
	v_mov_b32_e32 v13, v137
	v_mov_b32_e32 v12, v137
	v_mov_b32_e32 v11, v137
	v_mov_b32_e32 v10, v137
	v_mov_b32_e32 v9, v137
	v_mov_b32_e32 v8, v137
	v_mov_b32_e32 v7, v137
	v_mov_b32_e32 v6, v137
	v_mov_b32_e32 v5, v137
	v_mov_b32_e32 v4, v137
	v_mov_b32_e32 v3, v137
	v_mov_b32_e32 v2, v137
	s_cbranch_vccnz .LBB0_681
	s_and_b64 s[0:1], s[0:1], exec
	s_cselect_b32 s20, s65, s27
	s_cselect_b32 s21, s64, s26
	s_add_u32 s29, s26, 0x100
	s_addc_u32 s45, s27, 0
	s_mov_b32 s26, 0
	s_cmpk_lt_u32 s69, 0x100
	s_cbranch_scc1 .Lgy7
	s_barrier
.Lgy7:
.LBB0_692:
	s_add_i32 s51, s26, 2
	s_add_u32 s0, s22, 0x100
	s_addc_u32 s1, s23, 0
	s_add_i32 s60, 0, 0x10000
	v_add_u32_e32 v234, s60, v175
	ds_read_b128 v[82:85], v234
	ds_read_b128 v[86:89], v234 offset:1024
	ds_read_b128 v[138:141], v234 offset:2048
	ds_read_b128 v[142:145], v234 offset:3072
	s_cmp_eq_u32 s61, s26
	s_cselect_b32 s26, s21, s29
	s_cselect_b32 s49, s47, s1
	s_cselect_b32 s48, s46, s0
	s_cselect_b32 s27, s20, s45
	v_lshl_add_u64 v[172:173], s[22:23], 0, v[152:153]
	s_add_i32 m0, s74, 0xc000
	ds_read_b128 v[156:159], v177
	ds_read_b128 v[160:163], v177 offset:1024
	ds_read_b128 v[164:167], v177 offset:2048
	ds_read_b128 v[168:171], v177 offset:3072
	ds_read_b128 v[178:181], v177 offset:4096
	ds_read_b128 v[182:185], v177 offset:5120
	ds_read_b128 v[186:189], v177 offset:6144
	ds_read_b128 v[190:193], v177 offset:7168
	global_load_lds_dwordx4 v[172:173], off
	v_lshl_add_u64 v[172:173], s[22:23], 0, v[154:155]
	s_add_i32 m0, s74, 0xe000
	s_nop 0
	global_load_lds_dwordx4 v[172:173], off
	s_waitcnt lgkmcnt(11)
	s_add_i32 s62, 0, 0x14000
	v_add_u32_e32 v172, s62, v175
	s_add_i32 s22, s60, s71
	ds_read_b128 v[194:197], v172
	ds_read_b128 v[198:201], v172 offset:1024
	ds_read_b128 v[202:205], v172 offset:2048
	ds_read_b128 v[220:223], v172 offset:3072
	s_waitcnt vmcnt(8) lgkmcnt(0)
	s_barrier
; #define PG8_STAGE(bufoff, gbase, voff) do { _Pragma("unroll") for (int _i = 0; _i < 2; ++_i) \
;         __builtin_amdgcn_global_load_lds((const unsigned*)((const char*)(gbase) + (voff)[_i]), (LAS unsigned*)(lds + (bufoff) + ldsw + _i * 8192), 16, 0, 0); } while (0)
; #define PG8_LDA(dst, b, h) do { _Pragma("unroll") for (int m = 0; m < 4; ++m) _Pragma("unroll") for (int k = 0; k < 2; ++k) dst[m][k] = *(const LAS h16x8*)(lds + PG8_SA(b, h) + aoff + m * 2048 + k * 1024); } while (0)
; #define PG8_LDB(dst, b, h) do { _Pragma("unroll") for (int n = 0; n < 2; ++n) _Pragma("unroll") for (int k = 0; k < 2; ++k) dst[n][k] = *(const LAS h16x8*)(lds + PG8_SB(b, h) + boff + n * 2048 + k * 1024); } while (0)
; #define PG8_MMA(ai, bj, At, Bt_) do { __builtin_amdgcn_s_setprio(1); _Pragma("unroll") for (int m = 0; m < 4; ++m) _Pragma("unroll") for (int n = 0; n < 2; ++n) _Pragma("unroll") for (int k = 0; k < 2; ++k) \
;         acc[ai][bj][m][n] = __builtin_amdgcn_mfma_f32_16x16x32_f16(Bt_[n][k], At[m][k], acc[ai][bj][m][n], 0, 0, 0); __builtin_amdgcn_s_setprio(0); } while (0)
; #define PG8_WAIT_V(n) asm volatile("s_waitcnt vmcnt(" #n ")" ::: "memory")
; #define PG8_WAIT_L(n) asm volatile("s_waitcnt lgkmcnt(" #n ")" ::: "memory")
; #define PG8_BAR __builtin_amdgcn_s_barrier()
; #define PG8_SCHED __builtin_amdgcn_sched_barrier(0)
; template <class Epi, class AMap>
; __device__ __forceinline__ void gemm_phase(LAS unsigned char* lds, const AMap am, const int lda, const h16* Bt, const int ldb, const int M, const int N, const int K, const Epi& E) {
;     ...
;             PG8_LDB(B0, 0, 0); PG8_SCHED; PG8_LDA(At, 0, 0); PG8_STAGE(PG8_SA(1, 1), a1 + hstepA, voffA);
;             PG8_WAIT_L(8); PG8_BAR; PG8_WAIT_L(0); PG8_MMA(0, 0, At, B0); PG8_BAR; PG8_SCHED;
;             PG8_LDB(B1, 0, 1); PG8_STAGE(PG8_SB(0, 0), b2, voffB);
;             PG8_BAR; PG8_WAIT_L(0); PG8_MMA(0, 1, At, B1); PG8_BAR;
;             PG8_LDA(At, 0, 1); PG8_STAGE(PG8_SA(0, 0), a2, voffA);
;             PG8_BAR; PG8_WAIT_L(0); PG8_MMA(1, 0, At, B0); PG8_BAR; PG8_SCHED;
;             PG8_STAGE(PG8_SB(0, 1), b2 + hstepB, voffB);
;             PG8_WAIT_V(6); PG8_BAR; PG8_MMA(1, 1, At, B1); PG8_BAR;
	v_mfma_f32_16x16x32_f16 v[134:137], v[82:85], v[156:159], v[134:137]
	v_mfma_f32_16x16x32_f16 v[130:133], v[138:141], v[156:159], v[130:133]
	v_mfma_f32_16x16x32_f16 v[126:129], v[82:85], v[164:167], v[126:129]
	v_mfma_f32_16x16x32_f16 v[122:125], v[138:141], v[164:167], v[122:125]
	v_mfma_f32_16x16x32_f16 v[118:121], v[82:85], v[178:181], v[118:121]
	v_mfma_f32_16x16x32_f16 v[114:117], v[138:141], v[178:181], v[114:117]
	v_mfma_f32_16x16x32_f16 v[110:113], v[82:85], v[186:189], v[110:113]
	v_mfma_f32_16x16x32_f16 v[106:109], v[138:141], v[186:189], v[106:109]
	v_mfma_f32_16x16x32_f16 v[134:137], v[86:89], v[160:163], v[134:137]
	v_mfma_f32_16x16x32_f16 v[130:133], v[142:145], v[160:163], v[130:133]
	v_mfma_f32_16x16x32_f16 v[126:129], v[86:89], v[168:171], v[126:129]
	v_mfma_f32_16x16x32_f16 v[122:125], v[142:145], v[168:171], v[122:125]
	v_mfma_f32_16x16x32_f16 v[118:121], v[86:89], v[182:185], v[118:121]
	v_mfma_f32_16x16x32_f16 v[114:117], v[142:145], v[182:185], v[114:117]
	v_mfma_f32_16x16x32_f16 v[110:113], v[86:89], v[190:193], v[110:113]
	v_mfma_f32_16x16x32_f16 v[106:109], v[142:145], v[190:193], v[106:109]
	v_mfma_f32_16x16x32_f16 v[62:65], v[194:197], v[156:159], v[62:65]
	v_mfma_f32_16x16x32_f16 v[58:61], v[202:205], v[156:159], v[58:61]
	v_mfma_f32_16x16x32_f16 v[54:57], v[194:197], v[164:167], v[54:57]
	v_mfma_f32_16x16x32_f16 v[50:53], v[202:205], v[164:167], v[50:53]
	v_mfma_f32_16x16x32_f16 v[46:49], v[194:197], v[178:181], v[46:49]
	v_mfma_f32_16x16x32_f16 v[42:45], v[202:205], v[178:181], v[42:45]
	v_mfma_f32_16x16x32_f16 v[38:41], v[194:197], v[186:189], v[38:41]
	v_mfma_f32_16x16x32_f16 v[34:37], v[202:205], v[186:189], v[34:37]
	v_mfma_f32_16x16x32_f16 v[62:65], v[198:201], v[160:163], v[62:65]
	v_mfma_f32_16x16x32_f16 v[58:61], v[220:223], v[160:163], v[58:61]
	v_mfma_f32_16x16x32_f16 v[54:57], v[198:201], v[168:171], v[54:57]
	v_mfma_f32_16x16x32_f16 v[50:53], v[220:223], v[168:171], v[50:53]
	v_mfma_f32_16x16x32_f16 v[46:49], v[198:201], v[182:185], v[46:49]
	v_mfma_f32_16x16x32_f16 v[42:45], v[220:223], v[182:185], v[42:45]
	v_mfma_f32_16x16x32_f16 v[38:41], v[198:201], v[190:193], v[38:41]
	v_mfma_f32_16x16x32_f16 v[34:37], v[220:223], v[190:193], v[34:37]
	s_barrier
	v_lshl_add_u64 v[172:173], s[26:27], 0, v[0:1]
	s_mov_b32 m0, s22
	v_lshl_add_u64 v[206:207], s[26:27], 0, v[150:151]
	global_load_lds_dwordx4 v[172:173], off
	s_add_i32 m0, s22, 0x2000
	s_nop 0
	global_load_lds_dwordx4 v[206:207], off
	s_mov_b32 m0, s74
	v_lshl_add_u64 v[212:213], s[48:49], 0, v[146:147]
	ds_read_b128 v[156:159], v177 offset:16384
	ds_read_b128 v[160:163], v177 offset:17408
	ds_read_b128 v[164:167], v177 offset:18432
	ds_read_b128 v[168:171], v177 offset:19456
	ds_read_b128 v[178:181], v177 offset:20480
	ds_read_b128 v[182:185], v177 offset:21504
	ds_read_b128 v[186:189], v177 offset:22528
	ds_read_b128 v[190:193], v177 offset:23552
	global_load_lds_dwordx4 v[212:213], off
	v_lshl_add_u64 v[224:225], s[48:49], 0, v[148:149]
	s_mov_b32 m0, s75
	s_nop 0
	global_load_lds_dwordx4 v[224:225], off
	s_add_u32 s22, s26, 0x10000
	s_addc_u32 s23, s27, 0
	s_add_i32 s60, s62, s71
	v_lshl_add_u64 v[232:233], s[22:23], 0, v[0:1]
	s_mov_b32 m0, s60
	s_nop 0
	global_load_lds_dwordx4 v[232:233], off
	v_lshl_add_u64 v[232:233], s[22:23], 0, v[150:151]
	s_add_i32 m0, s60, 0x2000
	s_nop 0
	global_load_lds_dwordx4 v[232:233], off
	s_waitcnt vmcnt(8) lgkmcnt(0)
	s_barrier
	v_mfma_f32_16x16x32_f16 v[102:105], v[82:85], v[156:159], v[102:105]
	v_mfma_f32_16x16x32_f16 v[98:101], v[138:141], v[156:159], v[98:101]
	v_mfma_f32_16x16x32_f16 v[94:97], v[82:85], v[164:167], v[94:97]
	v_mfma_f32_16x16x32_f16 v[90:93], v[138:141], v[164:167], v[90:93]
	v_mfma_f32_16x16x32_f16 v[78:81], v[82:85], v[178:181], v[78:81]
	v_mfma_f32_16x16x32_f16 v[74:77], v[138:141], v[178:181], v[74:77]
	v_mfma_f32_16x16x32_f16 v[70:73], v[82:85], v[186:189], v[70:73]
	v_mfma_f32_16x16x32_f16 v[66:69], v[138:141], v[186:189], v[66:69]
	v_mfma_f32_16x16x32_f16 v[102:105], v[86:89], v[160:163], v[102:105]
	v_mfma_f32_16x16x32_f16 v[98:101], v[142:145], v[160:163], v[98:101]
	v_mfma_f32_16x16x32_f16 v[94:97], v[86:89], v[168:171], v[94:97]
	v_mfma_f32_16x16x32_f16 v[90:93], v[142:145], v[168:171], v[90:93]
	v_mfma_f32_16x16x32_f16 v[78:81], v[86:89], v[182:185], v[78:81]
	v_mfma_f32_16x16x32_f16 v[74:77], v[142:145], v[182:185], v[74:77]
	v_mfma_f32_16x16x32_f16 v[70:73], v[86:89], v[190:193], v[70:73]
	v_mfma_f32_16x16x32_f16 v[66:69], v[142:145], v[190:193], v[66:69]
	v_mfma_f32_16x16x32_f16 v[30:33], v[194:197], v[156:159], v[30:33]
	v_mfma_f32_16x16x32_f16 v[26:29], v[202:205], v[156:159], v[26:29]
	v_mfma_f32_16x16x32_f16 v[22:25], v[194:197], v[164:167], v[22:25]
	v_mfma_f32_16x16x32_f16 v[18:21], v[202:205], v[164:167], v[18:21]
	v_mfma_f32_16x16x32_f16 v[14:17], v[194:197], v[178:181], v[14:17]
	v_mfma_f32_16x16x32_f16 v[10:13], v[202:205], v[178:181], v[10:13]
	v_mfma_f32_16x16x32_f16 v[6:9], v[194:197], v[186:189], v[6:9]
	v_mfma_f32_16x16x32_f16 v[2:5], v[202:205], v[186:189], v[2:5]
	v_mfma_f32_16x16x32_f16 v[30:33], v[198:201], v[160:163], v[30:33]
	v_mfma_f32_16x16x32_f16 v[26:29], v[220:223], v[160:163], v[26:29]
	v_mfma_f32_16x16x32_f16 v[22:25], v[198:201], v[168:171], v[22:25]
	v_mfma_f32_16x16x32_f16 v[18:21], v[220:223], v[168:171], v[18:21]
	v_mfma_f32_16x16x32_f16 v[14:17], v[198:201], v[182:185], v[14:17]
	v_mfma_f32_16x16x32_f16 v[10:13], v[220:223], v[182:185], v[10:13]
	v_mfma_f32_16x16x32_f16 v[6:9], v[198:201], v[190:193], v[6:9]
	v_mfma_f32_16x16x32_f16 v[2:5], v[220:223], v[190:193], v[2:5]
	s_barrier
; #define PG8_STAGE(bufoff, gbase, voff) do { _Pragma("unroll") for (int _i = 0; _i < 2; ++_i) \
;         __builtin_amdgcn_global_load_lds((const unsigned*)((const char*)(gbase) + (voff)[_i]), (LAS unsigned*)(lds + (bufoff) + ldsw + _i * 8192), 16, 0, 0); } while (0)
; #define PG8_LDA(dst, b, h) do { _Pragma("unroll") for (int m = 0; m < 4; ++m) _Pragma("unroll") for (int k = 0; k < 2; ++k) dst[m][k] = *(const LAS h16x8*)(lds + PG8_SA(b, h) + aoff + m * 2048 + k * 1024); } while (0)
; #define PG8_LDB(dst, b, h) do { _Pragma("unroll") for (int n = 0; n < 2; ++n) _Pragma("unroll") for (int k = 0; k < 2; ++k) dst[n][k] = *(const LAS h16x8*)(lds + PG8_SB(b, h) + boff + n * 2048 + k * 1024); } while (0)
; #define PG8_MMA(ai, bj, At, Bt_) do { __builtin_amdgcn_s_setprio(1); _Pragma("unroll") for (int m = 0; m < 4; ++m) _Pragma("unroll") for (int n = 0; n < 2; ++n) _Pragma("unroll") for (int k = 0; k < 2; ++k) \
;         acc[ai][bj][m][n] = __builtin_amdgcn_mfma_f32_16x16x32_f16(Bt_[n][k], At[m][k], acc[ai][bj][m][n], 0, 0, 0); __builtin_amdgcn_s_setprio(0); } while (0)
; #define PG8_WAIT_V(n) asm volatile("s_waitcnt vmcnt(" #n ")" ::: "memory")
; #define PG8_WAIT_L(n) asm volatile("s_waitcnt lgkmcnt(" #n ")" ::: "memory")
; #define PG8_BAR __builtin_amdgcn_s_barrier()
; #define PG8_SCHED __builtin_amdgcn_sched_barrier(0)
; template <class Epi, class AMap>
; __device__ __forceinline__ void gemm_phase(LAS unsigned char* lds, const AMap am, const int lda, const h16* Bt, const int ldb, const int M, const int N, const int K, const Epi& E) {
;     ...
;             PG8_LDB(B0, 1, 0); PG8_SCHED; PG8_LDA(At, 1, 0); PG8_STAGE(PG8_SA(0, 1), a2 + hstepA, voffA);
;             PG8_WAIT_L(8); PG8_BAR; PG8_WAIT_L(0); PG8_MMA(0, 0, At, B0); PG8_BAR; PG8_SCHED;
;             PG8_LDB(B1, 1, 1); PG8_STAGE(PG8_SB(1, 0), b3, voffB);
;             PG8_BAR; PG8_WAIT_L(0); PG8_MMA(0, 1, At, B1); PG8_BAR;
;             PG8_LDA(At, 1, 1); PG8_STAGE(PG8_SA(1, 0), a3, voffA);
;             PG8_BAR; PG8_WAIT_L(0); PG8_MMA(1, 0, At, B0); PG8_BAR; PG8_SCHED;
;             PG8_STAGE(PG8_SB(1, 1), b3 + hstepB, voffB);
;             PG8_WAIT_V(6); PG8_BAR; PG8_MMA(1, 1, At, B1); PG8_BAR;
	s_add_i32 s60, 0, 0x18000
	v_add_u32_e32 v234, s60, v175
	ds_read_b128 v[82:85], v234
	ds_read_b128 v[86:89], v234 offset:1024
	ds_read_b128 v[138:141], v234 offset:2048
	ds_read_b128 v[142:145], v234 offset:3072
	s_add_u32 s22, s48, 0x1c0000
	s_addc_u32 s23, s49, 0
	s_mov_b32 m0, s76
	v_lshl_add_u64 v[232:233], s[22:23], 0, v[146:147]
	ds_read_b128 v[156:159], v177 offset:32768
	ds_read_b128 v[160:163], v177 offset:33792
	ds_read_b128 v[164:167], v177 offset:34816
	ds_read_b128 v[168:171], v177 offset:35840
	ds_read_b128 v[178:181], v177 offset:36864
	ds_read_b128 v[182:185], v177 offset:37888
	ds_read_b128 v[186:189], v177 offset:38912
	ds_read_b128 v[190:193], v177 offset:39936
	global_load_lds_dwordx4 v[232:233], off
	v_lshl_add_u64 v[232:233], s[22:23], 0, v[148:149]
	s_mov_b32 m0, s77
	s_nop 0
	global_load_lds_dwordx4 v[232:233], off
	s_waitcnt lgkmcnt(11)
	s_add_i32 s48, 0, 0x1c000
	s_add_i32 s22, s60, s71
	v_add_u32_e32 v214, s48, v175
	v_lshl_add_u64 v[172:173], v[172:173], 0, s[92:93]
	s_mov_b32 m0, s22
	ds_read_b128 v[194:197], v214
	ds_read_b128 v[198:201], v214 offset:1024
	ds_read_b128 v[202:205], v214 offset:2048
	ds_read_b128 v[220:223], v214 offset:3072
	s_waitcnt vmcnt(8) lgkmcnt(0)
	s_barrier
	v_mfma_f32_16x16x32_f16 v[134:137], v[82:85], v[156:159], v[134:137]
	v_mfma_f32_16x16x32_f16 v[130:133], v[138:141], v[156:159], v[130:133]
	v_mfma_f32_16x16x32_f16 v[126:129], v[82:85], v[164:167], v[126:129]
	v_mfma_f32_16x16x32_f16 v[122:125], v[138:141], v[164:167], v[122:125]
	v_mfma_f32_16x16x32_f16 v[118:121], v[82:85], v[178:181], v[118:121]
	v_mfma_f32_16x16x32_f16 v[114:117], v[138:141], v[178:181], v[114:117]
	v_mfma_f32_16x16x32_f16 v[110:113], v[82:85], v[186:189], v[110:113]
	v_mfma_f32_16x16x32_f16 v[106:109], v[138:141], v[186:189], v[106:109]
	v_mfma_f32_16x16x32_f16 v[134:137], v[86:89], v[160:163], v[134:137]
	v_mfma_f32_16x16x32_f16 v[130:133], v[142:145], v[160:163], v[130:133]
	v_mfma_f32_16x16x32_f16 v[126:129], v[86:89], v[168:171], v[126:129]
	v_mfma_f32_16x16x32_f16 v[122:125], v[142:145], v[168:171], v[122:125]
	v_mfma_f32_16x16x32_f16 v[118:121], v[86:89], v[182:185], v[118:121]
	v_mfma_f32_16x16x32_f16 v[114:117], v[142:145], v[182:185], v[114:117]
	v_mfma_f32_16x16x32_f16 v[110:113], v[86:89], v[190:193], v[110:113]
	v_mfma_f32_16x16x32_f16 v[106:109], v[142:145], v[190:193], v[106:109]
	v_mfma_f32_16x16x32_f16 v[62:65], v[194:197], v[156:159], v[62:65]
	v_mfma_f32_16x16x32_f16 v[58:61], v[202:205], v[156:159], v[58:61]
	v_mfma_f32_16x16x32_f16 v[54:57], v[194:197], v[164:167], v[54:57]
	v_mfma_f32_16x16x32_f16 v[50:53], v[202:205], v[164:167], v[50:53]
	v_mfma_f32_16x16x32_f16 v[46:49], v[194:197], v[178:181], v[46:49]
	v_mfma_f32_16x16x32_f16 v[42:45], v[202:205], v[178:181], v[42:45]
	v_mfma_f32_16x16x32_f16 v[38:41], v[194:197], v[186:189], v[38:41]
	v_mfma_f32_16x16x32_f16 v[34:37], v[202:205], v[186:189], v[34:37]
	v_mfma_f32_16x16x32_f16 v[62:65], v[198:201], v[160:163], v[62:65]
	v_mfma_f32_16x16x32_f16 v[58:61], v[220:223], v[160:163], v[58:61]
	v_mfma_f32_16x16x32_f16 v[54:57], v[198:201], v[168:171], v[54:57]
	v_mfma_f32_16x16x32_f16 v[50:53], v[220:223], v[168:171], v[50:53]
	v_mfma_f32_16x16x32_f16 v[46:49], v[198:201], v[182:185], v[46:49]
	v_mfma_f32_16x16x32_f16 v[42:45], v[220:223], v[182:185], v[42:45]
	v_mfma_f32_16x16x32_f16 v[38:41], v[198:201], v[190:193], v[38:41]
	v_mfma_f32_16x16x32_f16 v[34:37], v[220:223], v[190:193], v[34:37]
	s_barrier
	global_load_lds_dwordx4 v[172:173], off
	v_lshl_add_u64 v[172:173], v[206:207], 0, s[92:93]
	s_add_i32 m0, s22, 0x2000
	s_nop 0
	global_load_lds_dwordx4 v[172:173], off
	s_mov_b32 m0, s79
	v_lshl_add_u64 v[172:173], v[212:213], 0, s[92:93]
	ds_read_b128 v[156:159], v177 offset:49152
	ds_read_b128 v[160:163], v177 offset:50176
	ds_read_b128 v[164:167], v177 offset:51200
	ds_read_b128 v[168:171], v177 offset:52224
	ds_read_b128 v[178:181], v177 offset:53248
	ds_read_b128 v[182:185], v177 offset:54272
	ds_read_b128 v[186:189], v177 offset:55296
	ds_read_b128 v[190:193], v177 offset:56320
	global_load_lds_dwordx4 v[172:173], off
	v_lshl_add_u64 v[172:173], v[224:225], 0, s[92:93]
	s_mov_b32 m0, s80
	s_nop 0
	global_load_lds_dwordx4 v[172:173], off
	s_add_u32 s22, s26, 0x10080
	s_addc_u32 s23, s27, 0
	s_add_i32 s26, s48, s71
	v_lshl_add_u64 v[232:233], s[22:23], 0, v[0:1]
	s_mov_b32 m0, s26
	s_nop 0
	global_load_lds_dwordx4 v[232:233], off
	v_lshl_add_u64 v[232:233], s[22:23], 0, v[150:151]
	s_add_i32 m0, s26, 0x2000
	s_nop 0
	global_load_lds_dwordx4 v[232:233], off
	s_add_u32 s29, s29, 0x100
	s_addc_u32 s45, s45, 0
	s_cmp_ge_i32 s51, s24
	s_mov_b64 s[22:23], s[0:1]
	s_mov_b32 s26, s51
	s_waitcnt vmcnt(8) lgkmcnt(0)
	s_barrier
	v_mfma_f32_16x16x32_f16 v[102:105], v[82:85], v[156:159], v[102:105]
	v_mfma_f32_16x16x32_f16 v[98:101], v[138:141], v[156:159], v[98:101]
	v_mfma_f32_16x16x32_f16 v[94:97], v[82:85], v[164:167], v[94:97]
	v_mfma_f32_16x16x32_f16 v[90:93], v[138:141], v[164:167], v[90:93]
	v_mfma_f32_16x16x32_f16 v[78:81], v[82:85], v[178:181], v[78:81]
	v_mfma_f32_16x16x32_f16 v[74:77], v[138:141], v[178:181], v[74:77]
	v_mfma_f32_16x16x32_f16 v[70:73], v[82:85], v[186:189], v[70:73]
	v_mfma_f32_16x16x32_f16 v[66:69], v[138:141], v[186:189], v[66:69]
	v_mfma_f32_16x16x32_f16 v[102:105], v[86:89], v[160:163], v[102:105]
	v_mfma_f32_16x16x32_f16 v[98:101], v[142:145], v[160:163], v[98:101]
	v_mfma_f32_16x16x32_f16 v[94:97], v[86:89], v[168:171], v[94:97]
	v_mfma_f32_16x16x32_f16 v[90:93], v[142:145], v[168:171], v[90:93]
	v_mfma_f32_16x16x32_f16 v[78:81], v[86:89], v[182:185], v[78:81]
	v_mfma_f32_16x16x32_f16 v[74:77], v[142:145], v[182:185], v[74:77]
	v_mfma_f32_16x16x32_f16 v[70:73], v[86:89], v[190:193], v[70:73]
	v_mfma_f32_16x16x32_f16 v[66:69], v[142:145], v[190:193], v[66:69]
	v_mfma_f32_16x16x32_f16 v[30:33], v[194:197], v[156:159], v[30:33]
	v_mfma_f32_16x16x32_f16 v[26:29], v[202:205], v[156:159], v[26:29]
	v_mfma_f32_16x16x32_f16 v[22:25], v[194:197], v[164:167], v[22:25]
	v_mfma_f32_16x16x32_f16 v[18:21], v[202:205], v[164:167], v[18:21]
	v_mfma_f32_16x16x32_f16 v[14:17], v[194:197], v[178:181], v[14:17]
	v_mfma_f32_16x16x32_f16 v[10:13], v[202:205], v[178:181], v[10:13]
	v_mfma_f32_16x16x32_f16 v[6:9], v[194:197], v[186:189], v[6:9]
	v_mfma_f32_16x16x32_f16 v[2:5], v[202:205], v[186:189], v[2:5]
	v_mfma_f32_16x16x32_f16 v[30:33], v[198:201], v[160:163], v[30:33]
	v_mfma_f32_16x16x32_f16 v[26:29], v[220:223], v[160:163], v[26:29]
	v_mfma_f32_16x16x32_f16 v[22:25], v[198:201], v[168:171], v[22:25]
	v_mfma_f32_16x16x32_f16 v[18:21], v[220:223], v[168:171], v[18:21]
	v_mfma_f32_16x16x32_f16 v[14:17], v[198:201], v[182:185], v[14:17]
	v_mfma_f32_16x16x32_f16 v[10:13], v[220:223], v[182:185], v[10:13]
	v_mfma_f32_16x16x32_f16 v[6:9], v[198:201], v[190:193], v[6:9]
	v_mfma_f32_16x16x32_f16 v[2:5], v[220:223], v[190:193], v[2:5]
	s_barrier
	s_cbranch_scc0 .LBB0_692
	s_branch .LBB0_681

; #define PG8_WAIT_V(n) asm volatile("s_waitcnt vmcnt(" #n ")" ::: "memory")
; #define PG8_BAR __builtin_amdgcn_s_barrier()
; template <class Epi, class AMap>
; __device__ __forceinline__ void gemm_phase(LAS unsigned char* lds, const AMap am, const int lda, const h16* Bt, const int ldb, const int M, const int N, const int K, const Epi& E) {
;     ...
;     PG8_WAIT_V(0);
;     if (wr == 0) PG8_BAR;
;     PG8_BAR;
.LBB0_694:
	s_waitcnt vmcnt(0)
	s_cmpk_gt_u32 s69, 0xff
	s_cbranch_scc1 .LBB0_696
.LBB0_696:
	v_readlane_b32 s29, v254, 37
	v_readlane_b32 s10, v255, 10
	v_readlane_b32 s11, v255, 11
	s_barrier

; __device__ __forceinline__ int otid() { int t = (int)threadIdx.x; asm volatile("" : "+v"(t)); return t; }
; __device__ __forceinline__ int obid() { int t = (int)blockIdx.x; asm volatile("" : "+s"(t)); return t; }
; #define PG8_WAIT_V(n) asm volatile("s_waitcnt vmcnt(" #n ")" ::: "memory")
; #define PG8_BAR __builtin_amdgcn_s_barrier()
; template <class Epi, class AMap>
; __device__ __forceinline__ void gemm_phase(LAS unsigned char* lds, const AMap am, const int lda, const h16* Bt, const int ldb, const int M, const int N, const int K, const Epi& E) {
;     const int tid = otid(), wid = __builtin_amdgcn_readfirstlane(tid >> 6), lane = tid & 63, wr = wid >> 2, wc = wid & 3, fr = lane & 15, fq = lane >> 4;
;     const int nt = K / BK;
;     Order S; S.init(M, N, (int)gridDim.x, obid());
;     unsigned voffA[2], voffB[2];
; #pragma unroll
;     for (int i = 0; i < 2; ++i) { int R, C; stage_rc(tid * 16 + i * 8192, R, C); const int Rb = Epi::PERM ? ((R & ~31) + perm32(R & 31)) : R;
;         voffA[i] = (unsigned)(R * lda + C) * 2u; voffB[i] = (unsigned)(Rb * ldb + C) * 2u; }
;     const size_t kstep = (size_t)(BK * 2);
;     const size_t hstepA = (size_t)HALF * lda * 2, hstepB = (size_t)HALF * ldb * 2;
;     const size_t tstepA = 2 * hstepA, tstepB = 2 * hstepB;
;     const unsigned ldsw = (unsigned)wid * 1024u;
;     const int aoff = lds_byte(wr * 64 + fr, fq * 8), boff = lds_byte(wc * 32 + fr, fq * 8);
;     ...
;     Unit cur, nxt; int ui = 0;
;     if (!S.next(0, cur)) return;
;     f32x4 acc[2][2][4][2];
; #pragma unroll
;     for (int a = 0; a < 2; ++a)
; #pragma unroll
;         for (int b = 0; b < 2; ++b)
; #pragma unroll
;             for (int m = 0; m < 4; ++m)
; #pragma unroll
;                 for (int n = 0; n < 2; ++n) acc[a][b][m][n] = (f32x4){0.f, 0.f, 0.f, 0.f};
;     h16x8 At[4][2], B0[2][2], B1[2][2];
;     const char* cA = am(cur.pn) + (size_t)cur.pm * tstepA; const char* cB = (const char*)Bt + (size_t)cur.pn * tstepB;
;     PG8_STAGE(PG8_SB(0, 0), cB, voffB); PG8_STAGE(PG8_SA(0, 0), cA, voffA); PG8_STAGE(PG8_SB(0, 1), cB + hstepB, voffB); PG8_STAGE(PG8_SA(0, 1), cA + hstepA, voffA);
;     if (wr == 1) PG8_BAR;
;     PG8_WAIT_V(4); PG8_BAR;
;     PG8_STAGE(PG8_SB(1, 0), cB + kstep, voffB); PG8_STAGE(PG8_SA(1, 0), cA + kstep, voffA); PG8_STAGE(PG8_SB(1, 1), cB + hstepB + kstep, voffB);
;     PG8_WAIT_V(6); PG8_BAR;
.LBB0_778:
	v_ashrrev_i32_e32 v0, 31, v2
	v_lshrrev_b32_e32 v0, 26, v0
	v_add_u32_e32 v0, v2, v0
	v_ashrrev_i32_e32 v3, 6, v0
	v_bfe_i32 v0, v2, 27, 1
	v_lshlrev_b32_e32 v6, 4, v2
	v_lshrrev_b32_e32 v0, 22, v0
	v_add_u32_e32 v0, v6, v0
	v_and_b32_e32 v0, 0xfffffc00, v0
	v_sub_u32_e32 v0, v6, v0
	v_lshrrev_b32_e32 v4, 4, v0
	v_bitop3_b32 v5, v4, v0, 32 bitop3:0x6c
	v_ashrrev_i32_e32 v0, 31, v0
	v_lshrrev_b32_e32 v0, 26, v0
	v_lshlrev_b32_e32 v4, 3, v3
	v_add_u32_e32 v0, v5, v0
	v_and_b32_e32 v7, -16, v4
	v_ashrrev_i32_e32 v4, 6, v0
	v_mul_i32_i24_e32 v8, 64, v4
	v_add_u32_e32 v0, v4, v7
	v_sub_u32_e32 v5, v5, v8
	v_mov_b32_e32 v12, 1
	v_lshlrev_b32_e32 v7, 5, v3
	v_ashrrev_i16_sdwa v5, v12, sext(v5) dst_sel:DWORD dst_unused:UNUSED_PAD src0_sel:DWORD src1_sel:BYTE_0
	v_lshlrev_b32_e32 v8, 1, v0
	v_lshrrev_b32_e32 v9, 2, v0
	v_and_b32_e32 v10, 3, v4
	s_mov_b32 s4, 0xfffe0
	v_and_b32_e32 v7, 32, v7
	v_bfe_i32 v5, v5, 0, 16
	v_and_b32_e32 v8, 24, v8
	v_and_b32_e32 v9, 4, v9
	v_and_or_b32 v10, v0, s4, v10
	v_or3_b32 v8, v10, v9, v8
	v_add_lshl_u32 v7, v7, v5, 1
	v_lshl_add_u32 v138, v0, 12, v7
	v_lshl_add_u32 v0, v8, 12, v7
	v_add_u32_e32 v7, 0x2000, v6
	v_ashrrev_i32_e32 v6, 31, v7
	v_lshrrev_b32_e32 v6, 22, v6
	v_add_u32_e32 v6, v7, v6
	v_ashrrev_i32_e32 v6, 10, v6
	v_mul_i32_i24_e32 v8, 0x400, v6
	v_sub_u32_e32 v7, v7, v8
	v_lshrrev_b32_e32 v8, 4, v7
	v_bitop3_b32 v8, v8, v7, 32 bitop3:0x6c
	v_lshlrev_b32_e32 v7, 3, v6
	v_and_b32_e32 v9, -16, v7
	v_ashrrev_i32_e32 v7, 31, v8
	s_ashr_i32 s21, s71, 6
	s_ashr_i32 s27, s26, 31
	s_ashr_i32 s23, s22, 31
	s_ashr_i32 s20, s71, 8
	v_lshrrev_b32_e32 v7, 26, v7
	s_lshl_b32 s72, s21, 10
	s_lshl_b64 s[38:39], s[26:27], 20
	s_lshl_b64 s[40:41], s[22:23], 20
	v_add_u32_e32 v10, v8, v7
	s_add_u32 s40, s10, s40
	v_ashrrev_i32_e32 v7, 6, v10
	v_and_b32_e32 v10, 0xc0, v10
	s_addc_u32 s41, s11, s41
	s_add_i32 s23, s72, 0
	v_add_u32_e32 v9, v7, v9
	v_sub_u32_e32 v8, v8, v10
	s_add_i32 m0, s23, 0x10000
	v_lshlrev_b32_e32 v11, 5, v6
	v_ashrrev_i16_sdwa v8, v12, sext(v8) dst_sel:DWORD dst_unused:UNUSED_PAD src0_sel:DWORD src1_sel:BYTE_0
	v_lshlrev_b32_e32 v10, 1, v9
	v_lshrrev_b32_e32 v12, 2, v9
	v_and_b32_e32 v13, 3, v7
	global_load_lds_dwordx4 v0, s[40:41]
	s_add_i32 m0, s23, 0x12000
	v_readlane_b32 s6, v254, 56
	v_and_b32_e32 v11, 32, v11
	v_bfe_i32 v8, v8, 0, 16
	v_and_b32_e32 v10, 24, v10
	v_and_b32_e32 v12, 4, v12
	v_and_or_b32 v13, v9, s4, v13
	v_readlane_b32 s7, v254, 57
	s_add_u32 s0, s6, s0
	v_or3_b32 v10, v13, v12, v10
	v_add_lshl_u32 v11, v11, v8, 1
	s_addc_u32 s1, s7, s1
	v_lshl_add_u32 v142, v10, 12, v11
	s_add_u32 s48, s0, s38
	global_load_lds_dwordx4 v142, s[40:41]
	s_addc_u32 s49, s1, s39
	s_mov_b32 m0, s23
	s_add_i32 s27, s23, 0x2000
	v_lshl_add_u32 v140, v9, 12, v11
	global_load_lds_dwordx4 v138, s[48:49]
	s_mov_b32 m0, s27
	s_add_u32 s0, s40, 0x80000
	global_load_lds_dwordx4 v140, s[48:49]
	s_addc_u32 s1, s41, 0
	s_add_i32 m0, s23, 0x14000
	s_nop 0
	global_load_lds_dwordx4 v0, s[0:1]
	s_add_i32 m0, s23, 0x16000
	s_nop 0
	global_load_lds_dwordx4 v142, s[0:1]
	s_add_u32 s0, s48, 0x80000
	s_addc_u32 s1, s49, 0
	s_add_i32 s73, s23, 0x4000
	s_mov_b32 m0, s73
	s_add_i32 s74, s23, 0x6000
	global_load_lds_dwordx4 v138, s[0:1]
	s_mov_b32 m0, s74
	s_cmp_lg_u32 s20, 1
	global_load_lds_dwordx4 v140, s[0:1]
	s_cbranch_scc1 .LBB0_780
.LBB0_780:
	v_lshrrev_b32_e32 v18, 1, v2
	v_and_b32_e32 v18, 24, v18
	v_and_b32_e32 v9, 15, v2
	v_lshlrev_b32_e32 v19, 1, v18
	v_lshlrev_b32_e32 v2, 2, v2
	v_lshl_or_b32 v154, s20, 6, v9
	v_lshl_or_b32 v9, v9, 6, v19
	s_lshl_b32 s0, s20, 13
	v_and_b32_e32 v2, 32, v2
	v_lshl_add_u64 v[10:11], s[40:41], 0, v[0:1]
	v_mov_b32_e32 v143, v1
	v_bitop3_b32 v19, v9, s0, v2 bitop3:0xde
	s_lshl_b32 s0, s21, 5
	v_lshl_add_u64 v[12:13], s[40:41], 0, v[142:143]
	v_mov_b32_e32 v139, v1
	s_and_b32 s20, s0, 0x60
	s_add_i32 m0, s23, 0x18000
	v_lshl_add_u64 v[10:11], v[10:11], 0, s[92:93]
	v_lshl_add_u64 v[14:15], s[48:49], 0, v[138:139]
	v_mov_b32_e32 v141, v1
	s_lshl_b32 s0, s20, 7
	s_waitcnt vmcnt(0)
	s_barrier
	global_load_lds_dwordx4 v[10:11], off
	v_lshl_add_u64 v[10:11], v[12:13], 0, s[92:93]
	s_add_i32 m0, s23, 0x1a000
	s_add_i32 s75, s23, 0x8000
	s_add_i32 s76, s23, 0xa000
	v_lshl_add_u64 v[16:17], s[48:49], 0, v[140:141]
	v_bitop3_b32 v155, v9, s0, v2 bitop3:0xde
	global_load_lds_dwordx4 v[10:11], off
	v_lshl_add_u64 v[10:11], v[14:15], 0, s[92:93]
	s_mov_b32 m0, s75
	s_add_u32 s0, s40, 0x80080
	global_load_lds_dwordx4 v[10:11], off
	v_lshl_add_u64 v[10:11], v[16:17], 0, s[92:93]
	s_mov_b32 m0, s76
	s_addc_u32 s1, s41, 0
	global_load_lds_dwordx4 v[10:11], off
	s_add_i32 m0, s23, 0x1c000
	v_lshl_add_u64 v[10:11], s[0:1], 0, v[0:1]
	global_load_lds_dwordx4 v[10:11], off
	v_lshl_add_u64 v[10:11], s[0:1], 0, v[142:143]
	s_add_i32 m0, s23, 0x1e000
	v_cvt_f32_ubyte0_e32 v2, s68
	global_load_lds_dwordx4 v[10:11], off
	v_rcp_iflag_f32_e32 v2, v2
	s_sub_i32 s0, 0, s68
	s_waitcnt vmcnt(6)
	v_or_b32_e32 v156, s20, v18
	v_mul_f32_e32 v2, 0x4f7ffffe, v2
	v_cvt_u32_f32_e32 v2, v2
	s_mov_b32 s77, 0
	v_mov_b32_e32 v145, v1
	v_mov_b32_e32 v147, v1
	v_readfirstlane_b32 s1, v2
	v_lshlrev_b32_e32 v2, 15, v3
	v_and_b32_e32 v2, 0xffff0000, v2
	v_lshl_add_u32 v2, v4, 12, v2
	v_and_b32_e32 v3, 1, v3
	v_lshl_or_b32 v2, v3, 6, v2
	v_lshl_add_u32 v144, v5, 1, v2
	v_lshlrev_b32_e32 v2, 15, v6
	v_and_b32_e32 v2, 0xffff0000, v2
	s_mul_i32 s0, s0, s1
	v_lshl_add_u32 v2, v7, 12, v2
	v_and_b32_e32 v3, 1, v6
	s_mul_hi_u32 s0, s1, s0
	v_lshl_or_b32 v2, v3, 6, v2
	s_add_i32 s78, s1, s0
	v_lshl_add_u32 v146, v8, 1, v2
	v_add_u32_e32 v157, 0, v19
	s_barrier
	s_branch .LBB0_782

; #define PG8_STAGE(bufoff, gbase, voff) do { _Pragma("unroll") for (int _i = 0; _i < 2; ++_i) \
;         __builtin_amdgcn_global_load_lds((const unsigned*)((const char*)(gbase) + (voff)[_i]), (LAS unsigned*)(lds + (bufoff) + ldsw + _i * 8192), 16, 0, 0); } while (0)
; #define PG8_LDA(dst, b, h) do { _Pragma("unroll") for (int m = 0; m < 4; ++m) _Pragma("unroll") for (int k = 0; k < 2; ++k) dst[m][k] = *(const LAS h16x8*)(lds + PG8_SA(b, h) + aoff + m * 2048 + k * 1024); } while (0)
; #define PG8_LDB(dst, b, h) do { _Pragma("unroll") for (int n = 0; n < 2; ++n) _Pragma("unroll") for (int k = 0; k < 2; ++k) dst[n][k] = *(const LAS h16x8*)(lds + PG8_SB(b, h) + boff + n * 2048 + k * 1024); } while (0)
; #define PG8_WAIT_V(n) asm volatile("s_waitcnt vmcnt(" #n ")" ::: "memory")
; #define PG8_WAIT_L(n) asm volatile("s_waitcnt lgkmcnt(" #n ")" ::: "memory")
; #define PG8_BAR __builtin_amdgcn_s_barrier()
; #define PG8_SCHED __builtin_amdgcn_sched_barrier(0)
; template <class Epi, class AMap>
; __device__ __forceinline__ void gemm_phase(LAS unsigned char* lds, const AMap am, const int lda, const h16* Bt, const int ldb, const int M, const int N, const int K, const Epi& E) {
;     ...
;         const bool has_next = S.next(ui + 1, nxt);
;         const char* nA = has_next ? am(nxt.pn) + (size_t)nxt.pm * tstepA : cA; const char* nB = has_next ? (const char*)Bt + (size_t)nxt.pn * tstepB : cB;
; #pragma unroll 1
;         for (int t = 0; t < nt; t += 2) {
;             const bool last = (t == nt - 2);
;             const char* a1 = cA + (size_t)(t + 1) * kstep;
;             const char* a2 = last ? nA : cA + (size_t)(t + 2) * kstep; const char* b2 = last ? nB : cB + (size_t)(t + 2) * kstep;
;             const char* a3 = a2 + kstep; const char* b3 = b2 + kstep;
;             PG8_LDB(B0, 0, 0); PG8_SCHED; PG8_LDA(At, 0, 0); PG8_STAGE(PG8_SA(1, 1), a1 + hstepA, voffA);
;             PG8_WAIT_L(8); PG8_BAR; PG8_WAIT_L(0); PG8_MMA(0, 0, At, B0); PG8_BAR; PG8_SCHED;
;             PG8_LDB(B1, 0, 1); PG8_STAGE(PG8_SB(0, 0), b2, voffB);
;             PG8_BAR; PG8_WAIT_L(0); PG8_MMA(0, 1, At, B1); PG8_BAR;
;             PG8_LDA(At, 0, 1); PG8_STAGE(PG8_SA(0, 0), a2, voffA);
;             PG8_BAR; PG8_WAIT_L(0); PG8_MMA(1, 0, At, B0); PG8_BAR; PG8_SCHED;
;             PG8_STAGE(PG8_SB(0, 1), b2 + hstepB, voffB);
;             PG8_WAIT_V(6); PG8_BAR; PG8_MMA(1, 1, At, B1); PG8_BAR;
.LBB0_798:
	s_ashr_i32 s43, s42, 31
	s_lshl_b64 s[20:21], s[42:43], 20
	s_add_u32 s64, s10, s20
	s_addc_u32 s65, s11, s21
	s_and_b64 s[0:1], s[0:1], exec
	s_cselect_b32 s29, s65, s41
	s_cselect_b32 s20, s64, s40
	s_add_u32 s0, s48, 0x80080
	s_addc_u32 s1, s49, 0
	s_add_u32 s21, s40, 0x100
	s_addc_u32 s35, s41, 0
	s_mov_b32 s43, -2
	s_cmpk_lt_u32 s71, 0x100
	s_cbranch_scc1 .Lgy8
	s_barrier
.Lgy8:
.Lg4p_799:
	s_add_u32 s40, s0, 0xfff80080
	s_addc_u32 s41, s1, -1
	s_add_i32 s45, 0, 0x10000
	v_add_u32_e32 v152, s45, v155
	ds_read_b128 v[130:133], v152
	ds_read_b128 v[134:137], v152 offset:1024
	ds_read_b128 v[148:151], v152 offset:2048
	ds_read_b128 v[158:161], v152 offset:3072
	s_cmp_eq_u32 s43, 28
	s_cselect_b32 s49, s47, s41
	s_cselect_b32 s48, s46, s40
	s_cselect_b32 s41, s29, s35
	s_cselect_b32 s40, s20, s21
	v_lshl_add_u64 v[152:153], s[0:1], 0, v[144:145]
	s_add_i32 m0, s23, 0xc000
	ds_read_b128 v[162:165], v157
	ds_read_b128 v[166:169], v157 offset:1024
	ds_read_b128 v[170:173], v157 offset:2048
	ds_read_b128 v[174:177], v157 offset:3072
	ds_read_b128 v[178:181], v157 offset:4096
	ds_read_b128 v[182:185], v157 offset:5120
	ds_read_b128 v[186:189], v157 offset:6144
	ds_read_b128 v[190:193], v157 offset:7168
	global_load_lds_dwordx4 v[152:153], off
	v_lshl_add_u64 v[152:153], s[0:1], 0, v[146:147]
	s_add_i32 m0, s23, 0xe000
	s_nop 0
	global_load_lds_dwordx4 v[152:153], off
	s_waitcnt lgkmcnt(11)
	s_add_i32 s60, 0, 0x14000
	v_add_u32_e32 v152, s60, v155
	s_add_i32 s45, s45, s72
	ds_read_b128 v[194:197], v152
	ds_read_b128 v[198:201], v152 offset:1024
	ds_read_b128 v[202:205], v152 offset:2048
	ds_read_b128 v[220:223], v152 offset:3072
	s_waitcnt vmcnt(8) lgkmcnt(0)
	s_barrier
	v_mfma_f32_16x16x32_f16 v[126:129], v[130:133], v[162:165], 0
	v_mfma_f32_16x16x32_f16 v[122:125], v[148:151], v[162:165], 0
	v_mfma_f32_16x16x32_f16 v[110:113], v[130:133], v[170:173], 0
	v_mfma_f32_16x16x32_f16 v[106:109], v[148:151], v[170:173], 0
	v_mfma_f32_16x16x32_f16 v[94:97], v[130:133], v[178:181], 0
	v_mfma_f32_16x16x32_f16 v[90:93], v[148:151], v[178:181], 0
	v_mfma_f32_16x16x32_f16 v[78:81], v[130:133], v[186:189], 0
	v_mfma_f32_16x16x32_f16 v[74:77], v[148:151], v[186:189], 0
	v_mfma_f32_16x16x32_f16 v[126:129], v[134:137], v[166:169], v[126:129]
	v_mfma_f32_16x16x32_f16 v[122:125], v[158:161], v[166:169], v[122:125]
	v_mfma_f32_16x16x32_f16 v[110:113], v[134:137], v[174:177], v[110:113]
	v_mfma_f32_16x16x32_f16 v[106:109], v[158:161], v[174:177], v[106:109]
	v_mfma_f32_16x16x32_f16 v[94:97], v[134:137], v[182:185], v[94:97]
	v_mfma_f32_16x16x32_f16 v[90:93], v[158:161], v[182:185], v[90:93]
	v_mfma_f32_16x16x32_f16 v[78:81], v[134:137], v[190:193], v[78:81]
	v_mfma_f32_16x16x32_f16 v[74:77], v[158:161], v[190:193], v[74:77]
	v_mfma_f32_16x16x32_f16 v[118:121], v[194:197], v[162:165], 0
	v_mfma_f32_16x16x32_f16 v[114:117], v[202:205], v[162:165], 0
	v_mfma_f32_16x16x32_f16 v[102:105], v[194:197], v[170:173], 0
	v_mfma_f32_16x16x32_f16 v[98:101], v[202:205], v[170:173], 0
	v_mfma_f32_16x16x32_f16 v[86:89], v[194:197], v[178:181], 0
	v_mfma_f32_16x16x32_f16 v[82:85], v[202:205], v[178:181], 0
	v_mfma_f32_16x16x32_f16 v[70:73], v[194:197], v[186:189], 0
	v_mfma_f32_16x16x32_f16 v[66:69], v[202:205], v[186:189], 0
	v_mfma_f32_16x16x32_f16 v[118:121], v[198:201], v[166:169], v[118:121]
	v_mfma_f32_16x16x32_f16 v[114:117], v[220:223], v[166:169], v[114:117]
	v_mfma_f32_16x16x32_f16 v[102:105], v[198:201], v[174:177], v[102:105]
	v_mfma_f32_16x16x32_f16 v[98:101], v[220:223], v[174:177], v[98:101]
	v_mfma_f32_16x16x32_f16 v[86:89], v[198:201], v[182:185], v[86:89]
	v_mfma_f32_16x16x32_f16 v[82:85], v[220:223], v[182:185], v[82:85]
	v_mfma_f32_16x16x32_f16 v[70:73], v[198:201], v[190:193], v[70:73]
	v_mfma_f32_16x16x32_f16 v[66:69], v[220:223], v[190:193], v[66:69]
	s_barrier
	v_lshl_add_u64 v[152:153], s[40:41], 0, v[0:1]
	s_mov_b32 m0, s45
	v_lshl_add_u64 v[206:207], s[40:41], 0, v[142:143]
	global_load_lds_dwordx4 v[152:153], off
	s_add_i32 m0, s45, 0x2000
	s_nop 0
	global_load_lds_dwordx4 v[206:207], off
	s_mov_b32 m0, s23
	v_lshl_add_u64 v[212:213], s[48:49], 0, v[138:139]
	ds_read_b128 v[162:165], v157 offset:16384
	ds_read_b128 v[166:169], v157 offset:17408
	ds_read_b128 v[170:173], v157 offset:18432
	ds_read_b128 v[174:177], v157 offset:19456
	ds_read_b128 v[178:181], v157 offset:20480
	ds_read_b128 v[182:185], v157 offset:21504
	ds_read_b128 v[186:189], v157 offset:22528
	ds_read_b128 v[190:193], v157 offset:23552
	global_load_lds_dwordx4 v[212:213], off
	v_lshl_add_u64 v[224:225], s[48:49], 0, v[140:141]
	s_mov_b32 m0, s27
	s_nop 0
	global_load_lds_dwordx4 v[224:225], off
	s_add_u32 s50, s40, 0x80000
	s_addc_u32 s51, s41, 0
	s_add_i32 s45, s60, s72
	v_lshl_add_u64 v[232:233], s[50:51], 0, v[0:1]
	s_mov_b32 m0, s45
	s_nop 0
	global_load_lds_dwordx4 v[232:233], off
	v_lshl_add_u64 v[232:233], s[50:51], 0, v[142:143]
	s_add_i32 m0, s45, 0x2000
	s_nop 0
	global_load_lds_dwordx4 v[232:233], off
	s_waitcnt vmcnt(8) lgkmcnt(0)
	s_barrier
; #define PG8_STAGE(bufoff, gbase, voff) do { _Pragma("unroll") for (int _i = 0; _i < 2; ++_i) \
;         __builtin_amdgcn_global_load_lds((const unsigned*)((const char*)(gbase) + (voff)[_i]), (LAS unsigned*)(lds + (bufoff) + ldsw + _i * 8192), 16, 0, 0); } while (0)
; #define PG8_LDA(dst, b, h) do { _Pragma("unroll") for (int m = 0; m < 4; ++m) _Pragma("unroll") for (int k = 0; k < 2; ++k) dst[m][k] = *(const LAS h16x8*)(lds + PG8_SA(b, h) + aoff + m * 2048 + k * 1024); } while (0)
; #define PG8_LDB(dst, b, h) do { _Pragma("unroll") for (int n = 0; n < 2; ++n) _Pragma("unroll") for (int k = 0; k < 2; ++k) dst[n][k] = *(const LAS h16x8*)(lds + PG8_SB(b, h) + boff + n * 2048 + k * 1024); } while (0)
; #define PG8_MMA(ai, bj, At, Bt_) do { __builtin_amdgcn_s_setprio(1); _Pragma("unroll") for (int m = 0; m < 4; ++m) _Pragma("unroll") for (int n = 0; n < 2; ++n) _Pragma("unroll") for (int k = 0; k < 2; ++k) \
;         acc[ai][bj][m][n] = __builtin_amdgcn_mfma_f32_16x16x32_f16(Bt_[n][k], At[m][k], acc[ai][bj][m][n], 0, 0, 0); __builtin_amdgcn_s_setprio(0); } while (0)
; #define PG8_WAIT_V(n) asm volatile("s_waitcnt vmcnt(" #n ")" ::: "memory")
; #define PG8_WAIT_L(n) asm volatile("s_waitcnt lgkmcnt(" #n ")" ::: "memory")
; #define PG8_BAR __builtin_amdgcn_s_barrier()
; #define PG8_SCHED __builtin_amdgcn_sched_barrier(0)
; template <class Epi, class AMap>
; __device__ __forceinline__ void gemm_phase(LAS unsigned char* lds, const AMap am, const int lda, const h16* Bt, const int ldb, const int M, const int N, const int K, const Epi& E) {
;     ...
;             PG8_WAIT_V(6); PG8_BAR; PG8_MMA(1, 1, At, B1); PG8_BAR;
;             PG8_LDB(B0, 1, 0); PG8_SCHED; PG8_LDA(At, 1, 0); PG8_STAGE(PG8_SA(0, 1), a2 + hstepA, voffA);
;             PG8_WAIT_L(8); PG8_BAR; PG8_WAIT_L(0); PG8_MMA(0, 0, At, B0); PG8_BAR; PG8_SCHED;
;             PG8_LDB(B1, 1, 1); PG8_STAGE(PG8_SB(1, 0), b3, voffB);
;             PG8_BAR; PG8_WAIT_L(0); PG8_MMA(0, 1, At, B1); PG8_BAR;
	v_mfma_f32_16x16x32_f16 v[62:65], v[130:133], v[162:165], 0
	v_mfma_f32_16x16x32_f16 v[58:61], v[148:151], v[162:165], 0
	v_mfma_f32_16x16x32_f16 v[46:49], v[130:133], v[170:173], 0
	v_mfma_f32_16x16x32_f16 v[42:45], v[148:151], v[170:173], 0
	v_mfma_f32_16x16x32_f16 v[30:33], v[130:133], v[178:181], 0
	v_mfma_f32_16x16x32_f16 v[26:29], v[148:151], v[178:181], 0
	v_mfma_f32_16x16x32_f16 v[14:17], v[130:133], v[186:189], 0
	v_mfma_f32_16x16x32_f16 v[10:13], v[148:151], v[186:189], 0
	v_mfma_f32_16x16x32_f16 v[62:65], v[134:137], v[166:169], v[62:65]
	v_mfma_f32_16x16x32_f16 v[58:61], v[158:161], v[166:169], v[58:61]
	v_mfma_f32_16x16x32_f16 v[46:49], v[134:137], v[174:177], v[46:49]
	v_mfma_f32_16x16x32_f16 v[42:45], v[158:161], v[174:177], v[42:45]
	v_mfma_f32_16x16x32_f16 v[30:33], v[134:137], v[182:185], v[30:33]
	v_mfma_f32_16x16x32_f16 v[26:29], v[158:161], v[182:185], v[26:29]
	v_mfma_f32_16x16x32_f16 v[14:17], v[134:137], v[190:193], v[14:17]
	v_mfma_f32_16x16x32_f16 v[10:13], v[158:161], v[190:193], v[10:13]
	v_mfma_f32_16x16x32_f16 v[54:57], v[194:197], v[162:165], 0
	v_mfma_f32_16x16x32_f16 v[50:53], v[202:205], v[162:165], 0
	v_mfma_f32_16x16x32_f16 v[38:41], v[194:197], v[170:173], 0
	v_mfma_f32_16x16x32_f16 v[34:37], v[202:205], v[170:173], 0
	v_mfma_f32_16x16x32_f16 v[22:25], v[194:197], v[178:181], 0
	v_mfma_f32_16x16x32_f16 v[18:21], v[202:205], v[178:181], 0
	v_mfma_f32_16x16x32_f16 v[6:9], v[194:197], v[186:189], 0
	v_mfma_f32_16x16x32_f16 v[2:5], v[202:205], v[186:189], 0
	v_mfma_f32_16x16x32_f16 v[54:57], v[198:201], v[166:169], v[54:57]
	v_mfma_f32_16x16x32_f16 v[50:53], v[220:223], v[166:169], v[50:53]
	v_mfma_f32_16x16x32_f16 v[38:41], v[198:201], v[174:177], v[38:41]
	v_mfma_f32_16x16x32_f16 v[34:37], v[220:223], v[174:177], v[34:37]
	v_mfma_f32_16x16x32_f16 v[22:25], v[198:201], v[182:185], v[22:25]
	v_mfma_f32_16x16x32_f16 v[18:21], v[220:223], v[182:185], v[18:21]
	v_mfma_f32_16x16x32_f16 v[6:9], v[198:201], v[190:193], v[6:9]
	v_mfma_f32_16x16x32_f16 v[2:5], v[220:223], v[190:193], v[2:5]
	s_barrier
	s_add_i32 s45, 0, 0x18000
	v_add_u32_e32 v234, s45, v155
	ds_read_b128 v[130:133], v234
	ds_read_b128 v[134:137], v234 offset:1024
	ds_read_b128 v[148:151], v234 offset:2048
	ds_read_b128 v[158:161], v234 offset:3072
	s_add_u32 s48, s48, 0x80000
	s_addc_u32 s49, s49, 0
	s_mov_b32 m0, s73
	v_lshl_add_u64 v[232:233], s[48:49], 0, v[138:139]
	ds_read_b128 v[162:165], v157 offset:32768
	ds_read_b128 v[166:169], v157 offset:33792
	ds_read_b128 v[170:173], v157 offset:34816
	ds_read_b128 v[174:177], v157 offset:35840
	ds_read_b128 v[178:181], v157 offset:36864
	ds_read_b128 v[182:185], v157 offset:37888
	ds_read_b128 v[186:189], v157 offset:38912
	ds_read_b128 v[190:193], v157 offset:39936
	global_load_lds_dwordx4 v[232:233], off
	v_lshl_add_u64 v[232:233], s[48:49], 0, v[140:141]
	s_mov_b32 m0, s74
	s_nop 0
	global_load_lds_dwordx4 v[232:233], off
	s_waitcnt lgkmcnt(11)
	s_add_i32 s48, 0, 0x1c000
	s_add_i32 s45, s45, s72
	v_add_u32_e32 v214, s48, v155
	v_lshl_add_u64 v[152:153], v[152:153], 0, s[92:93]
	s_mov_b32 m0, s45
	ds_read_b128 v[194:197], v214
	ds_read_b128 v[198:201], v214 offset:1024
	ds_read_b128 v[202:205], v214 offset:2048
	ds_read_b128 v[220:223], v214 offset:3072
	s_waitcnt vmcnt(8) lgkmcnt(0)
	s_barrier
	v_mfma_f32_16x16x32_f16 v[126:129], v[130:133], v[162:165], v[126:129]
	v_mfma_f32_16x16x32_f16 v[122:125], v[148:151], v[162:165], v[122:125]
	v_mfma_f32_16x16x32_f16 v[110:113], v[130:133], v[170:173], v[110:113]
	v_mfma_f32_16x16x32_f16 v[106:109], v[148:151], v[170:173], v[106:109]
	v_mfma_f32_16x16x32_f16 v[94:97], v[130:133], v[178:181], v[94:97]
	v_mfma_f32_16x16x32_f16 v[90:93], v[148:151], v[178:181], v[90:93]
	v_mfma_f32_16x16x32_f16 v[78:81], v[130:133], v[186:189], v[78:81]
	v_mfma_f32_16x16x32_f16 v[74:77], v[148:151], v[186:189], v[74:77]
	v_mfma_f32_16x16x32_f16 v[126:129], v[134:137], v[166:169], v[126:129]
	v_mfma_f32_16x16x32_f16 v[122:125], v[158:161], v[166:169], v[122:125]
	v_mfma_f32_16x16x32_f16 v[110:113], v[134:137], v[174:177], v[110:113]
	v_mfma_f32_16x16x32_f16 v[106:109], v[158:161], v[174:177], v[106:109]
	v_mfma_f32_16x16x32_f16 v[94:97], v[134:137], v[182:185], v[94:97]
	v_mfma_f32_16x16x32_f16 v[90:93], v[158:161], v[182:185], v[90:93]
	v_mfma_f32_16x16x32_f16 v[78:81], v[134:137], v[190:193], v[78:81]
	v_mfma_f32_16x16x32_f16 v[74:77], v[158:161], v[190:193], v[74:77]
	v_mfma_f32_16x16x32_f16 v[118:121], v[194:197], v[162:165], v[118:121]
	v_mfma_f32_16x16x32_f16 v[114:117], v[202:205], v[162:165], v[114:117]
	v_mfma_f32_16x16x32_f16 v[102:105], v[194:197], v[170:173], v[102:105]
	v_mfma_f32_16x16x32_f16 v[98:101], v[202:205], v[170:173], v[98:101]
	v_mfma_f32_16x16x32_f16 v[86:89], v[194:197], v[178:181], v[86:89]
	v_mfma_f32_16x16x32_f16 v[82:85], v[202:205], v[178:181], v[82:85]
	v_mfma_f32_16x16x32_f16 v[70:73], v[194:197], v[186:189], v[70:73]
	v_mfma_f32_16x16x32_f16 v[66:69], v[202:205], v[186:189], v[66:69]
	v_mfma_f32_16x16x32_f16 v[118:121], v[198:201], v[166:169], v[118:121]
	v_mfma_f32_16x16x32_f16 v[114:117], v[220:223], v[166:169], v[114:117]
	v_mfma_f32_16x16x32_f16 v[102:105], v[198:201], v[174:177], v[102:105]
	v_mfma_f32_16x16x32_f16 v[98:101], v[220:223], v[174:177], v[98:101]
	v_mfma_f32_16x16x32_f16 v[86:89], v[198:201], v[182:185], v[86:89]
	v_mfma_f32_16x16x32_f16 v[82:85], v[220:223], v[182:185], v[82:85]
	v_mfma_f32_16x16x32_f16 v[70:73], v[198:201], v[190:193], v[70:73]
	v_mfma_f32_16x16x32_f16 v[66:69], v[220:223], v[190:193], v[66:69]
	s_barrier
; #define PG8_STAGE(bufoff, gbase, voff) do { _Pragma("unroll") for (int _i = 0; _i < 2; ++_i) \
;         __builtin_amdgcn_global_load_lds((const unsigned*)((const char*)(gbase) + (voff)[_i]), (LAS unsigned*)(lds + (bufoff) + ldsw + _i * 8192), 16, 0, 0); } while (0)
; #define PG8_LDA(dst, b, h) do { _Pragma("unroll") for (int m = 0; m < 4; ++m) _Pragma("unroll") for (int k = 0; k < 2; ++k) dst[m][k] = *(const LAS h16x8*)(lds + PG8_SA(b, h) + aoff + m * 2048 + k * 1024); } while (0)
; #define PG8_MMA(ai, bj, At, Bt_) do { __builtin_amdgcn_s_setprio(1); _Pragma("unroll") for (int m = 0; m < 4; ++m) _Pragma("unroll") for (int n = 0; n < 2; ++n) _Pragma("unroll") for (int k = 0; k < 2; ++k) \
;         acc[ai][bj][m][n] = __builtin_amdgcn_mfma_f32_16x16x32_f16(Bt_[n][k], At[m][k], acc[ai][bj][m][n], 0, 0, 0); __builtin_amdgcn_s_setprio(0); } while (0)
; #define PG8_WAIT_V(n) asm volatile("s_waitcnt vmcnt(" #n ")" ::: "memory")
; #define PG8_WAIT_L(n) asm volatile("s_waitcnt lgkmcnt(" #n ")" ::: "memory")
; #define PG8_BAR __builtin_amdgcn_s_barrier()
; #define PG8_SCHED __builtin_amdgcn_sched_barrier(0)
; template <class Epi, class AMap>
; __device__ __forceinline__ void gemm_phase(LAS unsigned char* lds, const AMap am, const int lda, const h16* Bt, const int ldb, const int M, const int N, const int K, const Epi& E) {
;     ...
;             PG8_LDA(At, 1, 1); PG8_STAGE(PG8_SA(1, 0), a3, voffA);
;             PG8_BAR; PG8_WAIT_L(0); PG8_MMA(1, 0, At, B0); PG8_BAR; PG8_SCHED;
;             PG8_STAGE(PG8_SB(1, 1), b3 + hstepB, voffB);
;             PG8_WAIT_V(6); PG8_BAR; PG8_MMA(1, 1, At, B1); PG8_BAR;
	global_load_lds_dwordx4 v[152:153], off
	v_lshl_add_u64 v[152:153], v[206:207], 0, s[92:93]
	s_add_i32 m0, s45, 0x2000
	s_nop 0
	global_load_lds_dwordx4 v[152:153], off
	s_mov_b32 m0, s75
	v_lshl_add_u64 v[152:153], v[212:213], 0, s[92:93]
	ds_read_b128 v[162:165], v157 offset:49152
	ds_read_b128 v[166:169], v157 offset:50176
	ds_read_b128 v[170:173], v157 offset:51200
	ds_read_b128 v[174:177], v157 offset:52224
	ds_read_b128 v[178:181], v157 offset:53248
	ds_read_b128 v[182:185], v157 offset:54272
	ds_read_b128 v[186:189], v157 offset:55296
	ds_read_b128 v[190:193], v157 offset:56320
	global_load_lds_dwordx4 v[152:153], off
	v_lshl_add_u64 v[152:153], v[224:225], 0, s[92:93]
	s_mov_b32 m0, s76
	s_nop 0
	global_load_lds_dwordx4 v[152:153], off
	s_add_u32 s40, s40, 0x80080
	s_addc_u32 s41, s41, 0
	s_add_i32 s45, s48, s72
	v_lshl_add_u64 v[232:233], s[40:41], 0, v[0:1]
	s_mov_b32 m0, s45
	s_nop 0
	global_load_lds_dwordx4 v[232:233], off
	v_lshl_add_u64 v[232:233], s[40:41], 0, v[142:143]
	s_add_i32 m0, s45, 0x2000
	s_nop 0
	global_load_lds_dwordx4 v[232:233], off
	s_add_i32 s43, s43, 2
	s_add_u32 s0, s0, 0x100
	s_addc_u32 s1, s1, 0
	s_add_u32 s21, s21, 0x100
	s_addc_u32 s35, s35, 0
	s_cmp_gt_u32 s43, 29
	s_waitcnt vmcnt(8) lgkmcnt(0)
	s_barrier
	v_mfma_f32_16x16x32_f16 v[62:65], v[130:133], v[162:165], v[62:65]
	v_mfma_f32_16x16x32_f16 v[58:61], v[148:151], v[162:165], v[58:61]
	v_mfma_f32_16x16x32_f16 v[46:49], v[130:133], v[170:173], v[46:49]
	v_mfma_f32_16x16x32_f16 v[42:45], v[148:151], v[170:173], v[42:45]
	v_mfma_f32_16x16x32_f16 v[30:33], v[130:133], v[178:181], v[30:33]
	v_mfma_f32_16x16x32_f16 v[26:29], v[148:151], v[178:181], v[26:29]
	v_mfma_f32_16x16x32_f16 v[14:17], v[130:133], v[186:189], v[14:17]
	v_mfma_f32_16x16x32_f16 v[10:13], v[148:151], v[186:189], v[10:13]
	v_mfma_f32_16x16x32_f16 v[62:65], v[134:137], v[166:169], v[62:65]
	v_mfma_f32_16x16x32_f16 v[58:61], v[158:161], v[166:169], v[58:61]
	v_mfma_f32_16x16x32_f16 v[46:49], v[134:137], v[174:177], v[46:49]
	v_mfma_f32_16x16x32_f16 v[42:45], v[158:161], v[174:177], v[42:45]
	v_mfma_f32_16x16x32_f16 v[30:33], v[134:137], v[182:185], v[30:33]
	v_mfma_f32_16x16x32_f16 v[26:29], v[158:161], v[182:185], v[26:29]
	v_mfma_f32_16x16x32_f16 v[14:17], v[134:137], v[190:193], v[14:17]
	v_mfma_f32_16x16x32_f16 v[10:13], v[158:161], v[190:193], v[10:13]
	v_mfma_f32_16x16x32_f16 v[54:57], v[194:197], v[162:165], v[54:57]
	v_mfma_f32_16x16x32_f16 v[50:53], v[202:205], v[162:165], v[50:53]
	v_mfma_f32_16x16x32_f16 v[38:41], v[194:197], v[170:173], v[38:41]
	v_mfma_f32_16x16x32_f16 v[34:37], v[202:205], v[170:173], v[34:37]
	v_mfma_f32_16x16x32_f16 v[22:25], v[194:197], v[178:181], v[22:25]
	v_mfma_f32_16x16x32_f16 v[18:21], v[202:205], v[178:181], v[18:21]
	v_mfma_f32_16x16x32_f16 v[6:9], v[194:197], v[186:189], v[6:9]
	v_mfma_f32_16x16x32_f16 v[2:5], v[202:205], v[186:189], v[2:5]
	v_mfma_f32_16x16x32_f16 v[54:57], v[198:201], v[166:169], v[54:57]
	v_mfma_f32_16x16x32_f16 v[50:53], v[220:223], v[166:169], v[50:53]
	v_mfma_f32_16x16x32_f16 v[38:41], v[198:201], v[174:177], v[38:41]
	v_mfma_f32_16x16x32_f16 v[34:37], v[220:223], v[174:177], v[34:37]
	v_mfma_f32_16x16x32_f16 v[22:25], v[198:201], v[182:185], v[22:25]
	v_mfma_f32_16x16x32_f16 v[18:21], v[220:223], v[182:185], v[18:21]
	v_mfma_f32_16x16x32_f16 v[6:9], v[198:201], v[190:193], v[6:9]
	v_mfma_f32_16x16x32_f16 v[2:5], v[220:223], v[190:193], v[2:5]
	s_barrier
	s_cbranch_scc1 .Lg4x_799

; #define PG8_WAIT_V(n) asm volatile("s_waitcnt vmcnt(" #n ")" ::: "memory")
; #define PG8_BAR __builtin_amdgcn_s_barrier()
; template <class Epi, class AMap>
; __device__ __forceinline__ void gemm_phase(LAS unsigned char* lds, const AMap am, const int lda, const h16* Bt, const int ldb, const int M, const int N, const int K, const Epi& E) {
;     ...
;     PG8_WAIT_V(0);
;     if (wr == 0) PG8_BAR;
;     PG8_BAR;
.LBB0_928:
	s_waitcnt vmcnt(0)
	s_cmpk_gt_u32 s71, 0xff
	s_cbranch_scc1 .LBB0_930
.LBB0_930:
	s_barrier
	v_readlane_b32 s29, v254, 37
